# embedded LDS-DMA groups after MFMA 15 and 31 of each MFMA segment (was 14 and 30)
# speedup vs baseline: 1.0069x; 1.0069x over previous
; #define PG8_STAGE(bufoff, gbase, voff) do { _Pragma("unroll") for (int _i = 0; _i < 2; ++_i) \
;         __builtin_amdgcn_global_load_lds((const unsigned*)((const char*)(gbase) + (voff)[_i]), (PG8_LAS unsigned*)(lds + (bufoff) + ldsw + _i * 8192), 16, 0, 0); } while (0)
; #define PG8_LDA(dst, b, h) do { _Pragma("unroll") for (int m = 0; m < 4; ++m) _Pragma("unroll") for (int k = 0; k < 2; ++k) dst[m][k] = *(const PG8_LAS bf16x8*)(lds + PG8_SA(b, h) + aoff + m * 2048 + k * 1024); } while (0)
; #define PG8_LDB(dst, b, h) do { _Pragma("unroll") for (int n = 0; n < 2; ++n) _Pragma("unroll") for (int k = 0; k < 2; ++k) dst[n][k] = *(const PG8_LAS bf16x8*)(lds + PG8_SB(b, h) + boff + n * 2048 + k * 1024); } while (0)
; #define PG8_MMA(ai, bj, At, Bt) do { __builtin_amdgcn_s_setprio(1); _Pragma("unroll") for (int m = 0; m < 4; ++m) _Pragma("unroll") for (int n = 0; n < 2; ++n) _Pragma("unroll") for (int k = 0; k < 2; ++k) \
;         acc[ai][bj][m][n] = __builtin_amdgcn_mfma_f32_16x16x32_bf16(Bt[n][k], At[m][k], acc[ai][bj][m][n], 0, 0, 0); __builtin_amdgcn_s_setprio(0); } while (0)
; #define PG8_BAR __builtin_amdgcn_s_barrier()
; template <class Epi, class Sched, bool ALIGN_EPI = false, bool SP2 = false>
; __device__ __forceinline__ void gemm_phase(PG8_LAS unsigned char* lds, const Gemm g, const Sched& S, const Epi& E) {
;     ...
;         const bool has_next = S.next(ui + 1, nxt);
;         const char* nA = has_next ? (const char*)g.A + (size_t)nxt.pm * tstep : cA; const char* nB = has_next ? (const char*)g.Bt + (size_t)nxt.pn * tstep : cB;
;         for (int t = 0; t < nt; t += 2) {
;             const bool last = (t == nt - 2);
;             const char* a1 = cA + (size_t)(t + 1) * kstep;
;             const char* a2 = last ? nA : cA + (size_t)(t + 2) * kstep; const char* b2 = last ? nB : cB + (size_t)(t + 2) * kstep;
;             const char* a3 = a2 + kstep; const char* b3 = b2 + kstep;
;             if (last && has_next) S.a_ready(nxt);
;             if constexpr (SP2) {
;             PG8_LDB(B0, 0, 0); PG8_LDB(B1, 0, 1); PG8_SCHED; PG8_LDA(At, 0, 0); PG8_STAGE(PG8_SA(1, 1), a1 + hstep, voffA);
;             PG8_WAIT_V(8); PG8_WAIT_L(0); PG8_BAR; PG8_MMA(0, 0, At, B0); PG8_MMA(0, 1, At, B1); PG8_BAR; PG8_SCHED;
;             PG8_LDA(At, 0, 1); PG8_STAGE(PG8_SB(0, 0), b2, voffB); PG8_STAGE(PG8_SB(0, 1), b2 + hstep, voffB); PG8_STAGE(PG8_SA(0, 0), a2, voffA);
.LBB0_190:
	s_ashr_i32 s27, s26, 31
	s_lshl_b64 s[14:15], s[26:27], 19
	s_add_u32 s28, s22, s14
	s_addc_u32 s29, s23, s15
	s_and_b64 s[14:15], s[0:1], exec
	s_cselect_b32 s27, s29, s49
	s_cselect_b32 s67, s28, s48
	s_ashr_i32 s25, s24, 31
	s_lshl_b64 s[14:15], s[24:25], 19
	s_add_u32 s40, s94, s14
	s_addc_u32 s41, s96, s15
	s_and_b64 s[14:15], s[0:1], exec
	s_cselect_b32 s25, s41, s51
	s_cselect_b32 s86, s40, s50
	s_add_u32 s48, s48, 0x40080
	s_addc_u32 s49, s49, 0
	s_add_u32 s87, s50, 0x100
	s_addc_u32 s88, s51, 0
	s_mov_b32 s89, -2
	ds_read_b128 v[144:147], v155
	ds_read_b128 v[148:151], v155 offset:1024
	ds_read_b128 v[160:163], v155 offset:2048
	ds_read_b128 v[168:171], v155 offset:3072
	ds_read_b128 v[172:175], v156
	ds_read_b128 v[176:179], v156 offset:1024
	ds_read_b128 v[182:185], v156 offset:2048
	ds_read_b128 v[186:189], v156 offset:3072
	s_add_u32 s3, s48, 0xfffc0080
	s_addc_u32 s14, s49, -1
	s_cmp_eq_u32 s89, 12
	s_cselect_b32 s55, s27, s14
	s_cselect_b32 s54, s67, s3
	s_cselect_b32 s51, s25, s88
	s_cselect_b32 s50, s86, s87
	v_lshl_add_u64 v[164:165], s[48:49], 0, v[136:137]
	s_add_i32 m0, s45, 0xc000
	ds_read_b128 v[190:193], v157
	ds_read_b128 v[194:197], v157 offset:1024
	ds_read_b128 v[198:201], v157 offset:2048
	ds_read_b128 v[208:211], v157 offset:3072
	ds_read_b128 v[212:215], v157 offset:4096
	ds_read_b128 v[216:219], v157 offset:5120
	ds_read_b128 v[220:223], v157 offset:6144
	ds_read_b128 v[224:227], v157 offset:7168
	global_load_lds_dwordx4 v[164:165], off
	v_lshl_add_u64 v[164:165], s[48:49], 0, v[138:139]
	s_add_i32 m0, s45, 0xe000
	s_nop 0
	global_load_lds_dwordx4 v[164:165], off
	s_waitcnt vmcnt(8)
	s_waitcnt lgkmcnt(0)
	s_barrier
	s_setprio 1
	s_waitcnt lgkmcnt(0)
	v_mfma_f32_16x16x32_bf16 v[124:127], v[144:147], v[190:193], 0
	v_mfma_f32_16x16x32_bf16 v[120:123], v[160:163], v[190:193], 0
	v_mfma_f32_16x16x32_bf16 v[108:111], v[144:147], v[198:201], 0
	v_mfma_f32_16x16x32_bf16 v[104:107], v[160:163], v[198:201], 0
	v_mfma_f32_16x16x32_bf16 v[92:95], v[144:147], v[212:215], 0
	v_mfma_f32_16x16x32_bf16 v[88:91], v[160:163], v[212:215], 0
	v_mfma_f32_16x16x32_bf16 v[76:79], v[144:147], v[220:223], 0
	v_mfma_f32_16x16x32_bf16 v[72:75], v[160:163], v[220:223], 0
	v_mfma_f32_16x16x32_bf16 v[124:127], v[148:151], v[194:197], v[124:127]
	v_mfma_f32_16x16x32_bf16 v[120:123], v[168:171], v[194:197], v[120:123]
	v_mfma_f32_16x16x32_bf16 v[108:111], v[148:151], v[208:211], v[108:111]
	v_mfma_f32_16x16x32_bf16 v[104:107], v[168:171], v[208:211], v[104:107]
	v_mfma_f32_16x16x32_bf16 v[92:95], v[148:151], v[216:219], v[92:95]
	v_mfma_f32_16x16x32_bf16 v[88:91], v[168:171], v[216:219], v[88:91]
	v_mfma_f32_16x16x32_bf16 v[76:79], v[148:151], v[224:227], v[76:79]
	v_mfma_f32_16x16x32_bf16 v[72:75], v[168:171], v[224:227], v[72:75]
	s_setprio 0
	s_setprio 1
	v_mfma_f32_16x16x32_bf16 v[116:119], v[172:175], v[190:193], 0
	v_mfma_f32_16x16x32_bf16 v[112:115], v[182:185], v[190:193], 0
	v_mfma_f32_16x16x32_bf16 v[100:103], v[172:175], v[198:201], 0
	v_mfma_f32_16x16x32_bf16 v[96:99], v[182:185], v[198:201], 0
	v_mfma_f32_16x16x32_bf16 v[84:87], v[172:175], v[212:215], 0
	v_mfma_f32_16x16x32_bf16 v[80:83], v[182:185], v[212:215], 0
	v_mfma_f32_16x16x32_bf16 v[68:71], v[172:175], v[220:223], 0
	v_mfma_f32_16x16x32_bf16 v[64:67], v[182:185], v[220:223], 0
	v_mfma_f32_16x16x32_bf16 v[116:119], v[176:179], v[194:197], v[116:119]
	v_mfma_f32_16x16x32_bf16 v[112:115], v[186:189], v[194:197], v[112:115]
	v_mfma_f32_16x16x32_bf16 v[100:103], v[176:179], v[208:211], v[100:103]
	v_mfma_f32_16x16x32_bf16 v[96:99], v[186:189], v[208:211], v[96:99]
	v_mfma_f32_16x16x32_bf16 v[84:87], v[176:179], v[216:219], v[84:87]
	v_mfma_f32_16x16x32_bf16 v[80:83], v[186:189], v[216:219], v[80:83]
	v_mfma_f32_16x16x32_bf16 v[68:71], v[176:179], v[224:227], v[68:71]
	v_mfma_f32_16x16x32_bf16 v[64:67], v[186:189], v[224:227], v[64:67]
	s_setprio 0
	s_barrier
	s_add_i32 s3, s63, s43
	v_lshl_add_u64 v[164:165], s[50:51], 0, v[132:133]
	s_mov_b32 m0, s3
	ds_read_b128 v[190:193], v157 offset:16384
	ds_read_b128 v[194:197], v157 offset:17408
	ds_read_b128 v[198:201], v157 offset:18432
	ds_read_b128 v[208:211], v157 offset:19456
	ds_read_b128 v[212:215], v157 offset:20480
	ds_read_b128 v[216:219], v157 offset:21504
	ds_read_b128 v[220:223], v157 offset:22528
	ds_read_b128 v[224:227], v157 offset:23552
	global_load_lds_dwordx4 v[164:165], off
	s_add_i32 m0, s3, 0x2000
	s_add_u32 s14, s50, 0x40000
	v_lshl_add_u64 v[202:203], s[50:51], 0, v[128:129]
	s_addc_u32 s15, s51, 0
	s_add_i32 s3, s64, s43
	global_load_lds_dwordx4 v[202:203], off
	v_lshl_add_u64 v[228:229], s[14:15], 0, v[132:133]
	s_mov_b32 m0, s3
	global_load_lds_dwordx4 v[228:229], off
	v_lshl_add_u64 v[228:229], s[14:15], 0, v[128:129]
	s_add_i32 m0, s3, 0x2000
	s_nop 0
	global_load_lds_dwordx4 v[228:229], off
	s_waitcnt vmcnt(6)
	s_waitcnt lgkmcnt(0)
	s_barrier
; #define PG8_STAGE(bufoff, gbase, voff) do { _Pragma("unroll") for (int _i = 0; _i < 2; ++_i) \
;         __builtin_amdgcn_global_load_lds((const unsigned*)((const char*)(gbase) + (voff)[_i]), (PG8_LAS unsigned*)(lds + (bufoff) + ldsw + _i * 8192), 16, 0, 0); } while (0)
; #define PG8_LDA(dst, b, h) do { _Pragma("unroll") for (int m = 0; m < 4; ++m) _Pragma("unroll") for (int k = 0; k < 2; ++k) dst[m][k] = *(const PG8_LAS bf16x8*)(lds + PG8_SA(b, h) + aoff + m * 2048 + k * 1024); } while (0)
; #define PG8_LDB(dst, b, h) do { _Pragma("unroll") for (int n = 0; n < 2; ++n) _Pragma("unroll") for (int k = 0; k < 2; ++k) dst[n][k] = *(const PG8_LAS bf16x8*)(lds + PG8_SB(b, h) + boff + n * 2048 + k * 1024); } while (0)
; #define PG8_MMA(ai, bj, At, Bt) do { __builtin_amdgcn_s_setprio(1); _Pragma("unroll") for (int m = 0; m < 4; ++m) _Pragma("unroll") for (int n = 0; n < 2; ++n) _Pragma("unroll") for (int k = 0; k < 2; ++k) \
;         acc[ai][bj][m][n] = __builtin_amdgcn_mfma_f32_16x16x32_bf16(Bt[n][k], At[m][k], acc[ai][bj][m][n], 0, 0, 0); __builtin_amdgcn_s_setprio(0); } while (0)
; #define PG8_WAIT_V(n) asm volatile("s_waitcnt vmcnt(" #n ")" ::: "memory")
; #define PG8_WAIT_L(n) asm volatile("s_waitcnt lgkmcnt(" #n ")" ::: "memory")
; #define PG8_BAR __builtin_amdgcn_s_barrier()
; #define PG8_SCHED __builtin_amdgcn_sched_barrier(0)
; template <class Epi, class Sched, bool ALIGN_EPI = false, bool SP2 = false>
; __device__ __forceinline__ void gemm_phase(PG8_LAS unsigned char* lds, const Gemm g, const Sched& S, const Epi& E) {
;     ...
;             PG8_LDA(At, 0, 1); PG8_STAGE(PG8_SB(0, 0), b2, voffB); PG8_STAGE(PG8_SB(0, 1), b2 + hstep, voffB); PG8_STAGE(PG8_SA(0, 0), a2, voffA);
;             PG8_WAIT_V(8); PG8_WAIT_L(0); PG8_BAR; PG8_MMA(1, 0, At, B0); PG8_MMA(1, 1, At, B1); PG8_BAR; PG8_SCHED;
;             PG8_LDB(B0, 1, 0); PG8_LDB(B1, 1, 1); PG8_SCHED; PG8_LDA(At, 1, 0); PG8_STAGE(PG8_SA(0, 1), a2 + hstep, voffA);
;             PG8_WAIT_V(8); PG8_WAIT_L(0); PG8_BAR; PG8_MMA(0, 0, At, B0); PG8_MMA(0, 1, At, B1); PG8_BAR; PG8_SCHED;
	s_setprio 1
	s_waitcnt lgkmcnt(0)
	v_mfma_f32_16x16x32_bf16 v[60:63], v[144:147], v[190:193], 0
	v_mfma_f32_16x16x32_bf16 v[56:59], v[160:163], v[190:193], 0
	v_mfma_f32_16x16x32_bf16 v[44:47], v[144:147], v[198:201], 0
	v_mfma_f32_16x16x32_bf16 v[40:43], v[160:163], v[198:201], 0
	v_mfma_f32_16x16x32_bf16 v[28:31], v[144:147], v[212:215], 0
	v_mfma_f32_16x16x32_bf16 v[24:27], v[160:163], v[212:215], 0
	v_mfma_f32_16x16x32_bf16 v[12:15], v[144:147], v[220:223], 0
	v_mfma_f32_16x16x32_bf16 v[8:11], v[160:163], v[220:223], 0
	v_mfma_f32_16x16x32_bf16 v[60:63], v[148:151], v[194:197], v[60:63]
	v_mfma_f32_16x16x32_bf16 v[56:59], v[168:171], v[194:197], v[56:59]
	v_mfma_f32_16x16x32_bf16 v[44:47], v[148:151], v[208:211], v[44:47]
	v_mfma_f32_16x16x32_bf16 v[40:43], v[168:171], v[208:211], v[40:43]
	v_mfma_f32_16x16x32_bf16 v[28:31], v[148:151], v[216:219], v[28:31]
	v_mfma_f32_16x16x32_bf16 v[24:27], v[168:171], v[216:219], v[24:27]
	v_mfma_f32_16x16x32_bf16 v[12:15], v[148:151], v[224:227], v[12:15]
	v_lshl_add_u64 v[228:229], s[54:55], 0, v[134:135]
	s_mov_b32 m0, s45
	s_nop 0
	global_load_lds_dwordx4 v[228:229], off
	v_mfma_f32_16x16x32_bf16 v[8:11], v[168:171], v[224:227], v[8:11]
	s_setprio 0
	s_setprio 1
	v_mfma_f32_16x16x32_bf16 v[52:55], v[172:175], v[190:193], 0
	v_mfma_f32_16x16x32_bf16 v[48:51], v[182:185], v[190:193], 0
	v_mfma_f32_16x16x32_bf16 v[36:39], v[172:175], v[198:201], 0
	v_mfma_f32_16x16x32_bf16 v[32:35], v[182:185], v[198:201], 0
	v_mfma_f32_16x16x32_bf16 v[20:23], v[172:175], v[212:215], 0
	v_mfma_f32_16x16x32_bf16 v[16:19], v[182:185], v[212:215], 0
	v_mfma_f32_16x16x32_bf16 v[4:7], v[172:175], v[220:223], 0
	v_mfma_f32_16x16x32_bf16 v[0:3], v[182:185], v[220:223], 0
	v_mfma_f32_16x16x32_bf16 v[52:55], v[176:179], v[194:197], v[52:55]
	v_mfma_f32_16x16x32_bf16 v[48:51], v[186:189], v[194:197], v[48:51]
	v_mfma_f32_16x16x32_bf16 v[36:39], v[176:179], v[208:211], v[36:39]
	v_mfma_f32_16x16x32_bf16 v[32:35], v[186:189], v[208:211], v[32:35]
	v_mfma_f32_16x16x32_bf16 v[20:23], v[176:179], v[216:219], v[20:23]
	v_mfma_f32_16x16x32_bf16 v[16:19], v[186:189], v[216:219], v[16:19]
	v_mfma_f32_16x16x32_bf16 v[4:7], v[176:179], v[224:227], v[4:7]
	v_lshl_add_u64 v[230:231], s[54:55], 0, v[130:131]
	s_mov_b32 m0, s57
	s_nop 0
	global_load_lds_dwordx4 v[230:231], off
	v_mfma_f32_16x16x32_bf16 v[0:3], v[186:189], v[224:227], v[0:3]
	s_setprio 0
	s_barrier
	s_add_i32 s3, 0, 0x18000
	v_add_u32_e32 v159, s3, v153
	s_add_i32 s33, 0, 0x1c000
	ds_read_b128 v[144:147], v159
	ds_read_b128 v[148:151], v159 offset:1024
	ds_read_b128 v[160:163], v159 offset:2048
	ds_read_b128 v[168:171], v159 offset:3072
	v_add_u32_e32 v159, s33, v153
	ds_read_b128 v[172:175], v159
	ds_read_b128 v[176:179], v159 offset:1024
	ds_read_b128 v[182:185], v159 offset:2048
	ds_read_b128 v[186:189], v159 offset:3072
	s_add_u32 s14, s54, 0x40000
	s_addc_u32 s15, s55, 0
	s_mov_b32 m0, s58
	v_lshl_add_u64 v[232:233], s[14:15], 0, v[134:135]
	ds_read_b128 v[190:193], v157 offset:32768
	ds_read_b128 v[194:197], v157 offset:33792
	ds_read_b128 v[198:201], v157 offset:34816
	ds_read_b128 v[208:211], v157 offset:35840
	ds_read_b128 v[212:215], v157 offset:36864
	ds_read_b128 v[216:219], v157 offset:37888
	ds_read_b128 v[220:223], v157 offset:38912
	ds_read_b128 v[224:227], v157 offset:39936
	global_load_lds_dwordx4 v[232:233], off
	v_lshl_add_u64 v[232:233], s[14:15], 0, v[130:131]
	s_mov_b32 m0, s59
	s_nop 0
	global_load_lds_dwordx4 v[232:233], off
	s_waitcnt vmcnt(8)
	s_waitcnt lgkmcnt(0)
	s_barrier
	s_setprio 1
	s_waitcnt lgkmcnt(0)
	v_mfma_f32_16x16x32_bf16 v[124:127], v[144:147], v[190:193], v[124:127]
	v_mfma_f32_16x16x32_bf16 v[120:123], v[160:163], v[190:193], v[120:123]
	v_mfma_f32_16x16x32_bf16 v[108:111], v[144:147], v[198:201], v[108:111]
	v_mfma_f32_16x16x32_bf16 v[104:107], v[160:163], v[198:201], v[104:107]
	v_mfma_f32_16x16x32_bf16 v[92:95], v[144:147], v[212:215], v[92:95]
	v_mfma_f32_16x16x32_bf16 v[88:91], v[160:163], v[212:215], v[88:91]
	v_mfma_f32_16x16x32_bf16 v[76:79], v[144:147], v[220:223], v[76:79]
	v_mfma_f32_16x16x32_bf16 v[72:75], v[160:163], v[220:223], v[72:75]
	v_mfma_f32_16x16x32_bf16 v[124:127], v[148:151], v[194:197], v[124:127]
	v_mfma_f32_16x16x32_bf16 v[120:123], v[168:171], v[194:197], v[120:123]
	v_mfma_f32_16x16x32_bf16 v[108:111], v[148:151], v[208:211], v[108:111]
	v_mfma_f32_16x16x32_bf16 v[104:107], v[168:171], v[208:211], v[104:107]
	v_mfma_f32_16x16x32_bf16 v[92:95], v[148:151], v[216:219], v[92:95]
	v_mfma_f32_16x16x32_bf16 v[88:91], v[168:171], v[216:219], v[88:91]
	v_mfma_f32_16x16x32_bf16 v[76:79], v[148:151], v[224:227], v[76:79]
	v_mfma_f32_16x16x32_bf16 v[72:75], v[168:171], v[224:227], v[72:75]
	s_setprio 0
	s_setprio 1
	v_mfma_f32_16x16x32_bf16 v[116:119], v[172:175], v[190:193], v[116:119]
	v_mfma_f32_16x16x32_bf16 v[112:115], v[182:185], v[190:193], v[112:115]
	v_mfma_f32_16x16x32_bf16 v[100:103], v[172:175], v[198:201], v[100:103]
	v_mfma_f32_16x16x32_bf16 v[96:99], v[182:185], v[198:201], v[96:99]
	v_mfma_f32_16x16x32_bf16 v[84:87], v[172:175], v[212:215], v[84:87]
	v_mfma_f32_16x16x32_bf16 v[80:83], v[182:185], v[212:215], v[80:83]
	v_mfma_f32_16x16x32_bf16 v[68:71], v[172:175], v[220:223], v[68:71]
	v_mfma_f32_16x16x32_bf16 v[64:67], v[182:185], v[220:223], v[64:67]
	v_mfma_f32_16x16x32_bf16 v[116:119], v[176:179], v[194:197], v[116:119]
	v_mfma_f32_16x16x32_bf16 v[112:115], v[186:189], v[194:197], v[112:115]
	v_mfma_f32_16x16x32_bf16 v[100:103], v[176:179], v[208:211], v[100:103]
	v_mfma_f32_16x16x32_bf16 v[96:99], v[186:189], v[208:211], v[96:99]
	v_mfma_f32_16x16x32_bf16 v[84:87], v[176:179], v[216:219], v[84:87]
	v_mfma_f32_16x16x32_bf16 v[80:83], v[186:189], v[216:219], v[80:83]
	v_mfma_f32_16x16x32_bf16 v[68:71], v[176:179], v[224:227], v[68:71]
	v_mfma_f32_16x16x32_bf16 v[64:67], v[186:189], v[224:227], v[64:67]
	s_setprio 0
	s_barrier
; #define PG8_STAGE(bufoff, gbase, voff) do { _Pragma("unroll") for (int _i = 0; _i < 2; ++_i) \
;         __builtin_amdgcn_global_load_lds((const unsigned*)((const char*)(gbase) + (voff)[_i]), (PG8_LAS unsigned*)(lds + (bufoff) + ldsw + _i * 8192), 16, 0, 0); } while (0)
; #define PG8_LDA(dst, b, h) do { _Pragma("unroll") for (int m = 0; m < 4; ++m) _Pragma("unroll") for (int k = 0; k < 2; ++k) dst[m][k] = *(const PG8_LAS bf16x8*)(lds + PG8_SA(b, h) + aoff + m * 2048 + k * 1024); } while (0)
; #define PG8_LDB(dst, b, h) do { _Pragma("unroll") for (int n = 0; n < 2; ++n) _Pragma("unroll") for (int k = 0; k < 2; ++k) dst[n][k] = *(const PG8_LAS bf16x8*)(lds + PG8_SB(b, h) + boff + n * 2048 + k * 1024); } while (0)
; #define PG8_MMA(ai, bj, At, Bt) do { __builtin_amdgcn_s_setprio(1); _Pragma("unroll") for (int m = 0; m < 4; ++m) _Pragma("unroll") for (int n = 0; n < 2; ++n) _Pragma("unroll") for (int k = 0; k < 2; ++k) \
;         acc[ai][bj][m][n] = __builtin_amdgcn_mfma_f32_16x16x32_bf16(Bt[n][k], At[m][k], acc[ai][bj][m][n], 0, 0, 0); __builtin_amdgcn_s_setprio(0); } while (0)
; #define PG8_WAIT_V(n) asm volatile("s_waitcnt vmcnt(" #n ")" ::: "memory")
; #define PG8_WAIT_L(n) asm volatile("s_waitcnt lgkmcnt(" #n ")" ::: "memory")
; #define PG8_BAR __builtin_amdgcn_s_barrier()
; #define PG8_SCHED __builtin_amdgcn_sched_barrier(0)
; template <class Epi, class Sched, bool ALIGN_EPI = false, bool SP2 = false>
; __device__ __forceinline__ void gemm_phase(PG8_LAS unsigned char* lds, const Gemm g, const Sched& S, const Epi& E) {
;     ...
;             PG8_LDB(B0, 0, 0); PG8_LDB(B1, 0, 1); PG8_SCHED; PG8_LDA(At, 0, 0); PG8_STAGE(PG8_SA(1, 1), a1 + hstep, voffA);
;     ...
;             PG8_LDA(At, 1, 1); PG8_STAGE(PG8_SB(1, 0), b3, voffB); PG8_STAGE(PG8_SB(1, 1), b3 + hstep, voffB); PG8_STAGE(PG8_SA(1, 0), a3, voffA);
;             PG8_WAIT_V(8); PG8_WAIT_L(0); PG8_BAR; PG8_MMA(1, 0, At, B0); PG8_MMA(1, 1, At, B1); PG8_BAR; PG8_SCHED;
	s_add_i32 s3, s3, s43
	v_lshl_add_u64 v[164:165], v[164:165], 0, s[10:11]
	s_mov_b32 m0, s3
	ds_read_b128 v[190:193], v157 offset:49152
	ds_read_b128 v[194:197], v157 offset:50176
	ds_read_b128 v[198:201], v157 offset:51200
	ds_read_b128 v[208:211], v157 offset:52224
	ds_read_b128 v[212:215], v157 offset:53248
	ds_read_b128 v[216:219], v157 offset:54272
	ds_read_b128 v[220:223], v157 offset:55296
	ds_read_b128 v[224:227], v157 offset:56320
	global_load_lds_dwordx4 v[164:165], off
	s_add_i32 m0, s3, 0x2000
	s_add_u32 s14, s50, 0x40080
	v_lshl_add_u64 v[164:165], v[202:203], 0, s[10:11]
	s_addc_u32 s15, s51, 0
	s_add_i32 s3, s33, s43
	global_load_lds_dwordx4 v[164:165], off
	v_lshl_add_u64 v[164:165], s[14:15], 0, v[132:133]
	s_mov_b32 m0, s3
	s_nop 0
	global_load_lds_dwordx4 v[164:165], off
	v_lshl_add_u64 v[164:165], s[14:15], 0, v[128:129]
	s_add_i32 m0, s3, 0x2000
	s_nop 0
	global_load_lds_dwordx4 v[164:165], off
	s_waitcnt vmcnt(6)
	s_waitcnt lgkmcnt(0)
	s_barrier
	s_setprio 1
	s_waitcnt lgkmcnt(0)
	v_mfma_f32_16x16x32_bf16 v[60:63], v[144:147], v[190:193], v[60:63]
	v_mfma_f32_16x16x32_bf16 v[56:59], v[160:163], v[190:193], v[56:59]
	v_mfma_f32_16x16x32_bf16 v[44:47], v[144:147], v[198:201], v[44:47]
	v_mfma_f32_16x16x32_bf16 v[40:43], v[160:163], v[198:201], v[40:43]
	v_mfma_f32_16x16x32_bf16 v[28:31], v[144:147], v[212:215], v[28:31]
	v_mfma_f32_16x16x32_bf16 v[24:27], v[160:163], v[212:215], v[24:27]
	v_mfma_f32_16x16x32_bf16 v[12:15], v[144:147], v[220:223], v[12:15]
	v_mfma_f32_16x16x32_bf16 v[8:11], v[160:163], v[220:223], v[8:11]
	v_mfma_f32_16x16x32_bf16 v[60:63], v[148:151], v[194:197], v[60:63]
	v_mfma_f32_16x16x32_bf16 v[56:59], v[168:171], v[194:197], v[56:59]
	v_mfma_f32_16x16x32_bf16 v[44:47], v[148:151], v[208:211], v[44:47]
	v_mfma_f32_16x16x32_bf16 v[40:43], v[168:171], v[208:211], v[40:43]
	v_mfma_f32_16x16x32_bf16 v[28:31], v[148:151], v[216:219], v[28:31]
	v_mfma_f32_16x16x32_bf16 v[24:27], v[168:171], v[216:219], v[24:27]
	v_mfma_f32_16x16x32_bf16 v[12:15], v[148:151], v[224:227], v[12:15]
	v_lshl_add_u64 v[164:165], v[228:229], 0, s[10:11]
	s_mov_b32 m0, s61
	s_nop 0
	global_load_lds_dwordx4 v[164:165], off
	v_mfma_f32_16x16x32_bf16 v[8:11], v[168:171], v[224:227], v[8:11]
	s_setprio 0
	s_setprio 1
	v_mfma_f32_16x16x32_bf16 v[52:55], v[172:175], v[190:193], v[52:55]
	v_mfma_f32_16x16x32_bf16 v[48:51], v[182:185], v[190:193], v[48:51]
	v_mfma_f32_16x16x32_bf16 v[36:39], v[172:175], v[198:201], v[36:39]
	v_mfma_f32_16x16x32_bf16 v[32:35], v[182:185], v[198:201], v[32:35]
	v_mfma_f32_16x16x32_bf16 v[20:23], v[172:175], v[212:215], v[20:23]
	v_mfma_f32_16x16x32_bf16 v[16:19], v[182:185], v[212:215], v[16:19]
	v_mfma_f32_16x16x32_bf16 v[4:7], v[172:175], v[220:223], v[4:7]
	v_mfma_f32_16x16x32_bf16 v[0:3], v[182:185], v[220:223], v[0:3]
	v_mfma_f32_16x16x32_bf16 v[52:55], v[176:179], v[194:197], v[52:55]
	v_mfma_f32_16x16x32_bf16 v[48:51], v[186:189], v[194:197], v[48:51]
	v_mfma_f32_16x16x32_bf16 v[36:39], v[176:179], v[208:211], v[36:39]
	v_mfma_f32_16x16x32_bf16 v[32:35], v[186:189], v[208:211], v[32:35]
	v_mfma_f32_16x16x32_bf16 v[20:23], v[176:179], v[216:219], v[20:23]
	v_mfma_f32_16x16x32_bf16 v[16:19], v[186:189], v[216:219], v[16:19]
	v_mfma_f32_16x16x32_bf16 v[4:7], v[176:179], v[224:227], v[4:7]
	v_lshl_add_u64 v[164:165], v[230:231], 0, s[10:11]
	s_mov_b32 m0, s62
	s_nop 0
	global_load_lds_dwordx4 v[164:165], off
	v_mfma_f32_16x16x32_bf16 v[0:3], v[186:189], v[224:227], v[0:3]
	s_setprio 0
	s_barrier
	s_add_i32 s89, s89, 2
	s_add_u32 s48, s48, 0x100
	s_addc_u32 s49, s49, 0
	s_add_u32 s87, s87, 0x100
	s_addc_u32 s88, s88, 0
.LBB0_191:
	ds_read_b128 v[144:147], v155
	ds_read_b128 v[148:151], v155 offset:1024
	ds_read_b128 v[160:163], v155 offset:2048
	ds_read_b128 v[168:171], v155 offset:3072
	ds_read_b128 v[172:175], v156
	ds_read_b128 v[176:179], v156 offset:1024
	ds_read_b128 v[182:185], v156 offset:2048
	ds_read_b128 v[186:189], v156 offset:3072
	s_add_u32 s3, s48, 0xfffc0080
	s_addc_u32 s14, s49, -1
	s_cmp_eq_u32 s89, 12
	s_cselect_b32 s55, s27, s14
	s_cselect_b32 s54, s67, s3
	s_cselect_b32 s51, s25, s88
	s_cselect_b32 s50, s86, s87
	v_lshl_add_u64 v[164:165], s[48:49], 0, v[136:137]
	s_add_i32 m0, s45, 0xc000
	ds_read_b128 v[190:193], v157
	ds_read_b128 v[194:197], v157 offset:1024
	ds_read_b128 v[198:201], v157 offset:2048
	ds_read_b128 v[208:211], v157 offset:3072
	ds_read_b128 v[212:215], v157 offset:4096
	ds_read_b128 v[216:219], v157 offset:5120
	ds_read_b128 v[220:223], v157 offset:6144
	ds_read_b128 v[224:227], v157 offset:7168
	global_load_lds_dwordx4 v[164:165], off
	v_lshl_add_u64 v[164:165], s[48:49], 0, v[138:139]
	s_add_i32 m0, s45, 0xe000
	s_nop 0
	global_load_lds_dwordx4 v[164:165], off
	s_waitcnt vmcnt(8)
	s_waitcnt lgkmcnt(0)
	s_barrier
; #define PG8_STAGE(bufoff, gbase, voff) do { _Pragma("unroll") for (int _i = 0; _i < 2; ++_i) \
;         __builtin_amdgcn_global_load_lds((const unsigned*)((const char*)(gbase) + (voff)[_i]), (PG8_LAS unsigned*)(lds + (bufoff) + ldsw + _i * 8192), 16, 0, 0); } while (0)
; #define PG8_LDA(dst, b, h) do { _Pragma("unroll") for (int m = 0; m < 4; ++m) _Pragma("unroll") for (int k = 0; k < 2; ++k) dst[m][k] = *(const PG8_LAS bf16x8*)(lds + PG8_SA(b, h) + aoff + m * 2048 + k * 1024); } while (0)
; #define PG8_MMA(ai, bj, At, Bt) do { __builtin_amdgcn_s_setprio(1); _Pragma("unroll") for (int m = 0; m < 4; ++m) _Pragma("unroll") for (int n = 0; n < 2; ++n) _Pragma("unroll") for (int k = 0; k < 2; ++k) \
;         acc[ai][bj][m][n] = __builtin_amdgcn_mfma_f32_16x16x32_bf16(Bt[n][k], At[m][k], acc[ai][bj][m][n], 0, 0, 0); __builtin_amdgcn_s_setprio(0); } while (0)
; #define PG8_WAIT_V(n) asm volatile("s_waitcnt vmcnt(" #n ")" ::: "memory")
; #define PG8_WAIT_L(n) asm volatile("s_waitcnt lgkmcnt(" #n ")" ::: "memory")
; #define PG8_BAR __builtin_amdgcn_s_barrier()
; #define PG8_SCHED __builtin_amdgcn_sched_barrier(0)
; template <class Epi, class Sched, bool ALIGN_EPI = false, bool SP2 = false>
; __device__ __forceinline__ void gemm_phase(PG8_LAS unsigned char* lds, const Gemm g, const Sched& S, const Epi& E) {
;     ...
;             PG8_WAIT_V(8); PG8_WAIT_L(0); PG8_BAR; PG8_MMA(0, 0, At, B0); PG8_MMA(0, 1, At, B1); PG8_BAR; PG8_SCHED;
;             PG8_LDA(At, 0, 1); PG8_STAGE(PG8_SB(0, 0), b2, voffB); PG8_STAGE(PG8_SB(0, 1), b2 + hstep, voffB); PG8_STAGE(PG8_SA(0, 0), a2, voffA);
;             PG8_WAIT_V(8); PG8_WAIT_L(0); PG8_BAR; PG8_MMA(1, 0, At, B0); PG8_MMA(1, 1, At, B1); PG8_BAR; PG8_SCHED;
	s_setprio 1
	s_waitcnt lgkmcnt(0)
	v_mfma_f32_16x16x32_bf16 v[124:127], v[144:147], v[190:193], v[124:127]
	v_mfma_f32_16x16x32_bf16 v[120:123], v[160:163], v[190:193], v[120:123]
	v_mfma_f32_16x16x32_bf16 v[108:111], v[144:147], v[198:201], v[108:111]
	v_mfma_f32_16x16x32_bf16 v[104:107], v[160:163], v[198:201], v[104:107]
	v_mfma_f32_16x16x32_bf16 v[92:95], v[144:147], v[212:215], v[92:95]
	v_mfma_f32_16x16x32_bf16 v[88:91], v[160:163], v[212:215], v[88:91]
	v_mfma_f32_16x16x32_bf16 v[76:79], v[144:147], v[220:223], v[76:79]
	v_mfma_f32_16x16x32_bf16 v[72:75], v[160:163], v[220:223], v[72:75]
	v_mfma_f32_16x16x32_bf16 v[124:127], v[148:151], v[194:197], v[124:127]
	v_mfma_f32_16x16x32_bf16 v[120:123], v[168:171], v[194:197], v[120:123]
	v_mfma_f32_16x16x32_bf16 v[108:111], v[148:151], v[208:211], v[108:111]
	v_mfma_f32_16x16x32_bf16 v[104:107], v[168:171], v[208:211], v[104:107]
	v_mfma_f32_16x16x32_bf16 v[92:95], v[148:151], v[216:219], v[92:95]
	v_mfma_f32_16x16x32_bf16 v[88:91], v[168:171], v[216:219], v[88:91]
	v_mfma_f32_16x16x32_bf16 v[76:79], v[148:151], v[224:227], v[76:79]
	v_mfma_f32_16x16x32_bf16 v[72:75], v[168:171], v[224:227], v[72:75]
	s_setprio 0
	s_setprio 1
	v_mfma_f32_16x16x32_bf16 v[116:119], v[172:175], v[190:193], v[116:119]
	v_mfma_f32_16x16x32_bf16 v[112:115], v[182:185], v[190:193], v[112:115]
	v_mfma_f32_16x16x32_bf16 v[100:103], v[172:175], v[198:201], v[100:103]
	v_mfma_f32_16x16x32_bf16 v[96:99], v[182:185], v[198:201], v[96:99]
	v_mfma_f32_16x16x32_bf16 v[84:87], v[172:175], v[212:215], v[84:87]
	v_mfma_f32_16x16x32_bf16 v[80:83], v[182:185], v[212:215], v[80:83]
	v_mfma_f32_16x16x32_bf16 v[68:71], v[172:175], v[220:223], v[68:71]
	v_mfma_f32_16x16x32_bf16 v[64:67], v[182:185], v[220:223], v[64:67]
	v_mfma_f32_16x16x32_bf16 v[116:119], v[176:179], v[194:197], v[116:119]
	v_mfma_f32_16x16x32_bf16 v[112:115], v[186:189], v[194:197], v[112:115]
	v_mfma_f32_16x16x32_bf16 v[100:103], v[176:179], v[208:211], v[100:103]
	v_mfma_f32_16x16x32_bf16 v[96:99], v[186:189], v[208:211], v[96:99]
	v_mfma_f32_16x16x32_bf16 v[84:87], v[176:179], v[216:219], v[84:87]
	v_mfma_f32_16x16x32_bf16 v[80:83], v[186:189], v[216:219], v[80:83]
	v_mfma_f32_16x16x32_bf16 v[68:71], v[176:179], v[224:227], v[68:71]
	v_mfma_f32_16x16x32_bf16 v[64:67], v[186:189], v[224:227], v[64:67]
	s_setprio 0
	s_barrier
	s_add_i32 s3, s63, s43
	v_lshl_add_u64 v[164:165], s[50:51], 0, v[132:133]
	s_mov_b32 m0, s3
	ds_read_b128 v[190:193], v157 offset:16384
	ds_read_b128 v[194:197], v157 offset:17408
	ds_read_b128 v[198:201], v157 offset:18432
	ds_read_b128 v[208:211], v157 offset:19456
	ds_read_b128 v[212:215], v157 offset:20480
	ds_read_b128 v[216:219], v157 offset:21504
	ds_read_b128 v[220:223], v157 offset:22528
	ds_read_b128 v[224:227], v157 offset:23552
	global_load_lds_dwordx4 v[164:165], off
	s_add_i32 m0, s3, 0x2000
	s_add_u32 s14, s50, 0x40000
	v_lshl_add_u64 v[202:203], s[50:51], 0, v[128:129]
	s_addc_u32 s15, s51, 0
	s_add_i32 s3, s64, s43
	global_load_lds_dwordx4 v[202:203], off
	v_lshl_add_u64 v[228:229], s[14:15], 0, v[132:133]
	s_mov_b32 m0, s3
	global_load_lds_dwordx4 v[228:229], off
	v_lshl_add_u64 v[228:229], s[14:15], 0, v[128:129]
	s_add_i32 m0, s3, 0x2000
	s_nop 0
	global_load_lds_dwordx4 v[228:229], off
	s_waitcnt vmcnt(6)
	s_waitcnt lgkmcnt(0)
	s_barrier
	s_setprio 1
	s_waitcnt lgkmcnt(0)
	v_mfma_f32_16x16x32_bf16 v[60:63], v[144:147], v[190:193], v[60:63]
	v_mfma_f32_16x16x32_bf16 v[56:59], v[160:163], v[190:193], v[56:59]
	v_mfma_f32_16x16x32_bf16 v[44:47], v[144:147], v[198:201], v[44:47]
	v_mfma_f32_16x16x32_bf16 v[40:43], v[160:163], v[198:201], v[40:43]
	v_mfma_f32_16x16x32_bf16 v[28:31], v[144:147], v[212:215], v[28:31]
	v_mfma_f32_16x16x32_bf16 v[24:27], v[160:163], v[212:215], v[24:27]
	v_mfma_f32_16x16x32_bf16 v[12:15], v[144:147], v[220:223], v[12:15]
	v_mfma_f32_16x16x32_bf16 v[8:11], v[160:163], v[220:223], v[8:11]
	v_mfma_f32_16x16x32_bf16 v[60:63], v[148:151], v[194:197], v[60:63]
	v_mfma_f32_16x16x32_bf16 v[56:59], v[168:171], v[194:197], v[56:59]
	v_mfma_f32_16x16x32_bf16 v[44:47], v[148:151], v[208:211], v[44:47]
	v_mfma_f32_16x16x32_bf16 v[40:43], v[168:171], v[208:211], v[40:43]
	v_mfma_f32_16x16x32_bf16 v[28:31], v[148:151], v[216:219], v[28:31]
	v_mfma_f32_16x16x32_bf16 v[24:27], v[168:171], v[216:219], v[24:27]
	v_mfma_f32_16x16x32_bf16 v[12:15], v[148:151], v[224:227], v[12:15]
	v_lshl_add_u64 v[228:229], s[54:55], 0, v[134:135]
	s_mov_b32 m0, s45
	s_nop 0
	global_load_lds_dwordx4 v[228:229], off
	v_mfma_f32_16x16x32_bf16 v[8:11], v[168:171], v[224:227], v[8:11]
	s_setprio 0
	s_setprio 1
	v_mfma_f32_16x16x32_bf16 v[52:55], v[172:175], v[190:193], v[52:55]
	v_mfma_f32_16x16x32_bf16 v[48:51], v[182:185], v[190:193], v[48:51]
	v_mfma_f32_16x16x32_bf16 v[36:39], v[172:175], v[198:201], v[36:39]
	v_mfma_f32_16x16x32_bf16 v[32:35], v[182:185], v[198:201], v[32:35]
	v_mfma_f32_16x16x32_bf16 v[20:23], v[172:175], v[212:215], v[20:23]
	v_mfma_f32_16x16x32_bf16 v[16:19], v[182:185], v[212:215], v[16:19]
	v_mfma_f32_16x16x32_bf16 v[4:7], v[172:175], v[220:223], v[4:7]
	v_mfma_f32_16x16x32_bf16 v[0:3], v[182:185], v[220:223], v[0:3]
	v_mfma_f32_16x16x32_bf16 v[52:55], v[176:179], v[194:197], v[52:55]
	v_mfma_f32_16x16x32_bf16 v[48:51], v[186:189], v[194:197], v[48:51]
	v_mfma_f32_16x16x32_bf16 v[36:39], v[176:179], v[208:211], v[36:39]
	v_mfma_f32_16x16x32_bf16 v[32:35], v[186:189], v[208:211], v[32:35]
	v_mfma_f32_16x16x32_bf16 v[20:23], v[176:179], v[216:219], v[20:23]
	v_mfma_f32_16x16x32_bf16 v[16:19], v[186:189], v[216:219], v[16:19]
	v_mfma_f32_16x16x32_bf16 v[4:7], v[176:179], v[224:227], v[4:7]
	v_lshl_add_u64 v[230:231], s[54:55], 0, v[130:131]
	s_mov_b32 m0, s57
	s_nop 0
	global_load_lds_dwordx4 v[230:231], off
	v_mfma_f32_16x16x32_bf16 v[0:3], v[186:189], v[224:227], v[0:3]
	s_setprio 0
	s_barrier
; #define PG8_STAGE(bufoff, gbase, voff) do { _Pragma("unroll") for (int _i = 0; _i < 2; ++_i) \
;         __builtin_amdgcn_global_load_lds((const unsigned*)((const char*)(gbase) + (voff)[_i]), (PG8_LAS unsigned*)(lds + (bufoff) + ldsw + _i * 8192), 16, 0, 0); } while (0)
; #define PG8_LDA(dst, b, h) do { _Pragma("unroll") for (int m = 0; m < 4; ++m) _Pragma("unroll") for (int k = 0; k < 2; ++k) dst[m][k] = *(const PG8_LAS bf16x8*)(lds + PG8_SA(b, h) + aoff + m * 2048 + k * 1024); } while (0)
; #define PG8_LDB(dst, b, h) do { _Pragma("unroll") for (int n = 0; n < 2; ++n) _Pragma("unroll") for (int k = 0; k < 2; ++k) dst[n][k] = *(const PG8_LAS bf16x8*)(lds + PG8_SB(b, h) + boff + n * 2048 + k * 1024); } while (0)
; #define PG8_MMA(ai, bj, At, Bt) do { __builtin_amdgcn_s_setprio(1); _Pragma("unroll") for (int m = 0; m < 4; ++m) _Pragma("unroll") for (int n = 0; n < 2; ++n) _Pragma("unroll") for (int k = 0; k < 2; ++k) \
;         acc[ai][bj][m][n] = __builtin_amdgcn_mfma_f32_16x16x32_bf16(Bt[n][k], At[m][k], acc[ai][bj][m][n], 0, 0, 0); __builtin_amdgcn_s_setprio(0); } while (0)
; #define PG8_WAIT_V(n) asm volatile("s_waitcnt vmcnt(" #n ")" ::: "memory")
; #define PG8_WAIT_L(n) asm volatile("s_waitcnt lgkmcnt(" #n ")" ::: "memory")
; #define PG8_BAR __builtin_amdgcn_s_barrier()
; #define PG8_SCHED __builtin_amdgcn_sched_barrier(0)
; template <class Epi, class Sched, bool ALIGN_EPI = false, bool SP2 = false>
; __device__ __forceinline__ void gemm_phase(PG8_LAS unsigned char* lds, const Gemm g, const Sched& S, const Epi& E) {
;     ...
;             PG8_LDB(B0, 1, 0); PG8_LDB(B1, 1, 1); PG8_SCHED; PG8_LDA(At, 1, 0); PG8_STAGE(PG8_SA(0, 1), a2 + hstep, voffA);
;             PG8_WAIT_V(8); PG8_WAIT_L(0); PG8_BAR; PG8_MMA(0, 0, At, B0); PG8_MMA(0, 1, At, B1); PG8_BAR; PG8_SCHED;
	s_add_i32 s3, 0, 0x18000
	v_add_u32_e32 v159, s3, v153
	s_add_i32 s33, 0, 0x1c000
	ds_read_b128 v[144:147], v159
	ds_read_b128 v[148:151], v159 offset:1024
	ds_read_b128 v[160:163], v159 offset:2048
	ds_read_b128 v[168:171], v159 offset:3072
	v_add_u32_e32 v159, s33, v153
	ds_read_b128 v[172:175], v159
	ds_read_b128 v[176:179], v159 offset:1024
	ds_read_b128 v[182:185], v159 offset:2048
	ds_read_b128 v[186:189], v159 offset:3072
	s_add_u32 s14, s54, 0x40000
	s_addc_u32 s15, s55, 0
	s_mov_b32 m0, s58
	v_lshl_add_u64 v[232:233], s[14:15], 0, v[134:135]
	ds_read_b128 v[190:193], v157 offset:32768
	ds_read_b128 v[194:197], v157 offset:33792
	ds_read_b128 v[198:201], v157 offset:34816
	ds_read_b128 v[208:211], v157 offset:35840
	ds_read_b128 v[212:215], v157 offset:36864
	ds_read_b128 v[216:219], v157 offset:37888
	ds_read_b128 v[220:223], v157 offset:38912
	ds_read_b128 v[224:227], v157 offset:39936
	global_load_lds_dwordx4 v[232:233], off
	v_lshl_add_u64 v[232:233], s[14:15], 0, v[130:131]
	s_mov_b32 m0, s59
	s_nop 0
	global_load_lds_dwordx4 v[232:233], off
	s_waitcnt vmcnt(8)
	s_waitcnt lgkmcnt(0)
	s_barrier
	s_setprio 1
	s_waitcnt lgkmcnt(0)
	v_mfma_f32_16x16x32_bf16 v[124:127], v[144:147], v[190:193], v[124:127]
	v_mfma_f32_16x16x32_bf16 v[120:123], v[160:163], v[190:193], v[120:123]
	v_mfma_f32_16x16x32_bf16 v[108:111], v[144:147], v[198:201], v[108:111]
	v_mfma_f32_16x16x32_bf16 v[104:107], v[160:163], v[198:201], v[104:107]
	v_mfma_f32_16x16x32_bf16 v[92:95], v[144:147], v[212:215], v[92:95]
	v_mfma_f32_16x16x32_bf16 v[88:91], v[160:163], v[212:215], v[88:91]
	v_mfma_f32_16x16x32_bf16 v[76:79], v[144:147], v[220:223], v[76:79]
	v_mfma_f32_16x16x32_bf16 v[72:75], v[160:163], v[220:223], v[72:75]
	v_mfma_f32_16x16x32_bf16 v[124:127], v[148:151], v[194:197], v[124:127]
	v_mfma_f32_16x16x32_bf16 v[120:123], v[168:171], v[194:197], v[120:123]
	v_mfma_f32_16x16x32_bf16 v[108:111], v[148:151], v[208:211], v[108:111]
	v_mfma_f32_16x16x32_bf16 v[104:107], v[168:171], v[208:211], v[104:107]
	v_mfma_f32_16x16x32_bf16 v[92:95], v[148:151], v[216:219], v[92:95]
	v_mfma_f32_16x16x32_bf16 v[88:91], v[168:171], v[216:219], v[88:91]
	v_mfma_f32_16x16x32_bf16 v[76:79], v[148:151], v[224:227], v[76:79]
	v_mfma_f32_16x16x32_bf16 v[72:75], v[168:171], v[224:227], v[72:75]
	s_setprio 0
	s_setprio 1
	v_mfma_f32_16x16x32_bf16 v[116:119], v[172:175], v[190:193], v[116:119]
	v_mfma_f32_16x16x32_bf16 v[112:115], v[182:185], v[190:193], v[112:115]
	v_mfma_f32_16x16x32_bf16 v[100:103], v[172:175], v[198:201], v[100:103]
	v_mfma_f32_16x16x32_bf16 v[96:99], v[182:185], v[198:201], v[96:99]
	v_mfma_f32_16x16x32_bf16 v[84:87], v[172:175], v[212:215], v[84:87]
	v_mfma_f32_16x16x32_bf16 v[80:83], v[182:185], v[212:215], v[80:83]
	v_mfma_f32_16x16x32_bf16 v[68:71], v[172:175], v[220:223], v[68:71]
	v_mfma_f32_16x16x32_bf16 v[64:67], v[182:185], v[220:223], v[64:67]
	v_mfma_f32_16x16x32_bf16 v[116:119], v[176:179], v[194:197], v[116:119]
	v_mfma_f32_16x16x32_bf16 v[112:115], v[186:189], v[194:197], v[112:115]
	v_mfma_f32_16x16x32_bf16 v[100:103], v[176:179], v[208:211], v[100:103]
	v_mfma_f32_16x16x32_bf16 v[96:99], v[186:189], v[208:211], v[96:99]
	v_mfma_f32_16x16x32_bf16 v[84:87], v[176:179], v[216:219], v[84:87]
	v_mfma_f32_16x16x32_bf16 v[80:83], v[186:189], v[216:219], v[80:83]
	v_mfma_f32_16x16x32_bf16 v[68:71], v[176:179], v[224:227], v[68:71]
	v_mfma_f32_16x16x32_bf16 v[64:67], v[186:189], v[224:227], v[64:67]
	s_setprio 0
	s_barrier
; #define PG8_STAGE(bufoff, gbase, voff) do { _Pragma("unroll") for (int _i = 0; _i < 2; ++_i) \
;         __builtin_amdgcn_global_load_lds((const unsigned*)((const char*)(gbase) + (voff)[_i]), (PG8_LAS unsigned*)(lds + (bufoff) + ldsw + _i * 8192), 16, 0, 0); } while (0)
; #define PG8_LDA(dst, b, h) do { _Pragma("unroll") for (int m = 0; m < 4; ++m) _Pragma("unroll") for (int k = 0; k < 2; ++k) dst[m][k] = *(const PG8_LAS bf16x8*)(lds + PG8_SA(b, h) + aoff + m * 2048 + k * 1024); } while (0)
; #define PG8_MMA(ai, bj, At, Bt) do { __builtin_amdgcn_s_setprio(1); _Pragma("unroll") for (int m = 0; m < 4; ++m) _Pragma("unroll") for (int n = 0; n < 2; ++n) _Pragma("unroll") for (int k = 0; k < 2; ++k) \
;         acc[ai][bj][m][n] = __builtin_amdgcn_mfma_f32_16x16x32_bf16(Bt[n][k], At[m][k], acc[ai][bj][m][n], 0, 0, 0); __builtin_amdgcn_s_setprio(0); } while (0)
; #define PG8_WAIT_V(n) asm volatile("s_waitcnt vmcnt(" #n ")" ::: "memory")
; #define PG8_WAIT_L(n) asm volatile("s_waitcnt lgkmcnt(" #n ")" ::: "memory")
; #define PG8_BAR __builtin_amdgcn_s_barrier()
; #define PG8_SCHED __builtin_amdgcn_sched_barrier(0)
; __device__ __forceinline__ float row_rs(const float* ssp, int row) { const unsigned long long v = ((const unsigned long long*)ssp)[row];
;     return __builtin_amdgcn_rsqf((float)v * (1.0f / 4294967296.0f) * (1.0f / 1024.0f) + RMS_EPS); }
; template <class Epi, class Sched, bool ALIGN_EPI = false, bool SP2 = false>
; __device__ __forceinline__ void gemm_phase(PG8_LAS unsigned char* lds, const Gemm g, const Sched& S, const Epi& E) {
;     ...
;             PG8_LDA(At, 1, 1); PG8_STAGE(PG8_SB(1, 0), b3, voffB); PG8_STAGE(PG8_SB(1, 1), b3 + hstep, voffB); PG8_STAGE(PG8_SA(1, 0), a3, voffA);
;             PG8_WAIT_V(8); PG8_WAIT_L(0); PG8_BAR; PG8_MMA(1, 0, At, B0); PG8_MMA(1, 1, At, B1); PG8_BAR; PG8_SCHED;
	s_add_i32 s3, s3, s43
	v_lshl_add_u64 v[164:165], v[164:165], 0, s[10:11]
	s_mov_b32 m0, s3
	ds_read_b128 v[190:193], v157 offset:49152
	ds_read_b128 v[194:197], v157 offset:50176
	ds_read_b128 v[198:201], v157 offset:51200
	ds_read_b128 v[208:211], v157 offset:52224
	ds_read_b128 v[212:215], v157 offset:53248
	ds_read_b128 v[216:219], v157 offset:54272
	ds_read_b128 v[220:223], v157 offset:55296
	ds_read_b128 v[224:227], v157 offset:56320
	global_load_lds_dwordx4 v[164:165], off
	s_add_i32 m0, s3, 0x2000
	s_add_u32 s14, s50, 0x40080
	v_lshl_add_u64 v[164:165], v[202:203], 0, s[10:11]
	s_addc_u32 s15, s51, 0
	s_add_i32 s3, s33, s43
	global_load_lds_dwordx4 v[164:165], off
	v_lshl_add_u64 v[164:165], s[14:15], 0, v[132:133]
	s_mov_b32 m0, s3
	s_nop 0
	global_load_lds_dwordx4 v[164:165], off
	v_lshl_add_u64 v[164:165], s[14:15], 0, v[128:129]
	s_add_i32 m0, s3, 0x2000
	s_nop 0
	global_load_lds_dwordx4 v[164:165], off
	s_waitcnt vmcnt(6)
	s_waitcnt lgkmcnt(0)
	s_barrier
	s_setprio 1
	s_waitcnt lgkmcnt(0)
	v_mfma_f32_16x16x32_bf16 v[60:63], v[144:147], v[190:193], v[60:63]
	v_mfma_f32_16x16x32_bf16 v[56:59], v[160:163], v[190:193], v[56:59]
	v_mfma_f32_16x16x32_bf16 v[44:47], v[144:147], v[198:201], v[44:47]
	v_mfma_f32_16x16x32_bf16 v[40:43], v[160:163], v[198:201], v[40:43]
	v_mfma_f32_16x16x32_bf16 v[28:31], v[144:147], v[212:215], v[28:31]
	v_mfma_f32_16x16x32_bf16 v[24:27], v[160:163], v[212:215], v[24:27]
	v_mfma_f32_16x16x32_bf16 v[12:15], v[144:147], v[220:223], v[12:15]
	v_mfma_f32_16x16x32_bf16 v[8:11], v[160:163], v[220:223], v[8:11]
	v_mfma_f32_16x16x32_bf16 v[60:63], v[148:151], v[194:197], v[60:63]
	v_mfma_f32_16x16x32_bf16 v[56:59], v[168:171], v[194:197], v[56:59]
	v_mfma_f32_16x16x32_bf16 v[44:47], v[148:151], v[208:211], v[44:47]
	v_mfma_f32_16x16x32_bf16 v[40:43], v[168:171], v[208:211], v[40:43]
	v_mfma_f32_16x16x32_bf16 v[28:31], v[148:151], v[216:219], v[28:31]
	v_mfma_f32_16x16x32_bf16 v[24:27], v[168:171], v[216:219], v[24:27]
	v_mfma_f32_16x16x32_bf16 v[12:15], v[148:151], v[224:227], v[12:15]
	v_lshl_add_u64 v[164:165], v[228:229], 0, s[10:11]
	s_mov_b32 m0, s61
	s_nop 0
	global_load_lds_dwordx4 v[164:165], off
	v_mfma_f32_16x16x32_bf16 v[8:11], v[168:171], v[224:227], v[8:11]
	s_setprio 0
	s_setprio 1
	v_mfma_f32_16x16x32_bf16 v[52:55], v[172:175], v[190:193], v[52:55]
	v_mfma_f32_16x16x32_bf16 v[48:51], v[182:185], v[190:193], v[48:51]
	v_mfma_f32_16x16x32_bf16 v[36:39], v[172:175], v[198:201], v[36:39]
	v_mfma_f32_16x16x32_bf16 v[32:35], v[182:185], v[198:201], v[32:35]
	v_mfma_f32_16x16x32_bf16 v[20:23], v[172:175], v[212:215], v[20:23]
	v_mfma_f32_16x16x32_bf16 v[16:19], v[182:185], v[212:215], v[16:19]
	v_mfma_f32_16x16x32_bf16 v[4:7], v[172:175], v[220:223], v[4:7]
	v_mfma_f32_16x16x32_bf16 v[0:3], v[182:185], v[220:223], v[0:3]
	v_mfma_f32_16x16x32_bf16 v[52:55], v[176:179], v[194:197], v[52:55]
	v_mfma_f32_16x16x32_bf16 v[48:51], v[186:189], v[194:197], v[48:51]
	v_mfma_f32_16x16x32_bf16 v[36:39], v[176:179], v[208:211], v[36:39]
	v_mfma_f32_16x16x32_bf16 v[32:35], v[186:189], v[208:211], v[32:35]
	v_mfma_f32_16x16x32_bf16 v[20:23], v[176:179], v[216:219], v[20:23]
	v_mfma_f32_16x16x32_bf16 v[16:19], v[186:189], v[216:219], v[16:19]
	v_mfma_f32_16x16x32_bf16 v[4:7], v[176:179], v[224:227], v[4:7]
	v_lshl_add_u64 v[164:165], v[230:231], 0, s[10:11]
	s_mov_b32 m0, s62
	s_nop 0
	global_load_lds_dwordx4 v[164:165], off
	v_mfma_f32_16x16x32_bf16 v[0:3], v[186:189], v[224:227], v[0:3]
	s_setprio 0
	s_barrier
	s_add_i32 s89, s89, 2
	s_add_u32 s48, s48, 0x100
	s_addc_u32 s49, s49, 0
	s_add_u32 s87, s87, 0x100
	s_addc_u32 s88, s88, 0
	s_cmp_gt_u32 s89, 13
	s_cbranch_scc0 .LBB0_191
	v_lshl_add_u32 v144, s44, 8, v152
	v_ashrrev_i32_e32 v145, 31, v144
	v_lshl_add_u64 v[150:151], v[144:145], 3, s[6:7]
	global_load_dwordx2 v[182:183], v[150:151], off
	global_load_dwordx2 v[184:185], v[150:151], off offset:128
	global_load_dwordx2 v[186:187], v[150:151], off offset:256
	global_load_dwordx2 v[188:189], v[150:151], off offset:384
	global_load_dwordx2 v[190:191], v[150:151], off offset:1024
	global_load_dwordx2 v[192:193], v[150:151], off offset:1152
	global_load_dwordx2 v[194:195], v[150:151], off offset:1280
	global_load_dwordx2 v[196:197], v[150:151], off offset:1408
	s_and_b64 vcc, exec, s[16:17]
	s_cbranch_vccz .LBB0_194
	s_barrier

; #define PG8_STAGE(bufoff, gbase, voff) do { _Pragma("unroll") for (int _i = 0; _i < 2; ++_i) \
;         __builtin_amdgcn_global_load_lds((const unsigned*)((const char*)(gbase) + (voff)[_i]), (PG8_LAS unsigned*)(lds + (bufoff) + ldsw + _i * 8192), 16, 0, 0); } while (0)
; #define PG8_LDA(dst, b, h) do { _Pragma("unroll") for (int m = 0; m < 4; ++m) _Pragma("unroll") for (int k = 0; k < 2; ++k) dst[m][k] = *(const PG8_LAS bf16x8*)(lds + PG8_SA(b, h) + aoff + m * 2048 + k * 1024); } while (0)
; #define PG8_LDB(dst, b, h) do { _Pragma("unroll") for (int n = 0; n < 2; ++n) _Pragma("unroll") for (int k = 0; k < 2; ++k) dst[n][k] = *(const PG8_LAS bf16x8*)(lds + PG8_SB(b, h) + boff + n * 2048 + k * 1024); } while (0)
; #define PG8_MMA(ai, bj, At, Bt) do { __builtin_amdgcn_s_setprio(1); _Pragma("unroll") for (int m = 0; m < 4; ++m) _Pragma("unroll") for (int n = 0; n < 2; ++n) _Pragma("unroll") for (int k = 0; k < 2; ++k) \
;         acc[ai][bj][m][n] = __builtin_amdgcn_mfma_f32_16x16x32_bf16(Bt[n][k], At[m][k], acc[ai][bj][m][n], 0, 0, 0); __builtin_amdgcn_s_setprio(0); } while (0)
; #define PG8_WAIT_V(n) asm volatile("s_waitcnt vmcnt(" #n ")" ::: "memory")
; #define PG8_WAIT_L(n) asm volatile("s_waitcnt lgkmcnt(" #n ")" ::: "memory")
; #define PG8_BAR __builtin_amdgcn_s_barrier()
; template <class Epi, class Sched, bool ALIGN_EPI = false, bool SP2 = false>
; __device__ __forceinline__ void gemm_phase(PG8_LAS unsigned char* lds, const Gemm g, const Sched& S, const Epi& E) {
;     ...
;         const bool has_next = S.next(ui + 1, nxt);
;         const char* nA = has_next ? (const char*)g.A + (size_t)nxt.pm * tstep : cA; const char* nB = has_next ? (const char*)g.Bt + (size_t)nxt.pn * tstep : cB;
;         for (int t = 0; t < nt; t += 2) {
;             const bool last = (t == nt - 2);
;             const char* a1 = cA + (size_t)(t + 1) * kstep;
;             const char* a2 = last ? nA : cA + (size_t)(t + 2) * kstep; const char* b2 = last ? nB : cB + (size_t)(t + 2) * kstep;
;             const char* a3 = a2 + kstep; const char* b3 = b2 + kstep;
;             if (last && has_next) S.a_ready(nxt);
;             if constexpr (SP2) {
;             PG8_LDB(B0, 0, 0); PG8_LDB(B1, 0, 1); PG8_SCHED; PG8_LDA(At, 0, 0); PG8_STAGE(PG8_SA(1, 1), a1 + hstep, voffA);
;             PG8_WAIT_V(8); PG8_WAIT_L(0); PG8_BAR; PG8_MMA(0, 0, At, B0); PG8_MMA(0, 1, At, B1); PG8_BAR; PG8_SCHED;
.LBB0_268:
	s_add_u32 s91, s50, 0x100
	s_addc_u32 s92, s51, 0
	s_mov_b32 s93, -2
	s_waitcnt lgkmcnt(0)
	ds_read_b128 v[128:131], v165
	ds_read_b128 v[132:135], v165 offset:1024
	ds_read_b128 v[152:155], v165 offset:2048
	ds_read_b128 v[156:159], v165 offset:3072
	ds_read_b128 v[172:175], v168
	ds_read_b128 v[176:179], v168 offset:1024
	ds_read_b128 v[182:185], v168 offset:2048
	ds_read_b128 v[186:189], v168 offset:3072
	s_add_u32 s50, s10, 0x100
	s_addc_u32 s51, s11, 0
	s_cmp_eq_u32 s93, 40
	s_cselect_b32 s57, s1, s51
	s_cselect_b32 s56, s0, s50
	s_cselect_b32 s55, s49, s92
	s_cselect_b32 s54, s48, s91
	v_lshl_add_u64 v[160:161], s[10:11], 0, v[144:145]
	s_add_i32 m0, s58, 0xc000
	ds_read_b128 v[190:193], v169
	ds_read_b128 v[194:197], v169 offset:1024
	ds_read_b128 v[198:201], v169 offset:2048
	ds_read_b128 v[208:211], v169 offset:3072
	ds_read_b128 v[212:215], v169 offset:4096
	ds_read_b128 v[216:219], v169 offset:5120
	ds_read_b128 v[220:223], v169 offset:6144
	ds_read_b128 v[224:227], v169 offset:7168
	global_load_lds_dwordx4 v[160:161], off
	v_lshl_add_u64 v[160:161], s[10:11], 0, v[146:147]
	s_add_i32 m0, s58, 0xe000
	s_nop 0
	global_load_lds_dwordx4 v[160:161], off
	s_waitcnt vmcnt(8)
	s_waitcnt lgkmcnt(0)
	s_barrier
	s_setprio 1
	s_waitcnt lgkmcnt(0)
	v_mfma_f32_16x16x32_bf16 v[124:127], v[128:131], v[190:193], 0
	v_mfma_f32_16x16x32_bf16 v[120:123], v[152:155], v[190:193], 0
	v_mfma_f32_16x16x32_bf16 v[108:111], v[128:131], v[198:201], 0
	v_mfma_f32_16x16x32_bf16 v[104:107], v[152:155], v[198:201], 0
	v_mfma_f32_16x16x32_bf16 v[92:95], v[128:131], v[212:215], 0
	v_mfma_f32_16x16x32_bf16 v[88:91], v[152:155], v[212:215], 0
	v_mfma_f32_16x16x32_bf16 v[76:79], v[128:131], v[220:223], 0
	v_mfma_f32_16x16x32_bf16 v[72:75], v[152:155], v[220:223], 0
	v_mfma_f32_16x16x32_bf16 v[124:127], v[132:135], v[194:197], v[124:127]
	v_mfma_f32_16x16x32_bf16 v[120:123], v[156:159], v[194:197], v[120:123]
	v_mfma_f32_16x16x32_bf16 v[108:111], v[132:135], v[208:211], v[108:111]
	v_mfma_f32_16x16x32_bf16 v[104:107], v[156:159], v[208:211], v[104:107]
	v_mfma_f32_16x16x32_bf16 v[92:95], v[132:135], v[216:219], v[92:95]
	v_mfma_f32_16x16x32_bf16 v[88:91], v[156:159], v[216:219], v[88:91]
	v_mfma_f32_16x16x32_bf16 v[76:79], v[132:135], v[224:227], v[76:79]
	v_mfma_f32_16x16x32_bf16 v[72:75], v[156:159], v[224:227], v[72:75]
	s_setprio 0
	s_setprio 1
	v_mfma_f32_16x16x32_bf16 v[116:119], v[172:175], v[190:193], 0
	v_mfma_f32_16x16x32_bf16 v[112:115], v[182:185], v[190:193], 0
	v_mfma_f32_16x16x32_bf16 v[100:103], v[172:175], v[198:201], 0
	v_mfma_f32_16x16x32_bf16 v[96:99], v[182:185], v[198:201], 0
	v_mfma_f32_16x16x32_bf16 v[84:87], v[172:175], v[212:215], 0
	v_mfma_f32_16x16x32_bf16 v[80:83], v[182:185], v[212:215], 0
	v_mfma_f32_16x16x32_bf16 v[68:71], v[172:175], v[220:223], 0
	v_mfma_f32_16x16x32_bf16 v[64:67], v[182:185], v[220:223], 0
	v_mfma_f32_16x16x32_bf16 v[116:119], v[176:179], v[194:197], v[116:119]
	v_mfma_f32_16x16x32_bf16 v[112:115], v[186:189], v[194:197], v[112:115]
	v_mfma_f32_16x16x32_bf16 v[100:103], v[176:179], v[208:211], v[100:103]
	v_mfma_f32_16x16x32_bf16 v[96:99], v[186:189], v[208:211], v[96:99]
	v_mfma_f32_16x16x32_bf16 v[84:87], v[176:179], v[216:219], v[84:87]
	v_mfma_f32_16x16x32_bf16 v[80:83], v[186:189], v[216:219], v[80:83]
	v_mfma_f32_16x16x32_bf16 v[68:71], v[176:179], v[224:227], v[68:71]
	v_mfma_f32_16x16x32_bf16 v[64:67], v[186:189], v[224:227], v[64:67]
	s_setprio 0
	s_barrier
	s_add_i32 s3, s65, s43
	v_lshl_add_u64 v[160:161], s[54:55], 0, v[138:139]
	s_mov_b32 m0, s3
	ds_read_b128 v[190:193], v169 offset:16384
	ds_read_b128 v[194:197], v169 offset:17408
	ds_read_b128 v[198:201], v169 offset:18432
	ds_read_b128 v[208:211], v169 offset:19456
	ds_read_b128 v[212:215], v169 offset:20480
	ds_read_b128 v[216:219], v169 offset:21504
	ds_read_b128 v[220:223], v169 offset:22528
	ds_read_b128 v[224:227], v169 offset:23552
	global_load_lds_dwordx4 v[160:161], off
	s_add_i32 m0, s3, 0x2000
	s_add_u32 s10, s54, 0xb0000
	v_lshl_add_u64 v[202:203], s[54:55], 0, v[142:143]
	s_addc_u32 s11, s55, 0
	s_add_i32 s3, s66, s43
	global_load_lds_dwordx4 v[202:203], off
	v_lshl_add_u64 v[228:229], s[10:11], 0, v[138:139]
	s_mov_b32 m0, s3
	global_load_lds_dwordx4 v[228:229], off
	v_lshl_add_u64 v[228:229], s[10:11], 0, v[142:143]
	s_add_i32 m0, s3, 0x2000
	s_nop 0
	global_load_lds_dwordx4 v[228:229], off
	s_waitcnt vmcnt(6)
	s_waitcnt lgkmcnt(0)
	s_barrier
; #define PG8_STAGE(bufoff, gbase, voff) do { _Pragma("unroll") for (int _i = 0; _i < 2; ++_i) \
;         __builtin_amdgcn_global_load_lds((const unsigned*)((const char*)(gbase) + (voff)[_i]), (PG8_LAS unsigned*)(lds + (bufoff) + ldsw + _i * 8192), 16, 0, 0); } while (0)
; #define PG8_LDA(dst, b, h) do { _Pragma("unroll") for (int m = 0; m < 4; ++m) _Pragma("unroll") for (int k = 0; k < 2; ++k) dst[m][k] = *(const PG8_LAS bf16x8*)(lds + PG8_SA(b, h) + aoff + m * 2048 + k * 1024); } while (0)
; #define PG8_LDB(dst, b, h) do { _Pragma("unroll") for (int n = 0; n < 2; ++n) _Pragma("unroll") for (int k = 0; k < 2; ++k) dst[n][k] = *(const PG8_LAS bf16x8*)(lds + PG8_SB(b, h) + boff + n * 2048 + k * 1024); } while (0)
; #define PG8_MMA(ai, bj, At, Bt) do { __builtin_amdgcn_s_setprio(1); _Pragma("unroll") for (int m = 0; m < 4; ++m) _Pragma("unroll") for (int n = 0; n < 2; ++n) _Pragma("unroll") for (int k = 0; k < 2; ++k) \
;         acc[ai][bj][m][n] = __builtin_amdgcn_mfma_f32_16x16x32_bf16(Bt[n][k], At[m][k], acc[ai][bj][m][n], 0, 0, 0); __builtin_amdgcn_s_setprio(0); } while (0)
; #define PG8_WAIT_V(n) asm volatile("s_waitcnt vmcnt(" #n ")" ::: "memory")
; #define PG8_WAIT_L(n) asm volatile("s_waitcnt lgkmcnt(" #n ")" ::: "memory")
; #define PG8_BAR __builtin_amdgcn_s_barrier()
; #define PG8_SCHED __builtin_amdgcn_sched_barrier(0)
; template <class Epi, class Sched, bool ALIGN_EPI = false, bool SP2 = false>
; __device__ __forceinline__ void gemm_phase(PG8_LAS unsigned char* lds, const Gemm g, const Sched& S, const Epi& E) {
;     ...
;             PG8_WAIT_V(8); PG8_WAIT_L(0); PG8_BAR; PG8_MMA(1, 0, At, B0); PG8_MMA(1, 1, At, B1); PG8_BAR; PG8_SCHED;
;             PG8_LDB(B0, 1, 0); PG8_LDB(B1, 1, 1); PG8_SCHED; PG8_LDA(At, 1, 0); PG8_STAGE(PG8_SA(0, 1), a2 + hstep, voffA);
;             PG8_WAIT_V(8); PG8_WAIT_L(0); PG8_BAR; PG8_MMA(0, 0, At, B0); PG8_MMA(0, 1, At, B1); PG8_BAR; PG8_SCHED;
	s_setprio 1
	s_waitcnt lgkmcnt(0)
	v_mfma_f32_16x16x32_bf16 v[60:63], v[128:131], v[190:193], 0
	v_mfma_f32_16x16x32_bf16 v[56:59], v[152:155], v[190:193], 0
	v_mfma_f32_16x16x32_bf16 v[44:47], v[128:131], v[198:201], 0
	v_mfma_f32_16x16x32_bf16 v[40:43], v[152:155], v[198:201], 0
	v_mfma_f32_16x16x32_bf16 v[28:31], v[128:131], v[212:215], 0
	v_mfma_f32_16x16x32_bf16 v[24:27], v[152:155], v[212:215], 0
	v_mfma_f32_16x16x32_bf16 v[12:15], v[128:131], v[220:223], 0
	v_mfma_f32_16x16x32_bf16 v[8:11], v[152:155], v[220:223], 0
	v_mfma_f32_16x16x32_bf16 v[60:63], v[132:135], v[194:197], v[60:63]
	v_mfma_f32_16x16x32_bf16 v[56:59], v[156:159], v[194:197], v[56:59]
	v_mfma_f32_16x16x32_bf16 v[44:47], v[132:135], v[208:211], v[44:47]
	v_mfma_f32_16x16x32_bf16 v[40:43], v[156:159], v[208:211], v[40:43]
	v_mfma_f32_16x16x32_bf16 v[28:31], v[132:135], v[216:219], v[28:31]
	v_mfma_f32_16x16x32_bf16 v[24:27], v[156:159], v[216:219], v[24:27]
	v_mfma_f32_16x16x32_bf16 v[12:15], v[132:135], v[224:227], v[12:15]
	v_lshl_add_u64 v[228:229], s[56:57], 0, v[136:137]
	s_mov_b32 m0, s58
	s_nop 0
	global_load_lds_dwordx4 v[228:229], off
	v_mfma_f32_16x16x32_bf16 v[8:11], v[156:159], v[224:227], v[8:11]
	s_setprio 0
	s_setprio 1
	v_mfma_f32_16x16x32_bf16 v[52:55], v[172:175], v[190:193], 0
	v_mfma_f32_16x16x32_bf16 v[48:51], v[182:185], v[190:193], 0
	v_mfma_f32_16x16x32_bf16 v[36:39], v[172:175], v[198:201], 0
	v_mfma_f32_16x16x32_bf16 v[32:35], v[182:185], v[198:201], 0
	v_mfma_f32_16x16x32_bf16 v[20:23], v[172:175], v[212:215], 0
	v_mfma_f32_16x16x32_bf16 v[16:19], v[182:185], v[212:215], 0
	v_mfma_f32_16x16x32_bf16 v[4:7], v[172:175], v[220:223], 0
	v_mfma_f32_16x16x32_bf16 v[0:3], v[182:185], v[220:223], 0
	v_mfma_f32_16x16x32_bf16 v[52:55], v[176:179], v[194:197], v[52:55]
	v_mfma_f32_16x16x32_bf16 v[48:51], v[186:189], v[194:197], v[48:51]
	v_mfma_f32_16x16x32_bf16 v[36:39], v[176:179], v[208:211], v[36:39]
	v_mfma_f32_16x16x32_bf16 v[32:35], v[186:189], v[208:211], v[32:35]
	v_mfma_f32_16x16x32_bf16 v[20:23], v[176:179], v[216:219], v[20:23]
	v_mfma_f32_16x16x32_bf16 v[16:19], v[186:189], v[216:219], v[16:19]
	v_mfma_f32_16x16x32_bf16 v[4:7], v[176:179], v[224:227], v[4:7]
	v_lshl_add_u64 v[230:231], s[56:57], 0, v[140:141]
	s_mov_b32 m0, s59
	s_nop 0
	global_load_lds_dwordx4 v[230:231], off
	v_mfma_f32_16x16x32_bf16 v[0:3], v[186:189], v[224:227], v[0:3]
	s_setprio 0
	s_barrier
	s_add_i32 s3, 0, 0x18000
	s_add_i32 s14, 0, 0x1c000
	v_add_u32_e32 v156, s3, v163
	v_add_u32_e32 v171, s14, v163
	ds_read_b128 v[128:131], v156
	ds_read_b128 v[132:135], v156 offset:1024
	ds_read_b128 v[152:155], v156 offset:2048
	ds_read_b128 v[156:159], v156 offset:3072
	ds_read_b128 v[172:175], v171
	ds_read_b128 v[176:179], v171 offset:1024
	ds_read_b128 v[182:185], v171 offset:2048
	ds_read_b128 v[186:189], v171 offset:3072
	s_add_u32 s10, s56, 0xb0000
	s_addc_u32 s11, s57, 0
	s_mov_b32 m0, s60
	v_lshl_add_u64 v[232:233], s[10:11], 0, v[136:137]
	ds_read_b128 v[190:193], v169 offset:32768
	ds_read_b128 v[194:197], v169 offset:33792
	ds_read_b128 v[198:201], v169 offset:34816
	ds_read_b128 v[208:211], v169 offset:35840
	ds_read_b128 v[212:215], v169 offset:36864
	ds_read_b128 v[216:219], v169 offset:37888
	ds_read_b128 v[220:223], v169 offset:38912
	ds_read_b128 v[224:227], v169 offset:39936
	global_load_lds_dwordx4 v[232:233], off
	v_lshl_add_u64 v[232:233], s[10:11], 0, v[140:141]
	s_mov_b32 m0, s61
	s_nop 0
	global_load_lds_dwordx4 v[232:233], off
	s_waitcnt vmcnt(8)
	s_waitcnt lgkmcnt(0)
	s_barrier
	s_setprio 1
	s_waitcnt lgkmcnt(0)
	v_mfma_f32_16x16x32_bf16 v[124:127], v[128:131], v[190:193], v[124:127]
	v_mfma_f32_16x16x32_bf16 v[120:123], v[152:155], v[190:193], v[120:123]
	v_mfma_f32_16x16x32_bf16 v[108:111], v[128:131], v[198:201], v[108:111]
	v_mfma_f32_16x16x32_bf16 v[104:107], v[152:155], v[198:201], v[104:107]
	v_mfma_f32_16x16x32_bf16 v[92:95], v[128:131], v[212:215], v[92:95]
	v_mfma_f32_16x16x32_bf16 v[88:91], v[152:155], v[212:215], v[88:91]
	v_mfma_f32_16x16x32_bf16 v[76:79], v[128:131], v[220:223], v[76:79]
	v_mfma_f32_16x16x32_bf16 v[72:75], v[152:155], v[220:223], v[72:75]
	v_mfma_f32_16x16x32_bf16 v[124:127], v[132:135], v[194:197], v[124:127]
	v_mfma_f32_16x16x32_bf16 v[120:123], v[156:159], v[194:197], v[120:123]
	v_mfma_f32_16x16x32_bf16 v[108:111], v[132:135], v[208:211], v[108:111]
	v_mfma_f32_16x16x32_bf16 v[104:107], v[156:159], v[208:211], v[104:107]
	v_mfma_f32_16x16x32_bf16 v[92:95], v[132:135], v[216:219], v[92:95]
	v_mfma_f32_16x16x32_bf16 v[88:91], v[156:159], v[216:219], v[88:91]
	v_mfma_f32_16x16x32_bf16 v[76:79], v[132:135], v[224:227], v[76:79]
	v_mfma_f32_16x16x32_bf16 v[72:75], v[156:159], v[224:227], v[72:75]
	s_setprio 0
	s_setprio 1
	v_mfma_f32_16x16x32_bf16 v[116:119], v[172:175], v[190:193], v[116:119]
	v_mfma_f32_16x16x32_bf16 v[112:115], v[182:185], v[190:193], v[112:115]
	v_mfma_f32_16x16x32_bf16 v[100:103], v[172:175], v[198:201], v[100:103]
	v_mfma_f32_16x16x32_bf16 v[96:99], v[182:185], v[198:201], v[96:99]
	v_mfma_f32_16x16x32_bf16 v[84:87], v[172:175], v[212:215], v[84:87]
	v_mfma_f32_16x16x32_bf16 v[80:83], v[182:185], v[212:215], v[80:83]
	v_mfma_f32_16x16x32_bf16 v[68:71], v[172:175], v[220:223], v[68:71]
	v_mfma_f32_16x16x32_bf16 v[64:67], v[182:185], v[220:223], v[64:67]
	v_mfma_f32_16x16x32_bf16 v[116:119], v[176:179], v[194:197], v[116:119]
	v_mfma_f32_16x16x32_bf16 v[112:115], v[186:189], v[194:197], v[112:115]
	v_mfma_f32_16x16x32_bf16 v[100:103], v[176:179], v[208:211], v[100:103]
	v_mfma_f32_16x16x32_bf16 v[96:99], v[186:189], v[208:211], v[96:99]
	v_mfma_f32_16x16x32_bf16 v[84:87], v[176:179], v[216:219], v[84:87]
	v_mfma_f32_16x16x32_bf16 v[80:83], v[186:189], v[216:219], v[80:83]
	v_mfma_f32_16x16x32_bf16 v[68:71], v[176:179], v[224:227], v[68:71]
	v_mfma_f32_16x16x32_bf16 v[64:67], v[186:189], v[224:227], v[64:67]
	s_setprio 0
	s_barrier
; #define PG8_STAGE(bufoff, gbase, voff) do { _Pragma("unroll") for (int _i = 0; _i < 2; ++_i) \
;         __builtin_amdgcn_global_load_lds((const unsigned*)((const char*)(gbase) + (voff)[_i]), (PG8_LAS unsigned*)(lds + (bufoff) + ldsw + _i * 8192), 16, 0, 0); } while (0)
; #define PG8_LDA(dst, b, h) do { _Pragma("unroll") for (int m = 0; m < 4; ++m) _Pragma("unroll") for (int k = 0; k < 2; ++k) dst[m][k] = *(const PG8_LAS bf16x8*)(lds + PG8_SA(b, h) + aoff + m * 2048 + k * 1024); } while (0)
; #define PG8_LDB(dst, b, h) do { _Pragma("unroll") for (int n = 0; n < 2; ++n) _Pragma("unroll") for (int k = 0; k < 2; ++k) dst[n][k] = *(const PG8_LAS bf16x8*)(lds + PG8_SB(b, h) + boff + n * 2048 + k * 1024); } while (0)
; #define PG8_MMA(ai, bj, At, Bt) do { __builtin_amdgcn_s_setprio(1); _Pragma("unroll") for (int m = 0; m < 4; ++m) _Pragma("unroll") for (int n = 0; n < 2; ++n) _Pragma("unroll") for (int k = 0; k < 2; ++k) \
;         acc[ai][bj][m][n] = __builtin_amdgcn_mfma_f32_16x16x32_bf16(Bt[n][k], At[m][k], acc[ai][bj][m][n], 0, 0, 0); __builtin_amdgcn_s_setprio(0); } while (0)
; #define PG8_WAIT_V(n) asm volatile("s_waitcnt vmcnt(" #n ")" ::: "memory")
; #define PG8_WAIT_L(n) asm volatile("s_waitcnt lgkmcnt(" #n ")" ::: "memory")
; #define PG8_BAR __builtin_amdgcn_s_barrier()
; #define PG8_SCHED __builtin_amdgcn_sched_barrier(0)
; template <class Epi, class Sched, bool ALIGN_EPI = false, bool SP2 = false>
; __device__ __forceinline__ void gemm_phase(PG8_LAS unsigned char* lds, const Gemm g, const Sched& S, const Epi& E) {
;     ...
;         for (int t = 0; t < nt; t += 2) {
;     ...
;             PG8_LDB(B0, 0, 0); PG8_LDB(B1, 0, 1); PG8_SCHED; PG8_LDA(At, 0, 0); PG8_STAGE(PG8_SA(1, 1), a1 + hstep, voffA);
;     ...
;             PG8_LDA(At, 1, 1); PG8_STAGE(PG8_SB(1, 0), b3, voffB); PG8_STAGE(PG8_SB(1, 1), b3 + hstep, voffB); PG8_STAGE(PG8_SA(1, 0), a3, voffA);
;             PG8_WAIT_V(8); PG8_WAIT_L(0); PG8_BAR; PG8_MMA(1, 0, At, B0); PG8_MMA(1, 1, At, B1); PG8_BAR; PG8_SCHED;
	s_add_i32 s3, s3, s43
	v_lshl_add_u64 v[160:161], v[160:161], 0, s[40:41]
	s_mov_b32 m0, s3
	ds_read_b128 v[190:193], v169 offset:49152
	ds_read_b128 v[194:197], v169 offset:50176
	ds_read_b128 v[198:201], v169 offset:51200
	ds_read_b128 v[208:211], v169 offset:52224
	ds_read_b128 v[212:215], v169 offset:53248
	ds_read_b128 v[216:219], v169 offset:54272
	ds_read_b128 v[220:223], v169 offset:55296
	ds_read_b128 v[224:227], v169 offset:56320
	global_load_lds_dwordx4 v[160:161], off
	s_add_i32 m0, s3, 0x2000
	s_add_u32 s10, s54, 0xb0080
	v_lshl_add_u64 v[160:161], v[202:203], 0, s[40:41]
	s_addc_u32 s11, s55, 0
	s_add_i32 s3, s14, s43
	global_load_lds_dwordx4 v[160:161], off
	v_lshl_add_u64 v[160:161], s[10:11], 0, v[138:139]
	s_mov_b32 m0, s3
	s_nop 0
	global_load_lds_dwordx4 v[160:161], off
	v_lshl_add_u64 v[160:161], s[10:11], 0, v[142:143]
	s_add_i32 m0, s3, 0x2000
	s_nop 0
	global_load_lds_dwordx4 v[160:161], off
	s_waitcnt vmcnt(6)
	s_waitcnt lgkmcnt(0)
	s_barrier
	s_setprio 1
	s_waitcnt lgkmcnt(0)
	v_mfma_f32_16x16x32_bf16 v[60:63], v[128:131], v[190:193], v[60:63]
	v_mfma_f32_16x16x32_bf16 v[56:59], v[152:155], v[190:193], v[56:59]
	v_mfma_f32_16x16x32_bf16 v[44:47], v[128:131], v[198:201], v[44:47]
	v_mfma_f32_16x16x32_bf16 v[40:43], v[152:155], v[198:201], v[40:43]
	v_mfma_f32_16x16x32_bf16 v[28:31], v[128:131], v[212:215], v[28:31]
	v_mfma_f32_16x16x32_bf16 v[24:27], v[152:155], v[212:215], v[24:27]
	v_mfma_f32_16x16x32_bf16 v[12:15], v[128:131], v[220:223], v[12:15]
	v_mfma_f32_16x16x32_bf16 v[8:11], v[152:155], v[220:223], v[8:11]
	v_mfma_f32_16x16x32_bf16 v[60:63], v[132:135], v[194:197], v[60:63]
	v_mfma_f32_16x16x32_bf16 v[56:59], v[156:159], v[194:197], v[56:59]
	v_mfma_f32_16x16x32_bf16 v[44:47], v[132:135], v[208:211], v[44:47]
	v_mfma_f32_16x16x32_bf16 v[40:43], v[156:159], v[208:211], v[40:43]
	v_mfma_f32_16x16x32_bf16 v[28:31], v[132:135], v[216:219], v[28:31]
	v_mfma_f32_16x16x32_bf16 v[24:27], v[156:159], v[216:219], v[24:27]
	v_mfma_f32_16x16x32_bf16 v[12:15], v[132:135], v[224:227], v[12:15]
	v_lshl_add_u64 v[160:161], v[228:229], 0, s[40:41]
	s_mov_b32 m0, s63
	s_nop 0
	global_load_lds_dwordx4 v[160:161], off
	v_mfma_f32_16x16x32_bf16 v[8:11], v[156:159], v[224:227], v[8:11]
	s_setprio 0
	s_setprio 1
	v_mfma_f32_16x16x32_bf16 v[52:55], v[172:175], v[190:193], v[52:55]
	v_mfma_f32_16x16x32_bf16 v[48:51], v[182:185], v[190:193], v[48:51]
	v_mfma_f32_16x16x32_bf16 v[36:39], v[172:175], v[198:201], v[36:39]
	v_mfma_f32_16x16x32_bf16 v[32:35], v[182:185], v[198:201], v[32:35]
	v_mfma_f32_16x16x32_bf16 v[20:23], v[172:175], v[212:215], v[20:23]
	v_mfma_f32_16x16x32_bf16 v[16:19], v[182:185], v[212:215], v[16:19]
	v_mfma_f32_16x16x32_bf16 v[4:7], v[172:175], v[220:223], v[4:7]
	v_mfma_f32_16x16x32_bf16 v[0:3], v[182:185], v[220:223], v[0:3]
	v_mfma_f32_16x16x32_bf16 v[52:55], v[176:179], v[194:197], v[52:55]
	v_mfma_f32_16x16x32_bf16 v[48:51], v[186:189], v[194:197], v[48:51]
	v_mfma_f32_16x16x32_bf16 v[36:39], v[176:179], v[208:211], v[36:39]
	v_mfma_f32_16x16x32_bf16 v[32:35], v[186:189], v[208:211], v[32:35]
	v_mfma_f32_16x16x32_bf16 v[20:23], v[176:179], v[216:219], v[20:23]
	v_mfma_f32_16x16x32_bf16 v[16:19], v[186:189], v[216:219], v[16:19]
	v_mfma_f32_16x16x32_bf16 v[4:7], v[176:179], v[224:227], v[4:7]
	v_lshl_add_u64 v[160:161], v[230:231], 0, s[40:41]
	s_mov_b32 m0, s64
	s_nop 0
	global_load_lds_dwordx4 v[160:161], off
	v_mfma_f32_16x16x32_bf16 v[0:3], v[186:189], v[224:227], v[0:3]
	s_setprio 0
	s_barrier
	s_add_i32 s93, s93, 2
	s_add_u32 s91, s91, 0x100
	s_addc_u32 s92, s92, 0
	s_mov_b64 s[10:11], s[50:51]
.LBB0_269:
	ds_read_b128 v[128:131], v165
	ds_read_b128 v[132:135], v165 offset:1024
	ds_read_b128 v[152:155], v165 offset:2048
	ds_read_b128 v[156:159], v165 offset:3072
	ds_read_b128 v[172:175], v168
	ds_read_b128 v[176:179], v168 offset:1024
	ds_read_b128 v[182:185], v168 offset:2048
	ds_read_b128 v[186:189], v168 offset:3072
	s_add_u32 s50, s10, 0x100
	s_addc_u32 s51, s11, 0
	s_cmp_eq_u32 s93, 40
	s_cselect_b32 s57, s1, s51
	s_cselect_b32 s56, s0, s50
	s_cselect_b32 s55, s49, s92
	s_cselect_b32 s54, s48, s91
	v_lshl_add_u64 v[160:161], s[10:11], 0, v[144:145]
	s_add_i32 m0, s58, 0xc000
	ds_read_b128 v[190:193], v169
	ds_read_b128 v[194:197], v169 offset:1024
	ds_read_b128 v[198:201], v169 offset:2048
	ds_read_b128 v[208:211], v169 offset:3072
	ds_read_b128 v[212:215], v169 offset:4096
	ds_read_b128 v[216:219], v169 offset:5120
	ds_read_b128 v[220:223], v169 offset:6144
	ds_read_b128 v[224:227], v169 offset:7168
	global_load_lds_dwordx4 v[160:161], off
	v_lshl_add_u64 v[160:161], s[10:11], 0, v[146:147]
	s_add_i32 m0, s58, 0xe000
	s_nop 0
	global_load_lds_dwordx4 v[160:161], off
	s_waitcnt vmcnt(8)
	s_waitcnt lgkmcnt(0)
	s_barrier
; #define PG8_STAGE(bufoff, gbase, voff) do { _Pragma("unroll") for (int _i = 0; _i < 2; ++_i) \
;         __builtin_amdgcn_global_load_lds((const unsigned*)((const char*)(gbase) + (voff)[_i]), (PG8_LAS unsigned*)(lds + (bufoff) + ldsw + _i * 8192), 16, 0, 0); } while (0)
; #define PG8_LDA(dst, b, h) do { _Pragma("unroll") for (int m = 0; m < 4; ++m) _Pragma("unroll") for (int k = 0; k < 2; ++k) dst[m][k] = *(const PG8_LAS bf16x8*)(lds + PG8_SA(b, h) + aoff + m * 2048 + k * 1024); } while (0)
; #define PG8_MMA(ai, bj, At, Bt) do { __builtin_amdgcn_s_setprio(1); _Pragma("unroll") for (int m = 0; m < 4; ++m) _Pragma("unroll") for (int n = 0; n < 2; ++n) _Pragma("unroll") for (int k = 0; k < 2; ++k) \
;         acc[ai][bj][m][n] = __builtin_amdgcn_mfma_f32_16x16x32_bf16(Bt[n][k], At[m][k], acc[ai][bj][m][n], 0, 0, 0); __builtin_amdgcn_s_setprio(0); } while (0)
; #define PG8_WAIT_V(n) asm volatile("s_waitcnt vmcnt(" #n ")" ::: "memory")
; #define PG8_WAIT_L(n) asm volatile("s_waitcnt lgkmcnt(" #n ")" ::: "memory")
; #define PG8_BAR __builtin_amdgcn_s_barrier()
; #define PG8_SCHED __builtin_amdgcn_sched_barrier(0)
; template <class Epi, class Sched, bool ALIGN_EPI = false, bool SP2 = false>
; __device__ __forceinline__ void gemm_phase(PG8_LAS unsigned char* lds, const Gemm g, const Sched& S, const Epi& E) {
;     ...
;             PG8_WAIT_V(8); PG8_WAIT_L(0); PG8_BAR; PG8_MMA(0, 0, At, B0); PG8_MMA(0, 1, At, B1); PG8_BAR; PG8_SCHED;
;             PG8_LDA(At, 0, 1); PG8_STAGE(PG8_SB(0, 0), b2, voffB); PG8_STAGE(PG8_SB(0, 1), b2 + hstep, voffB); PG8_STAGE(PG8_SA(0, 0), a2, voffA);
;             PG8_WAIT_V(8); PG8_WAIT_L(0); PG8_BAR; PG8_MMA(1, 0, At, B0); PG8_MMA(1, 1, At, B1); PG8_BAR; PG8_SCHED;
	s_setprio 1
	s_waitcnt lgkmcnt(0)
	v_mfma_f32_16x16x32_bf16 v[124:127], v[128:131], v[190:193], v[124:127]
	v_mfma_f32_16x16x32_bf16 v[120:123], v[152:155], v[190:193], v[120:123]
	v_mfma_f32_16x16x32_bf16 v[108:111], v[128:131], v[198:201], v[108:111]
	v_mfma_f32_16x16x32_bf16 v[104:107], v[152:155], v[198:201], v[104:107]
	v_mfma_f32_16x16x32_bf16 v[92:95], v[128:131], v[212:215], v[92:95]
	v_mfma_f32_16x16x32_bf16 v[88:91], v[152:155], v[212:215], v[88:91]
	v_mfma_f32_16x16x32_bf16 v[76:79], v[128:131], v[220:223], v[76:79]
	v_mfma_f32_16x16x32_bf16 v[72:75], v[152:155], v[220:223], v[72:75]
	v_mfma_f32_16x16x32_bf16 v[124:127], v[132:135], v[194:197], v[124:127]
	v_mfma_f32_16x16x32_bf16 v[120:123], v[156:159], v[194:197], v[120:123]
	v_mfma_f32_16x16x32_bf16 v[108:111], v[132:135], v[208:211], v[108:111]
	v_mfma_f32_16x16x32_bf16 v[104:107], v[156:159], v[208:211], v[104:107]
	v_mfma_f32_16x16x32_bf16 v[92:95], v[132:135], v[216:219], v[92:95]
	v_mfma_f32_16x16x32_bf16 v[88:91], v[156:159], v[216:219], v[88:91]
	v_mfma_f32_16x16x32_bf16 v[76:79], v[132:135], v[224:227], v[76:79]
	v_mfma_f32_16x16x32_bf16 v[72:75], v[156:159], v[224:227], v[72:75]
	s_setprio 0
	s_setprio 1
	v_mfma_f32_16x16x32_bf16 v[116:119], v[172:175], v[190:193], v[116:119]
	v_mfma_f32_16x16x32_bf16 v[112:115], v[182:185], v[190:193], v[112:115]
	v_mfma_f32_16x16x32_bf16 v[100:103], v[172:175], v[198:201], v[100:103]
	v_mfma_f32_16x16x32_bf16 v[96:99], v[182:185], v[198:201], v[96:99]
	v_mfma_f32_16x16x32_bf16 v[84:87], v[172:175], v[212:215], v[84:87]
	v_mfma_f32_16x16x32_bf16 v[80:83], v[182:185], v[212:215], v[80:83]
	v_mfma_f32_16x16x32_bf16 v[68:71], v[172:175], v[220:223], v[68:71]
	v_mfma_f32_16x16x32_bf16 v[64:67], v[182:185], v[220:223], v[64:67]
	v_mfma_f32_16x16x32_bf16 v[116:119], v[176:179], v[194:197], v[116:119]
	v_mfma_f32_16x16x32_bf16 v[112:115], v[186:189], v[194:197], v[112:115]
	v_mfma_f32_16x16x32_bf16 v[100:103], v[176:179], v[208:211], v[100:103]
	v_mfma_f32_16x16x32_bf16 v[96:99], v[186:189], v[208:211], v[96:99]
	v_mfma_f32_16x16x32_bf16 v[84:87], v[176:179], v[216:219], v[84:87]
	v_mfma_f32_16x16x32_bf16 v[80:83], v[186:189], v[216:219], v[80:83]
	v_mfma_f32_16x16x32_bf16 v[68:71], v[176:179], v[224:227], v[68:71]
	v_mfma_f32_16x16x32_bf16 v[64:67], v[186:189], v[224:227], v[64:67]
	s_setprio 0
	s_barrier
	s_add_i32 s3, s65, s43
	v_lshl_add_u64 v[160:161], s[54:55], 0, v[138:139]
	s_mov_b32 m0, s3
	ds_read_b128 v[190:193], v169 offset:16384
	ds_read_b128 v[194:197], v169 offset:17408
	ds_read_b128 v[198:201], v169 offset:18432
	ds_read_b128 v[208:211], v169 offset:19456
	ds_read_b128 v[212:215], v169 offset:20480
	ds_read_b128 v[216:219], v169 offset:21504
	ds_read_b128 v[220:223], v169 offset:22528
	ds_read_b128 v[224:227], v169 offset:23552
	global_load_lds_dwordx4 v[160:161], off
	s_add_i32 m0, s3, 0x2000
	s_add_u32 s10, s54, 0xb0000
	v_lshl_add_u64 v[202:203], s[54:55], 0, v[142:143]
	s_addc_u32 s11, s55, 0
	s_add_i32 s3, s66, s43
	global_load_lds_dwordx4 v[202:203], off
	v_lshl_add_u64 v[228:229], s[10:11], 0, v[138:139]
	s_mov_b32 m0, s3
	global_load_lds_dwordx4 v[228:229], off
	v_lshl_add_u64 v[228:229], s[10:11], 0, v[142:143]
	s_add_i32 m0, s3, 0x2000
	s_nop 0
	global_load_lds_dwordx4 v[228:229], off
	s_waitcnt vmcnt(6)
	s_waitcnt lgkmcnt(0)
	s_barrier
	s_setprio 1
	s_waitcnt lgkmcnt(0)
	v_mfma_f32_16x16x32_bf16 v[60:63], v[128:131], v[190:193], v[60:63]
	v_mfma_f32_16x16x32_bf16 v[56:59], v[152:155], v[190:193], v[56:59]
	v_mfma_f32_16x16x32_bf16 v[44:47], v[128:131], v[198:201], v[44:47]
	v_mfma_f32_16x16x32_bf16 v[40:43], v[152:155], v[198:201], v[40:43]
	v_mfma_f32_16x16x32_bf16 v[28:31], v[128:131], v[212:215], v[28:31]
	v_mfma_f32_16x16x32_bf16 v[24:27], v[152:155], v[212:215], v[24:27]
	v_mfma_f32_16x16x32_bf16 v[12:15], v[128:131], v[220:223], v[12:15]
	v_mfma_f32_16x16x32_bf16 v[8:11], v[152:155], v[220:223], v[8:11]
	v_mfma_f32_16x16x32_bf16 v[60:63], v[132:135], v[194:197], v[60:63]
	v_mfma_f32_16x16x32_bf16 v[56:59], v[156:159], v[194:197], v[56:59]
	v_mfma_f32_16x16x32_bf16 v[44:47], v[132:135], v[208:211], v[44:47]
	v_mfma_f32_16x16x32_bf16 v[40:43], v[156:159], v[208:211], v[40:43]
	v_mfma_f32_16x16x32_bf16 v[28:31], v[132:135], v[216:219], v[28:31]
	v_mfma_f32_16x16x32_bf16 v[24:27], v[156:159], v[216:219], v[24:27]
	v_mfma_f32_16x16x32_bf16 v[12:15], v[132:135], v[224:227], v[12:15]
	v_lshl_add_u64 v[228:229], s[56:57], 0, v[136:137]
	s_mov_b32 m0, s58
	s_nop 0
	global_load_lds_dwordx4 v[228:229], off
	v_mfma_f32_16x16x32_bf16 v[8:11], v[156:159], v[224:227], v[8:11]
	s_setprio 0
	s_setprio 1
	v_mfma_f32_16x16x32_bf16 v[52:55], v[172:175], v[190:193], v[52:55]
	v_mfma_f32_16x16x32_bf16 v[48:51], v[182:185], v[190:193], v[48:51]
	v_mfma_f32_16x16x32_bf16 v[36:39], v[172:175], v[198:201], v[36:39]
	v_mfma_f32_16x16x32_bf16 v[32:35], v[182:185], v[198:201], v[32:35]
	v_mfma_f32_16x16x32_bf16 v[20:23], v[172:175], v[212:215], v[20:23]
	v_mfma_f32_16x16x32_bf16 v[16:19], v[182:185], v[212:215], v[16:19]
	v_mfma_f32_16x16x32_bf16 v[4:7], v[172:175], v[220:223], v[4:7]
	v_mfma_f32_16x16x32_bf16 v[0:3], v[182:185], v[220:223], v[0:3]
	v_mfma_f32_16x16x32_bf16 v[52:55], v[176:179], v[194:197], v[52:55]
	v_mfma_f32_16x16x32_bf16 v[48:51], v[186:189], v[194:197], v[48:51]
	v_mfma_f32_16x16x32_bf16 v[36:39], v[176:179], v[208:211], v[36:39]
	v_mfma_f32_16x16x32_bf16 v[32:35], v[186:189], v[208:211], v[32:35]
	v_mfma_f32_16x16x32_bf16 v[20:23], v[176:179], v[216:219], v[20:23]
	v_mfma_f32_16x16x32_bf16 v[16:19], v[186:189], v[216:219], v[16:19]
	v_mfma_f32_16x16x32_bf16 v[4:7], v[176:179], v[224:227], v[4:7]
	v_lshl_add_u64 v[230:231], s[56:57], 0, v[140:141]
	s_mov_b32 m0, s59
	s_nop 0
	global_load_lds_dwordx4 v[230:231], off
	v_mfma_f32_16x16x32_bf16 v[0:3], v[186:189], v[224:227], v[0:3]
	s_setprio 0
	s_barrier
; #define PG8_STAGE(bufoff, gbase, voff) do { _Pragma("unroll") for (int _i = 0; _i < 2; ++_i) \
;         __builtin_amdgcn_global_load_lds((const unsigned*)((const char*)(gbase) + (voff)[_i]), (PG8_LAS unsigned*)(lds + (bufoff) + ldsw + _i * 8192), 16, 0, 0); } while (0)
; #define PG8_LDA(dst, b, h) do { _Pragma("unroll") for (int m = 0; m < 4; ++m) _Pragma("unroll") for (int k = 0; k < 2; ++k) dst[m][k] = *(const PG8_LAS bf16x8*)(lds + PG8_SA(b, h) + aoff + m * 2048 + k * 1024); } while (0)
; #define PG8_LDB(dst, b, h) do { _Pragma("unroll") for (int n = 0; n < 2; ++n) _Pragma("unroll") for (int k = 0; k < 2; ++k) dst[n][k] = *(const PG8_LAS bf16x8*)(lds + PG8_SB(b, h) + boff + n * 2048 + k * 1024); } while (0)
; #define PG8_MMA(ai, bj, At, Bt) do { __builtin_amdgcn_s_setprio(1); _Pragma("unroll") for (int m = 0; m < 4; ++m) _Pragma("unroll") for (int n = 0; n < 2; ++n) _Pragma("unroll") for (int k = 0; k < 2; ++k) \
;         acc[ai][bj][m][n] = __builtin_amdgcn_mfma_f32_16x16x32_bf16(Bt[n][k], At[m][k], acc[ai][bj][m][n], 0, 0, 0); __builtin_amdgcn_s_setprio(0); } while (0)
; #define PG8_WAIT_V(n) asm volatile("s_waitcnt vmcnt(" #n ")" ::: "memory")
; #define PG8_WAIT_L(n) asm volatile("s_waitcnt lgkmcnt(" #n ")" ::: "memory")
; #define PG8_BAR __builtin_amdgcn_s_barrier()
; #define PG8_SCHED __builtin_amdgcn_sched_barrier(0)
; template <class Epi, class Sched, bool ALIGN_EPI = false, bool SP2 = false>
; __device__ __forceinline__ void gemm_phase(PG8_LAS unsigned char* lds, const Gemm g, const Sched& S, const Epi& E) {
;     ...
;             PG8_LDB(B0, 1, 0); PG8_LDB(B1, 1, 1); PG8_SCHED; PG8_LDA(At, 1, 0); PG8_STAGE(PG8_SA(0, 1), a2 + hstep, voffA);
;             PG8_WAIT_V(8); PG8_WAIT_L(0); PG8_BAR; PG8_MMA(0, 0, At, B0); PG8_MMA(0, 1, At, B1); PG8_BAR; PG8_SCHED;
	s_add_i32 s3, 0, 0x18000
	s_add_i32 s14, 0, 0x1c000
	v_add_u32_e32 v156, s3, v163
	v_add_u32_e32 v171, s14, v163
	ds_read_b128 v[128:131], v156
	ds_read_b128 v[132:135], v156 offset:1024
	ds_read_b128 v[152:155], v156 offset:2048
	ds_read_b128 v[156:159], v156 offset:3072
	ds_read_b128 v[172:175], v171
	ds_read_b128 v[176:179], v171 offset:1024
	ds_read_b128 v[182:185], v171 offset:2048
	ds_read_b128 v[186:189], v171 offset:3072
	s_add_u32 s10, s56, 0xb0000
	s_addc_u32 s11, s57, 0
	s_mov_b32 m0, s60
	v_lshl_add_u64 v[232:233], s[10:11], 0, v[136:137]
	ds_read_b128 v[190:193], v169 offset:32768
	ds_read_b128 v[194:197], v169 offset:33792
	ds_read_b128 v[198:201], v169 offset:34816
	ds_read_b128 v[208:211], v169 offset:35840
	ds_read_b128 v[212:215], v169 offset:36864
	ds_read_b128 v[216:219], v169 offset:37888
	ds_read_b128 v[220:223], v169 offset:38912
	ds_read_b128 v[224:227], v169 offset:39936
	global_load_lds_dwordx4 v[232:233], off
	v_lshl_add_u64 v[232:233], s[10:11], 0, v[140:141]
	s_mov_b32 m0, s61
	s_nop 0
	global_load_lds_dwordx4 v[232:233], off
	s_waitcnt vmcnt(8)
	s_waitcnt lgkmcnt(0)
	s_barrier
	s_setprio 1
	s_waitcnt lgkmcnt(0)
	v_mfma_f32_16x16x32_bf16 v[124:127], v[128:131], v[190:193], v[124:127]
	v_mfma_f32_16x16x32_bf16 v[120:123], v[152:155], v[190:193], v[120:123]
	v_mfma_f32_16x16x32_bf16 v[108:111], v[128:131], v[198:201], v[108:111]
	v_mfma_f32_16x16x32_bf16 v[104:107], v[152:155], v[198:201], v[104:107]
	v_mfma_f32_16x16x32_bf16 v[92:95], v[128:131], v[212:215], v[92:95]
	v_mfma_f32_16x16x32_bf16 v[88:91], v[152:155], v[212:215], v[88:91]
	v_mfma_f32_16x16x32_bf16 v[76:79], v[128:131], v[220:223], v[76:79]
	v_mfma_f32_16x16x32_bf16 v[72:75], v[152:155], v[220:223], v[72:75]
	v_mfma_f32_16x16x32_bf16 v[124:127], v[132:135], v[194:197], v[124:127]
	v_mfma_f32_16x16x32_bf16 v[120:123], v[156:159], v[194:197], v[120:123]
	v_mfma_f32_16x16x32_bf16 v[108:111], v[132:135], v[208:211], v[108:111]
	v_mfma_f32_16x16x32_bf16 v[104:107], v[156:159], v[208:211], v[104:107]
	v_mfma_f32_16x16x32_bf16 v[92:95], v[132:135], v[216:219], v[92:95]
	v_mfma_f32_16x16x32_bf16 v[88:91], v[156:159], v[216:219], v[88:91]
	v_mfma_f32_16x16x32_bf16 v[76:79], v[132:135], v[224:227], v[76:79]
	v_mfma_f32_16x16x32_bf16 v[72:75], v[156:159], v[224:227], v[72:75]
	s_setprio 0
	s_setprio 1
	v_mfma_f32_16x16x32_bf16 v[116:119], v[172:175], v[190:193], v[116:119]
	v_mfma_f32_16x16x32_bf16 v[112:115], v[182:185], v[190:193], v[112:115]
	v_mfma_f32_16x16x32_bf16 v[100:103], v[172:175], v[198:201], v[100:103]
	v_mfma_f32_16x16x32_bf16 v[96:99], v[182:185], v[198:201], v[96:99]
	v_mfma_f32_16x16x32_bf16 v[84:87], v[172:175], v[212:215], v[84:87]
	v_mfma_f32_16x16x32_bf16 v[80:83], v[182:185], v[212:215], v[80:83]
	v_mfma_f32_16x16x32_bf16 v[68:71], v[172:175], v[220:223], v[68:71]
	v_mfma_f32_16x16x32_bf16 v[64:67], v[182:185], v[220:223], v[64:67]
	v_mfma_f32_16x16x32_bf16 v[116:119], v[176:179], v[194:197], v[116:119]
	v_mfma_f32_16x16x32_bf16 v[112:115], v[186:189], v[194:197], v[112:115]
	v_mfma_f32_16x16x32_bf16 v[100:103], v[176:179], v[208:211], v[100:103]
	v_mfma_f32_16x16x32_bf16 v[96:99], v[186:189], v[208:211], v[96:99]
	v_mfma_f32_16x16x32_bf16 v[84:87], v[176:179], v[216:219], v[84:87]
	v_mfma_f32_16x16x32_bf16 v[80:83], v[186:189], v[216:219], v[80:83]
	v_mfma_f32_16x16x32_bf16 v[68:71], v[176:179], v[224:227], v[68:71]
	v_mfma_f32_16x16x32_bf16 v[64:67], v[186:189], v[224:227], v[64:67]
	s_setprio 0
	s_barrier
; #define PG8_STAGE(bufoff, gbase, voff) do { _Pragma("unroll") for (int _i = 0; _i < 2; ++_i) \
;         __builtin_amdgcn_global_load_lds((const unsigned*)((const char*)(gbase) + (voff)[_i]), (PG8_LAS unsigned*)(lds + (bufoff) + ldsw + _i * 8192), 16, 0, 0); } while (0)
; #define PG8_LDA(dst, b, h) do { _Pragma("unroll") for (int m = 0; m < 4; ++m) _Pragma("unroll") for (int k = 0; k < 2; ++k) dst[m][k] = *(const PG8_LAS bf16x8*)(lds + PG8_SA(b, h) + aoff + m * 2048 + k * 1024); } while (0)
; #define PG8_MMA(ai, bj, At, Bt) do { __builtin_amdgcn_s_setprio(1); _Pragma("unroll") for (int m = 0; m < 4; ++m) _Pragma("unroll") for (int n = 0; n < 2; ++n) _Pragma("unroll") for (int k = 0; k < 2; ++k) \
;         acc[ai][bj][m][n] = __builtin_amdgcn_mfma_f32_16x16x32_bf16(Bt[n][k], At[m][k], acc[ai][bj][m][n], 0, 0, 0); __builtin_amdgcn_s_setprio(0); } while (0)
; #define PG8_WAIT_V(n) asm volatile("s_waitcnt vmcnt(" #n ")" ::: "memory")
; #define PG8_WAIT_L(n) asm volatile("s_waitcnt lgkmcnt(" #n ")" ::: "memory")
; #define PG8_BAR __builtin_amdgcn_s_barrier()
; #define PG8_SCHED __builtin_amdgcn_sched_barrier(0)
; template <class Epi, class Sched, bool ALIGN_EPI = false, bool SP2 = false>
; __device__ __forceinline__ void gemm_phase(PG8_LAS unsigned char* lds, const Gemm g, const Sched& S, const Epi& E) {
;     ...
;             PG8_LDA(At, 1, 1); PG8_STAGE(PG8_SB(1, 0), b3, voffB); PG8_STAGE(PG8_SB(1, 1), b3 + hstep, voffB); PG8_STAGE(PG8_SA(1, 0), a3, voffA);
;             PG8_WAIT_V(8); PG8_WAIT_L(0); PG8_BAR; PG8_MMA(1, 0, At, B0); PG8_MMA(1, 1, At, B1); PG8_BAR; PG8_SCHED;
;     ...
;         if constexpr (ALIGN_EPI) { if (wr == 0) PG8_BAR; }
	s_add_i32 s3, s3, s43
	v_lshl_add_u64 v[160:161], v[160:161], 0, s[40:41]
	s_mov_b32 m0, s3
	ds_read_b128 v[190:193], v169 offset:49152
	ds_read_b128 v[194:197], v169 offset:50176
	ds_read_b128 v[198:201], v169 offset:51200
	ds_read_b128 v[208:211], v169 offset:52224
	ds_read_b128 v[212:215], v169 offset:53248
	ds_read_b128 v[216:219], v169 offset:54272
	ds_read_b128 v[220:223], v169 offset:55296
	ds_read_b128 v[224:227], v169 offset:56320
	global_load_lds_dwordx4 v[160:161], off
	s_add_i32 m0, s3, 0x2000
	s_add_u32 s10, s54, 0xb0080
	v_lshl_add_u64 v[160:161], v[202:203], 0, s[40:41]
	s_addc_u32 s11, s55, 0
	s_add_i32 s3, s14, s43
	global_load_lds_dwordx4 v[160:161], off
	v_lshl_add_u64 v[160:161], s[10:11], 0, v[138:139]
	s_mov_b32 m0, s3
	s_nop 0
	global_load_lds_dwordx4 v[160:161], off
	v_lshl_add_u64 v[160:161], s[10:11], 0, v[142:143]
	s_add_i32 m0, s3, 0x2000
	s_nop 0
	global_load_lds_dwordx4 v[160:161], off
	s_waitcnt vmcnt(6)
	s_waitcnt lgkmcnt(0)
	s_barrier
	s_setprio 1
	s_waitcnt lgkmcnt(0)
	v_mfma_f32_16x16x32_bf16 v[60:63], v[128:131], v[190:193], v[60:63]
	v_mfma_f32_16x16x32_bf16 v[56:59], v[152:155], v[190:193], v[56:59]
	v_mfma_f32_16x16x32_bf16 v[44:47], v[128:131], v[198:201], v[44:47]
	v_mfma_f32_16x16x32_bf16 v[40:43], v[152:155], v[198:201], v[40:43]
	v_mfma_f32_16x16x32_bf16 v[28:31], v[128:131], v[212:215], v[28:31]
	v_mfma_f32_16x16x32_bf16 v[24:27], v[152:155], v[212:215], v[24:27]
	v_mfma_f32_16x16x32_bf16 v[12:15], v[128:131], v[220:223], v[12:15]
	v_mfma_f32_16x16x32_bf16 v[8:11], v[152:155], v[220:223], v[8:11]
	v_mfma_f32_16x16x32_bf16 v[60:63], v[132:135], v[194:197], v[60:63]
	v_mfma_f32_16x16x32_bf16 v[56:59], v[156:159], v[194:197], v[56:59]
	v_mfma_f32_16x16x32_bf16 v[44:47], v[132:135], v[208:211], v[44:47]
	v_mfma_f32_16x16x32_bf16 v[40:43], v[156:159], v[208:211], v[40:43]
	v_mfma_f32_16x16x32_bf16 v[28:31], v[132:135], v[216:219], v[28:31]
	v_mfma_f32_16x16x32_bf16 v[24:27], v[156:159], v[216:219], v[24:27]
	v_mfma_f32_16x16x32_bf16 v[12:15], v[132:135], v[224:227], v[12:15]
	v_lshl_add_u64 v[160:161], v[228:229], 0, s[40:41]
	s_mov_b32 m0, s63
	s_nop 0
	global_load_lds_dwordx4 v[160:161], off
	v_mfma_f32_16x16x32_bf16 v[8:11], v[156:159], v[224:227], v[8:11]
	s_setprio 0
	s_setprio 1
	v_mfma_f32_16x16x32_bf16 v[52:55], v[172:175], v[190:193], v[52:55]
	v_mfma_f32_16x16x32_bf16 v[48:51], v[182:185], v[190:193], v[48:51]
	v_mfma_f32_16x16x32_bf16 v[36:39], v[172:175], v[198:201], v[36:39]
	v_mfma_f32_16x16x32_bf16 v[32:35], v[182:185], v[198:201], v[32:35]
	v_mfma_f32_16x16x32_bf16 v[20:23], v[172:175], v[212:215], v[20:23]
	v_mfma_f32_16x16x32_bf16 v[16:19], v[182:185], v[212:215], v[16:19]
	v_mfma_f32_16x16x32_bf16 v[4:7], v[172:175], v[220:223], v[4:7]
	v_mfma_f32_16x16x32_bf16 v[0:3], v[182:185], v[220:223], v[0:3]
	v_mfma_f32_16x16x32_bf16 v[52:55], v[176:179], v[194:197], v[52:55]
	v_mfma_f32_16x16x32_bf16 v[48:51], v[186:189], v[194:197], v[48:51]
	v_mfma_f32_16x16x32_bf16 v[36:39], v[176:179], v[208:211], v[36:39]
	v_mfma_f32_16x16x32_bf16 v[32:35], v[186:189], v[208:211], v[32:35]
	v_mfma_f32_16x16x32_bf16 v[20:23], v[176:179], v[216:219], v[20:23]
	v_mfma_f32_16x16x32_bf16 v[16:19], v[186:189], v[216:219], v[16:19]
	v_mfma_f32_16x16x32_bf16 v[4:7], v[176:179], v[224:227], v[4:7]
	v_lshl_add_u64 v[160:161], v[230:231], 0, s[40:41]
	s_mov_b32 m0, s64
	s_nop 0
	global_load_lds_dwordx4 v[160:161], off
	v_mfma_f32_16x16x32_bf16 v[0:3], v[186:189], v[224:227], v[0:3]
	s_setprio 0
	s_barrier
	s_add_i32 s93, s93, 2
	s_add_u32 s91, s91, 0x100
	s_addc_u32 s92, s92, 0
	s_cmp_gt_u32 s93, 41
	s_mov_b64 s[10:11], s[50:51]
	s_cbranch_scc0 .LBB0_269
	s_and_b64 vcc, exec, s[44:45]
	s_cbranch_vccz .LBB0_272
	s_barrier

; #define PG8_STAGE(bufoff, gbase, voff) do { _Pragma("unroll") for (int _i = 0; _i < 2; ++_i) \
;         __builtin_amdgcn_global_load_lds((const unsigned*)((const char*)(gbase) + (voff)[_i]), (PG8_LAS unsigned*)(lds + (bufoff) + ldsw + _i * 8192), 16, 0, 0); } while (0)
; #define PG8_LDA(dst, b, h) do { _Pragma("unroll") for (int m = 0; m < 4; ++m) _Pragma("unroll") for (int k = 0; k < 2; ++k) dst[m][k] = *(const PG8_LAS bf16x8*)(lds + PG8_SA(b, h) + aoff + m * 2048 + k * 1024); } while (0)
; #define PG8_LDB(dst, b, h) do { _Pragma("unroll") for (int n = 0; n < 2; ++n) _Pragma("unroll") for (int k = 0; k < 2; ++k) dst[n][k] = *(const PG8_LAS bf16x8*)(lds + PG8_SB(b, h) + boff + n * 2048 + k * 1024); } while (0)
; #define PG8_MMA(ai, bj, At, Bt) do { __builtin_amdgcn_s_setprio(1); _Pragma("unroll") for (int m = 0; m < 4; ++m) _Pragma("unroll") for (int n = 0; n < 2; ++n) _Pragma("unroll") for (int k = 0; k < 2; ++k) \
;         acc[ai][bj][m][n] = __builtin_amdgcn_mfma_f32_16x16x32_bf16(Bt[n][k], At[m][k], acc[ai][bj][m][n], 0, 0, 0); __builtin_amdgcn_s_setprio(0); } while (0)
; #define PG8_WAIT_V(n) asm volatile("s_waitcnt vmcnt(" #n ")" ::: "memory")
; #define PG8_WAIT_L(n) asm volatile("s_waitcnt lgkmcnt(" #n ")" ::: "memory")
; #define PG8_BAR __builtin_amdgcn_s_barrier()
; template <class Epi, class Sched, bool ALIGN_EPI = false, bool SP2 = false>
; __device__ __forceinline__ void gemm_phase(PG8_LAS unsigned char* lds, const Gemm g, const Sched& S, const Epi& E) {
;     ...
;         const bool has_next = S.next(ui + 1, nxt);
;         const char* nA = has_next ? (const char*)g.A + (size_t)nxt.pm * tstep : cA; const char* nB = has_next ? (const char*)g.Bt + (size_t)nxt.pn * tstep : cB;
;         for (int t = 0; t < nt; t += 2) {
;             const bool last = (t == nt - 2);
;             const char* a1 = cA + (size_t)(t + 1) * kstep;
;             const char* a2 = last ? nA : cA + (size_t)(t + 2) * kstep; const char* b2 = last ? nB : cB + (size_t)(t + 2) * kstep;
;             const char* a3 = a2 + kstep; const char* b3 = b2 + kstep;
;             if (last && has_next) S.a_ready(nxt);
;             if constexpr (SP2) {
;             PG8_LDB(B0, 0, 0); PG8_LDB(B1, 0, 1); PG8_SCHED; PG8_LDA(At, 0, 0); PG8_STAGE(PG8_SA(1, 1), a1 + hstep, voffA);
;             PG8_WAIT_V(8); PG8_WAIT_L(0); PG8_BAR; PG8_MMA(0, 0, At, B0); PG8_MMA(0, 1, At, B1); PG8_BAR; PG8_SCHED;
.LBB0_416:
	s_ashr_i32 s45, s44, 31
	s_lshl_b64 s[14:15], s[44:45], 19
	s_add_u32 s48, s22, s14
	s_addc_u32 s49, s23, s15
	s_and_b64 s[14:15], s[6:7], exec
	s_cselect_b32 s45, s49, s55
	s_cselect_b32 s89, s48, s54
	s_ashr_i32 s41, s40, 31
	s_lshl_b64 s[14:15], s[40:41], 19
	s_add_u32 s50, s84, s14
	s_addc_u32 s51, s85, s15
	s_and_b64 s[14:15], s[6:7], exec
	s_cselect_b32 s41, s51, s57
	s_cselect_b32 s90, s50, s56
	s_add_u32 s54, s54, 0x40080
	s_addc_u32 s55, s55, 0
	s_add_u32 s91, s56, 0x100
	s_addc_u32 s92, s57, 0
	s_mov_b32 s93, -2
	ds_read_b128 v[154:157], v169
	ds_read_b128 v[158:161], v169 offset:1024
	ds_read_b128 v[162:165], v169 offset:2048
	ds_read_b128 v[174:177], v169 offset:3072
	ds_read_b128 v[182:185], v170
	ds_read_b128 v[186:189], v170 offset:1024
	ds_read_b128 v[190:193], v170 offset:2048
	ds_read_b128 v[194:197], v170 offset:3072
	s_add_u32 s3, s54, 0xfffc0080
	s_addc_u32 s14, s55, -1
	s_cmp_eq_u32 s93, 12
	s_cselect_b32 s59, s45, s14
	s_cselect_b32 s58, s89, s3
	s_cselect_b32 s57, s41, s92
	s_cselect_b32 s56, s90, s91
	v_lshl_add_u64 v[178:179], s[54:55], 0, v[146:147]
	s_add_i32 m0, s60, 0xc000
	ds_read_b128 v[198:201], v171
	ds_read_b128 v[208:211], v171 offset:1024
	ds_read_b128 v[212:215], v171 offset:2048
	ds_read_b128 v[216:219], v171 offset:3072
	ds_read_b128 v[220:223], v171 offset:4096
	ds_read_b128 v[224:227], v171 offset:5120
	ds_read_b128 v[228:231], v171 offset:6144
	ds_read_b128 v[232:235], v171 offset:7168
	global_load_lds_dwordx4 v[178:179], off
	v_lshl_add_u64 v[178:179], s[54:55], 0, v[148:149]
	s_add_i32 m0, s60, 0xe000
	s_nop 0
	global_load_lds_dwordx4 v[178:179], off
	s_waitcnt vmcnt(8)
	s_waitcnt lgkmcnt(0)
	s_barrier
	s_setprio 1
	s_waitcnt lgkmcnt(0)
	v_mfma_f32_16x16x32_bf16 v[124:127], v[154:157], v[198:201], 0
	v_mfma_f32_16x16x32_bf16 v[120:123], v[162:165], v[198:201], 0
	v_mfma_f32_16x16x32_bf16 v[116:119], v[154:157], v[212:215], 0
	v_mfma_f32_16x16x32_bf16 v[112:115], v[162:165], v[212:215], 0
	v_mfma_f32_16x16x32_bf16 v[108:111], v[154:157], v[220:223], 0
	v_mfma_f32_16x16x32_bf16 v[104:107], v[162:165], v[220:223], 0
	v_mfma_f32_16x16x32_bf16 v[100:103], v[154:157], v[228:231], 0
	v_mfma_f32_16x16x32_bf16 v[96:99], v[162:165], v[228:231], 0
	v_mfma_f32_16x16x32_bf16 v[124:127], v[158:161], v[208:211], v[124:127]
	v_mfma_f32_16x16x32_bf16 v[120:123], v[174:177], v[208:211], v[120:123]
	v_mfma_f32_16x16x32_bf16 v[116:119], v[158:161], v[216:219], v[116:119]
	v_mfma_f32_16x16x32_bf16 v[112:115], v[174:177], v[216:219], v[112:115]
	v_mfma_f32_16x16x32_bf16 v[108:111], v[158:161], v[224:227], v[108:111]
	v_mfma_f32_16x16x32_bf16 v[104:107], v[174:177], v[224:227], v[104:107]
	v_mfma_f32_16x16x32_bf16 v[100:103], v[158:161], v[232:235], v[100:103]
	v_mfma_f32_16x16x32_bf16 v[96:99], v[174:177], v[232:235], v[96:99]
	s_setprio 0
	s_setprio 1
	v_mfma_f32_16x16x32_bf16 v[68:71], v[182:185], v[198:201], 0
	v_mfma_f32_16x16x32_bf16 v[64:67], v[190:193], v[198:201], 0
	v_mfma_f32_16x16x32_bf16 v[52:55], v[182:185], v[212:215], 0
	v_mfma_f32_16x16x32_bf16 v[48:51], v[190:193], v[212:215], 0
	v_mfma_f32_16x16x32_bf16 v[44:47], v[182:185], v[220:223], 0
	v_mfma_f32_16x16x32_bf16 v[40:43], v[190:193], v[220:223], 0
	v_mfma_f32_16x16x32_bf16 v[36:39], v[182:185], v[228:231], 0
	v_mfma_f32_16x16x32_bf16 v[32:35], v[190:193], v[228:231], 0
	v_mfma_f32_16x16x32_bf16 v[68:71], v[186:189], v[208:211], v[68:71]
	v_mfma_f32_16x16x32_bf16 v[64:67], v[194:197], v[208:211], v[64:67]
	v_mfma_f32_16x16x32_bf16 v[52:55], v[186:189], v[216:219], v[52:55]
	v_mfma_f32_16x16x32_bf16 v[48:51], v[194:197], v[216:219], v[48:51]
	v_mfma_f32_16x16x32_bf16 v[44:47], v[186:189], v[224:227], v[44:47]
	v_mfma_f32_16x16x32_bf16 v[40:43], v[194:197], v[224:227], v[40:43]
	v_mfma_f32_16x16x32_bf16 v[36:39], v[186:189], v[232:235], v[36:39]
	v_mfma_f32_16x16x32_bf16 v[32:35], v[194:197], v[232:235], v[32:35]
	s_setprio 0
	s_barrier
	s_add_i32 s3, s86, s34
	v_lshl_add_u64 v[178:179], s[56:57], 0, v[132:133]
	s_mov_b32 m0, s3
	ds_read_b128 v[198:201], v171 offset:16384
	ds_read_b128 v[208:211], v171 offset:17408
	ds_read_b128 v[212:215], v171 offset:18432
	ds_read_b128 v[216:219], v171 offset:19456
	ds_read_b128 v[220:223], v171 offset:20480
	ds_read_b128 v[224:227], v171 offset:21504
	ds_read_b128 v[228:231], v171 offset:22528
	ds_read_b128 v[232:235], v171 offset:23552
	global_load_lds_dwordx4 v[178:179], off
	s_add_i32 m0, s3, 0x2000
	s_add_u32 s14, s56, 0x40000
	v_lshl_add_u64 v[202:203], s[56:57], 0, v[128:129]
	s_addc_u32 s15, s57, 0
	s_add_i32 s3, s87, s34
	global_load_lds_dwordx4 v[202:203], off
	v_lshl_add_u64 v[236:237], s[14:15], 0, v[132:133]
	s_mov_b32 m0, s3
	global_load_lds_dwordx4 v[236:237], off
	v_lshl_add_u64 v[236:237], s[14:15], 0, v[128:129]
	s_add_i32 m0, s3, 0x2000
	s_nop 0
	global_load_lds_dwordx4 v[236:237], off
	s_waitcnt vmcnt(6)
	s_waitcnt lgkmcnt(0)
	s_barrier
; #define PG8_STAGE(bufoff, gbase, voff) do { _Pragma("unroll") for (int _i = 0; _i < 2; ++_i) \
;         __builtin_amdgcn_global_load_lds((const unsigned*)((const char*)(gbase) + (voff)[_i]), (PG8_LAS unsigned*)(lds + (bufoff) + ldsw + _i * 8192), 16, 0, 0); } while (0)
; #define PG8_LDA(dst, b, h) do { _Pragma("unroll") for (int m = 0; m < 4; ++m) _Pragma("unroll") for (int k = 0; k < 2; ++k) dst[m][k] = *(const PG8_LAS bf16x8*)(lds + PG8_SA(b, h) + aoff + m * 2048 + k * 1024); } while (0)
; #define PG8_LDB(dst, b, h) do { _Pragma("unroll") for (int n = 0; n < 2; ++n) _Pragma("unroll") for (int k = 0; k < 2; ++k) dst[n][k] = *(const PG8_LAS bf16x8*)(lds + PG8_SB(b, h) + boff + n * 2048 + k * 1024); } while (0)
; #define PG8_MMA(ai, bj, At, Bt) do { __builtin_amdgcn_s_setprio(1); _Pragma("unroll") for (int m = 0; m < 4; ++m) _Pragma("unroll") for (int n = 0; n < 2; ++n) _Pragma("unroll") for (int k = 0; k < 2; ++k) \
;         acc[ai][bj][m][n] = __builtin_amdgcn_mfma_f32_16x16x32_bf16(Bt[n][k], At[m][k], acc[ai][bj][m][n], 0, 0, 0); __builtin_amdgcn_s_setprio(0); } while (0)
; #define PG8_WAIT_V(n) asm volatile("s_waitcnt vmcnt(" #n ")" ::: "memory")
; #define PG8_WAIT_L(n) asm volatile("s_waitcnt lgkmcnt(" #n ")" ::: "memory")
; #define PG8_BAR __builtin_amdgcn_s_barrier()
; #define PG8_SCHED __builtin_amdgcn_sched_barrier(0)
; template <class Epi, class Sched, bool ALIGN_EPI = false, bool SP2 = false>
; __device__ __forceinline__ void gemm_phase(PG8_LAS unsigned char* lds, const Gemm g, const Sched& S, const Epi& E) {
;     ...
;             PG8_WAIT_V(8); PG8_WAIT_L(0); PG8_BAR; PG8_MMA(1, 0, At, B0); PG8_MMA(1, 1, At, B1); PG8_BAR; PG8_SCHED;
;             PG8_LDB(B0, 1, 0); PG8_LDB(B1, 1, 1); PG8_SCHED; PG8_LDA(At, 1, 0); PG8_STAGE(PG8_SA(0, 1), a2 + hstep, voffA);
;             PG8_WAIT_V(8); PG8_WAIT_L(0); PG8_BAR; PG8_MMA(0, 0, At, B0); PG8_MMA(0, 1, At, B1); PG8_BAR; PG8_SCHED;
	s_setprio 1
	s_waitcnt lgkmcnt(0)
	v_mfma_f32_16x16x32_bf16 v[92:95], v[154:157], v[198:201], 0
	v_mfma_f32_16x16x32_bf16 v[88:91], v[162:165], v[198:201], 0
	v_mfma_f32_16x16x32_bf16 v[84:87], v[154:157], v[212:215], 0
	v_mfma_f32_16x16x32_bf16 v[80:83], v[162:165], v[212:215], 0
	v_mfma_f32_16x16x32_bf16 v[76:79], v[154:157], v[220:223], 0
	v_mfma_f32_16x16x32_bf16 v[72:75], v[162:165], v[220:223], 0
	v_mfma_f32_16x16x32_bf16 v[60:63], v[154:157], v[228:231], 0
	v_mfma_f32_16x16x32_bf16 v[56:59], v[162:165], v[228:231], 0
	v_mfma_f32_16x16x32_bf16 v[92:95], v[158:161], v[208:211], v[92:95]
	v_mfma_f32_16x16x32_bf16 v[88:91], v[174:177], v[208:211], v[88:91]
	v_mfma_f32_16x16x32_bf16 v[84:87], v[158:161], v[216:219], v[84:87]
	v_mfma_f32_16x16x32_bf16 v[80:83], v[174:177], v[216:219], v[80:83]
	v_mfma_f32_16x16x32_bf16 v[76:79], v[158:161], v[224:227], v[76:79]
	v_mfma_f32_16x16x32_bf16 v[72:75], v[174:177], v[224:227], v[72:75]
	v_mfma_f32_16x16x32_bf16 v[60:63], v[158:161], v[232:235], v[60:63]
	v_lshl_add_u64 v[236:237], s[58:59], 0, v[134:135]
	s_mov_b32 m0, s60
	s_nop 0
	global_load_lds_dwordx4 v[236:237], off
	v_mfma_f32_16x16x32_bf16 v[56:59], v[174:177], v[232:235], v[56:59]
	s_setprio 0
	s_setprio 1
	v_mfma_f32_16x16x32_bf16 v[28:31], v[182:185], v[198:201], 0
	v_mfma_f32_16x16x32_bf16 v[24:27], v[190:193], v[198:201], 0
	v_mfma_f32_16x16x32_bf16 v[20:23], v[182:185], v[212:215], 0
	v_mfma_f32_16x16x32_bf16 v[16:19], v[190:193], v[212:215], 0
	v_mfma_f32_16x16x32_bf16 v[12:15], v[182:185], v[220:223], 0
	v_mfma_f32_16x16x32_bf16 v[8:11], v[190:193], v[220:223], 0
	v_mfma_f32_16x16x32_bf16 v[4:7], v[182:185], v[228:231], 0
	v_mfma_f32_16x16x32_bf16 v[0:3], v[190:193], v[228:231], 0
	v_mfma_f32_16x16x32_bf16 v[28:31], v[186:189], v[208:211], v[28:31]
	v_mfma_f32_16x16x32_bf16 v[24:27], v[194:197], v[208:211], v[24:27]
	v_mfma_f32_16x16x32_bf16 v[20:23], v[186:189], v[216:219], v[20:23]
	v_mfma_f32_16x16x32_bf16 v[16:19], v[194:197], v[216:219], v[16:19]
	v_mfma_f32_16x16x32_bf16 v[12:15], v[186:189], v[224:227], v[12:15]
	v_mfma_f32_16x16x32_bf16 v[8:11], v[194:197], v[224:227], v[8:11]
	v_mfma_f32_16x16x32_bf16 v[4:7], v[186:189], v[232:235], v[4:7]
	v_lshl_add_u64 v[238:239], s[58:59], 0, v[130:131]
	s_mov_b32 m0, s61
	s_nop 0
	global_load_lds_dwordx4 v[238:239], off
	v_mfma_f32_16x16x32_bf16 v[0:3], v[194:197], v[232:235], v[0:3]
	s_setprio 0
	s_barrier
	s_add_i32 s3, 0, 0x18000
	v_add_u32_e32 v136, s3, v143
	s_add_i32 s33, 0, 0x1c000
	ds_read_b128 v[154:157], v136
	ds_read_b128 v[158:161], v136 offset:1024
	ds_read_b128 v[162:165], v136 offset:2048
	ds_read_b128 v[174:177], v136 offset:3072
	v_add_u32_e32 v136, s33, v143
	ds_read_b128 v[182:185], v136
	ds_read_b128 v[186:189], v136 offset:1024
	ds_read_b128 v[190:193], v136 offset:2048
	ds_read_b128 v[194:197], v136 offset:3072
	s_add_u32 s14, s58, 0x40000
	s_addc_u32 s15, s59, 0
	s_mov_b32 m0, s62
	v_lshl_add_u64 v[240:241], s[14:15], 0, v[134:135]
	ds_read_b128 v[198:201], v171 offset:32768
	ds_read_b128 v[208:211], v171 offset:33792
	ds_read_b128 v[212:215], v171 offset:34816
	ds_read_b128 v[216:219], v171 offset:35840
	ds_read_b128 v[220:223], v171 offset:36864
	ds_read_b128 v[224:227], v171 offset:37888
	ds_read_b128 v[228:231], v171 offset:38912
	ds_read_b128 v[232:235], v171 offset:39936
	global_load_lds_dwordx4 v[240:241], off
	v_lshl_add_u64 v[240:241], s[14:15], 0, v[130:131]
	s_mov_b32 m0, s63
	s_nop 0
	global_load_lds_dwordx4 v[240:241], off
	s_waitcnt vmcnt(8)
	s_waitcnt lgkmcnt(0)
	s_barrier
	s_setprio 1
	s_waitcnt lgkmcnt(0)
	v_mfma_f32_16x16x32_bf16 v[124:127], v[154:157], v[198:201], v[124:127]
	v_mfma_f32_16x16x32_bf16 v[120:123], v[162:165], v[198:201], v[120:123]
	v_mfma_f32_16x16x32_bf16 v[116:119], v[154:157], v[212:215], v[116:119]
	v_mfma_f32_16x16x32_bf16 v[112:115], v[162:165], v[212:215], v[112:115]
	v_mfma_f32_16x16x32_bf16 v[108:111], v[154:157], v[220:223], v[108:111]
	v_mfma_f32_16x16x32_bf16 v[104:107], v[162:165], v[220:223], v[104:107]
	v_mfma_f32_16x16x32_bf16 v[100:103], v[154:157], v[228:231], v[100:103]
	v_mfma_f32_16x16x32_bf16 v[96:99], v[162:165], v[228:231], v[96:99]
	v_mfma_f32_16x16x32_bf16 v[124:127], v[158:161], v[208:211], v[124:127]
	v_mfma_f32_16x16x32_bf16 v[120:123], v[174:177], v[208:211], v[120:123]
	v_mfma_f32_16x16x32_bf16 v[116:119], v[158:161], v[216:219], v[116:119]
	v_mfma_f32_16x16x32_bf16 v[112:115], v[174:177], v[216:219], v[112:115]
	v_mfma_f32_16x16x32_bf16 v[108:111], v[158:161], v[224:227], v[108:111]
	v_mfma_f32_16x16x32_bf16 v[104:107], v[174:177], v[224:227], v[104:107]
	v_mfma_f32_16x16x32_bf16 v[100:103], v[158:161], v[232:235], v[100:103]
	v_mfma_f32_16x16x32_bf16 v[96:99], v[174:177], v[232:235], v[96:99]
	s_setprio 0
	s_setprio 1
	v_mfma_f32_16x16x32_bf16 v[68:71], v[182:185], v[198:201], v[68:71]
	v_mfma_f32_16x16x32_bf16 v[64:67], v[190:193], v[198:201], v[64:67]
	v_mfma_f32_16x16x32_bf16 v[52:55], v[182:185], v[212:215], v[52:55]
	v_mfma_f32_16x16x32_bf16 v[48:51], v[190:193], v[212:215], v[48:51]
	v_mfma_f32_16x16x32_bf16 v[44:47], v[182:185], v[220:223], v[44:47]
	v_mfma_f32_16x16x32_bf16 v[40:43], v[190:193], v[220:223], v[40:43]
	v_mfma_f32_16x16x32_bf16 v[36:39], v[182:185], v[228:231], v[36:39]
	v_mfma_f32_16x16x32_bf16 v[32:35], v[190:193], v[228:231], v[32:35]
	v_mfma_f32_16x16x32_bf16 v[68:71], v[186:189], v[208:211], v[68:71]
	v_mfma_f32_16x16x32_bf16 v[64:67], v[194:197], v[208:211], v[64:67]
	v_mfma_f32_16x16x32_bf16 v[52:55], v[186:189], v[216:219], v[52:55]
	v_mfma_f32_16x16x32_bf16 v[48:51], v[194:197], v[216:219], v[48:51]
	v_mfma_f32_16x16x32_bf16 v[44:47], v[186:189], v[224:227], v[44:47]
	v_mfma_f32_16x16x32_bf16 v[40:43], v[194:197], v[224:227], v[40:43]
	v_mfma_f32_16x16x32_bf16 v[36:39], v[186:189], v[232:235], v[36:39]
	v_mfma_f32_16x16x32_bf16 v[32:35], v[194:197], v[232:235], v[32:35]
	s_setprio 0
	s_barrier
; #define PG8_STAGE(bufoff, gbase, voff) do { _Pragma("unroll") for (int _i = 0; _i < 2; ++_i) \
;         __builtin_amdgcn_global_load_lds((const unsigned*)((const char*)(gbase) + (voff)[_i]), (PG8_LAS unsigned*)(lds + (bufoff) + ldsw + _i * 8192), 16, 0, 0); } while (0)
; #define PG8_LDA(dst, b, h) do { _Pragma("unroll") for (int m = 0; m < 4; ++m) _Pragma("unroll") for (int k = 0; k < 2; ++k) dst[m][k] = *(const PG8_LAS bf16x8*)(lds + PG8_SA(b, h) + aoff + m * 2048 + k * 1024); } while (0)
; #define PG8_LDB(dst, b, h) do { _Pragma("unroll") for (int n = 0; n < 2; ++n) _Pragma("unroll") for (int k = 0; k < 2; ++k) dst[n][k] = *(const PG8_LAS bf16x8*)(lds + PG8_SB(b, h) + boff + n * 2048 + k * 1024); } while (0)
; #define PG8_MMA(ai, bj, At, Bt) do { __builtin_amdgcn_s_setprio(1); _Pragma("unroll") for (int m = 0; m < 4; ++m) _Pragma("unroll") for (int n = 0; n < 2; ++n) _Pragma("unroll") for (int k = 0; k < 2; ++k) \
;         acc[ai][bj][m][n] = __builtin_amdgcn_mfma_f32_16x16x32_bf16(Bt[n][k], At[m][k], acc[ai][bj][m][n], 0, 0, 0); __builtin_amdgcn_s_setprio(0); } while (0)
; #define PG8_WAIT_V(n) asm volatile("s_waitcnt vmcnt(" #n ")" ::: "memory")
; #define PG8_WAIT_L(n) asm volatile("s_waitcnt lgkmcnt(" #n ")" ::: "memory")
; #define PG8_BAR __builtin_amdgcn_s_barrier()
; #define PG8_SCHED __builtin_amdgcn_sched_barrier(0)
; template <class Epi, class Sched, bool ALIGN_EPI = false, bool SP2 = false>
; __device__ __forceinline__ void gemm_phase(PG8_LAS unsigned char* lds, const Gemm g, const Sched& S, const Epi& E) {
;     ...
;         for (int t = 0; t < nt; t += 2) {
;     ...
;             PG8_LDB(B0, 0, 0); PG8_LDB(B1, 0, 1); PG8_SCHED; PG8_LDA(At, 0, 0); PG8_STAGE(PG8_SA(1, 1), a1 + hstep, voffA);
;     ...
;             PG8_LDA(At, 1, 1); PG8_STAGE(PG8_SB(1, 0), b3, voffB); PG8_STAGE(PG8_SB(1, 1), b3 + hstep, voffB); PG8_STAGE(PG8_SA(1, 0), a3, voffA);
;             PG8_WAIT_V(8); PG8_WAIT_L(0); PG8_BAR; PG8_MMA(1, 0, At, B0); PG8_MMA(1, 1, At, B1); PG8_BAR; PG8_SCHED;
	s_add_i32 s3, s3, s34
	v_lshl_add_u64 v[178:179], v[178:179], 0, s[8:9]
	s_mov_b32 m0, s3
	ds_read_b128 v[198:201], v171 offset:49152
	ds_read_b128 v[208:211], v171 offset:50176
	ds_read_b128 v[212:215], v171 offset:51200
	ds_read_b128 v[216:219], v171 offset:52224
	ds_read_b128 v[220:223], v171 offset:53248
	ds_read_b128 v[224:227], v171 offset:54272
	ds_read_b128 v[228:231], v171 offset:55296
	ds_read_b128 v[232:235], v171 offset:56320
	global_load_lds_dwordx4 v[178:179], off
	s_add_i32 m0, s3, 0x2000
	s_add_u32 s14, s56, 0x40080
	v_lshl_add_u64 v[178:179], v[202:203], 0, s[8:9]
	s_addc_u32 s15, s57, 0
	s_add_i32 s3, s33, s34
	global_load_lds_dwordx4 v[178:179], off
	v_lshl_add_u64 v[178:179], s[14:15], 0, v[132:133]
	s_mov_b32 m0, s3
	s_nop 0
	global_load_lds_dwordx4 v[178:179], off
	v_lshl_add_u64 v[178:179], s[14:15], 0, v[128:129]
	s_add_i32 m0, s3, 0x2000
	s_nop 0
	global_load_lds_dwordx4 v[178:179], off
	s_waitcnt vmcnt(6)
	s_waitcnt lgkmcnt(0)
	s_barrier
	s_setprio 1
	s_waitcnt lgkmcnt(0)
	v_mfma_f32_16x16x32_bf16 v[92:95], v[154:157], v[198:201], v[92:95]
	v_mfma_f32_16x16x32_bf16 v[88:91], v[162:165], v[198:201], v[88:91]
	v_mfma_f32_16x16x32_bf16 v[84:87], v[154:157], v[212:215], v[84:87]
	v_mfma_f32_16x16x32_bf16 v[80:83], v[162:165], v[212:215], v[80:83]
	v_mfma_f32_16x16x32_bf16 v[76:79], v[154:157], v[220:223], v[76:79]
	v_mfma_f32_16x16x32_bf16 v[72:75], v[162:165], v[220:223], v[72:75]
	v_mfma_f32_16x16x32_bf16 v[60:63], v[154:157], v[228:231], v[60:63]
	v_mfma_f32_16x16x32_bf16 v[56:59], v[162:165], v[228:231], v[56:59]
	v_mfma_f32_16x16x32_bf16 v[92:95], v[158:161], v[208:211], v[92:95]
	v_mfma_f32_16x16x32_bf16 v[88:91], v[174:177], v[208:211], v[88:91]
	v_mfma_f32_16x16x32_bf16 v[84:87], v[158:161], v[216:219], v[84:87]
	v_mfma_f32_16x16x32_bf16 v[80:83], v[174:177], v[216:219], v[80:83]
	v_mfma_f32_16x16x32_bf16 v[76:79], v[158:161], v[224:227], v[76:79]
	v_mfma_f32_16x16x32_bf16 v[72:75], v[174:177], v[224:227], v[72:75]
	v_mfma_f32_16x16x32_bf16 v[60:63], v[158:161], v[232:235], v[60:63]
	v_lshl_add_u64 v[178:179], v[236:237], 0, s[8:9]
	s_mov_b32 m0, s66
	s_nop 0
	global_load_lds_dwordx4 v[178:179], off
	v_mfma_f32_16x16x32_bf16 v[56:59], v[174:177], v[232:235], v[56:59]
	s_setprio 0
	s_setprio 1
	v_mfma_f32_16x16x32_bf16 v[28:31], v[182:185], v[198:201], v[28:31]
	v_mfma_f32_16x16x32_bf16 v[24:27], v[190:193], v[198:201], v[24:27]
	v_mfma_f32_16x16x32_bf16 v[20:23], v[182:185], v[212:215], v[20:23]
	v_mfma_f32_16x16x32_bf16 v[16:19], v[190:193], v[212:215], v[16:19]
	v_mfma_f32_16x16x32_bf16 v[12:15], v[182:185], v[220:223], v[12:15]
	v_mfma_f32_16x16x32_bf16 v[8:11], v[190:193], v[220:223], v[8:11]
	v_mfma_f32_16x16x32_bf16 v[4:7], v[182:185], v[228:231], v[4:7]
	v_mfma_f32_16x16x32_bf16 v[0:3], v[190:193], v[228:231], v[0:3]
	v_mfma_f32_16x16x32_bf16 v[28:31], v[186:189], v[208:211], v[28:31]
	v_mfma_f32_16x16x32_bf16 v[24:27], v[194:197], v[208:211], v[24:27]
	v_mfma_f32_16x16x32_bf16 v[20:23], v[186:189], v[216:219], v[20:23]
	v_mfma_f32_16x16x32_bf16 v[16:19], v[194:197], v[216:219], v[16:19]
	v_mfma_f32_16x16x32_bf16 v[12:15], v[186:189], v[224:227], v[12:15]
	v_mfma_f32_16x16x32_bf16 v[8:11], v[194:197], v[224:227], v[8:11]
	v_mfma_f32_16x16x32_bf16 v[4:7], v[186:189], v[232:235], v[4:7]
	v_lshl_add_u64 v[178:179], v[238:239], 0, s[8:9]
	s_mov_b32 m0, s67
	s_nop 0
	global_load_lds_dwordx4 v[178:179], off
	v_mfma_f32_16x16x32_bf16 v[0:3], v[194:197], v[232:235], v[0:3]
	s_setprio 0
	s_barrier
	s_add_i32 s93, s93, 2
	s_add_u32 s54, s54, 0x100
	s_addc_u32 s55, s55, 0
	s_add_u32 s91, s91, 0x100
	s_addc_u32 s92, s92, 0
.LBB0_417:
	ds_read_b128 v[154:157], v169
	ds_read_b128 v[158:161], v169 offset:1024
	ds_read_b128 v[162:165], v169 offset:2048
	ds_read_b128 v[174:177], v169 offset:3072
	ds_read_b128 v[182:185], v170
	ds_read_b128 v[186:189], v170 offset:1024
	ds_read_b128 v[190:193], v170 offset:2048
	ds_read_b128 v[194:197], v170 offset:3072
	s_add_u32 s3, s54, 0xfffc0080
	s_addc_u32 s14, s55, -1
	s_cmp_eq_u32 s93, 12
	s_cselect_b32 s59, s45, s14
	s_cselect_b32 s58, s89, s3
	s_cselect_b32 s57, s41, s92
	s_cselect_b32 s56, s90, s91
	v_lshl_add_u64 v[178:179], s[54:55], 0, v[146:147]
	s_add_i32 m0, s60, 0xc000
	ds_read_b128 v[198:201], v171
	ds_read_b128 v[208:211], v171 offset:1024
	ds_read_b128 v[212:215], v171 offset:2048
	ds_read_b128 v[216:219], v171 offset:3072
	ds_read_b128 v[220:223], v171 offset:4096
	ds_read_b128 v[224:227], v171 offset:5120
	ds_read_b128 v[228:231], v171 offset:6144
	ds_read_b128 v[232:235], v171 offset:7168
	global_load_lds_dwordx4 v[178:179], off
	v_lshl_add_u64 v[178:179], s[54:55], 0, v[148:149]
	s_add_i32 m0, s60, 0xe000
	s_nop 0
	global_load_lds_dwordx4 v[178:179], off
	s_waitcnt vmcnt(8)
	s_waitcnt lgkmcnt(0)
	s_barrier
; #define PG8_STAGE(bufoff, gbase, voff) do { _Pragma("unroll") for (int _i = 0; _i < 2; ++_i) \
;         __builtin_amdgcn_global_load_lds((const unsigned*)((const char*)(gbase) + (voff)[_i]), (PG8_LAS unsigned*)(lds + (bufoff) + ldsw + _i * 8192), 16, 0, 0); } while (0)
; #define PG8_LDA(dst, b, h) do { _Pragma("unroll") for (int m = 0; m < 4; ++m) _Pragma("unroll") for (int k = 0; k < 2; ++k) dst[m][k] = *(const PG8_LAS bf16x8*)(lds + PG8_SA(b, h) + aoff + m * 2048 + k * 1024); } while (0)
; #define PG8_MMA(ai, bj, At, Bt) do { __builtin_amdgcn_s_setprio(1); _Pragma("unroll") for (int m = 0; m < 4; ++m) _Pragma("unroll") for (int n = 0; n < 2; ++n) _Pragma("unroll") for (int k = 0; k < 2; ++k) \
;         acc[ai][bj][m][n] = __builtin_amdgcn_mfma_f32_16x16x32_bf16(Bt[n][k], At[m][k], acc[ai][bj][m][n], 0, 0, 0); __builtin_amdgcn_s_setprio(0); } while (0)
; #define PG8_WAIT_V(n) asm volatile("s_waitcnt vmcnt(" #n ")" ::: "memory")
; #define PG8_WAIT_L(n) asm volatile("s_waitcnt lgkmcnt(" #n ")" ::: "memory")
; #define PG8_BAR __builtin_amdgcn_s_barrier()
; #define PG8_SCHED __builtin_amdgcn_sched_barrier(0)
; template <class Epi, class Sched, bool ALIGN_EPI = false, bool SP2 = false>
; __device__ __forceinline__ void gemm_phase(PG8_LAS unsigned char* lds, const Gemm g, const Sched& S, const Epi& E) {
;     ...
;             PG8_WAIT_V(8); PG8_WAIT_L(0); PG8_BAR; PG8_MMA(0, 0, At, B0); PG8_MMA(0, 1, At, B1); PG8_BAR; PG8_SCHED;
;             PG8_LDA(At, 0, 1); PG8_STAGE(PG8_SB(0, 0), b2, voffB); PG8_STAGE(PG8_SB(0, 1), b2 + hstep, voffB); PG8_STAGE(PG8_SA(0, 0), a2, voffA);
;             PG8_WAIT_V(8); PG8_WAIT_L(0); PG8_BAR; PG8_MMA(1, 0, At, B0); PG8_MMA(1, 1, At, B1); PG8_BAR; PG8_SCHED;
	s_setprio 1
	s_waitcnt lgkmcnt(0)
	v_mfma_f32_16x16x32_bf16 v[124:127], v[154:157], v[198:201], v[124:127]
	v_mfma_f32_16x16x32_bf16 v[120:123], v[162:165], v[198:201], v[120:123]
	v_mfma_f32_16x16x32_bf16 v[116:119], v[154:157], v[212:215], v[116:119]
	v_mfma_f32_16x16x32_bf16 v[112:115], v[162:165], v[212:215], v[112:115]
	v_mfma_f32_16x16x32_bf16 v[108:111], v[154:157], v[220:223], v[108:111]
	v_mfma_f32_16x16x32_bf16 v[104:107], v[162:165], v[220:223], v[104:107]
	v_mfma_f32_16x16x32_bf16 v[100:103], v[154:157], v[228:231], v[100:103]
	v_mfma_f32_16x16x32_bf16 v[96:99], v[162:165], v[228:231], v[96:99]
	v_mfma_f32_16x16x32_bf16 v[124:127], v[158:161], v[208:211], v[124:127]
	v_mfma_f32_16x16x32_bf16 v[120:123], v[174:177], v[208:211], v[120:123]
	v_mfma_f32_16x16x32_bf16 v[116:119], v[158:161], v[216:219], v[116:119]
	v_mfma_f32_16x16x32_bf16 v[112:115], v[174:177], v[216:219], v[112:115]
	v_mfma_f32_16x16x32_bf16 v[108:111], v[158:161], v[224:227], v[108:111]
	v_mfma_f32_16x16x32_bf16 v[104:107], v[174:177], v[224:227], v[104:107]
	v_mfma_f32_16x16x32_bf16 v[100:103], v[158:161], v[232:235], v[100:103]
	v_mfma_f32_16x16x32_bf16 v[96:99], v[174:177], v[232:235], v[96:99]
	s_setprio 0
	s_setprio 1
	v_mfma_f32_16x16x32_bf16 v[68:71], v[182:185], v[198:201], v[68:71]
	v_mfma_f32_16x16x32_bf16 v[64:67], v[190:193], v[198:201], v[64:67]
	v_mfma_f32_16x16x32_bf16 v[52:55], v[182:185], v[212:215], v[52:55]
	v_mfma_f32_16x16x32_bf16 v[48:51], v[190:193], v[212:215], v[48:51]
	v_mfma_f32_16x16x32_bf16 v[44:47], v[182:185], v[220:223], v[44:47]
	v_mfma_f32_16x16x32_bf16 v[40:43], v[190:193], v[220:223], v[40:43]
	v_mfma_f32_16x16x32_bf16 v[36:39], v[182:185], v[228:231], v[36:39]
	v_mfma_f32_16x16x32_bf16 v[32:35], v[190:193], v[228:231], v[32:35]
	v_mfma_f32_16x16x32_bf16 v[68:71], v[186:189], v[208:211], v[68:71]
	v_mfma_f32_16x16x32_bf16 v[64:67], v[194:197], v[208:211], v[64:67]
	v_mfma_f32_16x16x32_bf16 v[52:55], v[186:189], v[216:219], v[52:55]
	v_mfma_f32_16x16x32_bf16 v[48:51], v[194:197], v[216:219], v[48:51]
	v_mfma_f32_16x16x32_bf16 v[44:47], v[186:189], v[224:227], v[44:47]
	v_mfma_f32_16x16x32_bf16 v[40:43], v[194:197], v[224:227], v[40:43]
	v_mfma_f32_16x16x32_bf16 v[36:39], v[186:189], v[232:235], v[36:39]
	v_mfma_f32_16x16x32_bf16 v[32:35], v[194:197], v[232:235], v[32:35]
	s_setprio 0
	s_barrier
	s_add_i32 s3, s86, s34
	v_lshl_add_u64 v[178:179], s[56:57], 0, v[132:133]
	s_mov_b32 m0, s3
	ds_read_b128 v[198:201], v171 offset:16384
	ds_read_b128 v[208:211], v171 offset:17408
	ds_read_b128 v[212:215], v171 offset:18432
	ds_read_b128 v[216:219], v171 offset:19456
	ds_read_b128 v[220:223], v171 offset:20480
	ds_read_b128 v[224:227], v171 offset:21504
	ds_read_b128 v[228:231], v171 offset:22528
	ds_read_b128 v[232:235], v171 offset:23552
	global_load_lds_dwordx4 v[178:179], off
	s_add_i32 m0, s3, 0x2000
	s_add_u32 s14, s56, 0x40000
	v_lshl_add_u64 v[202:203], s[56:57], 0, v[128:129]
	s_addc_u32 s15, s57, 0
	s_add_i32 s3, s87, s34
	global_load_lds_dwordx4 v[202:203], off
	v_lshl_add_u64 v[236:237], s[14:15], 0, v[132:133]
	s_mov_b32 m0, s3
	global_load_lds_dwordx4 v[236:237], off
	v_lshl_add_u64 v[236:237], s[14:15], 0, v[128:129]
	s_add_i32 m0, s3, 0x2000
	s_nop 0
	global_load_lds_dwordx4 v[236:237], off
	s_waitcnt vmcnt(6)
	s_waitcnt lgkmcnt(0)
	s_barrier
	s_setprio 1
	s_waitcnt lgkmcnt(0)
	v_mfma_f32_16x16x32_bf16 v[92:95], v[154:157], v[198:201], v[92:95]
	v_mfma_f32_16x16x32_bf16 v[88:91], v[162:165], v[198:201], v[88:91]
	v_mfma_f32_16x16x32_bf16 v[84:87], v[154:157], v[212:215], v[84:87]
	v_mfma_f32_16x16x32_bf16 v[80:83], v[162:165], v[212:215], v[80:83]
	v_mfma_f32_16x16x32_bf16 v[76:79], v[154:157], v[220:223], v[76:79]
	v_mfma_f32_16x16x32_bf16 v[72:75], v[162:165], v[220:223], v[72:75]
	v_mfma_f32_16x16x32_bf16 v[60:63], v[154:157], v[228:231], v[60:63]
	v_mfma_f32_16x16x32_bf16 v[56:59], v[162:165], v[228:231], v[56:59]
	v_mfma_f32_16x16x32_bf16 v[92:95], v[158:161], v[208:211], v[92:95]
	v_mfma_f32_16x16x32_bf16 v[88:91], v[174:177], v[208:211], v[88:91]
	v_mfma_f32_16x16x32_bf16 v[84:87], v[158:161], v[216:219], v[84:87]
	v_mfma_f32_16x16x32_bf16 v[80:83], v[174:177], v[216:219], v[80:83]
	v_mfma_f32_16x16x32_bf16 v[76:79], v[158:161], v[224:227], v[76:79]
	v_mfma_f32_16x16x32_bf16 v[72:75], v[174:177], v[224:227], v[72:75]
	v_mfma_f32_16x16x32_bf16 v[60:63], v[158:161], v[232:235], v[60:63]
	v_lshl_add_u64 v[236:237], s[58:59], 0, v[134:135]
	s_mov_b32 m0, s60
	s_nop 0
	global_load_lds_dwordx4 v[236:237], off
	v_mfma_f32_16x16x32_bf16 v[56:59], v[174:177], v[232:235], v[56:59]
	s_setprio 0
	s_setprio 1
	v_mfma_f32_16x16x32_bf16 v[28:31], v[182:185], v[198:201], v[28:31]
	v_mfma_f32_16x16x32_bf16 v[24:27], v[190:193], v[198:201], v[24:27]
	v_mfma_f32_16x16x32_bf16 v[20:23], v[182:185], v[212:215], v[20:23]
	v_mfma_f32_16x16x32_bf16 v[16:19], v[190:193], v[212:215], v[16:19]
	v_mfma_f32_16x16x32_bf16 v[12:15], v[182:185], v[220:223], v[12:15]
	v_mfma_f32_16x16x32_bf16 v[8:11], v[190:193], v[220:223], v[8:11]
	v_mfma_f32_16x16x32_bf16 v[4:7], v[182:185], v[228:231], v[4:7]
	v_mfma_f32_16x16x32_bf16 v[0:3], v[190:193], v[228:231], v[0:3]
	v_mfma_f32_16x16x32_bf16 v[28:31], v[186:189], v[208:211], v[28:31]
	v_mfma_f32_16x16x32_bf16 v[24:27], v[194:197], v[208:211], v[24:27]
	v_mfma_f32_16x16x32_bf16 v[20:23], v[186:189], v[216:219], v[20:23]
	v_mfma_f32_16x16x32_bf16 v[16:19], v[194:197], v[216:219], v[16:19]
	v_mfma_f32_16x16x32_bf16 v[12:15], v[186:189], v[224:227], v[12:15]
	v_mfma_f32_16x16x32_bf16 v[8:11], v[194:197], v[224:227], v[8:11]
	v_mfma_f32_16x16x32_bf16 v[4:7], v[186:189], v[232:235], v[4:7]
	v_lshl_add_u64 v[238:239], s[58:59], 0, v[130:131]
	s_mov_b32 m0, s61
	s_nop 0
	global_load_lds_dwordx4 v[238:239], off
	v_mfma_f32_16x16x32_bf16 v[0:3], v[194:197], v[232:235], v[0:3]
	s_setprio 0
	s_barrier
; #define PG8_STAGE(bufoff, gbase, voff) do { _Pragma("unroll") for (int _i = 0; _i < 2; ++_i) \
;         __builtin_amdgcn_global_load_lds((const unsigned*)((const char*)(gbase) + (voff)[_i]), (PG8_LAS unsigned*)(lds + (bufoff) + ldsw + _i * 8192), 16, 0, 0); } while (0)
; #define PG8_LDA(dst, b, h) do { _Pragma("unroll") for (int m = 0; m < 4; ++m) _Pragma("unroll") for (int k = 0; k < 2; ++k) dst[m][k] = *(const PG8_LAS bf16x8*)(lds + PG8_SA(b, h) + aoff + m * 2048 + k * 1024); } while (0)
; #define PG8_LDB(dst, b, h) do { _Pragma("unroll") for (int n = 0; n < 2; ++n) _Pragma("unroll") for (int k = 0; k < 2; ++k) dst[n][k] = *(const PG8_LAS bf16x8*)(lds + PG8_SB(b, h) + boff + n * 2048 + k * 1024); } while (0)
; #define PG8_MMA(ai, bj, At, Bt) do { __builtin_amdgcn_s_setprio(1); _Pragma("unroll") for (int m = 0; m < 4; ++m) _Pragma("unroll") for (int n = 0; n < 2; ++n) _Pragma("unroll") for (int k = 0; k < 2; ++k) \
;         acc[ai][bj][m][n] = __builtin_amdgcn_mfma_f32_16x16x32_bf16(Bt[n][k], At[m][k], acc[ai][bj][m][n], 0, 0, 0); __builtin_amdgcn_s_setprio(0); } while (0)
; #define PG8_WAIT_V(n) asm volatile("s_waitcnt vmcnt(" #n ")" ::: "memory")
; #define PG8_WAIT_L(n) asm volatile("s_waitcnt lgkmcnt(" #n ")" ::: "memory")
; #define PG8_BAR __builtin_amdgcn_s_barrier()
; #define PG8_SCHED __builtin_amdgcn_sched_barrier(0)
; template <class Epi, class Sched, bool ALIGN_EPI = false, bool SP2 = false>
; __device__ __forceinline__ void gemm_phase(PG8_LAS unsigned char* lds, const Gemm g, const Sched& S, const Epi& E) {
;     ...
;             PG8_LDB(B0, 1, 0); PG8_LDB(B1, 1, 1); PG8_SCHED; PG8_LDA(At, 1, 0); PG8_STAGE(PG8_SA(0, 1), a2 + hstep, voffA);
;             PG8_WAIT_V(8); PG8_WAIT_L(0); PG8_BAR; PG8_MMA(0, 0, At, B0); PG8_MMA(0, 1, At, B1); PG8_BAR; PG8_SCHED;
	s_add_i32 s3, 0, 0x18000
	v_add_u32_e32 v136, s3, v143
	s_add_i32 s33, 0, 0x1c000
	ds_read_b128 v[154:157], v136
	ds_read_b128 v[158:161], v136 offset:1024
	ds_read_b128 v[162:165], v136 offset:2048
	ds_read_b128 v[174:177], v136 offset:3072
	v_add_u32_e32 v136, s33, v143
	ds_read_b128 v[182:185], v136
	ds_read_b128 v[186:189], v136 offset:1024
	ds_read_b128 v[190:193], v136 offset:2048
	ds_read_b128 v[194:197], v136 offset:3072
	s_add_u32 s14, s58, 0x40000
	s_addc_u32 s15, s59, 0
	s_mov_b32 m0, s62
	v_lshl_add_u64 v[240:241], s[14:15], 0, v[134:135]
	ds_read_b128 v[198:201], v171 offset:32768
	ds_read_b128 v[208:211], v171 offset:33792
	ds_read_b128 v[212:215], v171 offset:34816
	ds_read_b128 v[216:219], v171 offset:35840
	ds_read_b128 v[220:223], v171 offset:36864
	ds_read_b128 v[224:227], v171 offset:37888
	ds_read_b128 v[228:231], v171 offset:38912
	ds_read_b128 v[232:235], v171 offset:39936
	global_load_lds_dwordx4 v[240:241], off
	v_lshl_add_u64 v[240:241], s[14:15], 0, v[130:131]
	s_mov_b32 m0, s63
	s_nop 0
	global_load_lds_dwordx4 v[240:241], off
	s_waitcnt vmcnt(8)
	s_waitcnt lgkmcnt(0)
	s_barrier
	s_setprio 1
	s_waitcnt lgkmcnt(0)
	v_mfma_f32_16x16x32_bf16 v[124:127], v[154:157], v[198:201], v[124:127]
	v_mfma_f32_16x16x32_bf16 v[120:123], v[162:165], v[198:201], v[120:123]
	v_mfma_f32_16x16x32_bf16 v[116:119], v[154:157], v[212:215], v[116:119]
	v_mfma_f32_16x16x32_bf16 v[112:115], v[162:165], v[212:215], v[112:115]
	v_mfma_f32_16x16x32_bf16 v[108:111], v[154:157], v[220:223], v[108:111]
	v_mfma_f32_16x16x32_bf16 v[104:107], v[162:165], v[220:223], v[104:107]
	v_mfma_f32_16x16x32_bf16 v[100:103], v[154:157], v[228:231], v[100:103]
	v_mfma_f32_16x16x32_bf16 v[96:99], v[162:165], v[228:231], v[96:99]
	v_mfma_f32_16x16x32_bf16 v[124:127], v[158:161], v[208:211], v[124:127]
	v_mfma_f32_16x16x32_bf16 v[120:123], v[174:177], v[208:211], v[120:123]
	v_mfma_f32_16x16x32_bf16 v[116:119], v[158:161], v[216:219], v[116:119]
	v_mfma_f32_16x16x32_bf16 v[112:115], v[174:177], v[216:219], v[112:115]
	v_mfma_f32_16x16x32_bf16 v[108:111], v[158:161], v[224:227], v[108:111]
	v_mfma_f32_16x16x32_bf16 v[104:107], v[174:177], v[224:227], v[104:107]
	v_mfma_f32_16x16x32_bf16 v[100:103], v[158:161], v[232:235], v[100:103]
	v_mfma_f32_16x16x32_bf16 v[96:99], v[174:177], v[232:235], v[96:99]
	s_setprio 0
	s_setprio 1
	v_mfma_f32_16x16x32_bf16 v[68:71], v[182:185], v[198:201], v[68:71]
	v_mfma_f32_16x16x32_bf16 v[64:67], v[190:193], v[198:201], v[64:67]
	v_mfma_f32_16x16x32_bf16 v[52:55], v[182:185], v[212:215], v[52:55]
	v_mfma_f32_16x16x32_bf16 v[48:51], v[190:193], v[212:215], v[48:51]
	v_mfma_f32_16x16x32_bf16 v[44:47], v[182:185], v[220:223], v[44:47]
	v_mfma_f32_16x16x32_bf16 v[40:43], v[190:193], v[220:223], v[40:43]
	v_mfma_f32_16x16x32_bf16 v[36:39], v[182:185], v[228:231], v[36:39]
	v_mfma_f32_16x16x32_bf16 v[32:35], v[190:193], v[228:231], v[32:35]
	v_mfma_f32_16x16x32_bf16 v[68:71], v[186:189], v[208:211], v[68:71]
	v_mfma_f32_16x16x32_bf16 v[64:67], v[194:197], v[208:211], v[64:67]
	v_mfma_f32_16x16x32_bf16 v[52:55], v[186:189], v[216:219], v[52:55]
	v_mfma_f32_16x16x32_bf16 v[48:51], v[194:197], v[216:219], v[48:51]
	v_mfma_f32_16x16x32_bf16 v[44:47], v[186:189], v[224:227], v[44:47]
	v_mfma_f32_16x16x32_bf16 v[40:43], v[194:197], v[224:227], v[40:43]
	v_mfma_f32_16x16x32_bf16 v[36:39], v[186:189], v[232:235], v[36:39]
	v_mfma_f32_16x16x32_bf16 v[32:35], v[194:197], v[232:235], v[32:35]
	s_setprio 0
	s_barrier
; #define PG8_STAGE(bufoff, gbase, voff) do { _Pragma("unroll") for (int _i = 0; _i < 2; ++_i) \
;         __builtin_amdgcn_global_load_lds((const unsigned*)((const char*)(gbase) + (voff)[_i]), (PG8_LAS unsigned*)(lds + (bufoff) + ldsw + _i * 8192), 16, 0, 0); } while (0)
; #define PG8_LDA(dst, b, h) do { _Pragma("unroll") for (int m = 0; m < 4; ++m) _Pragma("unroll") for (int k = 0; k < 2; ++k) dst[m][k] = *(const PG8_LAS bf16x8*)(lds + PG8_SA(b, h) + aoff + m * 2048 + k * 1024); } while (0)
; #define PG8_MMA(ai, bj, At, Bt) do { __builtin_amdgcn_s_setprio(1); _Pragma("unroll") for (int m = 0; m < 4; ++m) _Pragma("unroll") for (int n = 0; n < 2; ++n) _Pragma("unroll") for (int k = 0; k < 2; ++k) \
;         acc[ai][bj][m][n] = __builtin_amdgcn_mfma_f32_16x16x32_bf16(Bt[n][k], At[m][k], acc[ai][bj][m][n], 0, 0, 0); __builtin_amdgcn_s_setprio(0); } while (0)
; #define PG8_WAIT_V(n) asm volatile("s_waitcnt vmcnt(" #n ")" ::: "memory")
; #define PG8_WAIT_L(n) asm volatile("s_waitcnt lgkmcnt(" #n ")" ::: "memory")
; #define PG8_BAR __builtin_amdgcn_s_barrier()
; #define PG8_SCHED __builtin_amdgcn_sched_barrier(0)
; template <class Epi, class Sched, bool ALIGN_EPI = false, bool SP2 = false>
; __device__ __forceinline__ void gemm_phase(PG8_LAS unsigned char* lds, const Gemm g, const Sched& S, const Epi& E) {
;     ...
;             PG8_LDA(At, 1, 1); PG8_STAGE(PG8_SB(1, 0), b3, voffB); PG8_STAGE(PG8_SB(1, 1), b3 + hstep, voffB); PG8_STAGE(PG8_SA(1, 0), a3, voffA);
;             PG8_WAIT_V(8); PG8_WAIT_L(0); PG8_BAR; PG8_MMA(1, 0, At, B0); PG8_MMA(1, 1, At, B1); PG8_BAR; PG8_SCHED;
;     ...
;         if constexpr (ALIGN_EPI) { if (wr == 0) PG8_BAR; }
	s_add_i32 s3, s3, s34
	v_lshl_add_u64 v[178:179], v[178:179], 0, s[8:9]
	s_mov_b32 m0, s3
	ds_read_b128 v[198:201], v171 offset:49152
	ds_read_b128 v[208:211], v171 offset:50176
	ds_read_b128 v[212:215], v171 offset:51200
	ds_read_b128 v[216:219], v171 offset:52224
	ds_read_b128 v[220:223], v171 offset:53248
	ds_read_b128 v[224:227], v171 offset:54272
	ds_read_b128 v[228:231], v171 offset:55296
	ds_read_b128 v[232:235], v171 offset:56320
	global_load_lds_dwordx4 v[178:179], off
	s_add_i32 m0, s3, 0x2000
	s_add_u32 s14, s56, 0x40080
	v_lshl_add_u64 v[178:179], v[202:203], 0, s[8:9]
	s_addc_u32 s15, s57, 0
	s_add_i32 s3, s33, s34
	global_load_lds_dwordx4 v[178:179], off
	v_lshl_add_u64 v[178:179], s[14:15], 0, v[132:133]
	s_mov_b32 m0, s3
	s_nop 0
	global_load_lds_dwordx4 v[178:179], off
	v_lshl_add_u64 v[178:179], s[14:15], 0, v[128:129]
	s_add_i32 m0, s3, 0x2000
	s_nop 0
	global_load_lds_dwordx4 v[178:179], off
	s_waitcnt vmcnt(6)
	s_waitcnt lgkmcnt(0)
	s_barrier
	s_setprio 1
	s_waitcnt lgkmcnt(0)
	v_mfma_f32_16x16x32_bf16 v[92:95], v[154:157], v[198:201], v[92:95]
	v_mfma_f32_16x16x32_bf16 v[88:91], v[162:165], v[198:201], v[88:91]
	v_mfma_f32_16x16x32_bf16 v[84:87], v[154:157], v[212:215], v[84:87]
	v_mfma_f32_16x16x32_bf16 v[80:83], v[162:165], v[212:215], v[80:83]
	v_mfma_f32_16x16x32_bf16 v[76:79], v[154:157], v[220:223], v[76:79]
	v_mfma_f32_16x16x32_bf16 v[72:75], v[162:165], v[220:223], v[72:75]
	v_mfma_f32_16x16x32_bf16 v[60:63], v[154:157], v[228:231], v[60:63]
	v_mfma_f32_16x16x32_bf16 v[56:59], v[162:165], v[228:231], v[56:59]
	v_mfma_f32_16x16x32_bf16 v[92:95], v[158:161], v[208:211], v[92:95]
	v_mfma_f32_16x16x32_bf16 v[88:91], v[174:177], v[208:211], v[88:91]
	v_mfma_f32_16x16x32_bf16 v[84:87], v[158:161], v[216:219], v[84:87]
	v_mfma_f32_16x16x32_bf16 v[80:83], v[174:177], v[216:219], v[80:83]
	v_mfma_f32_16x16x32_bf16 v[76:79], v[158:161], v[224:227], v[76:79]
	v_mfma_f32_16x16x32_bf16 v[72:75], v[174:177], v[224:227], v[72:75]
	v_mfma_f32_16x16x32_bf16 v[60:63], v[158:161], v[232:235], v[60:63]
	v_lshl_add_u64 v[178:179], v[236:237], 0, s[8:9]
	s_mov_b32 m0, s66
	s_nop 0
	global_load_lds_dwordx4 v[178:179], off
	v_mfma_f32_16x16x32_bf16 v[56:59], v[174:177], v[232:235], v[56:59]
	s_setprio 0
	s_setprio 1
	v_mfma_f32_16x16x32_bf16 v[28:31], v[182:185], v[198:201], v[28:31]
	v_mfma_f32_16x16x32_bf16 v[24:27], v[190:193], v[198:201], v[24:27]
	v_mfma_f32_16x16x32_bf16 v[20:23], v[182:185], v[212:215], v[20:23]
	v_mfma_f32_16x16x32_bf16 v[16:19], v[190:193], v[212:215], v[16:19]
	v_mfma_f32_16x16x32_bf16 v[12:15], v[182:185], v[220:223], v[12:15]
	v_mfma_f32_16x16x32_bf16 v[8:11], v[190:193], v[220:223], v[8:11]
	v_mfma_f32_16x16x32_bf16 v[4:7], v[182:185], v[228:231], v[4:7]
	v_mfma_f32_16x16x32_bf16 v[0:3], v[190:193], v[228:231], v[0:3]
	v_mfma_f32_16x16x32_bf16 v[28:31], v[186:189], v[208:211], v[28:31]
	v_mfma_f32_16x16x32_bf16 v[24:27], v[194:197], v[208:211], v[24:27]
	v_mfma_f32_16x16x32_bf16 v[20:23], v[186:189], v[216:219], v[20:23]
	v_mfma_f32_16x16x32_bf16 v[16:19], v[194:197], v[216:219], v[16:19]
	v_mfma_f32_16x16x32_bf16 v[12:15], v[186:189], v[224:227], v[12:15]
	v_mfma_f32_16x16x32_bf16 v[8:11], v[194:197], v[224:227], v[8:11]
	v_mfma_f32_16x16x32_bf16 v[4:7], v[186:189], v[232:235], v[4:7]
	v_lshl_add_u64 v[178:179], v[238:239], 0, s[8:9]
	s_mov_b32 m0, s67
	s_nop 0
	global_load_lds_dwordx4 v[178:179], off
	v_mfma_f32_16x16x32_bf16 v[0:3], v[194:197], v[232:235], v[0:3]
	s_setprio 0
	s_barrier
	s_add_i32 s93, s93, 2
	s_add_u32 s54, s54, 0x100
	s_addc_u32 s55, s55, 0
	s_add_u32 s91, s91, 0x100
	s_addc_u32 s92, s92, 0
	s_cmp_gt_u32 s93, 13
	s_cbranch_scc0 .LBB0_417
	s_and_b64 vcc, exec, s[10:11]
	s_cbranch_vccz .LBB0_420
	s_barrier

; #define PG8_STAGE(bufoff, gbase, voff) do { _Pragma("unroll") for (int _i = 0; _i < 2; ++_i) \
;         __builtin_amdgcn_global_load_lds((const unsigned*)((const char*)(gbase) + (voff)[_i]), (PG8_LAS unsigned*)(lds + (bufoff) + ldsw + _i * 8192), 16, 0, 0); } while (0)
; #define PG8_LDA(dst, b, h) do { _Pragma("unroll") for (int m = 0; m < 4; ++m) _Pragma("unroll") for (int k = 0; k < 2; ++k) dst[m][k] = *(const PG8_LAS bf16x8*)(lds + PG8_SA(b, h) + aoff + m * 2048 + k * 1024); } while (0)
; #define PG8_LDB(dst, b, h) do { _Pragma("unroll") for (int n = 0; n < 2; ++n) _Pragma("unroll") for (int k = 0; k < 2; ++k) dst[n][k] = *(const PG8_LAS bf16x8*)(lds + PG8_SB(b, h) + boff + n * 2048 + k * 1024); } while (0)
; #define PG8_MMA(ai, bj, At, Bt) do { __builtin_amdgcn_s_setprio(1); _Pragma("unroll") for (int m = 0; m < 4; ++m) _Pragma("unroll") for (int n = 0; n < 2; ++n) _Pragma("unroll") for (int k = 0; k < 2; ++k) \
;         acc[ai][bj][m][n] = __builtin_amdgcn_mfma_f32_16x16x32_bf16(Bt[n][k], At[m][k], acc[ai][bj][m][n], 0, 0, 0); __builtin_amdgcn_s_setprio(0); } while (0)
; #define PG8_WAIT_V(n) asm volatile("s_waitcnt vmcnt(" #n ")" ::: "memory")
; #define PG8_WAIT_L(n) asm volatile("s_waitcnt lgkmcnt(" #n ")" ::: "memory")
; #define PG8_BAR __builtin_amdgcn_s_barrier()
; template <class Epi, class Sched, bool ALIGN_EPI = false, bool SP2 = false>
; __device__ __forceinline__ void gemm_phase(PG8_LAS unsigned char* lds, const Gemm g, const Sched& S, const Epi& E) {
;     ...
;         const bool has_next = S.next(ui + 1, nxt);
;         const char* nA = has_next ? (const char*)g.A + (size_t)nxt.pm * tstep : cA; const char* nB = has_next ? (const char*)g.Bt + (size_t)nxt.pn * tstep : cB;
;         for (int t = 0; t < nt; t += 2) {
;             const bool last = (t == nt - 2);
;             const char* a1 = cA + (size_t)(t + 1) * kstep;
;             const char* a2 = last ? nA : cA + (size_t)(t + 2) * kstep; const char* b2 = last ? nB : cB + (size_t)(t + 2) * kstep;
;             const char* a3 = a2 + kstep; const char* b3 = b2 + kstep;
;             if (last && has_next) S.a_ready(nxt);
;             if constexpr (SP2) {
;             PG8_LDB(B0, 0, 0); PG8_LDB(B1, 0, 1); PG8_SCHED; PG8_LDA(At, 0, 0); PG8_STAGE(PG8_SA(1, 1), a1 + hstep, voffA);
;             PG8_WAIT_V(8); PG8_WAIT_L(0); PG8_BAR; PG8_MMA(0, 0, At, B0); PG8_MMA(0, 1, At, B1); PG8_BAR; PG8_SCHED;
.LBB0_458:
	s_ashr_i32 s49, s48, 31
	s_lshl_b64 s[14:15], s[48:49], 19
	s_add_u32 s50, s34, s14
	s_addc_u32 s51, s43, s15
	s_and_b64 s[14:15], s[40:41], exec
	s_cselect_b32 s49, s51, s59
	s_cselect_b32 s55, s50, s58
	s_ashr_i32 s45, s44, 31
	s_lshl_b64 s[14:15], s[44:45], 19
	v_readlane_b32 s3, v250, 13
	s_add_u32 s52, s3, s14
	v_readlane_b32 s3, v250, 14
	s_addc_u32 s53, s3, s15
	s_and_b64 s[14:15], s[40:41], exec
	s_cselect_b32 s45, s53, s61
	s_cselect_b32 s57, s52, s60
	s_add_u32 s58, s58, 0x40080
	s_addc_u32 s59, s59, 0
	s_add_u32 s96, s60, 0x100
	s_addc_u32 s97, s61, 0
	s_mov_b32 vcc_lo, -2
	ds_read_b128 v[170:173], v165
	ds_read_b128 v[174:177], v165 offset:1024
	ds_read_b128 v[182:185], v165 offset:2048
	ds_read_b128 v[186:189], v165 offset:3072
	ds_read_b128 v[190:193], v168
	ds_read_b128 v[194:197], v168 offset:1024
	ds_read_b128 v[198:201], v168 offset:2048
	ds_read_b128 v[208:211], v168 offset:3072
	s_add_u32 s3, s58, 0xfffc0080
	s_addc_u32 s14, s59, -1
	s_cmp_eq_u32 vcc_lo, 12
	s_cselect_b32 s63, s49, s14
	s_cselect_b32 s62, s55, s3
	s_cselect_b32 s61, s45, s97
	s_cselect_b32 s60, s57, s96
	v_lshl_add_u64 v[178:179], s[58:59], 0, v[160:161]
	s_add_i32 m0, s85, 0xc000
	ds_read_b128 v[212:215], v164
	ds_read_b128 v[216:219], v164 offset:1024
	ds_read_b128 v[220:223], v164 offset:2048
	ds_read_b128 v[224:227], v164 offset:3072
	ds_read_b128 v[228:231], v164 offset:4096
	ds_read_b128 v[232:235], v164 offset:5120
	ds_read_b128 v[236:239], v164 offset:6144
	ds_read_b128 v[240:243], v164 offset:7168
	global_load_lds_dwordx4 v[178:179], off
	v_lshl_add_u64 v[178:179], s[58:59], 0, v[162:163]
	s_add_i32 m0, s85, 0xe000
	s_nop 0
	global_load_lds_dwordx4 v[178:179], off
	s_waitcnt vmcnt(8)
	s_waitcnt lgkmcnt(0)
	s_barrier
	s_setprio 1
	s_waitcnt lgkmcnt(0)
	v_mfma_f32_16x16x32_bf16 v[124:127], v[170:173], v[212:215], 0
	v_mfma_f32_16x16x32_bf16 v[120:123], v[182:185], v[212:215], 0
	v_mfma_f32_16x16x32_bf16 v[116:119], v[170:173], v[220:223], 0
	v_mfma_f32_16x16x32_bf16 v[112:115], v[182:185], v[220:223], 0
	v_mfma_f32_16x16x32_bf16 v[108:111], v[170:173], v[228:231], 0
	v_mfma_f32_16x16x32_bf16 v[104:107], v[182:185], v[228:231], 0
	v_mfma_f32_16x16x32_bf16 v[100:103], v[170:173], v[236:239], 0
	v_mfma_f32_16x16x32_bf16 v[96:99], v[182:185], v[236:239], 0
	v_mfma_f32_16x16x32_bf16 v[124:127], v[174:177], v[216:219], v[124:127]
	v_mfma_f32_16x16x32_bf16 v[120:123], v[186:189], v[216:219], v[120:123]
	v_mfma_f32_16x16x32_bf16 v[116:119], v[174:177], v[224:227], v[116:119]
	v_mfma_f32_16x16x32_bf16 v[112:115], v[186:189], v[224:227], v[112:115]
	v_mfma_f32_16x16x32_bf16 v[108:111], v[174:177], v[232:235], v[108:111]
	v_mfma_f32_16x16x32_bf16 v[104:107], v[186:189], v[232:235], v[104:107]
	v_mfma_f32_16x16x32_bf16 v[100:103], v[174:177], v[240:243], v[100:103]
	v_mfma_f32_16x16x32_bf16 v[96:99], v[186:189], v[240:243], v[96:99]
	s_setprio 0
	s_setprio 1
	v_mfma_f32_16x16x32_bf16 v[60:63], v[190:193], v[212:215], 0
	v_mfma_f32_16x16x32_bf16 v[56:59], v[198:201], v[212:215], 0
	v_mfma_f32_16x16x32_bf16 v[52:55], v[190:193], v[220:223], 0
	v_mfma_f32_16x16x32_bf16 v[48:51], v[198:201], v[220:223], 0
	v_mfma_f32_16x16x32_bf16 v[44:47], v[190:193], v[228:231], 0
	v_mfma_f32_16x16x32_bf16 v[40:43], v[198:201], v[228:231], 0
	v_mfma_f32_16x16x32_bf16 v[36:39], v[190:193], v[236:239], 0
	v_mfma_f32_16x16x32_bf16 v[32:35], v[198:201], v[236:239], 0
	v_mfma_f32_16x16x32_bf16 v[60:63], v[194:197], v[216:219], v[60:63]
	v_mfma_f32_16x16x32_bf16 v[56:59], v[208:211], v[216:219], v[56:59]
	v_mfma_f32_16x16x32_bf16 v[52:55], v[194:197], v[224:227], v[52:55]
	v_mfma_f32_16x16x32_bf16 v[48:51], v[208:211], v[224:227], v[48:51]
	v_mfma_f32_16x16x32_bf16 v[44:47], v[194:197], v[232:235], v[44:47]
	v_mfma_f32_16x16x32_bf16 v[40:43], v[208:211], v[232:235], v[40:43]
	v_mfma_f32_16x16x32_bf16 v[36:39], v[194:197], v[240:243], v[36:39]
	v_mfma_f32_16x16x32_bf16 v[32:35], v[208:211], v[240:243], v[32:35]
	s_setprio 0
	s_barrier
	s_add_i32 s3, s94, s84
	v_lshl_add_u64 v[178:179], s[60:61], 0, v[130:131]
	s_mov_b32 m0, s3
	ds_read_b128 v[212:215], v164 offset:16384
	ds_read_b128 v[216:219], v164 offset:17408
	ds_read_b128 v[220:223], v164 offset:18432
	ds_read_b128 v[224:227], v164 offset:19456
	ds_read_b128 v[228:231], v164 offset:20480
	ds_read_b128 v[232:235], v164 offset:21504
	ds_read_b128 v[236:239], v164 offset:22528
	ds_read_b128 v[240:243], v164 offset:23552
	global_load_lds_dwordx4 v[178:179], off
	s_add_i32 m0, s3, 0x2000
	s_add_u32 s14, s60, 0x40000
	v_lshl_add_u64 v[202:203], s[60:61], 0, v[134:135]
	s_addc_u32 s15, s61, 0
	s_add_i32 s3, s95, s84
	global_load_lds_dwordx4 v[202:203], off
	v_lshl_add_u64 v[244:245], s[14:15], 0, v[130:131]
	s_mov_b32 m0, s3
	global_load_lds_dwordx4 v[244:245], off
	v_lshl_add_u64 v[244:245], s[14:15], 0, v[134:135]
	s_add_i32 m0, s3, 0x2000
	s_nop 0
	global_load_lds_dwordx4 v[244:245], off
	s_waitcnt vmcnt(6)
	s_waitcnt lgkmcnt(0)
	s_barrier
; #define PG8_STAGE(bufoff, gbase, voff) do { _Pragma("unroll") for (int _i = 0; _i < 2; ++_i) \
;         __builtin_amdgcn_global_load_lds((const unsigned*)((const char*)(gbase) + (voff)[_i]), (PG8_LAS unsigned*)(lds + (bufoff) + ldsw + _i * 8192), 16, 0, 0); } while (0)
; #define PG8_LDA(dst, b, h) do { _Pragma("unroll") for (int m = 0; m < 4; ++m) _Pragma("unroll") for (int k = 0; k < 2; ++k) dst[m][k] = *(const PG8_LAS bf16x8*)(lds + PG8_SA(b, h) + aoff + m * 2048 + k * 1024); } while (0)
; #define PG8_LDB(dst, b, h) do { _Pragma("unroll") for (int n = 0; n < 2; ++n) _Pragma("unroll") for (int k = 0; k < 2; ++k) dst[n][k] = *(const PG8_LAS bf16x8*)(lds + PG8_SB(b, h) + boff + n * 2048 + k * 1024); } while (0)
; #define PG8_MMA(ai, bj, At, Bt) do { __builtin_amdgcn_s_setprio(1); _Pragma("unroll") for (int m = 0; m < 4; ++m) _Pragma("unroll") for (int n = 0; n < 2; ++n) _Pragma("unroll") for (int k = 0; k < 2; ++k) \
;         acc[ai][bj][m][n] = __builtin_amdgcn_mfma_f32_16x16x32_bf16(Bt[n][k], At[m][k], acc[ai][bj][m][n], 0, 0, 0); __builtin_amdgcn_s_setprio(0); } while (0)
; #define PG8_WAIT_V(n) asm volatile("s_waitcnt vmcnt(" #n ")" ::: "memory")
; #define PG8_WAIT_L(n) asm volatile("s_waitcnt lgkmcnt(" #n ")" ::: "memory")
; #define PG8_BAR __builtin_amdgcn_s_barrier()
; #define PG8_SCHED __builtin_amdgcn_sched_barrier(0)
; template <class Epi, class Sched, bool ALIGN_EPI = false, bool SP2 = false>
; __device__ __forceinline__ void gemm_phase(PG8_LAS unsigned char* lds, const Gemm g, const Sched& S, const Epi& E) {
;     ...
;             PG8_WAIT_V(8); PG8_WAIT_L(0); PG8_BAR; PG8_MMA(1, 0, At, B0); PG8_MMA(1, 1, At, B1); PG8_BAR; PG8_SCHED;
;             PG8_LDB(B0, 1, 0); PG8_LDB(B1, 1, 1); PG8_SCHED; PG8_LDA(At, 1, 0); PG8_STAGE(PG8_SA(0, 1), a2 + hstep, voffA);
;             PG8_WAIT_V(8); PG8_WAIT_L(0); PG8_BAR; PG8_MMA(0, 0, At, B0); PG8_MMA(0, 1, At, B1); PG8_BAR; PG8_SCHED;
	s_setprio 1
	s_waitcnt lgkmcnt(0)
	v_mfma_f32_16x16x32_bf16 v[92:95], v[170:173], v[212:215], 0
	v_mfma_f32_16x16x32_bf16 v[88:91], v[182:185], v[212:215], 0
	v_mfma_f32_16x16x32_bf16 v[84:87], v[170:173], v[220:223], 0
	v_mfma_f32_16x16x32_bf16 v[80:83], v[182:185], v[220:223], 0
	v_mfma_f32_16x16x32_bf16 v[76:79], v[170:173], v[228:231], 0
	v_mfma_f32_16x16x32_bf16 v[72:75], v[182:185], v[228:231], 0
	v_mfma_f32_16x16x32_bf16 v[68:71], v[170:173], v[236:239], 0
	v_mfma_f32_16x16x32_bf16 v[64:67], v[182:185], v[236:239], 0
	v_mfma_f32_16x16x32_bf16 v[92:95], v[174:177], v[216:219], v[92:95]
	v_mfma_f32_16x16x32_bf16 v[88:91], v[186:189], v[216:219], v[88:91]
	v_mfma_f32_16x16x32_bf16 v[84:87], v[174:177], v[224:227], v[84:87]
	v_mfma_f32_16x16x32_bf16 v[80:83], v[186:189], v[224:227], v[80:83]
	v_mfma_f32_16x16x32_bf16 v[76:79], v[174:177], v[232:235], v[76:79]
	v_mfma_f32_16x16x32_bf16 v[72:75], v[186:189], v[232:235], v[72:75]
	v_mfma_f32_16x16x32_bf16 v[68:71], v[174:177], v[240:243], v[68:71]
	v_lshl_add_u64 v[244:245], s[62:63], 0, v[128:129]
	s_mov_b32 m0, s85
	s_nop 0
	global_load_lds_dwordx4 v[244:245], off
	v_mfma_f32_16x16x32_bf16 v[64:67], v[186:189], v[240:243], v[64:67]
	s_setprio 0
	s_setprio 1
	v_mfma_f32_16x16x32_bf16 v[28:31], v[190:193], v[212:215], 0
	v_mfma_f32_16x16x32_bf16 v[24:27], v[198:201], v[212:215], 0
	v_mfma_f32_16x16x32_bf16 v[20:23], v[190:193], v[220:223], 0
	v_mfma_f32_16x16x32_bf16 v[16:19], v[198:201], v[220:223], 0
	v_mfma_f32_16x16x32_bf16 v[12:15], v[190:193], v[228:231], 0
	v_mfma_f32_16x16x32_bf16 v[8:11], v[198:201], v[228:231], 0
	v_mfma_f32_16x16x32_bf16 v[4:7], v[190:193], v[236:239], 0
	v_mfma_f32_16x16x32_bf16 v[0:3], v[198:201], v[236:239], 0
	v_mfma_f32_16x16x32_bf16 v[28:31], v[194:197], v[216:219], v[28:31]
	v_mfma_f32_16x16x32_bf16 v[24:27], v[208:211], v[216:219], v[24:27]
	v_mfma_f32_16x16x32_bf16 v[20:23], v[194:197], v[224:227], v[20:23]
	v_mfma_f32_16x16x32_bf16 v[16:19], v[208:211], v[224:227], v[16:19]
	v_mfma_f32_16x16x32_bf16 v[12:15], v[194:197], v[232:235], v[12:15]
	v_mfma_f32_16x16x32_bf16 v[8:11], v[208:211], v[232:235], v[8:11]
	v_mfma_f32_16x16x32_bf16 v[4:7], v[194:197], v[240:243], v[4:7]
	v_lshl_add_u64 v[246:247], s[62:63], 0, v[132:133]
	s_mov_b32 m0, s86
	s_nop 0
	global_load_lds_dwordx4 v[246:247], off
	v_mfma_f32_16x16x32_bf16 v[0:3], v[208:211], v[240:243], v[0:3]
	s_setprio 0
	s_barrier
	s_add_i32 s3, 0, 0x18000
	v_add_u32_e32 v136, s3, v141
	s_add_i32 s33, 0, 0x1c000
	ds_read_b128 v[170:173], v136
	ds_read_b128 v[174:177], v136 offset:1024
	ds_read_b128 v[182:185], v136 offset:2048
	ds_read_b128 v[186:189], v136 offset:3072
	v_add_u32_e32 v136, s33, v141
	ds_read_b128 v[190:193], v136
	ds_read_b128 v[194:197], v136 offset:1024
	ds_read_b128 v[198:201], v136 offset:2048
	ds_read_b128 v[208:211], v136 offset:3072
	s_add_u32 s14, s62, 0x40000
	s_addc_u32 s15, s63, 0
	s_mov_b32 m0, s87
	v_lshl_add_u64 v[248:249], s[14:15], 0, v[128:129]
	ds_read_b128 v[212:215], v164 offset:32768
	ds_read_b128 v[216:219], v164 offset:33792
	ds_read_b128 v[220:223], v164 offset:34816
	ds_read_b128 v[224:227], v164 offset:35840
	ds_read_b128 v[228:231], v164 offset:36864
	ds_read_b128 v[232:235], v164 offset:37888
	ds_read_b128 v[236:239], v164 offset:38912
	ds_read_b128 v[240:243], v164 offset:39936
	global_load_lds_dwordx4 v[248:249], off
	v_lshl_add_u64 v[248:249], s[14:15], 0, v[132:133]
	s_mov_b32 m0, s88
	s_nop 0
	global_load_lds_dwordx4 v[248:249], off
	s_waitcnt vmcnt(8)
	s_waitcnt lgkmcnt(0)
	s_barrier
	s_setprio 1
	s_waitcnt lgkmcnt(0)
	v_mfma_f32_16x16x32_bf16 v[124:127], v[170:173], v[212:215], v[124:127]
	v_mfma_f32_16x16x32_bf16 v[120:123], v[182:185], v[212:215], v[120:123]
	v_mfma_f32_16x16x32_bf16 v[116:119], v[170:173], v[220:223], v[116:119]
	v_mfma_f32_16x16x32_bf16 v[112:115], v[182:185], v[220:223], v[112:115]
	v_mfma_f32_16x16x32_bf16 v[108:111], v[170:173], v[228:231], v[108:111]
	v_mfma_f32_16x16x32_bf16 v[104:107], v[182:185], v[228:231], v[104:107]
	v_mfma_f32_16x16x32_bf16 v[100:103], v[170:173], v[236:239], v[100:103]
	v_mfma_f32_16x16x32_bf16 v[96:99], v[182:185], v[236:239], v[96:99]
	v_mfma_f32_16x16x32_bf16 v[124:127], v[174:177], v[216:219], v[124:127]
	v_mfma_f32_16x16x32_bf16 v[120:123], v[186:189], v[216:219], v[120:123]
	v_mfma_f32_16x16x32_bf16 v[116:119], v[174:177], v[224:227], v[116:119]
	v_mfma_f32_16x16x32_bf16 v[112:115], v[186:189], v[224:227], v[112:115]
	v_mfma_f32_16x16x32_bf16 v[108:111], v[174:177], v[232:235], v[108:111]
	v_mfma_f32_16x16x32_bf16 v[104:107], v[186:189], v[232:235], v[104:107]
	v_mfma_f32_16x16x32_bf16 v[100:103], v[174:177], v[240:243], v[100:103]
	v_mfma_f32_16x16x32_bf16 v[96:99], v[186:189], v[240:243], v[96:99]
	s_setprio 0
	s_setprio 1
	v_mfma_f32_16x16x32_bf16 v[60:63], v[190:193], v[212:215], v[60:63]
	v_mfma_f32_16x16x32_bf16 v[56:59], v[198:201], v[212:215], v[56:59]
	v_mfma_f32_16x16x32_bf16 v[52:55], v[190:193], v[220:223], v[52:55]
	v_mfma_f32_16x16x32_bf16 v[48:51], v[198:201], v[220:223], v[48:51]
	v_mfma_f32_16x16x32_bf16 v[44:47], v[190:193], v[228:231], v[44:47]
	v_mfma_f32_16x16x32_bf16 v[40:43], v[198:201], v[228:231], v[40:43]
	v_mfma_f32_16x16x32_bf16 v[36:39], v[190:193], v[236:239], v[36:39]
	v_mfma_f32_16x16x32_bf16 v[32:35], v[198:201], v[236:239], v[32:35]
	v_mfma_f32_16x16x32_bf16 v[60:63], v[194:197], v[216:219], v[60:63]
	v_mfma_f32_16x16x32_bf16 v[56:59], v[208:211], v[216:219], v[56:59]
	v_mfma_f32_16x16x32_bf16 v[52:55], v[194:197], v[224:227], v[52:55]
	v_mfma_f32_16x16x32_bf16 v[48:51], v[208:211], v[224:227], v[48:51]
	v_mfma_f32_16x16x32_bf16 v[44:47], v[194:197], v[232:235], v[44:47]
	v_mfma_f32_16x16x32_bf16 v[40:43], v[208:211], v[232:235], v[40:43]
	v_mfma_f32_16x16x32_bf16 v[36:39], v[194:197], v[240:243], v[36:39]
	v_mfma_f32_16x16x32_bf16 v[32:35], v[208:211], v[240:243], v[32:35]
	s_setprio 0
	s_barrier
; #define PG8_STAGE(bufoff, gbase, voff) do { _Pragma("unroll") for (int _i = 0; _i < 2; ++_i) \
;         __builtin_amdgcn_global_load_lds((const unsigned*)((const char*)(gbase) + (voff)[_i]), (PG8_LAS unsigned*)(lds + (bufoff) + ldsw + _i * 8192), 16, 0, 0); } while (0)
; #define PG8_LDA(dst, b, h) do { _Pragma("unroll") for (int m = 0; m < 4; ++m) _Pragma("unroll") for (int k = 0; k < 2; ++k) dst[m][k] = *(const PG8_LAS bf16x8*)(lds + PG8_SA(b, h) + aoff + m * 2048 + k * 1024); } while (0)
; #define PG8_LDB(dst, b, h) do { _Pragma("unroll") for (int n = 0; n < 2; ++n) _Pragma("unroll") for (int k = 0; k < 2; ++k) dst[n][k] = *(const PG8_LAS bf16x8*)(lds + PG8_SB(b, h) + boff + n * 2048 + k * 1024); } while (0)
; #define PG8_MMA(ai, bj, At, Bt) do { __builtin_amdgcn_s_setprio(1); _Pragma("unroll") for (int m = 0; m < 4; ++m) _Pragma("unroll") for (int n = 0; n < 2; ++n) _Pragma("unroll") for (int k = 0; k < 2; ++k) \
;         acc[ai][bj][m][n] = __builtin_amdgcn_mfma_f32_16x16x32_bf16(Bt[n][k], At[m][k], acc[ai][bj][m][n], 0, 0, 0); __builtin_amdgcn_s_setprio(0); } while (0)
; #define PG8_WAIT_V(n) asm volatile("s_waitcnt vmcnt(" #n ")" ::: "memory")
; #define PG8_WAIT_L(n) asm volatile("s_waitcnt lgkmcnt(" #n ")" ::: "memory")
; #define PG8_BAR __builtin_amdgcn_s_barrier()
; #define PG8_SCHED __builtin_amdgcn_sched_barrier(0)
; template <class Epi, class Sched, bool ALIGN_EPI = false, bool SP2 = false>
; __device__ __forceinline__ void gemm_phase(PG8_LAS unsigned char* lds, const Gemm g, const Sched& S, const Epi& E) {
;     ...
;         for (int t = 0; t < nt; t += 2) {
;     ...
;             PG8_LDB(B0, 0, 0); PG8_LDB(B1, 0, 1); PG8_SCHED; PG8_LDA(At, 0, 0); PG8_STAGE(PG8_SA(1, 1), a1 + hstep, voffA);
;     ...
;             PG8_LDA(At, 1, 1); PG8_STAGE(PG8_SB(1, 0), b3, voffB); PG8_STAGE(PG8_SB(1, 1), b3 + hstep, voffB); PG8_STAGE(PG8_SA(1, 0), a3, voffA);
;             PG8_WAIT_V(8); PG8_WAIT_L(0); PG8_BAR; PG8_MMA(1, 0, At, B0); PG8_MMA(1, 1, At, B1); PG8_BAR; PG8_SCHED;
	s_add_i32 s3, s3, s84
	v_lshl_add_u64 v[178:179], v[178:179], 0, s[8:9]
	s_mov_b32 m0, s3
	ds_read_b128 v[212:215], v164 offset:49152
	ds_read_b128 v[216:219], v164 offset:50176
	ds_read_b128 v[220:223], v164 offset:51200
	ds_read_b128 v[224:227], v164 offset:52224
	ds_read_b128 v[228:231], v164 offset:53248
	ds_read_b128 v[232:235], v164 offset:54272
	ds_read_b128 v[236:239], v164 offset:55296
	ds_read_b128 v[240:243], v164 offset:56320
	global_load_lds_dwordx4 v[178:179], off
	s_add_i32 m0, s3, 0x2000
	s_add_u32 s14, s60, 0x40080
	v_lshl_add_u64 v[178:179], v[202:203], 0, s[8:9]
	s_addc_u32 s15, s61, 0
	s_add_i32 s3, s33, s84
	global_load_lds_dwordx4 v[178:179], off
	v_lshl_add_u64 v[178:179], s[14:15], 0, v[130:131]
	s_mov_b32 m0, s3
	s_nop 0
	global_load_lds_dwordx4 v[178:179], off
	v_lshl_add_u64 v[178:179], s[14:15], 0, v[134:135]
	s_add_i32 m0, s3, 0x2000
	s_nop 0
	global_load_lds_dwordx4 v[178:179], off
	s_waitcnt vmcnt(6)
	s_waitcnt lgkmcnt(0)
	s_barrier
	s_setprio 1
	s_waitcnt lgkmcnt(0)
	v_mfma_f32_16x16x32_bf16 v[92:95], v[170:173], v[212:215], v[92:95]
	v_mfma_f32_16x16x32_bf16 v[88:91], v[182:185], v[212:215], v[88:91]
	v_mfma_f32_16x16x32_bf16 v[84:87], v[170:173], v[220:223], v[84:87]
	v_mfma_f32_16x16x32_bf16 v[80:83], v[182:185], v[220:223], v[80:83]
	v_mfma_f32_16x16x32_bf16 v[76:79], v[170:173], v[228:231], v[76:79]
	v_mfma_f32_16x16x32_bf16 v[72:75], v[182:185], v[228:231], v[72:75]
	v_mfma_f32_16x16x32_bf16 v[68:71], v[170:173], v[236:239], v[68:71]
	v_mfma_f32_16x16x32_bf16 v[64:67], v[182:185], v[236:239], v[64:67]
	v_mfma_f32_16x16x32_bf16 v[92:95], v[174:177], v[216:219], v[92:95]
	v_mfma_f32_16x16x32_bf16 v[88:91], v[186:189], v[216:219], v[88:91]
	v_mfma_f32_16x16x32_bf16 v[84:87], v[174:177], v[224:227], v[84:87]
	v_mfma_f32_16x16x32_bf16 v[80:83], v[186:189], v[224:227], v[80:83]
	v_mfma_f32_16x16x32_bf16 v[76:79], v[174:177], v[232:235], v[76:79]
	v_mfma_f32_16x16x32_bf16 v[72:75], v[186:189], v[232:235], v[72:75]
	v_mfma_f32_16x16x32_bf16 v[68:71], v[174:177], v[240:243], v[68:71]
	v_lshl_add_u64 v[178:179], v[244:245], 0, s[8:9]
	s_mov_b32 m0, s90
	s_nop 0
	global_load_lds_dwordx4 v[178:179], off
	v_mfma_f32_16x16x32_bf16 v[64:67], v[186:189], v[240:243], v[64:67]
	s_setprio 0
	s_setprio 1
	v_mfma_f32_16x16x32_bf16 v[28:31], v[190:193], v[212:215], v[28:31]
	v_mfma_f32_16x16x32_bf16 v[24:27], v[198:201], v[212:215], v[24:27]
	v_mfma_f32_16x16x32_bf16 v[20:23], v[190:193], v[220:223], v[20:23]
	v_mfma_f32_16x16x32_bf16 v[16:19], v[198:201], v[220:223], v[16:19]
	v_mfma_f32_16x16x32_bf16 v[12:15], v[190:193], v[228:231], v[12:15]
	v_mfma_f32_16x16x32_bf16 v[8:11], v[198:201], v[228:231], v[8:11]
	v_mfma_f32_16x16x32_bf16 v[4:7], v[190:193], v[236:239], v[4:7]
	v_mfma_f32_16x16x32_bf16 v[0:3], v[198:201], v[236:239], v[0:3]
	v_mfma_f32_16x16x32_bf16 v[28:31], v[194:197], v[216:219], v[28:31]
	v_mfma_f32_16x16x32_bf16 v[24:27], v[208:211], v[216:219], v[24:27]
	v_mfma_f32_16x16x32_bf16 v[20:23], v[194:197], v[224:227], v[20:23]
	v_mfma_f32_16x16x32_bf16 v[16:19], v[208:211], v[224:227], v[16:19]
	v_mfma_f32_16x16x32_bf16 v[12:15], v[194:197], v[232:235], v[12:15]
	v_mfma_f32_16x16x32_bf16 v[8:11], v[208:211], v[232:235], v[8:11]
	v_mfma_f32_16x16x32_bf16 v[4:7], v[194:197], v[240:243], v[4:7]
	v_lshl_add_u64 v[178:179], v[246:247], 0, s[8:9]
	s_mov_b32 m0, s91
	s_nop 0
	global_load_lds_dwordx4 v[178:179], off
	v_mfma_f32_16x16x32_bf16 v[0:3], v[208:211], v[240:243], v[0:3]
	s_setprio 0
	s_barrier
	s_add_i32 vcc_lo, vcc_lo, 2
	s_add_u32 s58, s58, 0x100
	s_addc_u32 s59, s59, 0
	s_add_u32 s96, s96, 0x100
	s_addc_u32 s97, s97, 0
.LBB0_459:
	ds_read_b128 v[170:173], v165
	ds_read_b128 v[174:177], v165 offset:1024
	ds_read_b128 v[182:185], v165 offset:2048
	ds_read_b128 v[186:189], v165 offset:3072
	ds_read_b128 v[190:193], v168
	ds_read_b128 v[194:197], v168 offset:1024
	ds_read_b128 v[198:201], v168 offset:2048
	ds_read_b128 v[208:211], v168 offset:3072
	s_add_u32 s3, s58, 0xfffc0080
	s_addc_u32 s14, s59, -1
	s_cmp_eq_u32 vcc_lo, 12
	s_cselect_b32 s63, s49, s14
	s_cselect_b32 s62, s55, s3
	s_cselect_b32 s61, s45, s97
	s_cselect_b32 s60, s57, s96
	v_lshl_add_u64 v[178:179], s[58:59], 0, v[160:161]
	s_add_i32 m0, s85, 0xc000
	ds_read_b128 v[212:215], v164
	ds_read_b128 v[216:219], v164 offset:1024
	ds_read_b128 v[220:223], v164 offset:2048
	ds_read_b128 v[224:227], v164 offset:3072
	ds_read_b128 v[228:231], v164 offset:4096
	ds_read_b128 v[232:235], v164 offset:5120
	ds_read_b128 v[236:239], v164 offset:6144
	ds_read_b128 v[240:243], v164 offset:7168
	global_load_lds_dwordx4 v[178:179], off
	v_lshl_add_u64 v[178:179], s[58:59], 0, v[162:163]
	s_add_i32 m0, s85, 0xe000
	s_nop 0
	global_load_lds_dwordx4 v[178:179], off
	s_waitcnt vmcnt(8)
	s_waitcnt lgkmcnt(0)
	s_barrier
; #define PG8_STAGE(bufoff, gbase, voff) do { _Pragma("unroll") for (int _i = 0; _i < 2; ++_i) \
;         __builtin_amdgcn_global_load_lds((const unsigned*)((const char*)(gbase) + (voff)[_i]), (PG8_LAS unsigned*)(lds + (bufoff) + ldsw + _i * 8192), 16, 0, 0); } while (0)
; #define PG8_LDA(dst, b, h) do { _Pragma("unroll") for (int m = 0; m < 4; ++m) _Pragma("unroll") for (int k = 0; k < 2; ++k) dst[m][k] = *(const PG8_LAS bf16x8*)(lds + PG8_SA(b, h) + aoff + m * 2048 + k * 1024); } while (0)
; #define PG8_MMA(ai, bj, At, Bt) do { __builtin_amdgcn_s_setprio(1); _Pragma("unroll") for (int m = 0; m < 4; ++m) _Pragma("unroll") for (int n = 0; n < 2; ++n) _Pragma("unroll") for (int k = 0; k < 2; ++k) \
;         acc[ai][bj][m][n] = __builtin_amdgcn_mfma_f32_16x16x32_bf16(Bt[n][k], At[m][k], acc[ai][bj][m][n], 0, 0, 0); __builtin_amdgcn_s_setprio(0); } while (0)
; #define PG8_WAIT_V(n) asm volatile("s_waitcnt vmcnt(" #n ")" ::: "memory")
; #define PG8_WAIT_L(n) asm volatile("s_waitcnt lgkmcnt(" #n ")" ::: "memory")
; #define PG8_BAR __builtin_amdgcn_s_barrier()
; #define PG8_SCHED __builtin_amdgcn_sched_barrier(0)
; template <class Epi, class Sched, bool ALIGN_EPI = false, bool SP2 = false>
; __device__ __forceinline__ void gemm_phase(PG8_LAS unsigned char* lds, const Gemm g, const Sched& S, const Epi& E) {
;     ...
;             PG8_WAIT_V(8); PG8_WAIT_L(0); PG8_BAR; PG8_MMA(0, 0, At, B0); PG8_MMA(0, 1, At, B1); PG8_BAR; PG8_SCHED;
;             PG8_LDA(At, 0, 1); PG8_STAGE(PG8_SB(0, 0), b2, voffB); PG8_STAGE(PG8_SB(0, 1), b2 + hstep, voffB); PG8_STAGE(PG8_SA(0, 0), a2, voffA);
;             PG8_WAIT_V(8); PG8_WAIT_L(0); PG8_BAR; PG8_MMA(1, 0, At, B0); PG8_MMA(1, 1, At, B1); PG8_BAR; PG8_SCHED;
	s_setprio 1
	s_waitcnt lgkmcnt(0)
	v_mfma_f32_16x16x32_bf16 v[124:127], v[170:173], v[212:215], v[124:127]
	v_mfma_f32_16x16x32_bf16 v[120:123], v[182:185], v[212:215], v[120:123]
	v_mfma_f32_16x16x32_bf16 v[116:119], v[170:173], v[220:223], v[116:119]
	v_mfma_f32_16x16x32_bf16 v[112:115], v[182:185], v[220:223], v[112:115]
	v_mfma_f32_16x16x32_bf16 v[108:111], v[170:173], v[228:231], v[108:111]
	v_mfma_f32_16x16x32_bf16 v[104:107], v[182:185], v[228:231], v[104:107]
	v_mfma_f32_16x16x32_bf16 v[100:103], v[170:173], v[236:239], v[100:103]
	v_mfma_f32_16x16x32_bf16 v[96:99], v[182:185], v[236:239], v[96:99]
	v_mfma_f32_16x16x32_bf16 v[124:127], v[174:177], v[216:219], v[124:127]
	v_mfma_f32_16x16x32_bf16 v[120:123], v[186:189], v[216:219], v[120:123]
	v_mfma_f32_16x16x32_bf16 v[116:119], v[174:177], v[224:227], v[116:119]
	v_mfma_f32_16x16x32_bf16 v[112:115], v[186:189], v[224:227], v[112:115]
	v_mfma_f32_16x16x32_bf16 v[108:111], v[174:177], v[232:235], v[108:111]
	v_mfma_f32_16x16x32_bf16 v[104:107], v[186:189], v[232:235], v[104:107]
	v_mfma_f32_16x16x32_bf16 v[100:103], v[174:177], v[240:243], v[100:103]
	v_mfma_f32_16x16x32_bf16 v[96:99], v[186:189], v[240:243], v[96:99]
	s_setprio 0
	s_setprio 1
	v_mfma_f32_16x16x32_bf16 v[60:63], v[190:193], v[212:215], v[60:63]
	v_mfma_f32_16x16x32_bf16 v[56:59], v[198:201], v[212:215], v[56:59]
	v_mfma_f32_16x16x32_bf16 v[52:55], v[190:193], v[220:223], v[52:55]
	v_mfma_f32_16x16x32_bf16 v[48:51], v[198:201], v[220:223], v[48:51]
	v_mfma_f32_16x16x32_bf16 v[44:47], v[190:193], v[228:231], v[44:47]
	v_mfma_f32_16x16x32_bf16 v[40:43], v[198:201], v[228:231], v[40:43]
	v_mfma_f32_16x16x32_bf16 v[36:39], v[190:193], v[236:239], v[36:39]
	v_mfma_f32_16x16x32_bf16 v[32:35], v[198:201], v[236:239], v[32:35]
	v_mfma_f32_16x16x32_bf16 v[60:63], v[194:197], v[216:219], v[60:63]
	v_mfma_f32_16x16x32_bf16 v[56:59], v[208:211], v[216:219], v[56:59]
	v_mfma_f32_16x16x32_bf16 v[52:55], v[194:197], v[224:227], v[52:55]
	v_mfma_f32_16x16x32_bf16 v[48:51], v[208:211], v[224:227], v[48:51]
	v_mfma_f32_16x16x32_bf16 v[44:47], v[194:197], v[232:235], v[44:47]
	v_mfma_f32_16x16x32_bf16 v[40:43], v[208:211], v[232:235], v[40:43]
	v_mfma_f32_16x16x32_bf16 v[36:39], v[194:197], v[240:243], v[36:39]
	v_mfma_f32_16x16x32_bf16 v[32:35], v[208:211], v[240:243], v[32:35]
	s_setprio 0
	s_barrier
	s_add_i32 s3, s94, s84
	v_lshl_add_u64 v[178:179], s[60:61], 0, v[130:131]
	s_mov_b32 m0, s3
	ds_read_b128 v[212:215], v164 offset:16384
	ds_read_b128 v[216:219], v164 offset:17408
	ds_read_b128 v[220:223], v164 offset:18432
	ds_read_b128 v[224:227], v164 offset:19456
	ds_read_b128 v[228:231], v164 offset:20480
	ds_read_b128 v[232:235], v164 offset:21504
	ds_read_b128 v[236:239], v164 offset:22528
	ds_read_b128 v[240:243], v164 offset:23552
	global_load_lds_dwordx4 v[178:179], off
	s_add_i32 m0, s3, 0x2000
	s_add_u32 s14, s60, 0x40000
	v_lshl_add_u64 v[202:203], s[60:61], 0, v[134:135]
	s_addc_u32 s15, s61, 0
	s_add_i32 s3, s95, s84
	global_load_lds_dwordx4 v[202:203], off
	v_lshl_add_u64 v[244:245], s[14:15], 0, v[130:131]
	s_mov_b32 m0, s3
	global_load_lds_dwordx4 v[244:245], off
	v_lshl_add_u64 v[244:245], s[14:15], 0, v[134:135]
	s_add_i32 m0, s3, 0x2000
	s_nop 0
	global_load_lds_dwordx4 v[244:245], off
	s_waitcnt vmcnt(6)
	s_waitcnt lgkmcnt(0)
	s_barrier
	s_setprio 1
	s_waitcnt lgkmcnt(0)
	v_mfma_f32_16x16x32_bf16 v[92:95], v[170:173], v[212:215], v[92:95]
	v_mfma_f32_16x16x32_bf16 v[88:91], v[182:185], v[212:215], v[88:91]
	v_mfma_f32_16x16x32_bf16 v[84:87], v[170:173], v[220:223], v[84:87]
	v_mfma_f32_16x16x32_bf16 v[80:83], v[182:185], v[220:223], v[80:83]
	v_mfma_f32_16x16x32_bf16 v[76:79], v[170:173], v[228:231], v[76:79]
	v_mfma_f32_16x16x32_bf16 v[72:75], v[182:185], v[228:231], v[72:75]
	v_mfma_f32_16x16x32_bf16 v[68:71], v[170:173], v[236:239], v[68:71]
	v_mfma_f32_16x16x32_bf16 v[64:67], v[182:185], v[236:239], v[64:67]
	v_mfma_f32_16x16x32_bf16 v[92:95], v[174:177], v[216:219], v[92:95]
	v_mfma_f32_16x16x32_bf16 v[88:91], v[186:189], v[216:219], v[88:91]
	v_mfma_f32_16x16x32_bf16 v[84:87], v[174:177], v[224:227], v[84:87]
	v_mfma_f32_16x16x32_bf16 v[80:83], v[186:189], v[224:227], v[80:83]
	v_mfma_f32_16x16x32_bf16 v[76:79], v[174:177], v[232:235], v[76:79]
	v_mfma_f32_16x16x32_bf16 v[72:75], v[186:189], v[232:235], v[72:75]
	v_mfma_f32_16x16x32_bf16 v[68:71], v[174:177], v[240:243], v[68:71]
	v_lshl_add_u64 v[244:245], s[62:63], 0, v[128:129]
	s_mov_b32 m0, s85
	s_nop 0
	global_load_lds_dwordx4 v[244:245], off
	v_mfma_f32_16x16x32_bf16 v[64:67], v[186:189], v[240:243], v[64:67]
	s_setprio 0
	s_setprio 1
	v_mfma_f32_16x16x32_bf16 v[28:31], v[190:193], v[212:215], v[28:31]
	v_mfma_f32_16x16x32_bf16 v[24:27], v[198:201], v[212:215], v[24:27]
	v_mfma_f32_16x16x32_bf16 v[20:23], v[190:193], v[220:223], v[20:23]
	v_mfma_f32_16x16x32_bf16 v[16:19], v[198:201], v[220:223], v[16:19]
	v_mfma_f32_16x16x32_bf16 v[12:15], v[190:193], v[228:231], v[12:15]
	v_mfma_f32_16x16x32_bf16 v[8:11], v[198:201], v[228:231], v[8:11]
	v_mfma_f32_16x16x32_bf16 v[4:7], v[190:193], v[236:239], v[4:7]
	v_mfma_f32_16x16x32_bf16 v[0:3], v[198:201], v[236:239], v[0:3]
	v_mfma_f32_16x16x32_bf16 v[28:31], v[194:197], v[216:219], v[28:31]
	v_mfma_f32_16x16x32_bf16 v[24:27], v[208:211], v[216:219], v[24:27]
	v_mfma_f32_16x16x32_bf16 v[20:23], v[194:197], v[224:227], v[20:23]
	v_mfma_f32_16x16x32_bf16 v[16:19], v[208:211], v[224:227], v[16:19]
	v_mfma_f32_16x16x32_bf16 v[12:15], v[194:197], v[232:235], v[12:15]
	v_mfma_f32_16x16x32_bf16 v[8:11], v[208:211], v[232:235], v[8:11]
	v_mfma_f32_16x16x32_bf16 v[4:7], v[194:197], v[240:243], v[4:7]
	v_lshl_add_u64 v[246:247], s[62:63], 0, v[132:133]
	s_mov_b32 m0, s86
	s_nop 0
	global_load_lds_dwordx4 v[246:247], off
	v_mfma_f32_16x16x32_bf16 v[0:3], v[208:211], v[240:243], v[0:3]
	s_setprio 0
	s_barrier
; #define PG8_STAGE(bufoff, gbase, voff) do { _Pragma("unroll") for (int _i = 0; _i < 2; ++_i) \
;         __builtin_amdgcn_global_load_lds((const unsigned*)((const char*)(gbase) + (voff)[_i]), (PG8_LAS unsigned*)(lds + (bufoff) + ldsw + _i * 8192), 16, 0, 0); } while (0)
; #define PG8_LDA(dst, b, h) do { _Pragma("unroll") for (int m = 0; m < 4; ++m) _Pragma("unroll") for (int k = 0; k < 2; ++k) dst[m][k] = *(const PG8_LAS bf16x8*)(lds + PG8_SA(b, h) + aoff + m * 2048 + k * 1024); } while (0)
; #define PG8_LDB(dst, b, h) do { _Pragma("unroll") for (int n = 0; n < 2; ++n) _Pragma("unroll") for (int k = 0; k < 2; ++k) dst[n][k] = *(const PG8_LAS bf16x8*)(lds + PG8_SB(b, h) + boff + n * 2048 + k * 1024); } while (0)
; #define PG8_MMA(ai, bj, At, Bt) do { __builtin_amdgcn_s_setprio(1); _Pragma("unroll") for (int m = 0; m < 4; ++m) _Pragma("unroll") for (int n = 0; n < 2; ++n) _Pragma("unroll") for (int k = 0; k < 2; ++k) \
;         acc[ai][bj][m][n] = __builtin_amdgcn_mfma_f32_16x16x32_bf16(Bt[n][k], At[m][k], acc[ai][bj][m][n], 0, 0, 0); __builtin_amdgcn_s_setprio(0); } while (0)
; #define PG8_WAIT_V(n) asm volatile("s_waitcnt vmcnt(" #n ")" ::: "memory")
; #define PG8_WAIT_L(n) asm volatile("s_waitcnt lgkmcnt(" #n ")" ::: "memory")
; #define PG8_BAR __builtin_amdgcn_s_barrier()
; #define PG8_SCHED __builtin_amdgcn_sched_barrier(0)
; template <class Epi, class Sched, bool ALIGN_EPI = false, bool SP2 = false>
; __device__ __forceinline__ void gemm_phase(PG8_LAS unsigned char* lds, const Gemm g, const Sched& S, const Epi& E) {
;     ...
;             PG8_LDB(B0, 1, 0); PG8_LDB(B1, 1, 1); PG8_SCHED; PG8_LDA(At, 1, 0); PG8_STAGE(PG8_SA(0, 1), a2 + hstep, voffA);
;             PG8_WAIT_V(8); PG8_WAIT_L(0); PG8_BAR; PG8_MMA(0, 0, At, B0); PG8_MMA(0, 1, At, B1); PG8_BAR; PG8_SCHED;
	s_add_i32 s3, 0, 0x18000
	v_add_u32_e32 v136, s3, v141
	s_add_i32 s33, 0, 0x1c000
	ds_read_b128 v[170:173], v136
	ds_read_b128 v[174:177], v136 offset:1024
	ds_read_b128 v[182:185], v136 offset:2048
	ds_read_b128 v[186:189], v136 offset:3072
	v_add_u32_e32 v136, s33, v141
	ds_read_b128 v[190:193], v136
	ds_read_b128 v[194:197], v136 offset:1024
	ds_read_b128 v[198:201], v136 offset:2048
	ds_read_b128 v[208:211], v136 offset:3072
	s_add_u32 s14, s62, 0x40000
	s_addc_u32 s15, s63, 0
	s_mov_b32 m0, s87
	v_lshl_add_u64 v[248:249], s[14:15], 0, v[128:129]
	ds_read_b128 v[212:215], v164 offset:32768
	ds_read_b128 v[216:219], v164 offset:33792
	ds_read_b128 v[220:223], v164 offset:34816
	ds_read_b128 v[224:227], v164 offset:35840
	ds_read_b128 v[228:231], v164 offset:36864
	ds_read_b128 v[232:235], v164 offset:37888
	ds_read_b128 v[236:239], v164 offset:38912
	ds_read_b128 v[240:243], v164 offset:39936
	global_load_lds_dwordx4 v[248:249], off
	v_lshl_add_u64 v[248:249], s[14:15], 0, v[132:133]
	s_mov_b32 m0, s88
	s_nop 0
	global_load_lds_dwordx4 v[248:249], off
	s_waitcnt vmcnt(8)
	s_waitcnt lgkmcnt(0)
	s_barrier
	s_setprio 1
	s_waitcnt lgkmcnt(0)
	v_mfma_f32_16x16x32_bf16 v[124:127], v[170:173], v[212:215], v[124:127]
	v_mfma_f32_16x16x32_bf16 v[120:123], v[182:185], v[212:215], v[120:123]
	v_mfma_f32_16x16x32_bf16 v[116:119], v[170:173], v[220:223], v[116:119]
	v_mfma_f32_16x16x32_bf16 v[112:115], v[182:185], v[220:223], v[112:115]
	v_mfma_f32_16x16x32_bf16 v[108:111], v[170:173], v[228:231], v[108:111]
	v_mfma_f32_16x16x32_bf16 v[104:107], v[182:185], v[228:231], v[104:107]
	v_mfma_f32_16x16x32_bf16 v[100:103], v[170:173], v[236:239], v[100:103]
	v_mfma_f32_16x16x32_bf16 v[96:99], v[182:185], v[236:239], v[96:99]
	v_mfma_f32_16x16x32_bf16 v[124:127], v[174:177], v[216:219], v[124:127]
	v_mfma_f32_16x16x32_bf16 v[120:123], v[186:189], v[216:219], v[120:123]
	v_mfma_f32_16x16x32_bf16 v[116:119], v[174:177], v[224:227], v[116:119]
	v_mfma_f32_16x16x32_bf16 v[112:115], v[186:189], v[224:227], v[112:115]
	v_mfma_f32_16x16x32_bf16 v[108:111], v[174:177], v[232:235], v[108:111]
	v_mfma_f32_16x16x32_bf16 v[104:107], v[186:189], v[232:235], v[104:107]
	v_mfma_f32_16x16x32_bf16 v[100:103], v[174:177], v[240:243], v[100:103]
	v_mfma_f32_16x16x32_bf16 v[96:99], v[186:189], v[240:243], v[96:99]
	s_setprio 0
	s_setprio 1
	v_mfma_f32_16x16x32_bf16 v[60:63], v[190:193], v[212:215], v[60:63]
	v_mfma_f32_16x16x32_bf16 v[56:59], v[198:201], v[212:215], v[56:59]
	v_mfma_f32_16x16x32_bf16 v[52:55], v[190:193], v[220:223], v[52:55]
	v_mfma_f32_16x16x32_bf16 v[48:51], v[198:201], v[220:223], v[48:51]
	v_mfma_f32_16x16x32_bf16 v[44:47], v[190:193], v[228:231], v[44:47]
	v_mfma_f32_16x16x32_bf16 v[40:43], v[198:201], v[228:231], v[40:43]
	v_mfma_f32_16x16x32_bf16 v[36:39], v[190:193], v[236:239], v[36:39]
	v_mfma_f32_16x16x32_bf16 v[32:35], v[198:201], v[236:239], v[32:35]
	v_mfma_f32_16x16x32_bf16 v[60:63], v[194:197], v[216:219], v[60:63]
	v_mfma_f32_16x16x32_bf16 v[56:59], v[208:211], v[216:219], v[56:59]
	v_mfma_f32_16x16x32_bf16 v[52:55], v[194:197], v[224:227], v[52:55]
	v_mfma_f32_16x16x32_bf16 v[48:51], v[208:211], v[224:227], v[48:51]
	v_mfma_f32_16x16x32_bf16 v[44:47], v[194:197], v[232:235], v[44:47]
	v_mfma_f32_16x16x32_bf16 v[40:43], v[208:211], v[232:235], v[40:43]
	v_mfma_f32_16x16x32_bf16 v[36:39], v[194:197], v[240:243], v[36:39]
	v_mfma_f32_16x16x32_bf16 v[32:35], v[208:211], v[240:243], v[32:35]
	s_setprio 0
	s_barrier
; #define PG8_STAGE(bufoff, gbase, voff) do { _Pragma("unroll") for (int _i = 0; _i < 2; ++_i) \
;         __builtin_amdgcn_global_load_lds((const unsigned*)((const char*)(gbase) + (voff)[_i]), (PG8_LAS unsigned*)(lds + (bufoff) + ldsw + _i * 8192), 16, 0, 0); } while (0)
; #define PG8_LDA(dst, b, h) do { _Pragma("unroll") for (int m = 0; m < 4; ++m) _Pragma("unroll") for (int k = 0; k < 2; ++k) dst[m][k] = *(const PG8_LAS bf16x8*)(lds + PG8_SA(b, h) + aoff + m * 2048 + k * 1024); } while (0)
; #define PG8_MMA(ai, bj, At, Bt) do { __builtin_amdgcn_s_setprio(1); _Pragma("unroll") for (int m = 0; m < 4; ++m) _Pragma("unroll") for (int n = 0; n < 2; ++n) _Pragma("unroll") for (int k = 0; k < 2; ++k) \
;         acc[ai][bj][m][n] = __builtin_amdgcn_mfma_f32_16x16x32_bf16(Bt[n][k], At[m][k], acc[ai][bj][m][n], 0, 0, 0); __builtin_amdgcn_s_setprio(0); } while (0)
; #define PG8_WAIT_V(n) asm volatile("s_waitcnt vmcnt(" #n ")" ::: "memory")
; #define PG8_WAIT_L(n) asm volatile("s_waitcnt lgkmcnt(" #n ")" ::: "memory")
; #define PG8_BAR __builtin_amdgcn_s_barrier()
; #define PG8_SCHED __builtin_amdgcn_sched_barrier(0)
; template <class Epi, class Sched, bool ALIGN_EPI = false, bool SP2 = false>
; __device__ __forceinline__ void gemm_phase(PG8_LAS unsigned char* lds, const Gemm g, const Sched& S, const Epi& E) {
;     ...
;             PG8_LDA(At, 1, 1); PG8_STAGE(PG8_SB(1, 0), b3, voffB); PG8_STAGE(PG8_SB(1, 1), b3 + hstep, voffB); PG8_STAGE(PG8_SA(1, 0), a3, voffA);
;             PG8_WAIT_V(8); PG8_WAIT_L(0); PG8_BAR; PG8_MMA(1, 0, At, B0); PG8_MMA(1, 1, At, B1); PG8_BAR; PG8_SCHED;
;     ...
;         if constexpr (ALIGN_EPI) { if (wr == 0) PG8_BAR; }
	s_add_i32 s3, s3, s84
	v_lshl_add_u64 v[178:179], v[178:179], 0, s[8:9]
	s_mov_b32 m0, s3
	ds_read_b128 v[212:215], v164 offset:49152
	ds_read_b128 v[216:219], v164 offset:50176
	ds_read_b128 v[220:223], v164 offset:51200
	ds_read_b128 v[224:227], v164 offset:52224
	ds_read_b128 v[228:231], v164 offset:53248
	ds_read_b128 v[232:235], v164 offset:54272
	ds_read_b128 v[236:239], v164 offset:55296
	ds_read_b128 v[240:243], v164 offset:56320
	global_load_lds_dwordx4 v[178:179], off
	s_add_i32 m0, s3, 0x2000
	s_add_u32 s14, s60, 0x40080
	v_lshl_add_u64 v[178:179], v[202:203], 0, s[8:9]
	s_addc_u32 s15, s61, 0
	s_add_i32 s3, s33, s84
	global_load_lds_dwordx4 v[178:179], off
	v_lshl_add_u64 v[178:179], s[14:15], 0, v[130:131]
	s_mov_b32 m0, s3
	s_nop 0
	global_load_lds_dwordx4 v[178:179], off
	v_lshl_add_u64 v[178:179], s[14:15], 0, v[134:135]
	s_add_i32 m0, s3, 0x2000
	s_nop 0
	global_load_lds_dwordx4 v[178:179], off
	s_waitcnt vmcnt(6)
	s_waitcnt lgkmcnt(0)
	s_barrier
	s_setprio 1
	s_waitcnt lgkmcnt(0)
	v_mfma_f32_16x16x32_bf16 v[92:95], v[170:173], v[212:215], v[92:95]
	v_mfma_f32_16x16x32_bf16 v[88:91], v[182:185], v[212:215], v[88:91]
	v_mfma_f32_16x16x32_bf16 v[84:87], v[170:173], v[220:223], v[84:87]
	v_mfma_f32_16x16x32_bf16 v[80:83], v[182:185], v[220:223], v[80:83]
	v_mfma_f32_16x16x32_bf16 v[76:79], v[170:173], v[228:231], v[76:79]
	v_mfma_f32_16x16x32_bf16 v[72:75], v[182:185], v[228:231], v[72:75]
	v_mfma_f32_16x16x32_bf16 v[68:71], v[170:173], v[236:239], v[68:71]
	v_mfma_f32_16x16x32_bf16 v[64:67], v[182:185], v[236:239], v[64:67]
	v_mfma_f32_16x16x32_bf16 v[92:95], v[174:177], v[216:219], v[92:95]
	v_mfma_f32_16x16x32_bf16 v[88:91], v[186:189], v[216:219], v[88:91]
	v_mfma_f32_16x16x32_bf16 v[84:87], v[174:177], v[224:227], v[84:87]
	v_mfma_f32_16x16x32_bf16 v[80:83], v[186:189], v[224:227], v[80:83]
	v_mfma_f32_16x16x32_bf16 v[76:79], v[174:177], v[232:235], v[76:79]
	v_mfma_f32_16x16x32_bf16 v[72:75], v[186:189], v[232:235], v[72:75]
	v_mfma_f32_16x16x32_bf16 v[68:71], v[174:177], v[240:243], v[68:71]
	v_lshl_add_u64 v[178:179], v[244:245], 0, s[8:9]
	s_mov_b32 m0, s90
	s_nop 0
	global_load_lds_dwordx4 v[178:179], off
	v_mfma_f32_16x16x32_bf16 v[64:67], v[186:189], v[240:243], v[64:67]
	s_setprio 0
	s_setprio 1
	v_mfma_f32_16x16x32_bf16 v[28:31], v[190:193], v[212:215], v[28:31]
	v_mfma_f32_16x16x32_bf16 v[24:27], v[198:201], v[212:215], v[24:27]
	v_mfma_f32_16x16x32_bf16 v[20:23], v[190:193], v[220:223], v[20:23]
	v_mfma_f32_16x16x32_bf16 v[16:19], v[198:201], v[220:223], v[16:19]
	v_mfma_f32_16x16x32_bf16 v[12:15], v[190:193], v[228:231], v[12:15]
	v_mfma_f32_16x16x32_bf16 v[8:11], v[198:201], v[228:231], v[8:11]
	v_mfma_f32_16x16x32_bf16 v[4:7], v[190:193], v[236:239], v[4:7]
	v_mfma_f32_16x16x32_bf16 v[0:3], v[198:201], v[236:239], v[0:3]
	v_mfma_f32_16x16x32_bf16 v[28:31], v[194:197], v[216:219], v[28:31]
	v_mfma_f32_16x16x32_bf16 v[24:27], v[208:211], v[216:219], v[24:27]
	v_mfma_f32_16x16x32_bf16 v[20:23], v[194:197], v[224:227], v[20:23]
	v_mfma_f32_16x16x32_bf16 v[16:19], v[208:211], v[224:227], v[16:19]
	v_mfma_f32_16x16x32_bf16 v[12:15], v[194:197], v[232:235], v[12:15]
	v_mfma_f32_16x16x32_bf16 v[8:11], v[208:211], v[232:235], v[8:11]
	v_mfma_f32_16x16x32_bf16 v[4:7], v[194:197], v[240:243], v[4:7]
	v_lshl_add_u64 v[178:179], v[246:247], 0, s[8:9]
	s_mov_b32 m0, s91
	s_nop 0
	global_load_lds_dwordx4 v[178:179], off
	v_mfma_f32_16x16x32_bf16 v[0:3], v[208:211], v[240:243], v[0:3]
	s_setprio 0
	s_barrier
	s_add_i32 vcc_lo, vcc_lo, 2
	s_add_u32 s58, s58, 0x100
	s_addc_u32 s59, s59, 0
	s_add_u32 s96, s96, 0x100
	s_addc_u32 s97, s97, 0
	s_cmp_gt_u32 vcc_lo, 13
	s_cbranch_scc0 .LBB0_459
	s_and_b64 vcc, exec, s[10:11]
	s_cbranch_vccz .LBB0_462
	s_barrier

; #define PG8_STAGE(bufoff, gbase, voff) do { _Pragma("unroll") for (int _i = 0; _i < 2; ++_i) \
;         __builtin_amdgcn_global_load_lds((const unsigned*)((const char*)(gbase) + (voff)[_i]), (PG8_LAS unsigned*)(lds + (bufoff) + ldsw + _i * 8192), 16, 0, 0); } while (0)
; #define PG8_LDA(dst, b, h) do { _Pragma("unroll") for (int m = 0; m < 4; ++m) _Pragma("unroll") for (int k = 0; k < 2; ++k) dst[m][k] = *(const PG8_LAS bf16x8*)(lds + PG8_SA(b, h) + aoff + m * 2048 + k * 1024); } while (0)
; #define PG8_LDB(dst, b, h) do { _Pragma("unroll") for (int n = 0; n < 2; ++n) _Pragma("unroll") for (int k = 0; k < 2; ++k) dst[n][k] = *(const PG8_LAS bf16x8*)(lds + PG8_SB(b, h) + boff + n * 2048 + k * 1024); } while (0)
; #define PG8_MMA(ai, bj, At, Bt) do { __builtin_amdgcn_s_setprio(1); _Pragma("unroll") for (int m = 0; m < 4; ++m) _Pragma("unroll") for (int n = 0; n < 2; ++n) _Pragma("unroll") for (int k = 0; k < 2; ++k) \
;         acc[ai][bj][m][n] = __builtin_amdgcn_mfma_f32_16x16x32_bf16(Bt[n][k], At[m][k], acc[ai][bj][m][n], 0, 0, 0); __builtin_amdgcn_s_setprio(0); } while (0)
; #define PG8_WAIT_V(n) asm volatile("s_waitcnt vmcnt(" #n ")" ::: "memory")
; #define PG8_WAIT_L(n) asm volatile("s_waitcnt lgkmcnt(" #n ")" ::: "memory")
; #define PG8_BAR __builtin_amdgcn_s_barrier()
; #define PG8_SCHED __builtin_amdgcn_sched_barrier(0)
; template <class Epi, class Sched, bool ALIGN_EPI = false, bool SP2 = false>
; __device__ __forceinline__ void gemm_phase(PG8_LAS unsigned char* lds, const Gemm g, const Sched& S, const Epi& E) {
;     ...
;             PG8_LDB(B0, 0, 0); PG8_LDB(B1, 0, 1); PG8_SCHED; PG8_LDA(At, 0, 0); PG8_STAGE(PG8_SA(1, 1), a1 + hstep, voffA);
;             PG8_WAIT_V(8); PG8_WAIT_L(0); PG8_BAR; PG8_MMA(0, 0, At, B0); PG8_MMA(0, 1, At, B1); PG8_BAR; PG8_SCHED;
;             PG8_LDA(At, 0, 1); PG8_STAGE(PG8_SB(0, 0), b2, voffB); PG8_STAGE(PG8_SB(0, 1), b2 + hstep, voffB); PG8_STAGE(PG8_SA(0, 0), a2, voffA);
;             PG8_WAIT_V(8); PG8_WAIT_L(0); PG8_BAR; PG8_MMA(1, 0, At, B0); PG8_MMA(1, 1, At, B1); PG8_BAR; PG8_SCHED;
.LBB0_495:
	ds_read_b128 v[170:173], v165
	ds_read_b128 v[174:177], v165 offset:1024
	ds_read_b128 v[182:185], v165 offset:2048
	ds_read_b128 v[186:189], v165 offset:3072
	ds_read_b128 v[190:193], v168
	ds_read_b128 v[194:197], v168 offset:1024
	ds_read_b128 v[198:201], v168 offset:2048
	ds_read_b128 v[208:211], v168 offset:3072
	s_add_u32 s3, s60, 0xfffc0080
	s_addc_u32 s14, s61, -1
	s_cmp_eq_u32 s97, 12
	s_cselect_b32 s65, s49, s14
	s_cselect_b32 s64, s57, s3
	s_cselect_b32 s63, s45, s96
	s_cselect_b32 s62, s94, s95
	v_lshl_add_u64 v[178:179], s[60:61], 0, v[160:161]
	s_add_i32 m0, s59, 0xc000
	ds_read_b128 v[212:215], v164
	ds_read_b128 v[216:219], v164 offset:1024
	ds_read_b128 v[220:223], v164 offset:2048
	ds_read_b128 v[224:227], v164 offset:3072
	ds_read_b128 v[228:231], v164 offset:4096
	ds_read_b128 v[232:235], v164 offset:5120
	ds_read_b128 v[236:239], v164 offset:6144
	ds_read_b128 v[240:243], v164 offset:7168
	global_load_lds_dwordx4 v[178:179], off
	v_lshl_add_u64 v[178:179], s[60:61], 0, v[162:163]
	s_add_i32 m0, s59, 0xe000
	s_nop 0
	global_load_lds_dwordx4 v[178:179], off
	s_waitcnt vmcnt(8)
	s_waitcnt lgkmcnt(0)
	s_barrier
	s_setprio 1
	s_waitcnt lgkmcnt(0)
	v_mfma_f32_16x16x32_bf16 v[124:127], v[170:173], v[212:215], v[124:127]
	v_mfma_f32_16x16x32_bf16 v[120:123], v[182:185], v[212:215], v[120:123]
	v_mfma_f32_16x16x32_bf16 v[116:119], v[170:173], v[220:223], v[116:119]
	v_mfma_f32_16x16x32_bf16 v[112:115], v[182:185], v[220:223], v[112:115]
	v_mfma_f32_16x16x32_bf16 v[108:111], v[170:173], v[228:231], v[108:111]
	v_mfma_f32_16x16x32_bf16 v[104:107], v[182:185], v[228:231], v[104:107]
	v_mfma_f32_16x16x32_bf16 v[100:103], v[170:173], v[236:239], v[100:103]
	v_mfma_f32_16x16x32_bf16 v[96:99], v[182:185], v[236:239], v[96:99]
	v_mfma_f32_16x16x32_bf16 v[124:127], v[174:177], v[216:219], v[124:127]
	v_mfma_f32_16x16x32_bf16 v[120:123], v[186:189], v[216:219], v[120:123]
	v_mfma_f32_16x16x32_bf16 v[116:119], v[174:177], v[224:227], v[116:119]
	v_mfma_f32_16x16x32_bf16 v[112:115], v[186:189], v[224:227], v[112:115]
	v_mfma_f32_16x16x32_bf16 v[108:111], v[174:177], v[232:235], v[108:111]
	v_mfma_f32_16x16x32_bf16 v[104:107], v[186:189], v[232:235], v[104:107]
	v_mfma_f32_16x16x32_bf16 v[100:103], v[174:177], v[240:243], v[100:103]
	v_mfma_f32_16x16x32_bf16 v[96:99], v[186:189], v[240:243], v[96:99]
	s_setprio 0
	s_setprio 1
	v_mfma_f32_16x16x32_bf16 v[60:63], v[190:193], v[212:215], v[60:63]
	v_mfma_f32_16x16x32_bf16 v[56:59], v[198:201], v[212:215], v[56:59]
	v_mfma_f32_16x16x32_bf16 v[52:55], v[190:193], v[220:223], v[52:55]
	v_mfma_f32_16x16x32_bf16 v[48:51], v[198:201], v[220:223], v[48:51]
	v_mfma_f32_16x16x32_bf16 v[44:47], v[190:193], v[228:231], v[44:47]
	v_mfma_f32_16x16x32_bf16 v[40:43], v[198:201], v[228:231], v[40:43]
	v_mfma_f32_16x16x32_bf16 v[36:39], v[190:193], v[236:239], v[36:39]
	v_mfma_f32_16x16x32_bf16 v[32:35], v[198:201], v[236:239], v[32:35]
	v_mfma_f32_16x16x32_bf16 v[60:63], v[194:197], v[216:219], v[60:63]
	v_mfma_f32_16x16x32_bf16 v[56:59], v[208:211], v[216:219], v[56:59]
	v_mfma_f32_16x16x32_bf16 v[52:55], v[194:197], v[224:227], v[52:55]
	v_mfma_f32_16x16x32_bf16 v[48:51], v[208:211], v[224:227], v[48:51]
	v_mfma_f32_16x16x32_bf16 v[44:47], v[194:197], v[232:235], v[44:47]
	v_mfma_f32_16x16x32_bf16 v[40:43], v[208:211], v[232:235], v[40:43]
	v_mfma_f32_16x16x32_bf16 v[36:39], v[194:197], v[240:243], v[36:39]
	v_mfma_f32_16x16x32_bf16 v[32:35], v[208:211], v[240:243], v[32:35]
	s_setprio 0
	s_barrier
	s_add_i32 s3, s92, s75
	v_lshl_add_u64 v[178:179], s[62:63], 0, v[130:131]
	s_mov_b32 m0, s3
	ds_read_b128 v[212:215], v164 offset:16384
	ds_read_b128 v[216:219], v164 offset:17408
	ds_read_b128 v[220:223], v164 offset:18432
	ds_read_b128 v[224:227], v164 offset:19456
	ds_read_b128 v[228:231], v164 offset:20480
	ds_read_b128 v[232:235], v164 offset:21504
	ds_read_b128 v[236:239], v164 offset:22528
	ds_read_b128 v[240:243], v164 offset:23552
	global_load_lds_dwordx4 v[178:179], off
	s_add_i32 m0, s3, 0x2000
	s_add_u32 s14, s62, 0x40000
	v_lshl_add_u64 v[202:203], s[62:63], 0, v[134:135]
	s_addc_u32 s15, s63, 0
	s_add_i32 s3, s93, s75
	global_load_lds_dwordx4 v[202:203], off
	v_lshl_add_u64 v[244:245], s[14:15], 0, v[130:131]
	s_mov_b32 m0, s3
	global_load_lds_dwordx4 v[244:245], off
	v_lshl_add_u64 v[244:245], s[14:15], 0, v[134:135]
	s_add_i32 m0, s3, 0x2000
	s_nop 0
	global_load_lds_dwordx4 v[244:245], off
	s_waitcnt vmcnt(6)
	s_waitcnt lgkmcnt(0)
	s_barrier
; #define PG8_STAGE(bufoff, gbase, voff) do { _Pragma("unroll") for (int _i = 0; _i < 2; ++_i) \
;         __builtin_amdgcn_global_load_lds((const unsigned*)((const char*)(gbase) + (voff)[_i]), (PG8_LAS unsigned*)(lds + (bufoff) + ldsw + _i * 8192), 16, 0, 0); } while (0)
; #define PG8_LDA(dst, b, h) do { _Pragma("unroll") for (int m = 0; m < 4; ++m) _Pragma("unroll") for (int k = 0; k < 2; ++k) dst[m][k] = *(const PG8_LAS bf16x8*)(lds + PG8_SA(b, h) + aoff + m * 2048 + k * 1024); } while (0)
; #define PG8_LDB(dst, b, h) do { _Pragma("unroll") for (int n = 0; n < 2; ++n) _Pragma("unroll") for (int k = 0; k < 2; ++k) dst[n][k] = *(const PG8_LAS bf16x8*)(lds + PG8_SB(b, h) + boff + n * 2048 + k * 1024); } while (0)
; #define PG8_MMA(ai, bj, At, Bt) do { __builtin_amdgcn_s_setprio(1); _Pragma("unroll") for (int m = 0; m < 4; ++m) _Pragma("unroll") for (int n = 0; n < 2; ++n) _Pragma("unroll") for (int k = 0; k < 2; ++k) \
;         acc[ai][bj][m][n] = __builtin_amdgcn_mfma_f32_16x16x32_bf16(Bt[n][k], At[m][k], acc[ai][bj][m][n], 0, 0, 0); __builtin_amdgcn_s_setprio(0); } while (0)
; #define PG8_WAIT_V(n) asm volatile("s_waitcnt vmcnt(" #n ")" ::: "memory")
; #define PG8_WAIT_L(n) asm volatile("s_waitcnt lgkmcnt(" #n ")" ::: "memory")
; #define PG8_BAR __builtin_amdgcn_s_barrier()
; #define PG8_SCHED __builtin_amdgcn_sched_barrier(0)
; template <class Epi, class Sched, bool ALIGN_EPI = false, bool SP2 = false>
; __device__ __forceinline__ void gemm_phase(PG8_LAS unsigned char* lds, const Gemm g, const Sched& S, const Epi& E) {
;     ...
;             PG8_WAIT_V(8); PG8_WAIT_L(0); PG8_BAR; PG8_MMA(1, 0, At, B0); PG8_MMA(1, 1, At, B1); PG8_BAR; PG8_SCHED;
;             PG8_LDB(B0, 1, 0); PG8_LDB(B1, 1, 1); PG8_SCHED; PG8_LDA(At, 1, 0); PG8_STAGE(PG8_SA(0, 1), a2 + hstep, voffA);
;             PG8_WAIT_V(8); PG8_WAIT_L(0); PG8_BAR; PG8_MMA(0, 0, At, B0); PG8_MMA(0, 1, At, B1); PG8_BAR; PG8_SCHED;
	s_setprio 1
	s_waitcnt lgkmcnt(0)
	v_mfma_f32_16x16x32_bf16 v[92:95], v[170:173], v[212:215], v[92:95]
	v_mfma_f32_16x16x32_bf16 v[88:91], v[182:185], v[212:215], v[88:91]
	v_mfma_f32_16x16x32_bf16 v[84:87], v[170:173], v[220:223], v[84:87]
	v_mfma_f32_16x16x32_bf16 v[80:83], v[182:185], v[220:223], v[80:83]
	v_mfma_f32_16x16x32_bf16 v[76:79], v[170:173], v[228:231], v[76:79]
	v_mfma_f32_16x16x32_bf16 v[72:75], v[182:185], v[228:231], v[72:75]
	v_mfma_f32_16x16x32_bf16 v[68:71], v[170:173], v[236:239], v[68:71]
	v_mfma_f32_16x16x32_bf16 v[64:67], v[182:185], v[236:239], v[64:67]
	v_mfma_f32_16x16x32_bf16 v[92:95], v[174:177], v[216:219], v[92:95]
	v_mfma_f32_16x16x32_bf16 v[88:91], v[186:189], v[216:219], v[88:91]
	v_mfma_f32_16x16x32_bf16 v[84:87], v[174:177], v[224:227], v[84:87]
	v_mfma_f32_16x16x32_bf16 v[80:83], v[186:189], v[224:227], v[80:83]
	v_mfma_f32_16x16x32_bf16 v[76:79], v[174:177], v[232:235], v[76:79]
	v_mfma_f32_16x16x32_bf16 v[72:75], v[186:189], v[232:235], v[72:75]
	v_mfma_f32_16x16x32_bf16 v[68:71], v[174:177], v[240:243], v[68:71]
	v_lshl_add_u64 v[244:245], s[64:65], 0, v[128:129]
	s_mov_b32 m0, s59
	s_nop 0
	global_load_lds_dwordx4 v[244:245], off
	v_mfma_f32_16x16x32_bf16 v[64:67], v[186:189], v[240:243], v[64:67]
	s_setprio 0
	s_setprio 1
	v_mfma_f32_16x16x32_bf16 v[28:31], v[190:193], v[212:215], v[28:31]
	v_mfma_f32_16x16x32_bf16 v[24:27], v[198:201], v[212:215], v[24:27]
	v_mfma_f32_16x16x32_bf16 v[20:23], v[190:193], v[220:223], v[20:23]
	v_mfma_f32_16x16x32_bf16 v[16:19], v[198:201], v[220:223], v[16:19]
	v_mfma_f32_16x16x32_bf16 v[12:15], v[190:193], v[228:231], v[12:15]
	v_mfma_f32_16x16x32_bf16 v[8:11], v[198:201], v[228:231], v[8:11]
	v_mfma_f32_16x16x32_bf16 v[4:7], v[190:193], v[236:239], v[4:7]
	v_mfma_f32_16x16x32_bf16 v[0:3], v[198:201], v[236:239], v[0:3]
	v_mfma_f32_16x16x32_bf16 v[28:31], v[194:197], v[216:219], v[28:31]
	v_mfma_f32_16x16x32_bf16 v[24:27], v[208:211], v[216:219], v[24:27]
	v_mfma_f32_16x16x32_bf16 v[20:23], v[194:197], v[224:227], v[20:23]
	v_mfma_f32_16x16x32_bf16 v[16:19], v[208:211], v[224:227], v[16:19]
	v_mfma_f32_16x16x32_bf16 v[12:15], v[194:197], v[232:235], v[12:15]
	v_mfma_f32_16x16x32_bf16 v[8:11], v[208:211], v[232:235], v[8:11]
	v_mfma_f32_16x16x32_bf16 v[4:7], v[194:197], v[240:243], v[4:7]
	v_lshl_add_u64 v[246:247], s[64:65], 0, v[132:133]
	s_mov_b32 m0, s84
	s_nop 0
	global_load_lds_dwordx4 v[246:247], off
	v_mfma_f32_16x16x32_bf16 v[0:3], v[208:211], v[240:243], v[0:3]
	s_setprio 0
	s_barrier
	s_add_i32 s3, 0, 0x18000
	v_add_u32_e32 v136, s3, v141
	s_add_i32 s33, 0, 0x1c000
	ds_read_b128 v[170:173], v136
	ds_read_b128 v[174:177], v136 offset:1024
	ds_read_b128 v[182:185], v136 offset:2048
	ds_read_b128 v[186:189], v136 offset:3072
	v_add_u32_e32 v136, s33, v141
	ds_read_b128 v[190:193], v136
	ds_read_b128 v[194:197], v136 offset:1024
	ds_read_b128 v[198:201], v136 offset:2048
	ds_read_b128 v[208:211], v136 offset:3072
	s_add_u32 s14, s64, 0x40000
	s_addc_u32 s15, s65, 0
	s_mov_b32 m0, s85
	v_lshl_add_u64 v[248:249], s[14:15], 0, v[128:129]
	ds_read_b128 v[212:215], v164 offset:32768
	ds_read_b128 v[216:219], v164 offset:33792
	ds_read_b128 v[220:223], v164 offset:34816
	ds_read_b128 v[224:227], v164 offset:35840
	ds_read_b128 v[228:231], v164 offset:36864
	ds_read_b128 v[232:235], v164 offset:37888
	ds_read_b128 v[236:239], v164 offset:38912
	ds_read_b128 v[240:243], v164 offset:39936
	global_load_lds_dwordx4 v[248:249], off
	v_lshl_add_u64 v[248:249], s[14:15], 0, v[132:133]
	s_mov_b32 m0, s86
	s_nop 0
	global_load_lds_dwordx4 v[248:249], off
	s_waitcnt vmcnt(8)
	s_waitcnt lgkmcnt(0)
	s_barrier
	s_setprio 1
	s_waitcnt lgkmcnt(0)
	v_mfma_f32_16x16x32_bf16 v[124:127], v[170:173], v[212:215], v[124:127]
	v_mfma_f32_16x16x32_bf16 v[120:123], v[182:185], v[212:215], v[120:123]
	v_mfma_f32_16x16x32_bf16 v[116:119], v[170:173], v[220:223], v[116:119]
	v_mfma_f32_16x16x32_bf16 v[112:115], v[182:185], v[220:223], v[112:115]
	v_mfma_f32_16x16x32_bf16 v[108:111], v[170:173], v[228:231], v[108:111]
	v_mfma_f32_16x16x32_bf16 v[104:107], v[182:185], v[228:231], v[104:107]
	v_mfma_f32_16x16x32_bf16 v[100:103], v[170:173], v[236:239], v[100:103]
	v_mfma_f32_16x16x32_bf16 v[96:99], v[182:185], v[236:239], v[96:99]
	v_mfma_f32_16x16x32_bf16 v[124:127], v[174:177], v[216:219], v[124:127]
	v_mfma_f32_16x16x32_bf16 v[120:123], v[186:189], v[216:219], v[120:123]
	v_mfma_f32_16x16x32_bf16 v[116:119], v[174:177], v[224:227], v[116:119]
	v_mfma_f32_16x16x32_bf16 v[112:115], v[186:189], v[224:227], v[112:115]
	v_mfma_f32_16x16x32_bf16 v[108:111], v[174:177], v[232:235], v[108:111]
	v_mfma_f32_16x16x32_bf16 v[104:107], v[186:189], v[232:235], v[104:107]
	v_mfma_f32_16x16x32_bf16 v[100:103], v[174:177], v[240:243], v[100:103]
	v_mfma_f32_16x16x32_bf16 v[96:99], v[186:189], v[240:243], v[96:99]
	s_setprio 0
	s_setprio 1
	v_mfma_f32_16x16x32_bf16 v[60:63], v[190:193], v[212:215], v[60:63]
	v_mfma_f32_16x16x32_bf16 v[56:59], v[198:201], v[212:215], v[56:59]
	v_mfma_f32_16x16x32_bf16 v[52:55], v[190:193], v[220:223], v[52:55]
	v_mfma_f32_16x16x32_bf16 v[48:51], v[198:201], v[220:223], v[48:51]
	v_mfma_f32_16x16x32_bf16 v[44:47], v[190:193], v[228:231], v[44:47]
	v_mfma_f32_16x16x32_bf16 v[40:43], v[198:201], v[228:231], v[40:43]
	v_mfma_f32_16x16x32_bf16 v[36:39], v[190:193], v[236:239], v[36:39]
	v_mfma_f32_16x16x32_bf16 v[32:35], v[198:201], v[236:239], v[32:35]
	v_mfma_f32_16x16x32_bf16 v[60:63], v[194:197], v[216:219], v[60:63]
	v_mfma_f32_16x16x32_bf16 v[56:59], v[208:211], v[216:219], v[56:59]
	v_mfma_f32_16x16x32_bf16 v[52:55], v[194:197], v[224:227], v[52:55]
	v_mfma_f32_16x16x32_bf16 v[48:51], v[208:211], v[224:227], v[48:51]
	v_mfma_f32_16x16x32_bf16 v[44:47], v[194:197], v[232:235], v[44:47]
	v_mfma_f32_16x16x32_bf16 v[40:43], v[208:211], v[232:235], v[40:43]
	v_mfma_f32_16x16x32_bf16 v[36:39], v[194:197], v[240:243], v[36:39]
	v_mfma_f32_16x16x32_bf16 v[32:35], v[208:211], v[240:243], v[32:35]
	s_setprio 0
	s_barrier
; #define PG8_STAGE(bufoff, gbase, voff) do { _Pragma("unroll") for (int _i = 0; _i < 2; ++_i) \
;         __builtin_amdgcn_global_load_lds((const unsigned*)((const char*)(gbase) + (voff)[_i]), (PG8_LAS unsigned*)(lds + (bufoff) + ldsw + _i * 8192), 16, 0, 0); } while (0)
; #define PG8_LDA(dst, b, h) do { _Pragma("unroll") for (int m = 0; m < 4; ++m) _Pragma("unroll") for (int k = 0; k < 2; ++k) dst[m][k] = *(const PG8_LAS bf16x8*)(lds + PG8_SA(b, h) + aoff + m * 2048 + k * 1024); } while (0)
; #define PG8_MMA(ai, bj, At, Bt) do { __builtin_amdgcn_s_setprio(1); _Pragma("unroll") for (int m = 0; m < 4; ++m) _Pragma("unroll") for (int n = 0; n < 2; ++n) _Pragma("unroll") for (int k = 0; k < 2; ++k) \
;         acc[ai][bj][m][n] = __builtin_amdgcn_mfma_f32_16x16x32_bf16(Bt[n][k], At[m][k], acc[ai][bj][m][n], 0, 0, 0); __builtin_amdgcn_s_setprio(0); } while (0)
; #define PG8_WAIT_V(n) asm volatile("s_waitcnt vmcnt(" #n ")" ::: "memory")
; #define PG8_WAIT_L(n) asm volatile("s_waitcnt lgkmcnt(" #n ")" ::: "memory")
; #define PG8_BAR __builtin_amdgcn_s_barrier()
; #define PG8_SCHED __builtin_amdgcn_sched_barrier(0)
; template <class Epi, class Sched, bool ALIGN_EPI = false, bool SP2 = false>
; __device__ __forceinline__ void gemm_phase(PG8_LAS unsigned char* lds, const Gemm g, const Sched& S, const Epi& E) {
;     ...
;             PG8_LDA(At, 1, 1); PG8_STAGE(PG8_SB(1, 0), b3, voffB); PG8_STAGE(PG8_SB(1, 1), b3 + hstep, voffB); PG8_STAGE(PG8_SA(1, 0), a3, voffA);
;             PG8_WAIT_V(8); PG8_WAIT_L(0); PG8_BAR; PG8_MMA(1, 0, At, B0); PG8_MMA(1, 1, At, B1); PG8_BAR; PG8_SCHED;
;     ...
;         if constexpr (ALIGN_EPI) { if (wr == 0) PG8_BAR; }
;         if constexpr (!Epi::AFTER_DRAIN) { E(acc, cur, wr, wc, fr, fq); S.done(cur); }
;         if (!has_next) break;
	s_add_i32 s3, s3, s75
	v_lshl_add_u64 v[178:179], v[178:179], 0, s[10:11]
	s_mov_b32 m0, s3
	ds_read_b128 v[212:215], v164 offset:49152
	ds_read_b128 v[216:219], v164 offset:50176
	ds_read_b128 v[220:223], v164 offset:51200
	ds_read_b128 v[224:227], v164 offset:52224
	ds_read_b128 v[228:231], v164 offset:53248
	ds_read_b128 v[232:235], v164 offset:54272
	ds_read_b128 v[236:239], v164 offset:55296
	ds_read_b128 v[240:243], v164 offset:56320
	global_load_lds_dwordx4 v[178:179], off
	s_add_i32 m0, s3, 0x2000
	s_add_u32 s14, s62, 0x40080
	v_lshl_add_u64 v[178:179], v[202:203], 0, s[10:11]
	s_addc_u32 s15, s63, 0
	s_add_i32 s3, s33, s75
	global_load_lds_dwordx4 v[178:179], off
	v_lshl_add_u64 v[178:179], s[14:15], 0, v[130:131]
	s_mov_b32 m0, s3
	s_nop 0
	global_load_lds_dwordx4 v[178:179], off
	v_lshl_add_u64 v[178:179], s[14:15], 0, v[134:135]
	s_add_i32 m0, s3, 0x2000
	s_nop 0
	global_load_lds_dwordx4 v[178:179], off
	s_waitcnt vmcnt(6)
	s_waitcnt lgkmcnt(0)
	s_barrier
	s_setprio 1
	s_waitcnt lgkmcnt(0)
	v_mfma_f32_16x16x32_bf16 v[92:95], v[170:173], v[212:215], v[92:95]
	v_mfma_f32_16x16x32_bf16 v[88:91], v[182:185], v[212:215], v[88:91]
	v_mfma_f32_16x16x32_bf16 v[84:87], v[170:173], v[220:223], v[84:87]
	v_mfma_f32_16x16x32_bf16 v[80:83], v[182:185], v[220:223], v[80:83]
	v_mfma_f32_16x16x32_bf16 v[76:79], v[170:173], v[228:231], v[76:79]
	v_mfma_f32_16x16x32_bf16 v[72:75], v[182:185], v[228:231], v[72:75]
	v_mfma_f32_16x16x32_bf16 v[68:71], v[170:173], v[236:239], v[68:71]
	v_mfma_f32_16x16x32_bf16 v[64:67], v[182:185], v[236:239], v[64:67]
	v_mfma_f32_16x16x32_bf16 v[92:95], v[174:177], v[216:219], v[92:95]
	v_mfma_f32_16x16x32_bf16 v[88:91], v[186:189], v[216:219], v[88:91]
	v_mfma_f32_16x16x32_bf16 v[84:87], v[174:177], v[224:227], v[84:87]
	v_mfma_f32_16x16x32_bf16 v[80:83], v[186:189], v[224:227], v[80:83]
	v_mfma_f32_16x16x32_bf16 v[76:79], v[174:177], v[232:235], v[76:79]
	v_mfma_f32_16x16x32_bf16 v[72:75], v[186:189], v[232:235], v[72:75]
	v_mfma_f32_16x16x32_bf16 v[68:71], v[174:177], v[240:243], v[68:71]
	v_lshl_add_u64 v[178:179], v[244:245], 0, s[10:11]
	s_mov_b32 m0, s88
	s_nop 0
	global_load_lds_dwordx4 v[178:179], off
	v_mfma_f32_16x16x32_bf16 v[64:67], v[186:189], v[240:243], v[64:67]
	s_setprio 0
	s_setprio 1
	v_mfma_f32_16x16x32_bf16 v[28:31], v[190:193], v[212:215], v[28:31]
	v_mfma_f32_16x16x32_bf16 v[24:27], v[198:201], v[212:215], v[24:27]
	v_mfma_f32_16x16x32_bf16 v[20:23], v[190:193], v[220:223], v[20:23]
	v_mfma_f32_16x16x32_bf16 v[16:19], v[198:201], v[220:223], v[16:19]
	v_mfma_f32_16x16x32_bf16 v[12:15], v[190:193], v[228:231], v[12:15]
	v_mfma_f32_16x16x32_bf16 v[8:11], v[198:201], v[228:231], v[8:11]
	v_mfma_f32_16x16x32_bf16 v[4:7], v[190:193], v[236:239], v[4:7]
	v_mfma_f32_16x16x32_bf16 v[0:3], v[198:201], v[236:239], v[0:3]
	v_mfma_f32_16x16x32_bf16 v[28:31], v[194:197], v[216:219], v[28:31]
	v_mfma_f32_16x16x32_bf16 v[24:27], v[208:211], v[216:219], v[24:27]
	v_mfma_f32_16x16x32_bf16 v[20:23], v[194:197], v[224:227], v[20:23]
	v_mfma_f32_16x16x32_bf16 v[16:19], v[208:211], v[224:227], v[16:19]
	v_mfma_f32_16x16x32_bf16 v[12:15], v[194:197], v[232:235], v[12:15]
	v_mfma_f32_16x16x32_bf16 v[8:11], v[208:211], v[232:235], v[8:11]
	v_mfma_f32_16x16x32_bf16 v[4:7], v[194:197], v[240:243], v[4:7]
	v_lshl_add_u64 v[178:179], v[246:247], 0, s[10:11]
	s_mov_b32 m0, s89
	s_nop 0
	global_load_lds_dwordx4 v[178:179], off
	v_mfma_f32_16x16x32_bf16 v[0:3], v[208:211], v[240:243], v[0:3]
	s_setprio 0
	s_barrier
	s_add_i32 s97, s97, 2
	s_add_u32 s60, s60, 0x100
	s_addc_u32 s61, s61, 0
	s_add_u32 s95, s95, 0x100
	s_addc_u32 s96, s96, 0
	s_cmp_lt_u32 s97, 14
	s_cbranch_scc1 .LBB0_495
	s_andn2_b64 vcc, exec, s[40:41]
	s_cbranch_vccnz .LBB0_498
	s_barrier

; #define PG8_STAGE(bufoff, gbase, voff) do { _Pragma("unroll") for (int _i = 0; _i < 2; ++_i) \
;         __builtin_amdgcn_global_load_lds((const unsigned*)((const char*)(gbase) + (voff)[_i]), (PG8_LAS unsigned*)(lds + (bufoff) + ldsw + _i * 8192), 16, 0, 0); } while (0)
; #define PG8_LDA(dst, b, h) do { _Pragma("unroll") for (int m = 0; m < 4; ++m) _Pragma("unroll") for (int k = 0; k < 2; ++k) dst[m][k] = *(const PG8_LAS bf16x8*)(lds + PG8_SA(b, h) + aoff + m * 2048 + k * 1024); } while (0)
; #define PG8_LDB(dst, b, h) do { _Pragma("unroll") for (int n = 0; n < 2; ++n) _Pragma("unroll") for (int k = 0; k < 2; ++k) dst[n][k] = *(const PG8_LAS bf16x8*)(lds + PG8_SB(b, h) + boff + n * 2048 + k * 1024); } while (0)
; #define PG8_MMA(ai, bj, At, Bt) do { __builtin_amdgcn_s_setprio(1); _Pragma("unroll") for (int m = 0; m < 4; ++m) _Pragma("unroll") for (int n = 0; n < 2; ++n) _Pragma("unroll") for (int k = 0; k < 2; ++k) \
;         acc[ai][bj][m][n] = __builtin_amdgcn_mfma_f32_16x16x32_bf16(Bt[n][k], At[m][k], acc[ai][bj][m][n], 0, 0, 0); __builtin_amdgcn_s_setprio(0); } while (0)
; #define PG8_BAR __builtin_amdgcn_s_barrier()
; template <class Epi, class Sched, bool ALIGN_EPI = false, bool SP2 = false>
; __device__ __forceinline__ void gemm_phase(PG8_LAS unsigned char* lds, const Gemm g, const Sched& S, const Epi& E) {
;     ...
;         const bool has_next = S.next(ui + 1, nxt);
;         const char* nA = has_next ? (const char*)g.A + (size_t)nxt.pm * tstep : cA; const char* nB = has_next ? (const char*)g.Bt + (size_t)nxt.pn * tstep : cB;
;         for (int t = 0; t < nt; t += 2) {
;             const bool last = (t == nt - 2);
;             const char* a1 = cA + (size_t)(t + 1) * kstep;
;             const char* a2 = last ? nA : cA + (size_t)(t + 2) * kstep; const char* b2 = last ? nB : cB + (size_t)(t + 2) * kstep;
;             const char* a3 = a2 + kstep; const char* b3 = b2 + kstep;
;             if (last && has_next) S.a_ready(nxt);
;             if constexpr (SP2) {
;             PG8_LDB(B0, 0, 0); PG8_LDB(B1, 0, 1); PG8_SCHED; PG8_LDA(At, 0, 0); PG8_STAGE(PG8_SA(1, 1), a1 + hstep, voffA);
;             PG8_WAIT_V(8); PG8_WAIT_L(0); PG8_BAR; PG8_MMA(0, 0, At, B0); PG8_MMA(0, 1, At, B1); PG8_BAR; PG8_SCHED;
;             PG8_LDA(At, 0, 1); PG8_STAGE(PG8_SB(0, 0), b2, voffB); PG8_STAGE(PG8_SB(0, 1), b2 + hstep, voffB); PG8_STAGE(PG8_SA(0, 0), a2, voffA);
.LBB0_649:
	s_ashr_i32 s51, s50, 31
	s_lshl_b64 s[14:15], s[50:51], 19
	s_add_u32 s52, s40, s14
	s_addc_u32 s53, s41, s15
	s_and_b64 s[14:15], s[8:9], exec
	s_cselect_b32 s51, s53, s61
	s_cselect_b32 s57, s52, s60
	s_ashr_i32 s49, s48, 31
	s_lshl_b64 s[14:15], s[48:49], 19
	s_add_u32 s54, s82, s14
	s_addc_u32 s55, s83, s15
	s_and_b64 s[14:15], s[8:9], exec
	s_cselect_b32 s49, s55, s63
	s_cselect_b32 s89, s54, s62
	s_add_u32 s60, s60, 0x40080
	s_addc_u32 s61, s61, 0
	s_add_u32 s90, s62, 0x100
	s_addc_u32 s91, s63, 0
	s_mov_b32 s92, -2
	s_waitcnt lgkmcnt(0)
	s_waitcnt vmcnt(0)
	ds_read_b128 v[148:151], v155
	ds_read_b128 v[160:163], v155 offset:1024
	ds_read_b128 v[164:167], v155 offset:2048
	ds_read_b128 v[168:171], v155 offset:3072
	ds_read_b128 v[172:175], v156
	ds_read_b128 v[176:179], v156 offset:1024
	ds_read_b128 v[182:185], v156 offset:2048
	ds_read_b128 v[186:189], v156 offset:3072
	s_add_u32 s3, s60, 0xfffc0080
	s_addc_u32 s14, s61, -1
	s_cmp_eq_u32 s92, 12
	s_cselect_b32 s65, s51, s14
	s_cselect_b32 s64, s57, s3
	s_cselect_b32 s63, s49, s91
	s_cselect_b32 s62, s89, s90
	v_lshl_add_u64 v[202:203], s[60:61], 0, v[140:141]
	s_add_i32 m0, s43, 0xc000
	ds_read_b128 v[190:193], v157
	ds_read_b128 v[194:197], v157 offset:1024
	ds_read_b128 v[198:201], v157 offset:2048
	ds_read_b128 v[208:211], v157 offset:3072
	ds_read_b128 v[212:215], v157 offset:4096
	ds_read_b128 v[216:219], v157 offset:5120
	ds_read_b128 v[220:223], v157 offset:6144
	ds_read_b128 v[224:227], v157 offset:7168
	global_load_lds_dwordx4 v[202:203], off
	v_lshl_add_u64 v[202:203], s[60:61], 0, v[142:143]
	s_add_i32 m0, s43, 0xe000
	s_nop 0
	global_load_lds_dwordx4 v[202:203], off
	s_waitcnt vmcnt(8)
	s_waitcnt lgkmcnt(0)
	s_barrier
	s_setprio 1
	s_waitcnt lgkmcnt(0)
	v_mfma_f32_16x16x32_bf16 v[124:127], v[148:151], v[190:193], 0
	v_mfma_f32_16x16x32_bf16 v[120:123], v[164:167], v[190:193], 0
	v_mfma_f32_16x16x32_bf16 v[108:111], v[148:151], v[198:201], 0
	v_mfma_f32_16x16x32_bf16 v[104:107], v[164:167], v[198:201], 0
	v_mfma_f32_16x16x32_bf16 v[92:95], v[148:151], v[212:215], 0
	v_mfma_f32_16x16x32_bf16 v[88:91], v[164:167], v[212:215], 0
	v_mfma_f32_16x16x32_bf16 v[76:79], v[148:151], v[220:223], 0
	v_mfma_f32_16x16x32_bf16 v[72:75], v[164:167], v[220:223], 0
	v_mfma_f32_16x16x32_bf16 v[124:127], v[160:163], v[194:197], v[124:127]
	v_mfma_f32_16x16x32_bf16 v[120:123], v[168:171], v[194:197], v[120:123]
	v_mfma_f32_16x16x32_bf16 v[108:111], v[160:163], v[208:211], v[108:111]
	v_mfma_f32_16x16x32_bf16 v[104:107], v[168:171], v[208:211], v[104:107]
	v_mfma_f32_16x16x32_bf16 v[92:95], v[160:163], v[216:219], v[92:95]
	v_mfma_f32_16x16x32_bf16 v[88:91], v[168:171], v[216:219], v[88:91]
	v_mfma_f32_16x16x32_bf16 v[76:79], v[160:163], v[224:227], v[76:79]
	v_mfma_f32_16x16x32_bf16 v[72:75], v[168:171], v[224:227], v[72:75]
	s_setprio 0
	s_setprio 1
	v_mfma_f32_16x16x32_bf16 v[116:119], v[172:175], v[190:193], 0
	v_mfma_f32_16x16x32_bf16 v[112:115], v[182:185], v[190:193], 0
	v_mfma_f32_16x16x32_bf16 v[100:103], v[172:175], v[198:201], 0
	v_mfma_f32_16x16x32_bf16 v[96:99], v[182:185], v[198:201], 0
	v_mfma_f32_16x16x32_bf16 v[84:87], v[172:175], v[212:215], 0
	v_mfma_f32_16x16x32_bf16 v[80:83], v[182:185], v[212:215], 0
	v_mfma_f32_16x16x32_bf16 v[68:71], v[172:175], v[220:223], 0
	v_mfma_f32_16x16x32_bf16 v[64:67], v[182:185], v[220:223], 0
	v_mfma_f32_16x16x32_bf16 v[116:119], v[176:179], v[194:197], v[116:119]
	v_mfma_f32_16x16x32_bf16 v[112:115], v[186:189], v[194:197], v[112:115]
	v_mfma_f32_16x16x32_bf16 v[100:103], v[176:179], v[208:211], v[100:103]
	v_mfma_f32_16x16x32_bf16 v[96:99], v[186:189], v[208:211], v[96:99]
	v_mfma_f32_16x16x32_bf16 v[84:87], v[176:179], v[216:219], v[84:87]
	v_mfma_f32_16x16x32_bf16 v[80:83], v[186:189], v[216:219], v[80:83]
	v_mfma_f32_16x16x32_bf16 v[68:71], v[176:179], v[224:227], v[68:71]
	v_mfma_f32_16x16x32_bf16 v[64:67], v[186:189], v[224:227], v[64:67]
	s_setprio 0
	s_barrier
	s_add_i32 s3, s85, s34
	v_lshl_add_u64 v[202:203], s[62:63], 0, v[134:135]
	s_mov_b32 m0, s3
	ds_read_b128 v[190:193], v157 offset:16384
	ds_read_b128 v[194:197], v157 offset:17408
	ds_read_b128 v[198:201], v157 offset:18432
	ds_read_b128 v[208:211], v157 offset:19456
	ds_read_b128 v[212:215], v157 offset:20480
	ds_read_b128 v[216:219], v157 offset:21504
	ds_read_b128 v[220:223], v157 offset:22528
	ds_read_b128 v[224:227], v157 offset:23552
	global_load_lds_dwordx4 v[202:203], off
	s_add_i32 m0, s3, 0x2000
	s_add_u32 s14, s62, 0x40000
	v_lshl_add_u64 v[228:229], s[62:63], 0, v[138:139]
	s_addc_u32 s15, s63, 0
	s_add_i32 s3, s86, s34
	global_load_lds_dwordx4 v[228:229], off
	v_lshl_add_u64 v[230:231], s[14:15], 0, v[134:135]
	s_mov_b32 m0, s3
	global_load_lds_dwordx4 v[230:231], off
	v_lshl_add_u64 v[230:231], s[14:15], 0, v[138:139]
	s_add_i32 m0, s3, 0x2000
	s_nop 0
	global_load_lds_dwordx4 v[230:231], off
	s_waitcnt vmcnt(6)
	s_waitcnt lgkmcnt(0)
	s_barrier
; #define PG8_STAGE(bufoff, gbase, voff) do { _Pragma("unroll") for (int _i = 0; _i < 2; ++_i) \
;         __builtin_amdgcn_global_load_lds((const unsigned*)((const char*)(gbase) + (voff)[_i]), (PG8_LAS unsigned*)(lds + (bufoff) + ldsw + _i * 8192), 16, 0, 0); } while (0)
; #define PG8_LDA(dst, b, h) do { _Pragma("unroll") for (int m = 0; m < 4; ++m) _Pragma("unroll") for (int k = 0; k < 2; ++k) dst[m][k] = *(const PG8_LAS bf16x8*)(lds + PG8_SA(b, h) + aoff + m * 2048 + k * 1024); } while (0)
; #define PG8_LDB(dst, b, h) do { _Pragma("unroll") for (int n = 0; n < 2; ++n) _Pragma("unroll") for (int k = 0; k < 2; ++k) dst[n][k] = *(const PG8_LAS bf16x8*)(lds + PG8_SB(b, h) + boff + n * 2048 + k * 1024); } while (0)
; #define PG8_MMA(ai, bj, At, Bt) do { __builtin_amdgcn_s_setprio(1); _Pragma("unroll") for (int m = 0; m < 4; ++m) _Pragma("unroll") for (int n = 0; n < 2; ++n) _Pragma("unroll") for (int k = 0; k < 2; ++k) \
;         acc[ai][bj][m][n] = __builtin_amdgcn_mfma_f32_16x16x32_bf16(Bt[n][k], At[m][k], acc[ai][bj][m][n], 0, 0, 0); __builtin_amdgcn_s_setprio(0); } while (0)
; #define PG8_WAIT_V(n) asm volatile("s_waitcnt vmcnt(" #n ")" ::: "memory")
; #define PG8_WAIT_L(n) asm volatile("s_waitcnt lgkmcnt(" #n ")" ::: "memory")
; #define PG8_BAR __builtin_amdgcn_s_barrier()
; #define PG8_SCHED __builtin_amdgcn_sched_barrier(0)
; template <class Epi, class Sched, bool ALIGN_EPI = false, bool SP2 = false>
; __device__ __forceinline__ void gemm_phase(PG8_LAS unsigned char* lds, const Gemm g, const Sched& S, const Epi& E) {
;     ...
;             PG8_LDA(At, 0, 1); PG8_STAGE(PG8_SB(0, 0), b2, voffB); PG8_STAGE(PG8_SB(0, 1), b2 + hstep, voffB); PG8_STAGE(PG8_SA(0, 0), a2, voffA);
;             PG8_WAIT_V(8); PG8_WAIT_L(0); PG8_BAR; PG8_MMA(1, 0, At, B0); PG8_MMA(1, 1, At, B1); PG8_BAR; PG8_SCHED;
;             PG8_LDB(B0, 1, 0); PG8_LDB(B1, 1, 1); PG8_SCHED; PG8_LDA(At, 1, 0); PG8_STAGE(PG8_SA(0, 1), a2 + hstep, voffA);
;             PG8_WAIT_V(8); PG8_WAIT_L(0); PG8_BAR; PG8_MMA(0, 0, At, B0); PG8_MMA(0, 1, At, B1); PG8_BAR; PG8_SCHED;
	s_setprio 1
	s_waitcnt lgkmcnt(0)
	v_mfma_f32_16x16x32_bf16 v[60:63], v[148:151], v[190:193], 0
	v_mfma_f32_16x16x32_bf16 v[56:59], v[164:167], v[190:193], 0
	v_mfma_f32_16x16x32_bf16 v[44:47], v[148:151], v[198:201], 0
	v_mfma_f32_16x16x32_bf16 v[40:43], v[164:167], v[198:201], 0
	v_mfma_f32_16x16x32_bf16 v[28:31], v[148:151], v[212:215], 0
	v_mfma_f32_16x16x32_bf16 v[24:27], v[164:167], v[212:215], 0
	v_mfma_f32_16x16x32_bf16 v[12:15], v[148:151], v[220:223], 0
	v_mfma_f32_16x16x32_bf16 v[8:11], v[164:167], v[220:223], 0
	v_mfma_f32_16x16x32_bf16 v[60:63], v[160:163], v[194:197], v[60:63]
	v_mfma_f32_16x16x32_bf16 v[56:59], v[168:171], v[194:197], v[56:59]
	v_mfma_f32_16x16x32_bf16 v[44:47], v[160:163], v[208:211], v[44:47]
	v_mfma_f32_16x16x32_bf16 v[40:43], v[168:171], v[208:211], v[40:43]
	v_mfma_f32_16x16x32_bf16 v[28:31], v[160:163], v[216:219], v[28:31]
	v_mfma_f32_16x16x32_bf16 v[24:27], v[168:171], v[216:219], v[24:27]
	v_mfma_f32_16x16x32_bf16 v[12:15], v[160:163], v[224:227], v[12:15]
	v_lshl_add_u64 v[230:231], s[64:65], 0, v[132:133]
	s_mov_b32 m0, s43
	s_nop 0
	global_load_lds_dwordx4 v[230:231], off
	v_mfma_f32_16x16x32_bf16 v[8:11], v[168:171], v[224:227], v[8:11]
	s_setprio 0
	s_setprio 1
	v_mfma_f32_16x16x32_bf16 v[52:55], v[172:175], v[190:193], 0
	v_mfma_f32_16x16x32_bf16 v[48:51], v[182:185], v[190:193], 0
	v_mfma_f32_16x16x32_bf16 v[36:39], v[172:175], v[198:201], 0
	v_mfma_f32_16x16x32_bf16 v[32:35], v[182:185], v[198:201], 0
	v_mfma_f32_16x16x32_bf16 v[20:23], v[172:175], v[212:215], 0
	v_mfma_f32_16x16x32_bf16 v[16:19], v[182:185], v[212:215], 0
	v_mfma_f32_16x16x32_bf16 v[4:7], v[172:175], v[220:223], 0
	v_mfma_f32_16x16x32_bf16 v[0:3], v[182:185], v[220:223], 0
	v_mfma_f32_16x16x32_bf16 v[52:55], v[176:179], v[194:197], v[52:55]
	v_mfma_f32_16x16x32_bf16 v[48:51], v[186:189], v[194:197], v[48:51]
	v_mfma_f32_16x16x32_bf16 v[36:39], v[176:179], v[208:211], v[36:39]
	v_mfma_f32_16x16x32_bf16 v[32:35], v[186:189], v[208:211], v[32:35]
	v_mfma_f32_16x16x32_bf16 v[20:23], v[176:179], v[216:219], v[20:23]
	v_mfma_f32_16x16x32_bf16 v[16:19], v[186:189], v[216:219], v[16:19]
	v_mfma_f32_16x16x32_bf16 v[4:7], v[176:179], v[224:227], v[4:7]
	v_lshl_add_u64 v[232:233], s[64:65], 0, v[136:137]
	s_mov_b32 m0, s59
	s_nop 0
	global_load_lds_dwordx4 v[232:233], off
	v_mfma_f32_16x16x32_bf16 v[0:3], v[186:189], v[224:227], v[0:3]
	s_setprio 0
	s_barrier
	s_add_i32 s3, 0, 0x18000
	v_add_u32_e32 v159, s3, v131
	s_add_i32 s33, 0, 0x1c000
	ds_read_b128 v[148:151], v159
	ds_read_b128 v[160:163], v159 offset:1024
	ds_read_b128 v[164:167], v159 offset:2048
	ds_read_b128 v[168:171], v159 offset:3072
	v_add_u32_e32 v159, s33, v131
	ds_read_b128 v[172:175], v159
	ds_read_b128 v[176:179], v159 offset:1024
	ds_read_b128 v[182:185], v159 offset:2048
	ds_read_b128 v[186:189], v159 offset:3072
	s_add_u32 s14, s64, 0x40000
	s_addc_u32 s15, s65, 0
	s_mov_b32 m0, s66
	v_lshl_add_u64 v[234:235], s[14:15], 0, v[132:133]
	ds_read_b128 v[190:193], v157 offset:32768
	ds_read_b128 v[194:197], v157 offset:33792
	ds_read_b128 v[198:201], v157 offset:34816
	ds_read_b128 v[208:211], v157 offset:35840
	ds_read_b128 v[212:215], v157 offset:36864
	ds_read_b128 v[216:219], v157 offset:37888
	ds_read_b128 v[220:223], v157 offset:38912
	ds_read_b128 v[224:227], v157 offset:39936
	global_load_lds_dwordx4 v[234:235], off
	v_lshl_add_u64 v[234:235], s[14:15], 0, v[136:137]
	s_mov_b32 m0, s67
	s_nop 0
	global_load_lds_dwordx4 v[234:235], off
	s_waitcnt vmcnt(8)
	s_waitcnt lgkmcnt(0)
	s_barrier
	s_setprio 1
	s_waitcnt lgkmcnt(0)
	v_mfma_f32_16x16x32_bf16 v[124:127], v[148:151], v[190:193], v[124:127]
	v_mfma_f32_16x16x32_bf16 v[120:123], v[164:167], v[190:193], v[120:123]
	v_mfma_f32_16x16x32_bf16 v[108:111], v[148:151], v[198:201], v[108:111]
	v_mfma_f32_16x16x32_bf16 v[104:107], v[164:167], v[198:201], v[104:107]
	v_mfma_f32_16x16x32_bf16 v[92:95], v[148:151], v[212:215], v[92:95]
	v_mfma_f32_16x16x32_bf16 v[88:91], v[164:167], v[212:215], v[88:91]
	v_mfma_f32_16x16x32_bf16 v[76:79], v[148:151], v[220:223], v[76:79]
	v_mfma_f32_16x16x32_bf16 v[72:75], v[164:167], v[220:223], v[72:75]
	v_mfma_f32_16x16x32_bf16 v[124:127], v[160:163], v[194:197], v[124:127]
	v_mfma_f32_16x16x32_bf16 v[120:123], v[168:171], v[194:197], v[120:123]
	v_mfma_f32_16x16x32_bf16 v[108:111], v[160:163], v[208:211], v[108:111]
	v_mfma_f32_16x16x32_bf16 v[104:107], v[168:171], v[208:211], v[104:107]
	v_mfma_f32_16x16x32_bf16 v[92:95], v[160:163], v[216:219], v[92:95]
	v_mfma_f32_16x16x32_bf16 v[88:91], v[168:171], v[216:219], v[88:91]
	v_mfma_f32_16x16x32_bf16 v[76:79], v[160:163], v[224:227], v[76:79]
	v_mfma_f32_16x16x32_bf16 v[72:75], v[168:171], v[224:227], v[72:75]
	s_setprio 0
	s_setprio 1
	v_mfma_f32_16x16x32_bf16 v[116:119], v[172:175], v[190:193], v[116:119]
	v_mfma_f32_16x16x32_bf16 v[112:115], v[182:185], v[190:193], v[112:115]
	v_mfma_f32_16x16x32_bf16 v[100:103], v[172:175], v[198:201], v[100:103]
	v_mfma_f32_16x16x32_bf16 v[96:99], v[182:185], v[198:201], v[96:99]
	v_mfma_f32_16x16x32_bf16 v[84:87], v[172:175], v[212:215], v[84:87]
	v_mfma_f32_16x16x32_bf16 v[80:83], v[182:185], v[212:215], v[80:83]
	v_mfma_f32_16x16x32_bf16 v[68:71], v[172:175], v[220:223], v[68:71]
	v_mfma_f32_16x16x32_bf16 v[64:67], v[182:185], v[220:223], v[64:67]
	v_mfma_f32_16x16x32_bf16 v[116:119], v[176:179], v[194:197], v[116:119]
	v_mfma_f32_16x16x32_bf16 v[112:115], v[186:189], v[194:197], v[112:115]
	v_mfma_f32_16x16x32_bf16 v[100:103], v[176:179], v[208:211], v[100:103]
	v_mfma_f32_16x16x32_bf16 v[96:99], v[186:189], v[208:211], v[96:99]
	v_mfma_f32_16x16x32_bf16 v[84:87], v[176:179], v[216:219], v[84:87]
	v_mfma_f32_16x16x32_bf16 v[80:83], v[186:189], v[216:219], v[80:83]
	v_mfma_f32_16x16x32_bf16 v[68:71], v[176:179], v[224:227], v[68:71]
	v_mfma_f32_16x16x32_bf16 v[64:67], v[186:189], v[224:227], v[64:67]
	s_setprio 0
	s_barrier
; #define PG8_STAGE(bufoff, gbase, voff) do { _Pragma("unroll") for (int _i = 0; _i < 2; ++_i) \
;         __builtin_amdgcn_global_load_lds((const unsigned*)((const char*)(gbase) + (voff)[_i]), (PG8_LAS unsigned*)(lds + (bufoff) + ldsw + _i * 8192), 16, 0, 0); } while (0)
; #define PG8_LDA(dst, b, h) do { _Pragma("unroll") for (int m = 0; m < 4; ++m) _Pragma("unroll") for (int k = 0; k < 2; ++k) dst[m][k] = *(const PG8_LAS bf16x8*)(lds + PG8_SA(b, h) + aoff + m * 2048 + k * 1024); } while (0)
; #define PG8_LDB(dst, b, h) do { _Pragma("unroll") for (int n = 0; n < 2; ++n) _Pragma("unroll") for (int k = 0; k < 2; ++k) dst[n][k] = *(const PG8_LAS bf16x8*)(lds + PG8_SB(b, h) + boff + n * 2048 + k * 1024); } while (0)
; #define PG8_MMA(ai, bj, At, Bt) do { __builtin_amdgcn_s_setprio(1); _Pragma("unroll") for (int m = 0; m < 4; ++m) _Pragma("unroll") for (int n = 0; n < 2; ++n) _Pragma("unroll") for (int k = 0; k < 2; ++k) \
;         acc[ai][bj][m][n] = __builtin_amdgcn_mfma_f32_16x16x32_bf16(Bt[n][k], At[m][k], acc[ai][bj][m][n], 0, 0, 0); __builtin_amdgcn_s_setprio(0); } while (0)
; #define PG8_WAIT_V(n) asm volatile("s_waitcnt vmcnt(" #n ")" ::: "memory")
; template <class Epi, class Sched, bool ALIGN_EPI = false, bool SP2 = false>
; __device__ __forceinline__ void gemm_phase(PG8_LAS unsigned char* lds, const Gemm g, const Sched& S, const Epi& E) {
;     ...
;             PG8_LDB(B0, 0, 0); PG8_LDB(B1, 0, 1); PG8_SCHED; PG8_LDA(At, 0, 0); PG8_STAGE(PG8_SA(1, 1), a1 + hstep, voffA);
;             PG8_WAIT_V(8); PG8_WAIT_L(0); PG8_BAR; PG8_MMA(0, 0, At, B0); PG8_MMA(0, 1, At, B1); PG8_BAR; PG8_SCHED;
;             PG8_LDA(At, 0, 1); PG8_STAGE(PG8_SB(0, 0), b2, voffB); PG8_STAGE(PG8_SB(0, 1), b2 + hstep, voffB); PG8_STAGE(PG8_SA(0, 0), a2, voffA);
;             PG8_WAIT_V(8); PG8_WAIT_L(0); PG8_BAR; PG8_MMA(1, 0, At, B0); PG8_MMA(1, 1, At, B1); PG8_BAR; PG8_SCHED;
;             PG8_LDB(B0, 1, 0); PG8_LDB(B1, 1, 1); PG8_SCHED; PG8_LDA(At, 1, 0); PG8_STAGE(PG8_SA(0, 1), a2 + hstep, voffA);
;             PG8_WAIT_V(8); PG8_WAIT_L(0); PG8_BAR; PG8_MMA(0, 0, At, B0); PG8_MMA(0, 1, At, B1); PG8_BAR; PG8_SCHED;
;             PG8_LDA(At, 1, 1); PG8_STAGE(PG8_SB(1, 0), b3, voffB); PG8_STAGE(PG8_SB(1, 1), b3 + hstep, voffB); PG8_STAGE(PG8_SA(1, 0), a3, voffA);
;             PG8_WAIT_V(8); PG8_WAIT_L(0); PG8_BAR; PG8_MMA(1, 0, At, B0); PG8_MMA(1, 1, At, B1); PG8_BAR; PG8_SCHED;
	s_add_i32 s3, s3, s34
	v_lshl_add_u64 v[202:203], v[202:203], 0, s[38:39]
	s_mov_b32 m0, s3
	ds_read_b128 v[190:193], v157 offset:49152
	ds_read_b128 v[194:197], v157 offset:50176
	ds_read_b128 v[198:201], v157 offset:51200
	ds_read_b128 v[208:211], v157 offset:52224
	ds_read_b128 v[212:215], v157 offset:53248
	ds_read_b128 v[216:219], v157 offset:54272
	ds_read_b128 v[220:223], v157 offset:55296
	ds_read_b128 v[224:227], v157 offset:56320
	global_load_lds_dwordx4 v[202:203], off
	s_add_i32 m0, s3, 0x2000
	s_add_u32 s14, s62, 0x40080
	v_lshl_add_u64 v[202:203], v[228:229], 0, s[38:39]
	s_addc_u32 s15, s63, 0
	s_add_i32 s3, s33, s34
	global_load_lds_dwordx4 v[202:203], off
	v_lshl_add_u64 v[202:203], s[14:15], 0, v[134:135]
	s_mov_b32 m0, s3
	s_nop 0
	global_load_lds_dwordx4 v[202:203], off
	v_lshl_add_u64 v[202:203], s[14:15], 0, v[138:139]
	s_add_i32 m0, s3, 0x2000
	s_nop 0
	global_load_lds_dwordx4 v[202:203], off
	s_waitcnt vmcnt(6)
	s_waitcnt lgkmcnt(0)
	s_barrier
	s_setprio 1
	s_waitcnt lgkmcnt(0)
	v_mfma_f32_16x16x32_bf16 v[60:63], v[148:151], v[190:193], v[60:63]
	v_mfma_f32_16x16x32_bf16 v[56:59], v[164:167], v[190:193], v[56:59]
	v_mfma_f32_16x16x32_bf16 v[44:47], v[148:151], v[198:201], v[44:47]
	v_mfma_f32_16x16x32_bf16 v[40:43], v[164:167], v[198:201], v[40:43]
	v_mfma_f32_16x16x32_bf16 v[28:31], v[148:151], v[212:215], v[28:31]
	v_mfma_f32_16x16x32_bf16 v[24:27], v[164:167], v[212:215], v[24:27]
	v_mfma_f32_16x16x32_bf16 v[12:15], v[148:151], v[220:223], v[12:15]
	v_mfma_f32_16x16x32_bf16 v[8:11], v[164:167], v[220:223], v[8:11]
	v_mfma_f32_16x16x32_bf16 v[60:63], v[160:163], v[194:197], v[60:63]
	v_mfma_f32_16x16x32_bf16 v[56:59], v[168:171], v[194:197], v[56:59]
	v_mfma_f32_16x16x32_bf16 v[44:47], v[160:163], v[208:211], v[44:47]
	v_mfma_f32_16x16x32_bf16 v[40:43], v[168:171], v[208:211], v[40:43]
	v_mfma_f32_16x16x32_bf16 v[28:31], v[160:163], v[216:219], v[28:31]
	v_mfma_f32_16x16x32_bf16 v[24:27], v[168:171], v[216:219], v[24:27]
	v_mfma_f32_16x16x32_bf16 v[12:15], v[160:163], v[224:227], v[12:15]
	v_lshl_add_u64 v[202:203], v[230:231], 0, s[38:39]
	s_mov_b32 m0, s75
	s_nop 0
	global_load_lds_dwordx4 v[202:203], off
	v_mfma_f32_16x16x32_bf16 v[8:11], v[168:171], v[224:227], v[8:11]
	s_setprio 0
	s_setprio 1
	v_mfma_f32_16x16x32_bf16 v[52:55], v[172:175], v[190:193], v[52:55]
	v_mfma_f32_16x16x32_bf16 v[48:51], v[182:185], v[190:193], v[48:51]
	v_mfma_f32_16x16x32_bf16 v[36:39], v[172:175], v[198:201], v[36:39]
	v_mfma_f32_16x16x32_bf16 v[32:35], v[182:185], v[198:201], v[32:35]
	v_mfma_f32_16x16x32_bf16 v[20:23], v[172:175], v[212:215], v[20:23]
	v_mfma_f32_16x16x32_bf16 v[16:19], v[182:185], v[212:215], v[16:19]
	v_mfma_f32_16x16x32_bf16 v[4:7], v[172:175], v[220:223], v[4:7]
	v_mfma_f32_16x16x32_bf16 v[0:3], v[182:185], v[220:223], v[0:3]
	v_mfma_f32_16x16x32_bf16 v[52:55], v[176:179], v[194:197], v[52:55]
	v_mfma_f32_16x16x32_bf16 v[48:51], v[186:189], v[194:197], v[48:51]
	v_mfma_f32_16x16x32_bf16 v[36:39], v[176:179], v[208:211], v[36:39]
	v_mfma_f32_16x16x32_bf16 v[32:35], v[186:189], v[208:211], v[32:35]
	v_mfma_f32_16x16x32_bf16 v[20:23], v[176:179], v[216:219], v[20:23]
	v_mfma_f32_16x16x32_bf16 v[16:19], v[186:189], v[216:219], v[16:19]
	v_mfma_f32_16x16x32_bf16 v[4:7], v[176:179], v[224:227], v[4:7]
	v_lshl_add_u64 v[202:203], v[232:233], 0, s[38:39]
	s_mov_b32 m0, s84
	s_nop 0
	global_load_lds_dwordx4 v[202:203], off
	v_mfma_f32_16x16x32_bf16 v[0:3], v[186:189], v[224:227], v[0:3]
	s_setprio 0
	s_barrier
	s_add_i32 s92, s92, 2
	s_add_u32 s60, s60, 0x100
	s_addc_u32 s61, s61, 0
	s_add_u32 s90, s90, 0x100
	s_addc_u32 s91, s91, 0
.LBB0_650:
	ds_read_b128 v[148:151], v155
	ds_read_b128 v[160:163], v155 offset:1024
	ds_read_b128 v[164:167], v155 offset:2048
	ds_read_b128 v[168:171], v155 offset:3072
	ds_read_b128 v[172:175], v156
	ds_read_b128 v[176:179], v156 offset:1024
	ds_read_b128 v[182:185], v156 offset:2048
	ds_read_b128 v[186:189], v156 offset:3072
	s_add_u32 s3, s60, 0xfffc0080
	s_addc_u32 s14, s61, -1
	s_cmp_eq_u32 s92, 12
	s_cselect_b32 s65, s51, s14
	s_cselect_b32 s64, s57, s3
	s_cselect_b32 s63, s49, s91
	s_cselect_b32 s62, s89, s90
	v_lshl_add_u64 v[202:203], s[60:61], 0, v[140:141]
	s_add_i32 m0, s43, 0xc000
	ds_read_b128 v[190:193], v157
	ds_read_b128 v[194:197], v157 offset:1024
	ds_read_b128 v[198:201], v157 offset:2048
	ds_read_b128 v[208:211], v157 offset:3072
	ds_read_b128 v[212:215], v157 offset:4096
	ds_read_b128 v[216:219], v157 offset:5120
	ds_read_b128 v[220:223], v157 offset:6144
	ds_read_b128 v[224:227], v157 offset:7168
	global_load_lds_dwordx4 v[202:203], off
	v_lshl_add_u64 v[202:203], s[60:61], 0, v[142:143]
	s_add_i32 m0, s43, 0xe000
	s_nop 0
	global_load_lds_dwordx4 v[202:203], off
	s_waitcnt vmcnt(8)
	s_waitcnt lgkmcnt(0)
	s_barrier
; #define PG8_STAGE(bufoff, gbase, voff) do { _Pragma("unroll") for (int _i = 0; _i < 2; ++_i) \
;         __builtin_amdgcn_global_load_lds((const unsigned*)((const char*)(gbase) + (voff)[_i]), (PG8_LAS unsigned*)(lds + (bufoff) + ldsw + _i * 8192), 16, 0, 0); } while (0)
; #define PG8_LDA(dst, b, h) do { _Pragma("unroll") for (int m = 0; m < 4; ++m) _Pragma("unroll") for (int k = 0; k < 2; ++k) dst[m][k] = *(const PG8_LAS bf16x8*)(lds + PG8_SA(b, h) + aoff + m * 2048 + k * 1024); } while (0)
; #define PG8_MMA(ai, bj, At, Bt) do { __builtin_amdgcn_s_setprio(1); _Pragma("unroll") for (int m = 0; m < 4; ++m) _Pragma("unroll") for (int n = 0; n < 2; ++n) _Pragma("unroll") for (int k = 0; k < 2; ++k) \
;         acc[ai][bj][m][n] = __builtin_amdgcn_mfma_f32_16x16x32_bf16(Bt[n][k], At[m][k], acc[ai][bj][m][n], 0, 0, 0); __builtin_amdgcn_s_setprio(0); } while (0)
; #define PG8_WAIT_V(n) asm volatile("s_waitcnt vmcnt(" #n ")" ::: "memory")
; #define PG8_WAIT_L(n) asm volatile("s_waitcnt lgkmcnt(" #n ")" ::: "memory")
; #define PG8_BAR __builtin_amdgcn_s_barrier()
; #define PG8_SCHED __builtin_amdgcn_sched_barrier(0)
; template <class Epi, class Sched, bool ALIGN_EPI = false, bool SP2 = false>
; __device__ __forceinline__ void gemm_phase(PG8_LAS unsigned char* lds, const Gemm g, const Sched& S, const Epi& E) {
;     ...
;             PG8_WAIT_V(8); PG8_WAIT_L(0); PG8_BAR; PG8_MMA(0, 0, At, B0); PG8_MMA(0, 1, At, B1); PG8_BAR; PG8_SCHED;
;             PG8_LDA(At, 0, 1); PG8_STAGE(PG8_SB(0, 0), b2, voffB); PG8_STAGE(PG8_SB(0, 1), b2 + hstep, voffB); PG8_STAGE(PG8_SA(0, 0), a2, voffA);
;             PG8_WAIT_V(8); PG8_WAIT_L(0); PG8_BAR; PG8_MMA(1, 0, At, B0); PG8_MMA(1, 1, At, B1); PG8_BAR; PG8_SCHED;
	s_setprio 1
	s_waitcnt lgkmcnt(0)
	v_mfma_f32_16x16x32_bf16 v[124:127], v[148:151], v[190:193], v[124:127]
	v_mfma_f32_16x16x32_bf16 v[120:123], v[164:167], v[190:193], v[120:123]
	v_mfma_f32_16x16x32_bf16 v[108:111], v[148:151], v[198:201], v[108:111]
	v_mfma_f32_16x16x32_bf16 v[104:107], v[164:167], v[198:201], v[104:107]
	v_mfma_f32_16x16x32_bf16 v[92:95], v[148:151], v[212:215], v[92:95]
	v_mfma_f32_16x16x32_bf16 v[88:91], v[164:167], v[212:215], v[88:91]
	v_mfma_f32_16x16x32_bf16 v[76:79], v[148:151], v[220:223], v[76:79]
	v_mfma_f32_16x16x32_bf16 v[72:75], v[164:167], v[220:223], v[72:75]
	v_mfma_f32_16x16x32_bf16 v[124:127], v[160:163], v[194:197], v[124:127]
	v_mfma_f32_16x16x32_bf16 v[120:123], v[168:171], v[194:197], v[120:123]
	v_mfma_f32_16x16x32_bf16 v[108:111], v[160:163], v[208:211], v[108:111]
	v_mfma_f32_16x16x32_bf16 v[104:107], v[168:171], v[208:211], v[104:107]
	v_mfma_f32_16x16x32_bf16 v[92:95], v[160:163], v[216:219], v[92:95]
	v_mfma_f32_16x16x32_bf16 v[88:91], v[168:171], v[216:219], v[88:91]
	v_mfma_f32_16x16x32_bf16 v[76:79], v[160:163], v[224:227], v[76:79]
	v_mfma_f32_16x16x32_bf16 v[72:75], v[168:171], v[224:227], v[72:75]
	s_setprio 0
	s_setprio 1
	v_mfma_f32_16x16x32_bf16 v[116:119], v[172:175], v[190:193], v[116:119]
	v_mfma_f32_16x16x32_bf16 v[112:115], v[182:185], v[190:193], v[112:115]
	v_mfma_f32_16x16x32_bf16 v[100:103], v[172:175], v[198:201], v[100:103]
	v_mfma_f32_16x16x32_bf16 v[96:99], v[182:185], v[198:201], v[96:99]
	v_mfma_f32_16x16x32_bf16 v[84:87], v[172:175], v[212:215], v[84:87]
	v_mfma_f32_16x16x32_bf16 v[80:83], v[182:185], v[212:215], v[80:83]
	v_mfma_f32_16x16x32_bf16 v[68:71], v[172:175], v[220:223], v[68:71]
	v_mfma_f32_16x16x32_bf16 v[64:67], v[182:185], v[220:223], v[64:67]
	v_mfma_f32_16x16x32_bf16 v[116:119], v[176:179], v[194:197], v[116:119]
	v_mfma_f32_16x16x32_bf16 v[112:115], v[186:189], v[194:197], v[112:115]
	v_mfma_f32_16x16x32_bf16 v[100:103], v[176:179], v[208:211], v[100:103]
	v_mfma_f32_16x16x32_bf16 v[96:99], v[186:189], v[208:211], v[96:99]
	v_mfma_f32_16x16x32_bf16 v[84:87], v[176:179], v[216:219], v[84:87]
	v_mfma_f32_16x16x32_bf16 v[80:83], v[186:189], v[216:219], v[80:83]
	v_mfma_f32_16x16x32_bf16 v[68:71], v[176:179], v[224:227], v[68:71]
	v_mfma_f32_16x16x32_bf16 v[64:67], v[186:189], v[224:227], v[64:67]
	s_setprio 0
	s_barrier
	s_add_i32 s3, s85, s34
	v_lshl_add_u64 v[202:203], s[62:63], 0, v[134:135]
	s_mov_b32 m0, s3
	ds_read_b128 v[190:193], v157 offset:16384
	ds_read_b128 v[194:197], v157 offset:17408
	ds_read_b128 v[198:201], v157 offset:18432
	ds_read_b128 v[208:211], v157 offset:19456
	ds_read_b128 v[212:215], v157 offset:20480
	ds_read_b128 v[216:219], v157 offset:21504
	ds_read_b128 v[220:223], v157 offset:22528
	ds_read_b128 v[224:227], v157 offset:23552
	global_load_lds_dwordx4 v[202:203], off
	s_add_i32 m0, s3, 0x2000
	s_add_u32 s14, s62, 0x40000
	v_lshl_add_u64 v[228:229], s[62:63], 0, v[138:139]
	s_addc_u32 s15, s63, 0
	s_add_i32 s3, s86, s34
	global_load_lds_dwordx4 v[228:229], off
	v_lshl_add_u64 v[230:231], s[14:15], 0, v[134:135]
	s_mov_b32 m0, s3
	global_load_lds_dwordx4 v[230:231], off
	v_lshl_add_u64 v[230:231], s[14:15], 0, v[138:139]
	s_add_i32 m0, s3, 0x2000
	s_nop 0
	global_load_lds_dwordx4 v[230:231], off
	s_waitcnt vmcnt(6)
	s_waitcnt lgkmcnt(0)
	s_barrier
	s_setprio 1
	s_waitcnt lgkmcnt(0)
	v_mfma_f32_16x16x32_bf16 v[60:63], v[148:151], v[190:193], v[60:63]
	v_mfma_f32_16x16x32_bf16 v[56:59], v[164:167], v[190:193], v[56:59]
	v_mfma_f32_16x16x32_bf16 v[44:47], v[148:151], v[198:201], v[44:47]
	v_mfma_f32_16x16x32_bf16 v[40:43], v[164:167], v[198:201], v[40:43]
	v_mfma_f32_16x16x32_bf16 v[28:31], v[148:151], v[212:215], v[28:31]
	v_mfma_f32_16x16x32_bf16 v[24:27], v[164:167], v[212:215], v[24:27]
	v_mfma_f32_16x16x32_bf16 v[12:15], v[148:151], v[220:223], v[12:15]
	v_mfma_f32_16x16x32_bf16 v[8:11], v[164:167], v[220:223], v[8:11]
	v_mfma_f32_16x16x32_bf16 v[60:63], v[160:163], v[194:197], v[60:63]
	v_mfma_f32_16x16x32_bf16 v[56:59], v[168:171], v[194:197], v[56:59]
	v_mfma_f32_16x16x32_bf16 v[44:47], v[160:163], v[208:211], v[44:47]
	v_mfma_f32_16x16x32_bf16 v[40:43], v[168:171], v[208:211], v[40:43]
	v_mfma_f32_16x16x32_bf16 v[28:31], v[160:163], v[216:219], v[28:31]
	v_mfma_f32_16x16x32_bf16 v[24:27], v[168:171], v[216:219], v[24:27]
	v_mfma_f32_16x16x32_bf16 v[12:15], v[160:163], v[224:227], v[12:15]
	v_lshl_add_u64 v[230:231], s[64:65], 0, v[132:133]
	s_mov_b32 m0, s43
	s_nop 0
	global_load_lds_dwordx4 v[230:231], off
	v_mfma_f32_16x16x32_bf16 v[8:11], v[168:171], v[224:227], v[8:11]
	s_setprio 0
	s_setprio 1
	v_mfma_f32_16x16x32_bf16 v[52:55], v[172:175], v[190:193], v[52:55]
	v_mfma_f32_16x16x32_bf16 v[48:51], v[182:185], v[190:193], v[48:51]
	v_mfma_f32_16x16x32_bf16 v[36:39], v[172:175], v[198:201], v[36:39]
	v_mfma_f32_16x16x32_bf16 v[32:35], v[182:185], v[198:201], v[32:35]
	v_mfma_f32_16x16x32_bf16 v[20:23], v[172:175], v[212:215], v[20:23]
	v_mfma_f32_16x16x32_bf16 v[16:19], v[182:185], v[212:215], v[16:19]
	v_mfma_f32_16x16x32_bf16 v[4:7], v[172:175], v[220:223], v[4:7]
	v_mfma_f32_16x16x32_bf16 v[0:3], v[182:185], v[220:223], v[0:3]
	v_mfma_f32_16x16x32_bf16 v[52:55], v[176:179], v[194:197], v[52:55]
	v_mfma_f32_16x16x32_bf16 v[48:51], v[186:189], v[194:197], v[48:51]
	v_mfma_f32_16x16x32_bf16 v[36:39], v[176:179], v[208:211], v[36:39]
	v_mfma_f32_16x16x32_bf16 v[32:35], v[186:189], v[208:211], v[32:35]
	v_mfma_f32_16x16x32_bf16 v[20:23], v[176:179], v[216:219], v[20:23]
	v_mfma_f32_16x16x32_bf16 v[16:19], v[186:189], v[216:219], v[16:19]
	v_mfma_f32_16x16x32_bf16 v[4:7], v[176:179], v[224:227], v[4:7]
	v_lshl_add_u64 v[232:233], s[64:65], 0, v[136:137]
	s_mov_b32 m0, s59
	s_nop 0
	global_load_lds_dwordx4 v[232:233], off
	v_mfma_f32_16x16x32_bf16 v[0:3], v[186:189], v[224:227], v[0:3]
	s_setprio 0
	s_barrier
; #define PG8_STAGE(bufoff, gbase, voff) do { _Pragma("unroll") for (int _i = 0; _i < 2; ++_i) \
;         __builtin_amdgcn_global_load_lds((const unsigned*)((const char*)(gbase) + (voff)[_i]), (PG8_LAS unsigned*)(lds + (bufoff) + ldsw + _i * 8192), 16, 0, 0); } while (0)
; #define PG8_LDA(dst, b, h) do { _Pragma("unroll") for (int m = 0; m < 4; ++m) _Pragma("unroll") for (int k = 0; k < 2; ++k) dst[m][k] = *(const PG8_LAS bf16x8*)(lds + PG8_SA(b, h) + aoff + m * 2048 + k * 1024); } while (0)
; #define PG8_LDB(dst, b, h) do { _Pragma("unroll") for (int n = 0; n < 2; ++n) _Pragma("unroll") for (int k = 0; k < 2; ++k) dst[n][k] = *(const PG8_LAS bf16x8*)(lds + PG8_SB(b, h) + boff + n * 2048 + k * 1024); } while (0)
; #define PG8_MMA(ai, bj, At, Bt) do { __builtin_amdgcn_s_setprio(1); _Pragma("unroll") for (int m = 0; m < 4; ++m) _Pragma("unroll") for (int n = 0; n < 2; ++n) _Pragma("unroll") for (int k = 0; k < 2; ++k) \
;         acc[ai][bj][m][n] = __builtin_amdgcn_mfma_f32_16x16x32_bf16(Bt[n][k], At[m][k], acc[ai][bj][m][n], 0, 0, 0); __builtin_amdgcn_s_setprio(0); } while (0)
; #define PG8_WAIT_V(n) asm volatile("s_waitcnt vmcnt(" #n ")" ::: "memory")
; #define PG8_WAIT_L(n) asm volatile("s_waitcnt lgkmcnt(" #n ")" ::: "memory")
; #define PG8_BAR __builtin_amdgcn_s_barrier()
; #define PG8_SCHED __builtin_amdgcn_sched_barrier(0)
; template <class Epi, class Sched, bool ALIGN_EPI = false, bool SP2 = false>
; __device__ __forceinline__ void gemm_phase(PG8_LAS unsigned char* lds, const Gemm g, const Sched& S, const Epi& E) {
;     ...
;             PG8_LDB(B0, 1, 0); PG8_LDB(B1, 1, 1); PG8_SCHED; PG8_LDA(At, 1, 0); PG8_STAGE(PG8_SA(0, 1), a2 + hstep, voffA);
;             PG8_WAIT_V(8); PG8_WAIT_L(0); PG8_BAR; PG8_MMA(0, 0, At, B0); PG8_MMA(0, 1, At, B1); PG8_BAR; PG8_SCHED;
	s_add_i32 s3, 0, 0x18000
	v_add_u32_e32 v159, s3, v131
	s_add_i32 s33, 0, 0x1c000
	ds_read_b128 v[148:151], v159
	ds_read_b128 v[160:163], v159 offset:1024
	ds_read_b128 v[164:167], v159 offset:2048
	ds_read_b128 v[168:171], v159 offset:3072
	v_add_u32_e32 v159, s33, v131
	ds_read_b128 v[172:175], v159
	ds_read_b128 v[176:179], v159 offset:1024
	ds_read_b128 v[182:185], v159 offset:2048
	ds_read_b128 v[186:189], v159 offset:3072
	s_add_u32 s14, s64, 0x40000
	s_addc_u32 s15, s65, 0
	s_mov_b32 m0, s66
	v_lshl_add_u64 v[234:235], s[14:15], 0, v[132:133]
	ds_read_b128 v[190:193], v157 offset:32768
	ds_read_b128 v[194:197], v157 offset:33792
	ds_read_b128 v[198:201], v157 offset:34816
	ds_read_b128 v[208:211], v157 offset:35840
	ds_read_b128 v[212:215], v157 offset:36864
	ds_read_b128 v[216:219], v157 offset:37888
	ds_read_b128 v[220:223], v157 offset:38912
	ds_read_b128 v[224:227], v157 offset:39936
	global_load_lds_dwordx4 v[234:235], off
	v_lshl_add_u64 v[234:235], s[14:15], 0, v[136:137]
	s_mov_b32 m0, s67
	s_nop 0
	global_load_lds_dwordx4 v[234:235], off
	s_waitcnt vmcnt(8)
	s_waitcnt lgkmcnt(0)
	s_barrier
	s_setprio 1
	s_waitcnt lgkmcnt(0)
	v_mfma_f32_16x16x32_bf16 v[124:127], v[148:151], v[190:193], v[124:127]
	v_mfma_f32_16x16x32_bf16 v[120:123], v[164:167], v[190:193], v[120:123]
	v_mfma_f32_16x16x32_bf16 v[108:111], v[148:151], v[198:201], v[108:111]
	v_mfma_f32_16x16x32_bf16 v[104:107], v[164:167], v[198:201], v[104:107]
	v_mfma_f32_16x16x32_bf16 v[92:95], v[148:151], v[212:215], v[92:95]
	v_mfma_f32_16x16x32_bf16 v[88:91], v[164:167], v[212:215], v[88:91]
	v_mfma_f32_16x16x32_bf16 v[76:79], v[148:151], v[220:223], v[76:79]
	v_mfma_f32_16x16x32_bf16 v[72:75], v[164:167], v[220:223], v[72:75]
	v_mfma_f32_16x16x32_bf16 v[124:127], v[160:163], v[194:197], v[124:127]
	v_mfma_f32_16x16x32_bf16 v[120:123], v[168:171], v[194:197], v[120:123]
	v_mfma_f32_16x16x32_bf16 v[108:111], v[160:163], v[208:211], v[108:111]
	v_mfma_f32_16x16x32_bf16 v[104:107], v[168:171], v[208:211], v[104:107]
	v_mfma_f32_16x16x32_bf16 v[92:95], v[160:163], v[216:219], v[92:95]
	v_mfma_f32_16x16x32_bf16 v[88:91], v[168:171], v[216:219], v[88:91]
	v_mfma_f32_16x16x32_bf16 v[76:79], v[160:163], v[224:227], v[76:79]
	v_mfma_f32_16x16x32_bf16 v[72:75], v[168:171], v[224:227], v[72:75]
	s_setprio 0
	s_setprio 1
	v_mfma_f32_16x16x32_bf16 v[116:119], v[172:175], v[190:193], v[116:119]
	v_mfma_f32_16x16x32_bf16 v[112:115], v[182:185], v[190:193], v[112:115]
	v_mfma_f32_16x16x32_bf16 v[100:103], v[172:175], v[198:201], v[100:103]
	v_mfma_f32_16x16x32_bf16 v[96:99], v[182:185], v[198:201], v[96:99]
	v_mfma_f32_16x16x32_bf16 v[84:87], v[172:175], v[212:215], v[84:87]
	v_mfma_f32_16x16x32_bf16 v[80:83], v[182:185], v[212:215], v[80:83]
	v_mfma_f32_16x16x32_bf16 v[68:71], v[172:175], v[220:223], v[68:71]
	v_mfma_f32_16x16x32_bf16 v[64:67], v[182:185], v[220:223], v[64:67]
	v_mfma_f32_16x16x32_bf16 v[116:119], v[176:179], v[194:197], v[116:119]
	v_mfma_f32_16x16x32_bf16 v[112:115], v[186:189], v[194:197], v[112:115]
	v_mfma_f32_16x16x32_bf16 v[100:103], v[176:179], v[208:211], v[100:103]
	v_mfma_f32_16x16x32_bf16 v[96:99], v[186:189], v[208:211], v[96:99]
	v_mfma_f32_16x16x32_bf16 v[84:87], v[176:179], v[216:219], v[84:87]
	v_mfma_f32_16x16x32_bf16 v[80:83], v[186:189], v[216:219], v[80:83]
	v_mfma_f32_16x16x32_bf16 v[68:71], v[176:179], v[224:227], v[68:71]
	v_mfma_f32_16x16x32_bf16 v[64:67], v[186:189], v[224:227], v[64:67]
	s_setprio 0
	s_barrier
; #define PG8_STAGE(bufoff, gbase, voff) do { _Pragma("unroll") for (int _i = 0; _i < 2; ++_i) \
;         __builtin_amdgcn_global_load_lds((const unsigned*)((const char*)(gbase) + (voff)[_i]), (PG8_LAS unsigned*)(lds + (bufoff) + ldsw + _i * 8192), 16, 0, 0); } while (0)
; #define PG8_LDA(dst, b, h) do { _Pragma("unroll") for (int m = 0; m < 4; ++m) _Pragma("unroll") for (int k = 0; k < 2; ++k) dst[m][k] = *(const PG8_LAS bf16x8*)(lds + PG8_SA(b, h) + aoff + m * 2048 + k * 1024); } while (0)
; #define PG8_MMA(ai, bj, At, Bt) do { __builtin_amdgcn_s_setprio(1); _Pragma("unroll") for (int m = 0; m < 4; ++m) _Pragma("unroll") for (int n = 0; n < 2; ++n) _Pragma("unroll") for (int k = 0; k < 2; ++k) \
;         acc[ai][bj][m][n] = __builtin_amdgcn_mfma_f32_16x16x32_bf16(Bt[n][k], At[m][k], acc[ai][bj][m][n], 0, 0, 0); __builtin_amdgcn_s_setprio(0); } while (0)
; #define PG8_WAIT_V(n) asm volatile("s_waitcnt vmcnt(" #n ")" ::: "memory")
; #define PG8_WAIT_L(n) asm volatile("s_waitcnt lgkmcnt(" #n ")" ::: "memory")
; #define PG8_BAR __builtin_amdgcn_s_barrier()
; #define PG8_SCHED __builtin_amdgcn_sched_barrier(0)
; template <class Epi, class Sched, bool ALIGN_EPI = false, bool SP2 = false>
; __device__ __forceinline__ void gemm_phase(PG8_LAS unsigned char* lds, const Gemm g, const Sched& S, const Epi& E) {
;     ...
;             PG8_LDA(At, 1, 1); PG8_STAGE(PG8_SB(1, 0), b3, voffB); PG8_STAGE(PG8_SB(1, 1), b3 + hstep, voffB); PG8_STAGE(PG8_SA(1, 0), a3, voffA);
;             PG8_WAIT_V(8); PG8_WAIT_L(0); PG8_BAR; PG8_MMA(1, 0, At, B0); PG8_MMA(1, 1, At, B1); PG8_BAR; PG8_SCHED;
;     ...
;         }
;         if constexpr (ALIGN_EPI) { if (wr == 0) PG8_BAR; }
;         if constexpr (!Epi::AFTER_DRAIN) { E(acc, cur, wr, wc, fr, fq); S.done(cur); }
;         if (!has_next) break;
	s_add_i32 s3, s3, s34
	v_lshl_add_u64 v[202:203], v[202:203], 0, s[38:39]
	s_mov_b32 m0, s3
	ds_read_b128 v[190:193], v157 offset:49152
	ds_read_b128 v[194:197], v157 offset:50176
	ds_read_b128 v[198:201], v157 offset:51200
	ds_read_b128 v[208:211], v157 offset:52224
	ds_read_b128 v[212:215], v157 offset:53248
	ds_read_b128 v[216:219], v157 offset:54272
	ds_read_b128 v[220:223], v157 offset:55296
	ds_read_b128 v[224:227], v157 offset:56320
	global_load_lds_dwordx4 v[202:203], off
	s_add_i32 m0, s3, 0x2000
	s_add_u32 s14, s62, 0x40080
	v_lshl_add_u64 v[202:203], v[228:229], 0, s[38:39]
	s_addc_u32 s15, s63, 0
	s_add_i32 s3, s33, s34
	global_load_lds_dwordx4 v[202:203], off
	v_lshl_add_u64 v[202:203], s[14:15], 0, v[134:135]
	s_mov_b32 m0, s3
	s_nop 0
	global_load_lds_dwordx4 v[202:203], off
	v_lshl_add_u64 v[202:203], s[14:15], 0, v[138:139]
	s_add_i32 m0, s3, 0x2000
	s_nop 0
	global_load_lds_dwordx4 v[202:203], off
	s_waitcnt vmcnt(6)
	s_waitcnt lgkmcnt(0)
	s_barrier
	s_setprio 1
	s_waitcnt lgkmcnt(0)
	v_mfma_f32_16x16x32_bf16 v[60:63], v[148:151], v[190:193], v[60:63]
	v_mfma_f32_16x16x32_bf16 v[56:59], v[164:167], v[190:193], v[56:59]
	v_mfma_f32_16x16x32_bf16 v[44:47], v[148:151], v[198:201], v[44:47]
	v_mfma_f32_16x16x32_bf16 v[40:43], v[164:167], v[198:201], v[40:43]
	v_mfma_f32_16x16x32_bf16 v[28:31], v[148:151], v[212:215], v[28:31]
	v_mfma_f32_16x16x32_bf16 v[24:27], v[164:167], v[212:215], v[24:27]
	v_mfma_f32_16x16x32_bf16 v[12:15], v[148:151], v[220:223], v[12:15]
	v_mfma_f32_16x16x32_bf16 v[8:11], v[164:167], v[220:223], v[8:11]
	v_mfma_f32_16x16x32_bf16 v[60:63], v[160:163], v[194:197], v[60:63]
	v_mfma_f32_16x16x32_bf16 v[56:59], v[168:171], v[194:197], v[56:59]
	v_mfma_f32_16x16x32_bf16 v[44:47], v[160:163], v[208:211], v[44:47]
	v_mfma_f32_16x16x32_bf16 v[40:43], v[168:171], v[208:211], v[40:43]
	v_mfma_f32_16x16x32_bf16 v[28:31], v[160:163], v[216:219], v[28:31]
	v_mfma_f32_16x16x32_bf16 v[24:27], v[168:171], v[216:219], v[24:27]
	v_mfma_f32_16x16x32_bf16 v[12:15], v[160:163], v[224:227], v[12:15]
	v_lshl_add_u64 v[202:203], v[230:231], 0, s[38:39]
	s_mov_b32 m0, s75
	s_nop 0
	global_load_lds_dwordx4 v[202:203], off
	v_mfma_f32_16x16x32_bf16 v[8:11], v[168:171], v[224:227], v[8:11]
	s_setprio 0
	s_setprio 1
	v_mfma_f32_16x16x32_bf16 v[52:55], v[172:175], v[190:193], v[52:55]
	v_mfma_f32_16x16x32_bf16 v[48:51], v[182:185], v[190:193], v[48:51]
	v_mfma_f32_16x16x32_bf16 v[36:39], v[172:175], v[198:201], v[36:39]
	v_mfma_f32_16x16x32_bf16 v[32:35], v[182:185], v[198:201], v[32:35]
	v_mfma_f32_16x16x32_bf16 v[20:23], v[172:175], v[212:215], v[20:23]
	v_mfma_f32_16x16x32_bf16 v[16:19], v[182:185], v[212:215], v[16:19]
	v_mfma_f32_16x16x32_bf16 v[4:7], v[172:175], v[220:223], v[4:7]
	v_mfma_f32_16x16x32_bf16 v[0:3], v[182:185], v[220:223], v[0:3]
	v_mfma_f32_16x16x32_bf16 v[52:55], v[176:179], v[194:197], v[52:55]
	v_mfma_f32_16x16x32_bf16 v[48:51], v[186:189], v[194:197], v[48:51]
	v_mfma_f32_16x16x32_bf16 v[36:39], v[176:179], v[208:211], v[36:39]
	v_mfma_f32_16x16x32_bf16 v[32:35], v[186:189], v[208:211], v[32:35]
	v_mfma_f32_16x16x32_bf16 v[20:23], v[176:179], v[216:219], v[20:23]
	v_mfma_f32_16x16x32_bf16 v[16:19], v[186:189], v[216:219], v[16:19]
	v_mfma_f32_16x16x32_bf16 v[4:7], v[176:179], v[224:227], v[4:7]
	v_lshl_add_u64 v[202:203], v[232:233], 0, s[38:39]
	s_mov_b32 m0, s84
	s_nop 0
	global_load_lds_dwordx4 v[202:203], off
	v_mfma_f32_16x16x32_bf16 v[0:3], v[186:189], v[224:227], v[0:3]
	s_setprio 0
	s_barrier
	s_add_i32 s92, s92, 2
	s_add_u32 s60, s60, 0x100
	s_addc_u32 s61, s61, 0
	s_add_u32 s90, s90, 0x100
	s_addc_u32 s91, s91, 0
	s_cmp_gt_u32 s92, 13
	s_cbranch_scc0 .LBB0_650
	s_and_b64 vcc, exec, s[44:45]
	s_cbranch_vccz .LBB0_653
	s_barrier

; #define PG8_STAGE(bufoff, gbase, voff) do { _Pragma("unroll") for (int _i = 0; _i < 2; ++_i) \
;         __builtin_amdgcn_global_load_lds((const unsigned*)((const char*)(gbase) + (voff)[_i]), (PG8_LAS unsigned*)(lds + (bufoff) + ldsw + _i * 8192), 16, 0, 0); } while (0)
; #define PG8_LDA(dst, b, h) do { _Pragma("unroll") for (int m = 0; m < 4; ++m) _Pragma("unroll") for (int k = 0; k < 2; ++k) dst[m][k] = *(const PG8_LAS bf16x8*)(lds + PG8_SA(b, h) + aoff + m * 2048 + k * 1024); } while (0)
; #define PG8_LDB(dst, b, h) do { _Pragma("unroll") for (int n = 0; n < 2; ++n) _Pragma("unroll") for (int k = 0; k < 2; ++k) dst[n][k] = *(const PG8_LAS bf16x8*)(lds + PG8_SB(b, h) + boff + n * 2048 + k * 1024); } while (0)
; #define PG8_MMA(ai, bj, At, Bt) do { __builtin_amdgcn_s_setprio(1); _Pragma("unroll") for (int m = 0; m < 4; ++m) _Pragma("unroll") for (int n = 0; n < 2; ++n) _Pragma("unroll") for (int k = 0; k < 2; ++k) \
;         acc[ai][bj][m][n] = __builtin_amdgcn_mfma_f32_16x16x32_bf16(Bt[n][k], At[m][k], acc[ai][bj][m][n], 0, 0, 0); __builtin_amdgcn_s_setprio(0); } while (0)
; #define PG8_BAR __builtin_amdgcn_s_barrier()
; template <class Epi, class Sched, bool ALIGN_EPI = false, bool SP2 = false>
; __device__ __forceinline__ void gemm_phase(PG8_LAS unsigned char* lds, const Gemm g, const Sched& S, const Epi& E) {
;     ...
;         const bool has_next = S.next(ui + 1, nxt);
;         const char* nA = has_next ? (const char*)g.A + (size_t)nxt.pm * tstep : cA; const char* nB = has_next ? (const char*)g.Bt + (size_t)nxt.pn * tstep : cB;
;         for (int t = 0; t < nt; t += 2) {
;             const bool last = (t == nt - 2);
;             const char* a1 = cA + (size_t)(t + 1) * kstep;
;             const char* a2 = last ? nA : cA + (size_t)(t + 2) * kstep; const char* b2 = last ? nB : cB + (size_t)(t + 2) * kstep;
;             const char* a3 = a2 + kstep; const char* b3 = b2 + kstep;
;             if (last && has_next) S.a_ready(nxt);
;             if constexpr (SP2) {
;             PG8_LDB(B0, 0, 0); PG8_LDB(B1, 0, 1); PG8_SCHED; PG8_LDA(At, 0, 0); PG8_STAGE(PG8_SA(1, 1), a1 + hstep, voffA);
;             PG8_WAIT_V(8); PG8_WAIT_L(0); PG8_BAR; PG8_MMA(0, 0, At, B0); PG8_MMA(0, 1, At, B1); PG8_BAR; PG8_SCHED;
;             PG8_LDA(At, 0, 1); PG8_STAGE(PG8_SB(0, 0), b2, voffB); PG8_STAGE(PG8_SB(0, 1), b2 + hstep, voffB); PG8_STAGE(PG8_SA(0, 0), a2, voffA);
.LBB0_737:
	s_ashr_i32 s51, s50, 31
	s_lshl_b64 s[14:15], s[50:51], 19
	s_add_u32 s52, s22, s14
	s_addc_u32 s53, s23, s15
	s_and_b64 s[14:15], s[8:9], exec
	s_cselect_b32 s51, s53, s57
	s_cselect_b32 s82, s52, s56
	s_ashr_i32 s49, s48, 31
	s_lshl_b64 s[14:15], s[48:49], 19
	v_readlane_b32 s3, v250, 15
	s_add_u32 s54, s3, s14
	v_readlane_b32 s3, v250, 16
	s_addc_u32 s55, s3, s15
	s_and_b64 s[14:15], s[8:9], exec
	s_cselect_b32 s49, s55, s59
	s_cselect_b32 s83, s54, s58
	s_add_u32 s56, s56, 0x40080
	s_addc_u32 s57, s57, 0
	s_add_u32 s84, s58, 0x100
	s_addc_u32 s85, s59, 0
	s_mov_b32 s86, -2
	s_waitcnt vmcnt(0)
	ds_read_b128 v[148:151], v155
	ds_read_b128 v[160:163], v155 offset:1024
	ds_read_b128 v[164:167], v155 offset:2048
	ds_read_b128 v[168:171], v155 offset:3072
	ds_read_b128 v[172:175], v156
	ds_read_b128 v[176:179], v156 offset:1024
	ds_read_b128 v[182:185], v156 offset:2048
	ds_read_b128 v[186:189], v156 offset:3072
	s_add_u32 s3, s56, 0xfffc0080
	s_addc_u32 s14, s57, -1
	s_cmp_eq_u32 s86, 12
	s_cselect_b32 s61, s51, s14
	s_cselect_b32 s60, s82, s3
	s_cselect_b32 s59, s49, s85
	s_cselect_b32 s58, s83, s84
	v_lshl_add_u64 v[202:203], s[56:57], 0, v[140:141]
	s_add_i32 m0, s43, 0xc000
	ds_read_b128 v[190:193], v157
	ds_read_b128 v[194:197], v157 offset:1024
	ds_read_b128 v[198:201], v157 offset:2048
	ds_read_b128 v[208:211], v157 offset:3072
	ds_read_b128 v[212:215], v157 offset:4096
	ds_read_b128 v[216:219], v157 offset:5120
	ds_read_b128 v[220:223], v157 offset:6144
	ds_read_b128 v[224:227], v157 offset:7168
	global_load_lds_dwordx4 v[202:203], off
	v_lshl_add_u64 v[202:203], s[56:57], 0, v[142:143]
	s_add_i32 m0, s43, 0xe000
	s_nop 0
	global_load_lds_dwordx4 v[202:203], off
	s_waitcnt vmcnt(8)
	s_waitcnt lgkmcnt(0)
	s_barrier
	s_setprio 1
	s_waitcnt lgkmcnt(0)
	v_mfma_f32_16x16x32_bf16 v[124:127], v[148:151], v[190:193], 0
	v_mfma_f32_16x16x32_bf16 v[120:123], v[164:167], v[190:193], 0
	v_mfma_f32_16x16x32_bf16 v[108:111], v[148:151], v[198:201], 0
	v_mfma_f32_16x16x32_bf16 v[104:107], v[164:167], v[198:201], 0
	v_mfma_f32_16x16x32_bf16 v[92:95], v[148:151], v[212:215], 0
	v_mfma_f32_16x16x32_bf16 v[88:91], v[164:167], v[212:215], 0
	v_mfma_f32_16x16x32_bf16 v[76:79], v[148:151], v[220:223], 0
	v_mfma_f32_16x16x32_bf16 v[72:75], v[164:167], v[220:223], 0
	v_mfma_f32_16x16x32_bf16 v[124:127], v[160:163], v[194:197], v[124:127]
	v_mfma_f32_16x16x32_bf16 v[120:123], v[168:171], v[194:197], v[120:123]
	v_mfma_f32_16x16x32_bf16 v[108:111], v[160:163], v[208:211], v[108:111]
	v_mfma_f32_16x16x32_bf16 v[104:107], v[168:171], v[208:211], v[104:107]
	v_mfma_f32_16x16x32_bf16 v[92:95], v[160:163], v[216:219], v[92:95]
	v_mfma_f32_16x16x32_bf16 v[88:91], v[168:171], v[216:219], v[88:91]
	v_mfma_f32_16x16x32_bf16 v[76:79], v[160:163], v[224:227], v[76:79]
	v_mfma_f32_16x16x32_bf16 v[72:75], v[168:171], v[224:227], v[72:75]
	s_setprio 0
	s_setprio 1
	v_mfma_f32_16x16x32_bf16 v[116:119], v[172:175], v[190:193], 0
	v_mfma_f32_16x16x32_bf16 v[112:115], v[182:185], v[190:193], 0
	v_mfma_f32_16x16x32_bf16 v[100:103], v[172:175], v[198:201], 0
	v_mfma_f32_16x16x32_bf16 v[96:99], v[182:185], v[198:201], 0
	v_mfma_f32_16x16x32_bf16 v[84:87], v[172:175], v[212:215], 0
	v_mfma_f32_16x16x32_bf16 v[80:83], v[182:185], v[212:215], 0
	v_mfma_f32_16x16x32_bf16 v[68:71], v[172:175], v[220:223], 0
	v_mfma_f32_16x16x32_bf16 v[64:67], v[182:185], v[220:223], 0
	v_mfma_f32_16x16x32_bf16 v[116:119], v[176:179], v[194:197], v[116:119]
	v_mfma_f32_16x16x32_bf16 v[112:115], v[186:189], v[194:197], v[112:115]
	v_mfma_f32_16x16x32_bf16 v[100:103], v[176:179], v[208:211], v[100:103]
	v_mfma_f32_16x16x32_bf16 v[96:99], v[186:189], v[208:211], v[96:99]
	v_mfma_f32_16x16x32_bf16 v[84:87], v[176:179], v[216:219], v[84:87]
	v_mfma_f32_16x16x32_bf16 v[80:83], v[186:189], v[216:219], v[80:83]
	v_mfma_f32_16x16x32_bf16 v[68:71], v[176:179], v[224:227], v[68:71]
	v_mfma_f32_16x16x32_bf16 v[64:67], v[186:189], v[224:227], v[64:67]
	s_setprio 0
	s_barrier
	s_add_i32 s3, s74, s34
	v_lshl_add_u64 v[202:203], s[58:59], 0, v[136:137]
	s_mov_b32 m0, s3
	ds_read_b128 v[190:193], v157 offset:16384
	ds_read_b128 v[194:197], v157 offset:17408
	ds_read_b128 v[198:201], v157 offset:18432
	ds_read_b128 v[208:211], v157 offset:19456
	ds_read_b128 v[212:215], v157 offset:20480
	ds_read_b128 v[216:219], v157 offset:21504
	ds_read_b128 v[220:223], v157 offset:22528
	ds_read_b128 v[224:227], v157 offset:23552
	global_load_lds_dwordx4 v[202:203], off
	s_add_i32 m0, s3, 0x2000
	s_add_u32 s14, s58, 0x40000
	v_lshl_add_u64 v[228:229], s[58:59], 0, v[132:133]
	s_addc_u32 s15, s59, 0
	s_add_i32 s3, s75, s34
	global_load_lds_dwordx4 v[228:229], off
	v_lshl_add_u64 v[230:231], s[14:15], 0, v[136:137]
	s_mov_b32 m0, s3
	global_load_lds_dwordx4 v[230:231], off
	v_lshl_add_u64 v[230:231], s[14:15], 0, v[132:133]
	s_add_i32 m0, s3, 0x2000
	s_nop 0
	global_load_lds_dwordx4 v[230:231], off
	s_waitcnt vmcnt(6)
	s_waitcnt lgkmcnt(0)
	s_barrier
; #define PG8_STAGE(bufoff, gbase, voff) do { _Pragma("unroll") for (int _i = 0; _i < 2; ++_i) \
;         __builtin_amdgcn_global_load_lds((const unsigned*)((const char*)(gbase) + (voff)[_i]), (PG8_LAS unsigned*)(lds + (bufoff) + ldsw + _i * 8192), 16, 0, 0); } while (0)
; #define PG8_LDA(dst, b, h) do { _Pragma("unroll") for (int m = 0; m < 4; ++m) _Pragma("unroll") for (int k = 0; k < 2; ++k) dst[m][k] = *(const PG8_LAS bf16x8*)(lds + PG8_SA(b, h) + aoff + m * 2048 + k * 1024); } while (0)
; #define PG8_LDB(dst, b, h) do { _Pragma("unroll") for (int n = 0; n < 2; ++n) _Pragma("unroll") for (int k = 0; k < 2; ++k) dst[n][k] = *(const PG8_LAS bf16x8*)(lds + PG8_SB(b, h) + boff + n * 2048 + k * 1024); } while (0)
; #define PG8_MMA(ai, bj, At, Bt) do { __builtin_amdgcn_s_setprio(1); _Pragma("unroll") for (int m = 0; m < 4; ++m) _Pragma("unroll") for (int n = 0; n < 2; ++n) _Pragma("unroll") for (int k = 0; k < 2; ++k) \
;         acc[ai][bj][m][n] = __builtin_amdgcn_mfma_f32_16x16x32_bf16(Bt[n][k], At[m][k], acc[ai][bj][m][n], 0, 0, 0); __builtin_amdgcn_s_setprio(0); } while (0)
; #define PG8_WAIT_V(n) asm volatile("s_waitcnt vmcnt(" #n ")" ::: "memory")
; #define PG8_WAIT_L(n) asm volatile("s_waitcnt lgkmcnt(" #n ")" ::: "memory")
; #define PG8_BAR __builtin_amdgcn_s_barrier()
; #define PG8_SCHED __builtin_amdgcn_sched_barrier(0)
; template <class Epi, class Sched, bool ALIGN_EPI = false, bool SP2 = false>
; __device__ __forceinline__ void gemm_phase(PG8_LAS unsigned char* lds, const Gemm g, const Sched& S, const Epi& E) {
;     ...
;             PG8_LDA(At, 0, 1); PG8_STAGE(PG8_SB(0, 0), b2, voffB); PG8_STAGE(PG8_SB(0, 1), b2 + hstep, voffB); PG8_STAGE(PG8_SA(0, 0), a2, voffA);
;             PG8_WAIT_V(8); PG8_WAIT_L(0); PG8_BAR; PG8_MMA(1, 0, At, B0); PG8_MMA(1, 1, At, B1); PG8_BAR; PG8_SCHED;
;             PG8_LDB(B0, 1, 0); PG8_LDB(B1, 1, 1); PG8_SCHED; PG8_LDA(At, 1, 0); PG8_STAGE(PG8_SA(0, 1), a2 + hstep, voffA);
;             PG8_WAIT_V(8); PG8_WAIT_L(0); PG8_BAR; PG8_MMA(0, 0, At, B0); PG8_MMA(0, 1, At, B1); PG8_BAR; PG8_SCHED;
	s_setprio 1
	s_waitcnt lgkmcnt(0)
	v_mfma_f32_16x16x32_bf16 v[60:63], v[148:151], v[190:193], 0
	v_mfma_f32_16x16x32_bf16 v[56:59], v[164:167], v[190:193], 0
	v_mfma_f32_16x16x32_bf16 v[44:47], v[148:151], v[198:201], 0
	v_mfma_f32_16x16x32_bf16 v[40:43], v[164:167], v[198:201], 0
	v_mfma_f32_16x16x32_bf16 v[28:31], v[148:151], v[212:215], 0
	v_mfma_f32_16x16x32_bf16 v[24:27], v[164:167], v[212:215], 0
	v_mfma_f32_16x16x32_bf16 v[12:15], v[148:151], v[220:223], 0
	v_mfma_f32_16x16x32_bf16 v[8:11], v[164:167], v[220:223], 0
	v_mfma_f32_16x16x32_bf16 v[60:63], v[160:163], v[194:197], v[60:63]
	v_mfma_f32_16x16x32_bf16 v[56:59], v[168:171], v[194:197], v[56:59]
	v_mfma_f32_16x16x32_bf16 v[44:47], v[160:163], v[208:211], v[44:47]
	v_mfma_f32_16x16x32_bf16 v[40:43], v[168:171], v[208:211], v[40:43]
	v_mfma_f32_16x16x32_bf16 v[28:31], v[160:163], v[216:219], v[28:31]
	v_mfma_f32_16x16x32_bf16 v[24:27], v[168:171], v[216:219], v[24:27]
	v_mfma_f32_16x16x32_bf16 v[12:15], v[160:163], v[224:227], v[12:15]
	v_lshl_add_u64 v[230:231], s[60:61], 0, v[138:139]
	s_mov_b32 m0, s43
	s_nop 0
	global_load_lds_dwordx4 v[230:231], off
	v_mfma_f32_16x16x32_bf16 v[8:11], v[168:171], v[224:227], v[8:11]
	s_setprio 0
	s_setprio 1
	v_mfma_f32_16x16x32_bf16 v[52:55], v[172:175], v[190:193], 0
	v_mfma_f32_16x16x32_bf16 v[48:51], v[182:185], v[190:193], 0
	v_mfma_f32_16x16x32_bf16 v[36:39], v[172:175], v[198:201], 0
	v_mfma_f32_16x16x32_bf16 v[32:35], v[182:185], v[198:201], 0
	v_mfma_f32_16x16x32_bf16 v[20:23], v[172:175], v[212:215], 0
	v_mfma_f32_16x16x32_bf16 v[16:19], v[182:185], v[212:215], 0
	v_mfma_f32_16x16x32_bf16 v[4:7], v[172:175], v[220:223], 0
	v_mfma_f32_16x16x32_bf16 v[0:3], v[182:185], v[220:223], 0
	v_mfma_f32_16x16x32_bf16 v[52:55], v[176:179], v[194:197], v[52:55]
	v_mfma_f32_16x16x32_bf16 v[48:51], v[186:189], v[194:197], v[48:51]
	v_mfma_f32_16x16x32_bf16 v[36:39], v[176:179], v[208:211], v[36:39]
	v_mfma_f32_16x16x32_bf16 v[32:35], v[186:189], v[208:211], v[32:35]
	v_mfma_f32_16x16x32_bf16 v[20:23], v[176:179], v[216:219], v[20:23]
	v_mfma_f32_16x16x32_bf16 v[16:19], v[186:189], v[216:219], v[16:19]
	v_mfma_f32_16x16x32_bf16 v[4:7], v[176:179], v[224:227], v[4:7]
	v_lshl_add_u64 v[232:233], s[60:61], 0, v[134:135]
	s_mov_b32 m0, s62
	s_nop 0
	global_load_lds_dwordx4 v[232:233], off
	v_mfma_f32_16x16x32_bf16 v[0:3], v[186:189], v[224:227], v[0:3]
	s_setprio 0
	s_barrier
	s_add_i32 s3, 0, 0x18000
	v_add_u32_e32 v159, s3, v131
	s_add_i32 s33, 0, 0x1c000
	ds_read_b128 v[148:151], v159
	ds_read_b128 v[160:163], v159 offset:1024
	ds_read_b128 v[164:167], v159 offset:2048
	ds_read_b128 v[168:171], v159 offset:3072
	v_add_u32_e32 v159, s33, v131
	ds_read_b128 v[172:175], v159
	ds_read_b128 v[176:179], v159 offset:1024
	ds_read_b128 v[182:185], v159 offset:2048
	ds_read_b128 v[186:189], v159 offset:3072
	s_add_u32 s14, s60, 0x40000
	s_addc_u32 s15, s61, 0
	s_mov_b32 m0, s63
	v_lshl_add_u64 v[234:235], s[14:15], 0, v[138:139]
	ds_read_b128 v[190:193], v157 offset:32768
	ds_read_b128 v[194:197], v157 offset:33792
	ds_read_b128 v[198:201], v157 offset:34816
	ds_read_b128 v[208:211], v157 offset:35840
	ds_read_b128 v[212:215], v157 offset:36864
	ds_read_b128 v[216:219], v157 offset:37888
	ds_read_b128 v[220:223], v157 offset:38912
	ds_read_b128 v[224:227], v157 offset:39936
	global_load_lds_dwordx4 v[234:235], off
	v_lshl_add_u64 v[234:235], s[14:15], 0, v[134:135]
	s_mov_b32 m0, s64
	s_nop 0
	global_load_lds_dwordx4 v[234:235], off
	s_waitcnt vmcnt(8)
	s_waitcnt lgkmcnt(0)
	s_barrier
	s_setprio 1
	s_waitcnt lgkmcnt(0)
	v_mfma_f32_16x16x32_bf16 v[124:127], v[148:151], v[190:193], v[124:127]
	v_mfma_f32_16x16x32_bf16 v[120:123], v[164:167], v[190:193], v[120:123]
	v_mfma_f32_16x16x32_bf16 v[108:111], v[148:151], v[198:201], v[108:111]
	v_mfma_f32_16x16x32_bf16 v[104:107], v[164:167], v[198:201], v[104:107]
	v_mfma_f32_16x16x32_bf16 v[92:95], v[148:151], v[212:215], v[92:95]
	v_mfma_f32_16x16x32_bf16 v[88:91], v[164:167], v[212:215], v[88:91]
	v_mfma_f32_16x16x32_bf16 v[76:79], v[148:151], v[220:223], v[76:79]
	v_mfma_f32_16x16x32_bf16 v[72:75], v[164:167], v[220:223], v[72:75]
	v_mfma_f32_16x16x32_bf16 v[124:127], v[160:163], v[194:197], v[124:127]
	v_mfma_f32_16x16x32_bf16 v[120:123], v[168:171], v[194:197], v[120:123]
	v_mfma_f32_16x16x32_bf16 v[108:111], v[160:163], v[208:211], v[108:111]
	v_mfma_f32_16x16x32_bf16 v[104:107], v[168:171], v[208:211], v[104:107]
	v_mfma_f32_16x16x32_bf16 v[92:95], v[160:163], v[216:219], v[92:95]
	v_mfma_f32_16x16x32_bf16 v[88:91], v[168:171], v[216:219], v[88:91]
	v_mfma_f32_16x16x32_bf16 v[76:79], v[160:163], v[224:227], v[76:79]
	v_mfma_f32_16x16x32_bf16 v[72:75], v[168:171], v[224:227], v[72:75]
	s_setprio 0
	s_setprio 1
	v_mfma_f32_16x16x32_bf16 v[116:119], v[172:175], v[190:193], v[116:119]
	v_mfma_f32_16x16x32_bf16 v[112:115], v[182:185], v[190:193], v[112:115]
	v_mfma_f32_16x16x32_bf16 v[100:103], v[172:175], v[198:201], v[100:103]
	v_mfma_f32_16x16x32_bf16 v[96:99], v[182:185], v[198:201], v[96:99]
	v_mfma_f32_16x16x32_bf16 v[84:87], v[172:175], v[212:215], v[84:87]
	v_mfma_f32_16x16x32_bf16 v[80:83], v[182:185], v[212:215], v[80:83]
	v_mfma_f32_16x16x32_bf16 v[68:71], v[172:175], v[220:223], v[68:71]
	v_mfma_f32_16x16x32_bf16 v[64:67], v[182:185], v[220:223], v[64:67]
	v_mfma_f32_16x16x32_bf16 v[116:119], v[176:179], v[194:197], v[116:119]
	v_mfma_f32_16x16x32_bf16 v[112:115], v[186:189], v[194:197], v[112:115]
	v_mfma_f32_16x16x32_bf16 v[100:103], v[176:179], v[208:211], v[100:103]
	v_mfma_f32_16x16x32_bf16 v[96:99], v[186:189], v[208:211], v[96:99]
	v_mfma_f32_16x16x32_bf16 v[84:87], v[176:179], v[216:219], v[84:87]
	v_mfma_f32_16x16x32_bf16 v[80:83], v[186:189], v[216:219], v[80:83]
	v_mfma_f32_16x16x32_bf16 v[68:71], v[176:179], v[224:227], v[68:71]
	v_mfma_f32_16x16x32_bf16 v[64:67], v[186:189], v[224:227], v[64:67]
	s_setprio 0
	s_barrier
; #define PG8_STAGE(bufoff, gbase, voff) do { _Pragma("unroll") for (int _i = 0; _i < 2; ++_i) \
;         __builtin_amdgcn_global_load_lds((const unsigned*)((const char*)(gbase) + (voff)[_i]), (PG8_LAS unsigned*)(lds + (bufoff) + ldsw + _i * 8192), 16, 0, 0); } while (0)
; #define PG8_LDA(dst, b, h) do { _Pragma("unroll") for (int m = 0; m < 4; ++m) _Pragma("unroll") for (int k = 0; k < 2; ++k) dst[m][k] = *(const PG8_LAS bf16x8*)(lds + PG8_SA(b, h) + aoff + m * 2048 + k * 1024); } while (0)
; #define PG8_LDB(dst, b, h) do { _Pragma("unroll") for (int n = 0; n < 2; ++n) _Pragma("unroll") for (int k = 0; k < 2; ++k) dst[n][k] = *(const PG8_LAS bf16x8*)(lds + PG8_SB(b, h) + boff + n * 2048 + k * 1024); } while (0)
; #define PG8_MMA(ai, bj, At, Bt) do { __builtin_amdgcn_s_setprio(1); _Pragma("unroll") for (int m = 0; m < 4; ++m) _Pragma("unroll") for (int n = 0; n < 2; ++n) _Pragma("unroll") for (int k = 0; k < 2; ++k) \
;         acc[ai][bj][m][n] = __builtin_amdgcn_mfma_f32_16x16x32_bf16(Bt[n][k], At[m][k], acc[ai][bj][m][n], 0, 0, 0); __builtin_amdgcn_s_setprio(0); } while (0)
; #define PG8_WAIT_V(n) asm volatile("s_waitcnt vmcnt(" #n ")" ::: "memory")
; template <class Epi, class Sched, bool ALIGN_EPI = false, bool SP2 = false>
; __device__ __forceinline__ void gemm_phase(PG8_LAS unsigned char* lds, const Gemm g, const Sched& S, const Epi& E) {
;     ...
;             PG8_LDB(B0, 0, 0); PG8_LDB(B1, 0, 1); PG8_SCHED; PG8_LDA(At, 0, 0); PG8_STAGE(PG8_SA(1, 1), a1 + hstep, voffA);
;             PG8_WAIT_V(8); PG8_WAIT_L(0); PG8_BAR; PG8_MMA(0, 0, At, B0); PG8_MMA(0, 1, At, B1); PG8_BAR; PG8_SCHED;
;             PG8_LDA(At, 0, 1); PG8_STAGE(PG8_SB(0, 0), b2, voffB); PG8_STAGE(PG8_SB(0, 1), b2 + hstep, voffB); PG8_STAGE(PG8_SA(0, 0), a2, voffA);
;             PG8_WAIT_V(8); PG8_WAIT_L(0); PG8_BAR; PG8_MMA(1, 0, At, B0); PG8_MMA(1, 1, At, B1); PG8_BAR; PG8_SCHED;
;             PG8_LDB(B0, 1, 0); PG8_LDB(B1, 1, 1); PG8_SCHED; PG8_LDA(At, 1, 0); PG8_STAGE(PG8_SA(0, 1), a2 + hstep, voffA);
;             PG8_WAIT_V(8); PG8_WAIT_L(0); PG8_BAR; PG8_MMA(0, 0, At, B0); PG8_MMA(0, 1, At, B1); PG8_BAR; PG8_SCHED;
;             PG8_LDA(At, 1, 1); PG8_STAGE(PG8_SB(1, 0), b3, voffB); PG8_STAGE(PG8_SB(1, 1), b3 + hstep, voffB); PG8_STAGE(PG8_SA(1, 0), a3, voffA);
;             PG8_WAIT_V(8); PG8_WAIT_L(0); PG8_BAR; PG8_MMA(1, 0, At, B0); PG8_MMA(1, 1, At, B1); PG8_BAR; PG8_SCHED;
	s_add_i32 s3, s3, s34
	v_lshl_add_u64 v[202:203], v[202:203], 0, s[38:39]
	s_mov_b32 m0, s3
	ds_read_b128 v[190:193], v157 offset:49152
	ds_read_b128 v[194:197], v157 offset:50176
	ds_read_b128 v[198:201], v157 offset:51200
	ds_read_b128 v[208:211], v157 offset:52224
	ds_read_b128 v[212:215], v157 offset:53248
	ds_read_b128 v[216:219], v157 offset:54272
	ds_read_b128 v[220:223], v157 offset:55296
	ds_read_b128 v[224:227], v157 offset:56320
	global_load_lds_dwordx4 v[202:203], off
	s_add_i32 m0, s3, 0x2000
	s_add_u32 s14, s58, 0x40080
	v_lshl_add_u64 v[202:203], v[228:229], 0, s[38:39]
	s_addc_u32 s15, s59, 0
	s_add_i32 s3, s33, s34
	global_load_lds_dwordx4 v[202:203], off
	v_lshl_add_u64 v[202:203], s[14:15], 0, v[136:137]
	s_mov_b32 m0, s3
	s_nop 0
	global_load_lds_dwordx4 v[202:203], off
	v_lshl_add_u64 v[202:203], s[14:15], 0, v[132:133]
	s_add_i32 m0, s3, 0x2000
	s_nop 0
	global_load_lds_dwordx4 v[202:203], off
	s_waitcnt vmcnt(6)
	s_waitcnt lgkmcnt(0)
	s_barrier
	s_setprio 1
	s_waitcnt lgkmcnt(0)
	v_mfma_f32_16x16x32_bf16 v[60:63], v[148:151], v[190:193], v[60:63]
	v_mfma_f32_16x16x32_bf16 v[56:59], v[164:167], v[190:193], v[56:59]
	v_mfma_f32_16x16x32_bf16 v[44:47], v[148:151], v[198:201], v[44:47]
	v_mfma_f32_16x16x32_bf16 v[40:43], v[164:167], v[198:201], v[40:43]
	v_mfma_f32_16x16x32_bf16 v[28:31], v[148:151], v[212:215], v[28:31]
	v_mfma_f32_16x16x32_bf16 v[24:27], v[164:167], v[212:215], v[24:27]
	v_mfma_f32_16x16x32_bf16 v[12:15], v[148:151], v[220:223], v[12:15]
	v_mfma_f32_16x16x32_bf16 v[8:11], v[164:167], v[220:223], v[8:11]
	v_mfma_f32_16x16x32_bf16 v[60:63], v[160:163], v[194:197], v[60:63]
	v_mfma_f32_16x16x32_bf16 v[56:59], v[168:171], v[194:197], v[56:59]
	v_mfma_f32_16x16x32_bf16 v[44:47], v[160:163], v[208:211], v[44:47]
	v_mfma_f32_16x16x32_bf16 v[40:43], v[168:171], v[208:211], v[40:43]
	v_mfma_f32_16x16x32_bf16 v[28:31], v[160:163], v[216:219], v[28:31]
	v_mfma_f32_16x16x32_bf16 v[24:27], v[168:171], v[216:219], v[24:27]
	v_mfma_f32_16x16x32_bf16 v[12:15], v[160:163], v[224:227], v[12:15]
	v_lshl_add_u64 v[202:203], v[230:231], 0, s[38:39]
	s_mov_b32 m0, s66
	s_nop 0
	global_load_lds_dwordx4 v[202:203], off
	v_mfma_f32_16x16x32_bf16 v[8:11], v[168:171], v[224:227], v[8:11]
	s_setprio 0
	s_setprio 1
	v_mfma_f32_16x16x32_bf16 v[52:55], v[172:175], v[190:193], v[52:55]
	v_mfma_f32_16x16x32_bf16 v[48:51], v[182:185], v[190:193], v[48:51]
	v_mfma_f32_16x16x32_bf16 v[36:39], v[172:175], v[198:201], v[36:39]
	v_mfma_f32_16x16x32_bf16 v[32:35], v[182:185], v[198:201], v[32:35]
	v_mfma_f32_16x16x32_bf16 v[20:23], v[172:175], v[212:215], v[20:23]
	v_mfma_f32_16x16x32_bf16 v[16:19], v[182:185], v[212:215], v[16:19]
	v_mfma_f32_16x16x32_bf16 v[4:7], v[172:175], v[220:223], v[4:7]
	v_mfma_f32_16x16x32_bf16 v[0:3], v[182:185], v[220:223], v[0:3]
	v_mfma_f32_16x16x32_bf16 v[52:55], v[176:179], v[194:197], v[52:55]
	v_mfma_f32_16x16x32_bf16 v[48:51], v[186:189], v[194:197], v[48:51]
	v_mfma_f32_16x16x32_bf16 v[36:39], v[176:179], v[208:211], v[36:39]
	v_mfma_f32_16x16x32_bf16 v[32:35], v[186:189], v[208:211], v[32:35]
	v_mfma_f32_16x16x32_bf16 v[20:23], v[176:179], v[216:219], v[20:23]
	v_mfma_f32_16x16x32_bf16 v[16:19], v[186:189], v[216:219], v[16:19]
	v_mfma_f32_16x16x32_bf16 v[4:7], v[176:179], v[224:227], v[4:7]
	v_lshl_add_u64 v[202:203], v[232:233], 0, s[38:39]
	s_mov_b32 m0, s67
	s_nop 0
	global_load_lds_dwordx4 v[202:203], off
	v_mfma_f32_16x16x32_bf16 v[0:3], v[186:189], v[224:227], v[0:3]
	s_setprio 0
	s_barrier
	s_add_i32 s86, s86, 2
	s_add_u32 s56, s56, 0x100
	s_addc_u32 s57, s57, 0
	s_add_u32 s84, s84, 0x100
	s_addc_u32 s85, s85, 0
.LBB0_738:
	ds_read_b128 v[148:151], v155
	ds_read_b128 v[160:163], v155 offset:1024
	ds_read_b128 v[164:167], v155 offset:2048
	ds_read_b128 v[168:171], v155 offset:3072
	ds_read_b128 v[172:175], v156
	ds_read_b128 v[176:179], v156 offset:1024
	ds_read_b128 v[182:185], v156 offset:2048
	ds_read_b128 v[186:189], v156 offset:3072
	s_add_u32 s3, s56, 0xfffc0080
	s_addc_u32 s14, s57, -1
	s_cmp_eq_u32 s86, 12
	s_cselect_b32 s61, s51, s14
	s_cselect_b32 s60, s82, s3
	s_cselect_b32 s59, s49, s85
	s_cselect_b32 s58, s83, s84
	v_lshl_add_u64 v[202:203], s[56:57], 0, v[140:141]
	s_add_i32 m0, s43, 0xc000
	ds_read_b128 v[190:193], v157
	ds_read_b128 v[194:197], v157 offset:1024
	ds_read_b128 v[198:201], v157 offset:2048
	ds_read_b128 v[208:211], v157 offset:3072
	ds_read_b128 v[212:215], v157 offset:4096
	ds_read_b128 v[216:219], v157 offset:5120
	ds_read_b128 v[220:223], v157 offset:6144
	ds_read_b128 v[224:227], v157 offset:7168
	global_load_lds_dwordx4 v[202:203], off
	v_lshl_add_u64 v[202:203], s[56:57], 0, v[142:143]
	s_add_i32 m0, s43, 0xe000
	s_nop 0
	global_load_lds_dwordx4 v[202:203], off
	s_waitcnt vmcnt(8)
	s_waitcnt lgkmcnt(0)
	s_barrier
; #define PG8_STAGE(bufoff, gbase, voff) do { _Pragma("unroll") for (int _i = 0; _i < 2; ++_i) \
;         __builtin_amdgcn_global_load_lds((const unsigned*)((const char*)(gbase) + (voff)[_i]), (PG8_LAS unsigned*)(lds + (bufoff) + ldsw + _i * 8192), 16, 0, 0); } while (0)
; #define PG8_LDA(dst, b, h) do { _Pragma("unroll") for (int m = 0; m < 4; ++m) _Pragma("unroll") for (int k = 0; k < 2; ++k) dst[m][k] = *(const PG8_LAS bf16x8*)(lds + PG8_SA(b, h) + aoff + m * 2048 + k * 1024); } while (0)
; #define PG8_MMA(ai, bj, At, Bt) do { __builtin_amdgcn_s_setprio(1); _Pragma("unroll") for (int m = 0; m < 4; ++m) _Pragma("unroll") for (int n = 0; n < 2; ++n) _Pragma("unroll") for (int k = 0; k < 2; ++k) \
;         acc[ai][bj][m][n] = __builtin_amdgcn_mfma_f32_16x16x32_bf16(Bt[n][k], At[m][k], acc[ai][bj][m][n], 0, 0, 0); __builtin_amdgcn_s_setprio(0); } while (0)
; #define PG8_WAIT_V(n) asm volatile("s_waitcnt vmcnt(" #n ")" ::: "memory")
; #define PG8_WAIT_L(n) asm volatile("s_waitcnt lgkmcnt(" #n ")" ::: "memory")
; #define PG8_BAR __builtin_amdgcn_s_barrier()
; #define PG8_SCHED __builtin_amdgcn_sched_barrier(0)
; template <class Epi, class Sched, bool ALIGN_EPI = false, bool SP2 = false>
; __device__ __forceinline__ void gemm_phase(PG8_LAS unsigned char* lds, const Gemm g, const Sched& S, const Epi& E) {
;     ...
;             PG8_WAIT_V(8); PG8_WAIT_L(0); PG8_BAR; PG8_MMA(0, 0, At, B0); PG8_MMA(0, 1, At, B1); PG8_BAR; PG8_SCHED;
;             PG8_LDA(At, 0, 1); PG8_STAGE(PG8_SB(0, 0), b2, voffB); PG8_STAGE(PG8_SB(0, 1), b2 + hstep, voffB); PG8_STAGE(PG8_SA(0, 0), a2, voffA);
;             PG8_WAIT_V(8); PG8_WAIT_L(0); PG8_BAR; PG8_MMA(1, 0, At, B0); PG8_MMA(1, 1, At, B1); PG8_BAR; PG8_SCHED;
	s_setprio 1
	s_waitcnt lgkmcnt(0)
	v_mfma_f32_16x16x32_bf16 v[124:127], v[148:151], v[190:193], v[124:127]
	v_mfma_f32_16x16x32_bf16 v[120:123], v[164:167], v[190:193], v[120:123]
	v_mfma_f32_16x16x32_bf16 v[108:111], v[148:151], v[198:201], v[108:111]
	v_mfma_f32_16x16x32_bf16 v[104:107], v[164:167], v[198:201], v[104:107]
	v_mfma_f32_16x16x32_bf16 v[92:95], v[148:151], v[212:215], v[92:95]
	v_mfma_f32_16x16x32_bf16 v[88:91], v[164:167], v[212:215], v[88:91]
	v_mfma_f32_16x16x32_bf16 v[76:79], v[148:151], v[220:223], v[76:79]
	v_mfma_f32_16x16x32_bf16 v[72:75], v[164:167], v[220:223], v[72:75]
	v_mfma_f32_16x16x32_bf16 v[124:127], v[160:163], v[194:197], v[124:127]
	v_mfma_f32_16x16x32_bf16 v[120:123], v[168:171], v[194:197], v[120:123]
	v_mfma_f32_16x16x32_bf16 v[108:111], v[160:163], v[208:211], v[108:111]
	v_mfma_f32_16x16x32_bf16 v[104:107], v[168:171], v[208:211], v[104:107]
	v_mfma_f32_16x16x32_bf16 v[92:95], v[160:163], v[216:219], v[92:95]
	v_mfma_f32_16x16x32_bf16 v[88:91], v[168:171], v[216:219], v[88:91]
	v_mfma_f32_16x16x32_bf16 v[76:79], v[160:163], v[224:227], v[76:79]
	v_mfma_f32_16x16x32_bf16 v[72:75], v[168:171], v[224:227], v[72:75]
	s_setprio 0
	s_setprio 1
	v_mfma_f32_16x16x32_bf16 v[116:119], v[172:175], v[190:193], v[116:119]
	v_mfma_f32_16x16x32_bf16 v[112:115], v[182:185], v[190:193], v[112:115]
	v_mfma_f32_16x16x32_bf16 v[100:103], v[172:175], v[198:201], v[100:103]
	v_mfma_f32_16x16x32_bf16 v[96:99], v[182:185], v[198:201], v[96:99]
	v_mfma_f32_16x16x32_bf16 v[84:87], v[172:175], v[212:215], v[84:87]
	v_mfma_f32_16x16x32_bf16 v[80:83], v[182:185], v[212:215], v[80:83]
	v_mfma_f32_16x16x32_bf16 v[68:71], v[172:175], v[220:223], v[68:71]
	v_mfma_f32_16x16x32_bf16 v[64:67], v[182:185], v[220:223], v[64:67]
	v_mfma_f32_16x16x32_bf16 v[116:119], v[176:179], v[194:197], v[116:119]
	v_mfma_f32_16x16x32_bf16 v[112:115], v[186:189], v[194:197], v[112:115]
	v_mfma_f32_16x16x32_bf16 v[100:103], v[176:179], v[208:211], v[100:103]
	v_mfma_f32_16x16x32_bf16 v[96:99], v[186:189], v[208:211], v[96:99]
	v_mfma_f32_16x16x32_bf16 v[84:87], v[176:179], v[216:219], v[84:87]
	v_mfma_f32_16x16x32_bf16 v[80:83], v[186:189], v[216:219], v[80:83]
	v_mfma_f32_16x16x32_bf16 v[68:71], v[176:179], v[224:227], v[68:71]
	v_mfma_f32_16x16x32_bf16 v[64:67], v[186:189], v[224:227], v[64:67]
	s_setprio 0
	s_barrier
	s_add_i32 s3, s74, s34
	v_lshl_add_u64 v[202:203], s[58:59], 0, v[136:137]
	s_mov_b32 m0, s3
	ds_read_b128 v[190:193], v157 offset:16384
	ds_read_b128 v[194:197], v157 offset:17408
	ds_read_b128 v[198:201], v157 offset:18432
	ds_read_b128 v[208:211], v157 offset:19456
	ds_read_b128 v[212:215], v157 offset:20480
	ds_read_b128 v[216:219], v157 offset:21504
	ds_read_b128 v[220:223], v157 offset:22528
	ds_read_b128 v[224:227], v157 offset:23552
	global_load_lds_dwordx4 v[202:203], off
	s_add_i32 m0, s3, 0x2000
	s_add_u32 s14, s58, 0x40000
	v_lshl_add_u64 v[228:229], s[58:59], 0, v[132:133]
	s_addc_u32 s15, s59, 0
	s_add_i32 s3, s75, s34
	global_load_lds_dwordx4 v[228:229], off
	v_lshl_add_u64 v[230:231], s[14:15], 0, v[136:137]
	s_mov_b32 m0, s3
	global_load_lds_dwordx4 v[230:231], off
	v_lshl_add_u64 v[230:231], s[14:15], 0, v[132:133]
	s_add_i32 m0, s3, 0x2000
	s_nop 0
	global_load_lds_dwordx4 v[230:231], off
	s_waitcnt vmcnt(6)
	s_waitcnt lgkmcnt(0)
	s_barrier
	s_setprio 1
	s_waitcnt lgkmcnt(0)
	v_mfma_f32_16x16x32_bf16 v[60:63], v[148:151], v[190:193], v[60:63]
	v_mfma_f32_16x16x32_bf16 v[56:59], v[164:167], v[190:193], v[56:59]
	v_mfma_f32_16x16x32_bf16 v[44:47], v[148:151], v[198:201], v[44:47]
	v_mfma_f32_16x16x32_bf16 v[40:43], v[164:167], v[198:201], v[40:43]
	v_mfma_f32_16x16x32_bf16 v[28:31], v[148:151], v[212:215], v[28:31]
	v_mfma_f32_16x16x32_bf16 v[24:27], v[164:167], v[212:215], v[24:27]
	v_mfma_f32_16x16x32_bf16 v[12:15], v[148:151], v[220:223], v[12:15]
	v_mfma_f32_16x16x32_bf16 v[8:11], v[164:167], v[220:223], v[8:11]
	v_mfma_f32_16x16x32_bf16 v[60:63], v[160:163], v[194:197], v[60:63]
	v_mfma_f32_16x16x32_bf16 v[56:59], v[168:171], v[194:197], v[56:59]
	v_mfma_f32_16x16x32_bf16 v[44:47], v[160:163], v[208:211], v[44:47]
	v_mfma_f32_16x16x32_bf16 v[40:43], v[168:171], v[208:211], v[40:43]
	v_mfma_f32_16x16x32_bf16 v[28:31], v[160:163], v[216:219], v[28:31]
	v_mfma_f32_16x16x32_bf16 v[24:27], v[168:171], v[216:219], v[24:27]
	v_mfma_f32_16x16x32_bf16 v[12:15], v[160:163], v[224:227], v[12:15]
	v_lshl_add_u64 v[230:231], s[60:61], 0, v[138:139]
	s_mov_b32 m0, s43
	s_nop 0
	global_load_lds_dwordx4 v[230:231], off
	v_mfma_f32_16x16x32_bf16 v[8:11], v[168:171], v[224:227], v[8:11]
	s_setprio 0
	s_setprio 1
	v_mfma_f32_16x16x32_bf16 v[52:55], v[172:175], v[190:193], v[52:55]
	v_mfma_f32_16x16x32_bf16 v[48:51], v[182:185], v[190:193], v[48:51]
	v_mfma_f32_16x16x32_bf16 v[36:39], v[172:175], v[198:201], v[36:39]
	v_mfma_f32_16x16x32_bf16 v[32:35], v[182:185], v[198:201], v[32:35]
	v_mfma_f32_16x16x32_bf16 v[20:23], v[172:175], v[212:215], v[20:23]
	v_mfma_f32_16x16x32_bf16 v[16:19], v[182:185], v[212:215], v[16:19]
	v_mfma_f32_16x16x32_bf16 v[4:7], v[172:175], v[220:223], v[4:7]
	v_mfma_f32_16x16x32_bf16 v[0:3], v[182:185], v[220:223], v[0:3]
	v_mfma_f32_16x16x32_bf16 v[52:55], v[176:179], v[194:197], v[52:55]
	v_mfma_f32_16x16x32_bf16 v[48:51], v[186:189], v[194:197], v[48:51]
	v_mfma_f32_16x16x32_bf16 v[36:39], v[176:179], v[208:211], v[36:39]
	v_mfma_f32_16x16x32_bf16 v[32:35], v[186:189], v[208:211], v[32:35]
	v_mfma_f32_16x16x32_bf16 v[20:23], v[176:179], v[216:219], v[20:23]
	v_mfma_f32_16x16x32_bf16 v[16:19], v[186:189], v[216:219], v[16:19]
	v_mfma_f32_16x16x32_bf16 v[4:7], v[176:179], v[224:227], v[4:7]
	v_lshl_add_u64 v[232:233], s[60:61], 0, v[134:135]
	s_mov_b32 m0, s62
	s_nop 0
	global_load_lds_dwordx4 v[232:233], off
	v_mfma_f32_16x16x32_bf16 v[0:3], v[186:189], v[224:227], v[0:3]
	s_setprio 0
	s_barrier
; #define PG8_STAGE(bufoff, gbase, voff) do { _Pragma("unroll") for (int _i = 0; _i < 2; ++_i) \
;         __builtin_amdgcn_global_load_lds((const unsigned*)((const char*)(gbase) + (voff)[_i]), (PG8_LAS unsigned*)(lds + (bufoff) + ldsw + _i * 8192), 16, 0, 0); } while (0)
; #define PG8_LDA(dst, b, h) do { _Pragma("unroll") for (int m = 0; m < 4; ++m) _Pragma("unroll") for (int k = 0; k < 2; ++k) dst[m][k] = *(const PG8_LAS bf16x8*)(lds + PG8_SA(b, h) + aoff + m * 2048 + k * 1024); } while (0)
; #define PG8_LDB(dst, b, h) do { _Pragma("unroll") for (int n = 0; n < 2; ++n) _Pragma("unroll") for (int k = 0; k < 2; ++k) dst[n][k] = *(const PG8_LAS bf16x8*)(lds + PG8_SB(b, h) + boff + n * 2048 + k * 1024); } while (0)
; #define PG8_MMA(ai, bj, At, Bt) do { __builtin_amdgcn_s_setprio(1); _Pragma("unroll") for (int m = 0; m < 4; ++m) _Pragma("unroll") for (int n = 0; n < 2; ++n) _Pragma("unroll") for (int k = 0; k < 2; ++k) \
;         acc[ai][bj][m][n] = __builtin_amdgcn_mfma_f32_16x16x32_bf16(Bt[n][k], At[m][k], acc[ai][bj][m][n], 0, 0, 0); __builtin_amdgcn_s_setprio(0); } while (0)
; #define PG8_WAIT_V(n) asm volatile("s_waitcnt vmcnt(" #n ")" ::: "memory")
; #define PG8_WAIT_L(n) asm volatile("s_waitcnt lgkmcnt(" #n ")" ::: "memory")
; #define PG8_BAR __builtin_amdgcn_s_barrier()
; #define PG8_SCHED __builtin_amdgcn_sched_barrier(0)
; template <class Epi, class Sched, bool ALIGN_EPI = false, bool SP2 = false>
; __device__ __forceinline__ void gemm_phase(PG8_LAS unsigned char* lds, const Gemm g, const Sched& S, const Epi& E) {
;     ...
;             PG8_LDB(B0, 1, 0); PG8_LDB(B1, 1, 1); PG8_SCHED; PG8_LDA(At, 1, 0); PG8_STAGE(PG8_SA(0, 1), a2 + hstep, voffA);
;             PG8_WAIT_V(8); PG8_WAIT_L(0); PG8_BAR; PG8_MMA(0, 0, At, B0); PG8_MMA(0, 1, At, B1); PG8_BAR; PG8_SCHED;
	s_add_i32 s3, 0, 0x18000
	v_add_u32_e32 v159, s3, v131
	s_add_i32 s33, 0, 0x1c000
	ds_read_b128 v[148:151], v159
	ds_read_b128 v[160:163], v159 offset:1024
	ds_read_b128 v[164:167], v159 offset:2048
	ds_read_b128 v[168:171], v159 offset:3072
	v_add_u32_e32 v159, s33, v131
	ds_read_b128 v[172:175], v159
	ds_read_b128 v[176:179], v159 offset:1024
	ds_read_b128 v[182:185], v159 offset:2048
	ds_read_b128 v[186:189], v159 offset:3072
	s_add_u32 s14, s60, 0x40000
	s_addc_u32 s15, s61, 0
	s_mov_b32 m0, s63
	v_lshl_add_u64 v[234:235], s[14:15], 0, v[138:139]
	ds_read_b128 v[190:193], v157 offset:32768
	ds_read_b128 v[194:197], v157 offset:33792
	ds_read_b128 v[198:201], v157 offset:34816
	ds_read_b128 v[208:211], v157 offset:35840
	ds_read_b128 v[212:215], v157 offset:36864
	ds_read_b128 v[216:219], v157 offset:37888
	ds_read_b128 v[220:223], v157 offset:38912
	ds_read_b128 v[224:227], v157 offset:39936
	global_load_lds_dwordx4 v[234:235], off
	v_lshl_add_u64 v[234:235], s[14:15], 0, v[134:135]
	s_mov_b32 m0, s64
	s_nop 0
	global_load_lds_dwordx4 v[234:235], off
	s_waitcnt vmcnt(8)
	s_waitcnt lgkmcnt(0)
	s_barrier
	s_setprio 1
	s_waitcnt lgkmcnt(0)
	v_mfma_f32_16x16x32_bf16 v[124:127], v[148:151], v[190:193], v[124:127]
	v_mfma_f32_16x16x32_bf16 v[120:123], v[164:167], v[190:193], v[120:123]
	v_mfma_f32_16x16x32_bf16 v[108:111], v[148:151], v[198:201], v[108:111]
	v_mfma_f32_16x16x32_bf16 v[104:107], v[164:167], v[198:201], v[104:107]
	v_mfma_f32_16x16x32_bf16 v[92:95], v[148:151], v[212:215], v[92:95]
	v_mfma_f32_16x16x32_bf16 v[88:91], v[164:167], v[212:215], v[88:91]
	v_mfma_f32_16x16x32_bf16 v[76:79], v[148:151], v[220:223], v[76:79]
	v_mfma_f32_16x16x32_bf16 v[72:75], v[164:167], v[220:223], v[72:75]
	v_mfma_f32_16x16x32_bf16 v[124:127], v[160:163], v[194:197], v[124:127]
	v_mfma_f32_16x16x32_bf16 v[120:123], v[168:171], v[194:197], v[120:123]
	v_mfma_f32_16x16x32_bf16 v[108:111], v[160:163], v[208:211], v[108:111]
	v_mfma_f32_16x16x32_bf16 v[104:107], v[168:171], v[208:211], v[104:107]
	v_mfma_f32_16x16x32_bf16 v[92:95], v[160:163], v[216:219], v[92:95]
	v_mfma_f32_16x16x32_bf16 v[88:91], v[168:171], v[216:219], v[88:91]
	v_mfma_f32_16x16x32_bf16 v[76:79], v[160:163], v[224:227], v[76:79]
	v_mfma_f32_16x16x32_bf16 v[72:75], v[168:171], v[224:227], v[72:75]
	s_setprio 0
	s_setprio 1
	v_mfma_f32_16x16x32_bf16 v[116:119], v[172:175], v[190:193], v[116:119]
	v_mfma_f32_16x16x32_bf16 v[112:115], v[182:185], v[190:193], v[112:115]
	v_mfma_f32_16x16x32_bf16 v[100:103], v[172:175], v[198:201], v[100:103]
	v_mfma_f32_16x16x32_bf16 v[96:99], v[182:185], v[198:201], v[96:99]
	v_mfma_f32_16x16x32_bf16 v[84:87], v[172:175], v[212:215], v[84:87]
	v_mfma_f32_16x16x32_bf16 v[80:83], v[182:185], v[212:215], v[80:83]
	v_mfma_f32_16x16x32_bf16 v[68:71], v[172:175], v[220:223], v[68:71]
	v_mfma_f32_16x16x32_bf16 v[64:67], v[182:185], v[220:223], v[64:67]
	v_mfma_f32_16x16x32_bf16 v[116:119], v[176:179], v[194:197], v[116:119]
	v_mfma_f32_16x16x32_bf16 v[112:115], v[186:189], v[194:197], v[112:115]
	v_mfma_f32_16x16x32_bf16 v[100:103], v[176:179], v[208:211], v[100:103]
	v_mfma_f32_16x16x32_bf16 v[96:99], v[186:189], v[208:211], v[96:99]
	v_mfma_f32_16x16x32_bf16 v[84:87], v[176:179], v[216:219], v[84:87]
	v_mfma_f32_16x16x32_bf16 v[80:83], v[186:189], v[216:219], v[80:83]
	v_mfma_f32_16x16x32_bf16 v[68:71], v[176:179], v[224:227], v[68:71]
	v_mfma_f32_16x16x32_bf16 v[64:67], v[186:189], v[224:227], v[64:67]
	s_setprio 0
	s_barrier
; #define PG8_STAGE(bufoff, gbase, voff) do { _Pragma("unroll") for (int _i = 0; _i < 2; ++_i) \
;         __builtin_amdgcn_global_load_lds((const unsigned*)((const char*)(gbase) + (voff)[_i]), (PG8_LAS unsigned*)(lds + (bufoff) + ldsw + _i * 8192), 16, 0, 0); } while (0)
; #define PG8_LDA(dst, b, h) do { _Pragma("unroll") for (int m = 0; m < 4; ++m) _Pragma("unroll") for (int k = 0; k < 2; ++k) dst[m][k] = *(const PG8_LAS bf16x8*)(lds + PG8_SA(b, h) + aoff + m * 2048 + k * 1024); } while (0)
; #define PG8_MMA(ai, bj, At, Bt) do { __builtin_amdgcn_s_setprio(1); _Pragma("unroll") for (int m = 0; m < 4; ++m) _Pragma("unroll") for (int n = 0; n < 2; ++n) _Pragma("unroll") for (int k = 0; k < 2; ++k) \
;         acc[ai][bj][m][n] = __builtin_amdgcn_mfma_f32_16x16x32_bf16(Bt[n][k], At[m][k], acc[ai][bj][m][n], 0, 0, 0); __builtin_amdgcn_s_setprio(0); } while (0)
; #define PG8_WAIT_V(n) asm volatile("s_waitcnt vmcnt(" #n ")" ::: "memory")
; #define PG8_WAIT_L(n) asm volatile("s_waitcnt lgkmcnt(" #n ")" ::: "memory")
; #define PG8_BAR __builtin_amdgcn_s_barrier()
; #define PG8_SCHED __builtin_amdgcn_sched_barrier(0)
; template <class Epi, class Sched, bool ALIGN_EPI = false, bool SP2 = false>
; __device__ __forceinline__ void gemm_phase(PG8_LAS unsigned char* lds, const Gemm g, const Sched& S, const Epi& E) {
;     ...
;             PG8_LDA(At, 1, 1); PG8_STAGE(PG8_SB(1, 0), b3, voffB); PG8_STAGE(PG8_SB(1, 1), b3 + hstep, voffB); PG8_STAGE(PG8_SA(1, 0), a3, voffA);
;             PG8_WAIT_V(8); PG8_WAIT_L(0); PG8_BAR; PG8_MMA(1, 0, At, B0); PG8_MMA(1, 1, At, B1); PG8_BAR; PG8_SCHED;
;     ...
;         }
;         if constexpr (ALIGN_EPI) { if (wr == 0) PG8_BAR; }
;         if constexpr (!Epi::AFTER_DRAIN) { E(acc, cur, wr, wc, fr, fq); S.done(cur); }
;         if (!has_next) break;
	s_add_i32 s3, s3, s34
	v_lshl_add_u64 v[202:203], v[202:203], 0, s[38:39]
	s_mov_b32 m0, s3
	ds_read_b128 v[190:193], v157 offset:49152
	ds_read_b128 v[194:197], v157 offset:50176
	ds_read_b128 v[198:201], v157 offset:51200
	ds_read_b128 v[208:211], v157 offset:52224
	ds_read_b128 v[212:215], v157 offset:53248
	ds_read_b128 v[216:219], v157 offset:54272
	ds_read_b128 v[220:223], v157 offset:55296
	ds_read_b128 v[224:227], v157 offset:56320
	global_load_lds_dwordx4 v[202:203], off
	s_add_i32 m0, s3, 0x2000
	s_add_u32 s14, s58, 0x40080
	v_lshl_add_u64 v[202:203], v[228:229], 0, s[38:39]
	s_addc_u32 s15, s59, 0
	s_add_i32 s3, s33, s34
	global_load_lds_dwordx4 v[202:203], off
	v_lshl_add_u64 v[202:203], s[14:15], 0, v[136:137]
	s_mov_b32 m0, s3
	s_nop 0
	global_load_lds_dwordx4 v[202:203], off
	v_lshl_add_u64 v[202:203], s[14:15], 0, v[132:133]
	s_add_i32 m0, s3, 0x2000
	s_nop 0
	global_load_lds_dwordx4 v[202:203], off
	s_waitcnt vmcnt(6)
	s_waitcnt lgkmcnt(0)
	s_barrier
	s_setprio 1
	s_waitcnt lgkmcnt(0)
	v_mfma_f32_16x16x32_bf16 v[60:63], v[148:151], v[190:193], v[60:63]
	v_mfma_f32_16x16x32_bf16 v[56:59], v[164:167], v[190:193], v[56:59]
	v_mfma_f32_16x16x32_bf16 v[44:47], v[148:151], v[198:201], v[44:47]
	v_mfma_f32_16x16x32_bf16 v[40:43], v[164:167], v[198:201], v[40:43]
	v_mfma_f32_16x16x32_bf16 v[28:31], v[148:151], v[212:215], v[28:31]
	v_mfma_f32_16x16x32_bf16 v[24:27], v[164:167], v[212:215], v[24:27]
	v_mfma_f32_16x16x32_bf16 v[12:15], v[148:151], v[220:223], v[12:15]
	v_mfma_f32_16x16x32_bf16 v[8:11], v[164:167], v[220:223], v[8:11]
	v_mfma_f32_16x16x32_bf16 v[60:63], v[160:163], v[194:197], v[60:63]
	v_mfma_f32_16x16x32_bf16 v[56:59], v[168:171], v[194:197], v[56:59]
	v_mfma_f32_16x16x32_bf16 v[44:47], v[160:163], v[208:211], v[44:47]
	v_mfma_f32_16x16x32_bf16 v[40:43], v[168:171], v[208:211], v[40:43]
	v_mfma_f32_16x16x32_bf16 v[28:31], v[160:163], v[216:219], v[28:31]
	v_mfma_f32_16x16x32_bf16 v[24:27], v[168:171], v[216:219], v[24:27]
	v_mfma_f32_16x16x32_bf16 v[12:15], v[160:163], v[224:227], v[12:15]
	v_lshl_add_u64 v[202:203], v[230:231], 0, s[38:39]
	s_mov_b32 m0, s66
	s_nop 0
	global_load_lds_dwordx4 v[202:203], off
	v_mfma_f32_16x16x32_bf16 v[8:11], v[168:171], v[224:227], v[8:11]
	s_setprio 0
	s_setprio 1
	v_mfma_f32_16x16x32_bf16 v[52:55], v[172:175], v[190:193], v[52:55]
	v_mfma_f32_16x16x32_bf16 v[48:51], v[182:185], v[190:193], v[48:51]
	v_mfma_f32_16x16x32_bf16 v[36:39], v[172:175], v[198:201], v[36:39]
	v_mfma_f32_16x16x32_bf16 v[32:35], v[182:185], v[198:201], v[32:35]
	v_mfma_f32_16x16x32_bf16 v[20:23], v[172:175], v[212:215], v[20:23]
	v_mfma_f32_16x16x32_bf16 v[16:19], v[182:185], v[212:215], v[16:19]
	v_mfma_f32_16x16x32_bf16 v[4:7], v[172:175], v[220:223], v[4:7]
	v_mfma_f32_16x16x32_bf16 v[0:3], v[182:185], v[220:223], v[0:3]
	v_mfma_f32_16x16x32_bf16 v[52:55], v[176:179], v[194:197], v[52:55]
	v_mfma_f32_16x16x32_bf16 v[48:51], v[186:189], v[194:197], v[48:51]
	v_mfma_f32_16x16x32_bf16 v[36:39], v[176:179], v[208:211], v[36:39]
	v_mfma_f32_16x16x32_bf16 v[32:35], v[186:189], v[208:211], v[32:35]
	v_mfma_f32_16x16x32_bf16 v[20:23], v[176:179], v[216:219], v[20:23]
	v_mfma_f32_16x16x32_bf16 v[16:19], v[186:189], v[216:219], v[16:19]
	v_mfma_f32_16x16x32_bf16 v[4:7], v[176:179], v[224:227], v[4:7]
	v_lshl_add_u64 v[202:203], v[232:233], 0, s[38:39]
	s_mov_b32 m0, s67
	s_nop 0
	global_load_lds_dwordx4 v[202:203], off
	v_mfma_f32_16x16x32_bf16 v[0:3], v[186:189], v[224:227], v[0:3]
	s_setprio 0
	s_barrier
	s_add_i32 s86, s86, 2
	s_add_u32 s56, s56, 0x100
	s_addc_u32 s57, s57, 0
	s_add_u32 s84, s84, 0x100
	s_addc_u32 s85, s85, 0
	s_cmp_gt_u32 s86, 13
	s_cbranch_scc0 .LBB0_738
	s_and_b64 vcc, exec, s[44:45]
	s_cbranch_vccz .LBB0_741
	s_barrier

; #define PG8_STAGE(bufoff, gbase, voff) do { _Pragma("unroll") for (int _i = 0; _i < 2; ++_i) \
;         __builtin_amdgcn_global_load_lds((const unsigned*)((const char*)(gbase) + (voff)[_i]), (PG8_LAS unsigned*)(lds + (bufoff) + ldsw + _i * 8192), 16, 0, 0); } while (0)
; #define PG8_LDA(dst, b, h) do { _Pragma("unroll") for (int m = 0; m < 4; ++m) _Pragma("unroll") for (int k = 0; k < 2; ++k) dst[m][k] = *(const PG8_LAS bf16x8*)(lds + PG8_SA(b, h) + aoff + m * 2048 + k * 1024); } while (0)
; #define PG8_LDB(dst, b, h) do { _Pragma("unroll") for (int n = 0; n < 2; ++n) _Pragma("unroll") for (int k = 0; k < 2; ++k) dst[n][k] = *(const PG8_LAS bf16x8*)(lds + PG8_SB(b, h) + boff + n * 2048 + k * 1024); } while (0)
; #define PG8_MMA(ai, bj, At, Bt) do { __builtin_amdgcn_s_setprio(1); _Pragma("unroll") for (int m = 0; m < 4; ++m) _Pragma("unroll") for (int n = 0; n < 2; ++n) _Pragma("unroll") for (int k = 0; k < 2; ++k) \
;         acc[ai][bj][m][n] = __builtin_amdgcn_mfma_f32_16x16x32_bf16(Bt[n][k], At[m][k], acc[ai][bj][m][n], 0, 0, 0); __builtin_amdgcn_s_setprio(0); } while (0)
; #define PG8_BAR __builtin_amdgcn_s_barrier()
; template <class Epi, class Sched, bool ALIGN_EPI = false, bool SP2 = false>
; __device__ __forceinline__ void gemm_phase(PG8_LAS unsigned char* lds, const Gemm g, const Sched& S, const Epi& E) {
;     ...
;         const bool has_next = S.next(ui + 1, nxt);
;         const char* nA = has_next ? (const char*)g.A + (size_t)nxt.pm * tstep : cA; const char* nB = has_next ? (const char*)g.Bt + (size_t)nxt.pn * tstep : cB;
;         for (int t = 0; t < nt; t += 2) {
;             const bool last = (t == nt - 2);
;             const char* a1 = cA + (size_t)(t + 1) * kstep;
;             const char* a2 = last ? nA : cA + (size_t)(t + 2) * kstep; const char* b2 = last ? nB : cB + (size_t)(t + 2) * kstep;
;             const char* a3 = a2 + kstep; const char* b3 = b2 + kstep;
;             if (last && has_next) S.a_ready(nxt);
;             if constexpr (SP2) {
;             PG8_LDB(B0, 0, 0); PG8_LDB(B1, 0, 1); PG8_SCHED; PG8_LDA(At, 0, 0); PG8_STAGE(PG8_SA(1, 1), a1 + hstep, voffA);
;             PG8_WAIT_V(8); PG8_WAIT_L(0); PG8_BAR; PG8_MMA(0, 0, At, B0); PG8_MMA(0, 1, At, B1); PG8_BAR; PG8_SCHED;
;             PG8_LDA(At, 0, 1); PG8_STAGE(PG8_SB(0, 0), b2, voffB); PG8_STAGE(PG8_SB(0, 1), b2 + hstep, voffB); PG8_STAGE(PG8_SA(0, 0), a2, voffA);
.LBB0_872:
	s_ashr_i32 s49, s48, 31
	s_lshl_b64 s[50:51], s[48:49], 18
	s_add_u32 s50, s92, s50
	s_addc_u32 s51, s93, s51
	s_and_b64 s[52:53], s[10:11], exec
	s_cselect_b32 s49, s51, s59
	s_cselect_b32 s55, s50, s58
	s_ashr_i32 s45, s44, 31
	s_lshl_b64 s[52:53], s[44:45], 18
	s_add_u32 s52, s76, s52
	s_addc_u32 s53, s77, s53
	s_and_b64 s[62:63], s[10:11], exec
	s_cselect_b32 s45, s53, s61
	s_cselect_b32 s84, s52, s60
	s_add_u32 s58, s58, 0x20080
	s_addc_u32 s59, s59, 0
	s_add_u32 s85, s60, 0x100
	s_addc_u32 s86, s61, 0
	s_mov_b32 s87, -2
	s_waitcnt lgkmcnt(0)
	ds_read_b128 v[144:147], v151
	ds_read_b128 v[156:159], v151 offset:1024
	ds_read_b128 v[160:163], v151 offset:2048
	ds_read_b128 v[164:167], v151 offset:3072
	ds_read_b128 v[168:171], v152
	ds_read_b128 v[172:175], v152 offset:1024
	ds_read_b128 v[176:179], v152 offset:2048
	ds_read_b128 v[182:185], v152 offset:3072
	s_add_u32 s3, s58, 0xfffe0080
	s_addc_u32 s33, s59, -1
	s_cmp_eq_u32 s87, 4
	s_cselect_b32 s63, s49, s33
	s_cselect_b32 s62, s55, s3
	s_cselect_b32 s61, s45, s86
	s_cselect_b32 s60, s84, s85
	v_lshl_add_u64 v[202:203], s[58:59], 0, v[136:137]
	s_add_i32 m0, s15, 0xc000
	ds_read_b128 v[186:189], v153
	ds_read_b128 v[190:193], v153 offset:1024
	ds_read_b128 v[194:197], v153 offset:2048
	ds_read_b128 v[198:201], v153 offset:3072
	ds_read_b128 v[208:211], v153 offset:4096
	ds_read_b128 v[212:215], v153 offset:5120
	ds_read_b128 v[216:219], v153 offset:6144
	ds_read_b128 v[220:223], v153 offset:7168
	global_load_lds_dwordx4 v[202:203], off
	v_lshl_add_u64 v[202:203], s[58:59], 0, v[138:139]
	s_add_i32 m0, s15, 0xe000
	s_nop 0
	global_load_lds_dwordx4 v[202:203], off
	s_waitcnt vmcnt(8)
	s_waitcnt lgkmcnt(0)
	s_barrier
	s_setprio 1
	s_waitcnt lgkmcnt(0)
	v_mfma_f32_16x16x32_bf16 v[124:127], v[144:147], v[186:189], 0
	v_mfma_f32_16x16x32_bf16 v[120:123], v[160:163], v[186:189], 0
	v_mfma_f32_16x16x32_bf16 v[108:111], v[144:147], v[194:197], 0
	v_mfma_f32_16x16x32_bf16 v[104:107], v[160:163], v[194:197], 0
	v_mfma_f32_16x16x32_bf16 v[92:95], v[144:147], v[208:211], 0
	v_mfma_f32_16x16x32_bf16 v[88:91], v[160:163], v[208:211], 0
	v_mfma_f32_16x16x32_bf16 v[76:79], v[144:147], v[216:219], 0
	v_mfma_f32_16x16x32_bf16 v[72:75], v[160:163], v[216:219], 0
	v_mfma_f32_16x16x32_bf16 v[124:127], v[156:159], v[190:193], v[124:127]
	v_mfma_f32_16x16x32_bf16 v[120:123], v[164:167], v[190:193], v[120:123]
	v_mfma_f32_16x16x32_bf16 v[108:111], v[156:159], v[198:201], v[108:111]
	v_mfma_f32_16x16x32_bf16 v[104:107], v[164:167], v[198:201], v[104:107]
	v_mfma_f32_16x16x32_bf16 v[92:95], v[156:159], v[212:215], v[92:95]
	v_mfma_f32_16x16x32_bf16 v[88:91], v[164:167], v[212:215], v[88:91]
	v_mfma_f32_16x16x32_bf16 v[76:79], v[156:159], v[220:223], v[76:79]
	v_mfma_f32_16x16x32_bf16 v[72:75], v[164:167], v[220:223], v[72:75]
	s_setprio 0
	s_setprio 1
	v_mfma_f32_16x16x32_bf16 v[116:119], v[168:171], v[186:189], 0
	v_mfma_f32_16x16x32_bf16 v[112:115], v[176:179], v[186:189], 0
	v_mfma_f32_16x16x32_bf16 v[100:103], v[168:171], v[194:197], 0
	v_mfma_f32_16x16x32_bf16 v[96:99], v[176:179], v[194:197], 0
	v_mfma_f32_16x16x32_bf16 v[84:87], v[168:171], v[208:211], 0
	v_mfma_f32_16x16x32_bf16 v[80:83], v[176:179], v[208:211], 0
	v_mfma_f32_16x16x32_bf16 v[68:71], v[168:171], v[216:219], 0
	v_mfma_f32_16x16x32_bf16 v[64:67], v[176:179], v[216:219], 0
	v_mfma_f32_16x16x32_bf16 v[116:119], v[172:175], v[190:193], v[116:119]
	v_mfma_f32_16x16x32_bf16 v[112:115], v[182:185], v[190:193], v[112:115]
	v_mfma_f32_16x16x32_bf16 v[100:103], v[172:175], v[198:201], v[100:103]
	v_mfma_f32_16x16x32_bf16 v[96:99], v[182:185], v[198:201], v[96:99]
	v_mfma_f32_16x16x32_bf16 v[84:87], v[172:175], v[212:215], v[84:87]
	v_mfma_f32_16x16x32_bf16 v[80:83], v[182:185], v[212:215], v[80:83]
	v_mfma_f32_16x16x32_bf16 v[68:71], v[172:175], v[220:223], v[68:71]
	v_mfma_f32_16x16x32_bf16 v[64:67], v[182:185], v[220:223], v[64:67]
	s_setprio 0
	s_barrier
	s_add_i32 s3, s74, s14
	v_lshl_add_u64 v[202:203], s[60:61], 0, v[130:131]
	s_mov_b32 m0, s3
	ds_read_b128 v[186:189], v153 offset:16384
	ds_read_b128 v[190:193], v153 offset:17408
	ds_read_b128 v[194:197], v153 offset:18432
	ds_read_b128 v[198:201], v153 offset:19456
	ds_read_b128 v[208:211], v153 offset:20480
	ds_read_b128 v[212:215], v153 offset:21504
	ds_read_b128 v[216:219], v153 offset:22528
	ds_read_b128 v[220:223], v153 offset:23552
	global_load_lds_dwordx4 v[202:203], off
	s_add_i32 m0, s3, 0x2000
	s_add_u32 s78, s60, 0x20000
	v_lshl_add_u64 v[224:225], s[60:61], 0, v[134:135]
	s_addc_u32 s79, s61, 0
	s_add_i32 s3, s75, s14
	global_load_lds_dwordx4 v[224:225], off
	v_lshl_add_u64 v[226:227], s[78:79], 0, v[130:131]
	s_mov_b32 m0, s3
	global_load_lds_dwordx4 v[226:227], off
	v_lshl_add_u64 v[226:227], s[78:79], 0, v[134:135]
	s_add_i32 m0, s3, 0x2000
	s_nop 0
	global_load_lds_dwordx4 v[226:227], off
	s_waitcnt vmcnt(6)
	s_waitcnt lgkmcnt(0)
	s_barrier
; #define PG8_STAGE(bufoff, gbase, voff) do { _Pragma("unroll") for (int _i = 0; _i < 2; ++_i) \
;         __builtin_amdgcn_global_load_lds((const unsigned*)((const char*)(gbase) + (voff)[_i]), (PG8_LAS unsigned*)(lds + (bufoff) + ldsw + _i * 8192), 16, 0, 0); } while (0)
; #define PG8_LDA(dst, b, h) do { _Pragma("unroll") for (int m = 0; m < 4; ++m) _Pragma("unroll") for (int k = 0; k < 2; ++k) dst[m][k] = *(const PG8_LAS bf16x8*)(lds + PG8_SA(b, h) + aoff + m * 2048 + k * 1024); } while (0)
; #define PG8_LDB(dst, b, h) do { _Pragma("unroll") for (int n = 0; n < 2; ++n) _Pragma("unroll") for (int k = 0; k < 2; ++k) dst[n][k] = *(const PG8_LAS bf16x8*)(lds + PG8_SB(b, h) + boff + n * 2048 + k * 1024); } while (0)
; #define PG8_MMA(ai, bj, At, Bt) do { __builtin_amdgcn_s_setprio(1); _Pragma("unroll") for (int m = 0; m < 4; ++m) _Pragma("unroll") for (int n = 0; n < 2; ++n) _Pragma("unroll") for (int k = 0; k < 2; ++k) \
;         acc[ai][bj][m][n] = __builtin_amdgcn_mfma_f32_16x16x32_bf16(Bt[n][k], At[m][k], acc[ai][bj][m][n], 0, 0, 0); __builtin_amdgcn_s_setprio(0); } while (0)
; #define PG8_WAIT_V(n) asm volatile("s_waitcnt vmcnt(" #n ")" ::: "memory")
; #define PG8_WAIT_L(n) asm volatile("s_waitcnt lgkmcnt(" #n ")" ::: "memory")
; #define PG8_BAR __builtin_amdgcn_s_barrier()
; #define PG8_SCHED __builtin_amdgcn_sched_barrier(0)
; template <class Epi, class Sched, bool ALIGN_EPI = false, bool SP2 = false>
; __device__ __forceinline__ void gemm_phase(PG8_LAS unsigned char* lds, const Gemm g, const Sched& S, const Epi& E) {
;     ...
;             PG8_LDA(At, 0, 1); PG8_STAGE(PG8_SB(0, 0), b2, voffB); PG8_STAGE(PG8_SB(0, 1), b2 + hstep, voffB); PG8_STAGE(PG8_SA(0, 0), a2, voffA);
;             PG8_WAIT_V(8); PG8_WAIT_L(0); PG8_BAR; PG8_MMA(1, 0, At, B0); PG8_MMA(1, 1, At, B1); PG8_BAR; PG8_SCHED;
;             PG8_LDB(B0, 1, 0); PG8_LDB(B1, 1, 1); PG8_SCHED; PG8_LDA(At, 1, 0); PG8_STAGE(PG8_SA(0, 1), a2 + hstep, voffA);
;             PG8_WAIT_V(8); PG8_WAIT_L(0); PG8_BAR; PG8_MMA(0, 0, At, B0); PG8_MMA(0, 1, At, B1); PG8_BAR; PG8_SCHED;
	s_setprio 1
	s_waitcnt lgkmcnt(0)
	v_mfma_f32_16x16x32_bf16 v[60:63], v[144:147], v[186:189], 0
	v_mfma_f32_16x16x32_bf16 v[56:59], v[160:163], v[186:189], 0
	v_mfma_f32_16x16x32_bf16 v[44:47], v[144:147], v[194:197], 0
	v_mfma_f32_16x16x32_bf16 v[40:43], v[160:163], v[194:197], 0
	v_mfma_f32_16x16x32_bf16 v[28:31], v[144:147], v[208:211], 0
	v_mfma_f32_16x16x32_bf16 v[24:27], v[160:163], v[208:211], 0
	v_mfma_f32_16x16x32_bf16 v[12:15], v[144:147], v[216:219], 0
	v_mfma_f32_16x16x32_bf16 v[8:11], v[160:163], v[216:219], 0
	v_mfma_f32_16x16x32_bf16 v[60:63], v[156:159], v[190:193], v[60:63]
	v_mfma_f32_16x16x32_bf16 v[56:59], v[164:167], v[190:193], v[56:59]
	v_mfma_f32_16x16x32_bf16 v[44:47], v[156:159], v[198:201], v[44:47]
	v_mfma_f32_16x16x32_bf16 v[40:43], v[164:167], v[198:201], v[40:43]
	v_mfma_f32_16x16x32_bf16 v[28:31], v[156:159], v[212:215], v[28:31]
	v_mfma_f32_16x16x32_bf16 v[24:27], v[164:167], v[212:215], v[24:27]
	v_mfma_f32_16x16x32_bf16 v[12:15], v[156:159], v[220:223], v[12:15]
	v_lshl_add_u64 v[226:227], s[62:63], 0, v[128:129]
	s_mov_b32 m0, s15
	s_nop 0
	global_load_lds_dwordx4 v[226:227], off
	v_mfma_f32_16x16x32_bf16 v[8:11], v[164:167], v[220:223], v[8:11]
	s_setprio 0
	s_setprio 1
	v_mfma_f32_16x16x32_bf16 v[52:55], v[168:171], v[186:189], 0
	v_mfma_f32_16x16x32_bf16 v[48:51], v[176:179], v[186:189], 0
	v_mfma_f32_16x16x32_bf16 v[36:39], v[168:171], v[194:197], 0
	v_mfma_f32_16x16x32_bf16 v[32:35], v[176:179], v[194:197], 0
	v_mfma_f32_16x16x32_bf16 v[20:23], v[168:171], v[208:211], 0
	v_mfma_f32_16x16x32_bf16 v[16:19], v[176:179], v[208:211], 0
	v_mfma_f32_16x16x32_bf16 v[4:7], v[168:171], v[216:219], 0
	v_mfma_f32_16x16x32_bf16 v[0:3], v[176:179], v[216:219], 0
	v_mfma_f32_16x16x32_bf16 v[52:55], v[172:175], v[190:193], v[52:55]
	v_mfma_f32_16x16x32_bf16 v[48:51], v[182:185], v[190:193], v[48:51]
	v_mfma_f32_16x16x32_bf16 v[36:39], v[172:175], v[198:201], v[36:39]
	v_mfma_f32_16x16x32_bf16 v[32:35], v[182:185], v[198:201], v[32:35]
	v_mfma_f32_16x16x32_bf16 v[20:23], v[172:175], v[212:215], v[20:23]
	v_mfma_f32_16x16x32_bf16 v[16:19], v[182:185], v[212:215], v[16:19]
	v_mfma_f32_16x16x32_bf16 v[4:7], v[172:175], v[220:223], v[4:7]
	v_lshl_add_u64 v[228:229], s[62:63], 0, v[132:133]
	s_mov_b32 m0, s34
	s_nop 0
	global_load_lds_dwordx4 v[228:229], off
	v_mfma_f32_16x16x32_bf16 v[0:3], v[182:185], v[220:223], v[0:3]
	s_setprio 0
	s_barrier
	s_add_i32 s3, 0, 0x18000
	v_add_u32_e32 v155, s3, v149
	s_add_i32 s33, 0, 0x1c000
	ds_read_b128 v[144:147], v155
	ds_read_b128 v[156:159], v155 offset:1024
	ds_read_b128 v[160:163], v155 offset:2048
	ds_read_b128 v[164:167], v155 offset:3072
	v_add_u32_e32 v155, s33, v149
	ds_read_b128 v[168:171], v155
	ds_read_b128 v[172:175], v155 offset:1024
	ds_read_b128 v[176:179], v155 offset:2048
	ds_read_b128 v[182:185], v155 offset:3072
	s_add_u32 s62, s62, 0x20000
	s_addc_u32 s63, s63, 0
	s_mov_b32 m0, s57
	v_lshl_add_u64 v[230:231], s[62:63], 0, v[128:129]
	ds_read_b128 v[186:189], v153 offset:32768
	ds_read_b128 v[190:193], v153 offset:33792
	ds_read_b128 v[194:197], v153 offset:34816
	ds_read_b128 v[198:201], v153 offset:35840
	ds_read_b128 v[208:211], v153 offset:36864
	ds_read_b128 v[212:215], v153 offset:37888
	ds_read_b128 v[216:219], v153 offset:38912
	ds_read_b128 v[220:223], v153 offset:39936
	global_load_lds_dwordx4 v[230:231], off
	v_lshl_add_u64 v[230:231], s[62:63], 0, v[132:133]
	s_mov_b32 m0, s64
	s_nop 0
	global_load_lds_dwordx4 v[230:231], off
	s_waitcnt vmcnt(8)
	s_waitcnt lgkmcnt(0)
	s_barrier
	s_setprio 1
	s_waitcnt lgkmcnt(0)
	v_mfma_f32_16x16x32_bf16 v[124:127], v[144:147], v[186:189], v[124:127]
	v_mfma_f32_16x16x32_bf16 v[120:123], v[160:163], v[186:189], v[120:123]
	v_mfma_f32_16x16x32_bf16 v[108:111], v[144:147], v[194:197], v[108:111]
	v_mfma_f32_16x16x32_bf16 v[104:107], v[160:163], v[194:197], v[104:107]
	v_mfma_f32_16x16x32_bf16 v[92:95], v[144:147], v[208:211], v[92:95]
	v_mfma_f32_16x16x32_bf16 v[88:91], v[160:163], v[208:211], v[88:91]
	v_mfma_f32_16x16x32_bf16 v[76:79], v[144:147], v[216:219], v[76:79]
	v_mfma_f32_16x16x32_bf16 v[72:75], v[160:163], v[216:219], v[72:75]
	v_mfma_f32_16x16x32_bf16 v[124:127], v[156:159], v[190:193], v[124:127]
	v_mfma_f32_16x16x32_bf16 v[120:123], v[164:167], v[190:193], v[120:123]
	v_mfma_f32_16x16x32_bf16 v[108:111], v[156:159], v[198:201], v[108:111]
	v_mfma_f32_16x16x32_bf16 v[104:107], v[164:167], v[198:201], v[104:107]
	v_mfma_f32_16x16x32_bf16 v[92:95], v[156:159], v[212:215], v[92:95]
	v_mfma_f32_16x16x32_bf16 v[88:91], v[164:167], v[212:215], v[88:91]
	v_mfma_f32_16x16x32_bf16 v[76:79], v[156:159], v[220:223], v[76:79]
	v_mfma_f32_16x16x32_bf16 v[72:75], v[164:167], v[220:223], v[72:75]
	s_setprio 0
	s_setprio 1
	v_mfma_f32_16x16x32_bf16 v[116:119], v[168:171], v[186:189], v[116:119]
	v_mfma_f32_16x16x32_bf16 v[112:115], v[176:179], v[186:189], v[112:115]
	v_mfma_f32_16x16x32_bf16 v[100:103], v[168:171], v[194:197], v[100:103]
	v_mfma_f32_16x16x32_bf16 v[96:99], v[176:179], v[194:197], v[96:99]
	v_mfma_f32_16x16x32_bf16 v[84:87], v[168:171], v[208:211], v[84:87]
	v_mfma_f32_16x16x32_bf16 v[80:83], v[176:179], v[208:211], v[80:83]
	v_mfma_f32_16x16x32_bf16 v[68:71], v[168:171], v[216:219], v[68:71]
	v_mfma_f32_16x16x32_bf16 v[64:67], v[176:179], v[216:219], v[64:67]
	v_mfma_f32_16x16x32_bf16 v[116:119], v[172:175], v[190:193], v[116:119]
	v_mfma_f32_16x16x32_bf16 v[112:115], v[182:185], v[190:193], v[112:115]
	v_mfma_f32_16x16x32_bf16 v[100:103], v[172:175], v[198:201], v[100:103]
	v_mfma_f32_16x16x32_bf16 v[96:99], v[182:185], v[198:201], v[96:99]
	v_mfma_f32_16x16x32_bf16 v[84:87], v[172:175], v[212:215], v[84:87]
	v_mfma_f32_16x16x32_bf16 v[80:83], v[182:185], v[212:215], v[80:83]
	v_mfma_f32_16x16x32_bf16 v[68:71], v[172:175], v[220:223], v[68:71]
	v_mfma_f32_16x16x32_bf16 v[64:67], v[182:185], v[220:223], v[64:67]
	s_setprio 0
	s_barrier
; #define PG8_STAGE(bufoff, gbase, voff) do { _Pragma("unroll") for (int _i = 0; _i < 2; ++_i) \
;         __builtin_amdgcn_global_load_lds((const unsigned*)((const char*)(gbase) + (voff)[_i]), (PG8_LAS unsigned*)(lds + (bufoff) + ldsw + _i * 8192), 16, 0, 0); } while (0)
; #define PG8_LDA(dst, b, h) do { _Pragma("unroll") for (int m = 0; m < 4; ++m) _Pragma("unroll") for (int k = 0; k < 2; ++k) dst[m][k] = *(const PG8_LAS bf16x8*)(lds + PG8_SA(b, h) + aoff + m * 2048 + k * 1024); } while (0)
; #define PG8_LDB(dst, b, h) do { _Pragma("unroll") for (int n = 0; n < 2; ++n) _Pragma("unroll") for (int k = 0; k < 2; ++k) dst[n][k] = *(const PG8_LAS bf16x8*)(lds + PG8_SB(b, h) + boff + n * 2048 + k * 1024); } while (0)
; #define PG8_MMA(ai, bj, At, Bt) do { __builtin_amdgcn_s_setprio(1); _Pragma("unroll") for (int m = 0; m < 4; ++m) _Pragma("unroll") for (int n = 0; n < 2; ++n) _Pragma("unroll") for (int k = 0; k < 2; ++k) \
;         acc[ai][bj][m][n] = __builtin_amdgcn_mfma_f32_16x16x32_bf16(Bt[n][k], At[m][k], acc[ai][bj][m][n], 0, 0, 0); __builtin_amdgcn_s_setprio(0); } while (0)
; #define PG8_WAIT_V(n) asm volatile("s_waitcnt vmcnt(" #n ")" ::: "memory")
; template <class Epi, class Sched, bool ALIGN_EPI = false, bool SP2 = false>
; __device__ __forceinline__ void gemm_phase(PG8_LAS unsigned char* lds, const Gemm g, const Sched& S, const Epi& E) {
;     ...
;             PG8_LDB(B0, 0, 0); PG8_LDB(B1, 0, 1); PG8_SCHED; PG8_LDA(At, 0, 0); PG8_STAGE(PG8_SA(1, 1), a1 + hstep, voffA);
;             PG8_WAIT_V(8); PG8_WAIT_L(0); PG8_BAR; PG8_MMA(0, 0, At, B0); PG8_MMA(0, 1, At, B1); PG8_BAR; PG8_SCHED;
;             PG8_LDA(At, 0, 1); PG8_STAGE(PG8_SB(0, 0), b2, voffB); PG8_STAGE(PG8_SB(0, 1), b2 + hstep, voffB); PG8_STAGE(PG8_SA(0, 0), a2, voffA);
;             PG8_WAIT_V(8); PG8_WAIT_L(0); PG8_BAR; PG8_MMA(1, 0, At, B0); PG8_MMA(1, 1, At, B1); PG8_BAR; PG8_SCHED;
;             PG8_LDB(B0, 1, 0); PG8_LDB(B1, 1, 1); PG8_SCHED; PG8_LDA(At, 1, 0); PG8_STAGE(PG8_SA(0, 1), a2 + hstep, voffA);
;             PG8_WAIT_V(8); PG8_WAIT_L(0); PG8_BAR; PG8_MMA(0, 0, At, B0); PG8_MMA(0, 1, At, B1); PG8_BAR; PG8_SCHED;
;             PG8_LDA(At, 1, 1); PG8_STAGE(PG8_SB(1, 0), b3, voffB); PG8_STAGE(PG8_SB(1, 1), b3 + hstep, voffB); PG8_STAGE(PG8_SA(1, 0), a3, voffA);
;             PG8_WAIT_V(8); PG8_WAIT_L(0); PG8_BAR; PG8_MMA(1, 0, At, B0); PG8_MMA(1, 1, At, B1); PG8_BAR; PG8_SCHED;
	s_add_i32 s3, s3, s14
	v_lshl_add_u64 v[202:203], v[202:203], 0, s[38:39]
	s_mov_b32 m0, s3
	ds_read_b128 v[186:189], v153 offset:49152
	ds_read_b128 v[190:193], v153 offset:50176
	ds_read_b128 v[194:197], v153 offset:51200
	ds_read_b128 v[198:201], v153 offset:52224
	ds_read_b128 v[208:211], v153 offset:53248
	ds_read_b128 v[212:215], v153 offset:54272
	ds_read_b128 v[216:219], v153 offset:55296
	ds_read_b128 v[220:223], v153 offset:56320
	global_load_lds_dwordx4 v[202:203], off
	s_add_i32 m0, s3, 0x2000
	s_add_u32 s60, s60, 0x20080
	v_lshl_add_u64 v[202:203], v[224:225], 0, s[38:39]
	s_addc_u32 s61, s61, 0
	s_add_i32 s3, s33, s14
	global_load_lds_dwordx4 v[202:203], off
	v_lshl_add_u64 v[202:203], s[60:61], 0, v[130:131]
	s_mov_b32 m0, s3
	s_nop 0
	global_load_lds_dwordx4 v[202:203], off
	v_lshl_add_u64 v[202:203], s[60:61], 0, v[134:135]
	s_add_i32 m0, s3, 0x2000
	s_nop 0
	global_load_lds_dwordx4 v[202:203], off
	s_waitcnt vmcnt(6)
	s_waitcnt lgkmcnt(0)
	s_barrier
	s_setprio 1
	s_waitcnt lgkmcnt(0)
	v_mfma_f32_16x16x32_bf16 v[60:63], v[144:147], v[186:189], v[60:63]
	v_mfma_f32_16x16x32_bf16 v[56:59], v[160:163], v[186:189], v[56:59]
	v_mfma_f32_16x16x32_bf16 v[44:47], v[144:147], v[194:197], v[44:47]
	v_mfma_f32_16x16x32_bf16 v[40:43], v[160:163], v[194:197], v[40:43]
	v_mfma_f32_16x16x32_bf16 v[28:31], v[144:147], v[208:211], v[28:31]
	v_mfma_f32_16x16x32_bf16 v[24:27], v[160:163], v[208:211], v[24:27]
	v_mfma_f32_16x16x32_bf16 v[12:15], v[144:147], v[216:219], v[12:15]
	v_mfma_f32_16x16x32_bf16 v[8:11], v[160:163], v[216:219], v[8:11]
	v_mfma_f32_16x16x32_bf16 v[60:63], v[156:159], v[190:193], v[60:63]
	v_mfma_f32_16x16x32_bf16 v[56:59], v[164:167], v[190:193], v[56:59]
	v_mfma_f32_16x16x32_bf16 v[44:47], v[156:159], v[198:201], v[44:47]
	v_mfma_f32_16x16x32_bf16 v[40:43], v[164:167], v[198:201], v[40:43]
	v_mfma_f32_16x16x32_bf16 v[28:31], v[156:159], v[212:215], v[28:31]
	v_mfma_f32_16x16x32_bf16 v[24:27], v[164:167], v[212:215], v[24:27]
	v_mfma_f32_16x16x32_bf16 v[12:15], v[156:159], v[220:223], v[12:15]
	v_lshl_add_u64 v[202:203], v[226:227], 0, s[38:39]
	s_mov_b32 m0, s66
	s_nop 0
	global_load_lds_dwordx4 v[202:203], off
	v_mfma_f32_16x16x32_bf16 v[8:11], v[164:167], v[220:223], v[8:11]
	s_setprio 0
	s_setprio 1
	v_mfma_f32_16x16x32_bf16 v[52:55], v[168:171], v[186:189], v[52:55]
	v_mfma_f32_16x16x32_bf16 v[48:51], v[176:179], v[186:189], v[48:51]
	v_mfma_f32_16x16x32_bf16 v[36:39], v[168:171], v[194:197], v[36:39]
	v_mfma_f32_16x16x32_bf16 v[32:35], v[176:179], v[194:197], v[32:35]
	v_mfma_f32_16x16x32_bf16 v[20:23], v[168:171], v[208:211], v[20:23]
	v_mfma_f32_16x16x32_bf16 v[16:19], v[176:179], v[208:211], v[16:19]
	v_mfma_f32_16x16x32_bf16 v[4:7], v[168:171], v[216:219], v[4:7]
	v_mfma_f32_16x16x32_bf16 v[0:3], v[176:179], v[216:219], v[0:3]
	v_mfma_f32_16x16x32_bf16 v[52:55], v[172:175], v[190:193], v[52:55]
	v_mfma_f32_16x16x32_bf16 v[48:51], v[182:185], v[190:193], v[48:51]
	v_mfma_f32_16x16x32_bf16 v[36:39], v[172:175], v[198:201], v[36:39]
	v_mfma_f32_16x16x32_bf16 v[32:35], v[182:185], v[198:201], v[32:35]
	v_mfma_f32_16x16x32_bf16 v[20:23], v[172:175], v[212:215], v[20:23]
	v_mfma_f32_16x16x32_bf16 v[16:19], v[182:185], v[212:215], v[16:19]
	v_mfma_f32_16x16x32_bf16 v[4:7], v[172:175], v[220:223], v[4:7]
	v_lshl_add_u64 v[202:203], v[228:229], 0, s[38:39]
	s_mov_b32 m0, s67
	s_nop 0
	global_load_lds_dwordx4 v[202:203], off
	v_mfma_f32_16x16x32_bf16 v[0:3], v[182:185], v[220:223], v[0:3]
	s_setprio 0
	s_barrier
	s_add_i32 s87, s87, 2
	s_add_u32 s58, s58, 0x100
	s_addc_u32 s59, s59, 0
	s_add_u32 s85, s85, 0x100
	s_addc_u32 s86, s86, 0
.LBB0_873:
	ds_read_b128 v[144:147], v151
	ds_read_b128 v[156:159], v151 offset:1024
	ds_read_b128 v[160:163], v151 offset:2048
	ds_read_b128 v[164:167], v151 offset:3072
	ds_read_b128 v[168:171], v152
	ds_read_b128 v[172:175], v152 offset:1024
	ds_read_b128 v[176:179], v152 offset:2048
	ds_read_b128 v[182:185], v152 offset:3072
	s_add_u32 s3, s58, 0xfffe0080
	s_addc_u32 s33, s59, -1
	s_cmp_eq_u32 s87, 4
	s_cselect_b32 s63, s49, s33
	s_cselect_b32 s62, s55, s3
	s_cselect_b32 s61, s45, s86
	s_cselect_b32 s60, s84, s85
	v_lshl_add_u64 v[202:203], s[58:59], 0, v[136:137]
	s_add_i32 m0, s15, 0xc000
	ds_read_b128 v[186:189], v153
	ds_read_b128 v[190:193], v153 offset:1024
	ds_read_b128 v[194:197], v153 offset:2048
	ds_read_b128 v[198:201], v153 offset:3072
	ds_read_b128 v[208:211], v153 offset:4096
	ds_read_b128 v[212:215], v153 offset:5120
	ds_read_b128 v[216:219], v153 offset:6144
	ds_read_b128 v[220:223], v153 offset:7168
	global_load_lds_dwordx4 v[202:203], off
	v_lshl_add_u64 v[202:203], s[58:59], 0, v[138:139]
	s_add_i32 m0, s15, 0xe000
	s_nop 0
	global_load_lds_dwordx4 v[202:203], off
	s_waitcnt vmcnt(8)
	s_waitcnt lgkmcnt(0)
	s_barrier
; #define PG8_STAGE(bufoff, gbase, voff) do { _Pragma("unroll") for (int _i = 0; _i < 2; ++_i) \
;         __builtin_amdgcn_global_load_lds((const unsigned*)((const char*)(gbase) + (voff)[_i]), (PG8_LAS unsigned*)(lds + (bufoff) + ldsw + _i * 8192), 16, 0, 0); } while (0)
; #define PG8_LDA(dst, b, h) do { _Pragma("unroll") for (int m = 0; m < 4; ++m) _Pragma("unroll") for (int k = 0; k < 2; ++k) dst[m][k] = *(const PG8_LAS bf16x8*)(lds + PG8_SA(b, h) + aoff + m * 2048 + k * 1024); } while (0)
; #define PG8_MMA(ai, bj, At, Bt) do { __builtin_amdgcn_s_setprio(1); _Pragma("unroll") for (int m = 0; m < 4; ++m) _Pragma("unroll") for (int n = 0; n < 2; ++n) _Pragma("unroll") for (int k = 0; k < 2; ++k) \
;         acc[ai][bj][m][n] = __builtin_amdgcn_mfma_f32_16x16x32_bf16(Bt[n][k], At[m][k], acc[ai][bj][m][n], 0, 0, 0); __builtin_amdgcn_s_setprio(0); } while (0)
; #define PG8_WAIT_V(n) asm volatile("s_waitcnt vmcnt(" #n ")" ::: "memory")
; #define PG8_WAIT_L(n) asm volatile("s_waitcnt lgkmcnt(" #n ")" ::: "memory")
; #define PG8_BAR __builtin_amdgcn_s_barrier()
; #define PG8_SCHED __builtin_amdgcn_sched_barrier(0)
; template <class Epi, class Sched, bool ALIGN_EPI = false, bool SP2 = false>
; __device__ __forceinline__ void gemm_phase(PG8_LAS unsigned char* lds, const Gemm g, const Sched& S, const Epi& E) {
;     ...
;             PG8_WAIT_V(8); PG8_WAIT_L(0); PG8_BAR; PG8_MMA(0, 0, At, B0); PG8_MMA(0, 1, At, B1); PG8_BAR; PG8_SCHED;
;             PG8_LDA(At, 0, 1); PG8_STAGE(PG8_SB(0, 0), b2, voffB); PG8_STAGE(PG8_SB(0, 1), b2 + hstep, voffB); PG8_STAGE(PG8_SA(0, 0), a2, voffA);
;             PG8_WAIT_V(8); PG8_WAIT_L(0); PG8_BAR; PG8_MMA(1, 0, At, B0); PG8_MMA(1, 1, At, B1); PG8_BAR; PG8_SCHED;
	s_setprio 1
	s_waitcnt lgkmcnt(0)
	v_mfma_f32_16x16x32_bf16 v[124:127], v[144:147], v[186:189], v[124:127]
	v_mfma_f32_16x16x32_bf16 v[120:123], v[160:163], v[186:189], v[120:123]
	v_mfma_f32_16x16x32_bf16 v[108:111], v[144:147], v[194:197], v[108:111]
	v_mfma_f32_16x16x32_bf16 v[104:107], v[160:163], v[194:197], v[104:107]
	v_mfma_f32_16x16x32_bf16 v[92:95], v[144:147], v[208:211], v[92:95]
	v_mfma_f32_16x16x32_bf16 v[88:91], v[160:163], v[208:211], v[88:91]
	v_mfma_f32_16x16x32_bf16 v[76:79], v[144:147], v[216:219], v[76:79]
	v_mfma_f32_16x16x32_bf16 v[72:75], v[160:163], v[216:219], v[72:75]
	v_mfma_f32_16x16x32_bf16 v[124:127], v[156:159], v[190:193], v[124:127]
	v_mfma_f32_16x16x32_bf16 v[120:123], v[164:167], v[190:193], v[120:123]
	v_mfma_f32_16x16x32_bf16 v[108:111], v[156:159], v[198:201], v[108:111]
	v_mfma_f32_16x16x32_bf16 v[104:107], v[164:167], v[198:201], v[104:107]
	v_mfma_f32_16x16x32_bf16 v[92:95], v[156:159], v[212:215], v[92:95]
	v_mfma_f32_16x16x32_bf16 v[88:91], v[164:167], v[212:215], v[88:91]
	v_mfma_f32_16x16x32_bf16 v[76:79], v[156:159], v[220:223], v[76:79]
	v_mfma_f32_16x16x32_bf16 v[72:75], v[164:167], v[220:223], v[72:75]
	s_setprio 0
	s_setprio 1
	v_mfma_f32_16x16x32_bf16 v[116:119], v[168:171], v[186:189], v[116:119]
	v_mfma_f32_16x16x32_bf16 v[112:115], v[176:179], v[186:189], v[112:115]
	v_mfma_f32_16x16x32_bf16 v[100:103], v[168:171], v[194:197], v[100:103]
	v_mfma_f32_16x16x32_bf16 v[96:99], v[176:179], v[194:197], v[96:99]
	v_mfma_f32_16x16x32_bf16 v[84:87], v[168:171], v[208:211], v[84:87]
	v_mfma_f32_16x16x32_bf16 v[80:83], v[176:179], v[208:211], v[80:83]
	v_mfma_f32_16x16x32_bf16 v[68:71], v[168:171], v[216:219], v[68:71]
	v_mfma_f32_16x16x32_bf16 v[64:67], v[176:179], v[216:219], v[64:67]
	v_mfma_f32_16x16x32_bf16 v[116:119], v[172:175], v[190:193], v[116:119]
	v_mfma_f32_16x16x32_bf16 v[112:115], v[182:185], v[190:193], v[112:115]
	v_mfma_f32_16x16x32_bf16 v[100:103], v[172:175], v[198:201], v[100:103]
	v_mfma_f32_16x16x32_bf16 v[96:99], v[182:185], v[198:201], v[96:99]
	v_mfma_f32_16x16x32_bf16 v[84:87], v[172:175], v[212:215], v[84:87]
	v_mfma_f32_16x16x32_bf16 v[80:83], v[182:185], v[212:215], v[80:83]
	v_mfma_f32_16x16x32_bf16 v[68:71], v[172:175], v[220:223], v[68:71]
	v_mfma_f32_16x16x32_bf16 v[64:67], v[182:185], v[220:223], v[64:67]
	s_setprio 0
	s_barrier
	s_add_i32 s3, s74, s14
	v_lshl_add_u64 v[202:203], s[60:61], 0, v[130:131]
	s_mov_b32 m0, s3
	ds_read_b128 v[186:189], v153 offset:16384
	ds_read_b128 v[190:193], v153 offset:17408
	ds_read_b128 v[194:197], v153 offset:18432
	ds_read_b128 v[198:201], v153 offset:19456
	ds_read_b128 v[208:211], v153 offset:20480
	ds_read_b128 v[212:215], v153 offset:21504
	ds_read_b128 v[216:219], v153 offset:22528
	ds_read_b128 v[220:223], v153 offset:23552
	global_load_lds_dwordx4 v[202:203], off
	s_add_i32 m0, s3, 0x2000
	s_add_u32 s78, s60, 0x20000
	v_lshl_add_u64 v[224:225], s[60:61], 0, v[134:135]
	s_addc_u32 s79, s61, 0
	s_add_i32 s3, s75, s14
	global_load_lds_dwordx4 v[224:225], off
	v_lshl_add_u64 v[226:227], s[78:79], 0, v[130:131]
	s_mov_b32 m0, s3
	global_load_lds_dwordx4 v[226:227], off
	v_lshl_add_u64 v[226:227], s[78:79], 0, v[134:135]
	s_add_i32 m0, s3, 0x2000
	s_nop 0
	global_load_lds_dwordx4 v[226:227], off
	s_waitcnt vmcnt(6)
	s_waitcnt lgkmcnt(0)
	s_barrier
	s_setprio 1
	s_waitcnt lgkmcnt(0)
	v_mfma_f32_16x16x32_bf16 v[60:63], v[144:147], v[186:189], v[60:63]
	v_mfma_f32_16x16x32_bf16 v[56:59], v[160:163], v[186:189], v[56:59]
	v_mfma_f32_16x16x32_bf16 v[44:47], v[144:147], v[194:197], v[44:47]
	v_mfma_f32_16x16x32_bf16 v[40:43], v[160:163], v[194:197], v[40:43]
	v_mfma_f32_16x16x32_bf16 v[28:31], v[144:147], v[208:211], v[28:31]
	v_mfma_f32_16x16x32_bf16 v[24:27], v[160:163], v[208:211], v[24:27]
	v_mfma_f32_16x16x32_bf16 v[12:15], v[144:147], v[216:219], v[12:15]
	v_mfma_f32_16x16x32_bf16 v[8:11], v[160:163], v[216:219], v[8:11]
	v_mfma_f32_16x16x32_bf16 v[60:63], v[156:159], v[190:193], v[60:63]
	v_mfma_f32_16x16x32_bf16 v[56:59], v[164:167], v[190:193], v[56:59]
	v_mfma_f32_16x16x32_bf16 v[44:47], v[156:159], v[198:201], v[44:47]
	v_mfma_f32_16x16x32_bf16 v[40:43], v[164:167], v[198:201], v[40:43]
	v_mfma_f32_16x16x32_bf16 v[28:31], v[156:159], v[212:215], v[28:31]
	v_mfma_f32_16x16x32_bf16 v[24:27], v[164:167], v[212:215], v[24:27]
	v_mfma_f32_16x16x32_bf16 v[12:15], v[156:159], v[220:223], v[12:15]
	v_lshl_add_u64 v[226:227], s[62:63], 0, v[128:129]
	s_mov_b32 m0, s15
	s_nop 0
	global_load_lds_dwordx4 v[226:227], off
	v_mfma_f32_16x16x32_bf16 v[8:11], v[164:167], v[220:223], v[8:11]
	s_setprio 0
	s_setprio 1
	v_mfma_f32_16x16x32_bf16 v[52:55], v[168:171], v[186:189], v[52:55]
	v_mfma_f32_16x16x32_bf16 v[48:51], v[176:179], v[186:189], v[48:51]
	v_mfma_f32_16x16x32_bf16 v[36:39], v[168:171], v[194:197], v[36:39]
	v_mfma_f32_16x16x32_bf16 v[32:35], v[176:179], v[194:197], v[32:35]
	v_mfma_f32_16x16x32_bf16 v[20:23], v[168:171], v[208:211], v[20:23]
	v_mfma_f32_16x16x32_bf16 v[16:19], v[176:179], v[208:211], v[16:19]
	v_mfma_f32_16x16x32_bf16 v[4:7], v[168:171], v[216:219], v[4:7]
	v_mfma_f32_16x16x32_bf16 v[0:3], v[176:179], v[216:219], v[0:3]
	v_mfma_f32_16x16x32_bf16 v[52:55], v[172:175], v[190:193], v[52:55]
	v_mfma_f32_16x16x32_bf16 v[48:51], v[182:185], v[190:193], v[48:51]
	v_mfma_f32_16x16x32_bf16 v[36:39], v[172:175], v[198:201], v[36:39]
	v_mfma_f32_16x16x32_bf16 v[32:35], v[182:185], v[198:201], v[32:35]
	v_mfma_f32_16x16x32_bf16 v[20:23], v[172:175], v[212:215], v[20:23]
	v_mfma_f32_16x16x32_bf16 v[16:19], v[182:185], v[212:215], v[16:19]
	v_mfma_f32_16x16x32_bf16 v[4:7], v[172:175], v[220:223], v[4:7]
	v_lshl_add_u64 v[228:229], s[62:63], 0, v[132:133]
	s_mov_b32 m0, s34
	s_nop 0
	global_load_lds_dwordx4 v[228:229], off
	v_mfma_f32_16x16x32_bf16 v[0:3], v[182:185], v[220:223], v[0:3]
	s_setprio 0
	s_barrier
; #define PG8_STAGE(bufoff, gbase, voff) do { _Pragma("unroll") for (int _i = 0; _i < 2; ++_i) \
;         __builtin_amdgcn_global_load_lds((const unsigned*)((const char*)(gbase) + (voff)[_i]), (PG8_LAS unsigned*)(lds + (bufoff) + ldsw + _i * 8192), 16, 0, 0); } while (0)
; #define PG8_LDA(dst, b, h) do { _Pragma("unroll") for (int m = 0; m < 4; ++m) _Pragma("unroll") for (int k = 0; k < 2; ++k) dst[m][k] = *(const PG8_LAS bf16x8*)(lds + PG8_SA(b, h) + aoff + m * 2048 + k * 1024); } while (0)
; #define PG8_LDB(dst, b, h) do { _Pragma("unroll") for (int n = 0; n < 2; ++n) _Pragma("unroll") for (int k = 0; k < 2; ++k) dst[n][k] = *(const PG8_LAS bf16x8*)(lds + PG8_SB(b, h) + boff + n * 2048 + k * 1024); } while (0)
; #define PG8_MMA(ai, bj, At, Bt) do { __builtin_amdgcn_s_setprio(1); _Pragma("unroll") for (int m = 0; m < 4; ++m) _Pragma("unroll") for (int n = 0; n < 2; ++n) _Pragma("unroll") for (int k = 0; k < 2; ++k) \
;         acc[ai][bj][m][n] = __builtin_amdgcn_mfma_f32_16x16x32_bf16(Bt[n][k], At[m][k], acc[ai][bj][m][n], 0, 0, 0); __builtin_amdgcn_s_setprio(0); } while (0)
; #define PG8_WAIT_V(n) asm volatile("s_waitcnt vmcnt(" #n ")" ::: "memory")
; #define PG8_WAIT_L(n) asm volatile("s_waitcnt lgkmcnt(" #n ")" ::: "memory")
; #define PG8_BAR __builtin_amdgcn_s_barrier()
; #define PG8_SCHED __builtin_amdgcn_sched_barrier(0)
; template <class Epi, class Sched, bool ALIGN_EPI = false, bool SP2 = false>
; __device__ __forceinline__ void gemm_phase(PG8_LAS unsigned char* lds, const Gemm g, const Sched& S, const Epi& E) {
;     ...
;             PG8_LDB(B0, 1, 0); PG8_LDB(B1, 1, 1); PG8_SCHED; PG8_LDA(At, 1, 0); PG8_STAGE(PG8_SA(0, 1), a2 + hstep, voffA);
;             PG8_WAIT_V(8); PG8_WAIT_L(0); PG8_BAR; PG8_MMA(0, 0, At, B0); PG8_MMA(0, 1, At, B1); PG8_BAR; PG8_SCHED;
	s_add_i32 s3, 0, 0x18000
	v_add_u32_e32 v155, s3, v149
	s_add_i32 s33, 0, 0x1c000
	ds_read_b128 v[144:147], v155
	ds_read_b128 v[156:159], v155 offset:1024
	ds_read_b128 v[160:163], v155 offset:2048
	ds_read_b128 v[164:167], v155 offset:3072
	v_add_u32_e32 v155, s33, v149
	ds_read_b128 v[168:171], v155
	ds_read_b128 v[172:175], v155 offset:1024
	ds_read_b128 v[176:179], v155 offset:2048
	ds_read_b128 v[182:185], v155 offset:3072
	s_add_u32 s62, s62, 0x20000
	s_addc_u32 s63, s63, 0
	s_mov_b32 m0, s57
	v_lshl_add_u64 v[230:231], s[62:63], 0, v[128:129]
	ds_read_b128 v[186:189], v153 offset:32768
	ds_read_b128 v[190:193], v153 offset:33792
	ds_read_b128 v[194:197], v153 offset:34816
	ds_read_b128 v[198:201], v153 offset:35840
	ds_read_b128 v[208:211], v153 offset:36864
	ds_read_b128 v[212:215], v153 offset:37888
	ds_read_b128 v[216:219], v153 offset:38912
	ds_read_b128 v[220:223], v153 offset:39936
	global_load_lds_dwordx4 v[230:231], off
	v_lshl_add_u64 v[230:231], s[62:63], 0, v[132:133]
	s_mov_b32 m0, s64
	s_nop 0
	global_load_lds_dwordx4 v[230:231], off
	s_waitcnt vmcnt(8)
	s_waitcnt lgkmcnt(0)
	s_barrier
	s_setprio 1
	s_waitcnt lgkmcnt(0)
	v_mfma_f32_16x16x32_bf16 v[124:127], v[144:147], v[186:189], v[124:127]
	v_mfma_f32_16x16x32_bf16 v[120:123], v[160:163], v[186:189], v[120:123]
	v_mfma_f32_16x16x32_bf16 v[108:111], v[144:147], v[194:197], v[108:111]
	v_mfma_f32_16x16x32_bf16 v[104:107], v[160:163], v[194:197], v[104:107]
	v_mfma_f32_16x16x32_bf16 v[92:95], v[144:147], v[208:211], v[92:95]
	v_mfma_f32_16x16x32_bf16 v[88:91], v[160:163], v[208:211], v[88:91]
	v_mfma_f32_16x16x32_bf16 v[76:79], v[144:147], v[216:219], v[76:79]
	v_mfma_f32_16x16x32_bf16 v[72:75], v[160:163], v[216:219], v[72:75]
	v_mfma_f32_16x16x32_bf16 v[124:127], v[156:159], v[190:193], v[124:127]
	v_mfma_f32_16x16x32_bf16 v[120:123], v[164:167], v[190:193], v[120:123]
	v_mfma_f32_16x16x32_bf16 v[108:111], v[156:159], v[198:201], v[108:111]
	v_mfma_f32_16x16x32_bf16 v[104:107], v[164:167], v[198:201], v[104:107]
	v_mfma_f32_16x16x32_bf16 v[92:95], v[156:159], v[212:215], v[92:95]
	v_mfma_f32_16x16x32_bf16 v[88:91], v[164:167], v[212:215], v[88:91]
	v_mfma_f32_16x16x32_bf16 v[76:79], v[156:159], v[220:223], v[76:79]
	v_mfma_f32_16x16x32_bf16 v[72:75], v[164:167], v[220:223], v[72:75]
	s_setprio 0
	s_setprio 1
	v_mfma_f32_16x16x32_bf16 v[116:119], v[168:171], v[186:189], v[116:119]
	v_mfma_f32_16x16x32_bf16 v[112:115], v[176:179], v[186:189], v[112:115]
	v_mfma_f32_16x16x32_bf16 v[100:103], v[168:171], v[194:197], v[100:103]
	v_mfma_f32_16x16x32_bf16 v[96:99], v[176:179], v[194:197], v[96:99]
	v_mfma_f32_16x16x32_bf16 v[84:87], v[168:171], v[208:211], v[84:87]
	v_mfma_f32_16x16x32_bf16 v[80:83], v[176:179], v[208:211], v[80:83]
	v_mfma_f32_16x16x32_bf16 v[68:71], v[168:171], v[216:219], v[68:71]
	v_mfma_f32_16x16x32_bf16 v[64:67], v[176:179], v[216:219], v[64:67]
	v_mfma_f32_16x16x32_bf16 v[116:119], v[172:175], v[190:193], v[116:119]
	v_mfma_f32_16x16x32_bf16 v[112:115], v[182:185], v[190:193], v[112:115]
	v_mfma_f32_16x16x32_bf16 v[100:103], v[172:175], v[198:201], v[100:103]
	v_mfma_f32_16x16x32_bf16 v[96:99], v[182:185], v[198:201], v[96:99]
	v_mfma_f32_16x16x32_bf16 v[84:87], v[172:175], v[212:215], v[84:87]
	v_mfma_f32_16x16x32_bf16 v[80:83], v[182:185], v[212:215], v[80:83]
	v_mfma_f32_16x16x32_bf16 v[68:71], v[172:175], v[220:223], v[68:71]
	v_mfma_f32_16x16x32_bf16 v[64:67], v[182:185], v[220:223], v[64:67]
	s_setprio 0
	s_barrier
; #define PG8_STAGE(bufoff, gbase, voff) do { _Pragma("unroll") for (int _i = 0; _i < 2; ++_i) \
;         __builtin_amdgcn_global_load_lds((const unsigned*)((const char*)(gbase) + (voff)[_i]), (PG8_LAS unsigned*)(lds + (bufoff) + ldsw + _i * 8192), 16, 0, 0); } while (0)
; #define PG8_LDA(dst, b, h) do { _Pragma("unroll") for (int m = 0; m < 4; ++m) _Pragma("unroll") for (int k = 0; k < 2; ++k) dst[m][k] = *(const PG8_LAS bf16x8*)(lds + PG8_SA(b, h) + aoff + m * 2048 + k * 1024); } while (0)
; #define PG8_MMA(ai, bj, At, Bt) do { __builtin_amdgcn_s_setprio(1); _Pragma("unroll") for (int m = 0; m < 4; ++m) _Pragma("unroll") for (int n = 0; n < 2; ++n) _Pragma("unroll") for (int k = 0; k < 2; ++k) \
;         acc[ai][bj][m][n] = __builtin_amdgcn_mfma_f32_16x16x32_bf16(Bt[n][k], At[m][k], acc[ai][bj][m][n], 0, 0, 0); __builtin_amdgcn_s_setprio(0); } while (0)
; #define PG8_WAIT_V(n) asm volatile("s_waitcnt vmcnt(" #n ")" ::: "memory")
; #define PG8_WAIT_L(n) asm volatile("s_waitcnt lgkmcnt(" #n ")" ::: "memory")
; #define PG8_BAR __builtin_amdgcn_s_barrier()
; #define PG8_SCHED __builtin_amdgcn_sched_barrier(0)
; template <class Epi, class Sched, bool ALIGN_EPI = false, bool SP2 = false>
; __device__ __forceinline__ void gemm_phase(PG8_LAS unsigned char* lds, const Gemm g, const Sched& S, const Epi& E) {
;     ...
;             PG8_LDA(At, 1, 1); PG8_STAGE(PG8_SB(1, 0), b3, voffB); PG8_STAGE(PG8_SB(1, 1), b3 + hstep, voffB); PG8_STAGE(PG8_SA(1, 0), a3, voffA);
;             PG8_WAIT_V(8); PG8_WAIT_L(0); PG8_BAR; PG8_MMA(1, 0, At, B0); PG8_MMA(1, 1, At, B1); PG8_BAR; PG8_SCHED;
;     ...
;         }
;         if constexpr (ALIGN_EPI) { if (wr == 0) PG8_BAR; }
;         if constexpr (!Epi::AFTER_DRAIN) { E(acc, cur, wr, wc, fr, fq); S.done(cur); }
;         if (!has_next) break;
	s_add_i32 s3, s3, s14
	v_lshl_add_u64 v[202:203], v[202:203], 0, s[38:39]
	s_mov_b32 m0, s3
	ds_read_b128 v[186:189], v153 offset:49152
	ds_read_b128 v[190:193], v153 offset:50176
	ds_read_b128 v[194:197], v153 offset:51200
	ds_read_b128 v[198:201], v153 offset:52224
	ds_read_b128 v[208:211], v153 offset:53248
	ds_read_b128 v[212:215], v153 offset:54272
	ds_read_b128 v[216:219], v153 offset:55296
	ds_read_b128 v[220:223], v153 offset:56320
	global_load_lds_dwordx4 v[202:203], off
	s_add_i32 m0, s3, 0x2000
	s_add_u32 s60, s60, 0x20080
	v_lshl_add_u64 v[202:203], v[224:225], 0, s[38:39]
	s_addc_u32 s61, s61, 0
	s_add_i32 s3, s33, s14
	global_load_lds_dwordx4 v[202:203], off
	v_lshl_add_u64 v[202:203], s[60:61], 0, v[130:131]
	s_mov_b32 m0, s3
	s_nop 0
	global_load_lds_dwordx4 v[202:203], off
	v_lshl_add_u64 v[202:203], s[60:61], 0, v[134:135]
	s_add_i32 m0, s3, 0x2000
	s_nop 0
	global_load_lds_dwordx4 v[202:203], off
	s_waitcnt vmcnt(6)
	s_waitcnt lgkmcnt(0)
	s_barrier
	s_setprio 1
	s_waitcnt lgkmcnt(0)
	v_mfma_f32_16x16x32_bf16 v[60:63], v[144:147], v[186:189], v[60:63]
	v_mfma_f32_16x16x32_bf16 v[56:59], v[160:163], v[186:189], v[56:59]
	v_mfma_f32_16x16x32_bf16 v[44:47], v[144:147], v[194:197], v[44:47]
	v_mfma_f32_16x16x32_bf16 v[40:43], v[160:163], v[194:197], v[40:43]
	v_mfma_f32_16x16x32_bf16 v[28:31], v[144:147], v[208:211], v[28:31]
	v_mfma_f32_16x16x32_bf16 v[24:27], v[160:163], v[208:211], v[24:27]
	v_mfma_f32_16x16x32_bf16 v[12:15], v[144:147], v[216:219], v[12:15]
	v_mfma_f32_16x16x32_bf16 v[8:11], v[160:163], v[216:219], v[8:11]
	v_mfma_f32_16x16x32_bf16 v[60:63], v[156:159], v[190:193], v[60:63]
	v_mfma_f32_16x16x32_bf16 v[56:59], v[164:167], v[190:193], v[56:59]
	v_mfma_f32_16x16x32_bf16 v[44:47], v[156:159], v[198:201], v[44:47]
	v_mfma_f32_16x16x32_bf16 v[40:43], v[164:167], v[198:201], v[40:43]
	v_mfma_f32_16x16x32_bf16 v[28:31], v[156:159], v[212:215], v[28:31]
	v_mfma_f32_16x16x32_bf16 v[24:27], v[164:167], v[212:215], v[24:27]
	v_mfma_f32_16x16x32_bf16 v[12:15], v[156:159], v[220:223], v[12:15]
	v_lshl_add_u64 v[202:203], v[226:227], 0, s[38:39]
	s_mov_b32 m0, s66
	s_nop 0
	global_load_lds_dwordx4 v[202:203], off
	v_mfma_f32_16x16x32_bf16 v[8:11], v[164:167], v[220:223], v[8:11]
	s_setprio 0
	s_setprio 1
	v_mfma_f32_16x16x32_bf16 v[52:55], v[168:171], v[186:189], v[52:55]
	v_mfma_f32_16x16x32_bf16 v[48:51], v[176:179], v[186:189], v[48:51]
	v_mfma_f32_16x16x32_bf16 v[36:39], v[168:171], v[194:197], v[36:39]
	v_mfma_f32_16x16x32_bf16 v[32:35], v[176:179], v[194:197], v[32:35]
	v_mfma_f32_16x16x32_bf16 v[20:23], v[168:171], v[208:211], v[20:23]
	v_mfma_f32_16x16x32_bf16 v[16:19], v[176:179], v[208:211], v[16:19]
	v_mfma_f32_16x16x32_bf16 v[4:7], v[168:171], v[216:219], v[4:7]
	v_mfma_f32_16x16x32_bf16 v[0:3], v[176:179], v[216:219], v[0:3]
	v_mfma_f32_16x16x32_bf16 v[52:55], v[172:175], v[190:193], v[52:55]
	v_mfma_f32_16x16x32_bf16 v[48:51], v[182:185], v[190:193], v[48:51]
	v_mfma_f32_16x16x32_bf16 v[36:39], v[172:175], v[198:201], v[36:39]
	v_mfma_f32_16x16x32_bf16 v[32:35], v[182:185], v[198:201], v[32:35]
	v_mfma_f32_16x16x32_bf16 v[20:23], v[172:175], v[212:215], v[20:23]
	v_mfma_f32_16x16x32_bf16 v[16:19], v[182:185], v[212:215], v[16:19]
	v_mfma_f32_16x16x32_bf16 v[4:7], v[172:175], v[220:223], v[4:7]
	v_lshl_add_u64 v[202:203], v[228:229], 0, s[38:39]
	s_mov_b32 m0, s67
	s_nop 0
	global_load_lds_dwordx4 v[202:203], off
	v_mfma_f32_16x16x32_bf16 v[0:3], v[182:185], v[220:223], v[0:3]
	s_setprio 0
	s_barrier
	s_add_i32 s87, s87, 2
	s_add_u32 s58, s58, 0x100
	s_addc_u32 s59, s59, 0
	s_add_u32 s85, s85, 0x100
	s_addc_u32 s86, s86, 0
	s_cmp_gt_u32 s87, 5
	s_cbranch_scc0 .LBB0_873
	s_and_b64 vcc, exec, s[42:43]
	s_cbranch_vccz .LBB0_876
	s_barrier

; #define PG8_STAGE(bufoff, gbase, voff) do { _Pragma("unroll") for (int _i = 0; _i < 2; ++_i) \
;         __builtin_amdgcn_global_load_lds((const unsigned*)((const char*)(gbase) + (voff)[_i]), (PG8_LAS unsigned*)(lds + (bufoff) + ldsw + _i * 8192), 16, 0, 0); } while (0)
; #define PG8_LDA(dst, b, h) do { _Pragma("unroll") for (int m = 0; m < 4; ++m) _Pragma("unroll") for (int k = 0; k < 2; ++k) dst[m][k] = *(const PG8_LAS bf16x8*)(lds + PG8_SA(b, h) + aoff + m * 2048 + k * 1024); } while (0)
; #define PG8_LDB(dst, b, h) do { _Pragma("unroll") for (int n = 0; n < 2; ++n) _Pragma("unroll") for (int k = 0; k < 2; ++k) dst[n][k] = *(const PG8_LAS bf16x8*)(lds + PG8_SB(b, h) + boff + n * 2048 + k * 1024); } while (0)
; #define PG8_MMA(ai, bj, At, Bt) do { __builtin_amdgcn_s_setprio(1); _Pragma("unroll") for (int m = 0; m < 4; ++m) _Pragma("unroll") for (int n = 0; n < 2; ++n) _Pragma("unroll") for (int k = 0; k < 2; ++k) \
;         acc[ai][bj][m][n] = __builtin_amdgcn_mfma_f32_16x16x32_bf16(Bt[n][k], At[m][k], acc[ai][bj][m][n], 0, 0, 0); __builtin_amdgcn_s_setprio(0); } while (0)
; #define PG8_BAR __builtin_amdgcn_s_barrier()
; template <class Epi, class Sched, bool ALIGN_EPI = false, bool SP2 = false>
; __device__ __forceinline__ void gemm_phase(PG8_LAS unsigned char* lds, const Gemm g, const Sched& S, const Epi& E) {
;     ...
;         const bool has_next = S.next(ui + 1, nxt);
;         const char* nA = has_next ? (const char*)g.A + (size_t)nxt.pm * tstep : cA; const char* nB = has_next ? (const char*)g.Bt + (size_t)nxt.pn * tstep : cB;
;         for (int t = 0; t < nt; t += 2) {
;             const bool last = (t == nt - 2);
;             const char* a1 = cA + (size_t)(t + 1) * kstep;
;             const char* a2 = last ? nA : cA + (size_t)(t + 2) * kstep; const char* b2 = last ? nB : cB + (size_t)(t + 2) * kstep;
;             const char* a3 = a2 + kstep; const char* b3 = b2 + kstep;
;             if (last && has_next) S.a_ready(nxt);
;             if constexpr (SP2) {
;             PG8_LDB(B0, 0, 0); PG8_LDB(B1, 0, 1); PG8_SCHED; PG8_LDA(At, 0, 0); PG8_STAGE(PG8_SA(1, 1), a1 + hstep, voffA);
;             PG8_WAIT_V(8); PG8_WAIT_L(0); PG8_BAR; PG8_MMA(0, 0, At, B0); PG8_MMA(0, 1, At, B1); PG8_BAR; PG8_SCHED;
;             PG8_LDA(At, 0, 1); PG8_STAGE(PG8_SB(0, 0), b2, voffB); PG8_STAGE(PG8_SB(0, 1), b2 + hstep, voffB); PG8_STAGE(PG8_SA(0, 0), a2, voffA);
.LBB0_956:
	s_ashr_i32 s45, s44, 31
	s_lshl_b64 s[48:49], s[44:45], 19
	s_add_u32 s48, s22, s48
	s_addc_u32 s49, s23, s49
	s_and_b64 s[50:51], s[10:11], exec
	s_cselect_b32 s45, s49, s55
	s_cselect_b32 s75, s48, s54
	s_ashr_i32 s43, s42, 31
	s_lshl_b64 s[50:51], s[42:43], 19
	v_readlane_b32 s3, v250, 18
	s_add_u32 s50, s3, s50
	v_readlane_b32 s3, v250, 19
	s_addc_u32 s51, s3, s51
	s_and_b64 s[58:59], s[10:11], exec
	s_cselect_b32 s43, s51, s57
	s_cselect_b32 s76, s50, s56
	s_add_u32 s54, s54, 0x40080
	s_addc_u32 s55, s55, 0
	s_add_u32 s77, s56, 0x100
	s_addc_u32 s82, s57, 0
	s_mov_b32 s83, -2
	ds_read_b128 v[144:147], v155
	ds_read_b128 v[148:151], v155 offset:1024
	ds_read_b128 v[160:163], v155 offset:2048
	ds_read_b128 v[164:167], v155 offset:3072
	ds_read_b128 v[168:171], v156
	ds_read_b128 v[172:175], v156 offset:1024
	ds_read_b128 v[176:179], v156 offset:2048
	ds_read_b128 v[182:185], v156 offset:3072
	s_add_u32 s3, s54, 0xfffc0080
	s_addc_u32 s33, s55, -1
	s_cmp_eq_u32 s83, 12
	s_cselect_b32 s59, s45, s33
	s_cselect_b32 s58, s75, s3
	s_cselect_b32 s57, s43, s82
	s_cselect_b32 s56, s76, s77
	v_lshl_add_u64 v[202:203], s[54:55], 0, v[136:137]
	s_add_i32 m0, s34, 0xc000
	ds_read_b128 v[186:189], v157
	ds_read_b128 v[190:193], v157 offset:1024
	ds_read_b128 v[194:197], v157 offset:2048
	ds_read_b128 v[198:201], v157 offset:3072
	ds_read_b128 v[208:211], v157 offset:4096
	ds_read_b128 v[212:215], v157 offset:5120
	ds_read_b128 v[216:219], v157 offset:6144
	ds_read_b128 v[220:223], v157 offset:7168
	global_load_lds_dwordx4 v[202:203], off
	v_lshl_add_u64 v[202:203], s[54:55], 0, v[138:139]
	s_add_i32 m0, s34, 0xe000
	s_nop 0
	global_load_lds_dwordx4 v[202:203], off
	s_waitcnt vmcnt(8)
	s_waitcnt lgkmcnt(0)
	s_barrier
	s_setprio 1
	s_waitcnt lgkmcnt(0)
	v_mfma_f32_16x16x32_bf16 v[124:127], v[144:147], v[186:189], 0
	v_mfma_f32_16x16x32_bf16 v[120:123], v[160:163], v[186:189], 0
	v_mfma_f32_16x16x32_bf16 v[108:111], v[144:147], v[194:197], 0
	v_mfma_f32_16x16x32_bf16 v[104:107], v[160:163], v[194:197], 0
	v_mfma_f32_16x16x32_bf16 v[92:95], v[144:147], v[208:211], 0
	v_mfma_f32_16x16x32_bf16 v[88:91], v[160:163], v[208:211], 0
	v_mfma_f32_16x16x32_bf16 v[76:79], v[144:147], v[216:219], 0
	v_mfma_f32_16x16x32_bf16 v[72:75], v[160:163], v[216:219], 0
	v_mfma_f32_16x16x32_bf16 v[124:127], v[148:151], v[190:193], v[124:127]
	v_mfma_f32_16x16x32_bf16 v[120:123], v[164:167], v[190:193], v[120:123]
	v_mfma_f32_16x16x32_bf16 v[108:111], v[148:151], v[198:201], v[108:111]
	v_mfma_f32_16x16x32_bf16 v[104:107], v[164:167], v[198:201], v[104:107]
	v_mfma_f32_16x16x32_bf16 v[92:95], v[148:151], v[212:215], v[92:95]
	v_mfma_f32_16x16x32_bf16 v[88:91], v[164:167], v[212:215], v[88:91]
	v_mfma_f32_16x16x32_bf16 v[76:79], v[148:151], v[220:223], v[76:79]
	v_mfma_f32_16x16x32_bf16 v[72:75], v[164:167], v[220:223], v[72:75]
	s_setprio 0
	s_setprio 1
	v_mfma_f32_16x16x32_bf16 v[116:119], v[168:171], v[186:189], 0
	v_mfma_f32_16x16x32_bf16 v[112:115], v[176:179], v[186:189], 0
	v_mfma_f32_16x16x32_bf16 v[100:103], v[168:171], v[194:197], 0
	v_mfma_f32_16x16x32_bf16 v[96:99], v[176:179], v[194:197], 0
	v_mfma_f32_16x16x32_bf16 v[84:87], v[168:171], v[208:211], 0
	v_mfma_f32_16x16x32_bf16 v[80:83], v[176:179], v[208:211], 0
	v_mfma_f32_16x16x32_bf16 v[68:71], v[168:171], v[216:219], 0
	v_mfma_f32_16x16x32_bf16 v[64:67], v[176:179], v[216:219], 0
	v_mfma_f32_16x16x32_bf16 v[116:119], v[172:175], v[190:193], v[116:119]
	v_mfma_f32_16x16x32_bf16 v[112:115], v[182:185], v[190:193], v[112:115]
	v_mfma_f32_16x16x32_bf16 v[100:103], v[172:175], v[198:201], v[100:103]
	v_mfma_f32_16x16x32_bf16 v[96:99], v[182:185], v[198:201], v[96:99]
	v_mfma_f32_16x16x32_bf16 v[84:87], v[172:175], v[212:215], v[84:87]
	v_mfma_f32_16x16x32_bf16 v[80:83], v[182:185], v[212:215], v[80:83]
	v_mfma_f32_16x16x32_bf16 v[68:71], v[172:175], v[220:223], v[68:71]
	v_mfma_f32_16x16x32_bf16 v[64:67], v[182:185], v[220:223], v[64:67]
	s_setprio 0
	s_barrier
	s_add_i32 s3, s65, s14
	v_lshl_add_u64 v[202:203], s[56:57], 0, v[132:133]
	s_mov_b32 m0, s3
	ds_read_b128 v[186:189], v157 offset:16384
	ds_read_b128 v[190:193], v157 offset:17408
	ds_read_b128 v[194:197], v157 offset:18432
	ds_read_b128 v[198:201], v157 offset:19456
	ds_read_b128 v[208:211], v157 offset:20480
	ds_read_b128 v[212:215], v157 offset:21504
	ds_read_b128 v[216:219], v157 offset:22528
	ds_read_b128 v[220:223], v157 offset:23552
	global_load_lds_dwordx4 v[202:203], off
	s_add_i32 m0, s3, 0x2000
	s_add_u32 s78, s56, 0x40000
	v_lshl_add_u64 v[224:225], s[56:57], 0, v[128:129]
	s_addc_u32 s79, s57, 0
	s_add_i32 s3, s66, s14
	global_load_lds_dwordx4 v[224:225], off
	v_lshl_add_u64 v[226:227], s[78:79], 0, v[132:133]
	s_mov_b32 m0, s3
	global_load_lds_dwordx4 v[226:227], off
	v_lshl_add_u64 v[226:227], s[78:79], 0, v[128:129]
	s_add_i32 m0, s3, 0x2000
	s_nop 0
	global_load_lds_dwordx4 v[226:227], off
	s_waitcnt vmcnt(6)
	s_waitcnt lgkmcnt(0)
	s_barrier
; #define PG8_STAGE(bufoff, gbase, voff) do { _Pragma("unroll") for (int _i = 0; _i < 2; ++_i) \
;         __builtin_amdgcn_global_load_lds((const unsigned*)((const char*)(gbase) + (voff)[_i]), (PG8_LAS unsigned*)(lds + (bufoff) + ldsw + _i * 8192), 16, 0, 0); } while (0)
; #define PG8_LDA(dst, b, h) do { _Pragma("unroll") for (int m = 0; m < 4; ++m) _Pragma("unroll") for (int k = 0; k < 2; ++k) dst[m][k] = *(const PG8_LAS bf16x8*)(lds + PG8_SA(b, h) + aoff + m * 2048 + k * 1024); } while (0)
; #define PG8_LDB(dst, b, h) do { _Pragma("unroll") for (int n = 0; n < 2; ++n) _Pragma("unroll") for (int k = 0; k < 2; ++k) dst[n][k] = *(const PG8_LAS bf16x8*)(lds + PG8_SB(b, h) + boff + n * 2048 + k * 1024); } while (0)
; #define PG8_MMA(ai, bj, At, Bt) do { __builtin_amdgcn_s_setprio(1); _Pragma("unroll") for (int m = 0; m < 4; ++m) _Pragma("unroll") for (int n = 0; n < 2; ++n) _Pragma("unroll") for (int k = 0; k < 2; ++k) \
;         acc[ai][bj][m][n] = __builtin_amdgcn_mfma_f32_16x16x32_bf16(Bt[n][k], At[m][k], acc[ai][bj][m][n], 0, 0, 0); __builtin_amdgcn_s_setprio(0); } while (0)
; #define PG8_WAIT_V(n) asm volatile("s_waitcnt vmcnt(" #n ")" ::: "memory")
; #define PG8_WAIT_L(n) asm volatile("s_waitcnt lgkmcnt(" #n ")" ::: "memory")
; #define PG8_BAR __builtin_amdgcn_s_barrier()
; #define PG8_SCHED __builtin_amdgcn_sched_barrier(0)
; template <class Epi, class Sched, bool ALIGN_EPI = false, bool SP2 = false>
; __device__ __forceinline__ void gemm_phase(PG8_LAS unsigned char* lds, const Gemm g, const Sched& S, const Epi& E) {
;     ...
;             PG8_LDA(At, 0, 1); PG8_STAGE(PG8_SB(0, 0), b2, voffB); PG8_STAGE(PG8_SB(0, 1), b2 + hstep, voffB); PG8_STAGE(PG8_SA(0, 0), a2, voffA);
;             PG8_WAIT_V(8); PG8_WAIT_L(0); PG8_BAR; PG8_MMA(1, 0, At, B0); PG8_MMA(1, 1, At, B1); PG8_BAR; PG8_SCHED;
;             PG8_LDB(B0, 1, 0); PG8_LDB(B1, 1, 1); PG8_SCHED; PG8_LDA(At, 1, 0); PG8_STAGE(PG8_SA(0, 1), a2 + hstep, voffA);
;             PG8_WAIT_V(8); PG8_WAIT_L(0); PG8_BAR; PG8_MMA(0, 0, At, B0); PG8_MMA(0, 1, At, B1); PG8_BAR; PG8_SCHED;
	s_setprio 1
	s_waitcnt lgkmcnt(0)
	v_mfma_f32_16x16x32_bf16 v[60:63], v[144:147], v[186:189], 0
	v_mfma_f32_16x16x32_bf16 v[56:59], v[160:163], v[186:189], 0
	v_mfma_f32_16x16x32_bf16 v[44:47], v[144:147], v[194:197], 0
	v_mfma_f32_16x16x32_bf16 v[40:43], v[160:163], v[194:197], 0
	v_mfma_f32_16x16x32_bf16 v[28:31], v[144:147], v[208:211], 0
	v_mfma_f32_16x16x32_bf16 v[24:27], v[160:163], v[208:211], 0
	v_mfma_f32_16x16x32_bf16 v[12:15], v[144:147], v[216:219], 0
	v_mfma_f32_16x16x32_bf16 v[8:11], v[160:163], v[216:219], 0
	v_mfma_f32_16x16x32_bf16 v[60:63], v[148:151], v[190:193], v[60:63]
	v_mfma_f32_16x16x32_bf16 v[56:59], v[164:167], v[190:193], v[56:59]
	v_mfma_f32_16x16x32_bf16 v[44:47], v[148:151], v[198:201], v[44:47]
	v_mfma_f32_16x16x32_bf16 v[40:43], v[164:167], v[198:201], v[40:43]
	v_mfma_f32_16x16x32_bf16 v[28:31], v[148:151], v[212:215], v[28:31]
	v_mfma_f32_16x16x32_bf16 v[24:27], v[164:167], v[212:215], v[24:27]
	v_mfma_f32_16x16x32_bf16 v[12:15], v[148:151], v[220:223], v[12:15]
	v_lshl_add_u64 v[226:227], s[58:59], 0, v[134:135]
	s_mov_b32 m0, s34
	s_nop 0
	global_load_lds_dwordx4 v[226:227], off
	v_mfma_f32_16x16x32_bf16 v[8:11], v[164:167], v[220:223], v[8:11]
	s_setprio 0
	s_setprio 1
	v_mfma_f32_16x16x32_bf16 v[52:55], v[168:171], v[186:189], 0
	v_mfma_f32_16x16x32_bf16 v[48:51], v[176:179], v[186:189], 0
	v_mfma_f32_16x16x32_bf16 v[36:39], v[168:171], v[194:197], 0
	v_mfma_f32_16x16x32_bf16 v[32:35], v[176:179], v[194:197], 0
	v_mfma_f32_16x16x32_bf16 v[20:23], v[168:171], v[208:211], 0
	v_mfma_f32_16x16x32_bf16 v[16:19], v[176:179], v[208:211], 0
	v_mfma_f32_16x16x32_bf16 v[4:7], v[168:171], v[216:219], 0
	v_mfma_f32_16x16x32_bf16 v[0:3], v[176:179], v[216:219], 0
	v_mfma_f32_16x16x32_bf16 v[52:55], v[172:175], v[190:193], v[52:55]
	v_mfma_f32_16x16x32_bf16 v[48:51], v[182:185], v[190:193], v[48:51]
	v_mfma_f32_16x16x32_bf16 v[36:39], v[172:175], v[198:201], v[36:39]
	v_mfma_f32_16x16x32_bf16 v[32:35], v[182:185], v[198:201], v[32:35]
	v_mfma_f32_16x16x32_bf16 v[20:23], v[172:175], v[212:215], v[20:23]
	v_mfma_f32_16x16x32_bf16 v[16:19], v[182:185], v[212:215], v[16:19]
	v_mfma_f32_16x16x32_bf16 v[4:7], v[172:175], v[220:223], v[4:7]
	v_lshl_add_u64 v[228:229], s[58:59], 0, v[130:131]
	s_mov_b32 m0, s53
	s_nop 0
	global_load_lds_dwordx4 v[228:229], off
	v_mfma_f32_16x16x32_bf16 v[0:3], v[182:185], v[220:223], v[0:3]
	s_setprio 0
	s_barrier
	s_add_i32 s3, 0, 0x18000
	v_add_u32_e32 v159, s3, v153
	s_add_i32 s33, 0, 0x1c000
	ds_read_b128 v[144:147], v159
	ds_read_b128 v[148:151], v159 offset:1024
	ds_read_b128 v[160:163], v159 offset:2048
	ds_read_b128 v[164:167], v159 offset:3072
	v_add_u32_e32 v159, s33, v153
	ds_read_b128 v[168:171], v159
	ds_read_b128 v[172:175], v159 offset:1024
	ds_read_b128 v[176:179], v159 offset:2048
	ds_read_b128 v[182:185], v159 offset:3072
	s_add_u32 s58, s58, 0x40000
	s_addc_u32 s59, s59, 0
	s_mov_b32 m0, s60
	v_lshl_add_u64 v[230:231], s[58:59], 0, v[134:135]
	ds_read_b128 v[186:189], v157 offset:32768
	ds_read_b128 v[190:193], v157 offset:33792
	ds_read_b128 v[194:197], v157 offset:34816
	ds_read_b128 v[198:201], v157 offset:35840
	ds_read_b128 v[208:211], v157 offset:36864
	ds_read_b128 v[212:215], v157 offset:37888
	ds_read_b128 v[216:219], v157 offset:38912
	ds_read_b128 v[220:223], v157 offset:39936
	global_load_lds_dwordx4 v[230:231], off
	v_lshl_add_u64 v[230:231], s[58:59], 0, v[130:131]
	s_mov_b32 m0, s61
	s_nop 0
	global_load_lds_dwordx4 v[230:231], off
	s_waitcnt vmcnt(8)
	s_waitcnt lgkmcnt(0)
	s_barrier
	s_setprio 1
	s_waitcnt lgkmcnt(0)
	v_mfma_f32_16x16x32_bf16 v[124:127], v[144:147], v[186:189], v[124:127]
	v_mfma_f32_16x16x32_bf16 v[120:123], v[160:163], v[186:189], v[120:123]
	v_mfma_f32_16x16x32_bf16 v[108:111], v[144:147], v[194:197], v[108:111]
	v_mfma_f32_16x16x32_bf16 v[104:107], v[160:163], v[194:197], v[104:107]
	v_mfma_f32_16x16x32_bf16 v[92:95], v[144:147], v[208:211], v[92:95]
	v_mfma_f32_16x16x32_bf16 v[88:91], v[160:163], v[208:211], v[88:91]
	v_mfma_f32_16x16x32_bf16 v[76:79], v[144:147], v[216:219], v[76:79]
	v_mfma_f32_16x16x32_bf16 v[72:75], v[160:163], v[216:219], v[72:75]
	v_mfma_f32_16x16x32_bf16 v[124:127], v[148:151], v[190:193], v[124:127]
	v_mfma_f32_16x16x32_bf16 v[120:123], v[164:167], v[190:193], v[120:123]
	v_mfma_f32_16x16x32_bf16 v[108:111], v[148:151], v[198:201], v[108:111]
	v_mfma_f32_16x16x32_bf16 v[104:107], v[164:167], v[198:201], v[104:107]
	v_mfma_f32_16x16x32_bf16 v[92:95], v[148:151], v[212:215], v[92:95]
	v_mfma_f32_16x16x32_bf16 v[88:91], v[164:167], v[212:215], v[88:91]
	v_mfma_f32_16x16x32_bf16 v[76:79], v[148:151], v[220:223], v[76:79]
	v_mfma_f32_16x16x32_bf16 v[72:75], v[164:167], v[220:223], v[72:75]
	s_setprio 0
	s_setprio 1
	v_mfma_f32_16x16x32_bf16 v[116:119], v[168:171], v[186:189], v[116:119]
	v_mfma_f32_16x16x32_bf16 v[112:115], v[176:179], v[186:189], v[112:115]
	v_mfma_f32_16x16x32_bf16 v[100:103], v[168:171], v[194:197], v[100:103]
	v_mfma_f32_16x16x32_bf16 v[96:99], v[176:179], v[194:197], v[96:99]
	v_mfma_f32_16x16x32_bf16 v[84:87], v[168:171], v[208:211], v[84:87]
	v_mfma_f32_16x16x32_bf16 v[80:83], v[176:179], v[208:211], v[80:83]
	v_mfma_f32_16x16x32_bf16 v[68:71], v[168:171], v[216:219], v[68:71]
	v_mfma_f32_16x16x32_bf16 v[64:67], v[176:179], v[216:219], v[64:67]
	v_mfma_f32_16x16x32_bf16 v[116:119], v[172:175], v[190:193], v[116:119]
	v_mfma_f32_16x16x32_bf16 v[112:115], v[182:185], v[190:193], v[112:115]
	v_mfma_f32_16x16x32_bf16 v[100:103], v[172:175], v[198:201], v[100:103]
	v_mfma_f32_16x16x32_bf16 v[96:99], v[182:185], v[198:201], v[96:99]
	v_mfma_f32_16x16x32_bf16 v[84:87], v[172:175], v[212:215], v[84:87]
	v_mfma_f32_16x16x32_bf16 v[80:83], v[182:185], v[212:215], v[80:83]
	v_mfma_f32_16x16x32_bf16 v[68:71], v[172:175], v[220:223], v[68:71]
	v_mfma_f32_16x16x32_bf16 v[64:67], v[182:185], v[220:223], v[64:67]
	s_setprio 0
	s_barrier
; #define PG8_STAGE(bufoff, gbase, voff) do { _Pragma("unroll") for (int _i = 0; _i < 2; ++_i) \
;         __builtin_amdgcn_global_load_lds((const unsigned*)((const char*)(gbase) + (voff)[_i]), (PG8_LAS unsigned*)(lds + (bufoff) + ldsw + _i * 8192), 16, 0, 0); } while (0)
; #define PG8_LDA(dst, b, h) do { _Pragma("unroll") for (int m = 0; m < 4; ++m) _Pragma("unroll") for (int k = 0; k < 2; ++k) dst[m][k] = *(const PG8_LAS bf16x8*)(lds + PG8_SA(b, h) + aoff + m * 2048 + k * 1024); } while (0)
; #define PG8_LDB(dst, b, h) do { _Pragma("unroll") for (int n = 0; n < 2; ++n) _Pragma("unroll") for (int k = 0; k < 2; ++k) dst[n][k] = *(const PG8_LAS bf16x8*)(lds + PG8_SB(b, h) + boff + n * 2048 + k * 1024); } while (0)
; #define PG8_MMA(ai, bj, At, Bt) do { __builtin_amdgcn_s_setprio(1); _Pragma("unroll") for (int m = 0; m < 4; ++m) _Pragma("unroll") for (int n = 0; n < 2; ++n) _Pragma("unroll") for (int k = 0; k < 2; ++k) \
;         acc[ai][bj][m][n] = __builtin_amdgcn_mfma_f32_16x16x32_bf16(Bt[n][k], At[m][k], acc[ai][bj][m][n], 0, 0, 0); __builtin_amdgcn_s_setprio(0); } while (0)
; #define PG8_WAIT_V(n) asm volatile("s_waitcnt vmcnt(" #n ")" ::: "memory")
; template <class Epi, class Sched, bool ALIGN_EPI = false, bool SP2 = false>
; __device__ __forceinline__ void gemm_phase(PG8_LAS unsigned char* lds, const Gemm g, const Sched& S, const Epi& E) {
;     ...
;             PG8_LDB(B0, 0, 0); PG8_LDB(B1, 0, 1); PG8_SCHED; PG8_LDA(At, 0, 0); PG8_STAGE(PG8_SA(1, 1), a1 + hstep, voffA);
;             PG8_WAIT_V(8); PG8_WAIT_L(0); PG8_BAR; PG8_MMA(0, 0, At, B0); PG8_MMA(0, 1, At, B1); PG8_BAR; PG8_SCHED;
;             PG8_LDA(At, 0, 1); PG8_STAGE(PG8_SB(0, 0), b2, voffB); PG8_STAGE(PG8_SB(0, 1), b2 + hstep, voffB); PG8_STAGE(PG8_SA(0, 0), a2, voffA);
;             PG8_WAIT_V(8); PG8_WAIT_L(0); PG8_BAR; PG8_MMA(1, 0, At, B0); PG8_MMA(1, 1, At, B1); PG8_BAR; PG8_SCHED;
;             PG8_LDB(B0, 1, 0); PG8_LDB(B1, 1, 1); PG8_SCHED; PG8_LDA(At, 1, 0); PG8_STAGE(PG8_SA(0, 1), a2 + hstep, voffA);
;             PG8_WAIT_V(8); PG8_WAIT_L(0); PG8_BAR; PG8_MMA(0, 0, At, B0); PG8_MMA(0, 1, At, B1); PG8_BAR; PG8_SCHED;
;             PG8_LDA(At, 1, 1); PG8_STAGE(PG8_SB(1, 0), b3, voffB); PG8_STAGE(PG8_SB(1, 1), b3 + hstep, voffB); PG8_STAGE(PG8_SA(1, 0), a3, voffA);
;             PG8_WAIT_V(8); PG8_WAIT_L(0); PG8_BAR; PG8_MMA(1, 0, At, B0); PG8_MMA(1, 1, At, B1); PG8_BAR; PG8_SCHED;
	s_add_i32 s3, s3, s14
	v_lshl_add_u64 v[202:203], v[202:203], 0, s[36:37]
	s_mov_b32 m0, s3
	ds_read_b128 v[186:189], v157 offset:49152
	ds_read_b128 v[190:193], v157 offset:50176
	ds_read_b128 v[194:197], v157 offset:51200
	ds_read_b128 v[198:201], v157 offset:52224
	ds_read_b128 v[208:211], v157 offset:53248
	ds_read_b128 v[212:215], v157 offset:54272
	ds_read_b128 v[216:219], v157 offset:55296
	ds_read_b128 v[220:223], v157 offset:56320
	global_load_lds_dwordx4 v[202:203], off
	s_add_i32 m0, s3, 0x2000
	s_add_u32 s56, s56, 0x40080
	v_lshl_add_u64 v[202:203], v[224:225], 0, s[36:37]
	s_addc_u32 s57, s57, 0
	s_add_i32 s3, s33, s14
	global_load_lds_dwordx4 v[202:203], off
	v_lshl_add_u64 v[202:203], s[56:57], 0, v[132:133]
	s_mov_b32 m0, s3
	s_nop 0
	global_load_lds_dwordx4 v[202:203], off
	v_lshl_add_u64 v[202:203], s[56:57], 0, v[128:129]
	s_add_i32 m0, s3, 0x2000
	s_nop 0
	global_load_lds_dwordx4 v[202:203], off
	s_waitcnt vmcnt(6)
	s_waitcnt lgkmcnt(0)
	s_barrier
	s_setprio 1
	s_waitcnt lgkmcnt(0)
	v_mfma_f32_16x16x32_bf16 v[60:63], v[144:147], v[186:189], v[60:63]
	v_mfma_f32_16x16x32_bf16 v[56:59], v[160:163], v[186:189], v[56:59]
	v_mfma_f32_16x16x32_bf16 v[44:47], v[144:147], v[194:197], v[44:47]
	v_mfma_f32_16x16x32_bf16 v[40:43], v[160:163], v[194:197], v[40:43]
	v_mfma_f32_16x16x32_bf16 v[28:31], v[144:147], v[208:211], v[28:31]
	v_mfma_f32_16x16x32_bf16 v[24:27], v[160:163], v[208:211], v[24:27]
	v_mfma_f32_16x16x32_bf16 v[12:15], v[144:147], v[216:219], v[12:15]
	v_mfma_f32_16x16x32_bf16 v[8:11], v[160:163], v[216:219], v[8:11]
	v_mfma_f32_16x16x32_bf16 v[60:63], v[148:151], v[190:193], v[60:63]
	v_mfma_f32_16x16x32_bf16 v[56:59], v[164:167], v[190:193], v[56:59]
	v_mfma_f32_16x16x32_bf16 v[44:47], v[148:151], v[198:201], v[44:47]
	v_mfma_f32_16x16x32_bf16 v[40:43], v[164:167], v[198:201], v[40:43]
	v_mfma_f32_16x16x32_bf16 v[28:31], v[148:151], v[212:215], v[28:31]
	v_mfma_f32_16x16x32_bf16 v[24:27], v[164:167], v[212:215], v[24:27]
	v_mfma_f32_16x16x32_bf16 v[12:15], v[148:151], v[220:223], v[12:15]
	v_lshl_add_u64 v[202:203], v[226:227], 0, s[36:37]
	s_mov_b32 m0, s63
	s_nop 0
	global_load_lds_dwordx4 v[202:203], off
	v_mfma_f32_16x16x32_bf16 v[8:11], v[164:167], v[220:223], v[8:11]
	s_setprio 0
	s_setprio 1
	v_mfma_f32_16x16x32_bf16 v[52:55], v[168:171], v[186:189], v[52:55]
	v_mfma_f32_16x16x32_bf16 v[48:51], v[176:179], v[186:189], v[48:51]
	v_mfma_f32_16x16x32_bf16 v[36:39], v[168:171], v[194:197], v[36:39]
	v_mfma_f32_16x16x32_bf16 v[32:35], v[176:179], v[194:197], v[32:35]
	v_mfma_f32_16x16x32_bf16 v[20:23], v[168:171], v[208:211], v[20:23]
	v_mfma_f32_16x16x32_bf16 v[16:19], v[176:179], v[208:211], v[16:19]
	v_mfma_f32_16x16x32_bf16 v[4:7], v[168:171], v[216:219], v[4:7]
	v_mfma_f32_16x16x32_bf16 v[0:3], v[176:179], v[216:219], v[0:3]
	v_mfma_f32_16x16x32_bf16 v[52:55], v[172:175], v[190:193], v[52:55]
	v_mfma_f32_16x16x32_bf16 v[48:51], v[182:185], v[190:193], v[48:51]
	v_mfma_f32_16x16x32_bf16 v[36:39], v[172:175], v[198:201], v[36:39]
	v_mfma_f32_16x16x32_bf16 v[32:35], v[182:185], v[198:201], v[32:35]
	v_mfma_f32_16x16x32_bf16 v[20:23], v[172:175], v[212:215], v[20:23]
	v_mfma_f32_16x16x32_bf16 v[16:19], v[182:185], v[212:215], v[16:19]
	v_mfma_f32_16x16x32_bf16 v[4:7], v[172:175], v[220:223], v[4:7]
	v_lshl_add_u64 v[202:203], v[228:229], 0, s[36:37]
	s_mov_b32 m0, s64
	s_nop 0
	global_load_lds_dwordx4 v[202:203], off
	v_mfma_f32_16x16x32_bf16 v[0:3], v[182:185], v[220:223], v[0:3]
	s_setprio 0
	s_barrier
	s_add_i32 s83, s83, 2
	s_add_u32 s54, s54, 0x100
	s_addc_u32 s55, s55, 0
	s_add_u32 s77, s77, 0x100
	s_addc_u32 s82, s82, 0
.LBB0_957:
	ds_read_b128 v[144:147], v155
	ds_read_b128 v[148:151], v155 offset:1024
	ds_read_b128 v[160:163], v155 offset:2048
	ds_read_b128 v[164:167], v155 offset:3072
	ds_read_b128 v[168:171], v156
	ds_read_b128 v[172:175], v156 offset:1024
	ds_read_b128 v[176:179], v156 offset:2048
	ds_read_b128 v[182:185], v156 offset:3072
	s_add_u32 s3, s54, 0xfffc0080
	s_addc_u32 s33, s55, -1
	s_cmp_eq_u32 s83, 12
	s_cselect_b32 s59, s45, s33
	s_cselect_b32 s58, s75, s3
	s_cselect_b32 s57, s43, s82
	s_cselect_b32 s56, s76, s77
	v_lshl_add_u64 v[202:203], s[54:55], 0, v[136:137]
	s_add_i32 m0, s34, 0xc000
	ds_read_b128 v[186:189], v157
	ds_read_b128 v[190:193], v157 offset:1024
	ds_read_b128 v[194:197], v157 offset:2048
	ds_read_b128 v[198:201], v157 offset:3072
	ds_read_b128 v[208:211], v157 offset:4096
	ds_read_b128 v[212:215], v157 offset:5120
	ds_read_b128 v[216:219], v157 offset:6144
	ds_read_b128 v[220:223], v157 offset:7168
	global_load_lds_dwordx4 v[202:203], off
	v_lshl_add_u64 v[202:203], s[54:55], 0, v[138:139]
	s_add_i32 m0, s34, 0xe000
	s_nop 0
	global_load_lds_dwordx4 v[202:203], off
	s_waitcnt vmcnt(8)
	s_waitcnt lgkmcnt(0)
	s_barrier
; #define PG8_STAGE(bufoff, gbase, voff) do { _Pragma("unroll") for (int _i = 0; _i < 2; ++_i) \
;         __builtin_amdgcn_global_load_lds((const unsigned*)((const char*)(gbase) + (voff)[_i]), (PG8_LAS unsigned*)(lds + (bufoff) + ldsw + _i * 8192), 16, 0, 0); } while (0)
; #define PG8_LDA(dst, b, h) do { _Pragma("unroll") for (int m = 0; m < 4; ++m) _Pragma("unroll") for (int k = 0; k < 2; ++k) dst[m][k] = *(const PG8_LAS bf16x8*)(lds + PG8_SA(b, h) + aoff + m * 2048 + k * 1024); } while (0)
; #define PG8_MMA(ai, bj, At, Bt) do { __builtin_amdgcn_s_setprio(1); _Pragma("unroll") for (int m = 0; m < 4; ++m) _Pragma("unroll") for (int n = 0; n < 2; ++n) _Pragma("unroll") for (int k = 0; k < 2; ++k) \
;         acc[ai][bj][m][n] = __builtin_amdgcn_mfma_f32_16x16x32_bf16(Bt[n][k], At[m][k], acc[ai][bj][m][n], 0, 0, 0); __builtin_amdgcn_s_setprio(0); } while (0)
; #define PG8_WAIT_V(n) asm volatile("s_waitcnt vmcnt(" #n ")" ::: "memory")
; #define PG8_WAIT_L(n) asm volatile("s_waitcnt lgkmcnt(" #n ")" ::: "memory")
; #define PG8_BAR __builtin_amdgcn_s_barrier()
; #define PG8_SCHED __builtin_amdgcn_sched_barrier(0)
; template <class Epi, class Sched, bool ALIGN_EPI = false, bool SP2 = false>
; __device__ __forceinline__ void gemm_phase(PG8_LAS unsigned char* lds, const Gemm g, const Sched& S, const Epi& E) {
;     ...
;             PG8_WAIT_V(8); PG8_WAIT_L(0); PG8_BAR; PG8_MMA(0, 0, At, B0); PG8_MMA(0, 1, At, B1); PG8_BAR; PG8_SCHED;
;             PG8_LDA(At, 0, 1); PG8_STAGE(PG8_SB(0, 0), b2, voffB); PG8_STAGE(PG8_SB(0, 1), b2 + hstep, voffB); PG8_STAGE(PG8_SA(0, 0), a2, voffA);
;             PG8_WAIT_V(8); PG8_WAIT_L(0); PG8_BAR; PG8_MMA(1, 0, At, B0); PG8_MMA(1, 1, At, B1); PG8_BAR; PG8_SCHED;
	s_setprio 1
	s_waitcnt lgkmcnt(0)
	v_mfma_f32_16x16x32_bf16 v[124:127], v[144:147], v[186:189], v[124:127]
	v_mfma_f32_16x16x32_bf16 v[120:123], v[160:163], v[186:189], v[120:123]
	v_mfma_f32_16x16x32_bf16 v[108:111], v[144:147], v[194:197], v[108:111]
	v_mfma_f32_16x16x32_bf16 v[104:107], v[160:163], v[194:197], v[104:107]
	v_mfma_f32_16x16x32_bf16 v[92:95], v[144:147], v[208:211], v[92:95]
	v_mfma_f32_16x16x32_bf16 v[88:91], v[160:163], v[208:211], v[88:91]
	v_mfma_f32_16x16x32_bf16 v[76:79], v[144:147], v[216:219], v[76:79]
	v_mfma_f32_16x16x32_bf16 v[72:75], v[160:163], v[216:219], v[72:75]
	v_mfma_f32_16x16x32_bf16 v[124:127], v[148:151], v[190:193], v[124:127]
	v_mfma_f32_16x16x32_bf16 v[120:123], v[164:167], v[190:193], v[120:123]
	v_mfma_f32_16x16x32_bf16 v[108:111], v[148:151], v[198:201], v[108:111]
	v_mfma_f32_16x16x32_bf16 v[104:107], v[164:167], v[198:201], v[104:107]
	v_mfma_f32_16x16x32_bf16 v[92:95], v[148:151], v[212:215], v[92:95]
	v_mfma_f32_16x16x32_bf16 v[88:91], v[164:167], v[212:215], v[88:91]
	v_mfma_f32_16x16x32_bf16 v[76:79], v[148:151], v[220:223], v[76:79]
	v_mfma_f32_16x16x32_bf16 v[72:75], v[164:167], v[220:223], v[72:75]
	s_setprio 0
	s_setprio 1
	v_mfma_f32_16x16x32_bf16 v[116:119], v[168:171], v[186:189], v[116:119]
	v_mfma_f32_16x16x32_bf16 v[112:115], v[176:179], v[186:189], v[112:115]
	v_mfma_f32_16x16x32_bf16 v[100:103], v[168:171], v[194:197], v[100:103]
	v_mfma_f32_16x16x32_bf16 v[96:99], v[176:179], v[194:197], v[96:99]
	v_mfma_f32_16x16x32_bf16 v[84:87], v[168:171], v[208:211], v[84:87]
	v_mfma_f32_16x16x32_bf16 v[80:83], v[176:179], v[208:211], v[80:83]
	v_mfma_f32_16x16x32_bf16 v[68:71], v[168:171], v[216:219], v[68:71]
	v_mfma_f32_16x16x32_bf16 v[64:67], v[176:179], v[216:219], v[64:67]
	v_mfma_f32_16x16x32_bf16 v[116:119], v[172:175], v[190:193], v[116:119]
	v_mfma_f32_16x16x32_bf16 v[112:115], v[182:185], v[190:193], v[112:115]
	v_mfma_f32_16x16x32_bf16 v[100:103], v[172:175], v[198:201], v[100:103]
	v_mfma_f32_16x16x32_bf16 v[96:99], v[182:185], v[198:201], v[96:99]
	v_mfma_f32_16x16x32_bf16 v[84:87], v[172:175], v[212:215], v[84:87]
	v_mfma_f32_16x16x32_bf16 v[80:83], v[182:185], v[212:215], v[80:83]
	v_mfma_f32_16x16x32_bf16 v[68:71], v[172:175], v[220:223], v[68:71]
	v_mfma_f32_16x16x32_bf16 v[64:67], v[182:185], v[220:223], v[64:67]
	s_setprio 0
	s_barrier
	s_add_i32 s3, s65, s14
	v_lshl_add_u64 v[202:203], s[56:57], 0, v[132:133]
	s_mov_b32 m0, s3
	ds_read_b128 v[186:189], v157 offset:16384
	ds_read_b128 v[190:193], v157 offset:17408
	ds_read_b128 v[194:197], v157 offset:18432
	ds_read_b128 v[198:201], v157 offset:19456
	ds_read_b128 v[208:211], v157 offset:20480
	ds_read_b128 v[212:215], v157 offset:21504
	ds_read_b128 v[216:219], v157 offset:22528
	ds_read_b128 v[220:223], v157 offset:23552
	global_load_lds_dwordx4 v[202:203], off
	s_add_i32 m0, s3, 0x2000
	s_add_u32 s78, s56, 0x40000
	v_lshl_add_u64 v[224:225], s[56:57], 0, v[128:129]
	s_addc_u32 s79, s57, 0
	s_add_i32 s3, s66, s14
	global_load_lds_dwordx4 v[224:225], off
	v_lshl_add_u64 v[226:227], s[78:79], 0, v[132:133]
	s_mov_b32 m0, s3
	global_load_lds_dwordx4 v[226:227], off
	v_lshl_add_u64 v[226:227], s[78:79], 0, v[128:129]
	s_add_i32 m0, s3, 0x2000
	s_nop 0
	global_load_lds_dwordx4 v[226:227], off
	s_waitcnt vmcnt(6)
	s_waitcnt lgkmcnt(0)
	s_barrier
	s_setprio 1
	s_waitcnt lgkmcnt(0)
	v_mfma_f32_16x16x32_bf16 v[60:63], v[144:147], v[186:189], v[60:63]
	v_mfma_f32_16x16x32_bf16 v[56:59], v[160:163], v[186:189], v[56:59]
	v_mfma_f32_16x16x32_bf16 v[44:47], v[144:147], v[194:197], v[44:47]
	v_mfma_f32_16x16x32_bf16 v[40:43], v[160:163], v[194:197], v[40:43]
	v_mfma_f32_16x16x32_bf16 v[28:31], v[144:147], v[208:211], v[28:31]
	v_mfma_f32_16x16x32_bf16 v[24:27], v[160:163], v[208:211], v[24:27]
	v_mfma_f32_16x16x32_bf16 v[12:15], v[144:147], v[216:219], v[12:15]
	v_mfma_f32_16x16x32_bf16 v[8:11], v[160:163], v[216:219], v[8:11]
	v_mfma_f32_16x16x32_bf16 v[60:63], v[148:151], v[190:193], v[60:63]
	v_mfma_f32_16x16x32_bf16 v[56:59], v[164:167], v[190:193], v[56:59]
	v_mfma_f32_16x16x32_bf16 v[44:47], v[148:151], v[198:201], v[44:47]
	v_mfma_f32_16x16x32_bf16 v[40:43], v[164:167], v[198:201], v[40:43]
	v_mfma_f32_16x16x32_bf16 v[28:31], v[148:151], v[212:215], v[28:31]
	v_mfma_f32_16x16x32_bf16 v[24:27], v[164:167], v[212:215], v[24:27]
	v_mfma_f32_16x16x32_bf16 v[12:15], v[148:151], v[220:223], v[12:15]
	v_lshl_add_u64 v[226:227], s[58:59], 0, v[134:135]
	s_mov_b32 m0, s34
	s_nop 0
	global_load_lds_dwordx4 v[226:227], off
	v_mfma_f32_16x16x32_bf16 v[8:11], v[164:167], v[220:223], v[8:11]
	s_setprio 0
	s_setprio 1
	v_mfma_f32_16x16x32_bf16 v[52:55], v[168:171], v[186:189], v[52:55]
	v_mfma_f32_16x16x32_bf16 v[48:51], v[176:179], v[186:189], v[48:51]
	v_mfma_f32_16x16x32_bf16 v[36:39], v[168:171], v[194:197], v[36:39]
	v_mfma_f32_16x16x32_bf16 v[32:35], v[176:179], v[194:197], v[32:35]
	v_mfma_f32_16x16x32_bf16 v[20:23], v[168:171], v[208:211], v[20:23]
	v_mfma_f32_16x16x32_bf16 v[16:19], v[176:179], v[208:211], v[16:19]
	v_mfma_f32_16x16x32_bf16 v[4:7], v[168:171], v[216:219], v[4:7]
	v_mfma_f32_16x16x32_bf16 v[0:3], v[176:179], v[216:219], v[0:3]
	v_mfma_f32_16x16x32_bf16 v[52:55], v[172:175], v[190:193], v[52:55]
	v_mfma_f32_16x16x32_bf16 v[48:51], v[182:185], v[190:193], v[48:51]
	v_mfma_f32_16x16x32_bf16 v[36:39], v[172:175], v[198:201], v[36:39]
	v_mfma_f32_16x16x32_bf16 v[32:35], v[182:185], v[198:201], v[32:35]
	v_mfma_f32_16x16x32_bf16 v[20:23], v[172:175], v[212:215], v[20:23]
	v_mfma_f32_16x16x32_bf16 v[16:19], v[182:185], v[212:215], v[16:19]
	v_mfma_f32_16x16x32_bf16 v[4:7], v[172:175], v[220:223], v[4:7]
	v_lshl_add_u64 v[228:229], s[58:59], 0, v[130:131]
	s_mov_b32 m0, s53
	s_nop 0
	global_load_lds_dwordx4 v[228:229], off
	v_mfma_f32_16x16x32_bf16 v[0:3], v[182:185], v[220:223], v[0:3]
	s_setprio 0
	s_barrier
; #define PG8_STAGE(bufoff, gbase, voff) do { _Pragma("unroll") for (int _i = 0; _i < 2; ++_i) \
;         __builtin_amdgcn_global_load_lds((const unsigned*)((const char*)(gbase) + (voff)[_i]), (PG8_LAS unsigned*)(lds + (bufoff) + ldsw + _i * 8192), 16, 0, 0); } while (0)
; #define PG8_LDA(dst, b, h) do { _Pragma("unroll") for (int m = 0; m < 4; ++m) _Pragma("unroll") for (int k = 0; k < 2; ++k) dst[m][k] = *(const PG8_LAS bf16x8*)(lds + PG8_SA(b, h) + aoff + m * 2048 + k * 1024); } while (0)
; #define PG8_LDB(dst, b, h) do { _Pragma("unroll") for (int n = 0; n < 2; ++n) _Pragma("unroll") for (int k = 0; k < 2; ++k) dst[n][k] = *(const PG8_LAS bf16x8*)(lds + PG8_SB(b, h) + boff + n * 2048 + k * 1024); } while (0)
; #define PG8_MMA(ai, bj, At, Bt) do { __builtin_amdgcn_s_setprio(1); _Pragma("unroll") for (int m = 0; m < 4; ++m) _Pragma("unroll") for (int n = 0; n < 2; ++n) _Pragma("unroll") for (int k = 0; k < 2; ++k) \
;         acc[ai][bj][m][n] = __builtin_amdgcn_mfma_f32_16x16x32_bf16(Bt[n][k], At[m][k], acc[ai][bj][m][n], 0, 0, 0); __builtin_amdgcn_s_setprio(0); } while (0)
; #define PG8_WAIT_V(n) asm volatile("s_waitcnt vmcnt(" #n ")" ::: "memory")
; #define PG8_WAIT_L(n) asm volatile("s_waitcnt lgkmcnt(" #n ")" ::: "memory")
; #define PG8_BAR __builtin_amdgcn_s_barrier()
; #define PG8_SCHED __builtin_amdgcn_sched_barrier(0)
; template <class Epi, class Sched, bool ALIGN_EPI = false, bool SP2 = false>
; __device__ __forceinline__ void gemm_phase(PG8_LAS unsigned char* lds, const Gemm g, const Sched& S, const Epi& E) {
;     ...
;             PG8_LDB(B0, 1, 0); PG8_LDB(B1, 1, 1); PG8_SCHED; PG8_LDA(At, 1, 0); PG8_STAGE(PG8_SA(0, 1), a2 + hstep, voffA);
;             PG8_WAIT_V(8); PG8_WAIT_L(0); PG8_BAR; PG8_MMA(0, 0, At, B0); PG8_MMA(0, 1, At, B1); PG8_BAR; PG8_SCHED;
	s_add_i32 s3, 0, 0x18000
	v_add_u32_e32 v159, s3, v153
	s_add_i32 s33, 0, 0x1c000
	ds_read_b128 v[144:147], v159
	ds_read_b128 v[148:151], v159 offset:1024
	ds_read_b128 v[160:163], v159 offset:2048
	ds_read_b128 v[164:167], v159 offset:3072
	v_add_u32_e32 v159, s33, v153
	ds_read_b128 v[168:171], v159
	ds_read_b128 v[172:175], v159 offset:1024
	ds_read_b128 v[176:179], v159 offset:2048
	ds_read_b128 v[182:185], v159 offset:3072
	s_add_u32 s58, s58, 0x40000
	s_addc_u32 s59, s59, 0
	s_mov_b32 m0, s60
	v_lshl_add_u64 v[230:231], s[58:59], 0, v[134:135]
	ds_read_b128 v[186:189], v157 offset:32768
	ds_read_b128 v[190:193], v157 offset:33792
	ds_read_b128 v[194:197], v157 offset:34816
	ds_read_b128 v[198:201], v157 offset:35840
	ds_read_b128 v[208:211], v157 offset:36864
	ds_read_b128 v[212:215], v157 offset:37888
	ds_read_b128 v[216:219], v157 offset:38912
	ds_read_b128 v[220:223], v157 offset:39936
	global_load_lds_dwordx4 v[230:231], off
	v_lshl_add_u64 v[230:231], s[58:59], 0, v[130:131]
	s_mov_b32 m0, s61
	s_nop 0
	global_load_lds_dwordx4 v[230:231], off
	s_waitcnt vmcnt(8)
	s_waitcnt lgkmcnt(0)
	s_barrier
	s_setprio 1
	s_waitcnt lgkmcnt(0)
	v_mfma_f32_16x16x32_bf16 v[124:127], v[144:147], v[186:189], v[124:127]
	v_mfma_f32_16x16x32_bf16 v[120:123], v[160:163], v[186:189], v[120:123]
	v_mfma_f32_16x16x32_bf16 v[108:111], v[144:147], v[194:197], v[108:111]
	v_mfma_f32_16x16x32_bf16 v[104:107], v[160:163], v[194:197], v[104:107]
	v_mfma_f32_16x16x32_bf16 v[92:95], v[144:147], v[208:211], v[92:95]
	v_mfma_f32_16x16x32_bf16 v[88:91], v[160:163], v[208:211], v[88:91]
	v_mfma_f32_16x16x32_bf16 v[76:79], v[144:147], v[216:219], v[76:79]
	v_mfma_f32_16x16x32_bf16 v[72:75], v[160:163], v[216:219], v[72:75]
	v_mfma_f32_16x16x32_bf16 v[124:127], v[148:151], v[190:193], v[124:127]
	v_mfma_f32_16x16x32_bf16 v[120:123], v[164:167], v[190:193], v[120:123]
	v_mfma_f32_16x16x32_bf16 v[108:111], v[148:151], v[198:201], v[108:111]
	v_mfma_f32_16x16x32_bf16 v[104:107], v[164:167], v[198:201], v[104:107]
	v_mfma_f32_16x16x32_bf16 v[92:95], v[148:151], v[212:215], v[92:95]
	v_mfma_f32_16x16x32_bf16 v[88:91], v[164:167], v[212:215], v[88:91]
	v_mfma_f32_16x16x32_bf16 v[76:79], v[148:151], v[220:223], v[76:79]
	v_mfma_f32_16x16x32_bf16 v[72:75], v[164:167], v[220:223], v[72:75]
	s_setprio 0
	s_setprio 1
	v_mfma_f32_16x16x32_bf16 v[116:119], v[168:171], v[186:189], v[116:119]
	v_mfma_f32_16x16x32_bf16 v[112:115], v[176:179], v[186:189], v[112:115]
	v_mfma_f32_16x16x32_bf16 v[100:103], v[168:171], v[194:197], v[100:103]
	v_mfma_f32_16x16x32_bf16 v[96:99], v[176:179], v[194:197], v[96:99]
	v_mfma_f32_16x16x32_bf16 v[84:87], v[168:171], v[208:211], v[84:87]
	v_mfma_f32_16x16x32_bf16 v[80:83], v[176:179], v[208:211], v[80:83]
	v_mfma_f32_16x16x32_bf16 v[68:71], v[168:171], v[216:219], v[68:71]
	v_mfma_f32_16x16x32_bf16 v[64:67], v[176:179], v[216:219], v[64:67]
	v_mfma_f32_16x16x32_bf16 v[116:119], v[172:175], v[190:193], v[116:119]
	v_mfma_f32_16x16x32_bf16 v[112:115], v[182:185], v[190:193], v[112:115]
	v_mfma_f32_16x16x32_bf16 v[100:103], v[172:175], v[198:201], v[100:103]
	v_mfma_f32_16x16x32_bf16 v[96:99], v[182:185], v[198:201], v[96:99]
	v_mfma_f32_16x16x32_bf16 v[84:87], v[172:175], v[212:215], v[84:87]
	v_mfma_f32_16x16x32_bf16 v[80:83], v[182:185], v[212:215], v[80:83]
	v_mfma_f32_16x16x32_bf16 v[68:71], v[172:175], v[220:223], v[68:71]
	v_mfma_f32_16x16x32_bf16 v[64:67], v[182:185], v[220:223], v[64:67]
	s_setprio 0
	s_barrier
; #define PG8_STAGE(bufoff, gbase, voff) do { _Pragma("unroll") for (int _i = 0; _i < 2; ++_i) \
;         __builtin_amdgcn_global_load_lds((const unsigned*)((const char*)(gbase) + (voff)[_i]), (PG8_LAS unsigned*)(lds + (bufoff) + ldsw + _i * 8192), 16, 0, 0); } while (0)
; #define PG8_LDA(dst, b, h) do { _Pragma("unroll") for (int m = 0; m < 4; ++m) _Pragma("unroll") for (int k = 0; k < 2; ++k) dst[m][k] = *(const PG8_LAS bf16x8*)(lds + PG8_SA(b, h) + aoff + m * 2048 + k * 1024); } while (0)
; #define PG8_MMA(ai, bj, At, Bt) do { __builtin_amdgcn_s_setprio(1); _Pragma("unroll") for (int m = 0; m < 4; ++m) _Pragma("unroll") for (int n = 0; n < 2; ++n) _Pragma("unroll") for (int k = 0; k < 2; ++k) \
;         acc[ai][bj][m][n] = __builtin_amdgcn_mfma_f32_16x16x32_bf16(Bt[n][k], At[m][k], acc[ai][bj][m][n], 0, 0, 0); __builtin_amdgcn_s_setprio(0); } while (0)
; #define PG8_WAIT_V(n) asm volatile("s_waitcnt vmcnt(" #n ")" ::: "memory")
; #define PG8_WAIT_L(n) asm volatile("s_waitcnt lgkmcnt(" #n ")" ::: "memory")
; #define PG8_BAR __builtin_amdgcn_s_barrier()
; #define PG8_SCHED __builtin_amdgcn_sched_barrier(0)
; __device__ __forceinline__ float row_rs(const float* ssp, int row) { const unsigned long long v = ((const unsigned long long*)ssp)[row];
;     return __builtin_amdgcn_rsqf((float)v * (1.0f / 4294967296.0f) * (1.0f / 1024.0f) + RMS_EPS); }
; template <class Epi, class Sched, bool ALIGN_EPI = false, bool SP2 = false>
; __device__ __forceinline__ void gemm_phase(PG8_LAS unsigned char* lds, const Gemm g, const Sched& S, const Epi& E) {
;     ...
;             PG8_LDA(At, 1, 1); PG8_STAGE(PG8_SB(1, 0), b3, voffB); PG8_STAGE(PG8_SB(1, 1), b3 + hstep, voffB); PG8_STAGE(PG8_SA(1, 0), a3, voffA);
;             PG8_WAIT_V(8); PG8_WAIT_L(0); PG8_BAR; PG8_MMA(1, 0, At, B0); PG8_MMA(1, 1, At, B1); PG8_BAR; PG8_SCHED;
	s_add_i32 s3, s3, s14
	v_lshl_add_u64 v[202:203], v[202:203], 0, s[36:37]
	s_mov_b32 m0, s3
	ds_read_b128 v[186:189], v157 offset:49152
	ds_read_b128 v[190:193], v157 offset:50176
	ds_read_b128 v[194:197], v157 offset:51200
	ds_read_b128 v[198:201], v157 offset:52224
	ds_read_b128 v[208:211], v157 offset:53248
	ds_read_b128 v[212:215], v157 offset:54272
	ds_read_b128 v[216:219], v157 offset:55296
	ds_read_b128 v[220:223], v157 offset:56320
	global_load_lds_dwordx4 v[202:203], off
	s_add_i32 m0, s3, 0x2000
	s_add_u32 s56, s56, 0x40080
	v_lshl_add_u64 v[202:203], v[224:225], 0, s[36:37]
	s_addc_u32 s57, s57, 0
	s_add_i32 s3, s33, s14
	global_load_lds_dwordx4 v[202:203], off
	v_lshl_add_u64 v[202:203], s[56:57], 0, v[132:133]
	s_mov_b32 m0, s3
	s_nop 0
	global_load_lds_dwordx4 v[202:203], off
	v_lshl_add_u64 v[202:203], s[56:57], 0, v[128:129]
	s_add_i32 m0, s3, 0x2000
	s_nop 0
	global_load_lds_dwordx4 v[202:203], off
	s_waitcnt vmcnt(6)
	s_waitcnt lgkmcnt(0)
	s_barrier
	s_setprio 1
	s_waitcnt lgkmcnt(0)
	v_mfma_f32_16x16x32_bf16 v[60:63], v[144:147], v[186:189], v[60:63]
	v_mfma_f32_16x16x32_bf16 v[56:59], v[160:163], v[186:189], v[56:59]
	v_mfma_f32_16x16x32_bf16 v[44:47], v[144:147], v[194:197], v[44:47]
	v_mfma_f32_16x16x32_bf16 v[40:43], v[160:163], v[194:197], v[40:43]
	v_mfma_f32_16x16x32_bf16 v[28:31], v[144:147], v[208:211], v[28:31]
	v_mfma_f32_16x16x32_bf16 v[24:27], v[160:163], v[208:211], v[24:27]
	v_mfma_f32_16x16x32_bf16 v[12:15], v[144:147], v[216:219], v[12:15]
	v_mfma_f32_16x16x32_bf16 v[8:11], v[160:163], v[216:219], v[8:11]
	v_mfma_f32_16x16x32_bf16 v[60:63], v[148:151], v[190:193], v[60:63]
	v_mfma_f32_16x16x32_bf16 v[56:59], v[164:167], v[190:193], v[56:59]
	v_mfma_f32_16x16x32_bf16 v[44:47], v[148:151], v[198:201], v[44:47]
	v_mfma_f32_16x16x32_bf16 v[40:43], v[164:167], v[198:201], v[40:43]
	v_mfma_f32_16x16x32_bf16 v[28:31], v[148:151], v[212:215], v[28:31]
	v_mfma_f32_16x16x32_bf16 v[24:27], v[164:167], v[212:215], v[24:27]
	v_mfma_f32_16x16x32_bf16 v[12:15], v[148:151], v[220:223], v[12:15]
	v_lshl_add_u64 v[202:203], v[226:227], 0, s[36:37]
	s_mov_b32 m0, s63
	s_nop 0
	global_load_lds_dwordx4 v[202:203], off
	v_mfma_f32_16x16x32_bf16 v[8:11], v[164:167], v[220:223], v[8:11]
	s_setprio 0
	s_setprio 1
	v_mfma_f32_16x16x32_bf16 v[52:55], v[168:171], v[186:189], v[52:55]
	v_mfma_f32_16x16x32_bf16 v[48:51], v[176:179], v[186:189], v[48:51]
	v_mfma_f32_16x16x32_bf16 v[36:39], v[168:171], v[194:197], v[36:39]
	v_mfma_f32_16x16x32_bf16 v[32:35], v[176:179], v[194:197], v[32:35]
	v_mfma_f32_16x16x32_bf16 v[20:23], v[168:171], v[208:211], v[20:23]
	v_mfma_f32_16x16x32_bf16 v[16:19], v[176:179], v[208:211], v[16:19]
	v_mfma_f32_16x16x32_bf16 v[4:7], v[168:171], v[216:219], v[4:7]
	v_mfma_f32_16x16x32_bf16 v[0:3], v[176:179], v[216:219], v[0:3]
	v_mfma_f32_16x16x32_bf16 v[52:55], v[172:175], v[190:193], v[52:55]
	v_mfma_f32_16x16x32_bf16 v[48:51], v[182:185], v[190:193], v[48:51]
	v_mfma_f32_16x16x32_bf16 v[36:39], v[172:175], v[198:201], v[36:39]
	v_mfma_f32_16x16x32_bf16 v[32:35], v[182:185], v[198:201], v[32:35]
	v_mfma_f32_16x16x32_bf16 v[20:23], v[172:175], v[212:215], v[20:23]
	v_mfma_f32_16x16x32_bf16 v[16:19], v[182:185], v[212:215], v[16:19]
	v_mfma_f32_16x16x32_bf16 v[4:7], v[172:175], v[220:223], v[4:7]
	v_lshl_add_u64 v[202:203], v[228:229], 0, s[36:37]
	s_mov_b32 m0, s64
	s_nop 0
	global_load_lds_dwordx4 v[202:203], off
	v_mfma_f32_16x16x32_bf16 v[0:3], v[182:185], v[220:223], v[0:3]
	s_setprio 0
	s_barrier
	s_add_i32 s83, s83, 2
	s_add_u32 s54, s54, 0x100
	s_addc_u32 s55, s55, 0
	s_add_u32 s77, s77, 0x100
	s_addc_u32 s82, s82, 0
	s_cmp_gt_u32 s83, 13
	s_cbranch_scc0 .LBB0_957
	v_lshl_add_u32 v144, s52, 8, v152
	v_ashrrev_i32_e32 v145, 31, v144
	v_lshl_add_u64 v[150:151], v[144:145], 3, s[0:1]
	global_load_dwordx2 v[182:183], v[150:151], off
	global_load_dwordx2 v[184:185], v[150:151], off offset:128
	global_load_dwordx2 v[186:187], v[150:151], off offset:256
	global_load_dwordx2 v[188:189], v[150:151], off offset:384
	global_load_dwordx2 v[190:191], v[150:151], off offset:1024
	global_load_dwordx2 v[192:193], v[150:151], off offset:1152
	global_load_dwordx2 v[194:195], v[150:151], off offset:1280
	global_load_dwordx2 v[196:197], v[150:151], off offset:1408
	s_and_b64 vcc, exec, s[38:39]
	s_cbranch_vccz .LBB0_960
	s_barrier

; #define PG8_STAGE(bufoff, gbase, voff) do { _Pragma("unroll") for (int _i = 0; _i < 2; ++_i) \
;         __builtin_amdgcn_global_load_lds((const unsigned*)((const char*)(gbase) + (voff)[_i]), (PG8_LAS unsigned*)(lds + (bufoff) + ldsw + _i * 8192), 16, 0, 0); } while (0)
; #define PG8_LDA(dst, b, h) do { _Pragma("unroll") for (int m = 0; m < 4; ++m) _Pragma("unroll") for (int k = 0; k < 2; ++k) dst[m][k] = *(const PG8_LAS bf16x8*)(lds + PG8_SA(b, h) + aoff + m * 2048 + k * 1024); } while (0)
; #define PG8_LDB(dst, b, h) do { _Pragma("unroll") for (int n = 0; n < 2; ++n) _Pragma("unroll") for (int k = 0; k < 2; ++k) dst[n][k] = *(const PG8_LAS bf16x8*)(lds + PG8_SB(b, h) + boff + n * 2048 + k * 1024); } while (0)
; #define PG8_WAIT_V(n) asm volatile("s_waitcnt vmcnt(" #n ")" ::: "memory")
; #define PG8_WAIT_L(n) asm volatile("s_waitcnt lgkmcnt(" #n ")" ::: "memory")
; #define PG8_BAR __builtin_amdgcn_s_barrier()
; #define PG8_SCHED __builtin_amdgcn_sched_barrier(0)
; template <class Epi, class Sched, bool ALIGN_EPI = false, bool SP2 = false>
; __device__ __forceinline__ void gemm_phase(PG8_LAS unsigned char* lds, const Gemm g, const Sched& S, const Epi& E) {
;     ...
;         const bool has_next = S.next(ui + 1, nxt);
;         const char* nA = has_next ? (const char*)g.A + (size_t)nxt.pm * tstep : cA; const char* nB = has_next ? (const char*)g.Bt + (size_t)nxt.pn * tstep : cB;
;         for (int t = 0; t < nt; t += 2) {
;             const bool last = (t == nt - 2);
;             const char* a1 = cA + (size_t)(t + 1) * kstep;
;             const char* a2 = last ? nA : cA + (size_t)(t + 2) * kstep; const char* b2 = last ? nB : cB + (size_t)(t + 2) * kstep;
;             const char* a3 = a2 + kstep; const char* b3 = b2 + kstep;
;             if (last && has_next) S.a_ready(nxt);
;             if constexpr (SP2) {
;             PG8_LDB(B0, 0, 0); PG8_LDB(B1, 0, 1); PG8_SCHED; PG8_LDA(At, 0, 0); PG8_STAGE(PG8_SA(1, 1), a1 + hstep, voffA);
;             PG8_WAIT_V(8); PG8_WAIT_L(0); PG8_BAR; PG8_MMA(0, 0, At, B0); PG8_MMA(0, 1, At, B1); PG8_BAR; PG8_SCHED;
;             PG8_LDA(At, 0, 1); PG8_STAGE(PG8_SB(0, 0), b2, voffB); PG8_STAGE(PG8_SB(0, 1), b2 + hstep, voffB); PG8_STAGE(PG8_SA(0, 0), a2, voffA);
;             PG8_WAIT_V(8); PG8_WAIT_L(0); PG8_BAR; PG8_MMA(1, 0, At, B0); PG8_MMA(1, 1, At, B1); PG8_BAR; PG8_SCHED;
.LBB0_1034:
	s_add_u32 s75, s52, 0x100
	s_addc_u32 s76, s53, 0
	s_mov_b32 s77, -2
	s_waitcnt lgkmcnt(0)
	ds_read_b128 v[144:147], v151
	ds_read_b128 v[156:159], v151 offset:1024
	ds_read_b128 v[160:163], v151 offset:2048
	ds_read_b128 v[164:167], v151 offset:3072
	ds_read_b128 v[168:171], v152
	ds_read_b128 v[172:175], v152 offset:1024
	ds_read_b128 v[176:179], v152 offset:2048
	ds_read_b128 v[182:185], v152 offset:3072
	s_add_u32 s52, s50, 0x100
	s_addc_u32 s53, s51, 0
	s_cmp_eq_u32 s77, 40
	s_cselect_b32 s57, s1, s53
	s_cselect_b32 s56, s0, s52
	s_cselect_b32 s55, s49, s76
	s_cselect_b32 s54, s48, s75
	v_lshl_add_u64 v[202:203], s[50:51], 0, v[136:137]
	s_add_i32 m0, s14, 0xc000
	ds_read_b128 v[186:189], v153
	ds_read_b128 v[190:193], v153 offset:1024
	ds_read_b128 v[194:197], v153 offset:2048
	ds_read_b128 v[198:201], v153 offset:3072
	ds_read_b128 v[208:211], v153 offset:4096
	ds_read_b128 v[212:215], v153 offset:5120
	ds_read_b128 v[216:219], v153 offset:6144
	ds_read_b128 v[220:223], v153 offset:7168
	global_load_lds_dwordx4 v[202:203], off
	v_lshl_add_u64 v[202:203], s[50:51], 0, v[138:139]
	s_add_i32 m0, s14, 0xe000
	s_nop 0
	global_load_lds_dwordx4 v[202:203], off
	s_waitcnt vmcnt(8)
	s_waitcnt lgkmcnt(0)
	s_barrier
	s_setprio 1
	s_waitcnt lgkmcnt(0)
	v_mfma_f32_16x16x32_bf16 v[124:127], v[144:147], v[186:189], 0
	v_mfma_f32_16x16x32_bf16 v[120:123], v[160:163], v[186:189], 0
	v_mfma_f32_16x16x32_bf16 v[108:111], v[144:147], v[194:197], 0
	v_mfma_f32_16x16x32_bf16 v[104:107], v[160:163], v[194:197], 0
	v_mfma_f32_16x16x32_bf16 v[92:95], v[144:147], v[208:211], 0
	v_mfma_f32_16x16x32_bf16 v[88:91], v[160:163], v[208:211], 0
	v_mfma_f32_16x16x32_bf16 v[76:79], v[144:147], v[216:219], 0
	v_mfma_f32_16x16x32_bf16 v[72:75], v[160:163], v[216:219], 0
	v_mfma_f32_16x16x32_bf16 v[124:127], v[156:159], v[190:193], v[124:127]
	v_mfma_f32_16x16x32_bf16 v[120:123], v[164:167], v[190:193], v[120:123]
	v_mfma_f32_16x16x32_bf16 v[108:111], v[156:159], v[198:201], v[108:111]
	v_mfma_f32_16x16x32_bf16 v[104:107], v[164:167], v[198:201], v[104:107]
	v_mfma_f32_16x16x32_bf16 v[92:95], v[156:159], v[212:215], v[92:95]
	v_mfma_f32_16x16x32_bf16 v[88:91], v[164:167], v[212:215], v[88:91]
	v_mfma_f32_16x16x32_bf16 v[76:79], v[156:159], v[220:223], v[76:79]
	v_mfma_f32_16x16x32_bf16 v[72:75], v[164:167], v[220:223], v[72:75]
	s_setprio 0
	s_setprio 1
	v_mfma_f32_16x16x32_bf16 v[116:119], v[168:171], v[186:189], 0
	v_mfma_f32_16x16x32_bf16 v[112:115], v[176:179], v[186:189], 0
	v_mfma_f32_16x16x32_bf16 v[100:103], v[168:171], v[194:197], 0
	v_mfma_f32_16x16x32_bf16 v[96:99], v[176:179], v[194:197], 0
	v_mfma_f32_16x16x32_bf16 v[84:87], v[168:171], v[208:211], 0
	v_mfma_f32_16x16x32_bf16 v[80:83], v[176:179], v[208:211], 0
	v_mfma_f32_16x16x32_bf16 v[68:71], v[168:171], v[216:219], 0
	v_mfma_f32_16x16x32_bf16 v[64:67], v[176:179], v[216:219], 0
	v_mfma_f32_16x16x32_bf16 v[116:119], v[172:175], v[190:193], v[116:119]
	v_mfma_f32_16x16x32_bf16 v[112:115], v[182:185], v[190:193], v[112:115]
	v_mfma_f32_16x16x32_bf16 v[100:103], v[172:175], v[198:201], v[100:103]
	v_mfma_f32_16x16x32_bf16 v[96:99], v[182:185], v[198:201], v[96:99]
	v_mfma_f32_16x16x32_bf16 v[84:87], v[172:175], v[212:215], v[84:87]
	v_mfma_f32_16x16x32_bf16 v[80:83], v[182:185], v[212:215], v[80:83]
	v_mfma_f32_16x16x32_bf16 v[68:71], v[172:175], v[220:223], v[68:71]
	v_mfma_f32_16x16x32_bf16 v[64:67], v[182:185], v[220:223], v[64:67]
	s_setprio 0
	s_barrier
	s_add_i32 s50, s61, s3
	v_lshl_add_u64 v[202:203], s[54:55], 0, v[130:131]
	s_mov_b32 m0, s50
	ds_read_b128 v[186:189], v153 offset:16384
	ds_read_b128 v[190:193], v153 offset:17408
	ds_read_b128 v[194:197], v153 offset:18432
	ds_read_b128 v[198:201], v153 offset:19456
	ds_read_b128 v[208:211], v153 offset:20480
	ds_read_b128 v[212:215], v153 offset:21504
	ds_read_b128 v[216:219], v153 offset:22528
	ds_read_b128 v[220:223], v153 offset:23552
	global_load_lds_dwordx4 v[202:203], off
	s_add_i32 m0, s50, 0x2000
	s_add_u32 s50, s54, 0xb0000
	v_lshl_add_u64 v[224:225], s[54:55], 0, v[134:135]
	s_addc_u32 s51, s55, 0
	s_add_i32 s78, s62, s3
	global_load_lds_dwordx4 v[224:225], off
	v_lshl_add_u64 v[226:227], s[50:51], 0, v[130:131]
	s_mov_b32 m0, s78
	global_load_lds_dwordx4 v[226:227], off
	v_lshl_add_u64 v[226:227], s[50:51], 0, v[134:135]
	s_add_i32 m0, s78, 0x2000
	s_nop 0
	global_load_lds_dwordx4 v[226:227], off
	s_waitcnt vmcnt(6)
	s_waitcnt lgkmcnt(0)
	s_barrier
; #define PG8_STAGE(bufoff, gbase, voff) do { _Pragma("unroll") for (int _i = 0; _i < 2; ++_i) \
;         __builtin_amdgcn_global_load_lds((const unsigned*)((const char*)(gbase) + (voff)[_i]), (PG8_LAS unsigned*)(lds + (bufoff) + ldsw + _i * 8192), 16, 0, 0); } while (0)
; #define PG8_LDA(dst, b, h) do { _Pragma("unroll") for (int m = 0; m < 4; ++m) _Pragma("unroll") for (int k = 0; k < 2; ++k) dst[m][k] = *(const PG8_LAS bf16x8*)(lds + PG8_SA(b, h) + aoff + m * 2048 + k * 1024); } while (0)
; #define PG8_LDB(dst, b, h) do { _Pragma("unroll") for (int n = 0; n < 2; ++n) _Pragma("unroll") for (int k = 0; k < 2; ++k) dst[n][k] = *(const PG8_LAS bf16x8*)(lds + PG8_SB(b, h) + boff + n * 2048 + k * 1024); } while (0)
; #define PG8_MMA(ai, bj, At, Bt) do { __builtin_amdgcn_s_setprio(1); _Pragma("unroll") for (int m = 0; m < 4; ++m) _Pragma("unroll") for (int n = 0; n < 2; ++n) _Pragma("unroll") for (int k = 0; k < 2; ++k) \
;         acc[ai][bj][m][n] = __builtin_amdgcn_mfma_f32_16x16x32_bf16(Bt[n][k], At[m][k], acc[ai][bj][m][n], 0, 0, 0); __builtin_amdgcn_s_setprio(0); } while (0)
; #define PG8_WAIT_V(n) asm volatile("s_waitcnt vmcnt(" #n ")" ::: "memory")
; #define PG8_WAIT_L(n) asm volatile("s_waitcnt lgkmcnt(" #n ")" ::: "memory")
; #define PG8_BAR __builtin_amdgcn_s_barrier()
; #define PG8_SCHED __builtin_amdgcn_sched_barrier(0)
; template <class Epi, class Sched, bool ALIGN_EPI = false, bool SP2 = false>
; __device__ __forceinline__ void gemm_phase(PG8_LAS unsigned char* lds, const Gemm g, const Sched& S, const Epi& E) {
;     ...
;             PG8_LDA(At, 0, 1); PG8_STAGE(PG8_SB(0, 0), b2, voffB); PG8_STAGE(PG8_SB(0, 1), b2 + hstep, voffB); PG8_STAGE(PG8_SA(0, 0), a2, voffA);
;             PG8_WAIT_V(8); PG8_WAIT_L(0); PG8_BAR; PG8_MMA(1, 0, At, B0); PG8_MMA(1, 1, At, B1); PG8_BAR; PG8_SCHED;
;             PG8_LDB(B0, 1, 0); PG8_LDB(B1, 1, 1); PG8_SCHED; PG8_LDA(At, 1, 0); PG8_STAGE(PG8_SA(0, 1), a2 + hstep, voffA);
;             PG8_WAIT_V(8); PG8_WAIT_L(0); PG8_BAR; PG8_MMA(0, 0, At, B0); PG8_MMA(0, 1, At, B1); PG8_BAR; PG8_SCHED;
	s_setprio 1
	s_waitcnt lgkmcnt(0)
	v_mfma_f32_16x16x32_bf16 v[60:63], v[144:147], v[186:189], 0
	v_mfma_f32_16x16x32_bf16 v[56:59], v[160:163], v[186:189], 0
	v_mfma_f32_16x16x32_bf16 v[44:47], v[144:147], v[194:197], 0
	v_mfma_f32_16x16x32_bf16 v[40:43], v[160:163], v[194:197], 0
	v_mfma_f32_16x16x32_bf16 v[28:31], v[144:147], v[208:211], 0
	v_mfma_f32_16x16x32_bf16 v[24:27], v[160:163], v[208:211], 0
	v_mfma_f32_16x16x32_bf16 v[12:15], v[144:147], v[216:219], 0
	v_mfma_f32_16x16x32_bf16 v[8:11], v[160:163], v[216:219], 0
	v_mfma_f32_16x16x32_bf16 v[60:63], v[156:159], v[190:193], v[60:63]
	v_mfma_f32_16x16x32_bf16 v[56:59], v[164:167], v[190:193], v[56:59]
	v_mfma_f32_16x16x32_bf16 v[44:47], v[156:159], v[198:201], v[44:47]
	v_mfma_f32_16x16x32_bf16 v[40:43], v[164:167], v[198:201], v[40:43]
	v_mfma_f32_16x16x32_bf16 v[28:31], v[156:159], v[212:215], v[28:31]
	v_mfma_f32_16x16x32_bf16 v[24:27], v[164:167], v[212:215], v[24:27]
	v_mfma_f32_16x16x32_bf16 v[12:15], v[156:159], v[220:223], v[12:15]
	v_lshl_add_u64 v[226:227], s[56:57], 0, v[128:129]
	s_mov_b32 m0, s14
	s_nop 0
	global_load_lds_dwordx4 v[226:227], off
	v_mfma_f32_16x16x32_bf16 v[8:11], v[164:167], v[220:223], v[8:11]
	s_setprio 0
	s_setprio 1
	v_mfma_f32_16x16x32_bf16 v[52:55], v[168:171], v[186:189], 0
	v_mfma_f32_16x16x32_bf16 v[48:51], v[176:179], v[186:189], 0
	v_mfma_f32_16x16x32_bf16 v[36:39], v[168:171], v[194:197], 0
	v_mfma_f32_16x16x32_bf16 v[32:35], v[176:179], v[194:197], 0
	v_mfma_f32_16x16x32_bf16 v[20:23], v[168:171], v[208:211], 0
	v_mfma_f32_16x16x32_bf16 v[16:19], v[176:179], v[208:211], 0
	v_mfma_f32_16x16x32_bf16 v[4:7], v[168:171], v[216:219], 0
	v_mfma_f32_16x16x32_bf16 v[0:3], v[176:179], v[216:219], 0
	v_mfma_f32_16x16x32_bf16 v[52:55], v[172:175], v[190:193], v[52:55]
	v_mfma_f32_16x16x32_bf16 v[48:51], v[182:185], v[190:193], v[48:51]
	v_mfma_f32_16x16x32_bf16 v[36:39], v[172:175], v[198:201], v[36:39]
	v_mfma_f32_16x16x32_bf16 v[32:35], v[182:185], v[198:201], v[32:35]
	v_mfma_f32_16x16x32_bf16 v[20:23], v[172:175], v[212:215], v[20:23]
	v_mfma_f32_16x16x32_bf16 v[16:19], v[182:185], v[212:215], v[16:19]
	v_mfma_f32_16x16x32_bf16 v[4:7], v[172:175], v[220:223], v[4:7]
	v_lshl_add_u64 v[228:229], s[56:57], 0, v[132:133]
	s_mov_b32 m0, s15
	s_nop 0
	global_load_lds_dwordx4 v[228:229], off
	v_mfma_f32_16x16x32_bf16 v[0:3], v[182:185], v[220:223], v[0:3]
	s_setprio 0
	s_barrier
	s_add_i32 s78, 0, 0x18000
	v_add_u32_e32 v155, s78, v149
	s_add_i32 s79, 0, 0x1c000
	ds_read_b128 v[144:147], v155
	ds_read_b128 v[156:159], v155 offset:1024
	ds_read_b128 v[160:163], v155 offset:2048
	ds_read_b128 v[164:167], v155 offset:3072
	v_add_u32_e32 v155, s79, v149
	ds_read_b128 v[168:171], v155
	ds_read_b128 v[172:175], v155 offset:1024
	ds_read_b128 v[176:179], v155 offset:2048
	ds_read_b128 v[182:185], v155 offset:3072
	s_add_u32 s50, s56, 0xb0000
	s_addc_u32 s51, s57, 0
	s_mov_b32 m0, s33
	v_lshl_add_u64 v[230:231], s[50:51], 0, v[128:129]
	ds_read_b128 v[186:189], v153 offset:32768
	ds_read_b128 v[190:193], v153 offset:33792
	ds_read_b128 v[194:197], v153 offset:34816
	ds_read_b128 v[198:201], v153 offset:35840
	ds_read_b128 v[208:211], v153 offset:36864
	ds_read_b128 v[212:215], v153 offset:37888
	ds_read_b128 v[216:219], v153 offset:38912
	ds_read_b128 v[220:223], v153 offset:39936
	global_load_lds_dwordx4 v[230:231], off
	v_lshl_add_u64 v[230:231], s[50:51], 0, v[132:133]
	s_mov_b32 m0, s34
	s_nop 0
	global_load_lds_dwordx4 v[230:231], off
	s_waitcnt vmcnt(8)
	s_waitcnt lgkmcnt(0)
	s_barrier
	s_setprio 1
	s_waitcnt lgkmcnt(0)
	v_mfma_f32_16x16x32_bf16 v[124:127], v[144:147], v[186:189], v[124:127]
	v_mfma_f32_16x16x32_bf16 v[120:123], v[160:163], v[186:189], v[120:123]
	v_mfma_f32_16x16x32_bf16 v[108:111], v[144:147], v[194:197], v[108:111]
	v_mfma_f32_16x16x32_bf16 v[104:107], v[160:163], v[194:197], v[104:107]
	v_mfma_f32_16x16x32_bf16 v[92:95], v[144:147], v[208:211], v[92:95]
	v_mfma_f32_16x16x32_bf16 v[88:91], v[160:163], v[208:211], v[88:91]
	v_mfma_f32_16x16x32_bf16 v[76:79], v[144:147], v[216:219], v[76:79]
	v_mfma_f32_16x16x32_bf16 v[72:75], v[160:163], v[216:219], v[72:75]
	v_mfma_f32_16x16x32_bf16 v[124:127], v[156:159], v[190:193], v[124:127]
	v_mfma_f32_16x16x32_bf16 v[120:123], v[164:167], v[190:193], v[120:123]
	v_mfma_f32_16x16x32_bf16 v[108:111], v[156:159], v[198:201], v[108:111]
	v_mfma_f32_16x16x32_bf16 v[104:107], v[164:167], v[198:201], v[104:107]
	v_mfma_f32_16x16x32_bf16 v[92:95], v[156:159], v[212:215], v[92:95]
	v_mfma_f32_16x16x32_bf16 v[88:91], v[164:167], v[212:215], v[88:91]
	v_mfma_f32_16x16x32_bf16 v[76:79], v[156:159], v[220:223], v[76:79]
	v_mfma_f32_16x16x32_bf16 v[72:75], v[164:167], v[220:223], v[72:75]
	s_setprio 0
	s_setprio 1
	v_mfma_f32_16x16x32_bf16 v[116:119], v[168:171], v[186:189], v[116:119]
	v_mfma_f32_16x16x32_bf16 v[112:115], v[176:179], v[186:189], v[112:115]
	v_mfma_f32_16x16x32_bf16 v[100:103], v[168:171], v[194:197], v[100:103]
	v_mfma_f32_16x16x32_bf16 v[96:99], v[176:179], v[194:197], v[96:99]
	v_mfma_f32_16x16x32_bf16 v[84:87], v[168:171], v[208:211], v[84:87]
	v_mfma_f32_16x16x32_bf16 v[80:83], v[176:179], v[208:211], v[80:83]
	v_mfma_f32_16x16x32_bf16 v[68:71], v[168:171], v[216:219], v[68:71]
	v_mfma_f32_16x16x32_bf16 v[64:67], v[176:179], v[216:219], v[64:67]
	v_mfma_f32_16x16x32_bf16 v[116:119], v[172:175], v[190:193], v[116:119]
	v_mfma_f32_16x16x32_bf16 v[112:115], v[182:185], v[190:193], v[112:115]
	v_mfma_f32_16x16x32_bf16 v[100:103], v[172:175], v[198:201], v[100:103]
	v_mfma_f32_16x16x32_bf16 v[96:99], v[182:185], v[198:201], v[96:99]
	v_mfma_f32_16x16x32_bf16 v[84:87], v[172:175], v[212:215], v[84:87]
	v_mfma_f32_16x16x32_bf16 v[80:83], v[182:185], v[212:215], v[80:83]
	v_mfma_f32_16x16x32_bf16 v[68:71], v[172:175], v[220:223], v[68:71]
	v_mfma_f32_16x16x32_bf16 v[64:67], v[182:185], v[220:223], v[64:67]
	s_setprio 0
	s_barrier
; #define PG8_STAGE(bufoff, gbase, voff) do { _Pragma("unroll") for (int _i = 0; _i < 2; ++_i) \
;         __builtin_amdgcn_global_load_lds((const unsigned*)((const char*)(gbase) + (voff)[_i]), (PG8_LAS unsigned*)(lds + (bufoff) + ldsw + _i * 8192), 16, 0, 0); } while (0)
; #define PG8_LDA(dst, b, h) do { _Pragma("unroll") for (int m = 0; m < 4; ++m) _Pragma("unroll") for (int k = 0; k < 2; ++k) dst[m][k] = *(const PG8_LAS bf16x8*)(lds + PG8_SA(b, h) + aoff + m * 2048 + k * 1024); } while (0)
; #define PG8_LDB(dst, b, h) do { _Pragma("unroll") for (int n = 0; n < 2; ++n) _Pragma("unroll") for (int k = 0; k < 2; ++k) dst[n][k] = *(const PG8_LAS bf16x8*)(lds + PG8_SB(b, h) + boff + n * 2048 + k * 1024); } while (0)
; template <class Epi, class Sched, bool ALIGN_EPI = false, bool SP2 = false>
; __device__ __forceinline__ void gemm_phase(PG8_LAS unsigned char* lds, const Gemm g, const Sched& S, const Epi& E) {
;     ...
;         for (int t = 0; t < nt; t += 2) {
;             const bool last = (t == nt - 2);
;             const char* a1 = cA + (size_t)(t + 1) * kstep;
;             const char* a2 = last ? nA : cA + (size_t)(t + 2) * kstep; const char* b2 = last ? nB : cB + (size_t)(t + 2) * kstep;
;             const char* a3 = a2 + kstep; const char* b3 = b2 + kstep;
;             if (last && has_next) S.a_ready(nxt);
;             if constexpr (SP2) {
;             PG8_LDB(B0, 0, 0); PG8_LDB(B1, 0, 1); PG8_SCHED; PG8_LDA(At, 0, 0); PG8_STAGE(PG8_SA(1, 1), a1 + hstep, voffA);
;             PG8_WAIT_V(8); PG8_WAIT_L(0); PG8_BAR; PG8_MMA(0, 0, At, B0); PG8_MMA(0, 1, At, B1); PG8_BAR; PG8_SCHED;
;             PG8_LDA(At, 0, 1); PG8_STAGE(PG8_SB(0, 0), b2, voffB); PG8_STAGE(PG8_SB(0, 1), b2 + hstep, voffB); PG8_STAGE(PG8_SA(0, 0), a2, voffA);
;             PG8_WAIT_V(8); PG8_WAIT_L(0); PG8_BAR; PG8_MMA(1, 0, At, B0); PG8_MMA(1, 1, At, B1); PG8_BAR; PG8_SCHED;
;             PG8_LDB(B0, 1, 0); PG8_LDB(B1, 1, 1); PG8_SCHED; PG8_LDA(At, 1, 0); PG8_STAGE(PG8_SA(0, 1), a2 + hstep, voffA);
;             PG8_WAIT_V(8); PG8_WAIT_L(0); PG8_BAR; PG8_MMA(0, 0, At, B0); PG8_MMA(0, 1, At, B1); PG8_BAR; PG8_SCHED;
;             PG8_LDA(At, 1, 1); PG8_STAGE(PG8_SB(1, 0), b3, voffB); PG8_STAGE(PG8_SB(1, 1), b3 + hstep, voffB); PG8_STAGE(PG8_SA(1, 0), a3, voffA);
;             PG8_WAIT_V(8); PG8_WAIT_L(0); PG8_BAR; PG8_MMA(1, 0, At, B0); PG8_MMA(1, 1, At, B1); PG8_BAR; PG8_SCHED;
	s_add_i32 s50, s78, s3
	v_lshl_add_u64 v[202:203], v[202:203], 0, s[42:43]
	s_mov_b32 m0, s50
	ds_read_b128 v[186:189], v153 offset:49152
	ds_read_b128 v[190:193], v153 offset:50176
	ds_read_b128 v[194:197], v153 offset:51200
	ds_read_b128 v[198:201], v153 offset:52224
	ds_read_b128 v[208:211], v153 offset:53248
	ds_read_b128 v[212:215], v153 offset:54272
	ds_read_b128 v[216:219], v153 offset:55296
	ds_read_b128 v[220:223], v153 offset:56320
	global_load_lds_dwordx4 v[202:203], off
	s_add_i32 m0, s50, 0x2000
	s_add_u32 s50, s54, 0xb0080
	v_lshl_add_u64 v[202:203], v[224:225], 0, s[42:43]
	s_addc_u32 s51, s55, 0
	s_add_i32 s54, s79, s3
	global_load_lds_dwordx4 v[202:203], off
	v_lshl_add_u64 v[202:203], s[50:51], 0, v[130:131]
	s_mov_b32 m0, s54
	s_nop 0
	global_load_lds_dwordx4 v[202:203], off
	v_lshl_add_u64 v[202:203], s[50:51], 0, v[134:135]
	s_add_i32 m0, s54, 0x2000
	s_nop 0
	global_load_lds_dwordx4 v[202:203], off
	s_waitcnt vmcnt(6)
	s_waitcnt lgkmcnt(0)
	s_barrier
	s_setprio 1
	s_waitcnt lgkmcnt(0)
	v_mfma_f32_16x16x32_bf16 v[60:63], v[144:147], v[186:189], v[60:63]
	v_mfma_f32_16x16x32_bf16 v[56:59], v[160:163], v[186:189], v[56:59]
	v_mfma_f32_16x16x32_bf16 v[44:47], v[144:147], v[194:197], v[44:47]
	v_mfma_f32_16x16x32_bf16 v[40:43], v[160:163], v[194:197], v[40:43]
	v_mfma_f32_16x16x32_bf16 v[28:31], v[144:147], v[208:211], v[28:31]
	v_mfma_f32_16x16x32_bf16 v[24:27], v[160:163], v[208:211], v[24:27]
	v_mfma_f32_16x16x32_bf16 v[12:15], v[144:147], v[216:219], v[12:15]
	v_mfma_f32_16x16x32_bf16 v[8:11], v[160:163], v[216:219], v[8:11]
	v_mfma_f32_16x16x32_bf16 v[60:63], v[156:159], v[190:193], v[60:63]
	v_mfma_f32_16x16x32_bf16 v[56:59], v[164:167], v[190:193], v[56:59]
	v_mfma_f32_16x16x32_bf16 v[44:47], v[156:159], v[198:201], v[44:47]
	v_mfma_f32_16x16x32_bf16 v[40:43], v[164:167], v[198:201], v[40:43]
	v_mfma_f32_16x16x32_bf16 v[28:31], v[156:159], v[212:215], v[28:31]
	v_mfma_f32_16x16x32_bf16 v[24:27], v[164:167], v[212:215], v[24:27]
	v_mfma_f32_16x16x32_bf16 v[12:15], v[156:159], v[220:223], v[12:15]
	v_lshl_add_u64 v[202:203], v[226:227], 0, s[42:43]
	s_mov_b32 m0, s59
	s_nop 0
	global_load_lds_dwordx4 v[202:203], off
	v_mfma_f32_16x16x32_bf16 v[8:11], v[164:167], v[220:223], v[8:11]
	s_setprio 0
	s_setprio 1
	v_mfma_f32_16x16x32_bf16 v[52:55], v[168:171], v[186:189], v[52:55]
	v_mfma_f32_16x16x32_bf16 v[48:51], v[176:179], v[186:189], v[48:51]
	v_mfma_f32_16x16x32_bf16 v[36:39], v[168:171], v[194:197], v[36:39]
	v_mfma_f32_16x16x32_bf16 v[32:35], v[176:179], v[194:197], v[32:35]
	v_mfma_f32_16x16x32_bf16 v[20:23], v[168:171], v[208:211], v[20:23]
	v_mfma_f32_16x16x32_bf16 v[16:19], v[176:179], v[208:211], v[16:19]
	v_mfma_f32_16x16x32_bf16 v[4:7], v[168:171], v[216:219], v[4:7]
	v_mfma_f32_16x16x32_bf16 v[0:3], v[176:179], v[216:219], v[0:3]
	v_mfma_f32_16x16x32_bf16 v[52:55], v[172:175], v[190:193], v[52:55]
	v_mfma_f32_16x16x32_bf16 v[48:51], v[182:185], v[190:193], v[48:51]
	v_mfma_f32_16x16x32_bf16 v[36:39], v[172:175], v[198:201], v[36:39]
	v_mfma_f32_16x16x32_bf16 v[32:35], v[182:185], v[198:201], v[32:35]
	v_mfma_f32_16x16x32_bf16 v[20:23], v[172:175], v[212:215], v[20:23]
	v_mfma_f32_16x16x32_bf16 v[16:19], v[182:185], v[212:215], v[16:19]
	v_mfma_f32_16x16x32_bf16 v[4:7], v[172:175], v[220:223], v[4:7]
	v_lshl_add_u64 v[202:203], v[228:229], 0, s[42:43]
	s_mov_b32 m0, s60
	s_nop 0
	global_load_lds_dwordx4 v[202:203], off
	v_mfma_f32_16x16x32_bf16 v[0:3], v[182:185], v[220:223], v[0:3]
	s_setprio 0
	s_barrier
	s_add_i32 s77, s77, 2
	s_add_u32 s75, s75, 0x100
	s_addc_u32 s76, s76, 0
	s_mov_b64 s[50:51], s[52:53]
.LBB0_1035:
	ds_read_b128 v[144:147], v151
	ds_read_b128 v[156:159], v151 offset:1024
	ds_read_b128 v[160:163], v151 offset:2048
	ds_read_b128 v[164:167], v151 offset:3072
	ds_read_b128 v[168:171], v152
	ds_read_b128 v[172:175], v152 offset:1024
	ds_read_b128 v[176:179], v152 offset:2048
	ds_read_b128 v[182:185], v152 offset:3072
	s_add_u32 s52, s50, 0x100
	s_addc_u32 s53, s51, 0
	s_cmp_eq_u32 s77, 40
	s_cselect_b32 s57, s1, s53
	s_cselect_b32 s56, s0, s52
	s_cselect_b32 s55, s49, s76
	s_cselect_b32 s54, s48, s75
	v_lshl_add_u64 v[202:203], s[50:51], 0, v[136:137]
	s_add_i32 m0, s14, 0xc000
	ds_read_b128 v[186:189], v153
	ds_read_b128 v[190:193], v153 offset:1024
	ds_read_b128 v[194:197], v153 offset:2048
	ds_read_b128 v[198:201], v153 offset:3072
	ds_read_b128 v[208:211], v153 offset:4096
	ds_read_b128 v[212:215], v153 offset:5120
	ds_read_b128 v[216:219], v153 offset:6144
	ds_read_b128 v[220:223], v153 offset:7168
	global_load_lds_dwordx4 v[202:203], off
	v_lshl_add_u64 v[202:203], s[50:51], 0, v[138:139]
	s_add_i32 m0, s14, 0xe000
	s_nop 0
	global_load_lds_dwordx4 v[202:203], off
	s_waitcnt vmcnt(8)
	s_waitcnt lgkmcnt(0)
	s_barrier
; #define PG8_STAGE(bufoff, gbase, voff) do { _Pragma("unroll") for (int _i = 0; _i < 2; ++_i) \
;         __builtin_amdgcn_global_load_lds((const unsigned*)((const char*)(gbase) + (voff)[_i]), (PG8_LAS unsigned*)(lds + (bufoff) + ldsw + _i * 8192), 16, 0, 0); } while (0)
; #define PG8_LDA(dst, b, h) do { _Pragma("unroll") for (int m = 0; m < 4; ++m) _Pragma("unroll") for (int k = 0; k < 2; ++k) dst[m][k] = *(const PG8_LAS bf16x8*)(lds + PG8_SA(b, h) + aoff + m * 2048 + k * 1024); } while (0)
; #define PG8_LDB(dst, b, h) do { _Pragma("unroll") for (int n = 0; n < 2; ++n) _Pragma("unroll") for (int k = 0; k < 2; ++k) dst[n][k] = *(const PG8_LAS bf16x8*)(lds + PG8_SB(b, h) + boff + n * 2048 + k * 1024); } while (0)
; #define PG8_MMA(ai, bj, At, Bt) do { __builtin_amdgcn_s_setprio(1); _Pragma("unroll") for (int m = 0; m < 4; ++m) _Pragma("unroll") for (int n = 0; n < 2; ++n) _Pragma("unroll") for (int k = 0; k < 2; ++k) \
;         acc[ai][bj][m][n] = __builtin_amdgcn_mfma_f32_16x16x32_bf16(Bt[n][k], At[m][k], acc[ai][bj][m][n], 0, 0, 0); __builtin_amdgcn_s_setprio(0); } while (0)
; #define PG8_WAIT_V(n) asm volatile("s_waitcnt vmcnt(" #n ")" ::: "memory")
; #define PG8_WAIT_L(n) asm volatile("s_waitcnt lgkmcnt(" #n ")" ::: "memory")
; #define PG8_BAR __builtin_amdgcn_s_barrier()
; #define PG8_SCHED __builtin_amdgcn_sched_barrier(0)
; template <class Epi, class Sched, bool ALIGN_EPI = false, bool SP2 = false>
; __device__ __forceinline__ void gemm_phase(PG8_LAS unsigned char* lds, const Gemm g, const Sched& S, const Epi& E) {
;     ...
;             PG8_LDB(B0, 0, 0); PG8_LDB(B1, 0, 1); PG8_SCHED; PG8_LDA(At, 0, 0); PG8_STAGE(PG8_SA(1, 1), a1 + hstep, voffA);
;             PG8_WAIT_V(8); PG8_WAIT_L(0); PG8_BAR; PG8_MMA(0, 0, At, B0); PG8_MMA(0, 1, At, B1); PG8_BAR; PG8_SCHED;
;             PG8_LDA(At, 0, 1); PG8_STAGE(PG8_SB(0, 0), b2, voffB); PG8_STAGE(PG8_SB(0, 1), b2 + hstep, voffB); PG8_STAGE(PG8_SA(0, 0), a2, voffA);
;             PG8_WAIT_V(8); PG8_WAIT_L(0); PG8_BAR; PG8_MMA(1, 0, At, B0); PG8_MMA(1, 1, At, B1); PG8_BAR; PG8_SCHED;
	s_setprio 1
	s_waitcnt lgkmcnt(0)
	v_mfma_f32_16x16x32_bf16 v[124:127], v[144:147], v[186:189], v[124:127]
	v_mfma_f32_16x16x32_bf16 v[120:123], v[160:163], v[186:189], v[120:123]
	v_mfma_f32_16x16x32_bf16 v[108:111], v[144:147], v[194:197], v[108:111]
	v_mfma_f32_16x16x32_bf16 v[104:107], v[160:163], v[194:197], v[104:107]
	v_mfma_f32_16x16x32_bf16 v[92:95], v[144:147], v[208:211], v[92:95]
	v_mfma_f32_16x16x32_bf16 v[88:91], v[160:163], v[208:211], v[88:91]
	v_mfma_f32_16x16x32_bf16 v[76:79], v[144:147], v[216:219], v[76:79]
	v_mfma_f32_16x16x32_bf16 v[72:75], v[160:163], v[216:219], v[72:75]
	v_mfma_f32_16x16x32_bf16 v[124:127], v[156:159], v[190:193], v[124:127]
	v_mfma_f32_16x16x32_bf16 v[120:123], v[164:167], v[190:193], v[120:123]
	v_mfma_f32_16x16x32_bf16 v[108:111], v[156:159], v[198:201], v[108:111]
	v_mfma_f32_16x16x32_bf16 v[104:107], v[164:167], v[198:201], v[104:107]
	v_mfma_f32_16x16x32_bf16 v[92:95], v[156:159], v[212:215], v[92:95]
	v_mfma_f32_16x16x32_bf16 v[88:91], v[164:167], v[212:215], v[88:91]
	v_mfma_f32_16x16x32_bf16 v[76:79], v[156:159], v[220:223], v[76:79]
	v_mfma_f32_16x16x32_bf16 v[72:75], v[164:167], v[220:223], v[72:75]
	s_setprio 0
	s_setprio 1
	v_mfma_f32_16x16x32_bf16 v[116:119], v[168:171], v[186:189], v[116:119]
	v_mfma_f32_16x16x32_bf16 v[112:115], v[176:179], v[186:189], v[112:115]
	v_mfma_f32_16x16x32_bf16 v[100:103], v[168:171], v[194:197], v[100:103]
	v_mfma_f32_16x16x32_bf16 v[96:99], v[176:179], v[194:197], v[96:99]
	v_mfma_f32_16x16x32_bf16 v[84:87], v[168:171], v[208:211], v[84:87]
	v_mfma_f32_16x16x32_bf16 v[80:83], v[176:179], v[208:211], v[80:83]
	v_mfma_f32_16x16x32_bf16 v[68:71], v[168:171], v[216:219], v[68:71]
	v_mfma_f32_16x16x32_bf16 v[64:67], v[176:179], v[216:219], v[64:67]
	v_mfma_f32_16x16x32_bf16 v[116:119], v[172:175], v[190:193], v[116:119]
	v_mfma_f32_16x16x32_bf16 v[112:115], v[182:185], v[190:193], v[112:115]
	v_mfma_f32_16x16x32_bf16 v[100:103], v[172:175], v[198:201], v[100:103]
	v_mfma_f32_16x16x32_bf16 v[96:99], v[182:185], v[198:201], v[96:99]
	v_mfma_f32_16x16x32_bf16 v[84:87], v[172:175], v[212:215], v[84:87]
	v_mfma_f32_16x16x32_bf16 v[80:83], v[182:185], v[212:215], v[80:83]
	v_mfma_f32_16x16x32_bf16 v[68:71], v[172:175], v[220:223], v[68:71]
	v_mfma_f32_16x16x32_bf16 v[64:67], v[182:185], v[220:223], v[64:67]
	s_setprio 0
	s_barrier
	s_add_i32 s50, s61, s3
	v_lshl_add_u64 v[202:203], s[54:55], 0, v[130:131]
	s_mov_b32 m0, s50
	ds_read_b128 v[186:189], v153 offset:16384
	ds_read_b128 v[190:193], v153 offset:17408
	ds_read_b128 v[194:197], v153 offset:18432
	ds_read_b128 v[198:201], v153 offset:19456
	ds_read_b128 v[208:211], v153 offset:20480
	ds_read_b128 v[212:215], v153 offset:21504
	ds_read_b128 v[216:219], v153 offset:22528
	ds_read_b128 v[220:223], v153 offset:23552
	global_load_lds_dwordx4 v[202:203], off
	s_add_i32 m0, s50, 0x2000
	s_add_u32 s50, s54, 0xb0000
	v_lshl_add_u64 v[224:225], s[54:55], 0, v[134:135]
	s_addc_u32 s51, s55, 0
	s_add_i32 s78, s62, s3
	global_load_lds_dwordx4 v[224:225], off
	v_lshl_add_u64 v[226:227], s[50:51], 0, v[130:131]
	s_mov_b32 m0, s78
	global_load_lds_dwordx4 v[226:227], off
	v_lshl_add_u64 v[226:227], s[50:51], 0, v[134:135]
	s_add_i32 m0, s78, 0x2000
	s_nop 0
	global_load_lds_dwordx4 v[226:227], off
	s_waitcnt vmcnt(6)
	s_waitcnt lgkmcnt(0)
	s_barrier
	s_setprio 1
	s_waitcnt lgkmcnt(0)
	v_mfma_f32_16x16x32_bf16 v[60:63], v[144:147], v[186:189], v[60:63]
	v_mfma_f32_16x16x32_bf16 v[56:59], v[160:163], v[186:189], v[56:59]
	v_mfma_f32_16x16x32_bf16 v[44:47], v[144:147], v[194:197], v[44:47]
	v_mfma_f32_16x16x32_bf16 v[40:43], v[160:163], v[194:197], v[40:43]
	v_mfma_f32_16x16x32_bf16 v[28:31], v[144:147], v[208:211], v[28:31]
	v_mfma_f32_16x16x32_bf16 v[24:27], v[160:163], v[208:211], v[24:27]
	v_mfma_f32_16x16x32_bf16 v[12:15], v[144:147], v[216:219], v[12:15]
	v_mfma_f32_16x16x32_bf16 v[8:11], v[160:163], v[216:219], v[8:11]
	v_mfma_f32_16x16x32_bf16 v[60:63], v[156:159], v[190:193], v[60:63]
	v_mfma_f32_16x16x32_bf16 v[56:59], v[164:167], v[190:193], v[56:59]
	v_mfma_f32_16x16x32_bf16 v[44:47], v[156:159], v[198:201], v[44:47]
	v_mfma_f32_16x16x32_bf16 v[40:43], v[164:167], v[198:201], v[40:43]
	v_mfma_f32_16x16x32_bf16 v[28:31], v[156:159], v[212:215], v[28:31]
	v_mfma_f32_16x16x32_bf16 v[24:27], v[164:167], v[212:215], v[24:27]
	v_mfma_f32_16x16x32_bf16 v[12:15], v[156:159], v[220:223], v[12:15]
	v_lshl_add_u64 v[226:227], s[56:57], 0, v[128:129]
	s_mov_b32 m0, s14
	s_nop 0
	global_load_lds_dwordx4 v[226:227], off
	v_mfma_f32_16x16x32_bf16 v[8:11], v[164:167], v[220:223], v[8:11]
	s_setprio 0
	s_setprio 1
	v_mfma_f32_16x16x32_bf16 v[52:55], v[168:171], v[186:189], v[52:55]
	v_mfma_f32_16x16x32_bf16 v[48:51], v[176:179], v[186:189], v[48:51]
	v_mfma_f32_16x16x32_bf16 v[36:39], v[168:171], v[194:197], v[36:39]
	v_mfma_f32_16x16x32_bf16 v[32:35], v[176:179], v[194:197], v[32:35]
	v_mfma_f32_16x16x32_bf16 v[20:23], v[168:171], v[208:211], v[20:23]
	v_mfma_f32_16x16x32_bf16 v[16:19], v[176:179], v[208:211], v[16:19]
	v_mfma_f32_16x16x32_bf16 v[4:7], v[168:171], v[216:219], v[4:7]
	v_mfma_f32_16x16x32_bf16 v[0:3], v[176:179], v[216:219], v[0:3]
	v_mfma_f32_16x16x32_bf16 v[52:55], v[172:175], v[190:193], v[52:55]
	v_mfma_f32_16x16x32_bf16 v[48:51], v[182:185], v[190:193], v[48:51]
	v_mfma_f32_16x16x32_bf16 v[36:39], v[172:175], v[198:201], v[36:39]
	v_mfma_f32_16x16x32_bf16 v[32:35], v[182:185], v[198:201], v[32:35]
	v_mfma_f32_16x16x32_bf16 v[20:23], v[172:175], v[212:215], v[20:23]
	v_mfma_f32_16x16x32_bf16 v[16:19], v[182:185], v[212:215], v[16:19]
	v_mfma_f32_16x16x32_bf16 v[4:7], v[172:175], v[220:223], v[4:7]
	v_lshl_add_u64 v[228:229], s[56:57], 0, v[132:133]
	s_mov_b32 m0, s15
	s_nop 0
	global_load_lds_dwordx4 v[228:229], off
	v_mfma_f32_16x16x32_bf16 v[0:3], v[182:185], v[220:223], v[0:3]
	s_setprio 0
	s_barrier
; #define PG8_STAGE(bufoff, gbase, voff) do { _Pragma("unroll") for (int _i = 0; _i < 2; ++_i) \
;         __builtin_amdgcn_global_load_lds((const unsigned*)((const char*)(gbase) + (voff)[_i]), (PG8_LAS unsigned*)(lds + (bufoff) + ldsw + _i * 8192), 16, 0, 0); } while (0)
; #define PG8_LDA(dst, b, h) do { _Pragma("unroll") for (int m = 0; m < 4; ++m) _Pragma("unroll") for (int k = 0; k < 2; ++k) dst[m][k] = *(const PG8_LAS bf16x8*)(lds + PG8_SA(b, h) + aoff + m * 2048 + k * 1024); } while (0)
; #define PG8_LDB(dst, b, h) do { _Pragma("unroll") for (int n = 0; n < 2; ++n) _Pragma("unroll") for (int k = 0; k < 2; ++k) dst[n][k] = *(const PG8_LAS bf16x8*)(lds + PG8_SB(b, h) + boff + n * 2048 + k * 1024); } while (0)
; #define PG8_MMA(ai, bj, At, Bt) do { __builtin_amdgcn_s_setprio(1); _Pragma("unroll") for (int m = 0; m < 4; ++m) _Pragma("unroll") for (int n = 0; n < 2; ++n) _Pragma("unroll") for (int k = 0; k < 2; ++k) \
;         acc[ai][bj][m][n] = __builtin_amdgcn_mfma_f32_16x16x32_bf16(Bt[n][k], At[m][k], acc[ai][bj][m][n], 0, 0, 0); __builtin_amdgcn_s_setprio(0); } while (0)
; #define PG8_WAIT_V(n) asm volatile("s_waitcnt vmcnt(" #n ")" ::: "memory")
; #define PG8_WAIT_L(n) asm volatile("s_waitcnt lgkmcnt(" #n ")" ::: "memory")
; #define PG8_BAR __builtin_amdgcn_s_barrier()
; #define PG8_SCHED __builtin_amdgcn_sched_barrier(0)
; template <class Epi, class Sched, bool ALIGN_EPI = false, bool SP2 = false>
; __device__ __forceinline__ void gemm_phase(PG8_LAS unsigned char* lds, const Gemm g, const Sched& S, const Epi& E) {
;     ...
;             PG8_LDB(B0, 1, 0); PG8_LDB(B1, 1, 1); PG8_SCHED; PG8_LDA(At, 1, 0); PG8_STAGE(PG8_SA(0, 1), a2 + hstep, voffA);
;             PG8_WAIT_V(8); PG8_WAIT_L(0); PG8_BAR; PG8_MMA(0, 0, At, B0); PG8_MMA(0, 1, At, B1); PG8_BAR; PG8_SCHED;
	s_add_i32 s78, 0, 0x18000
	v_add_u32_e32 v155, s78, v149
	s_add_i32 s79, 0, 0x1c000
	ds_read_b128 v[144:147], v155
	ds_read_b128 v[156:159], v155 offset:1024
	ds_read_b128 v[160:163], v155 offset:2048
	ds_read_b128 v[164:167], v155 offset:3072
	v_add_u32_e32 v155, s79, v149
	ds_read_b128 v[168:171], v155
	ds_read_b128 v[172:175], v155 offset:1024
	ds_read_b128 v[176:179], v155 offset:2048
	ds_read_b128 v[182:185], v155 offset:3072
	s_add_u32 s50, s56, 0xb0000
	s_addc_u32 s51, s57, 0
	s_mov_b32 m0, s33
	v_lshl_add_u64 v[230:231], s[50:51], 0, v[128:129]
	ds_read_b128 v[186:189], v153 offset:32768
	ds_read_b128 v[190:193], v153 offset:33792
	ds_read_b128 v[194:197], v153 offset:34816
	ds_read_b128 v[198:201], v153 offset:35840
	ds_read_b128 v[208:211], v153 offset:36864
	ds_read_b128 v[212:215], v153 offset:37888
	ds_read_b128 v[216:219], v153 offset:38912
	ds_read_b128 v[220:223], v153 offset:39936
	global_load_lds_dwordx4 v[230:231], off
	v_lshl_add_u64 v[230:231], s[50:51], 0, v[132:133]
	s_mov_b32 m0, s34
	s_nop 0
	global_load_lds_dwordx4 v[230:231], off
	s_waitcnt vmcnt(8)
	s_waitcnt lgkmcnt(0)
	s_barrier
	s_setprio 1
	s_waitcnt lgkmcnt(0)
	v_mfma_f32_16x16x32_bf16 v[124:127], v[144:147], v[186:189], v[124:127]
	v_mfma_f32_16x16x32_bf16 v[120:123], v[160:163], v[186:189], v[120:123]
	v_mfma_f32_16x16x32_bf16 v[108:111], v[144:147], v[194:197], v[108:111]
	v_mfma_f32_16x16x32_bf16 v[104:107], v[160:163], v[194:197], v[104:107]
	v_mfma_f32_16x16x32_bf16 v[92:95], v[144:147], v[208:211], v[92:95]
	v_mfma_f32_16x16x32_bf16 v[88:91], v[160:163], v[208:211], v[88:91]
	v_mfma_f32_16x16x32_bf16 v[76:79], v[144:147], v[216:219], v[76:79]
	v_mfma_f32_16x16x32_bf16 v[72:75], v[160:163], v[216:219], v[72:75]
	v_mfma_f32_16x16x32_bf16 v[124:127], v[156:159], v[190:193], v[124:127]
	v_mfma_f32_16x16x32_bf16 v[120:123], v[164:167], v[190:193], v[120:123]
	v_mfma_f32_16x16x32_bf16 v[108:111], v[156:159], v[198:201], v[108:111]
	v_mfma_f32_16x16x32_bf16 v[104:107], v[164:167], v[198:201], v[104:107]
	v_mfma_f32_16x16x32_bf16 v[92:95], v[156:159], v[212:215], v[92:95]
	v_mfma_f32_16x16x32_bf16 v[88:91], v[164:167], v[212:215], v[88:91]
	v_mfma_f32_16x16x32_bf16 v[76:79], v[156:159], v[220:223], v[76:79]
	v_mfma_f32_16x16x32_bf16 v[72:75], v[164:167], v[220:223], v[72:75]
	s_setprio 0
	s_setprio 1
	v_mfma_f32_16x16x32_bf16 v[116:119], v[168:171], v[186:189], v[116:119]
	v_mfma_f32_16x16x32_bf16 v[112:115], v[176:179], v[186:189], v[112:115]
	v_mfma_f32_16x16x32_bf16 v[100:103], v[168:171], v[194:197], v[100:103]
	v_mfma_f32_16x16x32_bf16 v[96:99], v[176:179], v[194:197], v[96:99]
	v_mfma_f32_16x16x32_bf16 v[84:87], v[168:171], v[208:211], v[84:87]
	v_mfma_f32_16x16x32_bf16 v[80:83], v[176:179], v[208:211], v[80:83]
	v_mfma_f32_16x16x32_bf16 v[68:71], v[168:171], v[216:219], v[68:71]
	v_mfma_f32_16x16x32_bf16 v[64:67], v[176:179], v[216:219], v[64:67]
	v_mfma_f32_16x16x32_bf16 v[116:119], v[172:175], v[190:193], v[116:119]
	v_mfma_f32_16x16x32_bf16 v[112:115], v[182:185], v[190:193], v[112:115]
	v_mfma_f32_16x16x32_bf16 v[100:103], v[172:175], v[198:201], v[100:103]
	v_mfma_f32_16x16x32_bf16 v[96:99], v[182:185], v[198:201], v[96:99]
	v_mfma_f32_16x16x32_bf16 v[84:87], v[172:175], v[212:215], v[84:87]
	v_mfma_f32_16x16x32_bf16 v[80:83], v[182:185], v[212:215], v[80:83]
	v_mfma_f32_16x16x32_bf16 v[68:71], v[172:175], v[220:223], v[68:71]
	v_mfma_f32_16x16x32_bf16 v[64:67], v[182:185], v[220:223], v[64:67]
	s_setprio 0
	s_barrier
; #define PG8_STAGE(bufoff, gbase, voff) do { _Pragma("unroll") for (int _i = 0; _i < 2; ++_i) \
;         __builtin_amdgcn_global_load_lds((const unsigned*)((const char*)(gbase) + (voff)[_i]), (PG8_LAS unsigned*)(lds + (bufoff) + ldsw + _i * 8192), 16, 0, 0); } while (0)
; #define PG8_LDA(dst, b, h) do { _Pragma("unroll") for (int m = 0; m < 4; ++m) _Pragma("unroll") for (int k = 0; k < 2; ++k) dst[m][k] = *(const PG8_LAS bf16x8*)(lds + PG8_SA(b, h) + aoff + m * 2048 + k * 1024); } while (0)
; #define PG8_MMA(ai, bj, At, Bt) do { __builtin_amdgcn_s_setprio(1); _Pragma("unroll") for (int m = 0; m < 4; ++m) _Pragma("unroll") for (int n = 0; n < 2; ++n) _Pragma("unroll") for (int k = 0; k < 2; ++k) \
;         acc[ai][bj][m][n] = __builtin_amdgcn_mfma_f32_16x16x32_bf16(Bt[n][k], At[m][k], acc[ai][bj][m][n], 0, 0, 0); __builtin_amdgcn_s_setprio(0); } while (0)
; #define PG8_WAIT_V(n) asm volatile("s_waitcnt vmcnt(" #n ")" ::: "memory")
; #define PG8_WAIT_L(n) asm volatile("s_waitcnt lgkmcnt(" #n ")" ::: "memory")
; #define PG8_BAR __builtin_amdgcn_s_barrier()
; #define PG8_SCHED __builtin_amdgcn_sched_barrier(0)
; template <class Epi, class Sched, bool ALIGN_EPI = false, bool SP2 = false>
; __device__ __forceinline__ void gemm_phase(PG8_LAS unsigned char* lds, const Gemm g, const Sched& S, const Epi& E) {
;     ...
;             PG8_LDA(At, 1, 1); PG8_STAGE(PG8_SB(1, 0), b3, voffB); PG8_STAGE(PG8_SB(1, 1), b3 + hstep, voffB); PG8_STAGE(PG8_SA(1, 0), a3, voffA);
;             PG8_WAIT_V(8); PG8_WAIT_L(0); PG8_BAR; PG8_MMA(1, 0, At, B0); PG8_MMA(1, 1, At, B1); PG8_BAR; PG8_SCHED;
	s_add_i32 s50, s78, s3
	v_lshl_add_u64 v[202:203], v[202:203], 0, s[42:43]
	s_mov_b32 m0, s50
	ds_read_b128 v[186:189], v153 offset:49152
	ds_read_b128 v[190:193], v153 offset:50176
	ds_read_b128 v[194:197], v153 offset:51200
	ds_read_b128 v[198:201], v153 offset:52224
	ds_read_b128 v[208:211], v153 offset:53248
	ds_read_b128 v[212:215], v153 offset:54272
	ds_read_b128 v[216:219], v153 offset:55296
	ds_read_b128 v[220:223], v153 offset:56320
	global_load_lds_dwordx4 v[202:203], off
	s_add_i32 m0, s50, 0x2000
	s_add_u32 s50, s54, 0xb0080
	v_lshl_add_u64 v[202:203], v[224:225], 0, s[42:43]
	s_addc_u32 s51, s55, 0
	s_add_i32 s54, s79, s3
	global_load_lds_dwordx4 v[202:203], off
	v_lshl_add_u64 v[202:203], s[50:51], 0, v[130:131]
	s_mov_b32 m0, s54
	s_nop 0
	global_load_lds_dwordx4 v[202:203], off
	v_lshl_add_u64 v[202:203], s[50:51], 0, v[134:135]
	s_add_i32 m0, s54, 0x2000
	s_nop 0
	global_load_lds_dwordx4 v[202:203], off
	s_waitcnt vmcnt(6)
	s_waitcnt lgkmcnt(0)
	s_barrier
	s_setprio 1
	s_waitcnt lgkmcnt(0)
	v_mfma_f32_16x16x32_bf16 v[60:63], v[144:147], v[186:189], v[60:63]
	v_mfma_f32_16x16x32_bf16 v[56:59], v[160:163], v[186:189], v[56:59]
	v_mfma_f32_16x16x32_bf16 v[44:47], v[144:147], v[194:197], v[44:47]
	v_mfma_f32_16x16x32_bf16 v[40:43], v[160:163], v[194:197], v[40:43]
	v_mfma_f32_16x16x32_bf16 v[28:31], v[144:147], v[208:211], v[28:31]
	v_mfma_f32_16x16x32_bf16 v[24:27], v[160:163], v[208:211], v[24:27]
	v_mfma_f32_16x16x32_bf16 v[12:15], v[144:147], v[216:219], v[12:15]
	v_mfma_f32_16x16x32_bf16 v[8:11], v[160:163], v[216:219], v[8:11]
	v_mfma_f32_16x16x32_bf16 v[60:63], v[156:159], v[190:193], v[60:63]
	v_mfma_f32_16x16x32_bf16 v[56:59], v[164:167], v[190:193], v[56:59]
	v_mfma_f32_16x16x32_bf16 v[44:47], v[156:159], v[198:201], v[44:47]
	v_mfma_f32_16x16x32_bf16 v[40:43], v[164:167], v[198:201], v[40:43]
	v_mfma_f32_16x16x32_bf16 v[28:31], v[156:159], v[212:215], v[28:31]
	v_mfma_f32_16x16x32_bf16 v[24:27], v[164:167], v[212:215], v[24:27]
	v_mfma_f32_16x16x32_bf16 v[12:15], v[156:159], v[220:223], v[12:15]
	v_lshl_add_u64 v[202:203], v[226:227], 0, s[42:43]
	s_mov_b32 m0, s59
	s_nop 0
	global_load_lds_dwordx4 v[202:203], off
	v_mfma_f32_16x16x32_bf16 v[8:11], v[164:167], v[220:223], v[8:11]
	s_setprio 0
	s_setprio 1
	v_mfma_f32_16x16x32_bf16 v[52:55], v[168:171], v[186:189], v[52:55]
	v_mfma_f32_16x16x32_bf16 v[48:51], v[176:179], v[186:189], v[48:51]
	v_mfma_f32_16x16x32_bf16 v[36:39], v[168:171], v[194:197], v[36:39]
	v_mfma_f32_16x16x32_bf16 v[32:35], v[176:179], v[194:197], v[32:35]
	v_mfma_f32_16x16x32_bf16 v[20:23], v[168:171], v[208:211], v[20:23]
	v_mfma_f32_16x16x32_bf16 v[16:19], v[176:179], v[208:211], v[16:19]
	v_mfma_f32_16x16x32_bf16 v[4:7], v[168:171], v[216:219], v[4:7]
	v_mfma_f32_16x16x32_bf16 v[0:3], v[176:179], v[216:219], v[0:3]
	v_mfma_f32_16x16x32_bf16 v[52:55], v[172:175], v[190:193], v[52:55]
	v_mfma_f32_16x16x32_bf16 v[48:51], v[182:185], v[190:193], v[48:51]
	v_mfma_f32_16x16x32_bf16 v[36:39], v[172:175], v[198:201], v[36:39]
	v_mfma_f32_16x16x32_bf16 v[32:35], v[182:185], v[198:201], v[32:35]
	v_mfma_f32_16x16x32_bf16 v[20:23], v[172:175], v[212:215], v[20:23]
	v_mfma_f32_16x16x32_bf16 v[16:19], v[182:185], v[212:215], v[16:19]
	v_mfma_f32_16x16x32_bf16 v[4:7], v[172:175], v[220:223], v[4:7]
	v_lshl_add_u64 v[202:203], v[228:229], 0, s[42:43]
	s_mov_b32 m0, s60
	s_nop 0
	global_load_lds_dwordx4 v[202:203], off
	v_mfma_f32_16x16x32_bf16 v[0:3], v[182:185], v[220:223], v[0:3]
	s_setprio 0
	s_barrier
	s_add_i32 s77, s77, 2
	s_add_u32 s75, s75, 0x100
	s_addc_u32 s76, s76, 0
	s_cmp_gt_u32 s77, 41
	s_mov_b64 s[50:51], s[52:53]
	s_cbranch_scc0 .LBB0_1035
	s_and_b64 vcc, exec, s[44:45]
	s_cbranch_vccz .LBB0_1038
	s_barrier

; #define PG8_STAGE(bufoff, gbase, voff) do { _Pragma("unroll") for (int _i = 0; _i < 2; ++_i) \
;         __builtin_amdgcn_global_load_lds((const unsigned*)((const char*)(gbase) + (voff)[_i]), (PG8_LAS unsigned*)(lds + (bufoff) + ldsw + _i * 8192), 16, 0, 0); } while (0)
; #define PG8_LDA(dst, b, h) do { _Pragma("unroll") for (int m = 0; m < 4; ++m) _Pragma("unroll") for (int k = 0; k < 2; ++k) dst[m][k] = *(const PG8_LAS bf16x8*)(lds + PG8_SA(b, h) + aoff + m * 2048 + k * 1024); } while (0)
; #define PG8_LDB(dst, b, h) do { _Pragma("unroll") for (int n = 0; n < 2; ++n) _Pragma("unroll") for (int k = 0; k < 2; ++k) dst[n][k] = *(const PG8_LAS bf16x8*)(lds + PG8_SB(b, h) + boff + n * 2048 + k * 1024); } while (0)
; #define PG8_MMA(ai, bj, At, Bt) do { __builtin_amdgcn_s_setprio(1); _Pragma("unroll") for (int m = 0; m < 4; ++m) _Pragma("unroll") for (int n = 0; n < 2; ++n) _Pragma("unroll") for (int k = 0; k < 2; ++k) \
;         acc[ai][bj][m][n] = __builtin_amdgcn_mfma_f32_16x16x32_bf16(Bt[n][k], At[m][k], acc[ai][bj][m][n], 0, 0, 0); __builtin_amdgcn_s_setprio(0); } while (0)
; #define PG8_BAR __builtin_amdgcn_s_barrier()
; template <class Epi, class Sched, bool ALIGN_EPI = false, bool SP2 = false>
; __device__ __forceinline__ void gemm_phase(PG8_LAS unsigned char* lds, const Gemm g, const Sched& S, const Epi& E) {
;     ...
;         const bool has_next = S.next(ui + 1, nxt);
;         const char* nA = has_next ? (const char*)g.A + (size_t)nxt.pm * tstep : cA; const char* nB = has_next ? (const char*)g.Bt + (size_t)nxt.pn * tstep : cB;
;         for (int t = 0; t < nt; t += 2) {
;             const bool last = (t == nt - 2);
;             const char* a1 = cA + (size_t)(t + 1) * kstep;
;             const char* a2 = last ? nA : cA + (size_t)(t + 2) * kstep; const char* b2 = last ? nB : cB + (size_t)(t + 2) * kstep;
;             const char* a3 = a2 + kstep; const char* b3 = b2 + kstep;
;             if (last && has_next) S.a_ready(nxt);
;             if constexpr (SP2) {
;             PG8_LDB(B0, 0, 0); PG8_LDB(B1, 0, 1); PG8_SCHED; PG8_LDA(At, 0, 0); PG8_STAGE(PG8_SA(1, 1), a1 + hstep, voffA);
;             PG8_WAIT_V(8); PG8_WAIT_L(0); PG8_BAR; PG8_MMA(0, 0, At, B0); PG8_MMA(0, 1, At, B1); PG8_BAR; PG8_SCHED;
;             PG8_LDA(At, 0, 1); PG8_STAGE(PG8_SB(0, 0), b2, voffB); PG8_STAGE(PG8_SB(0, 1), b2 + hstep, voffB); PG8_STAGE(PG8_SA(0, 0), a2, voffA);
.LBB0_1118:
	s_ashr_i32 s45, s44, 31
	s_lshl_b64 s[48:49], s[44:45], 19
	s_add_u32 s48, s22, s48
	s_addc_u32 s49, s23, s49
	s_and_b64 s[50:51], s[10:11], exec
	s_cselect_b32 s45, s49, s55
	s_cselect_b32 s76, s48, s54
	s_ashr_i32 s43, s42, 31
	s_lshl_b64 s[50:51], s[42:43], 19
	s_add_u32 s50, s14, s50
	s_addc_u32 s51, s15, s51
	s_and_b64 s[58:59], s[10:11], exec
	s_cselect_b32 s43, s51, s57
	s_cselect_b32 s77, s50, s56
	s_add_u32 s54, s54, 0x40080
	s_addc_u32 s55, s55, 0
	s_add_u32 s82, s56, 0x100
	s_addc_u32 s83, s57, 0
	s_mov_b32 s84, -2
	ds_read_b128 v[144:147], v155
	ds_read_b128 v[148:151], v155 offset:1024
	ds_read_b128 v[160:163], v155 offset:2048
	ds_read_b128 v[164:167], v155 offset:3072
	ds_read_b128 v[168:171], v156
	ds_read_b128 v[172:175], v156 offset:1024
	ds_read_b128 v[176:179], v156 offset:2048
	ds_read_b128 v[182:185], v156 offset:3072
	s_add_u32 s56, s54, 0xfffc0080
	s_addc_u32 s57, s55, -1
	s_cmp_eq_u32 s84, 12
	s_cselect_b32 s59, s45, s57
	s_cselect_b32 s58, s76, s56
	s_cselect_b32 s57, s43, s83
	s_cselect_b32 s56, s77, s82
	v_lshl_add_u64 v[224:225], s[54:55], 0, v[136:137]
	s_add_i32 m0, s53, 0xc000
	ds_read_b128 v[186:189], v157
	ds_read_b128 v[190:193], v157 offset:1024
	ds_read_b128 v[194:197], v157 offset:2048
	ds_read_b128 v[198:201], v157 offset:3072
	ds_read_b128 v[208:211], v157 offset:4096
	ds_read_b128 v[212:215], v157 offset:5120
	ds_read_b128 v[216:219], v157 offset:6144
	ds_read_b128 v[220:223], v157 offset:7168
	global_load_lds_dwordx4 v[224:225], off
	v_lshl_add_u64 v[224:225], s[54:55], 0, v[138:139]
	s_add_i32 m0, s53, 0xe000
	s_nop 0
	global_load_lds_dwordx4 v[224:225], off
	s_waitcnt vmcnt(8)
	s_waitcnt lgkmcnt(0)
	s_barrier
	s_setprio 1
	s_waitcnt lgkmcnt(0)
	v_mfma_f32_16x16x32_bf16 v[124:127], v[144:147], v[186:189], 0
	v_mfma_f32_16x16x32_bf16 v[120:123], v[160:163], v[186:189], 0
	v_mfma_f32_16x16x32_bf16 v[108:111], v[144:147], v[194:197], 0
	v_mfma_f32_16x16x32_bf16 v[104:107], v[160:163], v[194:197], 0
	v_mfma_f32_16x16x32_bf16 v[92:95], v[144:147], v[208:211], 0
	v_mfma_f32_16x16x32_bf16 v[88:91], v[160:163], v[208:211], 0
	v_mfma_f32_16x16x32_bf16 v[76:79], v[144:147], v[216:219], 0
	v_mfma_f32_16x16x32_bf16 v[72:75], v[160:163], v[216:219], 0
	v_mfma_f32_16x16x32_bf16 v[124:127], v[148:151], v[190:193], v[124:127]
	v_mfma_f32_16x16x32_bf16 v[120:123], v[164:167], v[190:193], v[120:123]
	v_mfma_f32_16x16x32_bf16 v[108:111], v[148:151], v[198:201], v[108:111]
	v_mfma_f32_16x16x32_bf16 v[104:107], v[164:167], v[198:201], v[104:107]
	v_mfma_f32_16x16x32_bf16 v[92:95], v[148:151], v[212:215], v[92:95]
	v_mfma_f32_16x16x32_bf16 v[88:91], v[164:167], v[212:215], v[88:91]
	v_mfma_f32_16x16x32_bf16 v[76:79], v[148:151], v[220:223], v[76:79]
	v_mfma_f32_16x16x32_bf16 v[72:75], v[164:167], v[220:223], v[72:75]
	s_setprio 0
	s_setprio 1
	v_mfma_f32_16x16x32_bf16 v[116:119], v[168:171], v[186:189], 0
	v_mfma_f32_16x16x32_bf16 v[112:115], v[176:179], v[186:189], 0
	v_mfma_f32_16x16x32_bf16 v[100:103], v[168:171], v[194:197], 0
	v_mfma_f32_16x16x32_bf16 v[96:99], v[176:179], v[194:197], 0
	v_mfma_f32_16x16x32_bf16 v[84:87], v[168:171], v[208:211], 0
	v_mfma_f32_16x16x32_bf16 v[80:83], v[176:179], v[208:211], 0
	v_mfma_f32_16x16x32_bf16 v[68:71], v[168:171], v[216:219], 0
	v_mfma_f32_16x16x32_bf16 v[64:67], v[176:179], v[216:219], 0
	v_mfma_f32_16x16x32_bf16 v[116:119], v[172:175], v[190:193], v[116:119]
	v_mfma_f32_16x16x32_bf16 v[112:115], v[182:185], v[190:193], v[112:115]
	v_mfma_f32_16x16x32_bf16 v[100:103], v[172:175], v[198:201], v[100:103]
	v_mfma_f32_16x16x32_bf16 v[96:99], v[182:185], v[198:201], v[96:99]
	v_mfma_f32_16x16x32_bf16 v[84:87], v[172:175], v[212:215], v[84:87]
	v_mfma_f32_16x16x32_bf16 v[80:83], v[182:185], v[212:215], v[80:83]
	v_mfma_f32_16x16x32_bf16 v[68:71], v[172:175], v[220:223], v[68:71]
	v_mfma_f32_16x16x32_bf16 v[64:67], v[182:185], v[220:223], v[64:67]
	s_setprio 0
	s_barrier
	s_add_i32 s78, s66, s33
	v_lshl_add_u64 v[224:225], s[56:57], 0, v[132:133]
	s_mov_b32 m0, s78
	ds_read_b128 v[186:189], v157 offset:16384
	ds_read_b128 v[190:193], v157 offset:17408
	ds_read_b128 v[194:197], v157 offset:18432
	ds_read_b128 v[198:201], v157 offset:19456
	ds_read_b128 v[208:211], v157 offset:20480
	ds_read_b128 v[212:215], v157 offset:21504
	ds_read_b128 v[216:219], v157 offset:22528
	ds_read_b128 v[220:223], v157 offset:23552
	global_load_lds_dwordx4 v[224:225], off
	s_add_i32 m0, s78, 0x2000
	s_add_u32 s78, s56, 0x40000
	v_lshl_add_u64 v[226:227], s[56:57], 0, v[128:129]
	s_addc_u32 s79, s57, 0
	s_add_i32 s85, s67, s33
	global_load_lds_dwordx4 v[226:227], off
	v_lshl_add_u64 v[228:229], s[78:79], 0, v[132:133]
	s_mov_b32 m0, s85
	global_load_lds_dwordx4 v[228:229], off
	v_lshl_add_u64 v[228:229], s[78:79], 0, v[128:129]
	s_add_i32 m0, s85, 0x2000
	s_nop 0
	global_load_lds_dwordx4 v[228:229], off
	s_waitcnt vmcnt(6)
	s_waitcnt lgkmcnt(0)
	s_barrier
; #define PG8_STAGE(bufoff, gbase, voff) do { _Pragma("unroll") for (int _i = 0; _i < 2; ++_i) \
;         __builtin_amdgcn_global_load_lds((const unsigned*)((const char*)(gbase) + (voff)[_i]), (PG8_LAS unsigned*)(lds + (bufoff) + ldsw + _i * 8192), 16, 0, 0); } while (0)
; #define PG8_LDA(dst, b, h) do { _Pragma("unroll") for (int m = 0; m < 4; ++m) _Pragma("unroll") for (int k = 0; k < 2; ++k) dst[m][k] = *(const PG8_LAS bf16x8*)(lds + PG8_SA(b, h) + aoff + m * 2048 + k * 1024); } while (0)
; #define PG8_LDB(dst, b, h) do { _Pragma("unroll") for (int n = 0; n < 2; ++n) _Pragma("unroll") for (int k = 0; k < 2; ++k) dst[n][k] = *(const PG8_LAS bf16x8*)(lds + PG8_SB(b, h) + boff + n * 2048 + k * 1024); } while (0)
; #define PG8_MMA(ai, bj, At, Bt) do { __builtin_amdgcn_s_setprio(1); _Pragma("unroll") for (int m = 0; m < 4; ++m) _Pragma("unroll") for (int n = 0; n < 2; ++n) _Pragma("unroll") for (int k = 0; k < 2; ++k) \
;         acc[ai][bj][m][n] = __builtin_amdgcn_mfma_f32_16x16x32_bf16(Bt[n][k], At[m][k], acc[ai][bj][m][n], 0, 0, 0); __builtin_amdgcn_s_setprio(0); } while (0)
; #define PG8_WAIT_V(n) asm volatile("s_waitcnt vmcnt(" #n ")" ::: "memory")
; #define PG8_WAIT_L(n) asm volatile("s_waitcnt lgkmcnt(" #n ")" ::: "memory")
; #define PG8_BAR __builtin_amdgcn_s_barrier()
; #define PG8_SCHED __builtin_amdgcn_sched_barrier(0)
; template <class Epi, class Sched, bool ALIGN_EPI = false, bool SP2 = false>
; __device__ __forceinline__ void gemm_phase(PG8_LAS unsigned char* lds, const Gemm g, const Sched& S, const Epi& E) {
;     ...
;             PG8_LDA(At, 0, 1); PG8_STAGE(PG8_SB(0, 0), b2, voffB); PG8_STAGE(PG8_SB(0, 1), b2 + hstep, voffB); PG8_STAGE(PG8_SA(0, 0), a2, voffA);
;             PG8_WAIT_V(8); PG8_WAIT_L(0); PG8_BAR; PG8_MMA(1, 0, At, B0); PG8_MMA(1, 1, At, B1); PG8_BAR; PG8_SCHED;
;             PG8_LDB(B0, 1, 0); PG8_LDB(B1, 1, 1); PG8_SCHED; PG8_LDA(At, 1, 0); PG8_STAGE(PG8_SA(0, 1), a2 + hstep, voffA);
;             PG8_WAIT_V(8); PG8_WAIT_L(0); PG8_BAR; PG8_MMA(0, 0, At, B0); PG8_MMA(0, 1, At, B1); PG8_BAR; PG8_SCHED;
	s_setprio 1
	s_waitcnt lgkmcnt(0)
	v_mfma_f32_16x16x32_bf16 v[60:63], v[144:147], v[186:189], 0
	v_mfma_f32_16x16x32_bf16 v[56:59], v[160:163], v[186:189], 0
	v_mfma_f32_16x16x32_bf16 v[44:47], v[144:147], v[194:197], 0
	v_mfma_f32_16x16x32_bf16 v[40:43], v[160:163], v[194:197], 0
	v_mfma_f32_16x16x32_bf16 v[28:31], v[144:147], v[208:211], 0
	v_mfma_f32_16x16x32_bf16 v[24:27], v[160:163], v[208:211], 0
	v_mfma_f32_16x16x32_bf16 v[12:15], v[144:147], v[216:219], 0
	v_mfma_f32_16x16x32_bf16 v[8:11], v[160:163], v[216:219], 0
	v_mfma_f32_16x16x32_bf16 v[60:63], v[148:151], v[190:193], v[60:63]
	v_mfma_f32_16x16x32_bf16 v[56:59], v[164:167], v[190:193], v[56:59]
	v_mfma_f32_16x16x32_bf16 v[44:47], v[148:151], v[198:201], v[44:47]
	v_mfma_f32_16x16x32_bf16 v[40:43], v[164:167], v[198:201], v[40:43]
	v_mfma_f32_16x16x32_bf16 v[28:31], v[148:151], v[212:215], v[28:31]
	v_mfma_f32_16x16x32_bf16 v[24:27], v[164:167], v[212:215], v[24:27]
	v_mfma_f32_16x16x32_bf16 v[12:15], v[148:151], v[220:223], v[12:15]
	v_lshl_add_u64 v[228:229], s[58:59], 0, v[134:135]
	s_mov_b32 m0, s53
	s_nop 0
	global_load_lds_dwordx4 v[228:229], off
	v_mfma_f32_16x16x32_bf16 v[8:11], v[164:167], v[220:223], v[8:11]
	s_setprio 0
	s_setprio 1
	v_mfma_f32_16x16x32_bf16 v[52:55], v[168:171], v[186:189], 0
	v_mfma_f32_16x16x32_bf16 v[48:51], v[176:179], v[186:189], 0
	v_mfma_f32_16x16x32_bf16 v[36:39], v[168:171], v[194:197], 0
	v_mfma_f32_16x16x32_bf16 v[32:35], v[176:179], v[194:197], 0
	v_mfma_f32_16x16x32_bf16 v[20:23], v[168:171], v[208:211], 0
	v_mfma_f32_16x16x32_bf16 v[16:19], v[176:179], v[208:211], 0
	v_mfma_f32_16x16x32_bf16 v[4:7], v[168:171], v[216:219], 0
	v_mfma_f32_16x16x32_bf16 v[0:3], v[176:179], v[216:219], 0
	v_mfma_f32_16x16x32_bf16 v[52:55], v[172:175], v[190:193], v[52:55]
	v_mfma_f32_16x16x32_bf16 v[48:51], v[182:185], v[190:193], v[48:51]
	v_mfma_f32_16x16x32_bf16 v[36:39], v[172:175], v[198:201], v[36:39]
	v_mfma_f32_16x16x32_bf16 v[32:35], v[182:185], v[198:201], v[32:35]
	v_mfma_f32_16x16x32_bf16 v[20:23], v[172:175], v[212:215], v[20:23]
	v_mfma_f32_16x16x32_bf16 v[16:19], v[182:185], v[212:215], v[16:19]
	v_mfma_f32_16x16x32_bf16 v[4:7], v[172:175], v[220:223], v[4:7]
	v_lshl_add_u64 v[230:231], s[58:59], 0, v[130:131]
	s_mov_b32 m0, s60
	s_nop 0
	global_load_lds_dwordx4 v[230:231], off
	v_mfma_f32_16x16x32_bf16 v[0:3], v[182:185], v[220:223], v[0:3]
	s_setprio 0
	s_barrier
	s_add_i32 s78, 0, 0x18000
	v_add_u32_e32 v159, s78, v153
	s_add_i32 s79, 0, 0x1c000
	ds_read_b128 v[144:147], v159
	ds_read_b128 v[148:151], v159 offset:1024
	ds_read_b128 v[160:163], v159 offset:2048
	ds_read_b128 v[164:167], v159 offset:3072
	v_add_u32_e32 v159, s79, v153
	ds_read_b128 v[168:171], v159
	ds_read_b128 v[172:175], v159 offset:1024
	ds_read_b128 v[176:179], v159 offset:2048
	ds_read_b128 v[182:185], v159 offset:3072
	s_add_u32 s58, s58, 0x40000
	s_addc_u32 s59, s59, 0
	s_mov_b32 m0, s61
	v_lshl_add_u64 v[232:233], s[58:59], 0, v[134:135]
	ds_read_b128 v[186:189], v157 offset:32768
	ds_read_b128 v[190:193], v157 offset:33792
	ds_read_b128 v[194:197], v157 offset:34816
	ds_read_b128 v[198:201], v157 offset:35840
	ds_read_b128 v[208:211], v157 offset:36864
	ds_read_b128 v[212:215], v157 offset:37888
	ds_read_b128 v[216:219], v157 offset:38912
	ds_read_b128 v[220:223], v157 offset:39936
	global_load_lds_dwordx4 v[232:233], off
	v_lshl_add_u64 v[232:233], s[58:59], 0, v[130:131]
	s_mov_b32 m0, s62
	s_nop 0
	global_load_lds_dwordx4 v[232:233], off
	s_waitcnt vmcnt(8)
	s_waitcnt lgkmcnt(0)
	s_barrier
	s_setprio 1
	s_waitcnt lgkmcnt(0)
	v_mfma_f32_16x16x32_bf16 v[124:127], v[144:147], v[186:189], v[124:127]
	v_mfma_f32_16x16x32_bf16 v[120:123], v[160:163], v[186:189], v[120:123]
	v_mfma_f32_16x16x32_bf16 v[108:111], v[144:147], v[194:197], v[108:111]
	v_mfma_f32_16x16x32_bf16 v[104:107], v[160:163], v[194:197], v[104:107]
	v_mfma_f32_16x16x32_bf16 v[92:95], v[144:147], v[208:211], v[92:95]
	v_mfma_f32_16x16x32_bf16 v[88:91], v[160:163], v[208:211], v[88:91]
	v_mfma_f32_16x16x32_bf16 v[76:79], v[144:147], v[216:219], v[76:79]
	v_mfma_f32_16x16x32_bf16 v[72:75], v[160:163], v[216:219], v[72:75]
	v_mfma_f32_16x16x32_bf16 v[124:127], v[148:151], v[190:193], v[124:127]
	v_mfma_f32_16x16x32_bf16 v[120:123], v[164:167], v[190:193], v[120:123]
	v_mfma_f32_16x16x32_bf16 v[108:111], v[148:151], v[198:201], v[108:111]
	v_mfma_f32_16x16x32_bf16 v[104:107], v[164:167], v[198:201], v[104:107]
	v_mfma_f32_16x16x32_bf16 v[92:95], v[148:151], v[212:215], v[92:95]
	v_mfma_f32_16x16x32_bf16 v[88:91], v[164:167], v[212:215], v[88:91]
	v_mfma_f32_16x16x32_bf16 v[76:79], v[148:151], v[220:223], v[76:79]
	v_mfma_f32_16x16x32_bf16 v[72:75], v[164:167], v[220:223], v[72:75]
	s_setprio 0
	s_setprio 1
	v_mfma_f32_16x16x32_bf16 v[116:119], v[168:171], v[186:189], v[116:119]
	v_mfma_f32_16x16x32_bf16 v[112:115], v[176:179], v[186:189], v[112:115]
	v_mfma_f32_16x16x32_bf16 v[100:103], v[168:171], v[194:197], v[100:103]
	v_mfma_f32_16x16x32_bf16 v[96:99], v[176:179], v[194:197], v[96:99]
	v_mfma_f32_16x16x32_bf16 v[84:87], v[168:171], v[208:211], v[84:87]
	v_mfma_f32_16x16x32_bf16 v[80:83], v[176:179], v[208:211], v[80:83]
	v_mfma_f32_16x16x32_bf16 v[68:71], v[168:171], v[216:219], v[68:71]
	v_mfma_f32_16x16x32_bf16 v[64:67], v[176:179], v[216:219], v[64:67]
	v_mfma_f32_16x16x32_bf16 v[116:119], v[172:175], v[190:193], v[116:119]
	v_mfma_f32_16x16x32_bf16 v[112:115], v[182:185], v[190:193], v[112:115]
	v_mfma_f32_16x16x32_bf16 v[100:103], v[172:175], v[198:201], v[100:103]
	v_mfma_f32_16x16x32_bf16 v[96:99], v[182:185], v[198:201], v[96:99]
	v_mfma_f32_16x16x32_bf16 v[84:87], v[172:175], v[212:215], v[84:87]
	v_mfma_f32_16x16x32_bf16 v[80:83], v[182:185], v[212:215], v[80:83]
	v_mfma_f32_16x16x32_bf16 v[68:71], v[172:175], v[220:223], v[68:71]
	v_mfma_f32_16x16x32_bf16 v[64:67], v[182:185], v[220:223], v[64:67]
	s_setprio 0
	s_barrier
; #define PG8_STAGE(bufoff, gbase, voff) do { _Pragma("unroll") for (int _i = 0; _i < 2; ++_i) \
;         __builtin_amdgcn_global_load_lds((const unsigned*)((const char*)(gbase) + (voff)[_i]), (PG8_LAS unsigned*)(lds + (bufoff) + ldsw + _i * 8192), 16, 0, 0); } while (0)
; #define PG8_LDA(dst, b, h) do { _Pragma("unroll") for (int m = 0; m < 4; ++m) _Pragma("unroll") for (int k = 0; k < 2; ++k) dst[m][k] = *(const PG8_LAS bf16x8*)(lds + PG8_SA(b, h) + aoff + m * 2048 + k * 1024); } while (0)
; #define PG8_LDB(dst, b, h) do { _Pragma("unroll") for (int n = 0; n < 2; ++n) _Pragma("unroll") for (int k = 0; k < 2; ++k) dst[n][k] = *(const PG8_LAS bf16x8*)(lds + PG8_SB(b, h) + boff + n * 2048 + k * 1024); } while (0)
; template <class Epi, class Sched, bool ALIGN_EPI = false, bool SP2 = false>
; __device__ __forceinline__ void gemm_phase(PG8_LAS unsigned char* lds, const Gemm g, const Sched& S, const Epi& E) {
;     ...
;         for (int t = 0; t < nt; t += 2) {
;             const bool last = (t == nt - 2);
;             const char* a1 = cA + (size_t)(t + 1) * kstep;
;             const char* a2 = last ? nA : cA + (size_t)(t + 2) * kstep; const char* b2 = last ? nB : cB + (size_t)(t + 2) * kstep;
;             const char* a3 = a2 + kstep; const char* b3 = b2 + kstep;
;             if (last && has_next) S.a_ready(nxt);
;             if constexpr (SP2) {
;             PG8_LDB(B0, 0, 0); PG8_LDB(B1, 0, 1); PG8_SCHED; PG8_LDA(At, 0, 0); PG8_STAGE(PG8_SA(1, 1), a1 + hstep, voffA);
;             PG8_WAIT_V(8); PG8_WAIT_L(0); PG8_BAR; PG8_MMA(0, 0, At, B0); PG8_MMA(0, 1, At, B1); PG8_BAR; PG8_SCHED;
;             PG8_LDA(At, 0, 1); PG8_STAGE(PG8_SB(0, 0), b2, voffB); PG8_STAGE(PG8_SB(0, 1), b2 + hstep, voffB); PG8_STAGE(PG8_SA(0, 0), a2, voffA);
;             PG8_WAIT_V(8); PG8_WAIT_L(0); PG8_BAR; PG8_MMA(1, 0, At, B0); PG8_MMA(1, 1, At, B1); PG8_BAR; PG8_SCHED;
;             PG8_LDB(B0, 1, 0); PG8_LDB(B1, 1, 1); PG8_SCHED; PG8_LDA(At, 1, 0); PG8_STAGE(PG8_SA(0, 1), a2 + hstep, voffA);
;             PG8_WAIT_V(8); PG8_WAIT_L(0); PG8_BAR; PG8_MMA(0, 0, At, B0); PG8_MMA(0, 1, At, B1); PG8_BAR; PG8_SCHED;
;             PG8_LDA(At, 1, 1); PG8_STAGE(PG8_SB(1, 0), b3, voffB); PG8_STAGE(PG8_SB(1, 1), b3 + hstep, voffB); PG8_STAGE(PG8_SA(1, 0), a3, voffA);
;             PG8_WAIT_V(8); PG8_WAIT_L(0); PG8_BAR; PG8_MMA(1, 0, At, B0); PG8_MMA(1, 1, At, B1); PG8_BAR; PG8_SCHED;
	s_add_i32 s58, s78, s33
	v_lshl_add_u64 v[224:225], v[224:225], 0, s[12:13]
	s_mov_b32 m0, s58
	ds_read_b128 v[186:189], v157 offset:49152
	ds_read_b128 v[190:193], v157 offset:50176
	ds_read_b128 v[194:197], v157 offset:51200
	ds_read_b128 v[198:201], v157 offset:52224
	ds_read_b128 v[208:211], v157 offset:53248
	ds_read_b128 v[212:215], v157 offset:54272
	ds_read_b128 v[216:219], v157 offset:55296
	ds_read_b128 v[220:223], v157 offset:56320
	global_load_lds_dwordx4 v[224:225], off
	s_add_i32 m0, s58, 0x2000
	s_add_u32 s56, s56, 0x40080
	v_lshl_add_u64 v[224:225], v[226:227], 0, s[12:13]
	s_addc_u32 s57, s57, 0
	s_add_i32 s58, s79, s33
	global_load_lds_dwordx4 v[224:225], off
	v_lshl_add_u64 v[224:225], s[56:57], 0, v[132:133]
	s_mov_b32 m0, s58
	s_nop 0
	global_load_lds_dwordx4 v[224:225], off
	v_lshl_add_u64 v[224:225], s[56:57], 0, v[128:129]
	s_add_i32 m0, s58, 0x2000
	s_nop 0
	global_load_lds_dwordx4 v[224:225], off
	s_waitcnt vmcnt(6)
	s_waitcnt lgkmcnt(0)
	s_barrier
	s_setprio 1
	s_waitcnt lgkmcnt(0)
	v_mfma_f32_16x16x32_bf16 v[60:63], v[144:147], v[186:189], v[60:63]
	v_mfma_f32_16x16x32_bf16 v[56:59], v[160:163], v[186:189], v[56:59]
	v_mfma_f32_16x16x32_bf16 v[44:47], v[144:147], v[194:197], v[44:47]
	v_mfma_f32_16x16x32_bf16 v[40:43], v[160:163], v[194:197], v[40:43]
	v_mfma_f32_16x16x32_bf16 v[28:31], v[144:147], v[208:211], v[28:31]
	v_mfma_f32_16x16x32_bf16 v[24:27], v[160:163], v[208:211], v[24:27]
	v_mfma_f32_16x16x32_bf16 v[12:15], v[144:147], v[216:219], v[12:15]
	v_mfma_f32_16x16x32_bf16 v[8:11], v[160:163], v[216:219], v[8:11]
	v_mfma_f32_16x16x32_bf16 v[60:63], v[148:151], v[190:193], v[60:63]
	v_mfma_f32_16x16x32_bf16 v[56:59], v[164:167], v[190:193], v[56:59]
	v_mfma_f32_16x16x32_bf16 v[44:47], v[148:151], v[198:201], v[44:47]
	v_mfma_f32_16x16x32_bf16 v[40:43], v[164:167], v[198:201], v[40:43]
	v_mfma_f32_16x16x32_bf16 v[28:31], v[148:151], v[212:215], v[28:31]
	v_mfma_f32_16x16x32_bf16 v[24:27], v[164:167], v[212:215], v[24:27]
	v_mfma_f32_16x16x32_bf16 v[12:15], v[148:151], v[220:223], v[12:15]
	v_lshl_add_u64 v[224:225], v[228:229], 0, s[12:13]
	s_mov_b32 m0, s64
	s_nop 0
	global_load_lds_dwordx4 v[224:225], off
	v_mfma_f32_16x16x32_bf16 v[8:11], v[164:167], v[220:223], v[8:11]
	s_setprio 0
	s_setprio 1
	v_mfma_f32_16x16x32_bf16 v[52:55], v[168:171], v[186:189], v[52:55]
	v_mfma_f32_16x16x32_bf16 v[48:51], v[176:179], v[186:189], v[48:51]
	v_mfma_f32_16x16x32_bf16 v[36:39], v[168:171], v[194:197], v[36:39]
	v_mfma_f32_16x16x32_bf16 v[32:35], v[176:179], v[194:197], v[32:35]
	v_mfma_f32_16x16x32_bf16 v[20:23], v[168:171], v[208:211], v[20:23]
	v_mfma_f32_16x16x32_bf16 v[16:19], v[176:179], v[208:211], v[16:19]
	v_mfma_f32_16x16x32_bf16 v[4:7], v[168:171], v[216:219], v[4:7]
	v_mfma_f32_16x16x32_bf16 v[0:3], v[176:179], v[216:219], v[0:3]
	v_mfma_f32_16x16x32_bf16 v[52:55], v[172:175], v[190:193], v[52:55]
	v_mfma_f32_16x16x32_bf16 v[48:51], v[182:185], v[190:193], v[48:51]
	v_mfma_f32_16x16x32_bf16 v[36:39], v[172:175], v[198:201], v[36:39]
	v_mfma_f32_16x16x32_bf16 v[32:35], v[182:185], v[198:201], v[32:35]
	v_mfma_f32_16x16x32_bf16 v[20:23], v[172:175], v[212:215], v[20:23]
	v_mfma_f32_16x16x32_bf16 v[16:19], v[182:185], v[212:215], v[16:19]
	v_mfma_f32_16x16x32_bf16 v[4:7], v[172:175], v[220:223], v[4:7]
	v_lshl_add_u64 v[224:225], v[230:231], 0, s[12:13]
	s_mov_b32 m0, s65
	s_nop 0
	global_load_lds_dwordx4 v[224:225], off
	v_mfma_f32_16x16x32_bf16 v[0:3], v[182:185], v[220:223], v[0:3]
	s_setprio 0
	s_barrier
	s_add_i32 s84, s84, 2
	s_add_u32 s54, s54, 0x100
	s_addc_u32 s55, s55, 0
	s_add_u32 s82, s82, 0x100
	s_addc_u32 s83, s83, 0
.LBB0_1119:
	ds_read_b128 v[144:147], v155
	ds_read_b128 v[148:151], v155 offset:1024
	ds_read_b128 v[160:163], v155 offset:2048
	ds_read_b128 v[164:167], v155 offset:3072
	ds_read_b128 v[168:171], v156
	ds_read_b128 v[172:175], v156 offset:1024
	ds_read_b128 v[176:179], v156 offset:2048
	ds_read_b128 v[182:185], v156 offset:3072
	s_add_u32 s56, s54, 0xfffc0080
	s_addc_u32 s57, s55, -1
	s_cmp_eq_u32 s84, 12
	s_cselect_b32 s59, s45, s57
	s_cselect_b32 s58, s76, s56
	s_cselect_b32 s57, s43, s83
	s_cselect_b32 s56, s77, s82
	v_lshl_add_u64 v[224:225], s[54:55], 0, v[136:137]
	s_add_i32 m0, s53, 0xc000
	ds_read_b128 v[186:189], v157
	ds_read_b128 v[190:193], v157 offset:1024
	ds_read_b128 v[194:197], v157 offset:2048
	ds_read_b128 v[198:201], v157 offset:3072
	ds_read_b128 v[208:211], v157 offset:4096
	ds_read_b128 v[212:215], v157 offset:5120
	ds_read_b128 v[216:219], v157 offset:6144
	ds_read_b128 v[220:223], v157 offset:7168
	global_load_lds_dwordx4 v[224:225], off
	v_lshl_add_u64 v[224:225], s[54:55], 0, v[138:139]
	s_add_i32 m0, s53, 0xe000
	s_nop 0
	global_load_lds_dwordx4 v[224:225], off
	s_waitcnt vmcnt(8)
	s_waitcnt lgkmcnt(0)
	s_barrier
; #define PG8_STAGE(bufoff, gbase, voff) do { _Pragma("unroll") for (int _i = 0; _i < 2; ++_i) \
;         __builtin_amdgcn_global_load_lds((const unsigned*)((const char*)(gbase) + (voff)[_i]), (PG8_LAS unsigned*)(lds + (bufoff) + ldsw + _i * 8192), 16, 0, 0); } while (0)
; #define PG8_LDA(dst, b, h) do { _Pragma("unroll") for (int m = 0; m < 4; ++m) _Pragma("unroll") for (int k = 0; k < 2; ++k) dst[m][k] = *(const PG8_LAS bf16x8*)(lds + PG8_SA(b, h) + aoff + m * 2048 + k * 1024); } while (0)
; #define PG8_LDB(dst, b, h) do { _Pragma("unroll") for (int n = 0; n < 2; ++n) _Pragma("unroll") for (int k = 0; k < 2; ++k) dst[n][k] = *(const PG8_LAS bf16x8*)(lds + PG8_SB(b, h) + boff + n * 2048 + k * 1024); } while (0)
; #define PG8_MMA(ai, bj, At, Bt) do { __builtin_amdgcn_s_setprio(1); _Pragma("unroll") for (int m = 0; m < 4; ++m) _Pragma("unroll") for (int n = 0; n < 2; ++n) _Pragma("unroll") for (int k = 0; k < 2; ++k) \
;         acc[ai][bj][m][n] = __builtin_amdgcn_mfma_f32_16x16x32_bf16(Bt[n][k], At[m][k], acc[ai][bj][m][n], 0, 0, 0); __builtin_amdgcn_s_setprio(0); } while (0)
; #define PG8_WAIT_V(n) asm volatile("s_waitcnt vmcnt(" #n ")" ::: "memory")
; #define PG8_WAIT_L(n) asm volatile("s_waitcnt lgkmcnt(" #n ")" ::: "memory")
; #define PG8_BAR __builtin_amdgcn_s_barrier()
; #define PG8_SCHED __builtin_amdgcn_sched_barrier(0)
; template <class Epi, class Sched, bool ALIGN_EPI = false, bool SP2 = false>
; __device__ __forceinline__ void gemm_phase(PG8_LAS unsigned char* lds, const Gemm g, const Sched& S, const Epi& E) {
;     ...
;             PG8_LDB(B0, 0, 0); PG8_LDB(B1, 0, 1); PG8_SCHED; PG8_LDA(At, 0, 0); PG8_STAGE(PG8_SA(1, 1), a1 + hstep, voffA);
;             PG8_WAIT_V(8); PG8_WAIT_L(0); PG8_BAR; PG8_MMA(0, 0, At, B0); PG8_MMA(0, 1, At, B1); PG8_BAR; PG8_SCHED;
;             PG8_LDA(At, 0, 1); PG8_STAGE(PG8_SB(0, 0), b2, voffB); PG8_STAGE(PG8_SB(0, 1), b2 + hstep, voffB); PG8_STAGE(PG8_SA(0, 0), a2, voffA);
;             PG8_WAIT_V(8); PG8_WAIT_L(0); PG8_BAR; PG8_MMA(1, 0, At, B0); PG8_MMA(1, 1, At, B1); PG8_BAR; PG8_SCHED;
	s_setprio 1
	s_waitcnt lgkmcnt(0)
	v_mfma_f32_16x16x32_bf16 v[124:127], v[144:147], v[186:189], v[124:127]
	v_mfma_f32_16x16x32_bf16 v[120:123], v[160:163], v[186:189], v[120:123]
	v_mfma_f32_16x16x32_bf16 v[108:111], v[144:147], v[194:197], v[108:111]
	v_mfma_f32_16x16x32_bf16 v[104:107], v[160:163], v[194:197], v[104:107]
	v_mfma_f32_16x16x32_bf16 v[92:95], v[144:147], v[208:211], v[92:95]
	v_mfma_f32_16x16x32_bf16 v[88:91], v[160:163], v[208:211], v[88:91]
	v_mfma_f32_16x16x32_bf16 v[76:79], v[144:147], v[216:219], v[76:79]
	v_mfma_f32_16x16x32_bf16 v[72:75], v[160:163], v[216:219], v[72:75]
	v_mfma_f32_16x16x32_bf16 v[124:127], v[148:151], v[190:193], v[124:127]
	v_mfma_f32_16x16x32_bf16 v[120:123], v[164:167], v[190:193], v[120:123]
	v_mfma_f32_16x16x32_bf16 v[108:111], v[148:151], v[198:201], v[108:111]
	v_mfma_f32_16x16x32_bf16 v[104:107], v[164:167], v[198:201], v[104:107]
	v_mfma_f32_16x16x32_bf16 v[92:95], v[148:151], v[212:215], v[92:95]
	v_mfma_f32_16x16x32_bf16 v[88:91], v[164:167], v[212:215], v[88:91]
	v_mfma_f32_16x16x32_bf16 v[76:79], v[148:151], v[220:223], v[76:79]
	v_mfma_f32_16x16x32_bf16 v[72:75], v[164:167], v[220:223], v[72:75]
	s_setprio 0
	s_setprio 1
	v_mfma_f32_16x16x32_bf16 v[116:119], v[168:171], v[186:189], v[116:119]
	v_mfma_f32_16x16x32_bf16 v[112:115], v[176:179], v[186:189], v[112:115]
	v_mfma_f32_16x16x32_bf16 v[100:103], v[168:171], v[194:197], v[100:103]
	v_mfma_f32_16x16x32_bf16 v[96:99], v[176:179], v[194:197], v[96:99]
	v_mfma_f32_16x16x32_bf16 v[84:87], v[168:171], v[208:211], v[84:87]
	v_mfma_f32_16x16x32_bf16 v[80:83], v[176:179], v[208:211], v[80:83]
	v_mfma_f32_16x16x32_bf16 v[68:71], v[168:171], v[216:219], v[68:71]
	v_mfma_f32_16x16x32_bf16 v[64:67], v[176:179], v[216:219], v[64:67]
	v_mfma_f32_16x16x32_bf16 v[116:119], v[172:175], v[190:193], v[116:119]
	v_mfma_f32_16x16x32_bf16 v[112:115], v[182:185], v[190:193], v[112:115]
	v_mfma_f32_16x16x32_bf16 v[100:103], v[172:175], v[198:201], v[100:103]
	v_mfma_f32_16x16x32_bf16 v[96:99], v[182:185], v[198:201], v[96:99]
	v_mfma_f32_16x16x32_bf16 v[84:87], v[172:175], v[212:215], v[84:87]
	v_mfma_f32_16x16x32_bf16 v[80:83], v[182:185], v[212:215], v[80:83]
	v_mfma_f32_16x16x32_bf16 v[68:71], v[172:175], v[220:223], v[68:71]
	v_mfma_f32_16x16x32_bf16 v[64:67], v[182:185], v[220:223], v[64:67]
	s_setprio 0
	s_barrier
	s_add_i32 s78, s66, s33
	v_lshl_add_u64 v[224:225], s[56:57], 0, v[132:133]
	s_mov_b32 m0, s78
	ds_read_b128 v[186:189], v157 offset:16384
	ds_read_b128 v[190:193], v157 offset:17408
	ds_read_b128 v[194:197], v157 offset:18432
	ds_read_b128 v[198:201], v157 offset:19456
	ds_read_b128 v[208:211], v157 offset:20480
	ds_read_b128 v[212:215], v157 offset:21504
	ds_read_b128 v[216:219], v157 offset:22528
	ds_read_b128 v[220:223], v157 offset:23552
	global_load_lds_dwordx4 v[224:225], off
	s_add_i32 m0, s78, 0x2000
	s_add_u32 s78, s56, 0x40000
	v_lshl_add_u64 v[226:227], s[56:57], 0, v[128:129]
	s_addc_u32 s79, s57, 0
	s_add_i32 s85, s67, s33
	global_load_lds_dwordx4 v[226:227], off
	v_lshl_add_u64 v[228:229], s[78:79], 0, v[132:133]
	s_mov_b32 m0, s85
	global_load_lds_dwordx4 v[228:229], off
	v_lshl_add_u64 v[228:229], s[78:79], 0, v[128:129]
	s_add_i32 m0, s85, 0x2000
	s_nop 0
	global_load_lds_dwordx4 v[228:229], off
	s_waitcnt vmcnt(6)
	s_waitcnt lgkmcnt(0)
	s_barrier
	s_setprio 1
	s_waitcnt lgkmcnt(0)
	v_mfma_f32_16x16x32_bf16 v[60:63], v[144:147], v[186:189], v[60:63]
	v_mfma_f32_16x16x32_bf16 v[56:59], v[160:163], v[186:189], v[56:59]
	v_mfma_f32_16x16x32_bf16 v[44:47], v[144:147], v[194:197], v[44:47]
	v_mfma_f32_16x16x32_bf16 v[40:43], v[160:163], v[194:197], v[40:43]
	v_mfma_f32_16x16x32_bf16 v[28:31], v[144:147], v[208:211], v[28:31]
	v_mfma_f32_16x16x32_bf16 v[24:27], v[160:163], v[208:211], v[24:27]
	v_mfma_f32_16x16x32_bf16 v[12:15], v[144:147], v[216:219], v[12:15]
	v_mfma_f32_16x16x32_bf16 v[8:11], v[160:163], v[216:219], v[8:11]
	v_mfma_f32_16x16x32_bf16 v[60:63], v[148:151], v[190:193], v[60:63]
	v_mfma_f32_16x16x32_bf16 v[56:59], v[164:167], v[190:193], v[56:59]
	v_mfma_f32_16x16x32_bf16 v[44:47], v[148:151], v[198:201], v[44:47]
	v_mfma_f32_16x16x32_bf16 v[40:43], v[164:167], v[198:201], v[40:43]
	v_mfma_f32_16x16x32_bf16 v[28:31], v[148:151], v[212:215], v[28:31]
	v_mfma_f32_16x16x32_bf16 v[24:27], v[164:167], v[212:215], v[24:27]
	v_mfma_f32_16x16x32_bf16 v[12:15], v[148:151], v[220:223], v[12:15]
	v_lshl_add_u64 v[228:229], s[58:59], 0, v[134:135]
	s_mov_b32 m0, s53
	s_nop 0
	global_load_lds_dwordx4 v[228:229], off
	v_mfma_f32_16x16x32_bf16 v[8:11], v[164:167], v[220:223], v[8:11]
	s_setprio 0
	s_setprio 1
	v_mfma_f32_16x16x32_bf16 v[52:55], v[168:171], v[186:189], v[52:55]
	v_mfma_f32_16x16x32_bf16 v[48:51], v[176:179], v[186:189], v[48:51]
	v_mfma_f32_16x16x32_bf16 v[36:39], v[168:171], v[194:197], v[36:39]
	v_mfma_f32_16x16x32_bf16 v[32:35], v[176:179], v[194:197], v[32:35]
	v_mfma_f32_16x16x32_bf16 v[20:23], v[168:171], v[208:211], v[20:23]
	v_mfma_f32_16x16x32_bf16 v[16:19], v[176:179], v[208:211], v[16:19]
	v_mfma_f32_16x16x32_bf16 v[4:7], v[168:171], v[216:219], v[4:7]
	v_mfma_f32_16x16x32_bf16 v[0:3], v[176:179], v[216:219], v[0:3]
	v_mfma_f32_16x16x32_bf16 v[52:55], v[172:175], v[190:193], v[52:55]
	v_mfma_f32_16x16x32_bf16 v[48:51], v[182:185], v[190:193], v[48:51]
	v_mfma_f32_16x16x32_bf16 v[36:39], v[172:175], v[198:201], v[36:39]
	v_mfma_f32_16x16x32_bf16 v[32:35], v[182:185], v[198:201], v[32:35]
	v_mfma_f32_16x16x32_bf16 v[20:23], v[172:175], v[212:215], v[20:23]
	v_mfma_f32_16x16x32_bf16 v[16:19], v[182:185], v[212:215], v[16:19]
	v_mfma_f32_16x16x32_bf16 v[4:7], v[172:175], v[220:223], v[4:7]
	v_lshl_add_u64 v[230:231], s[58:59], 0, v[130:131]
	s_mov_b32 m0, s60
	s_nop 0
	global_load_lds_dwordx4 v[230:231], off
	v_mfma_f32_16x16x32_bf16 v[0:3], v[182:185], v[220:223], v[0:3]
	s_setprio 0
	s_barrier
; #define PG8_STAGE(bufoff, gbase, voff) do { _Pragma("unroll") for (int _i = 0; _i < 2; ++_i) \
;         __builtin_amdgcn_global_load_lds((const unsigned*)((const char*)(gbase) + (voff)[_i]), (PG8_LAS unsigned*)(lds + (bufoff) + ldsw + _i * 8192), 16, 0, 0); } while (0)
; #define PG8_LDA(dst, b, h) do { _Pragma("unroll") for (int m = 0; m < 4; ++m) _Pragma("unroll") for (int k = 0; k < 2; ++k) dst[m][k] = *(const PG8_LAS bf16x8*)(lds + PG8_SA(b, h) + aoff + m * 2048 + k * 1024); } while (0)
; #define PG8_LDB(dst, b, h) do { _Pragma("unroll") for (int n = 0; n < 2; ++n) _Pragma("unroll") for (int k = 0; k < 2; ++k) dst[n][k] = *(const PG8_LAS bf16x8*)(lds + PG8_SB(b, h) + boff + n * 2048 + k * 1024); } while (0)
; #define PG8_MMA(ai, bj, At, Bt) do { __builtin_amdgcn_s_setprio(1); _Pragma("unroll") for (int m = 0; m < 4; ++m) _Pragma("unroll") for (int n = 0; n < 2; ++n) _Pragma("unroll") for (int k = 0; k < 2; ++k) \
;         acc[ai][bj][m][n] = __builtin_amdgcn_mfma_f32_16x16x32_bf16(Bt[n][k], At[m][k], acc[ai][bj][m][n], 0, 0, 0); __builtin_amdgcn_s_setprio(0); } while (0)
; #define PG8_WAIT_V(n) asm volatile("s_waitcnt vmcnt(" #n ")" ::: "memory")
; #define PG8_WAIT_L(n) asm volatile("s_waitcnt lgkmcnt(" #n ")" ::: "memory")
; #define PG8_BAR __builtin_amdgcn_s_barrier()
; #define PG8_SCHED __builtin_amdgcn_sched_barrier(0)
; template <class Epi, class Sched, bool ALIGN_EPI = false, bool SP2 = false>
; __device__ __forceinline__ void gemm_phase(PG8_LAS unsigned char* lds, const Gemm g, const Sched& S, const Epi& E) {
;     ...
;             PG8_LDB(B0, 1, 0); PG8_LDB(B1, 1, 1); PG8_SCHED; PG8_LDA(At, 1, 0); PG8_STAGE(PG8_SA(0, 1), a2 + hstep, voffA);
;             PG8_WAIT_V(8); PG8_WAIT_L(0); PG8_BAR; PG8_MMA(0, 0, At, B0); PG8_MMA(0, 1, At, B1); PG8_BAR; PG8_SCHED;
	s_add_i32 s78, 0, 0x18000
	v_add_u32_e32 v159, s78, v153
	s_add_i32 s79, 0, 0x1c000
	ds_read_b128 v[144:147], v159
	ds_read_b128 v[148:151], v159 offset:1024
	ds_read_b128 v[160:163], v159 offset:2048
	ds_read_b128 v[164:167], v159 offset:3072
	v_add_u32_e32 v159, s79, v153
	ds_read_b128 v[168:171], v159
	ds_read_b128 v[172:175], v159 offset:1024
	ds_read_b128 v[176:179], v159 offset:2048
	ds_read_b128 v[182:185], v159 offset:3072
	s_add_u32 s58, s58, 0x40000
	s_addc_u32 s59, s59, 0
	s_mov_b32 m0, s61
	v_lshl_add_u64 v[232:233], s[58:59], 0, v[134:135]
	ds_read_b128 v[186:189], v157 offset:32768
	ds_read_b128 v[190:193], v157 offset:33792
	ds_read_b128 v[194:197], v157 offset:34816
	ds_read_b128 v[198:201], v157 offset:35840
	ds_read_b128 v[208:211], v157 offset:36864
	ds_read_b128 v[212:215], v157 offset:37888
	ds_read_b128 v[216:219], v157 offset:38912
	ds_read_b128 v[220:223], v157 offset:39936
	global_load_lds_dwordx4 v[232:233], off
	v_lshl_add_u64 v[232:233], s[58:59], 0, v[130:131]
	s_mov_b32 m0, s62
	s_nop 0
	global_load_lds_dwordx4 v[232:233], off
	s_waitcnt vmcnt(8)
	s_waitcnt lgkmcnt(0)
	s_barrier
	s_setprio 1
	s_waitcnt lgkmcnt(0)
	v_mfma_f32_16x16x32_bf16 v[124:127], v[144:147], v[186:189], v[124:127]
	v_mfma_f32_16x16x32_bf16 v[120:123], v[160:163], v[186:189], v[120:123]
	v_mfma_f32_16x16x32_bf16 v[108:111], v[144:147], v[194:197], v[108:111]
	v_mfma_f32_16x16x32_bf16 v[104:107], v[160:163], v[194:197], v[104:107]
	v_mfma_f32_16x16x32_bf16 v[92:95], v[144:147], v[208:211], v[92:95]
	v_mfma_f32_16x16x32_bf16 v[88:91], v[160:163], v[208:211], v[88:91]
	v_mfma_f32_16x16x32_bf16 v[76:79], v[144:147], v[216:219], v[76:79]
	v_mfma_f32_16x16x32_bf16 v[72:75], v[160:163], v[216:219], v[72:75]
	v_mfma_f32_16x16x32_bf16 v[124:127], v[148:151], v[190:193], v[124:127]
	v_mfma_f32_16x16x32_bf16 v[120:123], v[164:167], v[190:193], v[120:123]
	v_mfma_f32_16x16x32_bf16 v[108:111], v[148:151], v[198:201], v[108:111]
	v_mfma_f32_16x16x32_bf16 v[104:107], v[164:167], v[198:201], v[104:107]
	v_mfma_f32_16x16x32_bf16 v[92:95], v[148:151], v[212:215], v[92:95]
	v_mfma_f32_16x16x32_bf16 v[88:91], v[164:167], v[212:215], v[88:91]
	v_mfma_f32_16x16x32_bf16 v[76:79], v[148:151], v[220:223], v[76:79]
	v_mfma_f32_16x16x32_bf16 v[72:75], v[164:167], v[220:223], v[72:75]
	s_setprio 0
	s_setprio 1
	v_mfma_f32_16x16x32_bf16 v[116:119], v[168:171], v[186:189], v[116:119]
	v_mfma_f32_16x16x32_bf16 v[112:115], v[176:179], v[186:189], v[112:115]
	v_mfma_f32_16x16x32_bf16 v[100:103], v[168:171], v[194:197], v[100:103]
	v_mfma_f32_16x16x32_bf16 v[96:99], v[176:179], v[194:197], v[96:99]
	v_mfma_f32_16x16x32_bf16 v[84:87], v[168:171], v[208:211], v[84:87]
	v_mfma_f32_16x16x32_bf16 v[80:83], v[176:179], v[208:211], v[80:83]
	v_mfma_f32_16x16x32_bf16 v[68:71], v[168:171], v[216:219], v[68:71]
	v_mfma_f32_16x16x32_bf16 v[64:67], v[176:179], v[216:219], v[64:67]
	v_mfma_f32_16x16x32_bf16 v[116:119], v[172:175], v[190:193], v[116:119]
	v_mfma_f32_16x16x32_bf16 v[112:115], v[182:185], v[190:193], v[112:115]
	v_mfma_f32_16x16x32_bf16 v[100:103], v[172:175], v[198:201], v[100:103]
	v_mfma_f32_16x16x32_bf16 v[96:99], v[182:185], v[198:201], v[96:99]
	v_mfma_f32_16x16x32_bf16 v[84:87], v[172:175], v[212:215], v[84:87]
	v_mfma_f32_16x16x32_bf16 v[80:83], v[182:185], v[212:215], v[80:83]
	v_mfma_f32_16x16x32_bf16 v[68:71], v[172:175], v[220:223], v[68:71]
	v_mfma_f32_16x16x32_bf16 v[64:67], v[182:185], v[220:223], v[64:67]
	s_setprio 0
	s_barrier
; #define PG8_STAGE(bufoff, gbase, voff) do { _Pragma("unroll") for (int _i = 0; _i < 2; ++_i) \
;         __builtin_amdgcn_global_load_lds((const unsigned*)((const char*)(gbase) + (voff)[_i]), (PG8_LAS unsigned*)(lds + (bufoff) + ldsw + _i * 8192), 16, 0, 0); } while (0)
; #define PG8_LDA(dst, b, h) do { _Pragma("unroll") for (int m = 0; m < 4; ++m) _Pragma("unroll") for (int k = 0; k < 2; ++k) dst[m][k] = *(const PG8_LAS bf16x8*)(lds + PG8_SA(b, h) + aoff + m * 2048 + k * 1024); } while (0)
; #define PG8_MMA(ai, bj, At, Bt) do { __builtin_amdgcn_s_setprio(1); _Pragma("unroll") for (int m = 0; m < 4; ++m) _Pragma("unroll") for (int n = 0; n < 2; ++n) _Pragma("unroll") for (int k = 0; k < 2; ++k) \
;         acc[ai][bj][m][n] = __builtin_amdgcn_mfma_f32_16x16x32_bf16(Bt[n][k], At[m][k], acc[ai][bj][m][n], 0, 0, 0); __builtin_amdgcn_s_setprio(0); } while (0)
; #define PG8_WAIT_V(n) asm volatile("s_waitcnt vmcnt(" #n ")" ::: "memory")
; #define PG8_WAIT_L(n) asm volatile("s_waitcnt lgkmcnt(" #n ")" ::: "memory")
; #define PG8_BAR __builtin_amdgcn_s_barrier()
; #define PG8_SCHED __builtin_amdgcn_sched_barrier(0)
; __device__ __forceinline__ float row_rs(const float* ssp, int row) { const unsigned long long v = ((const unsigned long long*)ssp)[row];
;     return __builtin_amdgcn_rsqf((float)v * (1.0f / 4294967296.0f) * (1.0f / 1024.0f) + RMS_EPS); }
; template <class Epi, class Sched, bool ALIGN_EPI = false, bool SP2 = false>
; __device__ __forceinline__ void gemm_phase(PG8_LAS unsigned char* lds, const Gemm g, const Sched& S, const Epi& E) {
;     ...
;             PG8_LDA(At, 1, 1); PG8_STAGE(PG8_SB(1, 0), b3, voffB); PG8_STAGE(PG8_SB(1, 1), b3 + hstep, voffB); PG8_STAGE(PG8_SA(1, 0), a3, voffA);
;             PG8_WAIT_V(8); PG8_WAIT_L(0); PG8_BAR; PG8_MMA(1, 0, At, B0); PG8_MMA(1, 1, At, B1); PG8_BAR; PG8_SCHED;
	s_add_i32 s58, s78, s33
	v_lshl_add_u64 v[224:225], v[224:225], 0, s[12:13]
	s_mov_b32 m0, s58
	ds_read_b128 v[186:189], v157 offset:49152
	ds_read_b128 v[190:193], v157 offset:50176
	ds_read_b128 v[194:197], v157 offset:51200
	ds_read_b128 v[198:201], v157 offset:52224
	ds_read_b128 v[208:211], v157 offset:53248
	ds_read_b128 v[212:215], v157 offset:54272
	ds_read_b128 v[216:219], v157 offset:55296
	ds_read_b128 v[220:223], v157 offset:56320
	global_load_lds_dwordx4 v[224:225], off
	s_add_i32 m0, s58, 0x2000
	s_add_u32 s56, s56, 0x40080
	v_lshl_add_u64 v[224:225], v[226:227], 0, s[12:13]
	s_addc_u32 s57, s57, 0
	s_add_i32 s58, s79, s33
	global_load_lds_dwordx4 v[224:225], off
	v_lshl_add_u64 v[224:225], s[56:57], 0, v[132:133]
	s_mov_b32 m0, s58
	s_nop 0
	global_load_lds_dwordx4 v[224:225], off
	v_lshl_add_u64 v[224:225], s[56:57], 0, v[128:129]
	s_add_i32 m0, s58, 0x2000
	s_nop 0
	global_load_lds_dwordx4 v[224:225], off
	s_waitcnt vmcnt(6)
	s_waitcnt lgkmcnt(0)
	s_barrier
	s_setprio 1
	s_waitcnt lgkmcnt(0)
	v_mfma_f32_16x16x32_bf16 v[60:63], v[144:147], v[186:189], v[60:63]
	v_mfma_f32_16x16x32_bf16 v[56:59], v[160:163], v[186:189], v[56:59]
	v_mfma_f32_16x16x32_bf16 v[44:47], v[144:147], v[194:197], v[44:47]
	v_mfma_f32_16x16x32_bf16 v[40:43], v[160:163], v[194:197], v[40:43]
	v_mfma_f32_16x16x32_bf16 v[28:31], v[144:147], v[208:211], v[28:31]
	v_mfma_f32_16x16x32_bf16 v[24:27], v[160:163], v[208:211], v[24:27]
	v_mfma_f32_16x16x32_bf16 v[12:15], v[144:147], v[216:219], v[12:15]
	v_mfma_f32_16x16x32_bf16 v[8:11], v[160:163], v[216:219], v[8:11]
	v_mfma_f32_16x16x32_bf16 v[60:63], v[148:151], v[190:193], v[60:63]
	v_mfma_f32_16x16x32_bf16 v[56:59], v[164:167], v[190:193], v[56:59]
	v_mfma_f32_16x16x32_bf16 v[44:47], v[148:151], v[198:201], v[44:47]
	v_mfma_f32_16x16x32_bf16 v[40:43], v[164:167], v[198:201], v[40:43]
	v_mfma_f32_16x16x32_bf16 v[28:31], v[148:151], v[212:215], v[28:31]
	v_mfma_f32_16x16x32_bf16 v[24:27], v[164:167], v[212:215], v[24:27]
	v_mfma_f32_16x16x32_bf16 v[12:15], v[148:151], v[220:223], v[12:15]
	v_lshl_add_u64 v[224:225], v[228:229], 0, s[12:13]
	s_mov_b32 m0, s64
	s_nop 0
	global_load_lds_dwordx4 v[224:225], off
	v_mfma_f32_16x16x32_bf16 v[8:11], v[164:167], v[220:223], v[8:11]
	s_setprio 0
	s_setprio 1
	v_mfma_f32_16x16x32_bf16 v[52:55], v[168:171], v[186:189], v[52:55]
	v_mfma_f32_16x16x32_bf16 v[48:51], v[176:179], v[186:189], v[48:51]
	v_mfma_f32_16x16x32_bf16 v[36:39], v[168:171], v[194:197], v[36:39]
	v_mfma_f32_16x16x32_bf16 v[32:35], v[176:179], v[194:197], v[32:35]
	v_mfma_f32_16x16x32_bf16 v[20:23], v[168:171], v[208:211], v[20:23]
	v_mfma_f32_16x16x32_bf16 v[16:19], v[176:179], v[208:211], v[16:19]
	v_mfma_f32_16x16x32_bf16 v[4:7], v[168:171], v[216:219], v[4:7]
	v_mfma_f32_16x16x32_bf16 v[0:3], v[176:179], v[216:219], v[0:3]
	v_mfma_f32_16x16x32_bf16 v[52:55], v[172:175], v[190:193], v[52:55]
	v_mfma_f32_16x16x32_bf16 v[48:51], v[182:185], v[190:193], v[48:51]
	v_mfma_f32_16x16x32_bf16 v[36:39], v[172:175], v[198:201], v[36:39]
	v_mfma_f32_16x16x32_bf16 v[32:35], v[182:185], v[198:201], v[32:35]
	v_mfma_f32_16x16x32_bf16 v[20:23], v[172:175], v[212:215], v[20:23]
	v_mfma_f32_16x16x32_bf16 v[16:19], v[182:185], v[212:215], v[16:19]
	v_mfma_f32_16x16x32_bf16 v[4:7], v[172:175], v[220:223], v[4:7]
	v_lshl_add_u64 v[224:225], v[230:231], 0, s[12:13]
	s_mov_b32 m0, s65
	s_nop 0
	global_load_lds_dwordx4 v[224:225], off
	v_mfma_f32_16x16x32_bf16 v[0:3], v[182:185], v[220:223], v[0:3]
	s_setprio 0
	s_barrier
	s_add_i32 s84, s84, 2
	s_add_u32 s54, s54, 0x100
	s_addc_u32 s55, s55, 0
	s_add_u32 s82, s82, 0x100
	s_addc_u32 s83, s83, 0
	s_cmp_gt_u32 s84, 13
	s_cbranch_scc0 .LBB0_1119
	v_lshl_add_u32 v144, s52, 8, v152
	v_ashrrev_i32_e32 v145, 31, v144
	v_lshl_add_u64 v[150:151], v[144:145], 3, s[36:37]
	global_load_dwordx2 v[182:183], v[150:151], off
	global_load_dwordx2 v[184:185], v[150:151], off offset:128
	global_load_dwordx2 v[186:187], v[150:151], off offset:256
	global_load_dwordx2 v[188:189], v[150:151], off offset:384
	global_load_dwordx2 v[190:191], v[150:151], off offset:1024
	global_load_dwordx2 v[192:193], v[150:151], off offset:1152
	global_load_dwordx2 v[194:195], v[150:151], off offset:1280
	global_load_dwordx2 v[196:197], v[150:151], off offset:1408
	s_and_b64 vcc, exec, s[38:39]
	s_cbranch_vccz .LBB0_1122
	s_barrier

; #define PG8_STAGE(bufoff, gbase, voff) do { _Pragma("unroll") for (int _i = 0; _i < 2; ++_i) \
;         __builtin_amdgcn_global_load_lds((const unsigned*)((const char*)(gbase) + (voff)[_i]), (PG8_LAS unsigned*)(lds + (bufoff) + ldsw + _i * 8192), 16, 0, 0); } while (0)
; #define PG8_LDA(dst, b, h) do { _Pragma("unroll") for (int m = 0; m < 4; ++m) _Pragma("unroll") for (int k = 0; k < 2; ++k) dst[m][k] = *(const PG8_LAS bf16x8*)(lds + PG8_SA(b, h) + aoff + m * 2048 + k * 1024); } while (0)
; #define PG8_LDB(dst, b, h) do { _Pragma("unroll") for (int n = 0; n < 2; ++n) _Pragma("unroll") for (int k = 0; k < 2; ++k) dst[n][k] = *(const PG8_LAS bf16x8*)(lds + PG8_SB(b, h) + boff + n * 2048 + k * 1024); } while (0)
; #define PG8_MMA(ai, bj, At, Bt) do { __builtin_amdgcn_s_setprio(1); _Pragma("unroll") for (int m = 0; m < 4; ++m) _Pragma("unroll") for (int n = 0; n < 2; ++n) _Pragma("unroll") for (int k = 0; k < 2; ++k) \
;         acc[ai][bj][m][n] = __builtin_amdgcn_mfma_f32_16x16x32_bf16(Bt[n][k], At[m][k], acc[ai][bj][m][n], 0, 0, 0); __builtin_amdgcn_s_setprio(0); } while (0)
; #define PG8_BAR __builtin_amdgcn_s_barrier()
; template <class Epi, class Sched, bool ALIGN_EPI = false, bool SP2 = false>
; __device__ __forceinline__ void gemm_phase(PG8_LAS unsigned char* lds, const Gemm g, const Sched& S, const Epi& E) {
;     ...
;         const bool has_next = S.next(ui + 1, nxt);
;         const char* nA = has_next ? (const char*)g.A + (size_t)nxt.pm * tstep : cA; const char* nB = has_next ? (const char*)g.Bt + (size_t)nxt.pn * tstep : cB;
;         for (int t = 0; t < nt; t += 2) {
;             const bool last = (t == nt - 2);
;             const char* a1 = cA + (size_t)(t + 1) * kstep;
;             const char* a2 = last ? nA : cA + (size_t)(t + 2) * kstep; const char* b2 = last ? nB : cB + (size_t)(t + 2) * kstep;
;             const char* a3 = a2 + kstep; const char* b3 = b2 + kstep;
;             if (last && has_next) S.a_ready(nxt);
;             if constexpr (SP2) {
;             PG8_LDB(B0, 0, 0); PG8_LDB(B1, 0, 1); PG8_SCHED; PG8_LDA(At, 0, 0); PG8_STAGE(PG8_SA(1, 1), a1 + hstep, voffA);
;             PG8_WAIT_V(8); PG8_WAIT_L(0); PG8_BAR; PG8_MMA(0, 0, At, B0); PG8_MMA(0, 1, At, B1); PG8_BAR; PG8_SCHED;
;             PG8_LDA(At, 0, 1); PG8_STAGE(PG8_SB(0, 0), b2, voffB); PG8_STAGE(PG8_SB(0, 1), b2 + hstep, voffB); PG8_STAGE(PG8_SA(0, 0), a2, voffA);
.LBB0_1196:
	s_add_u32 s82, s52, 0x100
	s_addc_u32 s83, s53, 0
	s_mov_b32 s84, -2
	s_waitcnt lgkmcnt(0)
	ds_read_b128 v[144:147], v151
	ds_read_b128 v[156:159], v151 offset:1024
	ds_read_b128 v[160:163], v151 offset:2048
	ds_read_b128 v[164:167], v151 offset:3072
	ds_read_b128 v[168:171], v152
	ds_read_b128 v[172:175], v152 offset:1024
	ds_read_b128 v[176:179], v152 offset:2048
	ds_read_b128 v[182:185], v152 offset:3072
	s_add_u32 s52, s50, 0x100
	s_addc_u32 s53, s51, 0
	s_cmp_eq_u32 s84, 40
	s_cselect_b32 s57, s1, s53
	s_cselect_b32 s56, s0, s52
	s_cselect_b32 s55, s49, s83
	s_cselect_b32 s54, s48, s82
	v_lshl_add_u64 v[224:225], s[50:51], 0, v[136:137]
	s_add_i32 m0, s34, 0xc000
	ds_read_b128 v[186:189], v153
	ds_read_b128 v[190:193], v153 offset:1024
	ds_read_b128 v[194:197], v153 offset:2048
	ds_read_b128 v[198:201], v153 offset:3072
	ds_read_b128 v[208:211], v153 offset:4096
	ds_read_b128 v[212:215], v153 offset:5120
	ds_read_b128 v[216:219], v153 offset:6144
	ds_read_b128 v[220:223], v153 offset:7168
	global_load_lds_dwordx4 v[224:225], off
	v_lshl_add_u64 v[224:225], s[50:51], 0, v[138:139]
	s_add_i32 m0, s34, 0xe000
	s_nop 0
	global_load_lds_dwordx4 v[224:225], off
	s_waitcnt vmcnt(8)
	s_waitcnt lgkmcnt(0)
	s_barrier
	s_setprio 1
	s_waitcnt lgkmcnt(0)
	v_mfma_f32_16x16x32_bf16 v[124:127], v[144:147], v[186:189], 0
	v_mfma_f32_16x16x32_bf16 v[120:123], v[160:163], v[186:189], 0
	v_mfma_f32_16x16x32_bf16 v[108:111], v[144:147], v[194:197], 0
	v_mfma_f32_16x16x32_bf16 v[104:107], v[160:163], v[194:197], 0
	v_mfma_f32_16x16x32_bf16 v[92:95], v[144:147], v[208:211], 0
	v_mfma_f32_16x16x32_bf16 v[88:91], v[160:163], v[208:211], 0
	v_mfma_f32_16x16x32_bf16 v[76:79], v[144:147], v[216:219], 0
	v_mfma_f32_16x16x32_bf16 v[72:75], v[160:163], v[216:219], 0
	v_mfma_f32_16x16x32_bf16 v[124:127], v[156:159], v[190:193], v[124:127]
	v_mfma_f32_16x16x32_bf16 v[120:123], v[164:167], v[190:193], v[120:123]
	v_mfma_f32_16x16x32_bf16 v[108:111], v[156:159], v[198:201], v[108:111]
	v_mfma_f32_16x16x32_bf16 v[104:107], v[164:167], v[198:201], v[104:107]
	v_mfma_f32_16x16x32_bf16 v[92:95], v[156:159], v[212:215], v[92:95]
	v_mfma_f32_16x16x32_bf16 v[88:91], v[164:167], v[212:215], v[88:91]
	v_mfma_f32_16x16x32_bf16 v[76:79], v[156:159], v[220:223], v[76:79]
	v_mfma_f32_16x16x32_bf16 v[72:75], v[164:167], v[220:223], v[72:75]
	s_setprio 0
	s_setprio 1
	v_mfma_f32_16x16x32_bf16 v[116:119], v[168:171], v[186:189], 0
	v_mfma_f32_16x16x32_bf16 v[112:115], v[176:179], v[186:189], 0
	v_mfma_f32_16x16x32_bf16 v[100:103], v[168:171], v[194:197], 0
	v_mfma_f32_16x16x32_bf16 v[96:99], v[176:179], v[194:197], 0
	v_mfma_f32_16x16x32_bf16 v[84:87], v[168:171], v[208:211], 0
	v_mfma_f32_16x16x32_bf16 v[80:83], v[176:179], v[208:211], 0
	v_mfma_f32_16x16x32_bf16 v[68:71], v[168:171], v[216:219], 0
	v_mfma_f32_16x16x32_bf16 v[64:67], v[176:179], v[216:219], 0
	v_mfma_f32_16x16x32_bf16 v[116:119], v[172:175], v[190:193], v[116:119]
	v_mfma_f32_16x16x32_bf16 v[112:115], v[182:185], v[190:193], v[112:115]
	v_mfma_f32_16x16x32_bf16 v[100:103], v[172:175], v[198:201], v[100:103]
	v_mfma_f32_16x16x32_bf16 v[96:99], v[182:185], v[198:201], v[96:99]
	v_mfma_f32_16x16x32_bf16 v[84:87], v[172:175], v[212:215], v[84:87]
	v_mfma_f32_16x16x32_bf16 v[80:83], v[182:185], v[212:215], v[80:83]
	v_mfma_f32_16x16x32_bf16 v[68:71], v[172:175], v[220:223], v[68:71]
	v_mfma_f32_16x16x32_bf16 v[64:67], v[182:185], v[220:223], v[64:67]
	s_setprio 0
	s_barrier
	s_add_i32 s50, s64, s33
	v_lshl_add_u64 v[224:225], s[54:55], 0, v[130:131]
	s_mov_b32 m0, s50
	ds_read_b128 v[186:189], v153 offset:16384
	ds_read_b128 v[190:193], v153 offset:17408
	ds_read_b128 v[194:197], v153 offset:18432
	ds_read_b128 v[198:201], v153 offset:19456
	ds_read_b128 v[208:211], v153 offset:20480
	ds_read_b128 v[212:215], v153 offset:21504
	ds_read_b128 v[216:219], v153 offset:22528
	ds_read_b128 v[220:223], v153 offset:23552
	global_load_lds_dwordx4 v[224:225], off
	s_add_i32 m0, s50, 0x2000
	s_add_u32 s50, s54, 0xb0000
	v_lshl_add_u64 v[226:227], s[54:55], 0, v[134:135]
	s_addc_u32 s51, s55, 0
	s_add_i32 s78, s65, s33
	global_load_lds_dwordx4 v[226:227], off
	v_lshl_add_u64 v[228:229], s[50:51], 0, v[130:131]
	s_mov_b32 m0, s78
	global_load_lds_dwordx4 v[228:229], off
	v_lshl_add_u64 v[228:229], s[50:51], 0, v[134:135]
	s_add_i32 m0, s78, 0x2000
	s_nop 0
	global_load_lds_dwordx4 v[228:229], off
	s_waitcnt vmcnt(6)
	s_waitcnt lgkmcnt(0)
	s_barrier
; #define PG8_STAGE(bufoff, gbase, voff) do { _Pragma("unroll") for (int _i = 0; _i < 2; ++_i) \
;         __builtin_amdgcn_global_load_lds((const unsigned*)((const char*)(gbase) + (voff)[_i]), (PG8_LAS unsigned*)(lds + (bufoff) + ldsw + _i * 8192), 16, 0, 0); } while (0)
; #define PG8_LDA(dst, b, h) do { _Pragma("unroll") for (int m = 0; m < 4; ++m) _Pragma("unroll") for (int k = 0; k < 2; ++k) dst[m][k] = *(const PG8_LAS bf16x8*)(lds + PG8_SA(b, h) + aoff + m * 2048 + k * 1024); } while (0)
; #define PG8_LDB(dst, b, h) do { _Pragma("unroll") for (int n = 0; n < 2; ++n) _Pragma("unroll") for (int k = 0; k < 2; ++k) dst[n][k] = *(const PG8_LAS bf16x8*)(lds + PG8_SB(b, h) + boff + n * 2048 + k * 1024); } while (0)
; #define PG8_MMA(ai, bj, At, Bt) do { __builtin_amdgcn_s_setprio(1); _Pragma("unroll") for (int m = 0; m < 4; ++m) _Pragma("unroll") for (int n = 0; n < 2; ++n) _Pragma("unroll") for (int k = 0; k < 2; ++k) \
;         acc[ai][bj][m][n] = __builtin_amdgcn_mfma_f32_16x16x32_bf16(Bt[n][k], At[m][k], acc[ai][bj][m][n], 0, 0, 0); __builtin_amdgcn_s_setprio(0); } while (0)
; #define PG8_WAIT_V(n) asm volatile("s_waitcnt vmcnt(" #n ")" ::: "memory")
; #define PG8_WAIT_L(n) asm volatile("s_waitcnt lgkmcnt(" #n ")" ::: "memory")
; #define PG8_BAR __builtin_amdgcn_s_barrier()
; #define PG8_SCHED __builtin_amdgcn_sched_barrier(0)
; template <class Epi, class Sched, bool ALIGN_EPI = false, bool SP2 = false>
; __device__ __forceinline__ void gemm_phase(PG8_LAS unsigned char* lds, const Gemm g, const Sched& S, const Epi& E) {
;     ...
;             PG8_LDA(At, 0, 1); PG8_STAGE(PG8_SB(0, 0), b2, voffB); PG8_STAGE(PG8_SB(0, 1), b2 + hstep, voffB); PG8_STAGE(PG8_SA(0, 0), a2, voffA);
;             PG8_WAIT_V(8); PG8_WAIT_L(0); PG8_BAR; PG8_MMA(1, 0, At, B0); PG8_MMA(1, 1, At, B1); PG8_BAR; PG8_SCHED;
;             PG8_LDB(B0, 1, 0); PG8_LDB(B1, 1, 1); PG8_SCHED; PG8_LDA(At, 1, 0); PG8_STAGE(PG8_SA(0, 1), a2 + hstep, voffA);
;             PG8_WAIT_V(8); PG8_WAIT_L(0); PG8_BAR; PG8_MMA(0, 0, At, B0); PG8_MMA(0, 1, At, B1); PG8_BAR; PG8_SCHED;
	s_setprio 1
	s_waitcnt lgkmcnt(0)
	v_mfma_f32_16x16x32_bf16 v[60:63], v[144:147], v[186:189], 0
	v_mfma_f32_16x16x32_bf16 v[56:59], v[160:163], v[186:189], 0
	v_mfma_f32_16x16x32_bf16 v[44:47], v[144:147], v[194:197], 0
	v_mfma_f32_16x16x32_bf16 v[40:43], v[160:163], v[194:197], 0
	v_mfma_f32_16x16x32_bf16 v[28:31], v[144:147], v[208:211], 0
	v_mfma_f32_16x16x32_bf16 v[24:27], v[160:163], v[208:211], 0
	v_mfma_f32_16x16x32_bf16 v[12:15], v[144:147], v[216:219], 0
	v_mfma_f32_16x16x32_bf16 v[8:11], v[160:163], v[216:219], 0
	v_mfma_f32_16x16x32_bf16 v[60:63], v[156:159], v[190:193], v[60:63]
	v_mfma_f32_16x16x32_bf16 v[56:59], v[164:167], v[190:193], v[56:59]
	v_mfma_f32_16x16x32_bf16 v[44:47], v[156:159], v[198:201], v[44:47]
	v_mfma_f32_16x16x32_bf16 v[40:43], v[164:167], v[198:201], v[40:43]
	v_mfma_f32_16x16x32_bf16 v[28:31], v[156:159], v[212:215], v[28:31]
	v_mfma_f32_16x16x32_bf16 v[24:27], v[164:167], v[212:215], v[24:27]
	v_mfma_f32_16x16x32_bf16 v[12:15], v[156:159], v[220:223], v[12:15]
	v_lshl_add_u64 v[228:229], s[56:57], 0, v[128:129]
	s_mov_b32 m0, s34
	s_nop 0
	global_load_lds_dwordx4 v[228:229], off
	v_mfma_f32_16x16x32_bf16 v[8:11], v[164:167], v[220:223], v[8:11]
	s_setprio 0
	s_setprio 1
	v_mfma_f32_16x16x32_bf16 v[52:55], v[168:171], v[186:189], 0
	v_mfma_f32_16x16x32_bf16 v[48:51], v[176:179], v[186:189], 0
	v_mfma_f32_16x16x32_bf16 v[36:39], v[168:171], v[194:197], 0
	v_mfma_f32_16x16x32_bf16 v[32:35], v[176:179], v[194:197], 0
	v_mfma_f32_16x16x32_bf16 v[20:23], v[168:171], v[208:211], 0
	v_mfma_f32_16x16x32_bf16 v[16:19], v[176:179], v[208:211], 0
	v_mfma_f32_16x16x32_bf16 v[4:7], v[168:171], v[216:219], 0
	v_mfma_f32_16x16x32_bf16 v[0:3], v[176:179], v[216:219], 0
	v_mfma_f32_16x16x32_bf16 v[52:55], v[172:175], v[190:193], v[52:55]
	v_mfma_f32_16x16x32_bf16 v[48:51], v[182:185], v[190:193], v[48:51]
	v_mfma_f32_16x16x32_bf16 v[36:39], v[172:175], v[198:201], v[36:39]
	v_mfma_f32_16x16x32_bf16 v[32:35], v[182:185], v[198:201], v[32:35]
	v_mfma_f32_16x16x32_bf16 v[20:23], v[172:175], v[212:215], v[20:23]
	v_mfma_f32_16x16x32_bf16 v[16:19], v[182:185], v[212:215], v[16:19]
	v_mfma_f32_16x16x32_bf16 v[4:7], v[172:175], v[220:223], v[4:7]
	v_lshl_add_u64 v[230:231], s[56:57], 0, v[132:133]
	s_mov_b32 m0, s58
	s_nop 0
	global_load_lds_dwordx4 v[230:231], off
	v_mfma_f32_16x16x32_bf16 v[0:3], v[182:185], v[220:223], v[0:3]
	s_setprio 0
	s_barrier
	s_add_i32 s78, 0, 0x18000
	v_add_u32_e32 v155, s78, v149
	s_add_i32 s79, 0, 0x1c000
	ds_read_b128 v[144:147], v155
	ds_read_b128 v[156:159], v155 offset:1024
	ds_read_b128 v[160:163], v155 offset:2048
	ds_read_b128 v[164:167], v155 offset:3072
	v_add_u32_e32 v155, s79, v149
	ds_read_b128 v[168:171], v155
	ds_read_b128 v[172:175], v155 offset:1024
	ds_read_b128 v[176:179], v155 offset:2048
	ds_read_b128 v[182:185], v155 offset:3072
	s_add_u32 s50, s56, 0xb0000
	s_addc_u32 s51, s57, 0
	s_mov_b32 m0, s59
	v_lshl_add_u64 v[232:233], s[50:51], 0, v[128:129]
	ds_read_b128 v[186:189], v153 offset:32768
	ds_read_b128 v[190:193], v153 offset:33792
	ds_read_b128 v[194:197], v153 offset:34816
	ds_read_b128 v[198:201], v153 offset:35840
	ds_read_b128 v[208:211], v153 offset:36864
	ds_read_b128 v[212:215], v153 offset:37888
	ds_read_b128 v[216:219], v153 offset:38912
	ds_read_b128 v[220:223], v153 offset:39936
	global_load_lds_dwordx4 v[232:233], off
	v_lshl_add_u64 v[232:233], s[50:51], 0, v[132:133]
	s_mov_b32 m0, s60
	s_nop 0
	global_load_lds_dwordx4 v[232:233], off
	s_waitcnt vmcnt(8)
	s_waitcnt lgkmcnt(0)
	s_barrier
	s_setprio 1
	s_waitcnt lgkmcnt(0)
	v_mfma_f32_16x16x32_bf16 v[124:127], v[144:147], v[186:189], v[124:127]
	v_mfma_f32_16x16x32_bf16 v[120:123], v[160:163], v[186:189], v[120:123]
	v_mfma_f32_16x16x32_bf16 v[108:111], v[144:147], v[194:197], v[108:111]
	v_mfma_f32_16x16x32_bf16 v[104:107], v[160:163], v[194:197], v[104:107]
	v_mfma_f32_16x16x32_bf16 v[92:95], v[144:147], v[208:211], v[92:95]
	v_mfma_f32_16x16x32_bf16 v[88:91], v[160:163], v[208:211], v[88:91]
	v_mfma_f32_16x16x32_bf16 v[76:79], v[144:147], v[216:219], v[76:79]
	v_mfma_f32_16x16x32_bf16 v[72:75], v[160:163], v[216:219], v[72:75]
	v_mfma_f32_16x16x32_bf16 v[124:127], v[156:159], v[190:193], v[124:127]
	v_mfma_f32_16x16x32_bf16 v[120:123], v[164:167], v[190:193], v[120:123]
	v_mfma_f32_16x16x32_bf16 v[108:111], v[156:159], v[198:201], v[108:111]
	v_mfma_f32_16x16x32_bf16 v[104:107], v[164:167], v[198:201], v[104:107]
	v_mfma_f32_16x16x32_bf16 v[92:95], v[156:159], v[212:215], v[92:95]
	v_mfma_f32_16x16x32_bf16 v[88:91], v[164:167], v[212:215], v[88:91]
	v_mfma_f32_16x16x32_bf16 v[76:79], v[156:159], v[220:223], v[76:79]
	v_mfma_f32_16x16x32_bf16 v[72:75], v[164:167], v[220:223], v[72:75]
	s_setprio 0
	s_setprio 1
	v_mfma_f32_16x16x32_bf16 v[116:119], v[168:171], v[186:189], v[116:119]
	v_mfma_f32_16x16x32_bf16 v[112:115], v[176:179], v[186:189], v[112:115]
	v_mfma_f32_16x16x32_bf16 v[100:103], v[168:171], v[194:197], v[100:103]
	v_mfma_f32_16x16x32_bf16 v[96:99], v[176:179], v[194:197], v[96:99]
	v_mfma_f32_16x16x32_bf16 v[84:87], v[168:171], v[208:211], v[84:87]
	v_mfma_f32_16x16x32_bf16 v[80:83], v[176:179], v[208:211], v[80:83]
	v_mfma_f32_16x16x32_bf16 v[68:71], v[168:171], v[216:219], v[68:71]
	v_mfma_f32_16x16x32_bf16 v[64:67], v[176:179], v[216:219], v[64:67]
	v_mfma_f32_16x16x32_bf16 v[116:119], v[172:175], v[190:193], v[116:119]
	v_mfma_f32_16x16x32_bf16 v[112:115], v[182:185], v[190:193], v[112:115]
	v_mfma_f32_16x16x32_bf16 v[100:103], v[172:175], v[198:201], v[100:103]
	v_mfma_f32_16x16x32_bf16 v[96:99], v[182:185], v[198:201], v[96:99]
	v_mfma_f32_16x16x32_bf16 v[84:87], v[172:175], v[212:215], v[84:87]
	v_mfma_f32_16x16x32_bf16 v[80:83], v[182:185], v[212:215], v[80:83]
	v_mfma_f32_16x16x32_bf16 v[68:71], v[172:175], v[220:223], v[68:71]
	v_mfma_f32_16x16x32_bf16 v[64:67], v[182:185], v[220:223], v[64:67]
	s_setprio 0
	s_barrier
; #define PG8_STAGE(bufoff, gbase, voff) do { _Pragma("unroll") for (int _i = 0; _i < 2; ++_i) \
;         __builtin_amdgcn_global_load_lds((const unsigned*)((const char*)(gbase) + (voff)[_i]), (PG8_LAS unsigned*)(lds + (bufoff) + ldsw + _i * 8192), 16, 0, 0); } while (0)
; #define PG8_LDA(dst, b, h) do { _Pragma("unroll") for (int m = 0; m < 4; ++m) _Pragma("unroll") for (int k = 0; k < 2; ++k) dst[m][k] = *(const PG8_LAS bf16x8*)(lds + PG8_SA(b, h) + aoff + m * 2048 + k * 1024); } while (0)
; #define PG8_LDB(dst, b, h) do { _Pragma("unroll") for (int n = 0; n < 2; ++n) _Pragma("unroll") for (int k = 0; k < 2; ++k) dst[n][k] = *(const PG8_LAS bf16x8*)(lds + PG8_SB(b, h) + boff + n * 2048 + k * 1024); } while (0)
; template <class Epi, class Sched, bool ALIGN_EPI = false, bool SP2 = false>
; __device__ __forceinline__ void gemm_phase(PG8_LAS unsigned char* lds, const Gemm g, const Sched& S, const Epi& E) {
;     ...
;         for (int t = 0; t < nt; t += 2) {
;             const bool last = (t == nt - 2);
;             const char* a1 = cA + (size_t)(t + 1) * kstep;
;             const char* a2 = last ? nA : cA + (size_t)(t + 2) * kstep; const char* b2 = last ? nB : cB + (size_t)(t + 2) * kstep;
;             const char* a3 = a2 + kstep; const char* b3 = b2 + kstep;
;             if (last && has_next) S.a_ready(nxt);
;             if constexpr (SP2) {
;             PG8_LDB(B0, 0, 0); PG8_LDB(B1, 0, 1); PG8_SCHED; PG8_LDA(At, 0, 0); PG8_STAGE(PG8_SA(1, 1), a1 + hstep, voffA);
;             PG8_WAIT_V(8); PG8_WAIT_L(0); PG8_BAR; PG8_MMA(0, 0, At, B0); PG8_MMA(0, 1, At, B1); PG8_BAR; PG8_SCHED;
;             PG8_LDA(At, 0, 1); PG8_STAGE(PG8_SB(0, 0), b2, voffB); PG8_STAGE(PG8_SB(0, 1), b2 + hstep, voffB); PG8_STAGE(PG8_SA(0, 0), a2, voffA);
;             PG8_WAIT_V(8); PG8_WAIT_L(0); PG8_BAR; PG8_MMA(1, 0, At, B0); PG8_MMA(1, 1, At, B1); PG8_BAR; PG8_SCHED;
;             PG8_LDB(B0, 1, 0); PG8_LDB(B1, 1, 1); PG8_SCHED; PG8_LDA(At, 1, 0); PG8_STAGE(PG8_SA(0, 1), a2 + hstep, voffA);
;             PG8_WAIT_V(8); PG8_WAIT_L(0); PG8_BAR; PG8_MMA(0, 0, At, B0); PG8_MMA(0, 1, At, B1); PG8_BAR; PG8_SCHED;
;             PG8_LDA(At, 1, 1); PG8_STAGE(PG8_SB(1, 0), b3, voffB); PG8_STAGE(PG8_SB(1, 1), b3 + hstep, voffB); PG8_STAGE(PG8_SA(1, 0), a3, voffA);
;             PG8_WAIT_V(8); PG8_WAIT_L(0); PG8_BAR; PG8_MMA(1, 0, At, B0); PG8_MMA(1, 1, At, B1); PG8_BAR; PG8_SCHED;
	s_add_i32 s50, s78, s33
	v_lshl_add_u64 v[224:225], v[224:225], 0, s[42:43]
	s_mov_b32 m0, s50
	ds_read_b128 v[186:189], v153 offset:49152
	ds_read_b128 v[190:193], v153 offset:50176
	ds_read_b128 v[194:197], v153 offset:51200
	ds_read_b128 v[198:201], v153 offset:52224
	ds_read_b128 v[208:211], v153 offset:53248
	ds_read_b128 v[212:215], v153 offset:54272
	ds_read_b128 v[216:219], v153 offset:55296
	ds_read_b128 v[220:223], v153 offset:56320
	global_load_lds_dwordx4 v[224:225], off
	s_add_i32 m0, s50, 0x2000
	s_add_u32 s50, s54, 0xb0080
	v_lshl_add_u64 v[224:225], v[226:227], 0, s[42:43]
	s_addc_u32 s51, s55, 0
	s_add_i32 s54, s79, s33
	global_load_lds_dwordx4 v[224:225], off
	v_lshl_add_u64 v[224:225], s[50:51], 0, v[130:131]
	s_mov_b32 m0, s54
	s_nop 0
	global_load_lds_dwordx4 v[224:225], off
	v_lshl_add_u64 v[224:225], s[50:51], 0, v[134:135]
	s_add_i32 m0, s54, 0x2000
	s_nop 0
	global_load_lds_dwordx4 v[224:225], off
	s_waitcnt vmcnt(6)
	s_waitcnt lgkmcnt(0)
	s_barrier
	s_setprio 1
	s_waitcnt lgkmcnt(0)
	v_mfma_f32_16x16x32_bf16 v[60:63], v[144:147], v[186:189], v[60:63]
	v_mfma_f32_16x16x32_bf16 v[56:59], v[160:163], v[186:189], v[56:59]
	v_mfma_f32_16x16x32_bf16 v[44:47], v[144:147], v[194:197], v[44:47]
	v_mfma_f32_16x16x32_bf16 v[40:43], v[160:163], v[194:197], v[40:43]
	v_mfma_f32_16x16x32_bf16 v[28:31], v[144:147], v[208:211], v[28:31]
	v_mfma_f32_16x16x32_bf16 v[24:27], v[160:163], v[208:211], v[24:27]
	v_mfma_f32_16x16x32_bf16 v[12:15], v[144:147], v[216:219], v[12:15]
	v_mfma_f32_16x16x32_bf16 v[8:11], v[160:163], v[216:219], v[8:11]
	v_mfma_f32_16x16x32_bf16 v[60:63], v[156:159], v[190:193], v[60:63]
	v_mfma_f32_16x16x32_bf16 v[56:59], v[164:167], v[190:193], v[56:59]
	v_mfma_f32_16x16x32_bf16 v[44:47], v[156:159], v[198:201], v[44:47]
	v_mfma_f32_16x16x32_bf16 v[40:43], v[164:167], v[198:201], v[40:43]
	v_mfma_f32_16x16x32_bf16 v[28:31], v[156:159], v[212:215], v[28:31]
	v_mfma_f32_16x16x32_bf16 v[24:27], v[164:167], v[212:215], v[24:27]
	v_mfma_f32_16x16x32_bf16 v[12:15], v[156:159], v[220:223], v[12:15]
	v_lshl_add_u64 v[224:225], v[228:229], 0, s[42:43]
	s_mov_b32 m0, s62
	s_nop 0
	global_load_lds_dwordx4 v[224:225], off
	v_mfma_f32_16x16x32_bf16 v[8:11], v[164:167], v[220:223], v[8:11]
	s_setprio 0
	s_setprio 1
	v_mfma_f32_16x16x32_bf16 v[52:55], v[168:171], v[186:189], v[52:55]
	v_mfma_f32_16x16x32_bf16 v[48:51], v[176:179], v[186:189], v[48:51]
	v_mfma_f32_16x16x32_bf16 v[36:39], v[168:171], v[194:197], v[36:39]
	v_mfma_f32_16x16x32_bf16 v[32:35], v[176:179], v[194:197], v[32:35]
	v_mfma_f32_16x16x32_bf16 v[20:23], v[168:171], v[208:211], v[20:23]
	v_mfma_f32_16x16x32_bf16 v[16:19], v[176:179], v[208:211], v[16:19]
	v_mfma_f32_16x16x32_bf16 v[4:7], v[168:171], v[216:219], v[4:7]
	v_mfma_f32_16x16x32_bf16 v[0:3], v[176:179], v[216:219], v[0:3]
	v_mfma_f32_16x16x32_bf16 v[52:55], v[172:175], v[190:193], v[52:55]
	v_mfma_f32_16x16x32_bf16 v[48:51], v[182:185], v[190:193], v[48:51]
	v_mfma_f32_16x16x32_bf16 v[36:39], v[172:175], v[198:201], v[36:39]
	v_mfma_f32_16x16x32_bf16 v[32:35], v[182:185], v[198:201], v[32:35]
	v_mfma_f32_16x16x32_bf16 v[20:23], v[172:175], v[212:215], v[20:23]
	v_mfma_f32_16x16x32_bf16 v[16:19], v[182:185], v[212:215], v[16:19]
	v_mfma_f32_16x16x32_bf16 v[4:7], v[172:175], v[220:223], v[4:7]
	v_lshl_add_u64 v[224:225], v[230:231], 0, s[42:43]
	s_mov_b32 m0, s63
	s_nop 0
	global_load_lds_dwordx4 v[224:225], off
	v_mfma_f32_16x16x32_bf16 v[0:3], v[182:185], v[220:223], v[0:3]
	s_setprio 0
	s_barrier
	s_add_i32 s84, s84, 2
	s_add_u32 s82, s82, 0x100
	s_addc_u32 s83, s83, 0
	s_mov_b64 s[50:51], s[52:53]
.LBB0_1197:
	ds_read_b128 v[144:147], v151
	ds_read_b128 v[156:159], v151 offset:1024
	ds_read_b128 v[160:163], v151 offset:2048
	ds_read_b128 v[164:167], v151 offset:3072
	ds_read_b128 v[168:171], v152
	ds_read_b128 v[172:175], v152 offset:1024
	ds_read_b128 v[176:179], v152 offset:2048
	ds_read_b128 v[182:185], v152 offset:3072
	s_add_u32 s52, s50, 0x100
	s_addc_u32 s53, s51, 0
	s_cmp_eq_u32 s84, 40
	s_cselect_b32 s57, s1, s53
	s_cselect_b32 s56, s0, s52
	s_cselect_b32 s55, s49, s83
	s_cselect_b32 s54, s48, s82
	v_lshl_add_u64 v[224:225], s[50:51], 0, v[136:137]
	s_add_i32 m0, s34, 0xc000
	ds_read_b128 v[186:189], v153
	ds_read_b128 v[190:193], v153 offset:1024
	ds_read_b128 v[194:197], v153 offset:2048
	ds_read_b128 v[198:201], v153 offset:3072
	ds_read_b128 v[208:211], v153 offset:4096
	ds_read_b128 v[212:215], v153 offset:5120
	ds_read_b128 v[216:219], v153 offset:6144
	ds_read_b128 v[220:223], v153 offset:7168
	global_load_lds_dwordx4 v[224:225], off
	v_lshl_add_u64 v[224:225], s[50:51], 0, v[138:139]
	s_add_i32 m0, s34, 0xe000
	s_nop 0
	global_load_lds_dwordx4 v[224:225], off
	s_waitcnt vmcnt(8)
	s_waitcnt lgkmcnt(0)
	s_barrier
; #define PG8_STAGE(bufoff, gbase, voff) do { _Pragma("unroll") for (int _i = 0; _i < 2; ++_i) \
;         __builtin_amdgcn_global_load_lds((const unsigned*)((const char*)(gbase) + (voff)[_i]), (PG8_LAS unsigned*)(lds + (bufoff) + ldsw + _i * 8192), 16, 0, 0); } while (0)
; #define PG8_LDA(dst, b, h) do { _Pragma("unroll") for (int m = 0; m < 4; ++m) _Pragma("unroll") for (int k = 0; k < 2; ++k) dst[m][k] = *(const PG8_LAS bf16x8*)(lds + PG8_SA(b, h) + aoff + m * 2048 + k * 1024); } while (0)
; #define PG8_LDB(dst, b, h) do { _Pragma("unroll") for (int n = 0; n < 2; ++n) _Pragma("unroll") for (int k = 0; k < 2; ++k) dst[n][k] = *(const PG8_LAS bf16x8*)(lds + PG8_SB(b, h) + boff + n * 2048 + k * 1024); } while (0)
; #define PG8_MMA(ai, bj, At, Bt) do { __builtin_amdgcn_s_setprio(1); _Pragma("unroll") for (int m = 0; m < 4; ++m) _Pragma("unroll") for (int n = 0; n < 2; ++n) _Pragma("unroll") for (int k = 0; k < 2; ++k) \
;         acc[ai][bj][m][n] = __builtin_amdgcn_mfma_f32_16x16x32_bf16(Bt[n][k], At[m][k], acc[ai][bj][m][n], 0, 0, 0); __builtin_amdgcn_s_setprio(0); } while (0)
; #define PG8_WAIT_V(n) asm volatile("s_waitcnt vmcnt(" #n ")" ::: "memory")
; #define PG8_WAIT_L(n) asm volatile("s_waitcnt lgkmcnt(" #n ")" ::: "memory")
; #define PG8_BAR __builtin_amdgcn_s_barrier()
; #define PG8_SCHED __builtin_amdgcn_sched_barrier(0)
; template <class Epi, class Sched, bool ALIGN_EPI = false, bool SP2 = false>
; __device__ __forceinline__ void gemm_phase(PG8_LAS unsigned char* lds, const Gemm g, const Sched& S, const Epi& E) {
;     ...
;             PG8_LDB(B0, 0, 0); PG8_LDB(B1, 0, 1); PG8_SCHED; PG8_LDA(At, 0, 0); PG8_STAGE(PG8_SA(1, 1), a1 + hstep, voffA);
;             PG8_WAIT_V(8); PG8_WAIT_L(0); PG8_BAR; PG8_MMA(0, 0, At, B0); PG8_MMA(0, 1, At, B1); PG8_BAR; PG8_SCHED;
;             PG8_LDA(At, 0, 1); PG8_STAGE(PG8_SB(0, 0), b2, voffB); PG8_STAGE(PG8_SB(0, 1), b2 + hstep, voffB); PG8_STAGE(PG8_SA(0, 0), a2, voffA);
;             PG8_WAIT_V(8); PG8_WAIT_L(0); PG8_BAR; PG8_MMA(1, 0, At, B0); PG8_MMA(1, 1, At, B1); PG8_BAR; PG8_SCHED;
	s_setprio 1
	s_waitcnt lgkmcnt(0)
	v_mfma_f32_16x16x32_bf16 v[124:127], v[144:147], v[186:189], v[124:127]
	v_mfma_f32_16x16x32_bf16 v[120:123], v[160:163], v[186:189], v[120:123]
	v_mfma_f32_16x16x32_bf16 v[108:111], v[144:147], v[194:197], v[108:111]
	v_mfma_f32_16x16x32_bf16 v[104:107], v[160:163], v[194:197], v[104:107]
	v_mfma_f32_16x16x32_bf16 v[92:95], v[144:147], v[208:211], v[92:95]
	v_mfma_f32_16x16x32_bf16 v[88:91], v[160:163], v[208:211], v[88:91]
	v_mfma_f32_16x16x32_bf16 v[76:79], v[144:147], v[216:219], v[76:79]
	v_mfma_f32_16x16x32_bf16 v[72:75], v[160:163], v[216:219], v[72:75]
	v_mfma_f32_16x16x32_bf16 v[124:127], v[156:159], v[190:193], v[124:127]
	v_mfma_f32_16x16x32_bf16 v[120:123], v[164:167], v[190:193], v[120:123]
	v_mfma_f32_16x16x32_bf16 v[108:111], v[156:159], v[198:201], v[108:111]
	v_mfma_f32_16x16x32_bf16 v[104:107], v[164:167], v[198:201], v[104:107]
	v_mfma_f32_16x16x32_bf16 v[92:95], v[156:159], v[212:215], v[92:95]
	v_mfma_f32_16x16x32_bf16 v[88:91], v[164:167], v[212:215], v[88:91]
	v_mfma_f32_16x16x32_bf16 v[76:79], v[156:159], v[220:223], v[76:79]
	v_mfma_f32_16x16x32_bf16 v[72:75], v[164:167], v[220:223], v[72:75]
	s_setprio 0
	s_setprio 1
	v_mfma_f32_16x16x32_bf16 v[116:119], v[168:171], v[186:189], v[116:119]
	v_mfma_f32_16x16x32_bf16 v[112:115], v[176:179], v[186:189], v[112:115]
	v_mfma_f32_16x16x32_bf16 v[100:103], v[168:171], v[194:197], v[100:103]
	v_mfma_f32_16x16x32_bf16 v[96:99], v[176:179], v[194:197], v[96:99]
	v_mfma_f32_16x16x32_bf16 v[84:87], v[168:171], v[208:211], v[84:87]
	v_mfma_f32_16x16x32_bf16 v[80:83], v[176:179], v[208:211], v[80:83]
	v_mfma_f32_16x16x32_bf16 v[68:71], v[168:171], v[216:219], v[68:71]
	v_mfma_f32_16x16x32_bf16 v[64:67], v[176:179], v[216:219], v[64:67]
	v_mfma_f32_16x16x32_bf16 v[116:119], v[172:175], v[190:193], v[116:119]
	v_mfma_f32_16x16x32_bf16 v[112:115], v[182:185], v[190:193], v[112:115]
	v_mfma_f32_16x16x32_bf16 v[100:103], v[172:175], v[198:201], v[100:103]
	v_mfma_f32_16x16x32_bf16 v[96:99], v[182:185], v[198:201], v[96:99]
	v_mfma_f32_16x16x32_bf16 v[84:87], v[172:175], v[212:215], v[84:87]
	v_mfma_f32_16x16x32_bf16 v[80:83], v[182:185], v[212:215], v[80:83]
	v_mfma_f32_16x16x32_bf16 v[68:71], v[172:175], v[220:223], v[68:71]
	v_mfma_f32_16x16x32_bf16 v[64:67], v[182:185], v[220:223], v[64:67]
	s_setprio 0
	s_barrier
	s_add_i32 s50, s64, s33
	v_lshl_add_u64 v[224:225], s[54:55], 0, v[130:131]
	s_mov_b32 m0, s50
	ds_read_b128 v[186:189], v153 offset:16384
	ds_read_b128 v[190:193], v153 offset:17408
	ds_read_b128 v[194:197], v153 offset:18432
	ds_read_b128 v[198:201], v153 offset:19456
	ds_read_b128 v[208:211], v153 offset:20480
	ds_read_b128 v[212:215], v153 offset:21504
	ds_read_b128 v[216:219], v153 offset:22528
	ds_read_b128 v[220:223], v153 offset:23552
	global_load_lds_dwordx4 v[224:225], off
	s_add_i32 m0, s50, 0x2000
	s_add_u32 s50, s54, 0xb0000
	v_lshl_add_u64 v[226:227], s[54:55], 0, v[134:135]
	s_addc_u32 s51, s55, 0
	s_add_i32 s78, s65, s33
	global_load_lds_dwordx4 v[226:227], off
	v_lshl_add_u64 v[228:229], s[50:51], 0, v[130:131]
	s_mov_b32 m0, s78
	global_load_lds_dwordx4 v[228:229], off
	v_lshl_add_u64 v[228:229], s[50:51], 0, v[134:135]
	s_add_i32 m0, s78, 0x2000
	s_nop 0
	global_load_lds_dwordx4 v[228:229], off
	s_waitcnt vmcnt(6)
	s_waitcnt lgkmcnt(0)
	s_barrier
	s_setprio 1
	s_waitcnt lgkmcnt(0)
	v_mfma_f32_16x16x32_bf16 v[60:63], v[144:147], v[186:189], v[60:63]
	v_mfma_f32_16x16x32_bf16 v[56:59], v[160:163], v[186:189], v[56:59]
	v_mfma_f32_16x16x32_bf16 v[44:47], v[144:147], v[194:197], v[44:47]
	v_mfma_f32_16x16x32_bf16 v[40:43], v[160:163], v[194:197], v[40:43]
	v_mfma_f32_16x16x32_bf16 v[28:31], v[144:147], v[208:211], v[28:31]
	v_mfma_f32_16x16x32_bf16 v[24:27], v[160:163], v[208:211], v[24:27]
	v_mfma_f32_16x16x32_bf16 v[12:15], v[144:147], v[216:219], v[12:15]
	v_mfma_f32_16x16x32_bf16 v[8:11], v[160:163], v[216:219], v[8:11]
	v_mfma_f32_16x16x32_bf16 v[60:63], v[156:159], v[190:193], v[60:63]
	v_mfma_f32_16x16x32_bf16 v[56:59], v[164:167], v[190:193], v[56:59]
	v_mfma_f32_16x16x32_bf16 v[44:47], v[156:159], v[198:201], v[44:47]
	v_mfma_f32_16x16x32_bf16 v[40:43], v[164:167], v[198:201], v[40:43]
	v_mfma_f32_16x16x32_bf16 v[28:31], v[156:159], v[212:215], v[28:31]
	v_mfma_f32_16x16x32_bf16 v[24:27], v[164:167], v[212:215], v[24:27]
	v_mfma_f32_16x16x32_bf16 v[12:15], v[156:159], v[220:223], v[12:15]
	v_lshl_add_u64 v[228:229], s[56:57], 0, v[128:129]
	s_mov_b32 m0, s34
	s_nop 0
	global_load_lds_dwordx4 v[228:229], off
	v_mfma_f32_16x16x32_bf16 v[8:11], v[164:167], v[220:223], v[8:11]
	s_setprio 0
	s_setprio 1
	v_mfma_f32_16x16x32_bf16 v[52:55], v[168:171], v[186:189], v[52:55]
	v_mfma_f32_16x16x32_bf16 v[48:51], v[176:179], v[186:189], v[48:51]
	v_mfma_f32_16x16x32_bf16 v[36:39], v[168:171], v[194:197], v[36:39]
	v_mfma_f32_16x16x32_bf16 v[32:35], v[176:179], v[194:197], v[32:35]
	v_mfma_f32_16x16x32_bf16 v[20:23], v[168:171], v[208:211], v[20:23]
	v_mfma_f32_16x16x32_bf16 v[16:19], v[176:179], v[208:211], v[16:19]
	v_mfma_f32_16x16x32_bf16 v[4:7], v[168:171], v[216:219], v[4:7]
	v_mfma_f32_16x16x32_bf16 v[0:3], v[176:179], v[216:219], v[0:3]
	v_mfma_f32_16x16x32_bf16 v[52:55], v[172:175], v[190:193], v[52:55]
	v_mfma_f32_16x16x32_bf16 v[48:51], v[182:185], v[190:193], v[48:51]
	v_mfma_f32_16x16x32_bf16 v[36:39], v[172:175], v[198:201], v[36:39]
	v_mfma_f32_16x16x32_bf16 v[32:35], v[182:185], v[198:201], v[32:35]
	v_mfma_f32_16x16x32_bf16 v[20:23], v[172:175], v[212:215], v[20:23]
	v_mfma_f32_16x16x32_bf16 v[16:19], v[182:185], v[212:215], v[16:19]
	v_mfma_f32_16x16x32_bf16 v[4:7], v[172:175], v[220:223], v[4:7]
	v_lshl_add_u64 v[230:231], s[56:57], 0, v[132:133]
	s_mov_b32 m0, s58
	s_nop 0
	global_load_lds_dwordx4 v[230:231], off
	v_mfma_f32_16x16x32_bf16 v[0:3], v[182:185], v[220:223], v[0:3]
	s_setprio 0
	s_barrier
; #define PG8_STAGE(bufoff, gbase, voff) do { _Pragma("unroll") for (int _i = 0; _i < 2; ++_i) \
;         __builtin_amdgcn_global_load_lds((const unsigned*)((const char*)(gbase) + (voff)[_i]), (PG8_LAS unsigned*)(lds + (bufoff) + ldsw + _i * 8192), 16, 0, 0); } while (0)
; #define PG8_LDA(dst, b, h) do { _Pragma("unroll") for (int m = 0; m < 4; ++m) _Pragma("unroll") for (int k = 0; k < 2; ++k) dst[m][k] = *(const PG8_LAS bf16x8*)(lds + PG8_SA(b, h) + aoff + m * 2048 + k * 1024); } while (0)
; #define PG8_LDB(dst, b, h) do { _Pragma("unroll") for (int n = 0; n < 2; ++n) _Pragma("unroll") for (int k = 0; k < 2; ++k) dst[n][k] = *(const PG8_LAS bf16x8*)(lds + PG8_SB(b, h) + boff + n * 2048 + k * 1024); } while (0)
; #define PG8_MMA(ai, bj, At, Bt) do { __builtin_amdgcn_s_setprio(1); _Pragma("unroll") for (int m = 0; m < 4; ++m) _Pragma("unroll") for (int n = 0; n < 2; ++n) _Pragma("unroll") for (int k = 0; k < 2; ++k) \
;         acc[ai][bj][m][n] = __builtin_amdgcn_mfma_f32_16x16x32_bf16(Bt[n][k], At[m][k], acc[ai][bj][m][n], 0, 0, 0); __builtin_amdgcn_s_setprio(0); } while (0)
; #define PG8_WAIT_V(n) asm volatile("s_waitcnt vmcnt(" #n ")" ::: "memory")
; #define PG8_WAIT_L(n) asm volatile("s_waitcnt lgkmcnt(" #n ")" ::: "memory")
; #define PG8_BAR __builtin_amdgcn_s_barrier()
; #define PG8_SCHED __builtin_amdgcn_sched_barrier(0)
; template <class Epi, class Sched, bool ALIGN_EPI = false, bool SP2 = false>
; __device__ __forceinline__ void gemm_phase(PG8_LAS unsigned char* lds, const Gemm g, const Sched& S, const Epi& E) {
;     ...
;             PG8_LDB(B0, 1, 0); PG8_LDB(B1, 1, 1); PG8_SCHED; PG8_LDA(At, 1, 0); PG8_STAGE(PG8_SA(0, 1), a2 + hstep, voffA);
;             PG8_WAIT_V(8); PG8_WAIT_L(0); PG8_BAR; PG8_MMA(0, 0, At, B0); PG8_MMA(0, 1, At, B1); PG8_BAR; PG8_SCHED;
	s_add_i32 s78, 0, 0x18000
	v_add_u32_e32 v155, s78, v149
	s_add_i32 s79, 0, 0x1c000
	ds_read_b128 v[144:147], v155
	ds_read_b128 v[156:159], v155 offset:1024
	ds_read_b128 v[160:163], v155 offset:2048
	ds_read_b128 v[164:167], v155 offset:3072
	v_add_u32_e32 v155, s79, v149
	ds_read_b128 v[168:171], v155
	ds_read_b128 v[172:175], v155 offset:1024
	ds_read_b128 v[176:179], v155 offset:2048
	ds_read_b128 v[182:185], v155 offset:3072
	s_add_u32 s50, s56, 0xb0000
	s_addc_u32 s51, s57, 0
	s_mov_b32 m0, s59
	v_lshl_add_u64 v[232:233], s[50:51], 0, v[128:129]
	ds_read_b128 v[186:189], v153 offset:32768
	ds_read_b128 v[190:193], v153 offset:33792
	ds_read_b128 v[194:197], v153 offset:34816
	ds_read_b128 v[198:201], v153 offset:35840
	ds_read_b128 v[208:211], v153 offset:36864
	ds_read_b128 v[212:215], v153 offset:37888
	ds_read_b128 v[216:219], v153 offset:38912
	ds_read_b128 v[220:223], v153 offset:39936
	global_load_lds_dwordx4 v[232:233], off
	v_lshl_add_u64 v[232:233], s[50:51], 0, v[132:133]
	s_mov_b32 m0, s60
	s_nop 0
	global_load_lds_dwordx4 v[232:233], off
	s_waitcnt vmcnt(8)
	s_waitcnt lgkmcnt(0)
	s_barrier
	s_setprio 1
	s_waitcnt lgkmcnt(0)
	v_mfma_f32_16x16x32_bf16 v[124:127], v[144:147], v[186:189], v[124:127]
	v_mfma_f32_16x16x32_bf16 v[120:123], v[160:163], v[186:189], v[120:123]
	v_mfma_f32_16x16x32_bf16 v[108:111], v[144:147], v[194:197], v[108:111]
	v_mfma_f32_16x16x32_bf16 v[104:107], v[160:163], v[194:197], v[104:107]
	v_mfma_f32_16x16x32_bf16 v[92:95], v[144:147], v[208:211], v[92:95]
	v_mfma_f32_16x16x32_bf16 v[88:91], v[160:163], v[208:211], v[88:91]
	v_mfma_f32_16x16x32_bf16 v[76:79], v[144:147], v[216:219], v[76:79]
	v_mfma_f32_16x16x32_bf16 v[72:75], v[160:163], v[216:219], v[72:75]
	v_mfma_f32_16x16x32_bf16 v[124:127], v[156:159], v[190:193], v[124:127]
	v_mfma_f32_16x16x32_bf16 v[120:123], v[164:167], v[190:193], v[120:123]
	v_mfma_f32_16x16x32_bf16 v[108:111], v[156:159], v[198:201], v[108:111]
	v_mfma_f32_16x16x32_bf16 v[104:107], v[164:167], v[198:201], v[104:107]
	v_mfma_f32_16x16x32_bf16 v[92:95], v[156:159], v[212:215], v[92:95]
	v_mfma_f32_16x16x32_bf16 v[88:91], v[164:167], v[212:215], v[88:91]
	v_mfma_f32_16x16x32_bf16 v[76:79], v[156:159], v[220:223], v[76:79]
	v_mfma_f32_16x16x32_bf16 v[72:75], v[164:167], v[220:223], v[72:75]
	s_setprio 0
	s_setprio 1
	v_mfma_f32_16x16x32_bf16 v[116:119], v[168:171], v[186:189], v[116:119]
	v_mfma_f32_16x16x32_bf16 v[112:115], v[176:179], v[186:189], v[112:115]
	v_mfma_f32_16x16x32_bf16 v[100:103], v[168:171], v[194:197], v[100:103]
	v_mfma_f32_16x16x32_bf16 v[96:99], v[176:179], v[194:197], v[96:99]
	v_mfma_f32_16x16x32_bf16 v[84:87], v[168:171], v[208:211], v[84:87]
	v_mfma_f32_16x16x32_bf16 v[80:83], v[176:179], v[208:211], v[80:83]
	v_mfma_f32_16x16x32_bf16 v[68:71], v[168:171], v[216:219], v[68:71]
	v_mfma_f32_16x16x32_bf16 v[64:67], v[176:179], v[216:219], v[64:67]
	v_mfma_f32_16x16x32_bf16 v[116:119], v[172:175], v[190:193], v[116:119]
	v_mfma_f32_16x16x32_bf16 v[112:115], v[182:185], v[190:193], v[112:115]
	v_mfma_f32_16x16x32_bf16 v[100:103], v[172:175], v[198:201], v[100:103]
	v_mfma_f32_16x16x32_bf16 v[96:99], v[182:185], v[198:201], v[96:99]
	v_mfma_f32_16x16x32_bf16 v[84:87], v[172:175], v[212:215], v[84:87]
	v_mfma_f32_16x16x32_bf16 v[80:83], v[182:185], v[212:215], v[80:83]
	v_mfma_f32_16x16x32_bf16 v[68:71], v[172:175], v[220:223], v[68:71]
	v_mfma_f32_16x16x32_bf16 v[64:67], v[182:185], v[220:223], v[64:67]
	s_setprio 0
	s_barrier
; #define PG8_STAGE(bufoff, gbase, voff) do { _Pragma("unroll") for (int _i = 0; _i < 2; ++_i) \
;         __builtin_amdgcn_global_load_lds((const unsigned*)((const char*)(gbase) + (voff)[_i]), (PG8_LAS unsigned*)(lds + (bufoff) + ldsw + _i * 8192), 16, 0, 0); } while (0)
; #define PG8_LDA(dst, b, h) do { _Pragma("unroll") for (int m = 0; m < 4; ++m) _Pragma("unroll") for (int k = 0; k < 2; ++k) dst[m][k] = *(const PG8_LAS bf16x8*)(lds + PG8_SA(b, h) + aoff + m * 2048 + k * 1024); } while (0)
; #define PG8_MMA(ai, bj, At, Bt) do { __builtin_amdgcn_s_setprio(1); _Pragma("unroll") for (int m = 0; m < 4; ++m) _Pragma("unroll") for (int n = 0; n < 2; ++n) _Pragma("unroll") for (int k = 0; k < 2; ++k) \
;         acc[ai][bj][m][n] = __builtin_amdgcn_mfma_f32_16x16x32_bf16(Bt[n][k], At[m][k], acc[ai][bj][m][n], 0, 0, 0); __builtin_amdgcn_s_setprio(0); } while (0)
; #define PG8_WAIT_V(n) asm volatile("s_waitcnt vmcnt(" #n ")" ::: "memory")
; #define PG8_WAIT_L(n) asm volatile("s_waitcnt lgkmcnt(" #n ")" ::: "memory")
; #define PG8_BAR __builtin_amdgcn_s_barrier()
; #define PG8_SCHED __builtin_amdgcn_sched_barrier(0)
; template <class Epi, class Sched, bool ALIGN_EPI = false, bool SP2 = false>
; __device__ __forceinline__ void gemm_phase(PG8_LAS unsigned char* lds, const Gemm g, const Sched& S, const Epi& E) {
;     ...
;             PG8_LDA(At, 1, 1); PG8_STAGE(PG8_SB(1, 0), b3, voffB); PG8_STAGE(PG8_SB(1, 1), b3 + hstep, voffB); PG8_STAGE(PG8_SA(1, 0), a3, voffA);
;             PG8_WAIT_V(8); PG8_WAIT_L(0); PG8_BAR; PG8_MMA(1, 0, At, B0); PG8_MMA(1, 1, At, B1); PG8_BAR; PG8_SCHED;
	s_add_i32 s50, s78, s33
	v_lshl_add_u64 v[224:225], v[224:225], 0, s[42:43]
	s_mov_b32 m0, s50
	ds_read_b128 v[186:189], v153 offset:49152
	ds_read_b128 v[190:193], v153 offset:50176
	ds_read_b128 v[194:197], v153 offset:51200
	ds_read_b128 v[198:201], v153 offset:52224
	ds_read_b128 v[208:211], v153 offset:53248
	ds_read_b128 v[212:215], v153 offset:54272
	ds_read_b128 v[216:219], v153 offset:55296
	ds_read_b128 v[220:223], v153 offset:56320
	global_load_lds_dwordx4 v[224:225], off
	s_add_i32 m0, s50, 0x2000
	s_add_u32 s50, s54, 0xb0080
	v_lshl_add_u64 v[224:225], v[226:227], 0, s[42:43]
	s_addc_u32 s51, s55, 0
	s_add_i32 s54, s79, s33
	global_load_lds_dwordx4 v[224:225], off
	v_lshl_add_u64 v[224:225], s[50:51], 0, v[130:131]
	s_mov_b32 m0, s54
	s_nop 0
	global_load_lds_dwordx4 v[224:225], off
	v_lshl_add_u64 v[224:225], s[50:51], 0, v[134:135]
	s_add_i32 m0, s54, 0x2000
	s_nop 0
	global_load_lds_dwordx4 v[224:225], off
	s_waitcnt vmcnt(6)
	s_waitcnt lgkmcnt(0)
	s_barrier
	s_setprio 1
	s_waitcnt lgkmcnt(0)
	v_mfma_f32_16x16x32_bf16 v[60:63], v[144:147], v[186:189], v[60:63]
	v_mfma_f32_16x16x32_bf16 v[56:59], v[160:163], v[186:189], v[56:59]
	v_mfma_f32_16x16x32_bf16 v[44:47], v[144:147], v[194:197], v[44:47]
	v_mfma_f32_16x16x32_bf16 v[40:43], v[160:163], v[194:197], v[40:43]
	v_mfma_f32_16x16x32_bf16 v[28:31], v[144:147], v[208:211], v[28:31]
	v_mfma_f32_16x16x32_bf16 v[24:27], v[160:163], v[208:211], v[24:27]
	v_mfma_f32_16x16x32_bf16 v[12:15], v[144:147], v[216:219], v[12:15]
	v_mfma_f32_16x16x32_bf16 v[8:11], v[160:163], v[216:219], v[8:11]
	v_mfma_f32_16x16x32_bf16 v[60:63], v[156:159], v[190:193], v[60:63]
	v_mfma_f32_16x16x32_bf16 v[56:59], v[164:167], v[190:193], v[56:59]
	v_mfma_f32_16x16x32_bf16 v[44:47], v[156:159], v[198:201], v[44:47]
	v_mfma_f32_16x16x32_bf16 v[40:43], v[164:167], v[198:201], v[40:43]
	v_mfma_f32_16x16x32_bf16 v[28:31], v[156:159], v[212:215], v[28:31]
	v_mfma_f32_16x16x32_bf16 v[24:27], v[164:167], v[212:215], v[24:27]
	v_mfma_f32_16x16x32_bf16 v[12:15], v[156:159], v[220:223], v[12:15]
	v_lshl_add_u64 v[224:225], v[228:229], 0, s[42:43]
	s_mov_b32 m0, s62
	s_nop 0
	global_load_lds_dwordx4 v[224:225], off
	v_mfma_f32_16x16x32_bf16 v[8:11], v[164:167], v[220:223], v[8:11]
	s_setprio 0
	s_setprio 1
	v_mfma_f32_16x16x32_bf16 v[52:55], v[168:171], v[186:189], v[52:55]
	v_mfma_f32_16x16x32_bf16 v[48:51], v[176:179], v[186:189], v[48:51]
	v_mfma_f32_16x16x32_bf16 v[36:39], v[168:171], v[194:197], v[36:39]
	v_mfma_f32_16x16x32_bf16 v[32:35], v[176:179], v[194:197], v[32:35]
	v_mfma_f32_16x16x32_bf16 v[20:23], v[168:171], v[208:211], v[20:23]
	v_mfma_f32_16x16x32_bf16 v[16:19], v[176:179], v[208:211], v[16:19]
	v_mfma_f32_16x16x32_bf16 v[4:7], v[168:171], v[216:219], v[4:7]
	v_mfma_f32_16x16x32_bf16 v[0:3], v[176:179], v[216:219], v[0:3]
	v_mfma_f32_16x16x32_bf16 v[52:55], v[172:175], v[190:193], v[52:55]
	v_mfma_f32_16x16x32_bf16 v[48:51], v[182:185], v[190:193], v[48:51]
	v_mfma_f32_16x16x32_bf16 v[36:39], v[172:175], v[198:201], v[36:39]
	v_mfma_f32_16x16x32_bf16 v[32:35], v[182:185], v[198:201], v[32:35]
	v_mfma_f32_16x16x32_bf16 v[20:23], v[172:175], v[212:215], v[20:23]
	v_mfma_f32_16x16x32_bf16 v[16:19], v[182:185], v[212:215], v[16:19]
	v_mfma_f32_16x16x32_bf16 v[4:7], v[172:175], v[220:223], v[4:7]
	v_lshl_add_u64 v[224:225], v[230:231], 0, s[42:43]
	s_mov_b32 m0, s63
	s_nop 0
	global_load_lds_dwordx4 v[224:225], off
	v_mfma_f32_16x16x32_bf16 v[0:3], v[182:185], v[220:223], v[0:3]
	s_setprio 0
	s_barrier
	s_add_i32 s84, s84, 2
	s_add_u32 s82, s82, 0x100
	s_addc_u32 s83, s83, 0
	s_cmp_gt_u32 s84, 41
	s_mov_b64 s[50:51], s[52:53]
	s_cbranch_scc0 .LBB0_1197
	s_and_b64 vcc, exec, s[44:45]
	s_cbranch_vccz .LBB0_1200
	s_barrier

; #define PG8_STAGE(bufoff, gbase, voff) do { _Pragma("unroll") for (int _i = 0; _i < 2; ++_i) \
;         __builtin_amdgcn_global_load_lds((const unsigned*)((const char*)(gbase) + (voff)[_i]), (PG8_LAS unsigned*)(lds + (bufoff) + ldsw + _i * 8192), 16, 0, 0); } while (0)
; #define PG8_LDA(dst, b, h) do { _Pragma("unroll") for (int m = 0; m < 4; ++m) _Pragma("unroll") for (int k = 0; k < 2; ++k) dst[m][k] = *(const PG8_LAS bf16x8*)(lds + PG8_SA(b, h) + aoff + m * 2048 + k * 1024); } while (0)
; #define PG8_LDB(dst, b, h) do { _Pragma("unroll") for (int n = 0; n < 2; ++n) _Pragma("unroll") for (int k = 0; k < 2; ++k) dst[n][k] = *(const PG8_LAS bf16x8*)(lds + PG8_SB(b, h) + boff + n * 2048 + k * 1024); } while (0)
; #define PG8_MMA(ai, bj, At, Bt) do { __builtin_amdgcn_s_setprio(1); _Pragma("unroll") for (int m = 0; m < 4; ++m) _Pragma("unroll") for (int n = 0; n < 2; ++n) _Pragma("unroll") for (int k = 0; k < 2; ++k) \
;         acc[ai][bj][m][n] = __builtin_amdgcn_mfma_f32_16x16x32_bf16(Bt[n][k], At[m][k], acc[ai][bj][m][n], 0, 0, 0); __builtin_amdgcn_s_setprio(0); } while (0)
; #define PG8_BAR __builtin_amdgcn_s_barrier()
; template <class Epi, class Sched, bool ALIGN_EPI = false, bool SP2 = false>
; __device__ __forceinline__ void gemm_phase(PG8_LAS unsigned char* lds, const Gemm g, const Sched& S, const Epi& E) {
;     ...
;         const bool has_next = S.next(ui + 1, nxt);
;         const char* nA = has_next ? (const char*)g.A + (size_t)nxt.pm * tstep : cA; const char* nB = has_next ? (const char*)g.Bt + (size_t)nxt.pn * tstep : cB;
;         for (int t = 0; t < nt; t += 2) {
;             const bool last = (t == nt - 2);
;             const char* a1 = cA + (size_t)(t + 1) * kstep;
;             const char* a2 = last ? nA : cA + (size_t)(t + 2) * kstep; const char* b2 = last ? nB : cB + (size_t)(t + 2) * kstep;
;             const char* a3 = a2 + kstep; const char* b3 = b2 + kstep;
;             if (last && has_next) S.a_ready(nxt);
;             if constexpr (SP2) {
;             PG8_LDB(B0, 0, 0); PG8_LDB(B1, 0, 1); PG8_SCHED; PG8_LDA(At, 0, 0); PG8_STAGE(PG8_SA(1, 1), a1 + hstep, voffA);
;             PG8_WAIT_V(8); PG8_WAIT_L(0); PG8_BAR; PG8_MMA(0, 0, At, B0); PG8_MMA(0, 1, At, B1); PG8_BAR; PG8_SCHED;
;             PG8_LDA(At, 0, 1); PG8_STAGE(PG8_SB(0, 0), b2, voffB); PG8_STAGE(PG8_SB(0, 1), b2 + hstep, voffB); PG8_STAGE(PG8_SA(0, 0), a2, voffA);
.LBB0_1286:
	s_ashr_i32 s51, s50, 31
	s_lshl_b64 s[52:53], s[50:51], 19
	s_add_u32 s52, s22, s52
	s_addc_u32 s53, s23, s53
	s_and_b64 s[54:55], s[12:13], exec
	s_cselect_b32 s51, s53, s59
	s_cselect_b32 s61, s52, s58
	s_ashr_i32 s49, s48, 31
	s_lshl_b64 s[54:55], s[48:49], 19
	v_readlane_b32 s64, v250, 9
	v_readlane_b32 s65, v250, 10
	s_add_u32 s54, s64, s54
	s_addc_u32 s55, s65, s55
	s_and_b64 s[64:65], s[12:13], exec
	s_cselect_b32 s49, s55, s63
	s_cselect_b32 s87, s54, s62
	s_add_u32 s58, s58, 0x40080
	s_addc_u32 s59, s59, 0
	s_add_u32 s88, s62, 0x100
	s_addc_u32 s89, s63, 0
	s_mov_b32 s90, -2
	s_waitcnt lgkmcnt(0)
	ds_read_b128 v[128:131], v181
	ds_read_b128 v[160:163], v181 offset:1024
	ds_read_b128 v[164:167], v181 offset:2048
	ds_read_b128 v[168:171], v181 offset:3072
	ds_read_b128 v[172:175], v203
	ds_read_b128 v[176:179], v203 offset:1024
	ds_read_b128 v[182:185], v203 offset:2048
	ds_read_b128 v[186:189], v203 offset:3072
	s_add_u32 s62, s58, 0xfffc0080
	s_addc_u32 s63, s59, -1
	s_cmp_eq_u32 s90, 12
	s_cselect_b32 s65, s51, s63
	s_cselect_b32 s64, s61, s62
	s_cselect_b32 s63, s49, s89
	s_cselect_b32 s62, s87, s88
	v_lshl_add_u64 v[232:233], s[58:59], 0, v[152:153]
	s_add_i32 m0, s15, 0xc000
	ds_read_b128 v[190:193], v208
	ds_read_b128 v[194:197], v208 offset:1024
	ds_read_b128 v[198:201], v208 offset:2048
	ds_read_b128 v[212:215], v208 offset:3072
	ds_read_b128 v[216:219], v208 offset:4096
	ds_read_b128 v[220:223], v208 offset:5120
	ds_read_b128 v[224:227], v208 offset:6144
	ds_read_b128 v[228:231], v208 offset:7168
	global_load_lds_dwordx4 v[232:233], off
	v_lshl_add_u64 v[232:233], s[58:59], 0, v[154:155]
	s_add_i32 m0, s15, 0xe000
	s_nop 0
	global_load_lds_dwordx4 v[232:233], off
	s_waitcnt vmcnt(8)
	s_waitcnt lgkmcnt(0)
	s_barrier
	s_setprio 1
	s_waitcnt lgkmcnt(0)
	v_mfma_f32_16x16x32_bf16 v[124:127], v[128:131], v[190:193], 0
	v_mfma_f32_16x16x32_bf16 v[120:123], v[164:167], v[190:193], 0
	v_mfma_f32_16x16x32_bf16 v[116:119], v[128:131], v[198:201], 0
	v_mfma_f32_16x16x32_bf16 v[112:115], v[164:167], v[198:201], 0
	v_mfma_f32_16x16x32_bf16 v[108:111], v[128:131], v[216:219], 0
	v_mfma_f32_16x16x32_bf16 v[104:107], v[164:167], v[216:219], 0
	v_mfma_f32_16x16x32_bf16 v[100:103], v[128:131], v[224:227], 0
	v_mfma_f32_16x16x32_bf16 v[96:99], v[164:167], v[224:227], 0
	v_mfma_f32_16x16x32_bf16 v[124:127], v[160:163], v[194:197], v[124:127]
	v_mfma_f32_16x16x32_bf16 v[120:123], v[168:171], v[194:197], v[120:123]
	v_mfma_f32_16x16x32_bf16 v[116:119], v[160:163], v[212:215], v[116:119]
	v_mfma_f32_16x16x32_bf16 v[112:115], v[168:171], v[212:215], v[112:115]
	v_mfma_f32_16x16x32_bf16 v[108:111], v[160:163], v[220:223], v[108:111]
	v_mfma_f32_16x16x32_bf16 v[104:107], v[168:171], v[220:223], v[104:107]
	v_mfma_f32_16x16x32_bf16 v[100:103], v[160:163], v[228:231], v[100:103]
	v_mfma_f32_16x16x32_bf16 v[96:99], v[168:171], v[228:231], v[96:99]
	s_setprio 0
	s_setprio 1
	v_mfma_f32_16x16x32_bf16 v[60:63], v[172:175], v[190:193], 0
	v_mfma_f32_16x16x32_bf16 v[56:59], v[182:185], v[190:193], 0
	v_mfma_f32_16x16x32_bf16 v[52:55], v[172:175], v[198:201], 0
	v_mfma_f32_16x16x32_bf16 v[48:51], v[182:185], v[198:201], 0
	v_mfma_f32_16x16x32_bf16 v[44:47], v[172:175], v[216:219], 0
	v_mfma_f32_16x16x32_bf16 v[40:43], v[182:185], v[216:219], 0
	v_mfma_f32_16x16x32_bf16 v[36:39], v[172:175], v[224:227], 0
	v_mfma_f32_16x16x32_bf16 v[32:35], v[182:185], v[224:227], 0
	v_mfma_f32_16x16x32_bf16 v[60:63], v[176:179], v[194:197], v[60:63]
	v_mfma_f32_16x16x32_bf16 v[56:59], v[186:189], v[194:197], v[56:59]
	v_mfma_f32_16x16x32_bf16 v[52:55], v[176:179], v[212:215], v[52:55]
	v_mfma_f32_16x16x32_bf16 v[48:51], v[186:189], v[212:215], v[48:51]
	v_mfma_f32_16x16x32_bf16 v[44:47], v[176:179], v[220:223], v[44:47]
	v_mfma_f32_16x16x32_bf16 v[40:43], v[186:189], v[220:223], v[40:43]
	v_mfma_f32_16x16x32_bf16 v[36:39], v[176:179], v[228:231], v[36:39]
	v_mfma_f32_16x16x32_bf16 v[32:35], v[186:189], v[228:231], v[32:35]
	s_setprio 0
	s_barrier
	s_add_i32 s78, s75, s14
	v_lshl_add_u64 v[232:233], s[62:63], 0, v[134:135]
	s_mov_b32 m0, s78
	ds_read_b128 v[190:193], v208 offset:16384
	ds_read_b128 v[194:197], v208 offset:17408
	ds_read_b128 v[198:201], v208 offset:18432
	ds_read_b128 v[212:215], v208 offset:19456
	ds_read_b128 v[216:219], v208 offset:20480
	ds_read_b128 v[220:223], v208 offset:21504
	ds_read_b128 v[224:227], v208 offset:22528
	ds_read_b128 v[228:231], v208 offset:23552
	global_load_lds_dwordx4 v[232:233], off
	s_add_i32 m0, s78, 0x2000
	s_add_u32 s78, s62, 0x40000
	v_lshl_add_u64 v[234:235], s[62:63], 0, v[138:139]
	s_addc_u32 s79, s63, 0
	s_add_i32 s91, s76, s14
	global_load_lds_dwordx4 v[234:235], off
	v_lshl_add_u64 v[236:237], s[78:79], 0, v[134:135]
	s_mov_b32 m0, s91
	global_load_lds_dwordx4 v[236:237], off
	v_lshl_add_u64 v[236:237], s[78:79], 0, v[138:139]
	s_add_i32 m0, s91, 0x2000
	s_nop 0
	global_load_lds_dwordx4 v[236:237], off
	s_waitcnt vmcnt(6)
	s_waitcnt lgkmcnt(0)
	s_barrier
; #define PG8_STAGE(bufoff, gbase, voff) do { _Pragma("unroll") for (int _i = 0; _i < 2; ++_i) \
;         __builtin_amdgcn_global_load_lds((const unsigned*)((const char*)(gbase) + (voff)[_i]), (PG8_LAS unsigned*)(lds + (bufoff) + ldsw + _i * 8192), 16, 0, 0); } while (0)
; #define PG8_LDA(dst, b, h) do { _Pragma("unroll") for (int m = 0; m < 4; ++m) _Pragma("unroll") for (int k = 0; k < 2; ++k) dst[m][k] = *(const PG8_LAS bf16x8*)(lds + PG8_SA(b, h) + aoff + m * 2048 + k * 1024); } while (0)
; #define PG8_LDB(dst, b, h) do { _Pragma("unroll") for (int n = 0; n < 2; ++n) _Pragma("unroll") for (int k = 0; k < 2; ++k) dst[n][k] = *(const PG8_LAS bf16x8*)(lds + PG8_SB(b, h) + boff + n * 2048 + k * 1024); } while (0)
; #define PG8_MMA(ai, bj, At, Bt) do { __builtin_amdgcn_s_setprio(1); _Pragma("unroll") for (int m = 0; m < 4; ++m) _Pragma("unroll") for (int n = 0; n < 2; ++n) _Pragma("unroll") for (int k = 0; k < 2; ++k) \
;         acc[ai][bj][m][n] = __builtin_amdgcn_mfma_f32_16x16x32_bf16(Bt[n][k], At[m][k], acc[ai][bj][m][n], 0, 0, 0); __builtin_amdgcn_s_setprio(0); } while (0)
; #define PG8_WAIT_V(n) asm volatile("s_waitcnt vmcnt(" #n ")" ::: "memory")
; #define PG8_WAIT_L(n) asm volatile("s_waitcnt lgkmcnt(" #n ")" ::: "memory")
; #define PG8_BAR __builtin_amdgcn_s_barrier()
; #define PG8_SCHED __builtin_amdgcn_sched_barrier(0)
; template <class Epi, class Sched, bool ALIGN_EPI = false, bool SP2 = false>
; __device__ __forceinline__ void gemm_phase(PG8_LAS unsigned char* lds, const Gemm g, const Sched& S, const Epi& E) {
;     ...
;             PG8_LDA(At, 0, 1); PG8_STAGE(PG8_SB(0, 0), b2, voffB); PG8_STAGE(PG8_SB(0, 1), b2 + hstep, voffB); PG8_STAGE(PG8_SA(0, 0), a2, voffA);
;             PG8_WAIT_V(8); PG8_WAIT_L(0); PG8_BAR; PG8_MMA(1, 0, At, B0); PG8_MMA(1, 1, At, B1); PG8_BAR; PG8_SCHED;
;             PG8_LDB(B0, 1, 0); PG8_LDB(B1, 1, 1); PG8_SCHED; PG8_LDA(At, 1, 0); PG8_STAGE(PG8_SA(0, 1), a2 + hstep, voffA);
;             PG8_WAIT_V(8); PG8_WAIT_L(0); PG8_BAR; PG8_MMA(0, 0, At, B0); PG8_MMA(0, 1, At, B1); PG8_BAR; PG8_SCHED;
	s_setprio 1
	s_waitcnt lgkmcnt(0)
	v_mfma_f32_16x16x32_bf16 v[92:95], v[128:131], v[190:193], 0
	v_mfma_f32_16x16x32_bf16 v[88:91], v[164:167], v[190:193], 0
	v_mfma_f32_16x16x32_bf16 v[84:87], v[128:131], v[198:201], 0
	v_mfma_f32_16x16x32_bf16 v[80:83], v[164:167], v[198:201], 0
	v_mfma_f32_16x16x32_bf16 v[76:79], v[128:131], v[216:219], 0
	v_mfma_f32_16x16x32_bf16 v[72:75], v[164:167], v[216:219], 0
	v_mfma_f32_16x16x32_bf16 v[68:71], v[128:131], v[224:227], 0
	v_mfma_f32_16x16x32_bf16 v[64:67], v[164:167], v[224:227], 0
	v_mfma_f32_16x16x32_bf16 v[92:95], v[160:163], v[194:197], v[92:95]
	v_mfma_f32_16x16x32_bf16 v[88:91], v[168:171], v[194:197], v[88:91]
	v_mfma_f32_16x16x32_bf16 v[84:87], v[160:163], v[212:215], v[84:87]
	v_mfma_f32_16x16x32_bf16 v[80:83], v[168:171], v[212:215], v[80:83]
	v_mfma_f32_16x16x32_bf16 v[76:79], v[160:163], v[220:223], v[76:79]
	v_mfma_f32_16x16x32_bf16 v[72:75], v[168:171], v[220:223], v[72:75]
	v_mfma_f32_16x16x32_bf16 v[68:71], v[160:163], v[228:231], v[68:71]
	v_lshl_add_u64 v[236:237], s[64:65], 0, v[132:133]
	s_mov_b32 m0, s15
	s_nop 0
	global_load_lds_dwordx4 v[236:237], off
	v_mfma_f32_16x16x32_bf16 v[64:67], v[168:171], v[228:231], v[64:67]
	s_setprio 0
	s_setprio 1
	v_mfma_f32_16x16x32_bf16 v[28:31], v[172:175], v[190:193], 0
	v_mfma_f32_16x16x32_bf16 v[24:27], v[182:185], v[190:193], 0
	v_mfma_f32_16x16x32_bf16 v[20:23], v[172:175], v[198:201], 0
	v_mfma_f32_16x16x32_bf16 v[16:19], v[182:185], v[198:201], 0
	v_mfma_f32_16x16x32_bf16 v[12:15], v[172:175], v[216:219], 0
	v_mfma_f32_16x16x32_bf16 v[8:11], v[182:185], v[216:219], 0
	v_mfma_f32_16x16x32_bf16 v[4:7], v[172:175], v[224:227], 0
	v_mfma_f32_16x16x32_bf16 v[0:3], v[182:185], v[224:227], 0
	v_mfma_f32_16x16x32_bf16 v[28:31], v[176:179], v[194:197], v[28:31]
	v_mfma_f32_16x16x32_bf16 v[24:27], v[186:189], v[194:197], v[24:27]
	v_mfma_f32_16x16x32_bf16 v[20:23], v[176:179], v[212:215], v[20:23]
	v_mfma_f32_16x16x32_bf16 v[16:19], v[186:189], v[212:215], v[16:19]
	v_mfma_f32_16x16x32_bf16 v[12:15], v[176:179], v[220:223], v[12:15]
	v_mfma_f32_16x16x32_bf16 v[8:11], v[186:189], v[220:223], v[8:11]
	v_mfma_f32_16x16x32_bf16 v[4:7], v[176:179], v[228:231], v[4:7]
	v_lshl_add_u64 v[238:239], s[64:65], 0, v[136:137]
	s_mov_b32 m0, s33
	s_nop 0
	global_load_lds_dwordx4 v[238:239], off
	v_mfma_f32_16x16x32_bf16 v[0:3], v[186:189], v[228:231], v[0:3]
	s_setprio 0
	s_barrier
	s_add_i32 s78, 0, 0x18000
	v_add_u32_e32 v140, s78, v147
	s_add_i32 s79, 0, 0x1c000
	ds_read_b128 v[128:131], v140
	ds_read_b128 v[160:163], v140 offset:1024
	ds_read_b128 v[164:167], v140 offset:2048
	ds_read_b128 v[168:171], v140 offset:3072
	v_add_u32_e32 v140, s79, v147
	ds_read_b128 v[172:175], v140
	ds_read_b128 v[176:179], v140 offset:1024
	ds_read_b128 v[182:185], v140 offset:2048
	ds_read_b128 v[186:189], v140 offset:3072
	s_add_u32 s64, s64, 0x40000
	s_addc_u32 s65, s65, 0
	s_mov_b32 m0, s34
	v_lshl_add_u64 v[240:241], s[64:65], 0, v[132:133]
	ds_read_b128 v[190:193], v208 offset:32768
	ds_read_b128 v[194:197], v208 offset:33792
	ds_read_b128 v[198:201], v208 offset:34816
	ds_read_b128 v[212:215], v208 offset:35840
	ds_read_b128 v[216:219], v208 offset:36864
	ds_read_b128 v[220:223], v208 offset:37888
	ds_read_b128 v[224:227], v208 offset:38912
	ds_read_b128 v[228:231], v208 offset:39936
	global_load_lds_dwordx4 v[240:241], off
	v_lshl_add_u64 v[240:241], s[64:65], 0, v[136:137]
	s_mov_b32 m0, s57
	s_nop 0
	global_load_lds_dwordx4 v[240:241], off
	s_waitcnt vmcnt(8)
	s_waitcnt lgkmcnt(0)
	s_barrier
	s_setprio 1
	s_waitcnt lgkmcnt(0)
	v_mfma_f32_16x16x32_bf16 v[124:127], v[128:131], v[190:193], v[124:127]
	v_mfma_f32_16x16x32_bf16 v[120:123], v[164:167], v[190:193], v[120:123]
	v_mfma_f32_16x16x32_bf16 v[116:119], v[128:131], v[198:201], v[116:119]
	v_mfma_f32_16x16x32_bf16 v[112:115], v[164:167], v[198:201], v[112:115]
	v_mfma_f32_16x16x32_bf16 v[108:111], v[128:131], v[216:219], v[108:111]
	v_mfma_f32_16x16x32_bf16 v[104:107], v[164:167], v[216:219], v[104:107]
	v_mfma_f32_16x16x32_bf16 v[100:103], v[128:131], v[224:227], v[100:103]
	v_mfma_f32_16x16x32_bf16 v[96:99], v[164:167], v[224:227], v[96:99]
	v_mfma_f32_16x16x32_bf16 v[124:127], v[160:163], v[194:197], v[124:127]
	v_mfma_f32_16x16x32_bf16 v[120:123], v[168:171], v[194:197], v[120:123]
	v_mfma_f32_16x16x32_bf16 v[116:119], v[160:163], v[212:215], v[116:119]
	v_mfma_f32_16x16x32_bf16 v[112:115], v[168:171], v[212:215], v[112:115]
	v_mfma_f32_16x16x32_bf16 v[108:111], v[160:163], v[220:223], v[108:111]
	v_mfma_f32_16x16x32_bf16 v[104:107], v[168:171], v[220:223], v[104:107]
	v_mfma_f32_16x16x32_bf16 v[100:103], v[160:163], v[228:231], v[100:103]
	v_mfma_f32_16x16x32_bf16 v[96:99], v[168:171], v[228:231], v[96:99]
	s_setprio 0
	s_setprio 1
	v_mfma_f32_16x16x32_bf16 v[60:63], v[172:175], v[190:193], v[60:63]
	v_mfma_f32_16x16x32_bf16 v[56:59], v[182:185], v[190:193], v[56:59]
	v_mfma_f32_16x16x32_bf16 v[52:55], v[172:175], v[198:201], v[52:55]
	v_mfma_f32_16x16x32_bf16 v[48:51], v[182:185], v[198:201], v[48:51]
	v_mfma_f32_16x16x32_bf16 v[44:47], v[172:175], v[216:219], v[44:47]
	v_mfma_f32_16x16x32_bf16 v[40:43], v[182:185], v[216:219], v[40:43]
	v_mfma_f32_16x16x32_bf16 v[36:39], v[172:175], v[224:227], v[36:39]
	v_mfma_f32_16x16x32_bf16 v[32:35], v[182:185], v[224:227], v[32:35]
	v_mfma_f32_16x16x32_bf16 v[60:63], v[176:179], v[194:197], v[60:63]
	v_mfma_f32_16x16x32_bf16 v[56:59], v[186:189], v[194:197], v[56:59]
	v_mfma_f32_16x16x32_bf16 v[52:55], v[176:179], v[212:215], v[52:55]
	v_mfma_f32_16x16x32_bf16 v[48:51], v[186:189], v[212:215], v[48:51]
	v_mfma_f32_16x16x32_bf16 v[44:47], v[176:179], v[220:223], v[44:47]
	v_mfma_f32_16x16x32_bf16 v[40:43], v[186:189], v[220:223], v[40:43]
	v_mfma_f32_16x16x32_bf16 v[36:39], v[176:179], v[228:231], v[36:39]
	v_mfma_f32_16x16x32_bf16 v[32:35], v[186:189], v[228:231], v[32:35]
	s_setprio 0
	s_barrier
; #define PG8_STAGE(bufoff, gbase, voff) do { _Pragma("unroll") for (int _i = 0; _i < 2; ++_i) \
;         __builtin_amdgcn_global_load_lds((const unsigned*)((const char*)(gbase) + (voff)[_i]), (PG8_LAS unsigned*)(lds + (bufoff) + ldsw + _i * 8192), 16, 0, 0); } while (0)
; #define PG8_LDA(dst, b, h) do { _Pragma("unroll") for (int m = 0; m < 4; ++m) _Pragma("unroll") for (int k = 0; k < 2; ++k) dst[m][k] = *(const PG8_LAS bf16x8*)(lds + PG8_SA(b, h) + aoff + m * 2048 + k * 1024); } while (0)
; #define PG8_LDB(dst, b, h) do { _Pragma("unroll") for (int n = 0; n < 2; ++n) _Pragma("unroll") for (int k = 0; k < 2; ++k) dst[n][k] = *(const PG8_LAS bf16x8*)(lds + PG8_SB(b, h) + boff + n * 2048 + k * 1024); } while (0)
; template <class Epi, class Sched, bool ALIGN_EPI = false, bool SP2 = false>
; __device__ __forceinline__ void gemm_phase(PG8_LAS unsigned char* lds, const Gemm g, const Sched& S, const Epi& E) {
;     ...
;         for (int t = 0; t < nt; t += 2) {
;             const bool last = (t == nt - 2);
;             const char* a1 = cA + (size_t)(t + 1) * kstep;
;             const char* a2 = last ? nA : cA + (size_t)(t + 2) * kstep; const char* b2 = last ? nB : cB + (size_t)(t + 2) * kstep;
;             const char* a3 = a2 + kstep; const char* b3 = b2 + kstep;
;             if (last && has_next) S.a_ready(nxt);
;             if constexpr (SP2) {
;             PG8_LDB(B0, 0, 0); PG8_LDB(B1, 0, 1); PG8_SCHED; PG8_LDA(At, 0, 0); PG8_STAGE(PG8_SA(1, 1), a1 + hstep, voffA);
;             PG8_WAIT_V(8); PG8_WAIT_L(0); PG8_BAR; PG8_MMA(0, 0, At, B0); PG8_MMA(0, 1, At, B1); PG8_BAR; PG8_SCHED;
;             PG8_LDA(At, 0, 1); PG8_STAGE(PG8_SB(0, 0), b2, voffB); PG8_STAGE(PG8_SB(0, 1), b2 + hstep, voffB); PG8_STAGE(PG8_SA(0, 0), a2, voffA);
;             PG8_WAIT_V(8); PG8_WAIT_L(0); PG8_BAR; PG8_MMA(1, 0, At, B0); PG8_MMA(1, 1, At, B1); PG8_BAR; PG8_SCHED;
;             PG8_LDB(B0, 1, 0); PG8_LDB(B1, 1, 1); PG8_SCHED; PG8_LDA(At, 1, 0); PG8_STAGE(PG8_SA(0, 1), a2 + hstep, voffA);
;             PG8_WAIT_V(8); PG8_WAIT_L(0); PG8_BAR; PG8_MMA(0, 0, At, B0); PG8_MMA(0, 1, At, B1); PG8_BAR; PG8_SCHED;
;             PG8_LDA(At, 1, 1); PG8_STAGE(PG8_SB(1, 0), b3, voffB); PG8_STAGE(PG8_SB(1, 1), b3 + hstep, voffB); PG8_STAGE(PG8_SA(1, 0), a3, voffA);
;             PG8_WAIT_V(8); PG8_WAIT_L(0); PG8_BAR; PG8_MMA(1, 0, At, B0); PG8_MMA(1, 1, At, B1); PG8_BAR; PG8_SCHED;
	s_add_i32 s64, s78, s14
	v_lshl_add_u64 v[232:233], v[232:233], 0, s[42:43]
	s_mov_b32 m0, s64
	ds_read_b128 v[190:193], v208 offset:49152
	ds_read_b128 v[194:197], v208 offset:50176
	ds_read_b128 v[198:201], v208 offset:51200
	ds_read_b128 v[212:215], v208 offset:52224
	ds_read_b128 v[216:219], v208 offset:53248
	ds_read_b128 v[220:223], v208 offset:54272
	ds_read_b128 v[224:227], v208 offset:55296
	ds_read_b128 v[228:231], v208 offset:56320
	global_load_lds_dwordx4 v[232:233], off
	s_add_i32 m0, s64, 0x2000
	s_add_u32 s62, s62, 0x40080
	v_lshl_add_u64 v[232:233], v[234:235], 0, s[42:43]
	s_addc_u32 s63, s63, 0
	s_add_i32 s64, s79, s14
	global_load_lds_dwordx4 v[232:233], off
	v_lshl_add_u64 v[232:233], s[62:63], 0, v[134:135]
	s_mov_b32 m0, s64
	s_nop 0
	global_load_lds_dwordx4 v[232:233], off
	v_lshl_add_u64 v[232:233], s[62:63], 0, v[138:139]
	s_add_i32 m0, s64, 0x2000
	s_nop 0
	global_load_lds_dwordx4 v[232:233], off
	s_waitcnt vmcnt(6)
	s_waitcnt lgkmcnt(0)
	s_barrier
	s_setprio 1
	s_waitcnt lgkmcnt(0)
	v_mfma_f32_16x16x32_bf16 v[92:95], v[128:131], v[190:193], v[92:95]
	v_mfma_f32_16x16x32_bf16 v[88:91], v[164:167], v[190:193], v[88:91]
	v_mfma_f32_16x16x32_bf16 v[84:87], v[128:131], v[198:201], v[84:87]
	v_mfma_f32_16x16x32_bf16 v[80:83], v[164:167], v[198:201], v[80:83]
	v_mfma_f32_16x16x32_bf16 v[76:79], v[128:131], v[216:219], v[76:79]
	v_mfma_f32_16x16x32_bf16 v[72:75], v[164:167], v[216:219], v[72:75]
	v_mfma_f32_16x16x32_bf16 v[68:71], v[128:131], v[224:227], v[68:71]
	v_mfma_f32_16x16x32_bf16 v[64:67], v[164:167], v[224:227], v[64:67]
	v_mfma_f32_16x16x32_bf16 v[92:95], v[160:163], v[194:197], v[92:95]
	v_mfma_f32_16x16x32_bf16 v[88:91], v[168:171], v[194:197], v[88:91]
	v_mfma_f32_16x16x32_bf16 v[84:87], v[160:163], v[212:215], v[84:87]
	v_mfma_f32_16x16x32_bf16 v[80:83], v[168:171], v[212:215], v[80:83]
	v_mfma_f32_16x16x32_bf16 v[76:79], v[160:163], v[220:223], v[76:79]
	v_mfma_f32_16x16x32_bf16 v[72:75], v[168:171], v[220:223], v[72:75]
	v_mfma_f32_16x16x32_bf16 v[68:71], v[160:163], v[228:231], v[68:71]
	v_lshl_add_u64 v[232:233], v[236:237], 0, s[42:43]
	s_mov_b32 m0, s67
	s_nop 0
	global_load_lds_dwordx4 v[232:233], off
	v_mfma_f32_16x16x32_bf16 v[64:67], v[168:171], v[228:231], v[64:67]
	s_setprio 0
	s_setprio 1
	v_mfma_f32_16x16x32_bf16 v[28:31], v[172:175], v[190:193], v[28:31]
	v_mfma_f32_16x16x32_bf16 v[24:27], v[182:185], v[190:193], v[24:27]
	v_mfma_f32_16x16x32_bf16 v[20:23], v[172:175], v[198:201], v[20:23]
	v_mfma_f32_16x16x32_bf16 v[16:19], v[182:185], v[198:201], v[16:19]
	v_mfma_f32_16x16x32_bf16 v[12:15], v[172:175], v[216:219], v[12:15]
	v_mfma_f32_16x16x32_bf16 v[8:11], v[182:185], v[216:219], v[8:11]
	v_mfma_f32_16x16x32_bf16 v[4:7], v[172:175], v[224:227], v[4:7]
	v_mfma_f32_16x16x32_bf16 v[0:3], v[182:185], v[224:227], v[0:3]
	v_mfma_f32_16x16x32_bf16 v[28:31], v[176:179], v[194:197], v[28:31]
	v_mfma_f32_16x16x32_bf16 v[24:27], v[186:189], v[194:197], v[24:27]
	v_mfma_f32_16x16x32_bf16 v[20:23], v[176:179], v[212:215], v[20:23]
	v_mfma_f32_16x16x32_bf16 v[16:19], v[186:189], v[212:215], v[16:19]
	v_mfma_f32_16x16x32_bf16 v[12:15], v[176:179], v[220:223], v[12:15]
	v_mfma_f32_16x16x32_bf16 v[8:11], v[186:189], v[220:223], v[8:11]
	v_mfma_f32_16x16x32_bf16 v[4:7], v[176:179], v[228:231], v[4:7]
	v_lshl_add_u64 v[232:233], v[238:239], 0, s[42:43]
	s_mov_b32 m0, s74
	s_nop 0
	global_load_lds_dwordx4 v[232:233], off
	v_mfma_f32_16x16x32_bf16 v[0:3], v[186:189], v[228:231], v[0:3]
	s_setprio 0
	s_barrier
	s_add_i32 s90, s90, 2
	s_add_u32 s58, s58, 0x100
	s_addc_u32 s59, s59, 0
	s_add_u32 s88, s88, 0x100
	s_addc_u32 s89, s89, 0
.LBB0_1287:
	ds_read_b128 v[128:131], v181
	ds_read_b128 v[160:163], v181 offset:1024
	ds_read_b128 v[164:167], v181 offset:2048
	ds_read_b128 v[168:171], v181 offset:3072
	ds_read_b128 v[172:175], v203
	ds_read_b128 v[176:179], v203 offset:1024
	ds_read_b128 v[182:185], v203 offset:2048
	ds_read_b128 v[186:189], v203 offset:3072
	s_add_u32 s62, s58, 0xfffc0080
	s_addc_u32 s63, s59, -1
	s_cmp_eq_u32 s90, 12
	s_cselect_b32 s65, s51, s63
	s_cselect_b32 s64, s61, s62
	s_cselect_b32 s63, s49, s89
	s_cselect_b32 s62, s87, s88
	v_lshl_add_u64 v[232:233], s[58:59], 0, v[152:153]
	s_add_i32 m0, s15, 0xc000
	ds_read_b128 v[190:193], v208
	ds_read_b128 v[194:197], v208 offset:1024
	ds_read_b128 v[198:201], v208 offset:2048
	ds_read_b128 v[212:215], v208 offset:3072
	ds_read_b128 v[216:219], v208 offset:4096
	ds_read_b128 v[220:223], v208 offset:5120
	ds_read_b128 v[224:227], v208 offset:6144
	ds_read_b128 v[228:231], v208 offset:7168
	global_load_lds_dwordx4 v[232:233], off
	v_lshl_add_u64 v[232:233], s[58:59], 0, v[154:155]
	s_add_i32 m0, s15, 0xe000
	s_nop 0
	global_load_lds_dwordx4 v[232:233], off
	s_waitcnt vmcnt(8)
	s_waitcnt lgkmcnt(0)
	s_barrier
; #define PG8_STAGE(bufoff, gbase, voff) do { _Pragma("unroll") for (int _i = 0; _i < 2; ++_i) \
;         __builtin_amdgcn_global_load_lds((const unsigned*)((const char*)(gbase) + (voff)[_i]), (PG8_LAS unsigned*)(lds + (bufoff) + ldsw + _i * 8192), 16, 0, 0); } while (0)
; #define PG8_LDA(dst, b, h) do { _Pragma("unroll") for (int m = 0; m < 4; ++m) _Pragma("unroll") for (int k = 0; k < 2; ++k) dst[m][k] = *(const PG8_LAS bf16x8*)(lds + PG8_SA(b, h) + aoff + m * 2048 + k * 1024); } while (0)
; #define PG8_LDB(dst, b, h) do { _Pragma("unroll") for (int n = 0; n < 2; ++n) _Pragma("unroll") for (int k = 0; k < 2; ++k) dst[n][k] = *(const PG8_LAS bf16x8*)(lds + PG8_SB(b, h) + boff + n * 2048 + k * 1024); } while (0)
; #define PG8_MMA(ai, bj, At, Bt) do { __builtin_amdgcn_s_setprio(1); _Pragma("unroll") for (int m = 0; m < 4; ++m) _Pragma("unroll") for (int n = 0; n < 2; ++n) _Pragma("unroll") for (int k = 0; k < 2; ++k) \
;         acc[ai][bj][m][n] = __builtin_amdgcn_mfma_f32_16x16x32_bf16(Bt[n][k], At[m][k], acc[ai][bj][m][n], 0, 0, 0); __builtin_amdgcn_s_setprio(0); } while (0)
; #define PG8_WAIT_V(n) asm volatile("s_waitcnt vmcnt(" #n ")" ::: "memory")
; #define PG8_WAIT_L(n) asm volatile("s_waitcnt lgkmcnt(" #n ")" ::: "memory")
; #define PG8_BAR __builtin_amdgcn_s_barrier()
; #define PG8_SCHED __builtin_amdgcn_sched_barrier(0)
; template <class Epi, class Sched, bool ALIGN_EPI = false, bool SP2 = false>
; __device__ __forceinline__ void gemm_phase(PG8_LAS unsigned char* lds, const Gemm g, const Sched& S, const Epi& E) {
;     ...
;             PG8_LDB(B0, 0, 0); PG8_LDB(B1, 0, 1); PG8_SCHED; PG8_LDA(At, 0, 0); PG8_STAGE(PG8_SA(1, 1), a1 + hstep, voffA);
;             PG8_WAIT_V(8); PG8_WAIT_L(0); PG8_BAR; PG8_MMA(0, 0, At, B0); PG8_MMA(0, 1, At, B1); PG8_BAR; PG8_SCHED;
;             PG8_LDA(At, 0, 1); PG8_STAGE(PG8_SB(0, 0), b2, voffB); PG8_STAGE(PG8_SB(0, 1), b2 + hstep, voffB); PG8_STAGE(PG8_SA(0, 0), a2, voffA);
;             PG8_WAIT_V(8); PG8_WAIT_L(0); PG8_BAR; PG8_MMA(1, 0, At, B0); PG8_MMA(1, 1, At, B1); PG8_BAR; PG8_SCHED;
	s_setprio 1
	s_waitcnt lgkmcnt(0)
	v_mfma_f32_16x16x32_bf16 v[124:127], v[128:131], v[190:193], v[124:127]
	v_mfma_f32_16x16x32_bf16 v[120:123], v[164:167], v[190:193], v[120:123]
	v_mfma_f32_16x16x32_bf16 v[116:119], v[128:131], v[198:201], v[116:119]
	v_mfma_f32_16x16x32_bf16 v[112:115], v[164:167], v[198:201], v[112:115]
	v_mfma_f32_16x16x32_bf16 v[108:111], v[128:131], v[216:219], v[108:111]
	v_mfma_f32_16x16x32_bf16 v[104:107], v[164:167], v[216:219], v[104:107]
	v_mfma_f32_16x16x32_bf16 v[100:103], v[128:131], v[224:227], v[100:103]
	v_mfma_f32_16x16x32_bf16 v[96:99], v[164:167], v[224:227], v[96:99]
	v_mfma_f32_16x16x32_bf16 v[124:127], v[160:163], v[194:197], v[124:127]
	v_mfma_f32_16x16x32_bf16 v[120:123], v[168:171], v[194:197], v[120:123]
	v_mfma_f32_16x16x32_bf16 v[116:119], v[160:163], v[212:215], v[116:119]
	v_mfma_f32_16x16x32_bf16 v[112:115], v[168:171], v[212:215], v[112:115]
	v_mfma_f32_16x16x32_bf16 v[108:111], v[160:163], v[220:223], v[108:111]
	v_mfma_f32_16x16x32_bf16 v[104:107], v[168:171], v[220:223], v[104:107]
	v_mfma_f32_16x16x32_bf16 v[100:103], v[160:163], v[228:231], v[100:103]
	v_mfma_f32_16x16x32_bf16 v[96:99], v[168:171], v[228:231], v[96:99]
	s_setprio 0
	s_setprio 1
	v_mfma_f32_16x16x32_bf16 v[60:63], v[172:175], v[190:193], v[60:63]
	v_mfma_f32_16x16x32_bf16 v[56:59], v[182:185], v[190:193], v[56:59]
	v_mfma_f32_16x16x32_bf16 v[52:55], v[172:175], v[198:201], v[52:55]
	v_mfma_f32_16x16x32_bf16 v[48:51], v[182:185], v[198:201], v[48:51]
	v_mfma_f32_16x16x32_bf16 v[44:47], v[172:175], v[216:219], v[44:47]
	v_mfma_f32_16x16x32_bf16 v[40:43], v[182:185], v[216:219], v[40:43]
	v_mfma_f32_16x16x32_bf16 v[36:39], v[172:175], v[224:227], v[36:39]
	v_mfma_f32_16x16x32_bf16 v[32:35], v[182:185], v[224:227], v[32:35]
	v_mfma_f32_16x16x32_bf16 v[60:63], v[176:179], v[194:197], v[60:63]
	v_mfma_f32_16x16x32_bf16 v[56:59], v[186:189], v[194:197], v[56:59]
	v_mfma_f32_16x16x32_bf16 v[52:55], v[176:179], v[212:215], v[52:55]
	v_mfma_f32_16x16x32_bf16 v[48:51], v[186:189], v[212:215], v[48:51]
	v_mfma_f32_16x16x32_bf16 v[44:47], v[176:179], v[220:223], v[44:47]
	v_mfma_f32_16x16x32_bf16 v[40:43], v[186:189], v[220:223], v[40:43]
	v_mfma_f32_16x16x32_bf16 v[36:39], v[176:179], v[228:231], v[36:39]
	v_mfma_f32_16x16x32_bf16 v[32:35], v[186:189], v[228:231], v[32:35]
	s_setprio 0
	s_barrier
	s_add_i32 s78, s75, s14
	v_lshl_add_u64 v[232:233], s[62:63], 0, v[134:135]
	s_mov_b32 m0, s78
	ds_read_b128 v[190:193], v208 offset:16384
	ds_read_b128 v[194:197], v208 offset:17408
	ds_read_b128 v[198:201], v208 offset:18432
	ds_read_b128 v[212:215], v208 offset:19456
	ds_read_b128 v[216:219], v208 offset:20480
	ds_read_b128 v[220:223], v208 offset:21504
	ds_read_b128 v[224:227], v208 offset:22528
	ds_read_b128 v[228:231], v208 offset:23552
	global_load_lds_dwordx4 v[232:233], off
	s_add_i32 m0, s78, 0x2000
	s_add_u32 s78, s62, 0x40000
	v_lshl_add_u64 v[234:235], s[62:63], 0, v[138:139]
	s_addc_u32 s79, s63, 0
	s_add_i32 s91, s76, s14
	global_load_lds_dwordx4 v[234:235], off
	v_lshl_add_u64 v[236:237], s[78:79], 0, v[134:135]
	s_mov_b32 m0, s91
	global_load_lds_dwordx4 v[236:237], off
	v_lshl_add_u64 v[236:237], s[78:79], 0, v[138:139]
	s_add_i32 m0, s91, 0x2000
	s_nop 0
	global_load_lds_dwordx4 v[236:237], off
	s_waitcnt vmcnt(6)
	s_waitcnt lgkmcnt(0)
	s_barrier
	s_setprio 1
	s_waitcnt lgkmcnt(0)
	v_mfma_f32_16x16x32_bf16 v[92:95], v[128:131], v[190:193], v[92:95]
	v_mfma_f32_16x16x32_bf16 v[88:91], v[164:167], v[190:193], v[88:91]
	v_mfma_f32_16x16x32_bf16 v[84:87], v[128:131], v[198:201], v[84:87]
	v_mfma_f32_16x16x32_bf16 v[80:83], v[164:167], v[198:201], v[80:83]
	v_mfma_f32_16x16x32_bf16 v[76:79], v[128:131], v[216:219], v[76:79]
	v_mfma_f32_16x16x32_bf16 v[72:75], v[164:167], v[216:219], v[72:75]
	v_mfma_f32_16x16x32_bf16 v[68:71], v[128:131], v[224:227], v[68:71]
	v_mfma_f32_16x16x32_bf16 v[64:67], v[164:167], v[224:227], v[64:67]
	v_mfma_f32_16x16x32_bf16 v[92:95], v[160:163], v[194:197], v[92:95]
	v_mfma_f32_16x16x32_bf16 v[88:91], v[168:171], v[194:197], v[88:91]
	v_mfma_f32_16x16x32_bf16 v[84:87], v[160:163], v[212:215], v[84:87]
	v_mfma_f32_16x16x32_bf16 v[80:83], v[168:171], v[212:215], v[80:83]
	v_mfma_f32_16x16x32_bf16 v[76:79], v[160:163], v[220:223], v[76:79]
	v_mfma_f32_16x16x32_bf16 v[72:75], v[168:171], v[220:223], v[72:75]
	v_mfma_f32_16x16x32_bf16 v[68:71], v[160:163], v[228:231], v[68:71]
	v_lshl_add_u64 v[236:237], s[64:65], 0, v[132:133]
	s_mov_b32 m0, s15
	s_nop 0
	global_load_lds_dwordx4 v[236:237], off
	v_mfma_f32_16x16x32_bf16 v[64:67], v[168:171], v[228:231], v[64:67]
	s_setprio 0
	s_setprio 1
	v_mfma_f32_16x16x32_bf16 v[28:31], v[172:175], v[190:193], v[28:31]
	v_mfma_f32_16x16x32_bf16 v[24:27], v[182:185], v[190:193], v[24:27]
	v_mfma_f32_16x16x32_bf16 v[20:23], v[172:175], v[198:201], v[20:23]
	v_mfma_f32_16x16x32_bf16 v[16:19], v[182:185], v[198:201], v[16:19]
	v_mfma_f32_16x16x32_bf16 v[12:15], v[172:175], v[216:219], v[12:15]
	v_mfma_f32_16x16x32_bf16 v[8:11], v[182:185], v[216:219], v[8:11]
	v_mfma_f32_16x16x32_bf16 v[4:7], v[172:175], v[224:227], v[4:7]
	v_mfma_f32_16x16x32_bf16 v[0:3], v[182:185], v[224:227], v[0:3]
	v_mfma_f32_16x16x32_bf16 v[28:31], v[176:179], v[194:197], v[28:31]
	v_mfma_f32_16x16x32_bf16 v[24:27], v[186:189], v[194:197], v[24:27]
	v_mfma_f32_16x16x32_bf16 v[20:23], v[176:179], v[212:215], v[20:23]
	v_mfma_f32_16x16x32_bf16 v[16:19], v[186:189], v[212:215], v[16:19]
	v_mfma_f32_16x16x32_bf16 v[12:15], v[176:179], v[220:223], v[12:15]
	v_mfma_f32_16x16x32_bf16 v[8:11], v[186:189], v[220:223], v[8:11]
	v_mfma_f32_16x16x32_bf16 v[4:7], v[176:179], v[228:231], v[4:7]
	v_lshl_add_u64 v[238:239], s[64:65], 0, v[136:137]
	s_mov_b32 m0, s33
	s_nop 0
	global_load_lds_dwordx4 v[238:239], off
	v_mfma_f32_16x16x32_bf16 v[0:3], v[186:189], v[228:231], v[0:3]
	s_setprio 0
	s_barrier
; #define PG8_STAGE(bufoff, gbase, voff) do { _Pragma("unroll") for (int _i = 0; _i < 2; ++_i) \
;         __builtin_amdgcn_global_load_lds((const unsigned*)((const char*)(gbase) + (voff)[_i]), (PG8_LAS unsigned*)(lds + (bufoff) + ldsw + _i * 8192), 16, 0, 0); } while (0)
; #define PG8_LDA(dst, b, h) do { _Pragma("unroll") for (int m = 0; m < 4; ++m) _Pragma("unroll") for (int k = 0; k < 2; ++k) dst[m][k] = *(const PG8_LAS bf16x8*)(lds + PG8_SA(b, h) + aoff + m * 2048 + k * 1024); } while (0)
; #define PG8_LDB(dst, b, h) do { _Pragma("unroll") for (int n = 0; n < 2; ++n) _Pragma("unroll") for (int k = 0; k < 2; ++k) dst[n][k] = *(const PG8_LAS bf16x8*)(lds + PG8_SB(b, h) + boff + n * 2048 + k * 1024); } while (0)
; #define PG8_MMA(ai, bj, At, Bt) do { __builtin_amdgcn_s_setprio(1); _Pragma("unroll") for (int m = 0; m < 4; ++m) _Pragma("unroll") for (int n = 0; n < 2; ++n) _Pragma("unroll") for (int k = 0; k < 2; ++k) \
;         acc[ai][bj][m][n] = __builtin_amdgcn_mfma_f32_16x16x32_bf16(Bt[n][k], At[m][k], acc[ai][bj][m][n], 0, 0, 0); __builtin_amdgcn_s_setprio(0); } while (0)
; #define PG8_WAIT_V(n) asm volatile("s_waitcnt vmcnt(" #n ")" ::: "memory")
; #define PG8_WAIT_L(n) asm volatile("s_waitcnt lgkmcnt(" #n ")" ::: "memory")
; #define PG8_BAR __builtin_amdgcn_s_barrier()
; #define PG8_SCHED __builtin_amdgcn_sched_barrier(0)
; template <class Epi, class Sched, bool ALIGN_EPI = false, bool SP2 = false>
; __device__ __forceinline__ void gemm_phase(PG8_LAS unsigned char* lds, const Gemm g, const Sched& S, const Epi& E) {
;     ...
;             PG8_LDB(B0, 1, 0); PG8_LDB(B1, 1, 1); PG8_SCHED; PG8_LDA(At, 1, 0); PG8_STAGE(PG8_SA(0, 1), a2 + hstep, voffA);
;             PG8_WAIT_V(8); PG8_WAIT_L(0); PG8_BAR; PG8_MMA(0, 0, At, B0); PG8_MMA(0, 1, At, B1); PG8_BAR; PG8_SCHED;
	s_add_i32 s78, 0, 0x18000
	v_add_u32_e32 v140, s78, v147
	s_add_i32 s79, 0, 0x1c000
	ds_read_b128 v[128:131], v140
	ds_read_b128 v[160:163], v140 offset:1024
	ds_read_b128 v[164:167], v140 offset:2048
	ds_read_b128 v[168:171], v140 offset:3072
	v_add_u32_e32 v140, s79, v147
	ds_read_b128 v[172:175], v140
	ds_read_b128 v[176:179], v140 offset:1024
	ds_read_b128 v[182:185], v140 offset:2048
	ds_read_b128 v[186:189], v140 offset:3072
	s_add_u32 s64, s64, 0x40000
	s_addc_u32 s65, s65, 0
	s_mov_b32 m0, s34
	v_lshl_add_u64 v[240:241], s[64:65], 0, v[132:133]
	ds_read_b128 v[190:193], v208 offset:32768
	ds_read_b128 v[194:197], v208 offset:33792
	ds_read_b128 v[198:201], v208 offset:34816
	ds_read_b128 v[212:215], v208 offset:35840
	ds_read_b128 v[216:219], v208 offset:36864
	ds_read_b128 v[220:223], v208 offset:37888
	ds_read_b128 v[224:227], v208 offset:38912
	ds_read_b128 v[228:231], v208 offset:39936
	global_load_lds_dwordx4 v[240:241], off
	v_lshl_add_u64 v[240:241], s[64:65], 0, v[136:137]
	s_mov_b32 m0, s57
	s_nop 0
	global_load_lds_dwordx4 v[240:241], off
	s_waitcnt vmcnt(8)
	s_waitcnt lgkmcnt(0)
	s_barrier
	s_setprio 1
	s_waitcnt lgkmcnt(0)
	v_mfma_f32_16x16x32_bf16 v[124:127], v[128:131], v[190:193], v[124:127]
	v_mfma_f32_16x16x32_bf16 v[120:123], v[164:167], v[190:193], v[120:123]
	v_mfma_f32_16x16x32_bf16 v[116:119], v[128:131], v[198:201], v[116:119]
	v_mfma_f32_16x16x32_bf16 v[112:115], v[164:167], v[198:201], v[112:115]
	v_mfma_f32_16x16x32_bf16 v[108:111], v[128:131], v[216:219], v[108:111]
	v_mfma_f32_16x16x32_bf16 v[104:107], v[164:167], v[216:219], v[104:107]
	v_mfma_f32_16x16x32_bf16 v[100:103], v[128:131], v[224:227], v[100:103]
	v_mfma_f32_16x16x32_bf16 v[96:99], v[164:167], v[224:227], v[96:99]
	v_mfma_f32_16x16x32_bf16 v[124:127], v[160:163], v[194:197], v[124:127]
	v_mfma_f32_16x16x32_bf16 v[120:123], v[168:171], v[194:197], v[120:123]
	v_mfma_f32_16x16x32_bf16 v[116:119], v[160:163], v[212:215], v[116:119]
	v_mfma_f32_16x16x32_bf16 v[112:115], v[168:171], v[212:215], v[112:115]
	v_mfma_f32_16x16x32_bf16 v[108:111], v[160:163], v[220:223], v[108:111]
	v_mfma_f32_16x16x32_bf16 v[104:107], v[168:171], v[220:223], v[104:107]
	v_mfma_f32_16x16x32_bf16 v[100:103], v[160:163], v[228:231], v[100:103]
	v_mfma_f32_16x16x32_bf16 v[96:99], v[168:171], v[228:231], v[96:99]
	s_setprio 0
	s_setprio 1
	v_mfma_f32_16x16x32_bf16 v[60:63], v[172:175], v[190:193], v[60:63]
	v_mfma_f32_16x16x32_bf16 v[56:59], v[182:185], v[190:193], v[56:59]
	v_mfma_f32_16x16x32_bf16 v[52:55], v[172:175], v[198:201], v[52:55]
	v_mfma_f32_16x16x32_bf16 v[48:51], v[182:185], v[198:201], v[48:51]
	v_mfma_f32_16x16x32_bf16 v[44:47], v[172:175], v[216:219], v[44:47]
	v_mfma_f32_16x16x32_bf16 v[40:43], v[182:185], v[216:219], v[40:43]
	v_mfma_f32_16x16x32_bf16 v[36:39], v[172:175], v[224:227], v[36:39]
	v_mfma_f32_16x16x32_bf16 v[32:35], v[182:185], v[224:227], v[32:35]
	v_mfma_f32_16x16x32_bf16 v[60:63], v[176:179], v[194:197], v[60:63]
	v_mfma_f32_16x16x32_bf16 v[56:59], v[186:189], v[194:197], v[56:59]
	v_mfma_f32_16x16x32_bf16 v[52:55], v[176:179], v[212:215], v[52:55]
	v_mfma_f32_16x16x32_bf16 v[48:51], v[186:189], v[212:215], v[48:51]
	v_mfma_f32_16x16x32_bf16 v[44:47], v[176:179], v[220:223], v[44:47]
	v_mfma_f32_16x16x32_bf16 v[40:43], v[186:189], v[220:223], v[40:43]
	v_mfma_f32_16x16x32_bf16 v[36:39], v[176:179], v[228:231], v[36:39]
	v_mfma_f32_16x16x32_bf16 v[32:35], v[186:189], v[228:231], v[32:35]
	s_setprio 0
	s_barrier
; #define PG8_STAGE(bufoff, gbase, voff) do { _Pragma("unroll") for (int _i = 0; _i < 2; ++_i) \
;         __builtin_amdgcn_global_load_lds((const unsigned*)((const char*)(gbase) + (voff)[_i]), (PG8_LAS unsigned*)(lds + (bufoff) + ldsw + _i * 8192), 16, 0, 0); } while (0)
; #define PG8_LDA(dst, b, h) do { _Pragma("unroll") for (int m = 0; m < 4; ++m) _Pragma("unroll") for (int k = 0; k < 2; ++k) dst[m][k] = *(const PG8_LAS bf16x8*)(lds + PG8_SA(b, h) + aoff + m * 2048 + k * 1024); } while (0)
; #define PG8_MMA(ai, bj, At, Bt) do { __builtin_amdgcn_s_setprio(1); _Pragma("unroll") for (int m = 0; m < 4; ++m) _Pragma("unroll") for (int n = 0; n < 2; ++n) _Pragma("unroll") for (int k = 0; k < 2; ++k) \
;         acc[ai][bj][m][n] = __builtin_amdgcn_mfma_f32_16x16x32_bf16(Bt[n][k], At[m][k], acc[ai][bj][m][n], 0, 0, 0); __builtin_amdgcn_s_setprio(0); } while (0)
; #define PG8_WAIT_V(n) asm volatile("s_waitcnt vmcnt(" #n ")" ::: "memory")
; #define PG8_WAIT_L(n) asm volatile("s_waitcnt lgkmcnt(" #n ")" ::: "memory")
; #define PG8_BAR __builtin_amdgcn_s_barrier()
; #define PG8_SCHED __builtin_amdgcn_sched_barrier(0)
; template <class Epi, class Sched, bool ALIGN_EPI = false, bool SP2 = false>
; __device__ __forceinline__ void gemm_phase(PG8_LAS unsigned char* lds, const Gemm g, const Sched& S, const Epi& E) {
;     ...
;         for (int t = 0; t < nt; t += 2) {
;             const bool last = (t == nt - 2);
;     ...
;             PG8_LDA(At, 1, 1); PG8_STAGE(PG8_SB(1, 0), b3, voffB); PG8_STAGE(PG8_SB(1, 1), b3 + hstep, voffB); PG8_STAGE(PG8_SA(1, 0), a3, voffA);
;             PG8_WAIT_V(8); PG8_WAIT_L(0); PG8_BAR; PG8_MMA(1, 0, At, B0); PG8_MMA(1, 1, At, B1); PG8_BAR; PG8_SCHED;
	s_add_i32 s64, s78, s14
	v_lshl_add_u64 v[232:233], v[232:233], 0, s[42:43]
	s_mov_b32 m0, s64
	ds_read_b128 v[190:193], v208 offset:49152
	ds_read_b128 v[194:197], v208 offset:50176
	ds_read_b128 v[198:201], v208 offset:51200
	ds_read_b128 v[212:215], v208 offset:52224
	ds_read_b128 v[216:219], v208 offset:53248
	ds_read_b128 v[220:223], v208 offset:54272
	ds_read_b128 v[224:227], v208 offset:55296
	ds_read_b128 v[228:231], v208 offset:56320
	global_load_lds_dwordx4 v[232:233], off
	s_add_i32 m0, s64, 0x2000
	s_add_u32 s62, s62, 0x40080
	v_lshl_add_u64 v[232:233], v[234:235], 0, s[42:43]
	s_addc_u32 s63, s63, 0
	s_add_i32 s64, s79, s14
	global_load_lds_dwordx4 v[232:233], off
	v_lshl_add_u64 v[232:233], s[62:63], 0, v[134:135]
	s_mov_b32 m0, s64
	s_nop 0
	global_load_lds_dwordx4 v[232:233], off
	v_lshl_add_u64 v[232:233], s[62:63], 0, v[138:139]
	s_add_i32 m0, s64, 0x2000
	s_nop 0
	global_load_lds_dwordx4 v[232:233], off
	s_waitcnt vmcnt(6)
	s_waitcnt lgkmcnt(0)
	s_barrier
	s_setprio 1
	s_waitcnt lgkmcnt(0)
	v_mfma_f32_16x16x32_bf16 v[92:95], v[128:131], v[190:193], v[92:95]
	v_mfma_f32_16x16x32_bf16 v[88:91], v[164:167], v[190:193], v[88:91]
	v_mfma_f32_16x16x32_bf16 v[84:87], v[128:131], v[198:201], v[84:87]
	v_mfma_f32_16x16x32_bf16 v[80:83], v[164:167], v[198:201], v[80:83]
	v_mfma_f32_16x16x32_bf16 v[76:79], v[128:131], v[216:219], v[76:79]
	v_mfma_f32_16x16x32_bf16 v[72:75], v[164:167], v[216:219], v[72:75]
	v_mfma_f32_16x16x32_bf16 v[68:71], v[128:131], v[224:227], v[68:71]
	v_mfma_f32_16x16x32_bf16 v[64:67], v[164:167], v[224:227], v[64:67]
	v_mfma_f32_16x16x32_bf16 v[92:95], v[160:163], v[194:197], v[92:95]
	v_mfma_f32_16x16x32_bf16 v[88:91], v[168:171], v[194:197], v[88:91]
	v_mfma_f32_16x16x32_bf16 v[84:87], v[160:163], v[212:215], v[84:87]
	v_mfma_f32_16x16x32_bf16 v[80:83], v[168:171], v[212:215], v[80:83]
	v_mfma_f32_16x16x32_bf16 v[76:79], v[160:163], v[220:223], v[76:79]
	v_mfma_f32_16x16x32_bf16 v[72:75], v[168:171], v[220:223], v[72:75]
	v_mfma_f32_16x16x32_bf16 v[68:71], v[160:163], v[228:231], v[68:71]
	v_lshl_add_u64 v[232:233], v[236:237], 0, s[42:43]
	s_mov_b32 m0, s67
	s_nop 0
	global_load_lds_dwordx4 v[232:233], off
	v_mfma_f32_16x16x32_bf16 v[64:67], v[168:171], v[228:231], v[64:67]
	s_setprio 0
	s_setprio 1
	v_mfma_f32_16x16x32_bf16 v[28:31], v[172:175], v[190:193], v[28:31]
	v_mfma_f32_16x16x32_bf16 v[24:27], v[182:185], v[190:193], v[24:27]
	v_mfma_f32_16x16x32_bf16 v[20:23], v[172:175], v[198:201], v[20:23]
	v_mfma_f32_16x16x32_bf16 v[16:19], v[182:185], v[198:201], v[16:19]
	v_mfma_f32_16x16x32_bf16 v[12:15], v[172:175], v[216:219], v[12:15]
	v_mfma_f32_16x16x32_bf16 v[8:11], v[182:185], v[216:219], v[8:11]
	v_mfma_f32_16x16x32_bf16 v[4:7], v[172:175], v[224:227], v[4:7]
	v_mfma_f32_16x16x32_bf16 v[0:3], v[182:185], v[224:227], v[0:3]
	v_mfma_f32_16x16x32_bf16 v[28:31], v[176:179], v[194:197], v[28:31]
	v_mfma_f32_16x16x32_bf16 v[24:27], v[186:189], v[194:197], v[24:27]
	v_mfma_f32_16x16x32_bf16 v[20:23], v[176:179], v[212:215], v[20:23]
	v_mfma_f32_16x16x32_bf16 v[16:19], v[186:189], v[212:215], v[16:19]
	v_mfma_f32_16x16x32_bf16 v[12:15], v[176:179], v[220:223], v[12:15]
	v_mfma_f32_16x16x32_bf16 v[8:11], v[186:189], v[220:223], v[8:11]
	v_mfma_f32_16x16x32_bf16 v[4:7], v[176:179], v[228:231], v[4:7]
	v_lshl_add_u64 v[232:233], v[238:239], 0, s[42:43]
	s_mov_b32 m0, s74
	s_nop 0
	global_load_lds_dwordx4 v[232:233], off
	v_mfma_f32_16x16x32_bf16 v[0:3], v[186:189], v[228:231], v[0:3]
	s_setprio 0
	s_barrier
	s_add_i32 s90, s90, 2
	s_add_u32 s58, s58, 0x100
	s_addc_u32 s59, s59, 0
	s_add_u32 s88, s88, 0x100
	s_addc_u32 s89, s89, 0
	s_cmp_gt_u32 s90, 13
	s_cbranch_scc0 .LBB0_1287
	s_and_b64 vcc, exec, s[44:45]
	s_cbranch_vccz .LBB0_1290
	s_barrier

; #define PG8_STAGE(bufoff, gbase, voff) do { _Pragma("unroll") for (int _i = 0; _i < 2; ++_i) \
;         __builtin_amdgcn_global_load_lds((const unsigned*)((const char*)(gbase) + (voff)[_i]), (PG8_LAS unsigned*)(lds + (bufoff) + ldsw + _i * 8192), 16, 0, 0); } while (0)
; #define PG8_LDA(dst, b, h) do { _Pragma("unroll") for (int m = 0; m < 4; ++m) _Pragma("unroll") for (int k = 0; k < 2; ++k) dst[m][k] = *(const PG8_LAS bf16x8*)(lds + PG8_SA(b, h) + aoff + m * 2048 + k * 1024); } while (0)
; #define PG8_LDB(dst, b, h) do { _Pragma("unroll") for (int n = 0; n < 2; ++n) _Pragma("unroll") for (int k = 0; k < 2; ++k) dst[n][k] = *(const PG8_LAS bf16x8*)(lds + PG8_SB(b, h) + boff + n * 2048 + k * 1024); } while (0)
; #define PG8_MMA(ai, bj, At, Bt) do { __builtin_amdgcn_s_setprio(1); _Pragma("unroll") for (int m = 0; m < 4; ++m) _Pragma("unroll") for (int n = 0; n < 2; ++n) _Pragma("unroll") for (int k = 0; k < 2; ++k) \
;         acc[ai][bj][m][n] = __builtin_amdgcn_mfma_f32_16x16x32_bf16(Bt[n][k], At[m][k], acc[ai][bj][m][n], 0, 0, 0); __builtin_amdgcn_s_setprio(0); } while (0)
; #define PG8_BAR __builtin_amdgcn_s_barrier()
; template <class Epi, class Sched, bool ALIGN_EPI = false, bool SP2 = false>
; __device__ __forceinline__ void gemm_phase(PG8_LAS unsigned char* lds, const Gemm g, const Sched& S, const Epi& E) {
;     ...
;         const bool has_next = S.next(ui + 1, nxt);
;         const char* nA = has_next ? (const char*)g.A + (size_t)nxt.pm * tstep : cA; const char* nB = has_next ? (const char*)g.Bt + (size_t)nxt.pn * tstep : cB;
;         for (int t = 0; t < nt; t += 2) {
;             const bool last = (t == nt - 2);
;             const char* a1 = cA + (size_t)(t + 1) * kstep;
;             const char* a2 = last ? nA : cA + (size_t)(t + 2) * kstep; const char* b2 = last ? nB : cB + (size_t)(t + 2) * kstep;
;             const char* a3 = a2 + kstep; const char* b3 = b2 + kstep;
;             if (last && has_next) S.a_ready(nxt);
;             if constexpr (SP2) {
;             PG8_LDB(B0, 0, 0); PG8_LDB(B1, 0, 1); PG8_SCHED; PG8_LDA(At, 0, 0); PG8_STAGE(PG8_SA(1, 1), a1 + hstep, voffA);
;             PG8_WAIT_V(8); PG8_WAIT_L(0); PG8_BAR; PG8_MMA(0, 0, At, B0); PG8_MMA(0, 1, At, B1); PG8_BAR; PG8_SCHED;
;             PG8_LDA(At, 0, 1); PG8_STAGE(PG8_SB(0, 0), b2, voffB); PG8_STAGE(PG8_SB(0, 1), b2 + hstep, voffB); PG8_STAGE(PG8_SA(0, 0), a2, voffA);
.LBB0_1592:
	s_ashr_i32 s39, s38, 31
	s_lshl_b64 s[42:43], s[38:39], 19
	s_add_u32 s42, s40, s42
	s_addc_u32 s43, s41, s43
	s_and_b64 s[44:45], s[10:11], exec
	s_cselect_b32 s39, s43, s51
	s_cselect_b32 s47, s42, s50
	s_ashr_i32 s37, s36, 31
	s_lshl_b64 s[44:45], s[36:37], 19
	v_readlane_b32 s54, v250, 11
	v_readlane_b32 s55, v250, 12
	s_add_u32 s44, s54, s44
	s_addc_u32 s45, s55, s45
	s_and_b64 s[54:55], s[10:11], exec
	s_cselect_b32 s37, s45, s53
	s_cselect_b32 s64, s44, s52
	s_add_u32 s50, s50, 0x40080
	s_addc_u32 s51, s51, 0
	s_add_u32 s65, s52, 0x100
	s_addc_u32 s66, s53, 0
	s_mov_b32 s67, -2
	s_waitcnt lgkmcnt(0)
	ds_read_b128 v[146:149], v152
	ds_read_b128 v[156:159], v152 offset:1024
	ds_read_b128 v[160:163], v152 offset:2048
	ds_read_b128 v[164:167], v152 offset:3072
	ds_read_b128 v[168:171], v153
	ds_read_b128 v[172:175], v153 offset:1024
	ds_read_b128 v[180:183], v153 offset:2048
	ds_read_b128 v[184:187], v153 offset:3072
	s_add_u32 s52, s50, 0xfffc0080
	s_addc_u32 s53, s51, -1
	s_cmp_eq_u32 s67, 12
	s_cselect_b32 s55, s39, s53
	s_cselect_b32 s54, s47, s52
	s_cselect_b32 s53, s37, s66
	s_cselect_b32 s52, s64, s65
	v_lshl_add_u64 v[200:201], s[50:51], 0, v[136:137]
	s_add_i32 m0, s33, 0xc000
	ds_read_b128 v[188:191], v154
	ds_read_b128 v[192:195], v154 offset:1024
	ds_read_b128 v[196:199], v154 offset:2048
	ds_read_b128 v[206:209], v154 offset:3072
	ds_read_b128 v[210:213], v154 offset:4096
	ds_read_b128 v[214:217], v154 offset:5120
	ds_read_b128 v[218:221], v154 offset:6144
	ds_read_b128 v[222:225], v154 offset:7168
	global_load_lds_dwordx4 v[200:201], off
	v_lshl_add_u64 v[200:201], s[50:51], 0, v[138:139]
	s_add_i32 m0, s33, 0xe000
	s_nop 0
	global_load_lds_dwordx4 v[200:201], off
	s_waitcnt vmcnt(8)
	s_waitcnt lgkmcnt(0)
	s_barrier
	s_setprio 1
	s_waitcnt lgkmcnt(0)
	v_mfma_f32_16x16x32_bf16 v[124:127], v[146:149], v[188:191], 0
	v_mfma_f32_16x16x32_bf16 v[120:123], v[160:163], v[188:191], 0
	v_mfma_f32_16x16x32_bf16 v[108:111], v[146:149], v[196:199], 0
	v_mfma_f32_16x16x32_bf16 v[104:107], v[160:163], v[196:199], 0
	v_mfma_f32_16x16x32_bf16 v[92:95], v[146:149], v[210:213], 0
	v_mfma_f32_16x16x32_bf16 v[88:91], v[160:163], v[210:213], 0
	v_mfma_f32_16x16x32_bf16 v[76:79], v[146:149], v[218:221], 0
	v_mfma_f32_16x16x32_bf16 v[72:75], v[160:163], v[218:221], 0
	v_mfma_f32_16x16x32_bf16 v[124:127], v[156:159], v[192:195], v[124:127]
	v_mfma_f32_16x16x32_bf16 v[120:123], v[164:167], v[192:195], v[120:123]
	v_mfma_f32_16x16x32_bf16 v[108:111], v[156:159], v[206:209], v[108:111]
	v_mfma_f32_16x16x32_bf16 v[104:107], v[164:167], v[206:209], v[104:107]
	v_mfma_f32_16x16x32_bf16 v[92:95], v[156:159], v[214:217], v[92:95]
	v_mfma_f32_16x16x32_bf16 v[88:91], v[164:167], v[214:217], v[88:91]
	v_mfma_f32_16x16x32_bf16 v[76:79], v[156:159], v[222:225], v[76:79]
	v_mfma_f32_16x16x32_bf16 v[72:75], v[164:167], v[222:225], v[72:75]
	s_setprio 0
	s_setprio 1
	v_mfma_f32_16x16x32_bf16 v[116:119], v[168:171], v[188:191], 0
	v_mfma_f32_16x16x32_bf16 v[112:115], v[180:183], v[188:191], 0
	v_mfma_f32_16x16x32_bf16 v[100:103], v[168:171], v[196:199], 0
	v_mfma_f32_16x16x32_bf16 v[96:99], v[180:183], v[196:199], 0
	v_mfma_f32_16x16x32_bf16 v[84:87], v[168:171], v[210:213], 0
	v_mfma_f32_16x16x32_bf16 v[80:83], v[180:183], v[210:213], 0
	v_mfma_f32_16x16x32_bf16 v[68:71], v[168:171], v[218:221], 0
	v_mfma_f32_16x16x32_bf16 v[64:67], v[180:183], v[218:221], 0
	v_mfma_f32_16x16x32_bf16 v[116:119], v[172:175], v[192:195], v[116:119]
	v_mfma_f32_16x16x32_bf16 v[112:115], v[184:187], v[192:195], v[112:115]
	v_mfma_f32_16x16x32_bf16 v[100:103], v[172:175], v[206:209], v[100:103]
	v_mfma_f32_16x16x32_bf16 v[96:99], v[184:187], v[206:209], v[96:99]
	v_mfma_f32_16x16x32_bf16 v[84:87], v[172:175], v[214:217], v[84:87]
	v_mfma_f32_16x16x32_bf16 v[80:83], v[184:187], v[214:217], v[80:83]
	v_mfma_f32_16x16x32_bf16 v[68:71], v[172:175], v[222:225], v[68:71]
	v_mfma_f32_16x16x32_bf16 v[64:67], v[184:187], v[222:225], v[64:67]
	s_setprio 0
	s_barrier
	s_add_i32 s74, s60, s15
	v_lshl_add_u64 v[200:201], s[52:53], 0, v[130:131]
	s_mov_b32 m0, s74
	ds_read_b128 v[188:191], v154 offset:16384
	ds_read_b128 v[192:195], v154 offset:17408
	ds_read_b128 v[196:199], v154 offset:18432
	ds_read_b128 v[206:209], v154 offset:19456
	ds_read_b128 v[210:213], v154 offset:20480
	ds_read_b128 v[214:217], v154 offset:21504
	ds_read_b128 v[218:221], v154 offset:22528
	ds_read_b128 v[222:225], v154 offset:23552
	global_load_lds_dwordx4 v[200:201], off
	s_add_i32 m0, s74, 0x2000
	s_add_u32 s74, s52, 0x40000
	v_lshl_add_u64 v[226:227], s[52:53], 0, v[134:135]
	s_addc_u32 s75, s53, 0
	s_add_i32 s76, s61, s15
	global_load_lds_dwordx4 v[226:227], off
	v_lshl_add_u64 v[228:229], s[74:75], 0, v[130:131]
	s_mov_b32 m0, s76
	global_load_lds_dwordx4 v[228:229], off
	v_lshl_add_u64 v[228:229], s[74:75], 0, v[134:135]
	s_add_i32 m0, s76, 0x2000
	s_nop 0
	global_load_lds_dwordx4 v[228:229], off
	s_waitcnt vmcnt(6)
	s_waitcnt lgkmcnt(0)
	s_barrier
; #define PG8_STAGE(bufoff, gbase, voff) do { _Pragma("unroll") for (int _i = 0; _i < 2; ++_i) \
;         __builtin_amdgcn_global_load_lds((const unsigned*)((const char*)(gbase) + (voff)[_i]), (PG8_LAS unsigned*)(lds + (bufoff) + ldsw + _i * 8192), 16, 0, 0); } while (0)
; #define PG8_LDA(dst, b, h) do { _Pragma("unroll") for (int m = 0; m < 4; ++m) _Pragma("unroll") for (int k = 0; k < 2; ++k) dst[m][k] = *(const PG8_LAS bf16x8*)(lds + PG8_SA(b, h) + aoff + m * 2048 + k * 1024); } while (0)
; #define PG8_LDB(dst, b, h) do { _Pragma("unroll") for (int n = 0; n < 2; ++n) _Pragma("unroll") for (int k = 0; k < 2; ++k) dst[n][k] = *(const PG8_LAS bf16x8*)(lds + PG8_SB(b, h) + boff + n * 2048 + k * 1024); } while (0)
; #define PG8_MMA(ai, bj, At, Bt) do { __builtin_amdgcn_s_setprio(1); _Pragma("unroll") for (int m = 0; m < 4; ++m) _Pragma("unroll") for (int n = 0; n < 2; ++n) _Pragma("unroll") for (int k = 0; k < 2; ++k) \
;         acc[ai][bj][m][n] = __builtin_amdgcn_mfma_f32_16x16x32_bf16(Bt[n][k], At[m][k], acc[ai][bj][m][n], 0, 0, 0); __builtin_amdgcn_s_setprio(0); } while (0)
; #define PG8_WAIT_V(n) asm volatile("s_waitcnt vmcnt(" #n ")" ::: "memory")
; #define PG8_WAIT_L(n) asm volatile("s_waitcnt lgkmcnt(" #n ")" ::: "memory")
; #define PG8_BAR __builtin_amdgcn_s_barrier()
; #define PG8_SCHED __builtin_amdgcn_sched_barrier(0)
; template <class Epi, class Sched, bool ALIGN_EPI = false, bool SP2 = false>
; __device__ __forceinline__ void gemm_phase(PG8_LAS unsigned char* lds, const Gemm g, const Sched& S, const Epi& E) {
;     ...
;             PG8_WAIT_V(8); PG8_WAIT_L(0); PG8_BAR; PG8_MMA(0, 0, At, B0); PG8_MMA(0, 1, At, B1); PG8_BAR; PG8_SCHED;
;             PG8_LDA(At, 0, 1); PG8_STAGE(PG8_SB(0, 0), b2, voffB); PG8_STAGE(PG8_SB(0, 1), b2 + hstep, voffB); PG8_STAGE(PG8_SA(0, 0), a2, voffA);
;             PG8_WAIT_V(8); PG8_WAIT_L(0); PG8_BAR; PG8_MMA(1, 0, At, B0); PG8_MMA(1, 1, At, B1); PG8_BAR; PG8_SCHED;
;             PG8_LDB(B0, 1, 0); PG8_LDB(B1, 1, 1); PG8_SCHED; PG8_LDA(At, 1, 0); PG8_STAGE(PG8_SA(0, 1), a2 + hstep, voffA);
;             PG8_WAIT_V(8); PG8_WAIT_L(0); PG8_BAR; PG8_MMA(0, 0, At, B0); PG8_MMA(0, 1, At, B1); PG8_BAR; PG8_SCHED;
	s_setprio 1
	s_waitcnt lgkmcnt(0)
	v_mfma_f32_16x16x32_bf16 v[60:63], v[146:149], v[188:191], 0
	v_mfma_f32_16x16x32_bf16 v[56:59], v[160:163], v[188:191], 0
	v_mfma_f32_16x16x32_bf16 v[44:47], v[146:149], v[196:199], 0
	v_mfma_f32_16x16x32_bf16 v[40:43], v[160:163], v[196:199], 0
	v_mfma_f32_16x16x32_bf16 v[28:31], v[146:149], v[210:213], 0
	v_mfma_f32_16x16x32_bf16 v[24:27], v[160:163], v[210:213], 0
	v_mfma_f32_16x16x32_bf16 v[12:15], v[146:149], v[218:221], 0
	v_mfma_f32_16x16x32_bf16 v[8:11], v[160:163], v[218:221], 0
	v_mfma_f32_16x16x32_bf16 v[60:63], v[156:159], v[192:195], v[60:63]
	v_mfma_f32_16x16x32_bf16 v[56:59], v[164:167], v[192:195], v[56:59]
	v_mfma_f32_16x16x32_bf16 v[44:47], v[156:159], v[206:209], v[44:47]
	v_mfma_f32_16x16x32_bf16 v[40:43], v[164:167], v[206:209], v[40:43]
	v_mfma_f32_16x16x32_bf16 v[28:31], v[156:159], v[214:217], v[28:31]
	v_mfma_f32_16x16x32_bf16 v[24:27], v[164:167], v[214:217], v[24:27]
	v_mfma_f32_16x16x32_bf16 v[12:15], v[156:159], v[222:225], v[12:15]
	v_lshl_add_u64 v[228:229], s[54:55], 0, v[128:129]
	s_mov_b32 m0, s33
	s_nop 0
	global_load_lds_dwordx4 v[228:229], off
	v_mfma_f32_16x16x32_bf16 v[8:11], v[164:167], v[222:225], v[8:11]
	s_setprio 0
	s_setprio 1
	v_mfma_f32_16x16x32_bf16 v[52:55], v[168:171], v[188:191], 0
	v_mfma_f32_16x16x32_bf16 v[48:51], v[180:183], v[188:191], 0
	v_mfma_f32_16x16x32_bf16 v[36:39], v[168:171], v[196:199], 0
	v_mfma_f32_16x16x32_bf16 v[32:35], v[180:183], v[196:199], 0
	v_mfma_f32_16x16x32_bf16 v[20:23], v[168:171], v[210:213], 0
	v_mfma_f32_16x16x32_bf16 v[16:19], v[180:183], v[210:213], 0
	v_mfma_f32_16x16x32_bf16 v[4:7], v[168:171], v[218:221], 0
	v_mfma_f32_16x16x32_bf16 v[0:3], v[180:183], v[218:221], 0
	v_mfma_f32_16x16x32_bf16 v[52:55], v[172:175], v[192:195], v[52:55]
	v_mfma_f32_16x16x32_bf16 v[48:51], v[184:187], v[192:195], v[48:51]
	v_mfma_f32_16x16x32_bf16 v[36:39], v[172:175], v[206:209], v[36:39]
	v_mfma_f32_16x16x32_bf16 v[32:35], v[184:187], v[206:209], v[32:35]
	v_mfma_f32_16x16x32_bf16 v[20:23], v[172:175], v[214:217], v[20:23]
	v_mfma_f32_16x16x32_bf16 v[16:19], v[184:187], v[214:217], v[16:19]
	v_mfma_f32_16x16x32_bf16 v[4:7], v[172:175], v[222:225], v[4:7]
	v_lshl_add_u64 v[230:231], s[54:55], 0, v[132:133]
	s_mov_b32 m0, s34
	s_nop 0
	global_load_lds_dwordx4 v[230:231], off
	v_mfma_f32_16x16x32_bf16 v[0:3], v[184:187], v[222:225], v[0:3]
	s_setprio 0
	s_barrier
	s_add_i32 s74, 0, 0x18000
	s_add_i32 s75, 0, 0x1c000
	v_add_u32_e32 v164, s74, v150
	v_add_u32_e32 v179, s75, v150
	ds_read_b128 v[146:149], v164
	ds_read_b128 v[156:159], v164 offset:1024
	ds_read_b128 v[160:163], v164 offset:2048
	ds_read_b128 v[164:167], v164 offset:3072
	ds_read_b128 v[168:171], v179
	ds_read_b128 v[172:175], v179 offset:1024
	ds_read_b128 v[180:183], v179 offset:2048
	ds_read_b128 v[184:187], v179 offset:3072
	s_add_u32 s54, s54, 0x40000
	s_addc_u32 s55, s55, 0
	s_mov_b32 m0, s49
	v_lshl_add_u64 v[232:233], s[54:55], 0, v[128:129]
	ds_read_b128 v[188:191], v154 offset:32768
	ds_read_b128 v[192:195], v154 offset:33792
	ds_read_b128 v[196:199], v154 offset:34816
	ds_read_b128 v[206:209], v154 offset:35840
	ds_read_b128 v[210:213], v154 offset:36864
	ds_read_b128 v[214:217], v154 offset:37888
	ds_read_b128 v[218:221], v154 offset:38912
	ds_read_b128 v[222:225], v154 offset:39936
	global_load_lds_dwordx4 v[232:233], off
	v_lshl_add_u64 v[232:233], s[54:55], 0, v[132:133]
	s_mov_b32 m0, s56
	s_nop 0
	global_load_lds_dwordx4 v[232:233], off
	s_waitcnt vmcnt(8)
	s_waitcnt lgkmcnt(0)
	s_barrier
	s_setprio 1
	s_waitcnt lgkmcnt(0)
	v_mfma_f32_16x16x32_bf16 v[124:127], v[146:149], v[188:191], v[124:127]
	v_mfma_f32_16x16x32_bf16 v[120:123], v[160:163], v[188:191], v[120:123]
	v_mfma_f32_16x16x32_bf16 v[108:111], v[146:149], v[196:199], v[108:111]
	v_mfma_f32_16x16x32_bf16 v[104:107], v[160:163], v[196:199], v[104:107]
	v_mfma_f32_16x16x32_bf16 v[92:95], v[146:149], v[210:213], v[92:95]
	v_mfma_f32_16x16x32_bf16 v[88:91], v[160:163], v[210:213], v[88:91]
	v_mfma_f32_16x16x32_bf16 v[76:79], v[146:149], v[218:221], v[76:79]
	v_mfma_f32_16x16x32_bf16 v[72:75], v[160:163], v[218:221], v[72:75]
	v_mfma_f32_16x16x32_bf16 v[124:127], v[156:159], v[192:195], v[124:127]
	v_mfma_f32_16x16x32_bf16 v[120:123], v[164:167], v[192:195], v[120:123]
	v_mfma_f32_16x16x32_bf16 v[108:111], v[156:159], v[206:209], v[108:111]
	v_mfma_f32_16x16x32_bf16 v[104:107], v[164:167], v[206:209], v[104:107]
	v_mfma_f32_16x16x32_bf16 v[92:95], v[156:159], v[214:217], v[92:95]
	v_mfma_f32_16x16x32_bf16 v[88:91], v[164:167], v[214:217], v[88:91]
	v_mfma_f32_16x16x32_bf16 v[76:79], v[156:159], v[222:225], v[76:79]
	v_mfma_f32_16x16x32_bf16 v[72:75], v[164:167], v[222:225], v[72:75]
	s_setprio 0
	s_setprio 1
	v_mfma_f32_16x16x32_bf16 v[116:119], v[168:171], v[188:191], v[116:119]
	v_mfma_f32_16x16x32_bf16 v[112:115], v[180:183], v[188:191], v[112:115]
	v_mfma_f32_16x16x32_bf16 v[100:103], v[168:171], v[196:199], v[100:103]
	v_mfma_f32_16x16x32_bf16 v[96:99], v[180:183], v[196:199], v[96:99]
	v_mfma_f32_16x16x32_bf16 v[84:87], v[168:171], v[210:213], v[84:87]
	v_mfma_f32_16x16x32_bf16 v[80:83], v[180:183], v[210:213], v[80:83]
	v_mfma_f32_16x16x32_bf16 v[68:71], v[168:171], v[218:221], v[68:71]
	v_mfma_f32_16x16x32_bf16 v[64:67], v[180:183], v[218:221], v[64:67]
	v_mfma_f32_16x16x32_bf16 v[116:119], v[172:175], v[192:195], v[116:119]
	v_mfma_f32_16x16x32_bf16 v[112:115], v[184:187], v[192:195], v[112:115]
	v_mfma_f32_16x16x32_bf16 v[100:103], v[172:175], v[206:209], v[100:103]
	v_mfma_f32_16x16x32_bf16 v[96:99], v[184:187], v[206:209], v[96:99]
	v_mfma_f32_16x16x32_bf16 v[84:87], v[172:175], v[214:217], v[84:87]
	v_mfma_f32_16x16x32_bf16 v[80:83], v[184:187], v[214:217], v[80:83]
	v_mfma_f32_16x16x32_bf16 v[68:71], v[172:175], v[222:225], v[68:71]
	v_mfma_f32_16x16x32_bf16 v[64:67], v[184:187], v[222:225], v[64:67]
	s_setprio 0
	s_barrier
; #define PG8_STAGE(bufoff, gbase, voff) do { _Pragma("unroll") for (int _i = 0; _i < 2; ++_i) \
;         __builtin_amdgcn_global_load_lds((const unsigned*)((const char*)(gbase) + (voff)[_i]), (PG8_LAS unsigned*)(lds + (bufoff) + ldsw + _i * 8192), 16, 0, 0); } while (0)
; #define PG8_LDA(dst, b, h) do { _Pragma("unroll") for (int m = 0; m < 4; ++m) _Pragma("unroll") for (int k = 0; k < 2; ++k) dst[m][k] = *(const PG8_LAS bf16x8*)(lds + PG8_SA(b, h) + aoff + m * 2048 + k * 1024); } while (0)
; #define PG8_LDB(dst, b, h) do { _Pragma("unroll") for (int n = 0; n < 2; ++n) _Pragma("unroll") for (int k = 0; k < 2; ++k) dst[n][k] = *(const PG8_LAS bf16x8*)(lds + PG8_SB(b, h) + boff + n * 2048 + k * 1024); } while (0)
; #define PG8_MMA(ai, bj, At, Bt) do { __builtin_amdgcn_s_setprio(1); _Pragma("unroll") for (int m = 0; m < 4; ++m) _Pragma("unroll") for (int n = 0; n < 2; ++n) _Pragma("unroll") for (int k = 0; k < 2; ++k) \
;         acc[ai][bj][m][n] = __builtin_amdgcn_mfma_f32_16x16x32_bf16(Bt[n][k], At[m][k], acc[ai][bj][m][n], 0, 0, 0); __builtin_amdgcn_s_setprio(0); } while (0)
; #define PG8_WAIT_V(n) asm volatile("s_waitcnt vmcnt(" #n ")" ::: "memory")
; template <class Epi, class Sched, bool ALIGN_EPI = false, bool SP2 = false>
; __device__ __forceinline__ void gemm_phase(PG8_LAS unsigned char* lds, const Gemm g, const Sched& S, const Epi& E) {
;     ...
;             PG8_LDB(B0, 0, 0); PG8_LDB(B1, 0, 1); PG8_SCHED; PG8_LDA(At, 0, 0); PG8_STAGE(PG8_SA(1, 1), a1 + hstep, voffA);
;             PG8_WAIT_V(8); PG8_WAIT_L(0); PG8_BAR; PG8_MMA(0, 0, At, B0); PG8_MMA(0, 1, At, B1); PG8_BAR; PG8_SCHED;
;             PG8_LDA(At, 0, 1); PG8_STAGE(PG8_SB(0, 0), b2, voffB); PG8_STAGE(PG8_SB(0, 1), b2 + hstep, voffB); PG8_STAGE(PG8_SA(0, 0), a2, voffA);
;             PG8_WAIT_V(8); PG8_WAIT_L(0); PG8_BAR; PG8_MMA(1, 0, At, B0); PG8_MMA(1, 1, At, B1); PG8_BAR; PG8_SCHED;
;             PG8_LDB(B0, 1, 0); PG8_LDB(B1, 1, 1); PG8_SCHED; PG8_LDA(At, 1, 0); PG8_STAGE(PG8_SA(0, 1), a2 + hstep, voffA);
;             PG8_WAIT_V(8); PG8_WAIT_L(0); PG8_BAR; PG8_MMA(0, 0, At, B0); PG8_MMA(0, 1, At, B1); PG8_BAR; PG8_SCHED;
;             PG8_LDA(At, 1, 1); PG8_STAGE(PG8_SB(1, 0), b3, voffB); PG8_STAGE(PG8_SB(1, 1), b3 + hstep, voffB); PG8_STAGE(PG8_SA(1, 0), a3, voffA);
;             PG8_WAIT_V(8); PG8_WAIT_L(0); PG8_BAR; PG8_MMA(1, 0, At, B0); PG8_MMA(1, 1, At, B1); PG8_BAR; PG8_SCHED;
	s_add_i32 s54, s74, s15
	v_lshl_add_u64 v[200:201], v[200:201], 0, s[26:27]
	s_mov_b32 m0, s54
	ds_read_b128 v[188:191], v154 offset:49152
	ds_read_b128 v[192:195], v154 offset:50176
	ds_read_b128 v[196:199], v154 offset:51200
	ds_read_b128 v[206:209], v154 offset:52224
	ds_read_b128 v[210:213], v154 offset:53248
	ds_read_b128 v[214:217], v154 offset:54272
	ds_read_b128 v[218:221], v154 offset:55296
	ds_read_b128 v[222:225], v154 offset:56320
	global_load_lds_dwordx4 v[200:201], off
	s_add_i32 m0, s54, 0x2000
	s_add_u32 s52, s52, 0x40080
	v_lshl_add_u64 v[200:201], v[226:227], 0, s[26:27]
	s_addc_u32 s53, s53, 0
	s_add_i32 s54, s75, s15
	global_load_lds_dwordx4 v[200:201], off
	v_lshl_add_u64 v[200:201], s[52:53], 0, v[130:131]
	s_mov_b32 m0, s54
	s_nop 0
	global_load_lds_dwordx4 v[200:201], off
	v_lshl_add_u64 v[200:201], s[52:53], 0, v[134:135]
	s_add_i32 m0, s54, 0x2000
	s_nop 0
	global_load_lds_dwordx4 v[200:201], off
	s_waitcnt vmcnt(6)
	s_waitcnt lgkmcnt(0)
	s_barrier
	s_setprio 1
	s_waitcnt lgkmcnt(0)
	v_mfma_f32_16x16x32_bf16 v[60:63], v[146:149], v[188:191], v[60:63]
	v_mfma_f32_16x16x32_bf16 v[56:59], v[160:163], v[188:191], v[56:59]
	v_mfma_f32_16x16x32_bf16 v[44:47], v[146:149], v[196:199], v[44:47]
	v_mfma_f32_16x16x32_bf16 v[40:43], v[160:163], v[196:199], v[40:43]
	v_mfma_f32_16x16x32_bf16 v[28:31], v[146:149], v[210:213], v[28:31]
	v_mfma_f32_16x16x32_bf16 v[24:27], v[160:163], v[210:213], v[24:27]
	v_mfma_f32_16x16x32_bf16 v[12:15], v[146:149], v[218:221], v[12:15]
	v_mfma_f32_16x16x32_bf16 v[8:11], v[160:163], v[218:221], v[8:11]
	v_mfma_f32_16x16x32_bf16 v[60:63], v[156:159], v[192:195], v[60:63]
	v_mfma_f32_16x16x32_bf16 v[56:59], v[164:167], v[192:195], v[56:59]
	v_mfma_f32_16x16x32_bf16 v[44:47], v[156:159], v[206:209], v[44:47]
	v_mfma_f32_16x16x32_bf16 v[40:43], v[164:167], v[206:209], v[40:43]
	v_mfma_f32_16x16x32_bf16 v[28:31], v[156:159], v[214:217], v[28:31]
	v_mfma_f32_16x16x32_bf16 v[24:27], v[164:167], v[214:217], v[24:27]
	v_mfma_f32_16x16x32_bf16 v[12:15], v[156:159], v[222:225], v[12:15]
	v_lshl_add_u64 v[200:201], v[228:229], 0, s[26:27]
	s_mov_b32 m0, s58
	s_nop 0
	global_load_lds_dwordx4 v[200:201], off
	v_mfma_f32_16x16x32_bf16 v[8:11], v[164:167], v[222:225], v[8:11]
	s_setprio 0
	s_setprio 1
	v_mfma_f32_16x16x32_bf16 v[52:55], v[168:171], v[188:191], v[52:55]
	v_mfma_f32_16x16x32_bf16 v[48:51], v[180:183], v[188:191], v[48:51]
	v_mfma_f32_16x16x32_bf16 v[36:39], v[168:171], v[196:199], v[36:39]
	v_mfma_f32_16x16x32_bf16 v[32:35], v[180:183], v[196:199], v[32:35]
	v_mfma_f32_16x16x32_bf16 v[20:23], v[168:171], v[210:213], v[20:23]
	v_mfma_f32_16x16x32_bf16 v[16:19], v[180:183], v[210:213], v[16:19]
	v_mfma_f32_16x16x32_bf16 v[4:7], v[168:171], v[218:221], v[4:7]
	v_mfma_f32_16x16x32_bf16 v[0:3], v[180:183], v[218:221], v[0:3]
	v_mfma_f32_16x16x32_bf16 v[52:55], v[172:175], v[192:195], v[52:55]
	v_mfma_f32_16x16x32_bf16 v[48:51], v[184:187], v[192:195], v[48:51]
	v_mfma_f32_16x16x32_bf16 v[36:39], v[172:175], v[206:209], v[36:39]
	v_mfma_f32_16x16x32_bf16 v[32:35], v[184:187], v[206:209], v[32:35]
	v_mfma_f32_16x16x32_bf16 v[20:23], v[172:175], v[214:217], v[20:23]
	v_mfma_f32_16x16x32_bf16 v[16:19], v[184:187], v[214:217], v[16:19]
	v_mfma_f32_16x16x32_bf16 v[4:7], v[172:175], v[222:225], v[4:7]
	v_lshl_add_u64 v[200:201], v[230:231], 0, s[26:27]
	s_mov_b32 m0, s59
	s_nop 0
	global_load_lds_dwordx4 v[200:201], off
	v_mfma_f32_16x16x32_bf16 v[0:3], v[184:187], v[222:225], v[0:3]
	s_setprio 0
	s_barrier
	s_add_i32 s67, s67, 2
	s_add_u32 s50, s50, 0x100
	s_addc_u32 s51, s51, 0
	s_add_u32 s65, s65, 0x100
	s_addc_u32 s66, s66, 0
.LBB0_1593:
	ds_read_b128 v[146:149], v152
	ds_read_b128 v[156:159], v152 offset:1024
	ds_read_b128 v[160:163], v152 offset:2048
	ds_read_b128 v[164:167], v152 offset:3072
	ds_read_b128 v[168:171], v153
	ds_read_b128 v[172:175], v153 offset:1024
	ds_read_b128 v[180:183], v153 offset:2048
	ds_read_b128 v[184:187], v153 offset:3072
	s_add_u32 s52, s50, 0xfffc0080
	s_addc_u32 s53, s51, -1
	s_cmp_eq_u32 s67, 12
	s_cselect_b32 s55, s39, s53
	s_cselect_b32 s54, s47, s52
	s_cselect_b32 s53, s37, s66
	s_cselect_b32 s52, s64, s65
	v_lshl_add_u64 v[200:201], s[50:51], 0, v[136:137]
	s_add_i32 m0, s33, 0xc000
	ds_read_b128 v[188:191], v154
	ds_read_b128 v[192:195], v154 offset:1024
	ds_read_b128 v[196:199], v154 offset:2048
	ds_read_b128 v[206:209], v154 offset:3072
	ds_read_b128 v[210:213], v154 offset:4096
	ds_read_b128 v[214:217], v154 offset:5120
	ds_read_b128 v[218:221], v154 offset:6144
	ds_read_b128 v[222:225], v154 offset:7168
	global_load_lds_dwordx4 v[200:201], off
	v_lshl_add_u64 v[200:201], s[50:51], 0, v[138:139]
	s_add_i32 m0, s33, 0xe000
	s_nop 0
	global_load_lds_dwordx4 v[200:201], off
	s_waitcnt vmcnt(8)
	s_waitcnt lgkmcnt(0)
	s_barrier
; #define PG8_STAGE(bufoff, gbase, voff) do { _Pragma("unroll") for (int _i = 0; _i < 2; ++_i) \
;         __builtin_amdgcn_global_load_lds((const unsigned*)((const char*)(gbase) + (voff)[_i]), (PG8_LAS unsigned*)(lds + (bufoff) + ldsw + _i * 8192), 16, 0, 0); } while (0)
; #define PG8_LDA(dst, b, h) do { _Pragma("unroll") for (int m = 0; m < 4; ++m) _Pragma("unroll") for (int k = 0; k < 2; ++k) dst[m][k] = *(const PG8_LAS bf16x8*)(lds + PG8_SA(b, h) + aoff + m * 2048 + k * 1024); } while (0)
; #define PG8_MMA(ai, bj, At, Bt) do { __builtin_amdgcn_s_setprio(1); _Pragma("unroll") for (int m = 0; m < 4; ++m) _Pragma("unroll") for (int n = 0; n < 2; ++n) _Pragma("unroll") for (int k = 0; k < 2; ++k) \
;         acc[ai][bj][m][n] = __builtin_amdgcn_mfma_f32_16x16x32_bf16(Bt[n][k], At[m][k], acc[ai][bj][m][n], 0, 0, 0); __builtin_amdgcn_s_setprio(0); } while (0)
; #define PG8_WAIT_V(n) asm volatile("s_waitcnt vmcnt(" #n ")" ::: "memory")
; #define PG8_WAIT_L(n) asm volatile("s_waitcnt lgkmcnt(" #n ")" ::: "memory")
; #define PG8_BAR __builtin_amdgcn_s_barrier()
; #define PG8_SCHED __builtin_amdgcn_sched_barrier(0)
; template <class Epi, class Sched, bool ALIGN_EPI = false, bool SP2 = false>
; __device__ __forceinline__ void gemm_phase(PG8_LAS unsigned char* lds, const Gemm g, const Sched& S, const Epi& E) {
;     ...
;             PG8_WAIT_V(8); PG8_WAIT_L(0); PG8_BAR; PG8_MMA(0, 0, At, B0); PG8_MMA(0, 1, At, B1); PG8_BAR; PG8_SCHED;
;             PG8_LDA(At, 0, 1); PG8_STAGE(PG8_SB(0, 0), b2, voffB); PG8_STAGE(PG8_SB(0, 1), b2 + hstep, voffB); PG8_STAGE(PG8_SA(0, 0), a2, voffA);
;             PG8_WAIT_V(8); PG8_WAIT_L(0); PG8_BAR; PG8_MMA(1, 0, At, B0); PG8_MMA(1, 1, At, B1); PG8_BAR; PG8_SCHED;
	s_setprio 1
	s_waitcnt lgkmcnt(0)
	v_mfma_f32_16x16x32_bf16 v[124:127], v[146:149], v[188:191], v[124:127]
	v_mfma_f32_16x16x32_bf16 v[120:123], v[160:163], v[188:191], v[120:123]
	v_mfma_f32_16x16x32_bf16 v[108:111], v[146:149], v[196:199], v[108:111]
	v_mfma_f32_16x16x32_bf16 v[104:107], v[160:163], v[196:199], v[104:107]
	v_mfma_f32_16x16x32_bf16 v[92:95], v[146:149], v[210:213], v[92:95]
	v_mfma_f32_16x16x32_bf16 v[88:91], v[160:163], v[210:213], v[88:91]
	v_mfma_f32_16x16x32_bf16 v[76:79], v[146:149], v[218:221], v[76:79]
	v_mfma_f32_16x16x32_bf16 v[72:75], v[160:163], v[218:221], v[72:75]
	v_mfma_f32_16x16x32_bf16 v[124:127], v[156:159], v[192:195], v[124:127]
	v_mfma_f32_16x16x32_bf16 v[120:123], v[164:167], v[192:195], v[120:123]
	v_mfma_f32_16x16x32_bf16 v[108:111], v[156:159], v[206:209], v[108:111]
	v_mfma_f32_16x16x32_bf16 v[104:107], v[164:167], v[206:209], v[104:107]
	v_mfma_f32_16x16x32_bf16 v[92:95], v[156:159], v[214:217], v[92:95]
	v_mfma_f32_16x16x32_bf16 v[88:91], v[164:167], v[214:217], v[88:91]
	v_mfma_f32_16x16x32_bf16 v[76:79], v[156:159], v[222:225], v[76:79]
	v_mfma_f32_16x16x32_bf16 v[72:75], v[164:167], v[222:225], v[72:75]
	s_setprio 0
	s_setprio 1
	v_mfma_f32_16x16x32_bf16 v[116:119], v[168:171], v[188:191], v[116:119]
	v_mfma_f32_16x16x32_bf16 v[112:115], v[180:183], v[188:191], v[112:115]
	v_mfma_f32_16x16x32_bf16 v[100:103], v[168:171], v[196:199], v[100:103]
	v_mfma_f32_16x16x32_bf16 v[96:99], v[180:183], v[196:199], v[96:99]
	v_mfma_f32_16x16x32_bf16 v[84:87], v[168:171], v[210:213], v[84:87]
	v_mfma_f32_16x16x32_bf16 v[80:83], v[180:183], v[210:213], v[80:83]
	v_mfma_f32_16x16x32_bf16 v[68:71], v[168:171], v[218:221], v[68:71]
	v_mfma_f32_16x16x32_bf16 v[64:67], v[180:183], v[218:221], v[64:67]
	v_mfma_f32_16x16x32_bf16 v[116:119], v[172:175], v[192:195], v[116:119]
	v_mfma_f32_16x16x32_bf16 v[112:115], v[184:187], v[192:195], v[112:115]
	v_mfma_f32_16x16x32_bf16 v[100:103], v[172:175], v[206:209], v[100:103]
	v_mfma_f32_16x16x32_bf16 v[96:99], v[184:187], v[206:209], v[96:99]
	v_mfma_f32_16x16x32_bf16 v[84:87], v[172:175], v[214:217], v[84:87]
	v_mfma_f32_16x16x32_bf16 v[80:83], v[184:187], v[214:217], v[80:83]
	v_mfma_f32_16x16x32_bf16 v[68:71], v[172:175], v[222:225], v[68:71]
	v_mfma_f32_16x16x32_bf16 v[64:67], v[184:187], v[222:225], v[64:67]
	s_setprio 0
	s_barrier
	s_add_i32 s74, s60, s15
	v_lshl_add_u64 v[200:201], s[52:53], 0, v[130:131]
	s_mov_b32 m0, s74
	ds_read_b128 v[188:191], v154 offset:16384
	ds_read_b128 v[192:195], v154 offset:17408
	ds_read_b128 v[196:199], v154 offset:18432
	ds_read_b128 v[206:209], v154 offset:19456
	ds_read_b128 v[210:213], v154 offset:20480
	ds_read_b128 v[214:217], v154 offset:21504
	ds_read_b128 v[218:221], v154 offset:22528
	ds_read_b128 v[222:225], v154 offset:23552
	global_load_lds_dwordx4 v[200:201], off
	s_add_i32 m0, s74, 0x2000
	s_add_u32 s74, s52, 0x40000
	v_lshl_add_u64 v[226:227], s[52:53], 0, v[134:135]
	s_addc_u32 s75, s53, 0
	s_add_i32 s76, s61, s15
	global_load_lds_dwordx4 v[226:227], off
	v_lshl_add_u64 v[228:229], s[74:75], 0, v[130:131]
	s_mov_b32 m0, s76
	global_load_lds_dwordx4 v[228:229], off
	v_lshl_add_u64 v[228:229], s[74:75], 0, v[134:135]
	s_add_i32 m0, s76, 0x2000
	s_nop 0
	global_load_lds_dwordx4 v[228:229], off
	s_waitcnt vmcnt(6)
	s_waitcnt lgkmcnt(0)
	s_barrier
	s_setprio 1
	s_waitcnt lgkmcnt(0)
	v_mfma_f32_16x16x32_bf16 v[60:63], v[146:149], v[188:191], v[60:63]
	v_mfma_f32_16x16x32_bf16 v[56:59], v[160:163], v[188:191], v[56:59]
	v_mfma_f32_16x16x32_bf16 v[44:47], v[146:149], v[196:199], v[44:47]
	v_mfma_f32_16x16x32_bf16 v[40:43], v[160:163], v[196:199], v[40:43]
	v_mfma_f32_16x16x32_bf16 v[28:31], v[146:149], v[210:213], v[28:31]
	v_mfma_f32_16x16x32_bf16 v[24:27], v[160:163], v[210:213], v[24:27]
	v_mfma_f32_16x16x32_bf16 v[12:15], v[146:149], v[218:221], v[12:15]
	v_mfma_f32_16x16x32_bf16 v[8:11], v[160:163], v[218:221], v[8:11]
	v_mfma_f32_16x16x32_bf16 v[60:63], v[156:159], v[192:195], v[60:63]
	v_mfma_f32_16x16x32_bf16 v[56:59], v[164:167], v[192:195], v[56:59]
	v_mfma_f32_16x16x32_bf16 v[44:47], v[156:159], v[206:209], v[44:47]
	v_mfma_f32_16x16x32_bf16 v[40:43], v[164:167], v[206:209], v[40:43]
	v_mfma_f32_16x16x32_bf16 v[28:31], v[156:159], v[214:217], v[28:31]
	v_mfma_f32_16x16x32_bf16 v[24:27], v[164:167], v[214:217], v[24:27]
	v_mfma_f32_16x16x32_bf16 v[12:15], v[156:159], v[222:225], v[12:15]
	v_lshl_add_u64 v[228:229], s[54:55], 0, v[128:129]
	s_mov_b32 m0, s33
	s_nop 0
	global_load_lds_dwordx4 v[228:229], off
	v_mfma_f32_16x16x32_bf16 v[8:11], v[164:167], v[222:225], v[8:11]
	s_setprio 0
	s_setprio 1
	v_mfma_f32_16x16x32_bf16 v[52:55], v[168:171], v[188:191], v[52:55]
	v_mfma_f32_16x16x32_bf16 v[48:51], v[180:183], v[188:191], v[48:51]
	v_mfma_f32_16x16x32_bf16 v[36:39], v[168:171], v[196:199], v[36:39]
	v_mfma_f32_16x16x32_bf16 v[32:35], v[180:183], v[196:199], v[32:35]
	v_mfma_f32_16x16x32_bf16 v[20:23], v[168:171], v[210:213], v[20:23]
	v_mfma_f32_16x16x32_bf16 v[16:19], v[180:183], v[210:213], v[16:19]
	v_mfma_f32_16x16x32_bf16 v[4:7], v[168:171], v[218:221], v[4:7]
	v_mfma_f32_16x16x32_bf16 v[0:3], v[180:183], v[218:221], v[0:3]
	v_mfma_f32_16x16x32_bf16 v[52:55], v[172:175], v[192:195], v[52:55]
	v_mfma_f32_16x16x32_bf16 v[48:51], v[184:187], v[192:195], v[48:51]
	v_mfma_f32_16x16x32_bf16 v[36:39], v[172:175], v[206:209], v[36:39]
	v_mfma_f32_16x16x32_bf16 v[32:35], v[184:187], v[206:209], v[32:35]
	v_mfma_f32_16x16x32_bf16 v[20:23], v[172:175], v[214:217], v[20:23]
	v_mfma_f32_16x16x32_bf16 v[16:19], v[184:187], v[214:217], v[16:19]
	v_mfma_f32_16x16x32_bf16 v[4:7], v[172:175], v[222:225], v[4:7]
	v_lshl_add_u64 v[230:231], s[54:55], 0, v[132:133]
	s_mov_b32 m0, s34
	s_nop 0
	global_load_lds_dwordx4 v[230:231], off
	v_mfma_f32_16x16x32_bf16 v[0:3], v[184:187], v[222:225], v[0:3]
	s_setprio 0
	s_barrier
; #define PG8_STAGE(bufoff, gbase, voff) do { _Pragma("unroll") for (int _i = 0; _i < 2; ++_i) \
;         __builtin_amdgcn_global_load_lds((const unsigned*)((const char*)(gbase) + (voff)[_i]), (PG8_LAS unsigned*)(lds + (bufoff) + ldsw + _i * 8192), 16, 0, 0); } while (0)
; #define PG8_LDA(dst, b, h) do { _Pragma("unroll") for (int m = 0; m < 4; ++m) _Pragma("unroll") for (int k = 0; k < 2; ++k) dst[m][k] = *(const PG8_LAS bf16x8*)(lds + PG8_SA(b, h) + aoff + m * 2048 + k * 1024); } while (0)
; #define PG8_LDB(dst, b, h) do { _Pragma("unroll") for (int n = 0; n < 2; ++n) _Pragma("unroll") for (int k = 0; k < 2; ++k) dst[n][k] = *(const PG8_LAS bf16x8*)(lds + PG8_SB(b, h) + boff + n * 2048 + k * 1024); } while (0)
; #define PG8_MMA(ai, bj, At, Bt) do { __builtin_amdgcn_s_setprio(1); _Pragma("unroll") for (int m = 0; m < 4; ++m) _Pragma("unroll") for (int n = 0; n < 2; ++n) _Pragma("unroll") for (int k = 0; k < 2; ++k) \
;         acc[ai][bj][m][n] = __builtin_amdgcn_mfma_f32_16x16x32_bf16(Bt[n][k], At[m][k], acc[ai][bj][m][n], 0, 0, 0); __builtin_amdgcn_s_setprio(0); } while (0)
; #define PG8_WAIT_V(n) asm volatile("s_waitcnt vmcnt(" #n ")" ::: "memory")
; #define PG8_WAIT_L(n) asm volatile("s_waitcnt lgkmcnt(" #n ")" ::: "memory")
; #define PG8_BAR __builtin_amdgcn_s_barrier()
; #define PG8_SCHED __builtin_amdgcn_sched_barrier(0)
; template <class Epi, class Sched, bool ALIGN_EPI = false, bool SP2 = false>
; __device__ __forceinline__ void gemm_phase(PG8_LAS unsigned char* lds, const Gemm g, const Sched& S, const Epi& E) {
;     ...
;             PG8_LDB(B0, 1, 0); PG8_LDB(B1, 1, 1); PG8_SCHED; PG8_LDA(At, 1, 0); PG8_STAGE(PG8_SA(0, 1), a2 + hstep, voffA);
;             PG8_WAIT_V(8); PG8_WAIT_L(0); PG8_BAR; PG8_MMA(0, 0, At, B0); PG8_MMA(0, 1, At, B1); PG8_BAR; PG8_SCHED;
	s_add_i32 s74, 0, 0x18000
	s_add_i32 s75, 0, 0x1c000
	v_add_u32_e32 v164, s74, v150
	v_add_u32_e32 v179, s75, v150
	ds_read_b128 v[146:149], v164
	ds_read_b128 v[156:159], v164 offset:1024
	ds_read_b128 v[160:163], v164 offset:2048
	ds_read_b128 v[164:167], v164 offset:3072
	ds_read_b128 v[168:171], v179
	ds_read_b128 v[172:175], v179 offset:1024
	ds_read_b128 v[180:183], v179 offset:2048
	ds_read_b128 v[184:187], v179 offset:3072
	s_add_u32 s54, s54, 0x40000
	s_addc_u32 s55, s55, 0
	s_mov_b32 m0, s49
	v_lshl_add_u64 v[232:233], s[54:55], 0, v[128:129]
	ds_read_b128 v[188:191], v154 offset:32768
	ds_read_b128 v[192:195], v154 offset:33792
	ds_read_b128 v[196:199], v154 offset:34816
	ds_read_b128 v[206:209], v154 offset:35840
	ds_read_b128 v[210:213], v154 offset:36864
	ds_read_b128 v[214:217], v154 offset:37888
	ds_read_b128 v[218:221], v154 offset:38912
	ds_read_b128 v[222:225], v154 offset:39936
	global_load_lds_dwordx4 v[232:233], off
	v_lshl_add_u64 v[232:233], s[54:55], 0, v[132:133]
	s_mov_b32 m0, s56
	s_nop 0
	global_load_lds_dwordx4 v[232:233], off
	s_waitcnt vmcnt(8)
	s_waitcnt lgkmcnt(0)
	s_barrier
	s_setprio 1
	s_waitcnt lgkmcnt(0)
	v_mfma_f32_16x16x32_bf16 v[124:127], v[146:149], v[188:191], v[124:127]
	v_mfma_f32_16x16x32_bf16 v[120:123], v[160:163], v[188:191], v[120:123]
	v_mfma_f32_16x16x32_bf16 v[108:111], v[146:149], v[196:199], v[108:111]
	v_mfma_f32_16x16x32_bf16 v[104:107], v[160:163], v[196:199], v[104:107]
	v_mfma_f32_16x16x32_bf16 v[92:95], v[146:149], v[210:213], v[92:95]
	v_mfma_f32_16x16x32_bf16 v[88:91], v[160:163], v[210:213], v[88:91]
	v_mfma_f32_16x16x32_bf16 v[76:79], v[146:149], v[218:221], v[76:79]
	v_mfma_f32_16x16x32_bf16 v[72:75], v[160:163], v[218:221], v[72:75]
	v_mfma_f32_16x16x32_bf16 v[124:127], v[156:159], v[192:195], v[124:127]
	v_mfma_f32_16x16x32_bf16 v[120:123], v[164:167], v[192:195], v[120:123]
	v_mfma_f32_16x16x32_bf16 v[108:111], v[156:159], v[206:209], v[108:111]
	v_mfma_f32_16x16x32_bf16 v[104:107], v[164:167], v[206:209], v[104:107]
	v_mfma_f32_16x16x32_bf16 v[92:95], v[156:159], v[214:217], v[92:95]
	v_mfma_f32_16x16x32_bf16 v[88:91], v[164:167], v[214:217], v[88:91]
	v_mfma_f32_16x16x32_bf16 v[76:79], v[156:159], v[222:225], v[76:79]
	v_mfma_f32_16x16x32_bf16 v[72:75], v[164:167], v[222:225], v[72:75]
	s_setprio 0
	s_setprio 1
	v_mfma_f32_16x16x32_bf16 v[116:119], v[168:171], v[188:191], v[116:119]
	v_mfma_f32_16x16x32_bf16 v[112:115], v[180:183], v[188:191], v[112:115]
	v_mfma_f32_16x16x32_bf16 v[100:103], v[168:171], v[196:199], v[100:103]
	v_mfma_f32_16x16x32_bf16 v[96:99], v[180:183], v[196:199], v[96:99]
	v_mfma_f32_16x16x32_bf16 v[84:87], v[168:171], v[210:213], v[84:87]
	v_mfma_f32_16x16x32_bf16 v[80:83], v[180:183], v[210:213], v[80:83]
	v_mfma_f32_16x16x32_bf16 v[68:71], v[168:171], v[218:221], v[68:71]
	v_mfma_f32_16x16x32_bf16 v[64:67], v[180:183], v[218:221], v[64:67]
	v_mfma_f32_16x16x32_bf16 v[116:119], v[172:175], v[192:195], v[116:119]
	v_mfma_f32_16x16x32_bf16 v[112:115], v[184:187], v[192:195], v[112:115]
	v_mfma_f32_16x16x32_bf16 v[100:103], v[172:175], v[206:209], v[100:103]
	v_mfma_f32_16x16x32_bf16 v[96:99], v[184:187], v[206:209], v[96:99]
	v_mfma_f32_16x16x32_bf16 v[84:87], v[172:175], v[214:217], v[84:87]
	v_mfma_f32_16x16x32_bf16 v[80:83], v[184:187], v[214:217], v[80:83]
	v_mfma_f32_16x16x32_bf16 v[68:71], v[172:175], v[222:225], v[68:71]
	v_mfma_f32_16x16x32_bf16 v[64:67], v[184:187], v[222:225], v[64:67]
	s_setprio 0
	s_barrier
; #define PG8_STAGE(bufoff, gbase, voff) do { _Pragma("unroll") for (int _i = 0; _i < 2; ++_i) \
;         __builtin_amdgcn_global_load_lds((const unsigned*)((const char*)(gbase) + (voff)[_i]), (PG8_LAS unsigned*)(lds + (bufoff) + ldsw + _i * 8192), 16, 0, 0); } while (0)
; #define PG8_LDA(dst, b, h) do { _Pragma("unroll") for (int m = 0; m < 4; ++m) _Pragma("unroll") for (int k = 0; k < 2; ++k) dst[m][k] = *(const PG8_LAS bf16x8*)(lds + PG8_SA(b, h) + aoff + m * 2048 + k * 1024); } while (0)
; #define PG8_MMA(ai, bj, At, Bt) do { __builtin_amdgcn_s_setprio(1); _Pragma("unroll") for (int m = 0; m < 4; ++m) _Pragma("unroll") for (int n = 0; n < 2; ++n) _Pragma("unroll") for (int k = 0; k < 2; ++k) \
;         acc[ai][bj][m][n] = __builtin_amdgcn_mfma_f32_16x16x32_bf16(Bt[n][k], At[m][k], acc[ai][bj][m][n], 0, 0, 0); __builtin_amdgcn_s_setprio(0); } while (0)
; #define PG8_WAIT_V(n) asm volatile("s_waitcnt vmcnt(" #n ")" ::: "memory")
; #define PG8_WAIT_L(n) asm volatile("s_waitcnt lgkmcnt(" #n ")" ::: "memory")
; #define PG8_BAR __builtin_amdgcn_s_barrier()
; #define PG8_SCHED __builtin_amdgcn_sched_barrier(0)
; template <class Epi, class Sched, bool ALIGN_EPI = false, bool SP2 = false>
; __device__ __forceinline__ void gemm_phase(PG8_LAS unsigned char* lds, const Gemm g, const Sched& S, const Epi& E) {
;     ...
;         for (int t = 0; t < nt; t += 2) {
;     ...
;             PG8_LDA(At, 1, 1); PG8_STAGE(PG8_SB(1, 0), b3, voffB); PG8_STAGE(PG8_SB(1, 1), b3 + hstep, voffB); PG8_STAGE(PG8_SA(1, 0), a3, voffA);
;             PG8_WAIT_V(8); PG8_WAIT_L(0); PG8_BAR; PG8_MMA(1, 0, At, B0); PG8_MMA(1, 1, At, B1); PG8_BAR; PG8_SCHED;
	s_add_i32 s54, s74, s15
	v_lshl_add_u64 v[200:201], v[200:201], 0, s[26:27]
	s_mov_b32 m0, s54
	ds_read_b128 v[188:191], v154 offset:49152
	ds_read_b128 v[192:195], v154 offset:50176
	ds_read_b128 v[196:199], v154 offset:51200
	ds_read_b128 v[206:209], v154 offset:52224
	ds_read_b128 v[210:213], v154 offset:53248
	ds_read_b128 v[214:217], v154 offset:54272
	ds_read_b128 v[218:221], v154 offset:55296
	ds_read_b128 v[222:225], v154 offset:56320
	global_load_lds_dwordx4 v[200:201], off
	s_add_i32 m0, s54, 0x2000
	s_add_u32 s52, s52, 0x40080
	v_lshl_add_u64 v[200:201], v[226:227], 0, s[26:27]
	s_addc_u32 s53, s53, 0
	s_add_i32 s54, s75, s15
	global_load_lds_dwordx4 v[200:201], off
	v_lshl_add_u64 v[200:201], s[52:53], 0, v[130:131]
	s_mov_b32 m0, s54
	s_nop 0
	global_load_lds_dwordx4 v[200:201], off
	v_lshl_add_u64 v[200:201], s[52:53], 0, v[134:135]
	s_add_i32 m0, s54, 0x2000
	s_nop 0
	global_load_lds_dwordx4 v[200:201], off
	s_waitcnt vmcnt(6)
	s_waitcnt lgkmcnt(0)
	s_barrier
	s_setprio 1
	s_waitcnt lgkmcnt(0)
	v_mfma_f32_16x16x32_bf16 v[60:63], v[146:149], v[188:191], v[60:63]
	v_mfma_f32_16x16x32_bf16 v[56:59], v[160:163], v[188:191], v[56:59]
	v_mfma_f32_16x16x32_bf16 v[44:47], v[146:149], v[196:199], v[44:47]
	v_mfma_f32_16x16x32_bf16 v[40:43], v[160:163], v[196:199], v[40:43]
	v_mfma_f32_16x16x32_bf16 v[28:31], v[146:149], v[210:213], v[28:31]
	v_mfma_f32_16x16x32_bf16 v[24:27], v[160:163], v[210:213], v[24:27]
	v_mfma_f32_16x16x32_bf16 v[12:15], v[146:149], v[218:221], v[12:15]
	v_mfma_f32_16x16x32_bf16 v[8:11], v[160:163], v[218:221], v[8:11]
	v_mfma_f32_16x16x32_bf16 v[60:63], v[156:159], v[192:195], v[60:63]
	v_mfma_f32_16x16x32_bf16 v[56:59], v[164:167], v[192:195], v[56:59]
	v_mfma_f32_16x16x32_bf16 v[44:47], v[156:159], v[206:209], v[44:47]
	v_mfma_f32_16x16x32_bf16 v[40:43], v[164:167], v[206:209], v[40:43]
	v_mfma_f32_16x16x32_bf16 v[28:31], v[156:159], v[214:217], v[28:31]
	v_mfma_f32_16x16x32_bf16 v[24:27], v[164:167], v[214:217], v[24:27]
	v_mfma_f32_16x16x32_bf16 v[12:15], v[156:159], v[222:225], v[12:15]
	v_lshl_add_u64 v[200:201], v[228:229], 0, s[26:27]
	s_mov_b32 m0, s58
	s_nop 0
	global_load_lds_dwordx4 v[200:201], off
	v_mfma_f32_16x16x32_bf16 v[8:11], v[164:167], v[222:225], v[8:11]
	s_setprio 0
	s_setprio 1
	v_mfma_f32_16x16x32_bf16 v[52:55], v[168:171], v[188:191], v[52:55]
	v_mfma_f32_16x16x32_bf16 v[48:51], v[180:183], v[188:191], v[48:51]
	v_mfma_f32_16x16x32_bf16 v[36:39], v[168:171], v[196:199], v[36:39]
	v_mfma_f32_16x16x32_bf16 v[32:35], v[180:183], v[196:199], v[32:35]
	v_mfma_f32_16x16x32_bf16 v[20:23], v[168:171], v[210:213], v[20:23]
	v_mfma_f32_16x16x32_bf16 v[16:19], v[180:183], v[210:213], v[16:19]
	v_mfma_f32_16x16x32_bf16 v[4:7], v[168:171], v[218:221], v[4:7]
	v_mfma_f32_16x16x32_bf16 v[0:3], v[180:183], v[218:221], v[0:3]
	v_mfma_f32_16x16x32_bf16 v[52:55], v[172:175], v[192:195], v[52:55]
	v_mfma_f32_16x16x32_bf16 v[48:51], v[184:187], v[192:195], v[48:51]
	v_mfma_f32_16x16x32_bf16 v[36:39], v[172:175], v[206:209], v[36:39]
	v_mfma_f32_16x16x32_bf16 v[32:35], v[184:187], v[206:209], v[32:35]
	v_mfma_f32_16x16x32_bf16 v[20:23], v[172:175], v[214:217], v[20:23]
	v_mfma_f32_16x16x32_bf16 v[16:19], v[184:187], v[214:217], v[16:19]
	v_mfma_f32_16x16x32_bf16 v[4:7], v[172:175], v[222:225], v[4:7]
	v_lshl_add_u64 v[200:201], v[230:231], 0, s[26:27]
	s_mov_b32 m0, s59
	s_nop 0
	global_load_lds_dwordx4 v[200:201], off
	v_mfma_f32_16x16x32_bf16 v[0:3], v[184:187], v[222:225], v[0:3]
	s_setprio 0
	s_barrier
	s_add_i32 s67, s67, 2
	s_add_u32 s50, s50, 0x100
	s_addc_u32 s51, s51, 0
	s_add_u32 s65, s65, 0x100
	s_addc_u32 s66, s66, 0
	s_cmp_gt_u32 s67, 13
	s_cbranch_scc0 .LBB0_1593
	s_and_b64 vcc, exec, s[28:29]
	s_cbranch_vccz .LBB0_1596
	s_barrier

; #define PG8_STAGE(bufoff, gbase, voff) do { _Pragma("unroll") for (int _i = 0; _i < 2; ++_i) \
;         __builtin_amdgcn_global_load_lds((const unsigned*)((const char*)(gbase) + (voff)[_i]), (PG8_LAS unsigned*)(lds + (bufoff) + ldsw + _i * 8192), 16, 0, 0); } while (0)
; #define PG8_LDA(dst, b, h) do { _Pragma("unroll") for (int m = 0; m < 4; ++m) _Pragma("unroll") for (int k = 0; k < 2; ++k) dst[m][k] = *(const PG8_LAS bf16x8*)(lds + PG8_SA(b, h) + aoff + m * 2048 + k * 1024); } while (0)
; #define PG8_LDB(dst, b, h) do { _Pragma("unroll") for (int n = 0; n < 2; ++n) _Pragma("unroll") for (int k = 0; k < 2; ++k) dst[n][k] = *(const PG8_LAS bf16x8*)(lds + PG8_SB(b, h) + boff + n * 2048 + k * 1024); } while (0)
; #define PG8_MMA(ai, bj, At, Bt) do { __builtin_amdgcn_s_setprio(1); _Pragma("unroll") for (int m = 0; m < 4; ++m) _Pragma("unroll") for (int n = 0; n < 2; ++n) _Pragma("unroll") for (int k = 0; k < 2; ++k) \
;         acc[ai][bj][m][n] = __builtin_amdgcn_mfma_f32_16x16x32_bf16(Bt[n][k], At[m][k], acc[ai][bj][m][n], 0, 0, 0); __builtin_amdgcn_s_setprio(0); } while (0)
; #define PG8_BAR __builtin_amdgcn_s_barrier()
; template <class Epi, class Sched, bool ALIGN_EPI = false, bool SP2 = false>
; __device__ __forceinline__ void gemm_phase(PG8_LAS unsigned char* lds, const Gemm g, const Sched& S, const Epi& E) {
;     ...
;         const bool has_next = S.next(ui + 1, nxt);
;         const char* nA = has_next ? (const char*)g.A + (size_t)nxt.pm * tstep : cA; const char* nB = has_next ? (const char*)g.Bt + (size_t)nxt.pn * tstep : cB;
;         for (int t = 0; t < nt; t += 2) {
;             const bool last = (t == nt - 2);
;             const char* a1 = cA + (size_t)(t + 1) * kstep;
;             const char* a2 = last ? nA : cA + (size_t)(t + 2) * kstep; const char* b2 = last ? nB : cB + (size_t)(t + 2) * kstep;
;             const char* a3 = a2 + kstep; const char* b3 = b2 + kstep;
;             if (last && has_next) S.a_ready(nxt);
;             if constexpr (SP2) {
;             PG8_LDB(B0, 0, 0); PG8_LDB(B1, 0, 1); PG8_SCHED; PG8_LDA(At, 0, 0); PG8_STAGE(PG8_SA(1, 1), a1 + hstep, voffA);
;             PG8_WAIT_V(8); PG8_WAIT_L(0); PG8_BAR; PG8_MMA(0, 0, At, B0); PG8_MMA(0, 1, At, B1); PG8_BAR; PG8_SCHED;
;             PG8_LDA(At, 0, 1); PG8_STAGE(PG8_SB(0, 0), b2, voffB); PG8_STAGE(PG8_SB(0, 1), b2 + hstep, voffB); PG8_STAGE(PG8_SA(0, 0), a2, voffA);
.LBB0_1680:
	s_ashr_i32 s47, s46, 31
	s_lshl_b64 s[48:49], s[46:47], 19
	s_add_u32 s48, s22, s48
	s_addc_u32 s49, s23, s49
	s_and_b64 s[50:51], s[4:5], exec
	s_cselect_b32 s47, s49, s53
	s_cselect_b32 s77, s48, s52
	s_ashr_i32 s45, s44, 31
	s_lshl_b64 s[50:51], s[44:45], 19
	s_add_u32 s50, s15, s50
	s_addc_u32 s51, s33, s51
	s_and_b64 s[56:57], s[4:5], exec
	s_cselect_b32 s45, s51, s55
	s_cselect_b32 s78, s50, s54
	s_add_u32 s52, s52, 0x40080
	s_addc_u32 s53, s53, 0
	s_add_u32 s79, s54, 0x100
	s_addc_u32 s80, s55, 0
	s_mov_b32 s81, -2
	ds_read_b128 v[146:149], v152
	ds_read_b128 v[156:159], v152 offset:1024
	ds_read_b128 v[160:163], v152 offset:2048
	ds_read_b128 v[164:167], v152 offset:3072
	ds_read_b128 v[168:171], v153
	ds_read_b128 v[172:175], v153 offset:1024
	ds_read_b128 v[180:183], v153 offset:2048
	ds_read_b128 v[184:187], v153 offset:3072
	s_add_u32 s54, s52, 0xfffc0080
	s_addc_u32 s55, s53, -1
	s_cmp_eq_u32 s81, 12
	s_cselect_b32 s57, s47, s55
	s_cselect_b32 s56, s77, s54
	s_cselect_b32 s55, s45, s80
	s_cselect_b32 s54, s78, s79
	v_lshl_add_u64 v[200:201], s[52:53], 0, v[136:137]
	s_add_i32 m0, s58, 0xc000
	ds_read_b128 v[188:191], v154
	ds_read_b128 v[192:195], v154 offset:1024
	ds_read_b128 v[196:199], v154 offset:2048
	ds_read_b128 v[206:209], v154 offset:3072
	ds_read_b128 v[210:213], v154 offset:4096
	ds_read_b128 v[214:217], v154 offset:5120
	ds_read_b128 v[218:221], v154 offset:6144
	ds_read_b128 v[222:225], v154 offset:7168
	global_load_lds_dwordx4 v[200:201], off
	v_lshl_add_u64 v[200:201], s[52:53], 0, v[138:139]
	s_add_i32 m0, s58, 0xe000
	s_nop 0
	global_load_lds_dwordx4 v[200:201], off
	s_waitcnt vmcnt(8)
	s_waitcnt lgkmcnt(0)
	s_barrier
	s_setprio 1
	s_waitcnt lgkmcnt(0)
	v_mfma_f32_16x16x32_bf16 v[124:127], v[146:149], v[188:191], 0
	v_mfma_f32_16x16x32_bf16 v[120:123], v[160:163], v[188:191], 0
	v_mfma_f32_16x16x32_bf16 v[108:111], v[146:149], v[196:199], 0
	v_mfma_f32_16x16x32_bf16 v[104:107], v[160:163], v[196:199], 0
	v_mfma_f32_16x16x32_bf16 v[92:95], v[146:149], v[210:213], 0
	v_mfma_f32_16x16x32_bf16 v[88:91], v[160:163], v[210:213], 0
	v_mfma_f32_16x16x32_bf16 v[76:79], v[146:149], v[218:221], 0
	v_mfma_f32_16x16x32_bf16 v[72:75], v[160:163], v[218:221], 0
	v_mfma_f32_16x16x32_bf16 v[124:127], v[156:159], v[192:195], v[124:127]
	v_mfma_f32_16x16x32_bf16 v[120:123], v[164:167], v[192:195], v[120:123]
	v_mfma_f32_16x16x32_bf16 v[108:111], v[156:159], v[206:209], v[108:111]
	v_mfma_f32_16x16x32_bf16 v[104:107], v[164:167], v[206:209], v[104:107]
	v_mfma_f32_16x16x32_bf16 v[92:95], v[156:159], v[214:217], v[92:95]
	v_mfma_f32_16x16x32_bf16 v[88:91], v[164:167], v[214:217], v[88:91]
	v_mfma_f32_16x16x32_bf16 v[76:79], v[156:159], v[222:225], v[76:79]
	v_mfma_f32_16x16x32_bf16 v[72:75], v[164:167], v[222:225], v[72:75]
	s_setprio 0
	s_setprio 1
	v_mfma_f32_16x16x32_bf16 v[116:119], v[168:171], v[188:191], 0
	v_mfma_f32_16x16x32_bf16 v[112:115], v[180:183], v[188:191], 0
	v_mfma_f32_16x16x32_bf16 v[100:103], v[168:171], v[196:199], 0
	v_mfma_f32_16x16x32_bf16 v[96:99], v[180:183], v[196:199], 0
	v_mfma_f32_16x16x32_bf16 v[84:87], v[168:171], v[210:213], 0
	v_mfma_f32_16x16x32_bf16 v[80:83], v[180:183], v[210:213], 0
	v_mfma_f32_16x16x32_bf16 v[68:71], v[168:171], v[218:221], 0
	v_mfma_f32_16x16x32_bf16 v[64:67], v[180:183], v[218:221], 0
	v_mfma_f32_16x16x32_bf16 v[116:119], v[172:175], v[192:195], v[116:119]
	v_mfma_f32_16x16x32_bf16 v[112:115], v[184:187], v[192:195], v[112:115]
	v_mfma_f32_16x16x32_bf16 v[100:103], v[172:175], v[206:209], v[100:103]
	v_mfma_f32_16x16x32_bf16 v[96:99], v[184:187], v[206:209], v[96:99]
	v_mfma_f32_16x16x32_bf16 v[84:87], v[172:175], v[214:217], v[84:87]
	v_mfma_f32_16x16x32_bf16 v[80:83], v[184:187], v[214:217], v[80:83]
	v_mfma_f32_16x16x32_bf16 v[68:71], v[172:175], v[222:225], v[68:71]
	v_mfma_f32_16x16x32_bf16 v[64:67], v[184:187], v[222:225], v[64:67]
	s_setprio 0
	s_barrier
	s_add_i32 s82, s65, s34
	v_lshl_add_u64 v[200:201], s[54:55], 0, v[132:133]
	s_mov_b32 m0, s82
	ds_read_b128 v[188:191], v154 offset:16384
	ds_read_b128 v[192:195], v154 offset:17408
	ds_read_b128 v[196:199], v154 offset:18432
	ds_read_b128 v[206:209], v154 offset:19456
	ds_read_b128 v[210:213], v154 offset:20480
	ds_read_b128 v[214:217], v154 offset:21504
	ds_read_b128 v[218:221], v154 offset:22528
	ds_read_b128 v[222:225], v154 offset:23552
	global_load_lds_dwordx4 v[200:201], off
	s_add_i32 m0, s82, 0x2000
	s_add_u32 s82, s54, 0x40000
	v_lshl_add_u64 v[226:227], s[54:55], 0, v[128:129]
	s_addc_u32 s83, s55, 0
	s_add_i32 s84, s66, s34
	global_load_lds_dwordx4 v[226:227], off
	v_lshl_add_u64 v[228:229], s[82:83], 0, v[132:133]
	s_mov_b32 m0, s84
	global_load_lds_dwordx4 v[228:229], off
	v_lshl_add_u64 v[228:229], s[82:83], 0, v[128:129]
	s_add_i32 m0, s84, 0x2000
	s_nop 0
	global_load_lds_dwordx4 v[228:229], off
	s_waitcnt vmcnt(6)
	s_waitcnt lgkmcnt(0)
	s_barrier
; #define PG8_STAGE(bufoff, gbase, voff) do { _Pragma("unroll") for (int _i = 0; _i < 2; ++_i) \
;         __builtin_amdgcn_global_load_lds((const unsigned*)((const char*)(gbase) + (voff)[_i]), (PG8_LAS unsigned*)(lds + (bufoff) + ldsw + _i * 8192), 16, 0, 0); } while (0)
; #define PG8_LDA(dst, b, h) do { _Pragma("unroll") for (int m = 0; m < 4; ++m) _Pragma("unroll") for (int k = 0; k < 2; ++k) dst[m][k] = *(const PG8_LAS bf16x8*)(lds + PG8_SA(b, h) + aoff + m * 2048 + k * 1024); } while (0)
; #define PG8_LDB(dst, b, h) do { _Pragma("unroll") for (int n = 0; n < 2; ++n) _Pragma("unroll") for (int k = 0; k < 2; ++k) dst[n][k] = *(const PG8_LAS bf16x8*)(lds + PG8_SB(b, h) + boff + n * 2048 + k * 1024); } while (0)
; #define PG8_MMA(ai, bj, At, Bt) do { __builtin_amdgcn_s_setprio(1); _Pragma("unroll") for (int m = 0; m < 4; ++m) _Pragma("unroll") for (int n = 0; n < 2; ++n) _Pragma("unroll") for (int k = 0; k < 2; ++k) \
;         acc[ai][bj][m][n] = __builtin_amdgcn_mfma_f32_16x16x32_bf16(Bt[n][k], At[m][k], acc[ai][bj][m][n], 0, 0, 0); __builtin_amdgcn_s_setprio(0); } while (0)
; #define PG8_WAIT_V(n) asm volatile("s_waitcnt vmcnt(" #n ")" ::: "memory")
; #define PG8_WAIT_L(n) asm volatile("s_waitcnt lgkmcnt(" #n ")" ::: "memory")
; #define PG8_BAR __builtin_amdgcn_s_barrier()
; #define PG8_SCHED __builtin_amdgcn_sched_barrier(0)
; template <class Epi, class Sched, bool ALIGN_EPI = false, bool SP2 = false>
; __device__ __forceinline__ void gemm_phase(PG8_LAS unsigned char* lds, const Gemm g, const Sched& S, const Epi& E) {
;     ...
;             PG8_WAIT_V(8); PG8_WAIT_L(0); PG8_BAR; PG8_MMA(0, 0, At, B0); PG8_MMA(0, 1, At, B1); PG8_BAR; PG8_SCHED;
;             PG8_LDA(At, 0, 1); PG8_STAGE(PG8_SB(0, 0), b2, voffB); PG8_STAGE(PG8_SB(0, 1), b2 + hstep, voffB); PG8_STAGE(PG8_SA(0, 0), a2, voffA);
;             PG8_WAIT_V(8); PG8_WAIT_L(0); PG8_BAR; PG8_MMA(1, 0, At, B0); PG8_MMA(1, 1, At, B1); PG8_BAR; PG8_SCHED;
;             PG8_LDB(B0, 1, 0); PG8_LDB(B1, 1, 1); PG8_SCHED; PG8_LDA(At, 1, 0); PG8_STAGE(PG8_SA(0, 1), a2 + hstep, voffA);
;             PG8_WAIT_V(8); PG8_WAIT_L(0); PG8_BAR; PG8_MMA(0, 0, At, B0); PG8_MMA(0, 1, At, B1); PG8_BAR; PG8_SCHED;
	s_setprio 1
	s_waitcnt lgkmcnt(0)
	v_mfma_f32_16x16x32_bf16 v[60:63], v[146:149], v[188:191], 0
	v_mfma_f32_16x16x32_bf16 v[56:59], v[160:163], v[188:191], 0
	v_mfma_f32_16x16x32_bf16 v[44:47], v[146:149], v[196:199], 0
	v_mfma_f32_16x16x32_bf16 v[40:43], v[160:163], v[196:199], 0
	v_mfma_f32_16x16x32_bf16 v[28:31], v[146:149], v[210:213], 0
	v_mfma_f32_16x16x32_bf16 v[24:27], v[160:163], v[210:213], 0
	v_mfma_f32_16x16x32_bf16 v[12:15], v[146:149], v[218:221], 0
	v_mfma_f32_16x16x32_bf16 v[8:11], v[160:163], v[218:221], 0
	v_mfma_f32_16x16x32_bf16 v[60:63], v[156:159], v[192:195], v[60:63]
	v_mfma_f32_16x16x32_bf16 v[56:59], v[164:167], v[192:195], v[56:59]
	v_mfma_f32_16x16x32_bf16 v[44:47], v[156:159], v[206:209], v[44:47]
	v_mfma_f32_16x16x32_bf16 v[40:43], v[164:167], v[206:209], v[40:43]
	v_mfma_f32_16x16x32_bf16 v[28:31], v[156:159], v[214:217], v[28:31]
	v_mfma_f32_16x16x32_bf16 v[24:27], v[164:167], v[214:217], v[24:27]
	v_mfma_f32_16x16x32_bf16 v[12:15], v[156:159], v[222:225], v[12:15]
	v_lshl_add_u64 v[228:229], s[56:57], 0, v[134:135]
	s_mov_b32 m0, s58
	s_nop 0
	global_load_lds_dwordx4 v[228:229], off
	v_mfma_f32_16x16x32_bf16 v[8:11], v[164:167], v[222:225], v[8:11]
	s_setprio 0
	s_setprio 1
	v_mfma_f32_16x16x32_bf16 v[52:55], v[168:171], v[188:191], 0
	v_mfma_f32_16x16x32_bf16 v[48:51], v[180:183], v[188:191], 0
	v_mfma_f32_16x16x32_bf16 v[36:39], v[168:171], v[196:199], 0
	v_mfma_f32_16x16x32_bf16 v[32:35], v[180:183], v[196:199], 0
	v_mfma_f32_16x16x32_bf16 v[20:23], v[168:171], v[210:213], 0
	v_mfma_f32_16x16x32_bf16 v[16:19], v[180:183], v[210:213], 0
	v_mfma_f32_16x16x32_bf16 v[4:7], v[168:171], v[218:221], 0
	v_mfma_f32_16x16x32_bf16 v[0:3], v[180:183], v[218:221], 0
	v_mfma_f32_16x16x32_bf16 v[52:55], v[172:175], v[192:195], v[52:55]
	v_mfma_f32_16x16x32_bf16 v[48:51], v[184:187], v[192:195], v[48:51]
	v_mfma_f32_16x16x32_bf16 v[36:39], v[172:175], v[206:209], v[36:39]
	v_mfma_f32_16x16x32_bf16 v[32:35], v[184:187], v[206:209], v[32:35]
	v_mfma_f32_16x16x32_bf16 v[20:23], v[172:175], v[214:217], v[20:23]
	v_mfma_f32_16x16x32_bf16 v[16:19], v[184:187], v[214:217], v[16:19]
	v_mfma_f32_16x16x32_bf16 v[4:7], v[172:175], v[222:225], v[4:7]
	v_lshl_add_u64 v[230:231], s[56:57], 0, v[130:131]
	s_mov_b32 m0, s59
	s_nop 0
	global_load_lds_dwordx4 v[230:231], off
	v_mfma_f32_16x16x32_bf16 v[0:3], v[184:187], v[222:225], v[0:3]
	s_setprio 0
	s_barrier
	s_add_i32 s82, 0, 0x18000
	s_add_i32 s83, 0, 0x1c000
	v_add_u32_e32 v164, s82, v150
	v_add_u32_e32 v179, s83, v150
	ds_read_b128 v[146:149], v164
	ds_read_b128 v[156:159], v164 offset:1024
	ds_read_b128 v[160:163], v164 offset:2048
	ds_read_b128 v[164:167], v164 offset:3072
	ds_read_b128 v[168:171], v179
	ds_read_b128 v[172:175], v179 offset:1024
	ds_read_b128 v[180:183], v179 offset:2048
	ds_read_b128 v[184:187], v179 offset:3072
	s_add_u32 s56, s56, 0x40000
	s_addc_u32 s57, s57, 0
	s_mov_b32 m0, s60
	v_lshl_add_u64 v[232:233], s[56:57], 0, v[134:135]
	ds_read_b128 v[188:191], v154 offset:32768
	ds_read_b128 v[192:195], v154 offset:33792
	ds_read_b128 v[196:199], v154 offset:34816
	ds_read_b128 v[206:209], v154 offset:35840
	ds_read_b128 v[210:213], v154 offset:36864
	ds_read_b128 v[214:217], v154 offset:37888
	ds_read_b128 v[218:221], v154 offset:38912
	ds_read_b128 v[222:225], v154 offset:39936
	global_load_lds_dwordx4 v[232:233], off
	v_lshl_add_u64 v[232:233], s[56:57], 0, v[130:131]
	s_mov_b32 m0, s61
	s_nop 0
	global_load_lds_dwordx4 v[232:233], off
	s_waitcnt vmcnt(8)
	s_waitcnt lgkmcnt(0)
	s_barrier
	s_setprio 1
	s_waitcnt lgkmcnt(0)
	v_mfma_f32_16x16x32_bf16 v[124:127], v[146:149], v[188:191], v[124:127]
	v_mfma_f32_16x16x32_bf16 v[120:123], v[160:163], v[188:191], v[120:123]
	v_mfma_f32_16x16x32_bf16 v[108:111], v[146:149], v[196:199], v[108:111]
	v_mfma_f32_16x16x32_bf16 v[104:107], v[160:163], v[196:199], v[104:107]
	v_mfma_f32_16x16x32_bf16 v[92:95], v[146:149], v[210:213], v[92:95]
	v_mfma_f32_16x16x32_bf16 v[88:91], v[160:163], v[210:213], v[88:91]
	v_mfma_f32_16x16x32_bf16 v[76:79], v[146:149], v[218:221], v[76:79]
	v_mfma_f32_16x16x32_bf16 v[72:75], v[160:163], v[218:221], v[72:75]
	v_mfma_f32_16x16x32_bf16 v[124:127], v[156:159], v[192:195], v[124:127]
	v_mfma_f32_16x16x32_bf16 v[120:123], v[164:167], v[192:195], v[120:123]
	v_mfma_f32_16x16x32_bf16 v[108:111], v[156:159], v[206:209], v[108:111]
	v_mfma_f32_16x16x32_bf16 v[104:107], v[164:167], v[206:209], v[104:107]
	v_mfma_f32_16x16x32_bf16 v[92:95], v[156:159], v[214:217], v[92:95]
	v_mfma_f32_16x16x32_bf16 v[88:91], v[164:167], v[214:217], v[88:91]
	v_mfma_f32_16x16x32_bf16 v[76:79], v[156:159], v[222:225], v[76:79]
	v_mfma_f32_16x16x32_bf16 v[72:75], v[164:167], v[222:225], v[72:75]
	s_setprio 0
	s_setprio 1
	v_mfma_f32_16x16x32_bf16 v[116:119], v[168:171], v[188:191], v[116:119]
	v_mfma_f32_16x16x32_bf16 v[112:115], v[180:183], v[188:191], v[112:115]
	v_mfma_f32_16x16x32_bf16 v[100:103], v[168:171], v[196:199], v[100:103]
	v_mfma_f32_16x16x32_bf16 v[96:99], v[180:183], v[196:199], v[96:99]
	v_mfma_f32_16x16x32_bf16 v[84:87], v[168:171], v[210:213], v[84:87]
	v_mfma_f32_16x16x32_bf16 v[80:83], v[180:183], v[210:213], v[80:83]
	v_mfma_f32_16x16x32_bf16 v[68:71], v[168:171], v[218:221], v[68:71]
	v_mfma_f32_16x16x32_bf16 v[64:67], v[180:183], v[218:221], v[64:67]
	v_mfma_f32_16x16x32_bf16 v[116:119], v[172:175], v[192:195], v[116:119]
	v_mfma_f32_16x16x32_bf16 v[112:115], v[184:187], v[192:195], v[112:115]
	v_mfma_f32_16x16x32_bf16 v[100:103], v[172:175], v[206:209], v[100:103]
	v_mfma_f32_16x16x32_bf16 v[96:99], v[184:187], v[206:209], v[96:99]
	v_mfma_f32_16x16x32_bf16 v[84:87], v[172:175], v[214:217], v[84:87]
	v_mfma_f32_16x16x32_bf16 v[80:83], v[184:187], v[214:217], v[80:83]
	v_mfma_f32_16x16x32_bf16 v[68:71], v[172:175], v[222:225], v[68:71]
	v_mfma_f32_16x16x32_bf16 v[64:67], v[184:187], v[222:225], v[64:67]
	s_setprio 0
	s_barrier
; #define PG8_STAGE(bufoff, gbase, voff) do { _Pragma("unroll") for (int _i = 0; _i < 2; ++_i) \
;         __builtin_amdgcn_global_load_lds((const unsigned*)((const char*)(gbase) + (voff)[_i]), (PG8_LAS unsigned*)(lds + (bufoff) + ldsw + _i * 8192), 16, 0, 0); } while (0)
; #define PG8_LDA(dst, b, h) do { _Pragma("unroll") for (int m = 0; m < 4; ++m) _Pragma("unroll") for (int k = 0; k < 2; ++k) dst[m][k] = *(const PG8_LAS bf16x8*)(lds + PG8_SA(b, h) + aoff + m * 2048 + k * 1024); } while (0)
; #define PG8_LDB(dst, b, h) do { _Pragma("unroll") for (int n = 0; n < 2; ++n) _Pragma("unroll") for (int k = 0; k < 2; ++k) dst[n][k] = *(const PG8_LAS bf16x8*)(lds + PG8_SB(b, h) + boff + n * 2048 + k * 1024); } while (0)
; #define PG8_MMA(ai, bj, At, Bt) do { __builtin_amdgcn_s_setprio(1); _Pragma("unroll") for (int m = 0; m < 4; ++m) _Pragma("unroll") for (int n = 0; n < 2; ++n) _Pragma("unroll") for (int k = 0; k < 2; ++k) \
;         acc[ai][bj][m][n] = __builtin_amdgcn_mfma_f32_16x16x32_bf16(Bt[n][k], At[m][k], acc[ai][bj][m][n], 0, 0, 0); __builtin_amdgcn_s_setprio(0); } while (0)
; #define PG8_WAIT_V(n) asm volatile("s_waitcnt vmcnt(" #n ")" ::: "memory")
; template <class Epi, class Sched, bool ALIGN_EPI = false, bool SP2 = false>
; __device__ __forceinline__ void gemm_phase(PG8_LAS unsigned char* lds, const Gemm g, const Sched& S, const Epi& E) {
;     ...
;             PG8_LDB(B0, 0, 0); PG8_LDB(B1, 0, 1); PG8_SCHED; PG8_LDA(At, 0, 0); PG8_STAGE(PG8_SA(1, 1), a1 + hstep, voffA);
;             PG8_WAIT_V(8); PG8_WAIT_L(0); PG8_BAR; PG8_MMA(0, 0, At, B0); PG8_MMA(0, 1, At, B1); PG8_BAR; PG8_SCHED;
;             PG8_LDA(At, 0, 1); PG8_STAGE(PG8_SB(0, 0), b2, voffB); PG8_STAGE(PG8_SB(0, 1), b2 + hstep, voffB); PG8_STAGE(PG8_SA(0, 0), a2, voffA);
;             PG8_WAIT_V(8); PG8_WAIT_L(0); PG8_BAR; PG8_MMA(1, 0, At, B0); PG8_MMA(1, 1, At, B1); PG8_BAR; PG8_SCHED;
;             PG8_LDB(B0, 1, 0); PG8_LDB(B1, 1, 1); PG8_SCHED; PG8_LDA(At, 1, 0); PG8_STAGE(PG8_SA(0, 1), a2 + hstep, voffA);
;             PG8_WAIT_V(8); PG8_WAIT_L(0); PG8_BAR; PG8_MMA(0, 0, At, B0); PG8_MMA(0, 1, At, B1); PG8_BAR; PG8_SCHED;
;             PG8_LDA(At, 1, 1); PG8_STAGE(PG8_SB(1, 0), b3, voffB); PG8_STAGE(PG8_SB(1, 1), b3 + hstep, voffB); PG8_STAGE(PG8_SA(1, 0), a3, voffA);
;             PG8_WAIT_V(8); PG8_WAIT_L(0); PG8_BAR; PG8_MMA(1, 0, At, B0); PG8_MMA(1, 1, At, B1); PG8_BAR; PG8_SCHED;
	s_add_i32 s56, s82, s34
	v_lshl_add_u64 v[200:201], v[200:201], 0, s[26:27]
	s_mov_b32 m0, s56
	ds_read_b128 v[188:191], v154 offset:49152
	ds_read_b128 v[192:195], v154 offset:50176
	ds_read_b128 v[196:199], v154 offset:51200
	ds_read_b128 v[206:209], v154 offset:52224
	ds_read_b128 v[210:213], v154 offset:53248
	ds_read_b128 v[214:217], v154 offset:54272
	ds_read_b128 v[218:221], v154 offset:55296
	ds_read_b128 v[222:225], v154 offset:56320
	global_load_lds_dwordx4 v[200:201], off
	s_add_i32 m0, s56, 0x2000
	s_add_u32 s54, s54, 0x40080
	v_lshl_add_u64 v[200:201], v[226:227], 0, s[26:27]
	s_addc_u32 s55, s55, 0
	s_add_i32 s56, s83, s34
	global_load_lds_dwordx4 v[200:201], off
	v_lshl_add_u64 v[200:201], s[54:55], 0, v[132:133]
	s_mov_b32 m0, s56
	s_nop 0
	global_load_lds_dwordx4 v[200:201], off
	v_lshl_add_u64 v[200:201], s[54:55], 0, v[128:129]
	s_add_i32 m0, s56, 0x2000
	s_nop 0
	global_load_lds_dwordx4 v[200:201], off
	s_waitcnt vmcnt(6)
	s_waitcnt lgkmcnt(0)
	s_barrier
	s_setprio 1
	s_waitcnt lgkmcnt(0)
	v_mfma_f32_16x16x32_bf16 v[60:63], v[146:149], v[188:191], v[60:63]
	v_mfma_f32_16x16x32_bf16 v[56:59], v[160:163], v[188:191], v[56:59]
	v_mfma_f32_16x16x32_bf16 v[44:47], v[146:149], v[196:199], v[44:47]
	v_mfma_f32_16x16x32_bf16 v[40:43], v[160:163], v[196:199], v[40:43]
	v_mfma_f32_16x16x32_bf16 v[28:31], v[146:149], v[210:213], v[28:31]
	v_mfma_f32_16x16x32_bf16 v[24:27], v[160:163], v[210:213], v[24:27]
	v_mfma_f32_16x16x32_bf16 v[12:15], v[146:149], v[218:221], v[12:15]
	v_mfma_f32_16x16x32_bf16 v[8:11], v[160:163], v[218:221], v[8:11]
	v_mfma_f32_16x16x32_bf16 v[60:63], v[156:159], v[192:195], v[60:63]
	v_mfma_f32_16x16x32_bf16 v[56:59], v[164:167], v[192:195], v[56:59]
	v_mfma_f32_16x16x32_bf16 v[44:47], v[156:159], v[206:209], v[44:47]
	v_mfma_f32_16x16x32_bf16 v[40:43], v[164:167], v[206:209], v[40:43]
	v_mfma_f32_16x16x32_bf16 v[28:31], v[156:159], v[214:217], v[28:31]
	v_mfma_f32_16x16x32_bf16 v[24:27], v[164:167], v[214:217], v[24:27]
	v_mfma_f32_16x16x32_bf16 v[12:15], v[156:159], v[222:225], v[12:15]
	v_lshl_add_u64 v[200:201], v[228:229], 0, s[26:27]
	s_mov_b32 m0, s63
	s_nop 0
	global_load_lds_dwordx4 v[200:201], off
	v_mfma_f32_16x16x32_bf16 v[8:11], v[164:167], v[222:225], v[8:11]
	s_setprio 0
	s_setprio 1
	v_mfma_f32_16x16x32_bf16 v[52:55], v[168:171], v[188:191], v[52:55]
	v_mfma_f32_16x16x32_bf16 v[48:51], v[180:183], v[188:191], v[48:51]
	v_mfma_f32_16x16x32_bf16 v[36:39], v[168:171], v[196:199], v[36:39]
	v_mfma_f32_16x16x32_bf16 v[32:35], v[180:183], v[196:199], v[32:35]
	v_mfma_f32_16x16x32_bf16 v[20:23], v[168:171], v[210:213], v[20:23]
	v_mfma_f32_16x16x32_bf16 v[16:19], v[180:183], v[210:213], v[16:19]
	v_mfma_f32_16x16x32_bf16 v[4:7], v[168:171], v[218:221], v[4:7]
	v_mfma_f32_16x16x32_bf16 v[0:3], v[180:183], v[218:221], v[0:3]
	v_mfma_f32_16x16x32_bf16 v[52:55], v[172:175], v[192:195], v[52:55]
	v_mfma_f32_16x16x32_bf16 v[48:51], v[184:187], v[192:195], v[48:51]
	v_mfma_f32_16x16x32_bf16 v[36:39], v[172:175], v[206:209], v[36:39]
	v_mfma_f32_16x16x32_bf16 v[32:35], v[184:187], v[206:209], v[32:35]
	v_mfma_f32_16x16x32_bf16 v[20:23], v[172:175], v[214:217], v[20:23]
	v_mfma_f32_16x16x32_bf16 v[16:19], v[184:187], v[214:217], v[16:19]
	v_mfma_f32_16x16x32_bf16 v[4:7], v[172:175], v[222:225], v[4:7]
	v_lshl_add_u64 v[200:201], v[230:231], 0, s[26:27]
	s_mov_b32 m0, s64
	s_nop 0
	global_load_lds_dwordx4 v[200:201], off
	v_mfma_f32_16x16x32_bf16 v[0:3], v[184:187], v[222:225], v[0:3]
	s_setprio 0
	s_barrier
	s_add_i32 s81, s81, 2
	s_add_u32 s52, s52, 0x100
	s_addc_u32 s53, s53, 0
	s_add_u32 s79, s79, 0x100
	s_addc_u32 s80, s80, 0
.LBB0_1681:
	ds_read_b128 v[146:149], v152
	ds_read_b128 v[156:159], v152 offset:1024
	ds_read_b128 v[160:163], v152 offset:2048
	ds_read_b128 v[164:167], v152 offset:3072
	ds_read_b128 v[168:171], v153
	ds_read_b128 v[172:175], v153 offset:1024
	ds_read_b128 v[180:183], v153 offset:2048
	ds_read_b128 v[184:187], v153 offset:3072
	s_add_u32 s54, s52, 0xfffc0080
	s_addc_u32 s55, s53, -1
	s_cmp_eq_u32 s81, 12
	s_cselect_b32 s57, s47, s55
	s_cselect_b32 s56, s77, s54
	s_cselect_b32 s55, s45, s80
	s_cselect_b32 s54, s78, s79
	v_lshl_add_u64 v[200:201], s[52:53], 0, v[136:137]
	s_add_i32 m0, s58, 0xc000
	ds_read_b128 v[188:191], v154
	ds_read_b128 v[192:195], v154 offset:1024
	ds_read_b128 v[196:199], v154 offset:2048
	ds_read_b128 v[206:209], v154 offset:3072
	ds_read_b128 v[210:213], v154 offset:4096
	ds_read_b128 v[214:217], v154 offset:5120
	ds_read_b128 v[218:221], v154 offset:6144
	ds_read_b128 v[222:225], v154 offset:7168
	global_load_lds_dwordx4 v[200:201], off
	v_lshl_add_u64 v[200:201], s[52:53], 0, v[138:139]
	s_add_i32 m0, s58, 0xe000
	s_nop 0
	global_load_lds_dwordx4 v[200:201], off
	s_waitcnt vmcnt(8)
	s_waitcnt lgkmcnt(0)
	s_barrier
; #define PG8_STAGE(bufoff, gbase, voff) do { _Pragma("unroll") for (int _i = 0; _i < 2; ++_i) \
;         __builtin_amdgcn_global_load_lds((const unsigned*)((const char*)(gbase) + (voff)[_i]), (PG8_LAS unsigned*)(lds + (bufoff) + ldsw + _i * 8192), 16, 0, 0); } while (0)
; #define PG8_LDA(dst, b, h) do { _Pragma("unroll") for (int m = 0; m < 4; ++m) _Pragma("unroll") for (int k = 0; k < 2; ++k) dst[m][k] = *(const PG8_LAS bf16x8*)(lds + PG8_SA(b, h) + aoff + m * 2048 + k * 1024); } while (0)
; #define PG8_MMA(ai, bj, At, Bt) do { __builtin_amdgcn_s_setprio(1); _Pragma("unroll") for (int m = 0; m < 4; ++m) _Pragma("unroll") for (int n = 0; n < 2; ++n) _Pragma("unroll") for (int k = 0; k < 2; ++k) \
;         acc[ai][bj][m][n] = __builtin_amdgcn_mfma_f32_16x16x32_bf16(Bt[n][k], At[m][k], acc[ai][bj][m][n], 0, 0, 0); __builtin_amdgcn_s_setprio(0); } while (0)
; #define PG8_WAIT_V(n) asm volatile("s_waitcnt vmcnt(" #n ")" ::: "memory")
; #define PG8_WAIT_L(n) asm volatile("s_waitcnt lgkmcnt(" #n ")" ::: "memory")
; #define PG8_BAR __builtin_amdgcn_s_barrier()
; #define PG8_SCHED __builtin_amdgcn_sched_barrier(0)
; template <class Epi, class Sched, bool ALIGN_EPI = false, bool SP2 = false>
; __device__ __forceinline__ void gemm_phase(PG8_LAS unsigned char* lds, const Gemm g, const Sched& S, const Epi& E) {
;     ...
;             PG8_WAIT_V(8); PG8_WAIT_L(0); PG8_BAR; PG8_MMA(0, 0, At, B0); PG8_MMA(0, 1, At, B1); PG8_BAR; PG8_SCHED;
;             PG8_LDA(At, 0, 1); PG8_STAGE(PG8_SB(0, 0), b2, voffB); PG8_STAGE(PG8_SB(0, 1), b2 + hstep, voffB); PG8_STAGE(PG8_SA(0, 0), a2, voffA);
;             PG8_WAIT_V(8); PG8_WAIT_L(0); PG8_BAR; PG8_MMA(1, 0, At, B0); PG8_MMA(1, 1, At, B1); PG8_BAR; PG8_SCHED;
	s_setprio 1
	s_waitcnt lgkmcnt(0)
	v_mfma_f32_16x16x32_bf16 v[124:127], v[146:149], v[188:191], v[124:127]
	v_mfma_f32_16x16x32_bf16 v[120:123], v[160:163], v[188:191], v[120:123]
	v_mfma_f32_16x16x32_bf16 v[108:111], v[146:149], v[196:199], v[108:111]
	v_mfma_f32_16x16x32_bf16 v[104:107], v[160:163], v[196:199], v[104:107]
	v_mfma_f32_16x16x32_bf16 v[92:95], v[146:149], v[210:213], v[92:95]
	v_mfma_f32_16x16x32_bf16 v[88:91], v[160:163], v[210:213], v[88:91]
	v_mfma_f32_16x16x32_bf16 v[76:79], v[146:149], v[218:221], v[76:79]
	v_mfma_f32_16x16x32_bf16 v[72:75], v[160:163], v[218:221], v[72:75]
	v_mfma_f32_16x16x32_bf16 v[124:127], v[156:159], v[192:195], v[124:127]
	v_mfma_f32_16x16x32_bf16 v[120:123], v[164:167], v[192:195], v[120:123]
	v_mfma_f32_16x16x32_bf16 v[108:111], v[156:159], v[206:209], v[108:111]
	v_mfma_f32_16x16x32_bf16 v[104:107], v[164:167], v[206:209], v[104:107]
	v_mfma_f32_16x16x32_bf16 v[92:95], v[156:159], v[214:217], v[92:95]
	v_mfma_f32_16x16x32_bf16 v[88:91], v[164:167], v[214:217], v[88:91]
	v_mfma_f32_16x16x32_bf16 v[76:79], v[156:159], v[222:225], v[76:79]
	v_mfma_f32_16x16x32_bf16 v[72:75], v[164:167], v[222:225], v[72:75]
	s_setprio 0
	s_setprio 1
	v_mfma_f32_16x16x32_bf16 v[116:119], v[168:171], v[188:191], v[116:119]
	v_mfma_f32_16x16x32_bf16 v[112:115], v[180:183], v[188:191], v[112:115]
	v_mfma_f32_16x16x32_bf16 v[100:103], v[168:171], v[196:199], v[100:103]
	v_mfma_f32_16x16x32_bf16 v[96:99], v[180:183], v[196:199], v[96:99]
	v_mfma_f32_16x16x32_bf16 v[84:87], v[168:171], v[210:213], v[84:87]
	v_mfma_f32_16x16x32_bf16 v[80:83], v[180:183], v[210:213], v[80:83]
	v_mfma_f32_16x16x32_bf16 v[68:71], v[168:171], v[218:221], v[68:71]
	v_mfma_f32_16x16x32_bf16 v[64:67], v[180:183], v[218:221], v[64:67]
	v_mfma_f32_16x16x32_bf16 v[116:119], v[172:175], v[192:195], v[116:119]
	v_mfma_f32_16x16x32_bf16 v[112:115], v[184:187], v[192:195], v[112:115]
	v_mfma_f32_16x16x32_bf16 v[100:103], v[172:175], v[206:209], v[100:103]
	v_mfma_f32_16x16x32_bf16 v[96:99], v[184:187], v[206:209], v[96:99]
	v_mfma_f32_16x16x32_bf16 v[84:87], v[172:175], v[214:217], v[84:87]
	v_mfma_f32_16x16x32_bf16 v[80:83], v[184:187], v[214:217], v[80:83]
	v_mfma_f32_16x16x32_bf16 v[68:71], v[172:175], v[222:225], v[68:71]
	v_mfma_f32_16x16x32_bf16 v[64:67], v[184:187], v[222:225], v[64:67]
	s_setprio 0
	s_barrier
	s_add_i32 s82, s65, s34
	v_lshl_add_u64 v[200:201], s[54:55], 0, v[132:133]
	s_mov_b32 m0, s82
	ds_read_b128 v[188:191], v154 offset:16384
	ds_read_b128 v[192:195], v154 offset:17408
	ds_read_b128 v[196:199], v154 offset:18432
	ds_read_b128 v[206:209], v154 offset:19456
	ds_read_b128 v[210:213], v154 offset:20480
	ds_read_b128 v[214:217], v154 offset:21504
	ds_read_b128 v[218:221], v154 offset:22528
	ds_read_b128 v[222:225], v154 offset:23552
	global_load_lds_dwordx4 v[200:201], off
	s_add_i32 m0, s82, 0x2000
	s_add_u32 s82, s54, 0x40000
	v_lshl_add_u64 v[226:227], s[54:55], 0, v[128:129]
	s_addc_u32 s83, s55, 0
	s_add_i32 s84, s66, s34
	global_load_lds_dwordx4 v[226:227], off
	v_lshl_add_u64 v[228:229], s[82:83], 0, v[132:133]
	s_mov_b32 m0, s84
	global_load_lds_dwordx4 v[228:229], off
	v_lshl_add_u64 v[228:229], s[82:83], 0, v[128:129]
	s_add_i32 m0, s84, 0x2000
	s_nop 0
	global_load_lds_dwordx4 v[228:229], off
	s_waitcnt vmcnt(6)
	s_waitcnt lgkmcnt(0)
	s_barrier
	s_setprio 1
	s_waitcnt lgkmcnt(0)
	v_mfma_f32_16x16x32_bf16 v[60:63], v[146:149], v[188:191], v[60:63]
	v_mfma_f32_16x16x32_bf16 v[56:59], v[160:163], v[188:191], v[56:59]
	v_mfma_f32_16x16x32_bf16 v[44:47], v[146:149], v[196:199], v[44:47]
	v_mfma_f32_16x16x32_bf16 v[40:43], v[160:163], v[196:199], v[40:43]
	v_mfma_f32_16x16x32_bf16 v[28:31], v[146:149], v[210:213], v[28:31]
	v_mfma_f32_16x16x32_bf16 v[24:27], v[160:163], v[210:213], v[24:27]
	v_mfma_f32_16x16x32_bf16 v[12:15], v[146:149], v[218:221], v[12:15]
	v_mfma_f32_16x16x32_bf16 v[8:11], v[160:163], v[218:221], v[8:11]
	v_mfma_f32_16x16x32_bf16 v[60:63], v[156:159], v[192:195], v[60:63]
	v_mfma_f32_16x16x32_bf16 v[56:59], v[164:167], v[192:195], v[56:59]
	v_mfma_f32_16x16x32_bf16 v[44:47], v[156:159], v[206:209], v[44:47]
	v_mfma_f32_16x16x32_bf16 v[40:43], v[164:167], v[206:209], v[40:43]
	v_mfma_f32_16x16x32_bf16 v[28:31], v[156:159], v[214:217], v[28:31]
	v_mfma_f32_16x16x32_bf16 v[24:27], v[164:167], v[214:217], v[24:27]
	v_mfma_f32_16x16x32_bf16 v[12:15], v[156:159], v[222:225], v[12:15]
	v_lshl_add_u64 v[228:229], s[56:57], 0, v[134:135]
	s_mov_b32 m0, s58
	s_nop 0
	global_load_lds_dwordx4 v[228:229], off
	v_mfma_f32_16x16x32_bf16 v[8:11], v[164:167], v[222:225], v[8:11]
	s_setprio 0
	s_setprio 1
	v_mfma_f32_16x16x32_bf16 v[52:55], v[168:171], v[188:191], v[52:55]
	v_mfma_f32_16x16x32_bf16 v[48:51], v[180:183], v[188:191], v[48:51]
	v_mfma_f32_16x16x32_bf16 v[36:39], v[168:171], v[196:199], v[36:39]
	v_mfma_f32_16x16x32_bf16 v[32:35], v[180:183], v[196:199], v[32:35]
	v_mfma_f32_16x16x32_bf16 v[20:23], v[168:171], v[210:213], v[20:23]
	v_mfma_f32_16x16x32_bf16 v[16:19], v[180:183], v[210:213], v[16:19]
	v_mfma_f32_16x16x32_bf16 v[4:7], v[168:171], v[218:221], v[4:7]
	v_mfma_f32_16x16x32_bf16 v[0:3], v[180:183], v[218:221], v[0:3]
	v_mfma_f32_16x16x32_bf16 v[52:55], v[172:175], v[192:195], v[52:55]
	v_mfma_f32_16x16x32_bf16 v[48:51], v[184:187], v[192:195], v[48:51]
	v_mfma_f32_16x16x32_bf16 v[36:39], v[172:175], v[206:209], v[36:39]
	v_mfma_f32_16x16x32_bf16 v[32:35], v[184:187], v[206:209], v[32:35]
	v_mfma_f32_16x16x32_bf16 v[20:23], v[172:175], v[214:217], v[20:23]
	v_mfma_f32_16x16x32_bf16 v[16:19], v[184:187], v[214:217], v[16:19]
	v_mfma_f32_16x16x32_bf16 v[4:7], v[172:175], v[222:225], v[4:7]
	v_lshl_add_u64 v[230:231], s[56:57], 0, v[130:131]
	s_mov_b32 m0, s59
	s_nop 0
	global_load_lds_dwordx4 v[230:231], off
	v_mfma_f32_16x16x32_bf16 v[0:3], v[184:187], v[222:225], v[0:3]
	s_setprio 0
	s_barrier
; #define PG8_STAGE(bufoff, gbase, voff) do { _Pragma("unroll") for (int _i = 0; _i < 2; ++_i) \
;         __builtin_amdgcn_global_load_lds((const unsigned*)((const char*)(gbase) + (voff)[_i]), (PG8_LAS unsigned*)(lds + (bufoff) + ldsw + _i * 8192), 16, 0, 0); } while (0)
; #define PG8_LDA(dst, b, h) do { _Pragma("unroll") for (int m = 0; m < 4; ++m) _Pragma("unroll") for (int k = 0; k < 2; ++k) dst[m][k] = *(const PG8_LAS bf16x8*)(lds + PG8_SA(b, h) + aoff + m * 2048 + k * 1024); } while (0)
; #define PG8_LDB(dst, b, h) do { _Pragma("unroll") for (int n = 0; n < 2; ++n) _Pragma("unroll") for (int k = 0; k < 2; ++k) dst[n][k] = *(const PG8_LAS bf16x8*)(lds + PG8_SB(b, h) + boff + n * 2048 + k * 1024); } while (0)
; #define PG8_MMA(ai, bj, At, Bt) do { __builtin_amdgcn_s_setprio(1); _Pragma("unroll") for (int m = 0; m < 4; ++m) _Pragma("unroll") for (int n = 0; n < 2; ++n) _Pragma("unroll") for (int k = 0; k < 2; ++k) \
;         acc[ai][bj][m][n] = __builtin_amdgcn_mfma_f32_16x16x32_bf16(Bt[n][k], At[m][k], acc[ai][bj][m][n], 0, 0, 0); __builtin_amdgcn_s_setprio(0); } while (0)
; #define PG8_WAIT_V(n) asm volatile("s_waitcnt vmcnt(" #n ")" ::: "memory")
; #define PG8_WAIT_L(n) asm volatile("s_waitcnt lgkmcnt(" #n ")" ::: "memory")
; #define PG8_BAR __builtin_amdgcn_s_barrier()
; #define PG8_SCHED __builtin_amdgcn_sched_barrier(0)
; template <class Epi, class Sched, bool ALIGN_EPI = false, bool SP2 = false>
; __device__ __forceinline__ void gemm_phase(PG8_LAS unsigned char* lds, const Gemm g, const Sched& S, const Epi& E) {
;     ...
;             PG8_LDB(B0, 1, 0); PG8_LDB(B1, 1, 1); PG8_SCHED; PG8_LDA(At, 1, 0); PG8_STAGE(PG8_SA(0, 1), a2 + hstep, voffA);
;             PG8_WAIT_V(8); PG8_WAIT_L(0); PG8_BAR; PG8_MMA(0, 0, At, B0); PG8_MMA(0, 1, At, B1); PG8_BAR; PG8_SCHED;
	s_add_i32 s82, 0, 0x18000
	s_add_i32 s83, 0, 0x1c000
	v_add_u32_e32 v164, s82, v150
	v_add_u32_e32 v179, s83, v150
	ds_read_b128 v[146:149], v164
	ds_read_b128 v[156:159], v164 offset:1024
	ds_read_b128 v[160:163], v164 offset:2048
	ds_read_b128 v[164:167], v164 offset:3072
	ds_read_b128 v[168:171], v179
	ds_read_b128 v[172:175], v179 offset:1024
	ds_read_b128 v[180:183], v179 offset:2048
	ds_read_b128 v[184:187], v179 offset:3072
	s_add_u32 s56, s56, 0x40000
	s_addc_u32 s57, s57, 0
	s_mov_b32 m0, s60
	v_lshl_add_u64 v[232:233], s[56:57], 0, v[134:135]
	ds_read_b128 v[188:191], v154 offset:32768
	ds_read_b128 v[192:195], v154 offset:33792
	ds_read_b128 v[196:199], v154 offset:34816
	ds_read_b128 v[206:209], v154 offset:35840
	ds_read_b128 v[210:213], v154 offset:36864
	ds_read_b128 v[214:217], v154 offset:37888
	ds_read_b128 v[218:221], v154 offset:38912
	ds_read_b128 v[222:225], v154 offset:39936
	global_load_lds_dwordx4 v[232:233], off
	v_lshl_add_u64 v[232:233], s[56:57], 0, v[130:131]
	s_mov_b32 m0, s61
	s_nop 0
	global_load_lds_dwordx4 v[232:233], off
	s_waitcnt vmcnt(8)
	s_waitcnt lgkmcnt(0)
	s_barrier
	s_setprio 1
	s_waitcnt lgkmcnt(0)
	v_mfma_f32_16x16x32_bf16 v[124:127], v[146:149], v[188:191], v[124:127]
	v_mfma_f32_16x16x32_bf16 v[120:123], v[160:163], v[188:191], v[120:123]
	v_mfma_f32_16x16x32_bf16 v[108:111], v[146:149], v[196:199], v[108:111]
	v_mfma_f32_16x16x32_bf16 v[104:107], v[160:163], v[196:199], v[104:107]
	v_mfma_f32_16x16x32_bf16 v[92:95], v[146:149], v[210:213], v[92:95]
	v_mfma_f32_16x16x32_bf16 v[88:91], v[160:163], v[210:213], v[88:91]
	v_mfma_f32_16x16x32_bf16 v[76:79], v[146:149], v[218:221], v[76:79]
	v_mfma_f32_16x16x32_bf16 v[72:75], v[160:163], v[218:221], v[72:75]
	v_mfma_f32_16x16x32_bf16 v[124:127], v[156:159], v[192:195], v[124:127]
	v_mfma_f32_16x16x32_bf16 v[120:123], v[164:167], v[192:195], v[120:123]
	v_mfma_f32_16x16x32_bf16 v[108:111], v[156:159], v[206:209], v[108:111]
	v_mfma_f32_16x16x32_bf16 v[104:107], v[164:167], v[206:209], v[104:107]
	v_mfma_f32_16x16x32_bf16 v[92:95], v[156:159], v[214:217], v[92:95]
	v_mfma_f32_16x16x32_bf16 v[88:91], v[164:167], v[214:217], v[88:91]
	v_mfma_f32_16x16x32_bf16 v[76:79], v[156:159], v[222:225], v[76:79]
	v_mfma_f32_16x16x32_bf16 v[72:75], v[164:167], v[222:225], v[72:75]
	s_setprio 0
	s_setprio 1
	v_mfma_f32_16x16x32_bf16 v[116:119], v[168:171], v[188:191], v[116:119]
	v_mfma_f32_16x16x32_bf16 v[112:115], v[180:183], v[188:191], v[112:115]
	v_mfma_f32_16x16x32_bf16 v[100:103], v[168:171], v[196:199], v[100:103]
	v_mfma_f32_16x16x32_bf16 v[96:99], v[180:183], v[196:199], v[96:99]
	v_mfma_f32_16x16x32_bf16 v[84:87], v[168:171], v[210:213], v[84:87]
	v_mfma_f32_16x16x32_bf16 v[80:83], v[180:183], v[210:213], v[80:83]
	v_mfma_f32_16x16x32_bf16 v[68:71], v[168:171], v[218:221], v[68:71]
	v_mfma_f32_16x16x32_bf16 v[64:67], v[180:183], v[218:221], v[64:67]
	v_mfma_f32_16x16x32_bf16 v[116:119], v[172:175], v[192:195], v[116:119]
	v_mfma_f32_16x16x32_bf16 v[112:115], v[184:187], v[192:195], v[112:115]
	v_mfma_f32_16x16x32_bf16 v[100:103], v[172:175], v[206:209], v[100:103]
	v_mfma_f32_16x16x32_bf16 v[96:99], v[184:187], v[206:209], v[96:99]
	v_mfma_f32_16x16x32_bf16 v[84:87], v[172:175], v[214:217], v[84:87]
	v_mfma_f32_16x16x32_bf16 v[80:83], v[184:187], v[214:217], v[80:83]
	v_mfma_f32_16x16x32_bf16 v[68:71], v[172:175], v[222:225], v[68:71]
	v_mfma_f32_16x16x32_bf16 v[64:67], v[184:187], v[222:225], v[64:67]
	s_setprio 0
	s_barrier
; #define PG8_STAGE(bufoff, gbase, voff) do { _Pragma("unroll") for (int _i = 0; _i < 2; ++_i) \
;         __builtin_amdgcn_global_load_lds((const unsigned*)((const char*)(gbase) + (voff)[_i]), (PG8_LAS unsigned*)(lds + (bufoff) + ldsw + _i * 8192), 16, 0, 0); } while (0)
; #define PG8_LDA(dst, b, h) do { _Pragma("unroll") for (int m = 0; m < 4; ++m) _Pragma("unroll") for (int k = 0; k < 2; ++k) dst[m][k] = *(const PG8_LAS bf16x8*)(lds + PG8_SA(b, h) + aoff + m * 2048 + k * 1024); } while (0)
; #define PG8_MMA(ai, bj, At, Bt) do { __builtin_amdgcn_s_setprio(1); _Pragma("unroll") for (int m = 0; m < 4; ++m) _Pragma("unroll") for (int n = 0; n < 2; ++n) _Pragma("unroll") for (int k = 0; k < 2; ++k) \
;         acc[ai][bj][m][n] = __builtin_amdgcn_mfma_f32_16x16x32_bf16(Bt[n][k], At[m][k], acc[ai][bj][m][n], 0, 0, 0); __builtin_amdgcn_s_setprio(0); } while (0)
; #define PG8_WAIT_V(n) asm volatile("s_waitcnt vmcnt(" #n ")" ::: "memory")
; #define PG8_WAIT_L(n) asm volatile("s_waitcnt lgkmcnt(" #n ")" ::: "memory")
; #define PG8_BAR __builtin_amdgcn_s_barrier()
; #define PG8_SCHED __builtin_amdgcn_sched_barrier(0)
; template <class Epi, class Sched, bool ALIGN_EPI = false, bool SP2 = false>
; __device__ __forceinline__ void gemm_phase(PG8_LAS unsigned char* lds, const Gemm g, const Sched& S, const Epi& E) {
;     ...
;         for (int t = 0; t < nt; t += 2) {
;     ...
;             PG8_LDA(At, 1, 1); PG8_STAGE(PG8_SB(1, 0), b3, voffB); PG8_STAGE(PG8_SB(1, 1), b3 + hstep, voffB); PG8_STAGE(PG8_SA(1, 0), a3, voffA);
;             PG8_WAIT_V(8); PG8_WAIT_L(0); PG8_BAR; PG8_MMA(1, 0, At, B0); PG8_MMA(1, 1, At, B1); PG8_BAR; PG8_SCHED;
	s_add_i32 s56, s82, s34
	v_lshl_add_u64 v[200:201], v[200:201], 0, s[26:27]
	s_mov_b32 m0, s56
	ds_read_b128 v[188:191], v154 offset:49152
	ds_read_b128 v[192:195], v154 offset:50176
	ds_read_b128 v[196:199], v154 offset:51200
	ds_read_b128 v[206:209], v154 offset:52224
	ds_read_b128 v[210:213], v154 offset:53248
	ds_read_b128 v[214:217], v154 offset:54272
	ds_read_b128 v[218:221], v154 offset:55296
	ds_read_b128 v[222:225], v154 offset:56320
	global_load_lds_dwordx4 v[200:201], off
	s_add_i32 m0, s56, 0x2000
	s_add_u32 s54, s54, 0x40080
	v_lshl_add_u64 v[200:201], v[226:227], 0, s[26:27]
	s_addc_u32 s55, s55, 0
	s_add_i32 s56, s83, s34
	global_load_lds_dwordx4 v[200:201], off
	v_lshl_add_u64 v[200:201], s[54:55], 0, v[132:133]
	s_mov_b32 m0, s56
	s_nop 0
	global_load_lds_dwordx4 v[200:201], off
	v_lshl_add_u64 v[200:201], s[54:55], 0, v[128:129]
	s_add_i32 m0, s56, 0x2000
	s_nop 0
	global_load_lds_dwordx4 v[200:201], off
	s_waitcnt vmcnt(6)
	s_waitcnt lgkmcnt(0)
	s_barrier
	s_setprio 1
	s_waitcnt lgkmcnt(0)
	v_mfma_f32_16x16x32_bf16 v[60:63], v[146:149], v[188:191], v[60:63]
	v_mfma_f32_16x16x32_bf16 v[56:59], v[160:163], v[188:191], v[56:59]
	v_mfma_f32_16x16x32_bf16 v[44:47], v[146:149], v[196:199], v[44:47]
	v_mfma_f32_16x16x32_bf16 v[40:43], v[160:163], v[196:199], v[40:43]
	v_mfma_f32_16x16x32_bf16 v[28:31], v[146:149], v[210:213], v[28:31]
	v_mfma_f32_16x16x32_bf16 v[24:27], v[160:163], v[210:213], v[24:27]
	v_mfma_f32_16x16x32_bf16 v[12:15], v[146:149], v[218:221], v[12:15]
	v_mfma_f32_16x16x32_bf16 v[8:11], v[160:163], v[218:221], v[8:11]
	v_mfma_f32_16x16x32_bf16 v[60:63], v[156:159], v[192:195], v[60:63]
	v_mfma_f32_16x16x32_bf16 v[56:59], v[164:167], v[192:195], v[56:59]
	v_mfma_f32_16x16x32_bf16 v[44:47], v[156:159], v[206:209], v[44:47]
	v_mfma_f32_16x16x32_bf16 v[40:43], v[164:167], v[206:209], v[40:43]
	v_mfma_f32_16x16x32_bf16 v[28:31], v[156:159], v[214:217], v[28:31]
	v_mfma_f32_16x16x32_bf16 v[24:27], v[164:167], v[214:217], v[24:27]
	v_mfma_f32_16x16x32_bf16 v[12:15], v[156:159], v[222:225], v[12:15]
	v_lshl_add_u64 v[200:201], v[228:229], 0, s[26:27]
	s_mov_b32 m0, s63
	s_nop 0
	global_load_lds_dwordx4 v[200:201], off
	v_mfma_f32_16x16x32_bf16 v[8:11], v[164:167], v[222:225], v[8:11]
	s_setprio 0
	s_setprio 1
	v_mfma_f32_16x16x32_bf16 v[52:55], v[168:171], v[188:191], v[52:55]
	v_mfma_f32_16x16x32_bf16 v[48:51], v[180:183], v[188:191], v[48:51]
	v_mfma_f32_16x16x32_bf16 v[36:39], v[168:171], v[196:199], v[36:39]
	v_mfma_f32_16x16x32_bf16 v[32:35], v[180:183], v[196:199], v[32:35]
	v_mfma_f32_16x16x32_bf16 v[20:23], v[168:171], v[210:213], v[20:23]
	v_mfma_f32_16x16x32_bf16 v[16:19], v[180:183], v[210:213], v[16:19]
	v_mfma_f32_16x16x32_bf16 v[4:7], v[168:171], v[218:221], v[4:7]
	v_mfma_f32_16x16x32_bf16 v[0:3], v[180:183], v[218:221], v[0:3]
	v_mfma_f32_16x16x32_bf16 v[52:55], v[172:175], v[192:195], v[52:55]
	v_mfma_f32_16x16x32_bf16 v[48:51], v[184:187], v[192:195], v[48:51]
	v_mfma_f32_16x16x32_bf16 v[36:39], v[172:175], v[206:209], v[36:39]
	v_mfma_f32_16x16x32_bf16 v[32:35], v[184:187], v[206:209], v[32:35]
	v_mfma_f32_16x16x32_bf16 v[20:23], v[172:175], v[214:217], v[20:23]
	v_mfma_f32_16x16x32_bf16 v[16:19], v[184:187], v[214:217], v[16:19]
	v_mfma_f32_16x16x32_bf16 v[4:7], v[172:175], v[222:225], v[4:7]
	v_lshl_add_u64 v[200:201], v[230:231], 0, s[26:27]
	s_mov_b32 m0, s64
	s_nop 0
	global_load_lds_dwordx4 v[200:201], off
	v_mfma_f32_16x16x32_bf16 v[0:3], v[184:187], v[222:225], v[0:3]
	s_setprio 0
	s_barrier
	s_add_i32 s81, s81, 2
	s_add_u32 s52, s52, 0x100
	s_addc_u32 s53, s53, 0
	s_add_u32 s79, s79, 0x100
	s_addc_u32 s80, s80, 0
	s_cmp_gt_u32 s81, 13
	s_cbranch_scc0 .LBB0_1681
	s_and_b64 vcc, exec, s[28:29]
	s_cbranch_vccz .LBB0_1684
	s_barrier

; #define PG8_STAGE(bufoff, gbase, voff) do { _Pragma("unroll") for (int _i = 0; _i < 2; ++_i) \
;         __builtin_amdgcn_global_load_lds((const unsigned*)((const char*)(gbase) + (voff)[_i]), (PG8_LAS unsigned*)(lds + (bufoff) + ldsw + _i * 8192), 16, 0, 0); } while (0)
; #define PG8_LDA(dst, b, h) do { _Pragma("unroll") for (int m = 0; m < 4; ++m) _Pragma("unroll") for (int k = 0; k < 2; ++k) dst[m][k] = *(const PG8_LAS bf16x8*)(lds + PG8_SA(b, h) + aoff + m * 2048 + k * 1024); } while (0)
; #define PG8_LDB(dst, b, h) do { _Pragma("unroll") for (int n = 0; n < 2; ++n) _Pragma("unroll") for (int k = 0; k < 2; ++k) dst[n][k] = *(const PG8_LAS bf16x8*)(lds + PG8_SB(b, h) + boff + n * 2048 + k * 1024); } while (0)
; #define PG8_MMA(ai, bj, At, Bt) do { __builtin_amdgcn_s_setprio(1); _Pragma("unroll") for (int m = 0; m < 4; ++m) _Pragma("unroll") for (int n = 0; n < 2; ++n) _Pragma("unroll") for (int k = 0; k < 2; ++k) \
;         acc[ai][bj][m][n] = __builtin_amdgcn_mfma_f32_16x16x32_bf16(Bt[n][k], At[m][k], acc[ai][bj][m][n], 0, 0, 0); __builtin_amdgcn_s_setprio(0); } while (0)
; #define PG8_BAR __builtin_amdgcn_s_barrier()
; template <class Epi, class Sched, bool ALIGN_EPI = false, bool SP2 = false>
; __device__ __forceinline__ void gemm_phase(PG8_LAS unsigned char* lds, const Gemm g, const Sched& S, const Epi& E) {
;     ...
;         const bool has_next = S.next(ui + 1, nxt);
;         const char* nA = has_next ? (const char*)g.A + (size_t)nxt.pm * tstep : cA; const char* nB = has_next ? (const char*)g.Bt + (size_t)nxt.pn * tstep : cB;
;         for (int t = 0; t < nt; t += 2) {
;             const bool last = (t == nt - 2);
;             const char* a1 = cA + (size_t)(t + 1) * kstep;
;             const char* a2 = last ? nA : cA + (size_t)(t + 2) * kstep; const char* b2 = last ? nB : cB + (size_t)(t + 2) * kstep;
;             const char* a3 = a2 + kstep; const char* b3 = b2 + kstep;
;             if (last && has_next) S.a_ready(nxt);
;             if constexpr (SP2) {
;             PG8_LDB(B0, 0, 0); PG8_LDB(B1, 0, 1); PG8_SCHED; PG8_LDA(At, 0, 0); PG8_STAGE(PG8_SA(1, 1), a1 + hstep, voffA);
;             PG8_WAIT_V(8); PG8_WAIT_L(0); PG8_BAR; PG8_MMA(0, 0, At, B0); PG8_MMA(0, 1, At, B1); PG8_BAR; PG8_SCHED;
;             PG8_LDA(At, 0, 1); PG8_STAGE(PG8_SB(0, 0), b2, voffB); PG8_STAGE(PG8_SB(0, 1), b2 + hstep, voffB); PG8_STAGE(PG8_SA(0, 0), a2, voffA);
.LBB0_1815:
	s_ashr_i32 s29, s28, 31
	s_lshl_b64 s[36:37], s[28:29], 18
	s_add_u32 s36, s92, s36
	s_addc_u32 s37, s93, s37
	s_and_b64 s[38:39], s[6:7], exec
	s_cselect_b32 s29, s37, s45
	s_cselect_b32 s41, s36, s44
	s_ashr_i32 s27, s26, 31
	s_lshl_b64 s[38:39], s[26:27], 18
	s_add_u32 s38, s3, s38
	s_addc_u32 s39, s14, s39
	s_and_b64 s[48:49], s[6:7], exec
	s_cselect_b32 s27, s39, s47
	s_cselect_b32 s58, s38, s46
	s_add_u32 s44, s44, 0x20080
	s_addc_u32 s45, s45, 0
	s_add_u32 s59, s46, 0x100
	s_addc_u32 s60, s47, 0
	s_mov_b32 s61, -2
	s_waitcnt lgkmcnt(0)
	ds_read_b128 v[144:147], v151
	ds_read_b128 v[156:159], v151 offset:1024
	ds_read_b128 v[160:163], v151 offset:2048
	ds_read_b128 v[164:167], v151 offset:3072
	ds_read_b128 v[168:171], v152
	ds_read_b128 v[172:175], v152 offset:1024
	ds_read_b128 v[176:179], v152 offset:2048
	ds_read_b128 v[180:183], v152 offset:3072
	s_add_u32 s46, s44, 0xfffe0080
	s_addc_u32 s47, s45, -1
	s_cmp_eq_u32 s61, 4
	s_cselect_b32 s49, s29, s47
	s_cselect_b32 s48, s41, s46
	s_cselect_b32 s47, s27, s60
	s_cselect_b32 s46, s58, s59
	v_lshl_add_u64 v[218:219], s[44:45], 0, v[136:137]
	s_add_i32 m0, s33, 0xc000
	ds_read_b128 v[184:187], v153
	ds_read_b128 v[188:191], v153 offset:1024
	ds_read_b128 v[192:195], v153 offset:2048
	ds_read_b128 v[196:199], v153 offset:3072
	ds_read_b128 v[200:203], v153 offset:4096
	ds_read_b128 v[206:209], v153 offset:5120
	ds_read_b128 v[210:213], v153 offset:6144
	ds_read_b128 v[214:217], v153 offset:7168
	global_load_lds_dwordx4 v[218:219], off
	v_lshl_add_u64 v[218:219], s[44:45], 0, v[138:139]
	s_add_i32 m0, s33, 0xe000
	s_nop 0
	global_load_lds_dwordx4 v[218:219], off
	s_waitcnt vmcnt(8)
	s_waitcnt lgkmcnt(0)
	s_barrier
	s_setprio 1
	s_waitcnt lgkmcnt(0)
	v_mfma_f32_16x16x32_bf16 v[124:127], v[144:147], v[184:187], 0
	v_mfma_f32_16x16x32_bf16 v[120:123], v[160:163], v[184:187], 0
	v_mfma_f32_16x16x32_bf16 v[108:111], v[144:147], v[192:195], 0
	v_mfma_f32_16x16x32_bf16 v[104:107], v[160:163], v[192:195], 0
	v_mfma_f32_16x16x32_bf16 v[92:95], v[144:147], v[200:203], 0
	v_mfma_f32_16x16x32_bf16 v[88:91], v[160:163], v[200:203], 0
	v_mfma_f32_16x16x32_bf16 v[76:79], v[144:147], v[210:213], 0
	v_mfma_f32_16x16x32_bf16 v[72:75], v[160:163], v[210:213], 0
	v_mfma_f32_16x16x32_bf16 v[124:127], v[156:159], v[188:191], v[124:127]
	v_mfma_f32_16x16x32_bf16 v[120:123], v[164:167], v[188:191], v[120:123]
	v_mfma_f32_16x16x32_bf16 v[108:111], v[156:159], v[196:199], v[108:111]
	v_mfma_f32_16x16x32_bf16 v[104:107], v[164:167], v[196:199], v[104:107]
	v_mfma_f32_16x16x32_bf16 v[92:95], v[156:159], v[206:209], v[92:95]
	v_mfma_f32_16x16x32_bf16 v[88:91], v[164:167], v[206:209], v[88:91]
	v_mfma_f32_16x16x32_bf16 v[76:79], v[156:159], v[214:217], v[76:79]
	v_mfma_f32_16x16x32_bf16 v[72:75], v[164:167], v[214:217], v[72:75]
	s_setprio 0
	s_setprio 1
	v_mfma_f32_16x16x32_bf16 v[116:119], v[168:171], v[184:187], 0
	v_mfma_f32_16x16x32_bf16 v[112:115], v[176:179], v[184:187], 0
	v_mfma_f32_16x16x32_bf16 v[100:103], v[168:171], v[192:195], 0
	v_mfma_f32_16x16x32_bf16 v[96:99], v[176:179], v[192:195], 0
	v_mfma_f32_16x16x32_bf16 v[84:87], v[168:171], v[200:203], 0
	v_mfma_f32_16x16x32_bf16 v[80:83], v[176:179], v[200:203], 0
	v_mfma_f32_16x16x32_bf16 v[68:71], v[168:171], v[210:213], 0
	v_mfma_f32_16x16x32_bf16 v[64:67], v[176:179], v[210:213], 0
	v_mfma_f32_16x16x32_bf16 v[116:119], v[172:175], v[188:191], v[116:119]
	v_mfma_f32_16x16x32_bf16 v[112:115], v[180:183], v[188:191], v[112:115]
	v_mfma_f32_16x16x32_bf16 v[100:103], v[172:175], v[196:199], v[100:103]
	v_mfma_f32_16x16x32_bf16 v[96:99], v[180:183], v[196:199], v[96:99]
	v_mfma_f32_16x16x32_bf16 v[84:87], v[172:175], v[206:209], v[84:87]
	v_mfma_f32_16x16x32_bf16 v[80:83], v[180:183], v[206:209], v[80:83]
	v_mfma_f32_16x16x32_bf16 v[68:71], v[172:175], v[214:217], v[68:71]
	v_mfma_f32_16x16x32_bf16 v[64:67], v[180:183], v[214:217], v[64:67]
	s_setprio 0
	s_barrier
	s_add_i32 s62, s54, s15
	v_lshl_add_u64 v[218:219], s[46:47], 0, v[130:131]
	s_mov_b32 m0, s62
	ds_read_b128 v[184:187], v153 offset:16384
	ds_read_b128 v[188:191], v153 offset:17408
	ds_read_b128 v[192:195], v153 offset:18432
	ds_read_b128 v[196:199], v153 offset:19456
	ds_read_b128 v[200:203], v153 offset:20480
	ds_read_b128 v[206:209], v153 offset:21504
	ds_read_b128 v[210:213], v153 offset:22528
	ds_read_b128 v[214:217], v153 offset:23552
	global_load_lds_dwordx4 v[218:219], off
	s_add_i32 m0, s62, 0x2000
	s_add_u32 s62, s46, 0x20000
	v_lshl_add_u64 v[220:221], s[46:47], 0, v[134:135]
	s_addc_u32 s63, s47, 0
	s_add_i32 s64, s55, s15
	global_load_lds_dwordx4 v[220:221], off
	v_lshl_add_u64 v[222:223], s[62:63], 0, v[130:131]
	s_mov_b32 m0, s64
	global_load_lds_dwordx4 v[222:223], off
	v_lshl_add_u64 v[222:223], s[62:63], 0, v[134:135]
	s_add_i32 m0, s64, 0x2000
	s_nop 0
	global_load_lds_dwordx4 v[222:223], off
	s_waitcnt vmcnt(6)
	s_waitcnt lgkmcnt(0)
	s_barrier
; #define PG8_STAGE(bufoff, gbase, voff) do { _Pragma("unroll") for (int _i = 0; _i < 2; ++_i) \
;         __builtin_amdgcn_global_load_lds((const unsigned*)((const char*)(gbase) + (voff)[_i]), (PG8_LAS unsigned*)(lds + (bufoff) + ldsw + _i * 8192), 16, 0, 0); } while (0)
; #define PG8_LDA(dst, b, h) do { _Pragma("unroll") for (int m = 0; m < 4; ++m) _Pragma("unroll") for (int k = 0; k < 2; ++k) dst[m][k] = *(const PG8_LAS bf16x8*)(lds + PG8_SA(b, h) + aoff + m * 2048 + k * 1024); } while (0)
; #define PG8_LDB(dst, b, h) do { _Pragma("unroll") for (int n = 0; n < 2; ++n) _Pragma("unroll") for (int k = 0; k < 2; ++k) dst[n][k] = *(const PG8_LAS bf16x8*)(lds + PG8_SB(b, h) + boff + n * 2048 + k * 1024); } while (0)
; #define PG8_MMA(ai, bj, At, Bt) do { __builtin_amdgcn_s_setprio(1); _Pragma("unroll") for (int m = 0; m < 4; ++m) _Pragma("unroll") for (int n = 0; n < 2; ++n) _Pragma("unroll") for (int k = 0; k < 2; ++k) \
;         acc[ai][bj][m][n] = __builtin_amdgcn_mfma_f32_16x16x32_bf16(Bt[n][k], At[m][k], acc[ai][bj][m][n], 0, 0, 0); __builtin_amdgcn_s_setprio(0); } while (0)
; #define PG8_WAIT_V(n) asm volatile("s_waitcnt vmcnt(" #n ")" ::: "memory")
; #define PG8_WAIT_L(n) asm volatile("s_waitcnt lgkmcnt(" #n ")" ::: "memory")
; #define PG8_BAR __builtin_amdgcn_s_barrier()
; #define PG8_SCHED __builtin_amdgcn_sched_barrier(0)
; template <class Epi, class Sched, bool ALIGN_EPI = false, bool SP2 = false>
; __device__ __forceinline__ void gemm_phase(PG8_LAS unsigned char* lds, const Gemm g, const Sched& S, const Epi& E) {
;     ...
;             PG8_WAIT_V(8); PG8_WAIT_L(0); PG8_BAR; PG8_MMA(0, 0, At, B0); PG8_MMA(0, 1, At, B1); PG8_BAR; PG8_SCHED;
;             PG8_LDA(At, 0, 1); PG8_STAGE(PG8_SB(0, 0), b2, voffB); PG8_STAGE(PG8_SB(0, 1), b2 + hstep, voffB); PG8_STAGE(PG8_SA(0, 0), a2, voffA);
;             PG8_WAIT_V(8); PG8_WAIT_L(0); PG8_BAR; PG8_MMA(1, 0, At, B0); PG8_MMA(1, 1, At, B1); PG8_BAR; PG8_SCHED;
;             PG8_LDB(B0, 1, 0); PG8_LDB(B1, 1, 1); PG8_SCHED; PG8_LDA(At, 1, 0); PG8_STAGE(PG8_SA(0, 1), a2 + hstep, voffA);
;             PG8_WAIT_V(8); PG8_WAIT_L(0); PG8_BAR; PG8_MMA(0, 0, At, B0); PG8_MMA(0, 1, At, B1); PG8_BAR; PG8_SCHED;
	s_setprio 1
	s_waitcnt lgkmcnt(0)
	v_mfma_f32_16x16x32_bf16 v[60:63], v[144:147], v[184:187], 0
	v_mfma_f32_16x16x32_bf16 v[56:59], v[160:163], v[184:187], 0
	v_mfma_f32_16x16x32_bf16 v[44:47], v[144:147], v[192:195], 0
	v_mfma_f32_16x16x32_bf16 v[40:43], v[160:163], v[192:195], 0
	v_mfma_f32_16x16x32_bf16 v[28:31], v[144:147], v[200:203], 0
	v_mfma_f32_16x16x32_bf16 v[24:27], v[160:163], v[200:203], 0
	v_mfma_f32_16x16x32_bf16 v[12:15], v[144:147], v[210:213], 0
	v_mfma_f32_16x16x32_bf16 v[8:11], v[160:163], v[210:213], 0
	v_mfma_f32_16x16x32_bf16 v[60:63], v[156:159], v[188:191], v[60:63]
	v_mfma_f32_16x16x32_bf16 v[56:59], v[164:167], v[188:191], v[56:59]
	v_mfma_f32_16x16x32_bf16 v[44:47], v[156:159], v[196:199], v[44:47]
	v_mfma_f32_16x16x32_bf16 v[40:43], v[164:167], v[196:199], v[40:43]
	v_mfma_f32_16x16x32_bf16 v[28:31], v[156:159], v[206:209], v[28:31]
	v_mfma_f32_16x16x32_bf16 v[24:27], v[164:167], v[206:209], v[24:27]
	v_mfma_f32_16x16x32_bf16 v[12:15], v[156:159], v[214:217], v[12:15]
	v_lshl_add_u64 v[222:223], s[48:49], 0, v[128:129]
	s_mov_b32 m0, s33
	s_nop 0
	global_load_lds_dwordx4 v[222:223], off
	v_mfma_f32_16x16x32_bf16 v[8:11], v[164:167], v[214:217], v[8:11]
	s_setprio 0
	s_setprio 1
	v_mfma_f32_16x16x32_bf16 v[52:55], v[168:171], v[184:187], 0
	v_mfma_f32_16x16x32_bf16 v[48:51], v[176:179], v[184:187], 0
	v_mfma_f32_16x16x32_bf16 v[36:39], v[168:171], v[192:195], 0
	v_mfma_f32_16x16x32_bf16 v[32:35], v[176:179], v[192:195], 0
	v_mfma_f32_16x16x32_bf16 v[20:23], v[168:171], v[200:203], 0
	v_mfma_f32_16x16x32_bf16 v[16:19], v[176:179], v[200:203], 0
	v_mfma_f32_16x16x32_bf16 v[4:7], v[168:171], v[210:213], 0
	v_mfma_f32_16x16x32_bf16 v[0:3], v[176:179], v[210:213], 0
	v_mfma_f32_16x16x32_bf16 v[52:55], v[172:175], v[188:191], v[52:55]
	v_mfma_f32_16x16x32_bf16 v[48:51], v[180:183], v[188:191], v[48:51]
	v_mfma_f32_16x16x32_bf16 v[36:39], v[172:175], v[196:199], v[36:39]
	v_mfma_f32_16x16x32_bf16 v[32:35], v[180:183], v[196:199], v[32:35]
	v_mfma_f32_16x16x32_bf16 v[20:23], v[172:175], v[206:209], v[20:23]
	v_mfma_f32_16x16x32_bf16 v[16:19], v[180:183], v[206:209], v[16:19]
	v_mfma_f32_16x16x32_bf16 v[4:7], v[172:175], v[214:217], v[4:7]
	v_lshl_add_u64 v[224:225], s[48:49], 0, v[132:133]
	s_mov_b32 m0, s34
	s_nop 0
	global_load_lds_dwordx4 v[224:225], off
	v_mfma_f32_16x16x32_bf16 v[0:3], v[180:183], v[214:217], v[0:3]
	s_setprio 0
	s_barrier
	s_add_i32 s62, 0, 0x18000
	v_add_u32_e32 v155, s62, v149
	s_add_i32 s63, 0, 0x1c000
	ds_read_b128 v[144:147], v155
	ds_read_b128 v[156:159], v155 offset:1024
	ds_read_b128 v[160:163], v155 offset:2048
	ds_read_b128 v[164:167], v155 offset:3072
	v_add_u32_e32 v155, s63, v149
	ds_read_b128 v[168:171], v155
	ds_read_b128 v[172:175], v155 offset:1024
	ds_read_b128 v[176:179], v155 offset:2048
	ds_read_b128 v[180:183], v155 offset:3072
	s_add_u32 s48, s48, 0x20000
	s_addc_u32 s49, s49, 0
	s_mov_b32 m0, s43
	v_lshl_add_u64 v[226:227], s[48:49], 0, v[128:129]
	ds_read_b128 v[184:187], v153 offset:32768
	ds_read_b128 v[188:191], v153 offset:33792
	ds_read_b128 v[192:195], v153 offset:34816
	ds_read_b128 v[196:199], v153 offset:35840
	ds_read_b128 v[200:203], v153 offset:36864
	ds_read_b128 v[206:209], v153 offset:37888
	ds_read_b128 v[210:213], v153 offset:38912
	ds_read_b128 v[214:217], v153 offset:39936
	global_load_lds_dwordx4 v[226:227], off
	v_lshl_add_u64 v[226:227], s[48:49], 0, v[132:133]
	s_mov_b32 m0, s50
	s_nop 0
	global_load_lds_dwordx4 v[226:227], off
	s_waitcnt vmcnt(8)
	s_waitcnt lgkmcnt(0)
	s_barrier
	s_setprio 1
	s_waitcnt lgkmcnt(0)
	v_mfma_f32_16x16x32_bf16 v[124:127], v[144:147], v[184:187], v[124:127]
	v_mfma_f32_16x16x32_bf16 v[120:123], v[160:163], v[184:187], v[120:123]
	v_mfma_f32_16x16x32_bf16 v[108:111], v[144:147], v[192:195], v[108:111]
	v_mfma_f32_16x16x32_bf16 v[104:107], v[160:163], v[192:195], v[104:107]
	v_mfma_f32_16x16x32_bf16 v[92:95], v[144:147], v[200:203], v[92:95]
	v_mfma_f32_16x16x32_bf16 v[88:91], v[160:163], v[200:203], v[88:91]
	v_mfma_f32_16x16x32_bf16 v[76:79], v[144:147], v[210:213], v[76:79]
	v_mfma_f32_16x16x32_bf16 v[72:75], v[160:163], v[210:213], v[72:75]
	v_mfma_f32_16x16x32_bf16 v[124:127], v[156:159], v[188:191], v[124:127]
	v_mfma_f32_16x16x32_bf16 v[120:123], v[164:167], v[188:191], v[120:123]
	v_mfma_f32_16x16x32_bf16 v[108:111], v[156:159], v[196:199], v[108:111]
	v_mfma_f32_16x16x32_bf16 v[104:107], v[164:167], v[196:199], v[104:107]
	v_mfma_f32_16x16x32_bf16 v[92:95], v[156:159], v[206:209], v[92:95]
	v_mfma_f32_16x16x32_bf16 v[88:91], v[164:167], v[206:209], v[88:91]
	v_mfma_f32_16x16x32_bf16 v[76:79], v[156:159], v[214:217], v[76:79]
	v_mfma_f32_16x16x32_bf16 v[72:75], v[164:167], v[214:217], v[72:75]
	s_setprio 0
	s_setprio 1
	v_mfma_f32_16x16x32_bf16 v[116:119], v[168:171], v[184:187], v[116:119]
	v_mfma_f32_16x16x32_bf16 v[112:115], v[176:179], v[184:187], v[112:115]
	v_mfma_f32_16x16x32_bf16 v[100:103], v[168:171], v[192:195], v[100:103]
	v_mfma_f32_16x16x32_bf16 v[96:99], v[176:179], v[192:195], v[96:99]
	v_mfma_f32_16x16x32_bf16 v[84:87], v[168:171], v[200:203], v[84:87]
	v_mfma_f32_16x16x32_bf16 v[80:83], v[176:179], v[200:203], v[80:83]
	v_mfma_f32_16x16x32_bf16 v[68:71], v[168:171], v[210:213], v[68:71]
	v_mfma_f32_16x16x32_bf16 v[64:67], v[176:179], v[210:213], v[64:67]
	v_mfma_f32_16x16x32_bf16 v[116:119], v[172:175], v[188:191], v[116:119]
	v_mfma_f32_16x16x32_bf16 v[112:115], v[180:183], v[188:191], v[112:115]
	v_mfma_f32_16x16x32_bf16 v[100:103], v[172:175], v[196:199], v[100:103]
	v_mfma_f32_16x16x32_bf16 v[96:99], v[180:183], v[196:199], v[96:99]
	v_mfma_f32_16x16x32_bf16 v[84:87], v[172:175], v[206:209], v[84:87]
	v_mfma_f32_16x16x32_bf16 v[80:83], v[180:183], v[206:209], v[80:83]
	v_mfma_f32_16x16x32_bf16 v[68:71], v[172:175], v[214:217], v[68:71]
	v_mfma_f32_16x16x32_bf16 v[64:67], v[180:183], v[214:217], v[64:67]
	s_setprio 0
	s_barrier
; #define PG8_STAGE(bufoff, gbase, voff) do { _Pragma("unroll") for (int _i = 0; _i < 2; ++_i) \
;         __builtin_amdgcn_global_load_lds((const unsigned*)((const char*)(gbase) + (voff)[_i]), (PG8_LAS unsigned*)(lds + (bufoff) + ldsw + _i * 8192), 16, 0, 0); } while (0)
; #define PG8_LDA(dst, b, h) do { _Pragma("unroll") for (int m = 0; m < 4; ++m) _Pragma("unroll") for (int k = 0; k < 2; ++k) dst[m][k] = *(const PG8_LAS bf16x8*)(lds + PG8_SA(b, h) + aoff + m * 2048 + k * 1024); } while (0)
; #define PG8_LDB(dst, b, h) do { _Pragma("unroll") for (int n = 0; n < 2; ++n) _Pragma("unroll") for (int k = 0; k < 2; ++k) dst[n][k] = *(const PG8_LAS bf16x8*)(lds + PG8_SB(b, h) + boff + n * 2048 + k * 1024); } while (0)
; #define PG8_MMA(ai, bj, At, Bt) do { __builtin_amdgcn_s_setprio(1); _Pragma("unroll") for (int m = 0; m < 4; ++m) _Pragma("unroll") for (int n = 0; n < 2; ++n) _Pragma("unroll") for (int k = 0; k < 2; ++k) \
;         acc[ai][bj][m][n] = __builtin_amdgcn_mfma_f32_16x16x32_bf16(Bt[n][k], At[m][k], acc[ai][bj][m][n], 0, 0, 0); __builtin_amdgcn_s_setprio(0); } while (0)
; #define PG8_WAIT_V(n) asm volatile("s_waitcnt vmcnt(" #n ")" ::: "memory")
; template <class Epi, class Sched, bool ALIGN_EPI = false, bool SP2 = false>
; __device__ __forceinline__ void gemm_phase(PG8_LAS unsigned char* lds, const Gemm g, const Sched& S, const Epi& E) {
;     ...
;             PG8_LDB(B0, 0, 0); PG8_LDB(B1, 0, 1); PG8_SCHED; PG8_LDA(At, 0, 0); PG8_STAGE(PG8_SA(1, 1), a1 + hstep, voffA);
;             PG8_WAIT_V(8); PG8_WAIT_L(0); PG8_BAR; PG8_MMA(0, 0, At, B0); PG8_MMA(0, 1, At, B1); PG8_BAR; PG8_SCHED;
;             PG8_LDA(At, 0, 1); PG8_STAGE(PG8_SB(0, 0), b2, voffB); PG8_STAGE(PG8_SB(0, 1), b2 + hstep, voffB); PG8_STAGE(PG8_SA(0, 0), a2, voffA);
;             PG8_WAIT_V(8); PG8_WAIT_L(0); PG8_BAR; PG8_MMA(1, 0, At, B0); PG8_MMA(1, 1, At, B1); PG8_BAR; PG8_SCHED;
;             PG8_LDB(B0, 1, 0); PG8_LDB(B1, 1, 1); PG8_SCHED; PG8_LDA(At, 1, 0); PG8_STAGE(PG8_SA(0, 1), a2 + hstep, voffA);
;             PG8_WAIT_V(8); PG8_WAIT_L(0); PG8_BAR; PG8_MMA(0, 0, At, B0); PG8_MMA(0, 1, At, B1); PG8_BAR; PG8_SCHED;
;             PG8_LDA(At, 1, 1); PG8_STAGE(PG8_SB(1, 0), b3, voffB); PG8_STAGE(PG8_SB(1, 1), b3 + hstep, voffB); PG8_STAGE(PG8_SA(1, 0), a3, voffA);
;             PG8_WAIT_V(8); PG8_WAIT_L(0); PG8_BAR; PG8_MMA(1, 0, At, B0); PG8_MMA(1, 1, At, B1); PG8_BAR; PG8_SCHED;
	s_add_i32 s48, s62, s15
	v_lshl_add_u64 v[218:219], v[218:219], 0, s[12:13]
	s_mov_b32 m0, s48
	ds_read_b128 v[184:187], v153 offset:49152
	ds_read_b128 v[188:191], v153 offset:50176
	ds_read_b128 v[192:195], v153 offset:51200
	ds_read_b128 v[196:199], v153 offset:52224
	ds_read_b128 v[200:203], v153 offset:53248
	ds_read_b128 v[206:209], v153 offset:54272
	ds_read_b128 v[210:213], v153 offset:55296
	ds_read_b128 v[214:217], v153 offset:56320
	global_load_lds_dwordx4 v[218:219], off
	s_add_i32 m0, s48, 0x2000
	s_add_u32 s46, s46, 0x20080
	v_lshl_add_u64 v[218:219], v[220:221], 0, s[12:13]
	s_addc_u32 s47, s47, 0
	s_add_i32 s48, s63, s15
	global_load_lds_dwordx4 v[218:219], off
	v_lshl_add_u64 v[218:219], s[46:47], 0, v[130:131]
	s_mov_b32 m0, s48
	s_nop 0
	global_load_lds_dwordx4 v[218:219], off
	v_lshl_add_u64 v[218:219], s[46:47], 0, v[134:135]
	s_add_i32 m0, s48, 0x2000
	s_nop 0
	global_load_lds_dwordx4 v[218:219], off
	s_waitcnt vmcnt(6)
	s_waitcnt lgkmcnt(0)
	s_barrier
	s_setprio 1
	s_waitcnt lgkmcnt(0)
	v_mfma_f32_16x16x32_bf16 v[60:63], v[144:147], v[184:187], v[60:63]
	v_mfma_f32_16x16x32_bf16 v[56:59], v[160:163], v[184:187], v[56:59]
	v_mfma_f32_16x16x32_bf16 v[44:47], v[144:147], v[192:195], v[44:47]
	v_mfma_f32_16x16x32_bf16 v[40:43], v[160:163], v[192:195], v[40:43]
	v_mfma_f32_16x16x32_bf16 v[28:31], v[144:147], v[200:203], v[28:31]
	v_mfma_f32_16x16x32_bf16 v[24:27], v[160:163], v[200:203], v[24:27]
	v_mfma_f32_16x16x32_bf16 v[12:15], v[144:147], v[210:213], v[12:15]
	v_mfma_f32_16x16x32_bf16 v[8:11], v[160:163], v[210:213], v[8:11]
	v_mfma_f32_16x16x32_bf16 v[60:63], v[156:159], v[188:191], v[60:63]
	v_mfma_f32_16x16x32_bf16 v[56:59], v[164:167], v[188:191], v[56:59]
	v_mfma_f32_16x16x32_bf16 v[44:47], v[156:159], v[196:199], v[44:47]
	v_mfma_f32_16x16x32_bf16 v[40:43], v[164:167], v[196:199], v[40:43]
	v_mfma_f32_16x16x32_bf16 v[28:31], v[156:159], v[206:209], v[28:31]
	v_mfma_f32_16x16x32_bf16 v[24:27], v[164:167], v[206:209], v[24:27]
	v_mfma_f32_16x16x32_bf16 v[12:15], v[156:159], v[214:217], v[12:15]
	v_lshl_add_u64 v[218:219], v[222:223], 0, s[12:13]
	s_mov_b32 m0, s52
	s_nop 0
	global_load_lds_dwordx4 v[218:219], off
	v_mfma_f32_16x16x32_bf16 v[8:11], v[164:167], v[214:217], v[8:11]
	s_setprio 0
	s_setprio 1
	v_mfma_f32_16x16x32_bf16 v[52:55], v[168:171], v[184:187], v[52:55]
	v_mfma_f32_16x16x32_bf16 v[48:51], v[176:179], v[184:187], v[48:51]
	v_mfma_f32_16x16x32_bf16 v[36:39], v[168:171], v[192:195], v[36:39]
	v_mfma_f32_16x16x32_bf16 v[32:35], v[176:179], v[192:195], v[32:35]
	v_mfma_f32_16x16x32_bf16 v[20:23], v[168:171], v[200:203], v[20:23]
	v_mfma_f32_16x16x32_bf16 v[16:19], v[176:179], v[200:203], v[16:19]
	v_mfma_f32_16x16x32_bf16 v[4:7], v[168:171], v[210:213], v[4:7]
	v_mfma_f32_16x16x32_bf16 v[0:3], v[176:179], v[210:213], v[0:3]
	v_mfma_f32_16x16x32_bf16 v[52:55], v[172:175], v[188:191], v[52:55]
	v_mfma_f32_16x16x32_bf16 v[48:51], v[180:183], v[188:191], v[48:51]
	v_mfma_f32_16x16x32_bf16 v[36:39], v[172:175], v[196:199], v[36:39]
	v_mfma_f32_16x16x32_bf16 v[32:35], v[180:183], v[196:199], v[32:35]
	v_mfma_f32_16x16x32_bf16 v[20:23], v[172:175], v[206:209], v[20:23]
	v_mfma_f32_16x16x32_bf16 v[16:19], v[180:183], v[206:209], v[16:19]
	v_mfma_f32_16x16x32_bf16 v[4:7], v[172:175], v[214:217], v[4:7]
	v_lshl_add_u64 v[218:219], v[224:225], 0, s[12:13]
	s_mov_b32 m0, s53
	s_nop 0
	global_load_lds_dwordx4 v[218:219], off
	v_mfma_f32_16x16x32_bf16 v[0:3], v[180:183], v[214:217], v[0:3]
	s_setprio 0
	s_barrier
	s_add_i32 s61, s61, 2
	s_add_u32 s44, s44, 0x100
	s_addc_u32 s45, s45, 0
	s_add_u32 s59, s59, 0x100
	s_addc_u32 s60, s60, 0
.LBB0_1816:
	ds_read_b128 v[144:147], v151
	ds_read_b128 v[156:159], v151 offset:1024
	ds_read_b128 v[160:163], v151 offset:2048
	ds_read_b128 v[164:167], v151 offset:3072
	ds_read_b128 v[168:171], v152
	ds_read_b128 v[172:175], v152 offset:1024
	ds_read_b128 v[176:179], v152 offset:2048
	ds_read_b128 v[180:183], v152 offset:3072
	s_add_u32 s46, s44, 0xfffe0080
	s_addc_u32 s47, s45, -1
	s_cmp_eq_u32 s61, 4
	s_cselect_b32 s49, s29, s47
	s_cselect_b32 s48, s41, s46
	s_cselect_b32 s47, s27, s60
	s_cselect_b32 s46, s58, s59
	v_lshl_add_u64 v[218:219], s[44:45], 0, v[136:137]
	s_add_i32 m0, s33, 0xc000
	ds_read_b128 v[184:187], v153
	ds_read_b128 v[188:191], v153 offset:1024
	ds_read_b128 v[192:195], v153 offset:2048
	ds_read_b128 v[196:199], v153 offset:3072
	ds_read_b128 v[200:203], v153 offset:4096
	ds_read_b128 v[206:209], v153 offset:5120
	ds_read_b128 v[210:213], v153 offset:6144
	ds_read_b128 v[214:217], v153 offset:7168
	global_load_lds_dwordx4 v[218:219], off
	v_lshl_add_u64 v[218:219], s[44:45], 0, v[138:139]
	s_add_i32 m0, s33, 0xe000
	s_nop 0
	global_load_lds_dwordx4 v[218:219], off
	s_waitcnt vmcnt(8)
	s_waitcnt lgkmcnt(0)
	s_barrier
; #define PG8_STAGE(bufoff, gbase, voff) do { _Pragma("unroll") for (int _i = 0; _i < 2; ++_i) \
;         __builtin_amdgcn_global_load_lds((const unsigned*)((const char*)(gbase) + (voff)[_i]), (PG8_LAS unsigned*)(lds + (bufoff) + ldsw + _i * 8192), 16, 0, 0); } while (0)
; #define PG8_LDA(dst, b, h) do { _Pragma("unroll") for (int m = 0; m < 4; ++m) _Pragma("unroll") for (int k = 0; k < 2; ++k) dst[m][k] = *(const PG8_LAS bf16x8*)(lds + PG8_SA(b, h) + aoff + m * 2048 + k * 1024); } while (0)
; #define PG8_MMA(ai, bj, At, Bt) do { __builtin_amdgcn_s_setprio(1); _Pragma("unroll") for (int m = 0; m < 4; ++m) _Pragma("unroll") for (int n = 0; n < 2; ++n) _Pragma("unroll") for (int k = 0; k < 2; ++k) \
;         acc[ai][bj][m][n] = __builtin_amdgcn_mfma_f32_16x16x32_bf16(Bt[n][k], At[m][k], acc[ai][bj][m][n], 0, 0, 0); __builtin_amdgcn_s_setprio(0); } while (0)
; #define PG8_WAIT_V(n) asm volatile("s_waitcnt vmcnt(" #n ")" ::: "memory")
; #define PG8_WAIT_L(n) asm volatile("s_waitcnt lgkmcnt(" #n ")" ::: "memory")
; #define PG8_BAR __builtin_amdgcn_s_barrier()
; #define PG8_SCHED __builtin_amdgcn_sched_barrier(0)
; template <class Epi, class Sched, bool ALIGN_EPI = false, bool SP2 = false>
; __device__ __forceinline__ void gemm_phase(PG8_LAS unsigned char* lds, const Gemm g, const Sched& S, const Epi& E) {
;     ...
;             PG8_WAIT_V(8); PG8_WAIT_L(0); PG8_BAR; PG8_MMA(0, 0, At, B0); PG8_MMA(0, 1, At, B1); PG8_BAR; PG8_SCHED;
;             PG8_LDA(At, 0, 1); PG8_STAGE(PG8_SB(0, 0), b2, voffB); PG8_STAGE(PG8_SB(0, 1), b2 + hstep, voffB); PG8_STAGE(PG8_SA(0, 0), a2, voffA);
;             PG8_WAIT_V(8); PG8_WAIT_L(0); PG8_BAR; PG8_MMA(1, 0, At, B0); PG8_MMA(1, 1, At, B1); PG8_BAR; PG8_SCHED;
	s_setprio 1
	s_waitcnt lgkmcnt(0)
	v_mfma_f32_16x16x32_bf16 v[124:127], v[144:147], v[184:187], v[124:127]
	v_mfma_f32_16x16x32_bf16 v[120:123], v[160:163], v[184:187], v[120:123]
	v_mfma_f32_16x16x32_bf16 v[108:111], v[144:147], v[192:195], v[108:111]
	v_mfma_f32_16x16x32_bf16 v[104:107], v[160:163], v[192:195], v[104:107]
	v_mfma_f32_16x16x32_bf16 v[92:95], v[144:147], v[200:203], v[92:95]
	v_mfma_f32_16x16x32_bf16 v[88:91], v[160:163], v[200:203], v[88:91]
	v_mfma_f32_16x16x32_bf16 v[76:79], v[144:147], v[210:213], v[76:79]
	v_mfma_f32_16x16x32_bf16 v[72:75], v[160:163], v[210:213], v[72:75]
	v_mfma_f32_16x16x32_bf16 v[124:127], v[156:159], v[188:191], v[124:127]
	v_mfma_f32_16x16x32_bf16 v[120:123], v[164:167], v[188:191], v[120:123]
	v_mfma_f32_16x16x32_bf16 v[108:111], v[156:159], v[196:199], v[108:111]
	v_mfma_f32_16x16x32_bf16 v[104:107], v[164:167], v[196:199], v[104:107]
	v_mfma_f32_16x16x32_bf16 v[92:95], v[156:159], v[206:209], v[92:95]
	v_mfma_f32_16x16x32_bf16 v[88:91], v[164:167], v[206:209], v[88:91]
	v_mfma_f32_16x16x32_bf16 v[76:79], v[156:159], v[214:217], v[76:79]
	v_mfma_f32_16x16x32_bf16 v[72:75], v[164:167], v[214:217], v[72:75]
	s_setprio 0
	s_setprio 1
	v_mfma_f32_16x16x32_bf16 v[116:119], v[168:171], v[184:187], v[116:119]
	v_mfma_f32_16x16x32_bf16 v[112:115], v[176:179], v[184:187], v[112:115]
	v_mfma_f32_16x16x32_bf16 v[100:103], v[168:171], v[192:195], v[100:103]
	v_mfma_f32_16x16x32_bf16 v[96:99], v[176:179], v[192:195], v[96:99]
	v_mfma_f32_16x16x32_bf16 v[84:87], v[168:171], v[200:203], v[84:87]
	v_mfma_f32_16x16x32_bf16 v[80:83], v[176:179], v[200:203], v[80:83]
	v_mfma_f32_16x16x32_bf16 v[68:71], v[168:171], v[210:213], v[68:71]
	v_mfma_f32_16x16x32_bf16 v[64:67], v[176:179], v[210:213], v[64:67]
	v_mfma_f32_16x16x32_bf16 v[116:119], v[172:175], v[188:191], v[116:119]
	v_mfma_f32_16x16x32_bf16 v[112:115], v[180:183], v[188:191], v[112:115]
	v_mfma_f32_16x16x32_bf16 v[100:103], v[172:175], v[196:199], v[100:103]
	v_mfma_f32_16x16x32_bf16 v[96:99], v[180:183], v[196:199], v[96:99]
	v_mfma_f32_16x16x32_bf16 v[84:87], v[172:175], v[206:209], v[84:87]
	v_mfma_f32_16x16x32_bf16 v[80:83], v[180:183], v[206:209], v[80:83]
	v_mfma_f32_16x16x32_bf16 v[68:71], v[172:175], v[214:217], v[68:71]
	v_mfma_f32_16x16x32_bf16 v[64:67], v[180:183], v[214:217], v[64:67]
	s_setprio 0
	s_barrier
	s_add_i32 s62, s54, s15
	v_lshl_add_u64 v[218:219], s[46:47], 0, v[130:131]
	s_mov_b32 m0, s62
	ds_read_b128 v[184:187], v153 offset:16384
	ds_read_b128 v[188:191], v153 offset:17408
	ds_read_b128 v[192:195], v153 offset:18432
	ds_read_b128 v[196:199], v153 offset:19456
	ds_read_b128 v[200:203], v153 offset:20480
	ds_read_b128 v[206:209], v153 offset:21504
	ds_read_b128 v[210:213], v153 offset:22528
	ds_read_b128 v[214:217], v153 offset:23552
	global_load_lds_dwordx4 v[218:219], off
	s_add_i32 m0, s62, 0x2000
	s_add_u32 s62, s46, 0x20000
	v_lshl_add_u64 v[220:221], s[46:47], 0, v[134:135]
	s_addc_u32 s63, s47, 0
	s_add_i32 s64, s55, s15
	global_load_lds_dwordx4 v[220:221], off
	v_lshl_add_u64 v[222:223], s[62:63], 0, v[130:131]
	s_mov_b32 m0, s64
	global_load_lds_dwordx4 v[222:223], off
	v_lshl_add_u64 v[222:223], s[62:63], 0, v[134:135]
	s_add_i32 m0, s64, 0x2000
	s_nop 0
	global_load_lds_dwordx4 v[222:223], off
	s_waitcnt vmcnt(6)
	s_waitcnt lgkmcnt(0)
	s_barrier
	s_setprio 1
	s_waitcnt lgkmcnt(0)
	v_mfma_f32_16x16x32_bf16 v[60:63], v[144:147], v[184:187], v[60:63]
	v_mfma_f32_16x16x32_bf16 v[56:59], v[160:163], v[184:187], v[56:59]
	v_mfma_f32_16x16x32_bf16 v[44:47], v[144:147], v[192:195], v[44:47]
	v_mfma_f32_16x16x32_bf16 v[40:43], v[160:163], v[192:195], v[40:43]
	v_mfma_f32_16x16x32_bf16 v[28:31], v[144:147], v[200:203], v[28:31]
	v_mfma_f32_16x16x32_bf16 v[24:27], v[160:163], v[200:203], v[24:27]
	v_mfma_f32_16x16x32_bf16 v[12:15], v[144:147], v[210:213], v[12:15]
	v_mfma_f32_16x16x32_bf16 v[8:11], v[160:163], v[210:213], v[8:11]
	v_mfma_f32_16x16x32_bf16 v[60:63], v[156:159], v[188:191], v[60:63]
	v_mfma_f32_16x16x32_bf16 v[56:59], v[164:167], v[188:191], v[56:59]
	v_mfma_f32_16x16x32_bf16 v[44:47], v[156:159], v[196:199], v[44:47]
	v_mfma_f32_16x16x32_bf16 v[40:43], v[164:167], v[196:199], v[40:43]
	v_mfma_f32_16x16x32_bf16 v[28:31], v[156:159], v[206:209], v[28:31]
	v_mfma_f32_16x16x32_bf16 v[24:27], v[164:167], v[206:209], v[24:27]
	v_mfma_f32_16x16x32_bf16 v[12:15], v[156:159], v[214:217], v[12:15]
	v_lshl_add_u64 v[222:223], s[48:49], 0, v[128:129]
	s_mov_b32 m0, s33
	s_nop 0
	global_load_lds_dwordx4 v[222:223], off
	v_mfma_f32_16x16x32_bf16 v[8:11], v[164:167], v[214:217], v[8:11]
	s_setprio 0
	s_setprio 1
	v_mfma_f32_16x16x32_bf16 v[52:55], v[168:171], v[184:187], v[52:55]
	v_mfma_f32_16x16x32_bf16 v[48:51], v[176:179], v[184:187], v[48:51]
	v_mfma_f32_16x16x32_bf16 v[36:39], v[168:171], v[192:195], v[36:39]
	v_mfma_f32_16x16x32_bf16 v[32:35], v[176:179], v[192:195], v[32:35]
	v_mfma_f32_16x16x32_bf16 v[20:23], v[168:171], v[200:203], v[20:23]
	v_mfma_f32_16x16x32_bf16 v[16:19], v[176:179], v[200:203], v[16:19]
	v_mfma_f32_16x16x32_bf16 v[4:7], v[168:171], v[210:213], v[4:7]
	v_mfma_f32_16x16x32_bf16 v[0:3], v[176:179], v[210:213], v[0:3]
	v_mfma_f32_16x16x32_bf16 v[52:55], v[172:175], v[188:191], v[52:55]
	v_mfma_f32_16x16x32_bf16 v[48:51], v[180:183], v[188:191], v[48:51]
	v_mfma_f32_16x16x32_bf16 v[36:39], v[172:175], v[196:199], v[36:39]
	v_mfma_f32_16x16x32_bf16 v[32:35], v[180:183], v[196:199], v[32:35]
	v_mfma_f32_16x16x32_bf16 v[20:23], v[172:175], v[206:209], v[20:23]
	v_mfma_f32_16x16x32_bf16 v[16:19], v[180:183], v[206:209], v[16:19]
	v_mfma_f32_16x16x32_bf16 v[4:7], v[172:175], v[214:217], v[4:7]
	v_lshl_add_u64 v[224:225], s[48:49], 0, v[132:133]
	s_mov_b32 m0, s34
	s_nop 0
	global_load_lds_dwordx4 v[224:225], off
	v_mfma_f32_16x16x32_bf16 v[0:3], v[180:183], v[214:217], v[0:3]
	s_setprio 0
	s_barrier
; #define PG8_STAGE(bufoff, gbase, voff) do { _Pragma("unroll") for (int _i = 0; _i < 2; ++_i) \
;         __builtin_amdgcn_global_load_lds((const unsigned*)((const char*)(gbase) + (voff)[_i]), (PG8_LAS unsigned*)(lds + (bufoff) + ldsw + _i * 8192), 16, 0, 0); } while (0)
; #define PG8_LDA(dst, b, h) do { _Pragma("unroll") for (int m = 0; m < 4; ++m) _Pragma("unroll") for (int k = 0; k < 2; ++k) dst[m][k] = *(const PG8_LAS bf16x8*)(lds + PG8_SA(b, h) + aoff + m * 2048 + k * 1024); } while (0)
; #define PG8_LDB(dst, b, h) do { _Pragma("unroll") for (int n = 0; n < 2; ++n) _Pragma("unroll") for (int k = 0; k < 2; ++k) dst[n][k] = *(const PG8_LAS bf16x8*)(lds + PG8_SB(b, h) + boff + n * 2048 + k * 1024); } while (0)
; #define PG8_MMA(ai, bj, At, Bt) do { __builtin_amdgcn_s_setprio(1); _Pragma("unroll") for (int m = 0; m < 4; ++m) _Pragma("unroll") for (int n = 0; n < 2; ++n) _Pragma("unroll") for (int k = 0; k < 2; ++k) \
;         acc[ai][bj][m][n] = __builtin_amdgcn_mfma_f32_16x16x32_bf16(Bt[n][k], At[m][k], acc[ai][bj][m][n], 0, 0, 0); __builtin_amdgcn_s_setprio(0); } while (0)
; #define PG8_WAIT_V(n) asm volatile("s_waitcnt vmcnt(" #n ")" ::: "memory")
; #define PG8_WAIT_L(n) asm volatile("s_waitcnt lgkmcnt(" #n ")" ::: "memory")
; #define PG8_BAR __builtin_amdgcn_s_barrier()
; #define PG8_SCHED __builtin_amdgcn_sched_barrier(0)
; template <class Epi, class Sched, bool ALIGN_EPI = false, bool SP2 = false>
; __device__ __forceinline__ void gemm_phase(PG8_LAS unsigned char* lds, const Gemm g, const Sched& S, const Epi& E) {
;     ...
;             PG8_LDB(B0, 1, 0); PG8_LDB(B1, 1, 1); PG8_SCHED; PG8_LDA(At, 1, 0); PG8_STAGE(PG8_SA(0, 1), a2 + hstep, voffA);
;             PG8_WAIT_V(8); PG8_WAIT_L(0); PG8_BAR; PG8_MMA(0, 0, At, B0); PG8_MMA(0, 1, At, B1); PG8_BAR; PG8_SCHED;
	s_add_i32 s62, 0, 0x18000
	v_add_u32_e32 v155, s62, v149
	s_add_i32 s63, 0, 0x1c000
	ds_read_b128 v[144:147], v155
	ds_read_b128 v[156:159], v155 offset:1024
	ds_read_b128 v[160:163], v155 offset:2048
	ds_read_b128 v[164:167], v155 offset:3072
	v_add_u32_e32 v155, s63, v149
	ds_read_b128 v[168:171], v155
	ds_read_b128 v[172:175], v155 offset:1024
	ds_read_b128 v[176:179], v155 offset:2048
	ds_read_b128 v[180:183], v155 offset:3072
	s_add_u32 s48, s48, 0x20000
	s_addc_u32 s49, s49, 0
	s_mov_b32 m0, s43
	v_lshl_add_u64 v[226:227], s[48:49], 0, v[128:129]
	ds_read_b128 v[184:187], v153 offset:32768
	ds_read_b128 v[188:191], v153 offset:33792
	ds_read_b128 v[192:195], v153 offset:34816
	ds_read_b128 v[196:199], v153 offset:35840
	ds_read_b128 v[200:203], v153 offset:36864
	ds_read_b128 v[206:209], v153 offset:37888
	ds_read_b128 v[210:213], v153 offset:38912
	ds_read_b128 v[214:217], v153 offset:39936
	global_load_lds_dwordx4 v[226:227], off
	v_lshl_add_u64 v[226:227], s[48:49], 0, v[132:133]
	s_mov_b32 m0, s50
	s_nop 0
	global_load_lds_dwordx4 v[226:227], off
	s_waitcnt vmcnt(8)
	s_waitcnt lgkmcnt(0)
	s_barrier
	s_setprio 1
	s_waitcnt lgkmcnt(0)
	v_mfma_f32_16x16x32_bf16 v[124:127], v[144:147], v[184:187], v[124:127]
	v_mfma_f32_16x16x32_bf16 v[120:123], v[160:163], v[184:187], v[120:123]
	v_mfma_f32_16x16x32_bf16 v[108:111], v[144:147], v[192:195], v[108:111]
	v_mfma_f32_16x16x32_bf16 v[104:107], v[160:163], v[192:195], v[104:107]
	v_mfma_f32_16x16x32_bf16 v[92:95], v[144:147], v[200:203], v[92:95]
	v_mfma_f32_16x16x32_bf16 v[88:91], v[160:163], v[200:203], v[88:91]
	v_mfma_f32_16x16x32_bf16 v[76:79], v[144:147], v[210:213], v[76:79]
	v_mfma_f32_16x16x32_bf16 v[72:75], v[160:163], v[210:213], v[72:75]
	v_mfma_f32_16x16x32_bf16 v[124:127], v[156:159], v[188:191], v[124:127]
	v_mfma_f32_16x16x32_bf16 v[120:123], v[164:167], v[188:191], v[120:123]
	v_mfma_f32_16x16x32_bf16 v[108:111], v[156:159], v[196:199], v[108:111]
	v_mfma_f32_16x16x32_bf16 v[104:107], v[164:167], v[196:199], v[104:107]
	v_mfma_f32_16x16x32_bf16 v[92:95], v[156:159], v[206:209], v[92:95]
	v_mfma_f32_16x16x32_bf16 v[88:91], v[164:167], v[206:209], v[88:91]
	v_mfma_f32_16x16x32_bf16 v[76:79], v[156:159], v[214:217], v[76:79]
	v_mfma_f32_16x16x32_bf16 v[72:75], v[164:167], v[214:217], v[72:75]
	s_setprio 0
	s_setprio 1
	v_mfma_f32_16x16x32_bf16 v[116:119], v[168:171], v[184:187], v[116:119]
	v_mfma_f32_16x16x32_bf16 v[112:115], v[176:179], v[184:187], v[112:115]
	v_mfma_f32_16x16x32_bf16 v[100:103], v[168:171], v[192:195], v[100:103]
	v_mfma_f32_16x16x32_bf16 v[96:99], v[176:179], v[192:195], v[96:99]
	v_mfma_f32_16x16x32_bf16 v[84:87], v[168:171], v[200:203], v[84:87]
	v_mfma_f32_16x16x32_bf16 v[80:83], v[176:179], v[200:203], v[80:83]
	v_mfma_f32_16x16x32_bf16 v[68:71], v[168:171], v[210:213], v[68:71]
	v_mfma_f32_16x16x32_bf16 v[64:67], v[176:179], v[210:213], v[64:67]
	v_mfma_f32_16x16x32_bf16 v[116:119], v[172:175], v[188:191], v[116:119]
	v_mfma_f32_16x16x32_bf16 v[112:115], v[180:183], v[188:191], v[112:115]
	v_mfma_f32_16x16x32_bf16 v[100:103], v[172:175], v[196:199], v[100:103]
	v_mfma_f32_16x16x32_bf16 v[96:99], v[180:183], v[196:199], v[96:99]
	v_mfma_f32_16x16x32_bf16 v[84:87], v[172:175], v[206:209], v[84:87]
	v_mfma_f32_16x16x32_bf16 v[80:83], v[180:183], v[206:209], v[80:83]
	v_mfma_f32_16x16x32_bf16 v[68:71], v[172:175], v[214:217], v[68:71]
	v_mfma_f32_16x16x32_bf16 v[64:67], v[180:183], v[214:217], v[64:67]
	s_setprio 0
	s_barrier
; #define PG8_STAGE(bufoff, gbase, voff) do { _Pragma("unroll") for (int _i = 0; _i < 2; ++_i) \
;         __builtin_amdgcn_global_load_lds((const unsigned*)((const char*)(gbase) + (voff)[_i]), (PG8_LAS unsigned*)(lds + (bufoff) + ldsw + _i * 8192), 16, 0, 0); } while (0)
; #define PG8_LDA(dst, b, h) do { _Pragma("unroll") for (int m = 0; m < 4; ++m) _Pragma("unroll") for (int k = 0; k < 2; ++k) dst[m][k] = *(const PG8_LAS bf16x8*)(lds + PG8_SA(b, h) + aoff + m * 2048 + k * 1024); } while (0)
; #define PG8_MMA(ai, bj, At, Bt) do { __builtin_amdgcn_s_setprio(1); _Pragma("unroll") for (int m = 0; m < 4; ++m) _Pragma("unroll") for (int n = 0; n < 2; ++n) _Pragma("unroll") for (int k = 0; k < 2; ++k) \
;         acc[ai][bj][m][n] = __builtin_amdgcn_mfma_f32_16x16x32_bf16(Bt[n][k], At[m][k], acc[ai][bj][m][n], 0, 0, 0); __builtin_amdgcn_s_setprio(0); } while (0)
; #define PG8_WAIT_V(n) asm volatile("s_waitcnt vmcnt(" #n ")" ::: "memory")
; #define PG8_WAIT_L(n) asm volatile("s_waitcnt lgkmcnt(" #n ")" ::: "memory")
; #define PG8_BAR __builtin_amdgcn_s_barrier()
; #define PG8_SCHED __builtin_amdgcn_sched_barrier(0)
; template <class Epi, class Sched, bool ALIGN_EPI = false, bool SP2 = false>
; __device__ __forceinline__ void gemm_phase(PG8_LAS unsigned char* lds, const Gemm g, const Sched& S, const Epi& E) {
;     ...
;         for (int t = 0; t < nt; t += 2) {
;     ...
;             PG8_LDA(At, 1, 1); PG8_STAGE(PG8_SB(1, 0), b3, voffB); PG8_STAGE(PG8_SB(1, 1), b3 + hstep, voffB); PG8_STAGE(PG8_SA(1, 0), a3, voffA);
;             PG8_WAIT_V(8); PG8_WAIT_L(0); PG8_BAR; PG8_MMA(1, 0, At, B0); PG8_MMA(1, 1, At, B1); PG8_BAR; PG8_SCHED;
	s_add_i32 s48, s62, s15
	v_lshl_add_u64 v[218:219], v[218:219], 0, s[12:13]
	s_mov_b32 m0, s48
	ds_read_b128 v[184:187], v153 offset:49152
	ds_read_b128 v[188:191], v153 offset:50176
	ds_read_b128 v[192:195], v153 offset:51200
	ds_read_b128 v[196:199], v153 offset:52224
	ds_read_b128 v[200:203], v153 offset:53248
	ds_read_b128 v[206:209], v153 offset:54272
	ds_read_b128 v[210:213], v153 offset:55296
	ds_read_b128 v[214:217], v153 offset:56320
	global_load_lds_dwordx4 v[218:219], off
	s_add_i32 m0, s48, 0x2000
	s_add_u32 s46, s46, 0x20080
	v_lshl_add_u64 v[218:219], v[220:221], 0, s[12:13]
	s_addc_u32 s47, s47, 0
	s_add_i32 s48, s63, s15
	global_load_lds_dwordx4 v[218:219], off
	v_lshl_add_u64 v[218:219], s[46:47], 0, v[130:131]
	s_mov_b32 m0, s48
	s_nop 0
	global_load_lds_dwordx4 v[218:219], off
	v_lshl_add_u64 v[218:219], s[46:47], 0, v[134:135]
	s_add_i32 m0, s48, 0x2000
	s_nop 0
	global_load_lds_dwordx4 v[218:219], off
	s_waitcnt vmcnt(6)
	s_waitcnt lgkmcnt(0)
	s_barrier
	s_setprio 1
	s_waitcnt lgkmcnt(0)
	v_mfma_f32_16x16x32_bf16 v[60:63], v[144:147], v[184:187], v[60:63]
	v_mfma_f32_16x16x32_bf16 v[56:59], v[160:163], v[184:187], v[56:59]
	v_mfma_f32_16x16x32_bf16 v[44:47], v[144:147], v[192:195], v[44:47]
	v_mfma_f32_16x16x32_bf16 v[40:43], v[160:163], v[192:195], v[40:43]
	v_mfma_f32_16x16x32_bf16 v[28:31], v[144:147], v[200:203], v[28:31]
	v_mfma_f32_16x16x32_bf16 v[24:27], v[160:163], v[200:203], v[24:27]
	v_mfma_f32_16x16x32_bf16 v[12:15], v[144:147], v[210:213], v[12:15]
	v_mfma_f32_16x16x32_bf16 v[8:11], v[160:163], v[210:213], v[8:11]
	v_mfma_f32_16x16x32_bf16 v[60:63], v[156:159], v[188:191], v[60:63]
	v_mfma_f32_16x16x32_bf16 v[56:59], v[164:167], v[188:191], v[56:59]
	v_mfma_f32_16x16x32_bf16 v[44:47], v[156:159], v[196:199], v[44:47]
	v_mfma_f32_16x16x32_bf16 v[40:43], v[164:167], v[196:199], v[40:43]
	v_mfma_f32_16x16x32_bf16 v[28:31], v[156:159], v[206:209], v[28:31]
	v_mfma_f32_16x16x32_bf16 v[24:27], v[164:167], v[206:209], v[24:27]
	v_mfma_f32_16x16x32_bf16 v[12:15], v[156:159], v[214:217], v[12:15]
	v_lshl_add_u64 v[218:219], v[222:223], 0, s[12:13]
	s_mov_b32 m0, s52
	s_nop 0
	global_load_lds_dwordx4 v[218:219], off
	v_mfma_f32_16x16x32_bf16 v[8:11], v[164:167], v[214:217], v[8:11]
	s_setprio 0
	s_setprio 1
	v_mfma_f32_16x16x32_bf16 v[52:55], v[168:171], v[184:187], v[52:55]
	v_mfma_f32_16x16x32_bf16 v[48:51], v[176:179], v[184:187], v[48:51]
	v_mfma_f32_16x16x32_bf16 v[36:39], v[168:171], v[192:195], v[36:39]
	v_mfma_f32_16x16x32_bf16 v[32:35], v[176:179], v[192:195], v[32:35]
	v_mfma_f32_16x16x32_bf16 v[20:23], v[168:171], v[200:203], v[20:23]
	v_mfma_f32_16x16x32_bf16 v[16:19], v[176:179], v[200:203], v[16:19]
	v_mfma_f32_16x16x32_bf16 v[4:7], v[168:171], v[210:213], v[4:7]
	v_mfma_f32_16x16x32_bf16 v[0:3], v[176:179], v[210:213], v[0:3]
	v_mfma_f32_16x16x32_bf16 v[52:55], v[172:175], v[188:191], v[52:55]
	v_mfma_f32_16x16x32_bf16 v[48:51], v[180:183], v[188:191], v[48:51]
	v_mfma_f32_16x16x32_bf16 v[36:39], v[172:175], v[196:199], v[36:39]
	v_mfma_f32_16x16x32_bf16 v[32:35], v[180:183], v[196:199], v[32:35]
	v_mfma_f32_16x16x32_bf16 v[20:23], v[172:175], v[206:209], v[20:23]
	v_mfma_f32_16x16x32_bf16 v[16:19], v[180:183], v[206:209], v[16:19]
	v_mfma_f32_16x16x32_bf16 v[4:7], v[172:175], v[214:217], v[4:7]
	v_lshl_add_u64 v[218:219], v[224:225], 0, s[12:13]
	s_mov_b32 m0, s53
	s_nop 0
	global_load_lds_dwordx4 v[218:219], off
	v_mfma_f32_16x16x32_bf16 v[0:3], v[180:183], v[214:217], v[0:3]
	s_setprio 0
	s_barrier
	s_add_i32 s61, s61, 2
	s_add_u32 s44, s44, 0x100
	s_addc_u32 s45, s45, 0
	s_add_u32 s59, s59, 0x100
	s_addc_u32 s60, s60, 0
	s_cmp_gt_u32 s61, 5
	s_cbranch_scc0 .LBB0_1816
	s_and_b64 vcc, exec, s[24:25]
	s_cbranch_vccz .LBB0_1819
	s_barrier

; #define PG8_STAGE(bufoff, gbase, voff) do { _Pragma("unroll") for (int _i = 0; _i < 2; ++_i) \
;         __builtin_amdgcn_global_load_lds((const unsigned*)((const char*)(gbase) + (voff)[_i]), (PG8_LAS unsigned*)(lds + (bufoff) + ldsw + _i * 8192), 16, 0, 0); } while (0)
; #define PG8_LDA(dst, b, h) do { _Pragma("unroll") for (int m = 0; m < 4; ++m) _Pragma("unroll") for (int k = 0; k < 2; ++k) dst[m][k] = *(const PG8_LAS bf16x8*)(lds + PG8_SA(b, h) + aoff + m * 2048 + k * 1024); } while (0)
; #define PG8_LDB(dst, b, h) do { _Pragma("unroll") for (int n = 0; n < 2; ++n) _Pragma("unroll") for (int k = 0; k < 2; ++k) dst[n][k] = *(const PG8_LAS bf16x8*)(lds + PG8_SB(b, h) + boff + n * 2048 + k * 1024); } while (0)
; #define PG8_MMA(ai, bj, At, Bt) do { __builtin_amdgcn_s_setprio(1); _Pragma("unroll") for (int m = 0; m < 4; ++m) _Pragma("unroll") for (int n = 0; n < 2; ++n) _Pragma("unroll") for (int k = 0; k < 2; ++k) \
;         acc[ai][bj][m][n] = __builtin_amdgcn_mfma_f32_16x16x32_bf16(Bt[n][k], At[m][k], acc[ai][bj][m][n], 0, 0, 0); __builtin_amdgcn_s_setprio(0); } while (0)
; #define PG8_BAR __builtin_amdgcn_s_barrier()
; template <class Epi, class Sched, bool ALIGN_EPI = false, bool SP2 = false>
; __device__ __forceinline__ void gemm_phase(PG8_LAS unsigned char* lds, const Gemm g, const Sched& S, const Epi& E) {
;     ...
;         const bool has_next = S.next(ui + 1, nxt);
;         const char* nA = has_next ? (const char*)g.A + (size_t)nxt.pm * tstep : cA; const char* nB = has_next ? (const char*)g.Bt + (size_t)nxt.pn * tstep : cB;
;         for (int t = 0; t < nt; t += 2) {
;             const bool last = (t == nt - 2);
;             const char* a1 = cA + (size_t)(t + 1) * kstep;
;             const char* a2 = last ? nA : cA + (size_t)(t + 2) * kstep; const char* b2 = last ? nB : cB + (size_t)(t + 2) * kstep;
;             const char* a3 = a2 + kstep; const char* b3 = b2 + kstep;
;             if (last && has_next) S.a_ready(nxt);
;             if constexpr (SP2) {
;             PG8_LDB(B0, 0, 0); PG8_LDB(B1, 0, 1); PG8_SCHED; PG8_LDA(At, 0, 0); PG8_STAGE(PG8_SA(1, 1), a1 + hstep, voffA);
;             PG8_WAIT_V(8); PG8_WAIT_L(0); PG8_BAR; PG8_MMA(0, 0, At, B0); PG8_MMA(0, 1, At, B1); PG8_BAR; PG8_SCHED;
;             PG8_LDA(At, 0, 1); PG8_STAGE(PG8_SB(0, 0), b2, voffB); PG8_STAGE(PG8_SB(0, 1), b2 + hstep, voffB); PG8_STAGE(PG8_SA(0, 0), a2, voffA);
.LBB0_1899:
	s_ashr_i32 s25, s24, 31
	s_lshl_b64 s[26:27], s[24:25], 19
	s_add_u32 s26, s22, s26
	s_addc_u32 s27, s23, s27
	s_and_b64 s[28:29], s[4:5], exec
	s_cselect_b32 s25, s27, s39
	s_cselect_b32 s53, s26, s38
	s_ashr_i32 s13, s12, 31
	s_lshl_b64 s[28:29], s[12:13], 19
	s_add_u32 s28, s3, s28
	s_addc_u32 s29, s14, s29
	s_and_b64 s[42:43], s[4:5], exec
	s_cselect_b32 s13, s29, s41
	s_cselect_b32 s54, s28, s40
	s_add_u32 s38, s38, 0x40080
	s_addc_u32 s39, s39, 0
	s_add_u32 s55, s40, 0x100
	s_addc_u32 s56, s41, 0
	s_mov_b32 s57, -2
	ds_read_b128 v[144:147], v155
	ds_read_b128 v[148:151], v155 offset:1024
	ds_read_b128 v[160:163], v155 offset:2048
	ds_read_b128 v[164:167], v155 offset:3072
	ds_read_b128 v[168:171], v156
	ds_read_b128 v[172:175], v156 offset:1024
	ds_read_b128 v[176:179], v156 offset:2048
	ds_read_b128 v[180:183], v156 offset:3072
	s_add_u32 s40, s38, 0xfffc0080
	s_addc_u32 s41, s39, -1
	s_cmp_eq_u32 s57, 12
	s_cselect_b32 s43, s25, s41
	s_cselect_b32 s42, s53, s40
	s_cselect_b32 s41, s13, s56
	s_cselect_b32 s40, s54, s55
	v_lshl_add_u64 v[218:219], s[38:39], 0, v[136:137]
	s_add_i32 m0, s34, 0xc000
	ds_read_b128 v[184:187], v157
	ds_read_b128 v[188:191], v157 offset:1024
	ds_read_b128 v[192:195], v157 offset:2048
	ds_read_b128 v[196:199], v157 offset:3072
	ds_read_b128 v[200:203], v157 offset:4096
	ds_read_b128 v[206:209], v157 offset:5120
	ds_read_b128 v[210:213], v157 offset:6144
	ds_read_b128 v[214:217], v157 offset:7168
	global_load_lds_dwordx4 v[218:219], off
	v_lshl_add_u64 v[218:219], s[38:39], 0, v[138:139]
	s_add_i32 m0, s34, 0xe000
	s_nop 0
	global_load_lds_dwordx4 v[218:219], off
	s_waitcnt vmcnt(8)
	s_waitcnt lgkmcnt(0)
	s_barrier
	s_setprio 1
	s_waitcnt lgkmcnt(0)
	v_mfma_f32_16x16x32_bf16 v[124:127], v[144:147], v[184:187], 0
	v_mfma_f32_16x16x32_bf16 v[120:123], v[160:163], v[184:187], 0
	v_mfma_f32_16x16x32_bf16 v[108:111], v[144:147], v[192:195], 0
	v_mfma_f32_16x16x32_bf16 v[104:107], v[160:163], v[192:195], 0
	v_mfma_f32_16x16x32_bf16 v[92:95], v[144:147], v[200:203], 0
	v_mfma_f32_16x16x32_bf16 v[88:91], v[160:163], v[200:203], 0
	v_mfma_f32_16x16x32_bf16 v[76:79], v[144:147], v[210:213], 0
	v_mfma_f32_16x16x32_bf16 v[72:75], v[160:163], v[210:213], 0
	v_mfma_f32_16x16x32_bf16 v[124:127], v[148:151], v[188:191], v[124:127]
	v_mfma_f32_16x16x32_bf16 v[120:123], v[164:167], v[188:191], v[120:123]
	v_mfma_f32_16x16x32_bf16 v[108:111], v[148:151], v[196:199], v[108:111]
	v_mfma_f32_16x16x32_bf16 v[104:107], v[164:167], v[196:199], v[104:107]
	v_mfma_f32_16x16x32_bf16 v[92:95], v[148:151], v[206:209], v[92:95]
	v_mfma_f32_16x16x32_bf16 v[88:91], v[164:167], v[206:209], v[88:91]
	v_mfma_f32_16x16x32_bf16 v[76:79], v[148:151], v[214:217], v[76:79]
	v_mfma_f32_16x16x32_bf16 v[72:75], v[164:167], v[214:217], v[72:75]
	s_setprio 0
	s_setprio 1
	v_mfma_f32_16x16x32_bf16 v[116:119], v[168:171], v[184:187], 0
	v_mfma_f32_16x16x32_bf16 v[112:115], v[176:179], v[184:187], 0
	v_mfma_f32_16x16x32_bf16 v[100:103], v[168:171], v[192:195], 0
	v_mfma_f32_16x16x32_bf16 v[96:99], v[176:179], v[192:195], 0
	v_mfma_f32_16x16x32_bf16 v[84:87], v[168:171], v[200:203], 0
	v_mfma_f32_16x16x32_bf16 v[80:83], v[176:179], v[200:203], 0
	v_mfma_f32_16x16x32_bf16 v[68:71], v[168:171], v[210:213], 0
	v_mfma_f32_16x16x32_bf16 v[64:67], v[176:179], v[210:213], 0
	v_mfma_f32_16x16x32_bf16 v[116:119], v[172:175], v[188:191], v[116:119]
	v_mfma_f32_16x16x32_bf16 v[112:115], v[180:183], v[188:191], v[112:115]
	v_mfma_f32_16x16x32_bf16 v[100:103], v[172:175], v[196:199], v[100:103]
	v_mfma_f32_16x16x32_bf16 v[96:99], v[180:183], v[196:199], v[96:99]
	v_mfma_f32_16x16x32_bf16 v[84:87], v[172:175], v[206:209], v[84:87]
	v_mfma_f32_16x16x32_bf16 v[80:83], v[180:183], v[206:209], v[80:83]
	v_mfma_f32_16x16x32_bf16 v[68:71], v[172:175], v[214:217], v[68:71]
	v_mfma_f32_16x16x32_bf16 v[64:67], v[180:183], v[214:217], v[64:67]
	s_setprio 0
	s_barrier
	s_add_i32 s58, s49, s15
	v_lshl_add_u64 v[218:219], s[40:41], 0, v[132:133]
	s_mov_b32 m0, s58
	ds_read_b128 v[184:187], v157 offset:16384
	ds_read_b128 v[188:191], v157 offset:17408
	ds_read_b128 v[192:195], v157 offset:18432
	ds_read_b128 v[196:199], v157 offset:19456
	ds_read_b128 v[200:203], v157 offset:20480
	ds_read_b128 v[206:209], v157 offset:21504
	ds_read_b128 v[210:213], v157 offset:22528
	ds_read_b128 v[214:217], v157 offset:23552
	global_load_lds_dwordx4 v[218:219], off
	s_add_i32 m0, s58, 0x2000
	s_add_u32 s58, s40, 0x40000
	v_lshl_add_u64 v[220:221], s[40:41], 0, v[128:129]
	s_addc_u32 s59, s41, 0
	s_add_i32 s60, s50, s15
	global_load_lds_dwordx4 v[220:221], off
	v_lshl_add_u64 v[222:223], s[58:59], 0, v[132:133]
	s_mov_b32 m0, s60
	global_load_lds_dwordx4 v[222:223], off
	v_lshl_add_u64 v[222:223], s[58:59], 0, v[128:129]
	s_add_i32 m0, s60, 0x2000
	s_nop 0
	global_load_lds_dwordx4 v[222:223], off
	s_waitcnt vmcnt(6)
	s_waitcnt lgkmcnt(0)
	s_barrier
; #define PG8_STAGE(bufoff, gbase, voff) do { _Pragma("unroll") for (int _i = 0; _i < 2; ++_i) \
;         __builtin_amdgcn_global_load_lds((const unsigned*)((const char*)(gbase) + (voff)[_i]), (PG8_LAS unsigned*)(lds + (bufoff) + ldsw + _i * 8192), 16, 0, 0); } while (0)
; #define PG8_LDA(dst, b, h) do { _Pragma("unroll") for (int m = 0; m < 4; ++m) _Pragma("unroll") for (int k = 0; k < 2; ++k) dst[m][k] = *(const PG8_LAS bf16x8*)(lds + PG8_SA(b, h) + aoff + m * 2048 + k * 1024); } while (0)
; #define PG8_LDB(dst, b, h) do { _Pragma("unroll") for (int n = 0; n < 2; ++n) _Pragma("unroll") for (int k = 0; k < 2; ++k) dst[n][k] = *(const PG8_LAS bf16x8*)(lds + PG8_SB(b, h) + boff + n * 2048 + k * 1024); } while (0)
; #define PG8_MMA(ai, bj, At, Bt) do { __builtin_amdgcn_s_setprio(1); _Pragma("unroll") for (int m = 0; m < 4; ++m) _Pragma("unroll") for (int n = 0; n < 2; ++n) _Pragma("unroll") for (int k = 0; k < 2; ++k) \
;         acc[ai][bj][m][n] = __builtin_amdgcn_mfma_f32_16x16x32_bf16(Bt[n][k], At[m][k], acc[ai][bj][m][n], 0, 0, 0); __builtin_amdgcn_s_setprio(0); } while (0)
; #define PG8_WAIT_V(n) asm volatile("s_waitcnt vmcnt(" #n ")" ::: "memory")
; #define PG8_WAIT_L(n) asm volatile("s_waitcnt lgkmcnt(" #n ")" ::: "memory")
; #define PG8_BAR __builtin_amdgcn_s_barrier()
; #define PG8_SCHED __builtin_amdgcn_sched_barrier(0)
; template <class Epi, class Sched, bool ALIGN_EPI = false, bool SP2 = false>
; __device__ __forceinline__ void gemm_phase(PG8_LAS unsigned char* lds, const Gemm g, const Sched& S, const Epi& E) {
;     ...
;             PG8_WAIT_V(8); PG8_WAIT_L(0); PG8_BAR; PG8_MMA(0, 0, At, B0); PG8_MMA(0, 1, At, B1); PG8_BAR; PG8_SCHED;
;             PG8_LDA(At, 0, 1); PG8_STAGE(PG8_SB(0, 0), b2, voffB); PG8_STAGE(PG8_SB(0, 1), b2 + hstep, voffB); PG8_STAGE(PG8_SA(0, 0), a2, voffA);
;             PG8_WAIT_V(8); PG8_WAIT_L(0); PG8_BAR; PG8_MMA(1, 0, At, B0); PG8_MMA(1, 1, At, B1); PG8_BAR; PG8_SCHED;
;             PG8_LDB(B0, 1, 0); PG8_LDB(B1, 1, 1); PG8_SCHED; PG8_LDA(At, 1, 0); PG8_STAGE(PG8_SA(0, 1), a2 + hstep, voffA);
;             PG8_WAIT_V(8); PG8_WAIT_L(0); PG8_BAR; PG8_MMA(0, 0, At, B0); PG8_MMA(0, 1, At, B1); PG8_BAR; PG8_SCHED;
	s_setprio 1
	s_waitcnt lgkmcnt(0)
	v_mfma_f32_16x16x32_bf16 v[60:63], v[144:147], v[184:187], 0
	v_mfma_f32_16x16x32_bf16 v[56:59], v[160:163], v[184:187], 0
	v_mfma_f32_16x16x32_bf16 v[44:47], v[144:147], v[192:195], 0
	v_mfma_f32_16x16x32_bf16 v[40:43], v[160:163], v[192:195], 0
	v_mfma_f32_16x16x32_bf16 v[28:31], v[144:147], v[200:203], 0
	v_mfma_f32_16x16x32_bf16 v[24:27], v[160:163], v[200:203], 0
	v_mfma_f32_16x16x32_bf16 v[12:15], v[144:147], v[210:213], 0
	v_mfma_f32_16x16x32_bf16 v[8:11], v[160:163], v[210:213], 0
	v_mfma_f32_16x16x32_bf16 v[60:63], v[148:151], v[188:191], v[60:63]
	v_mfma_f32_16x16x32_bf16 v[56:59], v[164:167], v[188:191], v[56:59]
	v_mfma_f32_16x16x32_bf16 v[44:47], v[148:151], v[196:199], v[44:47]
	v_mfma_f32_16x16x32_bf16 v[40:43], v[164:167], v[196:199], v[40:43]
	v_mfma_f32_16x16x32_bf16 v[28:31], v[148:151], v[206:209], v[28:31]
	v_mfma_f32_16x16x32_bf16 v[24:27], v[164:167], v[206:209], v[24:27]
	v_mfma_f32_16x16x32_bf16 v[12:15], v[148:151], v[214:217], v[12:15]
	v_lshl_add_u64 v[222:223], s[42:43], 0, v[134:135]
	s_mov_b32 m0, s34
	s_nop 0
	global_load_lds_dwordx4 v[222:223], off
	v_mfma_f32_16x16x32_bf16 v[8:11], v[164:167], v[214:217], v[8:11]
	s_setprio 0
	s_setprio 1
	v_mfma_f32_16x16x32_bf16 v[52:55], v[168:171], v[184:187], 0
	v_mfma_f32_16x16x32_bf16 v[48:51], v[176:179], v[184:187], 0
	v_mfma_f32_16x16x32_bf16 v[36:39], v[168:171], v[192:195], 0
	v_mfma_f32_16x16x32_bf16 v[32:35], v[176:179], v[192:195], 0
	v_mfma_f32_16x16x32_bf16 v[20:23], v[168:171], v[200:203], 0
	v_mfma_f32_16x16x32_bf16 v[16:19], v[176:179], v[200:203], 0
	v_mfma_f32_16x16x32_bf16 v[4:7], v[168:171], v[210:213], 0
	v_mfma_f32_16x16x32_bf16 v[0:3], v[176:179], v[210:213], 0
	v_mfma_f32_16x16x32_bf16 v[52:55], v[172:175], v[188:191], v[52:55]
	v_mfma_f32_16x16x32_bf16 v[48:51], v[180:183], v[188:191], v[48:51]
	v_mfma_f32_16x16x32_bf16 v[36:39], v[172:175], v[196:199], v[36:39]
	v_mfma_f32_16x16x32_bf16 v[32:35], v[180:183], v[196:199], v[32:35]
	v_mfma_f32_16x16x32_bf16 v[20:23], v[172:175], v[206:209], v[20:23]
	v_mfma_f32_16x16x32_bf16 v[16:19], v[180:183], v[206:209], v[16:19]
	v_mfma_f32_16x16x32_bf16 v[4:7], v[172:175], v[214:217], v[4:7]
	v_lshl_add_u64 v[224:225], s[42:43], 0, v[130:131]
	s_mov_b32 m0, s37
	s_nop 0
	global_load_lds_dwordx4 v[224:225], off
	v_mfma_f32_16x16x32_bf16 v[0:3], v[180:183], v[214:217], v[0:3]
	s_setprio 0
	s_barrier
	s_add_i32 s58, 0, 0x18000
	v_add_u32_e32 v159, s58, v153
	s_add_i32 s59, 0, 0x1c000
	ds_read_b128 v[144:147], v159
	ds_read_b128 v[148:151], v159 offset:1024
	ds_read_b128 v[160:163], v159 offset:2048
	ds_read_b128 v[164:167], v159 offset:3072
	v_add_u32_e32 v159, s59, v153
	ds_read_b128 v[168:171], v159
	ds_read_b128 v[172:175], v159 offset:1024
	ds_read_b128 v[176:179], v159 offset:2048
	ds_read_b128 v[180:183], v159 offset:3072
	s_add_u32 s42, s42, 0x40000
	s_addc_u32 s43, s43, 0
	s_mov_b32 m0, s44
	v_lshl_add_u64 v[226:227], s[42:43], 0, v[134:135]
	ds_read_b128 v[184:187], v157 offset:32768
	ds_read_b128 v[188:191], v157 offset:33792
	ds_read_b128 v[192:195], v157 offset:34816
	ds_read_b128 v[196:199], v157 offset:35840
	ds_read_b128 v[200:203], v157 offset:36864
	ds_read_b128 v[206:209], v157 offset:37888
	ds_read_b128 v[210:213], v157 offset:38912
	ds_read_b128 v[214:217], v157 offset:39936
	global_load_lds_dwordx4 v[226:227], off
	v_lshl_add_u64 v[226:227], s[42:43], 0, v[130:131]
	s_mov_b32 m0, s45
	s_nop 0
	global_load_lds_dwordx4 v[226:227], off
	s_waitcnt vmcnt(8)
	s_waitcnt lgkmcnt(0)
	s_barrier
	s_setprio 1
	s_waitcnt lgkmcnt(0)
	v_mfma_f32_16x16x32_bf16 v[124:127], v[144:147], v[184:187], v[124:127]
	v_mfma_f32_16x16x32_bf16 v[120:123], v[160:163], v[184:187], v[120:123]
	v_mfma_f32_16x16x32_bf16 v[108:111], v[144:147], v[192:195], v[108:111]
	v_mfma_f32_16x16x32_bf16 v[104:107], v[160:163], v[192:195], v[104:107]
	v_mfma_f32_16x16x32_bf16 v[92:95], v[144:147], v[200:203], v[92:95]
	v_mfma_f32_16x16x32_bf16 v[88:91], v[160:163], v[200:203], v[88:91]
	v_mfma_f32_16x16x32_bf16 v[76:79], v[144:147], v[210:213], v[76:79]
	v_mfma_f32_16x16x32_bf16 v[72:75], v[160:163], v[210:213], v[72:75]
	v_mfma_f32_16x16x32_bf16 v[124:127], v[148:151], v[188:191], v[124:127]
	v_mfma_f32_16x16x32_bf16 v[120:123], v[164:167], v[188:191], v[120:123]
	v_mfma_f32_16x16x32_bf16 v[108:111], v[148:151], v[196:199], v[108:111]
	v_mfma_f32_16x16x32_bf16 v[104:107], v[164:167], v[196:199], v[104:107]
	v_mfma_f32_16x16x32_bf16 v[92:95], v[148:151], v[206:209], v[92:95]
	v_mfma_f32_16x16x32_bf16 v[88:91], v[164:167], v[206:209], v[88:91]
	v_mfma_f32_16x16x32_bf16 v[76:79], v[148:151], v[214:217], v[76:79]
	v_mfma_f32_16x16x32_bf16 v[72:75], v[164:167], v[214:217], v[72:75]
	s_setprio 0
	s_setprio 1
	v_mfma_f32_16x16x32_bf16 v[116:119], v[168:171], v[184:187], v[116:119]
	v_mfma_f32_16x16x32_bf16 v[112:115], v[176:179], v[184:187], v[112:115]
	v_mfma_f32_16x16x32_bf16 v[100:103], v[168:171], v[192:195], v[100:103]
	v_mfma_f32_16x16x32_bf16 v[96:99], v[176:179], v[192:195], v[96:99]
	v_mfma_f32_16x16x32_bf16 v[84:87], v[168:171], v[200:203], v[84:87]
	v_mfma_f32_16x16x32_bf16 v[80:83], v[176:179], v[200:203], v[80:83]
	v_mfma_f32_16x16x32_bf16 v[68:71], v[168:171], v[210:213], v[68:71]
	v_mfma_f32_16x16x32_bf16 v[64:67], v[176:179], v[210:213], v[64:67]
	v_mfma_f32_16x16x32_bf16 v[116:119], v[172:175], v[188:191], v[116:119]
	v_mfma_f32_16x16x32_bf16 v[112:115], v[180:183], v[188:191], v[112:115]
	v_mfma_f32_16x16x32_bf16 v[100:103], v[172:175], v[196:199], v[100:103]
	v_mfma_f32_16x16x32_bf16 v[96:99], v[180:183], v[196:199], v[96:99]
	v_mfma_f32_16x16x32_bf16 v[84:87], v[172:175], v[206:209], v[84:87]
	v_mfma_f32_16x16x32_bf16 v[80:83], v[180:183], v[206:209], v[80:83]
	v_mfma_f32_16x16x32_bf16 v[68:71], v[172:175], v[214:217], v[68:71]
	v_mfma_f32_16x16x32_bf16 v[64:67], v[180:183], v[214:217], v[64:67]
	s_setprio 0
	s_barrier
; #define PG8_STAGE(bufoff, gbase, voff) do { _Pragma("unroll") for (int _i = 0; _i < 2; ++_i) \
;         __builtin_amdgcn_global_load_lds((const unsigned*)((const char*)(gbase) + (voff)[_i]), (PG8_LAS unsigned*)(lds + (bufoff) + ldsw + _i * 8192), 16, 0, 0); } while (0)
; #define PG8_LDA(dst, b, h) do { _Pragma("unroll") for (int m = 0; m < 4; ++m) _Pragma("unroll") for (int k = 0; k < 2; ++k) dst[m][k] = *(const PG8_LAS bf16x8*)(lds + PG8_SA(b, h) + aoff + m * 2048 + k * 1024); } while (0)
; #define PG8_LDB(dst, b, h) do { _Pragma("unroll") for (int n = 0; n < 2; ++n) _Pragma("unroll") for (int k = 0; k < 2; ++k) dst[n][k] = *(const PG8_LAS bf16x8*)(lds + PG8_SB(b, h) + boff + n * 2048 + k * 1024); } while (0)
; #define PG8_MMA(ai, bj, At, Bt) do { __builtin_amdgcn_s_setprio(1); _Pragma("unroll") for (int m = 0; m < 4; ++m) _Pragma("unroll") for (int n = 0; n < 2; ++n) _Pragma("unroll") for (int k = 0; k < 2; ++k) \
;         acc[ai][bj][m][n] = __builtin_amdgcn_mfma_f32_16x16x32_bf16(Bt[n][k], At[m][k], acc[ai][bj][m][n], 0, 0, 0); __builtin_amdgcn_s_setprio(0); } while (0)
; #define PG8_WAIT_V(n) asm volatile("s_waitcnt vmcnt(" #n ")" ::: "memory")
; template <class Epi, class Sched, bool ALIGN_EPI = false, bool SP2 = false>
; __device__ __forceinline__ void gemm_phase(PG8_LAS unsigned char* lds, const Gemm g, const Sched& S, const Epi& E) {
;     ...
;             PG8_LDB(B0, 0, 0); PG8_LDB(B1, 0, 1); PG8_SCHED; PG8_LDA(At, 0, 0); PG8_STAGE(PG8_SA(1, 1), a1 + hstep, voffA);
;             PG8_WAIT_V(8); PG8_WAIT_L(0); PG8_BAR; PG8_MMA(0, 0, At, B0); PG8_MMA(0, 1, At, B1); PG8_BAR; PG8_SCHED;
;             PG8_LDA(At, 0, 1); PG8_STAGE(PG8_SB(0, 0), b2, voffB); PG8_STAGE(PG8_SB(0, 1), b2 + hstep, voffB); PG8_STAGE(PG8_SA(0, 0), a2, voffA);
;             PG8_WAIT_V(8); PG8_WAIT_L(0); PG8_BAR; PG8_MMA(1, 0, At, B0); PG8_MMA(1, 1, At, B1); PG8_BAR; PG8_SCHED;
;             PG8_LDB(B0, 1, 0); PG8_LDB(B1, 1, 1); PG8_SCHED; PG8_LDA(At, 1, 0); PG8_STAGE(PG8_SA(0, 1), a2 + hstep, voffA);
;             PG8_WAIT_V(8); PG8_WAIT_L(0); PG8_BAR; PG8_MMA(0, 0, At, B0); PG8_MMA(0, 1, At, B1); PG8_BAR; PG8_SCHED;
;             PG8_LDA(At, 1, 1); PG8_STAGE(PG8_SB(1, 0), b3, voffB); PG8_STAGE(PG8_SB(1, 1), b3 + hstep, voffB); PG8_STAGE(PG8_SA(1, 0), a3, voffA);
;             PG8_WAIT_V(8); PG8_WAIT_L(0); PG8_BAR; PG8_MMA(1, 0, At, B0); PG8_MMA(1, 1, At, B1); PG8_BAR; PG8_SCHED;
	s_add_i32 s42, s58, s15
	v_lshl_add_u64 v[218:219], v[218:219], 0, s[8:9]
	s_mov_b32 m0, s42
	ds_read_b128 v[184:187], v157 offset:49152
	ds_read_b128 v[188:191], v157 offset:50176
	ds_read_b128 v[192:195], v157 offset:51200
	ds_read_b128 v[196:199], v157 offset:52224
	ds_read_b128 v[200:203], v157 offset:53248
	ds_read_b128 v[206:209], v157 offset:54272
	ds_read_b128 v[210:213], v157 offset:55296
	ds_read_b128 v[214:217], v157 offset:56320
	global_load_lds_dwordx4 v[218:219], off
	s_add_i32 m0, s42, 0x2000
	s_add_u32 s40, s40, 0x40080
	v_lshl_add_u64 v[218:219], v[220:221], 0, s[8:9]
	s_addc_u32 s41, s41, 0
	s_add_i32 s42, s59, s15
	global_load_lds_dwordx4 v[218:219], off
	v_lshl_add_u64 v[218:219], s[40:41], 0, v[132:133]
	s_mov_b32 m0, s42
	s_nop 0
	global_load_lds_dwordx4 v[218:219], off
	v_lshl_add_u64 v[218:219], s[40:41], 0, v[128:129]
	s_add_i32 m0, s42, 0x2000
	s_nop 0
	global_load_lds_dwordx4 v[218:219], off
	s_waitcnt vmcnt(6)
	s_waitcnt lgkmcnt(0)
	s_barrier
	s_setprio 1
	s_waitcnt lgkmcnt(0)
	v_mfma_f32_16x16x32_bf16 v[60:63], v[144:147], v[184:187], v[60:63]
	v_mfma_f32_16x16x32_bf16 v[56:59], v[160:163], v[184:187], v[56:59]
	v_mfma_f32_16x16x32_bf16 v[44:47], v[144:147], v[192:195], v[44:47]
	v_mfma_f32_16x16x32_bf16 v[40:43], v[160:163], v[192:195], v[40:43]
	v_mfma_f32_16x16x32_bf16 v[28:31], v[144:147], v[200:203], v[28:31]
	v_mfma_f32_16x16x32_bf16 v[24:27], v[160:163], v[200:203], v[24:27]
	v_mfma_f32_16x16x32_bf16 v[12:15], v[144:147], v[210:213], v[12:15]
	v_mfma_f32_16x16x32_bf16 v[8:11], v[160:163], v[210:213], v[8:11]
	v_mfma_f32_16x16x32_bf16 v[60:63], v[148:151], v[188:191], v[60:63]
	v_mfma_f32_16x16x32_bf16 v[56:59], v[164:167], v[188:191], v[56:59]
	v_mfma_f32_16x16x32_bf16 v[44:47], v[148:151], v[196:199], v[44:47]
	v_mfma_f32_16x16x32_bf16 v[40:43], v[164:167], v[196:199], v[40:43]
	v_mfma_f32_16x16x32_bf16 v[28:31], v[148:151], v[206:209], v[28:31]
	v_mfma_f32_16x16x32_bf16 v[24:27], v[164:167], v[206:209], v[24:27]
	v_mfma_f32_16x16x32_bf16 v[12:15], v[148:151], v[214:217], v[12:15]
	v_lshl_add_u64 v[218:219], v[222:223], 0, s[8:9]
	s_mov_b32 m0, s47
	s_nop 0
	global_load_lds_dwordx4 v[218:219], off
	v_mfma_f32_16x16x32_bf16 v[8:11], v[164:167], v[214:217], v[8:11]
	s_setprio 0
	s_setprio 1
	v_mfma_f32_16x16x32_bf16 v[52:55], v[168:171], v[184:187], v[52:55]
	v_mfma_f32_16x16x32_bf16 v[48:51], v[176:179], v[184:187], v[48:51]
	v_mfma_f32_16x16x32_bf16 v[36:39], v[168:171], v[192:195], v[36:39]
	v_mfma_f32_16x16x32_bf16 v[32:35], v[176:179], v[192:195], v[32:35]
	v_mfma_f32_16x16x32_bf16 v[20:23], v[168:171], v[200:203], v[20:23]
	v_mfma_f32_16x16x32_bf16 v[16:19], v[176:179], v[200:203], v[16:19]
	v_mfma_f32_16x16x32_bf16 v[4:7], v[168:171], v[210:213], v[4:7]
	v_mfma_f32_16x16x32_bf16 v[0:3], v[176:179], v[210:213], v[0:3]
	v_mfma_f32_16x16x32_bf16 v[52:55], v[172:175], v[188:191], v[52:55]
	v_mfma_f32_16x16x32_bf16 v[48:51], v[180:183], v[188:191], v[48:51]
	v_mfma_f32_16x16x32_bf16 v[36:39], v[172:175], v[196:199], v[36:39]
	v_mfma_f32_16x16x32_bf16 v[32:35], v[180:183], v[196:199], v[32:35]
	v_mfma_f32_16x16x32_bf16 v[20:23], v[172:175], v[206:209], v[20:23]
	v_mfma_f32_16x16x32_bf16 v[16:19], v[180:183], v[206:209], v[16:19]
	v_mfma_f32_16x16x32_bf16 v[4:7], v[172:175], v[214:217], v[4:7]
	v_lshl_add_u64 v[218:219], v[224:225], 0, s[8:9]
	s_mov_b32 m0, s48
	s_nop 0
	global_load_lds_dwordx4 v[218:219], off
	v_mfma_f32_16x16x32_bf16 v[0:3], v[180:183], v[214:217], v[0:3]
	s_setprio 0
	s_barrier
	s_add_i32 s57, s57, 2
	s_add_u32 s38, s38, 0x100
	s_addc_u32 s39, s39, 0
	s_add_u32 s55, s55, 0x100
	s_addc_u32 s56, s56, 0
.LBB0_1900:
	ds_read_b128 v[144:147], v155
	ds_read_b128 v[148:151], v155 offset:1024
	ds_read_b128 v[160:163], v155 offset:2048
	ds_read_b128 v[164:167], v155 offset:3072
	ds_read_b128 v[168:171], v156
	ds_read_b128 v[172:175], v156 offset:1024
	ds_read_b128 v[176:179], v156 offset:2048
	ds_read_b128 v[180:183], v156 offset:3072
	s_add_u32 s40, s38, 0xfffc0080
	s_addc_u32 s41, s39, -1
	s_cmp_eq_u32 s57, 12
	s_cselect_b32 s43, s25, s41
	s_cselect_b32 s42, s53, s40
	s_cselect_b32 s41, s13, s56
	s_cselect_b32 s40, s54, s55
	v_lshl_add_u64 v[218:219], s[38:39], 0, v[136:137]
	s_add_i32 m0, s34, 0xc000
	ds_read_b128 v[184:187], v157
	ds_read_b128 v[188:191], v157 offset:1024
	ds_read_b128 v[192:195], v157 offset:2048
	ds_read_b128 v[196:199], v157 offset:3072
	ds_read_b128 v[200:203], v157 offset:4096
	ds_read_b128 v[206:209], v157 offset:5120
	ds_read_b128 v[210:213], v157 offset:6144
	ds_read_b128 v[214:217], v157 offset:7168
	global_load_lds_dwordx4 v[218:219], off
	v_lshl_add_u64 v[218:219], s[38:39], 0, v[138:139]
	s_add_i32 m0, s34, 0xe000
	s_nop 0
	global_load_lds_dwordx4 v[218:219], off
	s_waitcnt vmcnt(8)
	s_waitcnt lgkmcnt(0)
	s_barrier
; #define PG8_STAGE(bufoff, gbase, voff) do { _Pragma("unroll") for (int _i = 0; _i < 2; ++_i) \
;         __builtin_amdgcn_global_load_lds((const unsigned*)((const char*)(gbase) + (voff)[_i]), (PG8_LAS unsigned*)(lds + (bufoff) + ldsw + _i * 8192), 16, 0, 0); } while (0)
; #define PG8_LDA(dst, b, h) do { _Pragma("unroll") for (int m = 0; m < 4; ++m) _Pragma("unroll") for (int k = 0; k < 2; ++k) dst[m][k] = *(const PG8_LAS bf16x8*)(lds + PG8_SA(b, h) + aoff + m * 2048 + k * 1024); } while (0)
; #define PG8_MMA(ai, bj, At, Bt) do { __builtin_amdgcn_s_setprio(1); _Pragma("unroll") for (int m = 0; m < 4; ++m) _Pragma("unroll") for (int n = 0; n < 2; ++n) _Pragma("unroll") for (int k = 0; k < 2; ++k) \
;         acc[ai][bj][m][n] = __builtin_amdgcn_mfma_f32_16x16x32_bf16(Bt[n][k], At[m][k], acc[ai][bj][m][n], 0, 0, 0); __builtin_amdgcn_s_setprio(0); } while (0)
; #define PG8_WAIT_V(n) asm volatile("s_waitcnt vmcnt(" #n ")" ::: "memory")
; #define PG8_WAIT_L(n) asm volatile("s_waitcnt lgkmcnt(" #n ")" ::: "memory")
; #define PG8_BAR __builtin_amdgcn_s_barrier()
; #define PG8_SCHED __builtin_amdgcn_sched_barrier(0)
; template <class Epi, class Sched, bool ALIGN_EPI = false, bool SP2 = false>
; __device__ __forceinline__ void gemm_phase(PG8_LAS unsigned char* lds, const Gemm g, const Sched& S, const Epi& E) {
;     ...
;             PG8_WAIT_V(8); PG8_WAIT_L(0); PG8_BAR; PG8_MMA(0, 0, At, B0); PG8_MMA(0, 1, At, B1); PG8_BAR; PG8_SCHED;
;             PG8_LDA(At, 0, 1); PG8_STAGE(PG8_SB(0, 0), b2, voffB); PG8_STAGE(PG8_SB(0, 1), b2 + hstep, voffB); PG8_STAGE(PG8_SA(0, 0), a2, voffA);
;             PG8_WAIT_V(8); PG8_WAIT_L(0); PG8_BAR; PG8_MMA(1, 0, At, B0); PG8_MMA(1, 1, At, B1); PG8_BAR; PG8_SCHED;
	s_setprio 1
	s_waitcnt lgkmcnt(0)
	v_mfma_f32_16x16x32_bf16 v[124:127], v[144:147], v[184:187], v[124:127]
	v_mfma_f32_16x16x32_bf16 v[120:123], v[160:163], v[184:187], v[120:123]
	v_mfma_f32_16x16x32_bf16 v[108:111], v[144:147], v[192:195], v[108:111]
	v_mfma_f32_16x16x32_bf16 v[104:107], v[160:163], v[192:195], v[104:107]
	v_mfma_f32_16x16x32_bf16 v[92:95], v[144:147], v[200:203], v[92:95]
	v_mfma_f32_16x16x32_bf16 v[88:91], v[160:163], v[200:203], v[88:91]
	v_mfma_f32_16x16x32_bf16 v[76:79], v[144:147], v[210:213], v[76:79]
	v_mfma_f32_16x16x32_bf16 v[72:75], v[160:163], v[210:213], v[72:75]
	v_mfma_f32_16x16x32_bf16 v[124:127], v[148:151], v[188:191], v[124:127]
	v_mfma_f32_16x16x32_bf16 v[120:123], v[164:167], v[188:191], v[120:123]
	v_mfma_f32_16x16x32_bf16 v[108:111], v[148:151], v[196:199], v[108:111]
	v_mfma_f32_16x16x32_bf16 v[104:107], v[164:167], v[196:199], v[104:107]
	v_mfma_f32_16x16x32_bf16 v[92:95], v[148:151], v[206:209], v[92:95]
	v_mfma_f32_16x16x32_bf16 v[88:91], v[164:167], v[206:209], v[88:91]
	v_mfma_f32_16x16x32_bf16 v[76:79], v[148:151], v[214:217], v[76:79]
	v_mfma_f32_16x16x32_bf16 v[72:75], v[164:167], v[214:217], v[72:75]
	s_setprio 0
	s_setprio 1
	v_mfma_f32_16x16x32_bf16 v[116:119], v[168:171], v[184:187], v[116:119]
	v_mfma_f32_16x16x32_bf16 v[112:115], v[176:179], v[184:187], v[112:115]
	v_mfma_f32_16x16x32_bf16 v[100:103], v[168:171], v[192:195], v[100:103]
	v_mfma_f32_16x16x32_bf16 v[96:99], v[176:179], v[192:195], v[96:99]
	v_mfma_f32_16x16x32_bf16 v[84:87], v[168:171], v[200:203], v[84:87]
	v_mfma_f32_16x16x32_bf16 v[80:83], v[176:179], v[200:203], v[80:83]
	v_mfma_f32_16x16x32_bf16 v[68:71], v[168:171], v[210:213], v[68:71]
	v_mfma_f32_16x16x32_bf16 v[64:67], v[176:179], v[210:213], v[64:67]
	v_mfma_f32_16x16x32_bf16 v[116:119], v[172:175], v[188:191], v[116:119]
	v_mfma_f32_16x16x32_bf16 v[112:115], v[180:183], v[188:191], v[112:115]
	v_mfma_f32_16x16x32_bf16 v[100:103], v[172:175], v[196:199], v[100:103]
	v_mfma_f32_16x16x32_bf16 v[96:99], v[180:183], v[196:199], v[96:99]
	v_mfma_f32_16x16x32_bf16 v[84:87], v[172:175], v[206:209], v[84:87]
	v_mfma_f32_16x16x32_bf16 v[80:83], v[180:183], v[206:209], v[80:83]
	v_mfma_f32_16x16x32_bf16 v[68:71], v[172:175], v[214:217], v[68:71]
	v_mfma_f32_16x16x32_bf16 v[64:67], v[180:183], v[214:217], v[64:67]
	s_setprio 0
	s_barrier
	s_add_i32 s58, s49, s15
	v_lshl_add_u64 v[218:219], s[40:41], 0, v[132:133]
	s_mov_b32 m0, s58
	ds_read_b128 v[184:187], v157 offset:16384
	ds_read_b128 v[188:191], v157 offset:17408
	ds_read_b128 v[192:195], v157 offset:18432
	ds_read_b128 v[196:199], v157 offset:19456
	ds_read_b128 v[200:203], v157 offset:20480
	ds_read_b128 v[206:209], v157 offset:21504
	ds_read_b128 v[210:213], v157 offset:22528
	ds_read_b128 v[214:217], v157 offset:23552
	global_load_lds_dwordx4 v[218:219], off
	s_add_i32 m0, s58, 0x2000
	s_add_u32 s58, s40, 0x40000
	v_lshl_add_u64 v[220:221], s[40:41], 0, v[128:129]
	s_addc_u32 s59, s41, 0
	s_add_i32 s60, s50, s15
	global_load_lds_dwordx4 v[220:221], off
	v_lshl_add_u64 v[222:223], s[58:59], 0, v[132:133]
	s_mov_b32 m0, s60
	global_load_lds_dwordx4 v[222:223], off
	v_lshl_add_u64 v[222:223], s[58:59], 0, v[128:129]
	s_add_i32 m0, s60, 0x2000
	s_nop 0
	global_load_lds_dwordx4 v[222:223], off
	s_waitcnt vmcnt(6)
	s_waitcnt lgkmcnt(0)
	s_barrier
	s_setprio 1
	s_waitcnt lgkmcnt(0)
	v_mfma_f32_16x16x32_bf16 v[60:63], v[144:147], v[184:187], v[60:63]
	v_mfma_f32_16x16x32_bf16 v[56:59], v[160:163], v[184:187], v[56:59]
	v_mfma_f32_16x16x32_bf16 v[44:47], v[144:147], v[192:195], v[44:47]
	v_mfma_f32_16x16x32_bf16 v[40:43], v[160:163], v[192:195], v[40:43]
	v_mfma_f32_16x16x32_bf16 v[28:31], v[144:147], v[200:203], v[28:31]
	v_mfma_f32_16x16x32_bf16 v[24:27], v[160:163], v[200:203], v[24:27]
	v_mfma_f32_16x16x32_bf16 v[12:15], v[144:147], v[210:213], v[12:15]
	v_mfma_f32_16x16x32_bf16 v[8:11], v[160:163], v[210:213], v[8:11]
	v_mfma_f32_16x16x32_bf16 v[60:63], v[148:151], v[188:191], v[60:63]
	v_mfma_f32_16x16x32_bf16 v[56:59], v[164:167], v[188:191], v[56:59]
	v_mfma_f32_16x16x32_bf16 v[44:47], v[148:151], v[196:199], v[44:47]
	v_mfma_f32_16x16x32_bf16 v[40:43], v[164:167], v[196:199], v[40:43]
	v_mfma_f32_16x16x32_bf16 v[28:31], v[148:151], v[206:209], v[28:31]
	v_mfma_f32_16x16x32_bf16 v[24:27], v[164:167], v[206:209], v[24:27]
	v_mfma_f32_16x16x32_bf16 v[12:15], v[148:151], v[214:217], v[12:15]
	v_lshl_add_u64 v[222:223], s[42:43], 0, v[134:135]
	s_mov_b32 m0, s34
	s_nop 0
	global_load_lds_dwordx4 v[222:223], off
	v_mfma_f32_16x16x32_bf16 v[8:11], v[164:167], v[214:217], v[8:11]
	s_setprio 0
	s_setprio 1
	v_mfma_f32_16x16x32_bf16 v[52:55], v[168:171], v[184:187], v[52:55]
	v_mfma_f32_16x16x32_bf16 v[48:51], v[176:179], v[184:187], v[48:51]
	v_mfma_f32_16x16x32_bf16 v[36:39], v[168:171], v[192:195], v[36:39]
	v_mfma_f32_16x16x32_bf16 v[32:35], v[176:179], v[192:195], v[32:35]
	v_mfma_f32_16x16x32_bf16 v[20:23], v[168:171], v[200:203], v[20:23]
	v_mfma_f32_16x16x32_bf16 v[16:19], v[176:179], v[200:203], v[16:19]
	v_mfma_f32_16x16x32_bf16 v[4:7], v[168:171], v[210:213], v[4:7]
	v_mfma_f32_16x16x32_bf16 v[0:3], v[176:179], v[210:213], v[0:3]
	v_mfma_f32_16x16x32_bf16 v[52:55], v[172:175], v[188:191], v[52:55]
	v_mfma_f32_16x16x32_bf16 v[48:51], v[180:183], v[188:191], v[48:51]
	v_mfma_f32_16x16x32_bf16 v[36:39], v[172:175], v[196:199], v[36:39]
	v_mfma_f32_16x16x32_bf16 v[32:35], v[180:183], v[196:199], v[32:35]
	v_mfma_f32_16x16x32_bf16 v[20:23], v[172:175], v[206:209], v[20:23]
	v_mfma_f32_16x16x32_bf16 v[16:19], v[180:183], v[206:209], v[16:19]
	v_mfma_f32_16x16x32_bf16 v[4:7], v[172:175], v[214:217], v[4:7]
	v_lshl_add_u64 v[224:225], s[42:43], 0, v[130:131]
	s_mov_b32 m0, s37
	s_nop 0
	global_load_lds_dwordx4 v[224:225], off
	v_mfma_f32_16x16x32_bf16 v[0:3], v[180:183], v[214:217], v[0:3]
	s_setprio 0
	s_barrier
; #define PG8_STAGE(bufoff, gbase, voff) do { _Pragma("unroll") for (int _i = 0; _i < 2; ++_i) \
;         __builtin_amdgcn_global_load_lds((const unsigned*)((const char*)(gbase) + (voff)[_i]), (PG8_LAS unsigned*)(lds + (bufoff) + ldsw + _i * 8192), 16, 0, 0); } while (0)
; #define PG8_LDA(dst, b, h) do { _Pragma("unroll") for (int m = 0; m < 4; ++m) _Pragma("unroll") for (int k = 0; k < 2; ++k) dst[m][k] = *(const PG8_LAS bf16x8*)(lds + PG8_SA(b, h) + aoff + m * 2048 + k * 1024); } while (0)
; #define PG8_LDB(dst, b, h) do { _Pragma("unroll") for (int n = 0; n < 2; ++n) _Pragma("unroll") for (int k = 0; k < 2; ++k) dst[n][k] = *(const PG8_LAS bf16x8*)(lds + PG8_SB(b, h) + boff + n * 2048 + k * 1024); } while (0)
; #define PG8_MMA(ai, bj, At, Bt) do { __builtin_amdgcn_s_setprio(1); _Pragma("unroll") for (int m = 0; m < 4; ++m) _Pragma("unroll") for (int n = 0; n < 2; ++n) _Pragma("unroll") for (int k = 0; k < 2; ++k) \
;         acc[ai][bj][m][n] = __builtin_amdgcn_mfma_f32_16x16x32_bf16(Bt[n][k], At[m][k], acc[ai][bj][m][n], 0, 0, 0); __builtin_amdgcn_s_setprio(0); } while (0)
; #define PG8_WAIT_V(n) asm volatile("s_waitcnt vmcnt(" #n ")" ::: "memory")
; #define PG8_WAIT_L(n) asm volatile("s_waitcnt lgkmcnt(" #n ")" ::: "memory")
; #define PG8_BAR __builtin_amdgcn_s_barrier()
; #define PG8_SCHED __builtin_amdgcn_sched_barrier(0)
; template <class Epi, class Sched, bool ALIGN_EPI = false, bool SP2 = false>
; __device__ __forceinline__ void gemm_phase(PG8_LAS unsigned char* lds, const Gemm g, const Sched& S, const Epi& E) {
;     ...
;             PG8_LDB(B0, 1, 0); PG8_LDB(B1, 1, 1); PG8_SCHED; PG8_LDA(At, 1, 0); PG8_STAGE(PG8_SA(0, 1), a2 + hstep, voffA);
;             PG8_WAIT_V(8); PG8_WAIT_L(0); PG8_BAR; PG8_MMA(0, 0, At, B0); PG8_MMA(0, 1, At, B1); PG8_BAR; PG8_SCHED;
	s_add_i32 s58, 0, 0x18000
	v_add_u32_e32 v159, s58, v153
	s_add_i32 s59, 0, 0x1c000
	ds_read_b128 v[144:147], v159
	ds_read_b128 v[148:151], v159 offset:1024
	ds_read_b128 v[160:163], v159 offset:2048
	ds_read_b128 v[164:167], v159 offset:3072
	v_add_u32_e32 v159, s59, v153
	ds_read_b128 v[168:171], v159
	ds_read_b128 v[172:175], v159 offset:1024
	ds_read_b128 v[176:179], v159 offset:2048
	ds_read_b128 v[180:183], v159 offset:3072
	s_add_u32 s42, s42, 0x40000
	s_addc_u32 s43, s43, 0
	s_mov_b32 m0, s44
	v_lshl_add_u64 v[226:227], s[42:43], 0, v[134:135]
	ds_read_b128 v[184:187], v157 offset:32768
	ds_read_b128 v[188:191], v157 offset:33792
	ds_read_b128 v[192:195], v157 offset:34816
	ds_read_b128 v[196:199], v157 offset:35840
	ds_read_b128 v[200:203], v157 offset:36864
	ds_read_b128 v[206:209], v157 offset:37888
	ds_read_b128 v[210:213], v157 offset:38912
	ds_read_b128 v[214:217], v157 offset:39936
	global_load_lds_dwordx4 v[226:227], off
	v_lshl_add_u64 v[226:227], s[42:43], 0, v[130:131]
	s_mov_b32 m0, s45
	s_nop 0
	global_load_lds_dwordx4 v[226:227], off
	s_waitcnt vmcnt(8)
	s_waitcnt lgkmcnt(0)
	s_barrier
	s_setprio 1
	s_waitcnt lgkmcnt(0)
	v_mfma_f32_16x16x32_bf16 v[124:127], v[144:147], v[184:187], v[124:127]
	v_mfma_f32_16x16x32_bf16 v[120:123], v[160:163], v[184:187], v[120:123]
	v_mfma_f32_16x16x32_bf16 v[108:111], v[144:147], v[192:195], v[108:111]
	v_mfma_f32_16x16x32_bf16 v[104:107], v[160:163], v[192:195], v[104:107]
	v_mfma_f32_16x16x32_bf16 v[92:95], v[144:147], v[200:203], v[92:95]
	v_mfma_f32_16x16x32_bf16 v[88:91], v[160:163], v[200:203], v[88:91]
	v_mfma_f32_16x16x32_bf16 v[76:79], v[144:147], v[210:213], v[76:79]
	v_mfma_f32_16x16x32_bf16 v[72:75], v[160:163], v[210:213], v[72:75]
	v_mfma_f32_16x16x32_bf16 v[124:127], v[148:151], v[188:191], v[124:127]
	v_mfma_f32_16x16x32_bf16 v[120:123], v[164:167], v[188:191], v[120:123]
	v_mfma_f32_16x16x32_bf16 v[108:111], v[148:151], v[196:199], v[108:111]
	v_mfma_f32_16x16x32_bf16 v[104:107], v[164:167], v[196:199], v[104:107]
	v_mfma_f32_16x16x32_bf16 v[92:95], v[148:151], v[206:209], v[92:95]
	v_mfma_f32_16x16x32_bf16 v[88:91], v[164:167], v[206:209], v[88:91]
	v_mfma_f32_16x16x32_bf16 v[76:79], v[148:151], v[214:217], v[76:79]
	v_mfma_f32_16x16x32_bf16 v[72:75], v[164:167], v[214:217], v[72:75]
	s_setprio 0
	s_setprio 1
	v_mfma_f32_16x16x32_bf16 v[116:119], v[168:171], v[184:187], v[116:119]
	v_mfma_f32_16x16x32_bf16 v[112:115], v[176:179], v[184:187], v[112:115]
	v_mfma_f32_16x16x32_bf16 v[100:103], v[168:171], v[192:195], v[100:103]
	v_mfma_f32_16x16x32_bf16 v[96:99], v[176:179], v[192:195], v[96:99]
	v_mfma_f32_16x16x32_bf16 v[84:87], v[168:171], v[200:203], v[84:87]
	v_mfma_f32_16x16x32_bf16 v[80:83], v[176:179], v[200:203], v[80:83]
	v_mfma_f32_16x16x32_bf16 v[68:71], v[168:171], v[210:213], v[68:71]
	v_mfma_f32_16x16x32_bf16 v[64:67], v[176:179], v[210:213], v[64:67]
	v_mfma_f32_16x16x32_bf16 v[116:119], v[172:175], v[188:191], v[116:119]
	v_mfma_f32_16x16x32_bf16 v[112:115], v[180:183], v[188:191], v[112:115]
	v_mfma_f32_16x16x32_bf16 v[100:103], v[172:175], v[196:199], v[100:103]
	v_mfma_f32_16x16x32_bf16 v[96:99], v[180:183], v[196:199], v[96:99]
	v_mfma_f32_16x16x32_bf16 v[84:87], v[172:175], v[206:209], v[84:87]
	v_mfma_f32_16x16x32_bf16 v[80:83], v[180:183], v[206:209], v[80:83]
	v_mfma_f32_16x16x32_bf16 v[68:71], v[172:175], v[214:217], v[68:71]
	v_mfma_f32_16x16x32_bf16 v[64:67], v[180:183], v[214:217], v[64:67]
	s_setprio 0
	s_barrier
; #define PG8_STAGE(bufoff, gbase, voff) do { _Pragma("unroll") for (int _i = 0; _i < 2; ++_i) \
;         __builtin_amdgcn_global_load_lds((const unsigned*)((const char*)(gbase) + (voff)[_i]), (PG8_LAS unsigned*)(lds + (bufoff) + ldsw + _i * 8192), 16, 0, 0); } while (0)
; #define PG8_LDA(dst, b, h) do { _Pragma("unroll") for (int m = 0; m < 4; ++m) _Pragma("unroll") for (int k = 0; k < 2; ++k) dst[m][k] = *(const PG8_LAS bf16x8*)(lds + PG8_SA(b, h) + aoff + m * 2048 + k * 1024); } while (0)
; #define PG8_MMA(ai, bj, At, Bt) do { __builtin_amdgcn_s_setprio(1); _Pragma("unroll") for (int m = 0; m < 4; ++m) _Pragma("unroll") for (int n = 0; n < 2; ++n) _Pragma("unroll") for (int k = 0; k < 2; ++k) \
;         acc[ai][bj][m][n] = __builtin_amdgcn_mfma_f32_16x16x32_bf16(Bt[n][k], At[m][k], acc[ai][bj][m][n], 0, 0, 0); __builtin_amdgcn_s_setprio(0); } while (0)
; #define PG8_WAIT_V(n) asm volatile("s_waitcnt vmcnt(" #n ")" ::: "memory")
; #define PG8_WAIT_L(n) asm volatile("s_waitcnt lgkmcnt(" #n ")" ::: "memory")
; #define PG8_BAR __builtin_amdgcn_s_barrier()
; #define PG8_SCHED __builtin_amdgcn_sched_barrier(0)
;     __device__ __forceinline__ void operator()(const f32x4 (&acc)[2][2][4][2], const Unit& u, int wr, int wc, int fr, int fq) const {
;         const int row0 = u.pm * BM + wr * 64 + fr, col0 = u.pn * HALF + wc * 32 + 8 * fq;
; #pragma unroll
;         for (int ai = 0; ai < 2; ++ai)
; #pragma unroll
;             for (int m = 0; m < 4; ++m) { const int row = row0 + ai * HALF + m * 16; const float rs = row_rs(ss, row);
; template <class Epi, class Sched, bool ALIGN_EPI = false, bool SP2 = false>
; __device__ __forceinline__ void gemm_phase(PG8_LAS unsigned char* lds, const Gemm g, const Sched& S, const Epi& E) {
;     ...
;             PG8_LDA(At, 1, 1); PG8_STAGE(PG8_SB(1, 0), b3, voffB); PG8_STAGE(PG8_SB(1, 1), b3 + hstep, voffB); PG8_STAGE(PG8_SA(1, 0), a3, voffA);
;             PG8_WAIT_V(8); PG8_WAIT_L(0); PG8_BAR; PG8_MMA(1, 0, At, B0); PG8_MMA(1, 1, At, B1); PG8_BAR; PG8_SCHED;
	s_add_i32 s42, s58, s15
	v_lshl_add_u64 v[218:219], v[218:219], 0, s[8:9]
	s_mov_b32 m0, s42
	ds_read_b128 v[184:187], v157 offset:49152
	ds_read_b128 v[188:191], v157 offset:50176
	ds_read_b128 v[192:195], v157 offset:51200
	ds_read_b128 v[196:199], v157 offset:52224
	ds_read_b128 v[200:203], v157 offset:53248
	ds_read_b128 v[206:209], v157 offset:54272
	ds_read_b128 v[210:213], v157 offset:55296
	ds_read_b128 v[214:217], v157 offset:56320
	global_load_lds_dwordx4 v[218:219], off
	s_add_i32 m0, s42, 0x2000
	s_add_u32 s40, s40, 0x40080
	v_lshl_add_u64 v[218:219], v[220:221], 0, s[8:9]
	s_addc_u32 s41, s41, 0
	s_add_i32 s42, s59, s15
	global_load_lds_dwordx4 v[218:219], off
	v_lshl_add_u64 v[218:219], s[40:41], 0, v[132:133]
	s_mov_b32 m0, s42
	s_nop 0
	global_load_lds_dwordx4 v[218:219], off
	v_lshl_add_u64 v[218:219], s[40:41], 0, v[128:129]
	s_add_i32 m0, s42, 0x2000
	s_nop 0
	global_load_lds_dwordx4 v[218:219], off
	s_waitcnt vmcnt(6)
	s_waitcnt lgkmcnt(0)
	s_barrier
	s_setprio 1
	s_waitcnt lgkmcnt(0)
	v_mfma_f32_16x16x32_bf16 v[60:63], v[144:147], v[184:187], v[60:63]
	v_mfma_f32_16x16x32_bf16 v[56:59], v[160:163], v[184:187], v[56:59]
	v_mfma_f32_16x16x32_bf16 v[44:47], v[144:147], v[192:195], v[44:47]
	v_mfma_f32_16x16x32_bf16 v[40:43], v[160:163], v[192:195], v[40:43]
	v_mfma_f32_16x16x32_bf16 v[28:31], v[144:147], v[200:203], v[28:31]
	v_mfma_f32_16x16x32_bf16 v[24:27], v[160:163], v[200:203], v[24:27]
	v_mfma_f32_16x16x32_bf16 v[12:15], v[144:147], v[210:213], v[12:15]
	v_mfma_f32_16x16x32_bf16 v[8:11], v[160:163], v[210:213], v[8:11]
	v_mfma_f32_16x16x32_bf16 v[60:63], v[148:151], v[188:191], v[60:63]
	v_mfma_f32_16x16x32_bf16 v[56:59], v[164:167], v[188:191], v[56:59]
	v_mfma_f32_16x16x32_bf16 v[44:47], v[148:151], v[196:199], v[44:47]
	v_mfma_f32_16x16x32_bf16 v[40:43], v[164:167], v[196:199], v[40:43]
	v_mfma_f32_16x16x32_bf16 v[28:31], v[148:151], v[206:209], v[28:31]
	v_mfma_f32_16x16x32_bf16 v[24:27], v[164:167], v[206:209], v[24:27]
	v_mfma_f32_16x16x32_bf16 v[12:15], v[148:151], v[214:217], v[12:15]
	v_lshl_add_u64 v[218:219], v[222:223], 0, s[8:9]
	s_mov_b32 m0, s47
	s_nop 0
	global_load_lds_dwordx4 v[218:219], off
	v_mfma_f32_16x16x32_bf16 v[8:11], v[164:167], v[214:217], v[8:11]
	s_setprio 0
	s_setprio 1
	v_mfma_f32_16x16x32_bf16 v[52:55], v[168:171], v[184:187], v[52:55]
	v_mfma_f32_16x16x32_bf16 v[48:51], v[176:179], v[184:187], v[48:51]
	v_mfma_f32_16x16x32_bf16 v[36:39], v[168:171], v[192:195], v[36:39]
	v_mfma_f32_16x16x32_bf16 v[32:35], v[176:179], v[192:195], v[32:35]
	v_mfma_f32_16x16x32_bf16 v[20:23], v[168:171], v[200:203], v[20:23]
	v_mfma_f32_16x16x32_bf16 v[16:19], v[176:179], v[200:203], v[16:19]
	v_mfma_f32_16x16x32_bf16 v[4:7], v[168:171], v[210:213], v[4:7]
	v_mfma_f32_16x16x32_bf16 v[0:3], v[176:179], v[210:213], v[0:3]
	v_mfma_f32_16x16x32_bf16 v[52:55], v[172:175], v[188:191], v[52:55]
	v_mfma_f32_16x16x32_bf16 v[48:51], v[180:183], v[188:191], v[48:51]
	v_mfma_f32_16x16x32_bf16 v[36:39], v[172:175], v[196:199], v[36:39]
	v_mfma_f32_16x16x32_bf16 v[32:35], v[180:183], v[196:199], v[32:35]
	v_mfma_f32_16x16x32_bf16 v[20:23], v[172:175], v[206:209], v[20:23]
	v_mfma_f32_16x16x32_bf16 v[16:19], v[180:183], v[206:209], v[16:19]
	v_mfma_f32_16x16x32_bf16 v[4:7], v[172:175], v[214:217], v[4:7]
	v_lshl_add_u64 v[218:219], v[224:225], 0, s[8:9]
	s_mov_b32 m0, s48
	s_nop 0
	global_load_lds_dwordx4 v[218:219], off
	v_mfma_f32_16x16x32_bf16 v[0:3], v[180:183], v[214:217], v[0:3]
	s_setprio 0
	s_barrier
	s_add_i32 s57, s57, 2
	s_add_u32 s38, s38, 0x100
	s_addc_u32 s39, s39, 0
	s_add_u32 s55, s55, 0x100
	s_addc_u32 s56, s56, 0
	s_cmp_gt_u32 s57, 13
	s_cbranch_scc0 .LBB0_1900
	v_lshl_add_u32 v144, s36, 8, v152
	v_ashrrev_i32_e32 v145, 31, v144
	v_lshl_add_u64 v[150:151], v[144:145], 3, s[0:1]
	global_load_dwordx2 v[182:183], v[150:151], off
	global_load_dwordx2 v[184:185], v[150:151], off offset:128
	global_load_dwordx2 v[186:187], v[150:151], off offset:256
	global_load_dwordx2 v[188:189], v[150:151], off offset:384
	global_load_dwordx2 v[190:191], v[150:151], off offset:1024
	global_load_dwordx2 v[192:193], v[150:151], off offset:1152
	global_load_dwordx2 v[194:195], v[150:151], off offset:1280
	global_load_dwordx2 v[196:197], v[150:151], off offset:1408
	s_and_b64 vcc, exec, s[10:11]
	s_cbranch_vccz .LBB0_1903
	s_barrier

; #define PG8_STAGE(bufoff, gbase, voff) do { _Pragma("unroll") for (int _i = 0; _i < 2; ++_i) \
;         __builtin_amdgcn_global_load_lds((const unsigned*)((const char*)(gbase) + (voff)[_i]), (PG8_LAS unsigned*)(lds + (bufoff) + ldsw + _i * 8192), 16, 0, 0); } while (0)
; #define PG8_LDA(dst, b, h) do { _Pragma("unroll") for (int m = 0; m < 4; ++m) _Pragma("unroll") for (int k = 0; k < 2; ++k) dst[m][k] = *(const PG8_LAS bf16x8*)(lds + PG8_SA(b, h) + aoff + m * 2048 + k * 1024); } while (0)
; #define PG8_LDB(dst, b, h) do { _Pragma("unroll") for (int n = 0; n < 2; ++n) _Pragma("unroll") for (int k = 0; k < 2; ++k) dst[n][k] = *(const PG8_LAS bf16x8*)(lds + PG8_SB(b, h) + boff + n * 2048 + k * 1024); } while (0)
; #define PG8_MMA(ai, bj, At, Bt) do { __builtin_amdgcn_s_setprio(1); _Pragma("unroll") for (int m = 0; m < 4; ++m) _Pragma("unroll") for (int n = 0; n < 2; ++n) _Pragma("unroll") for (int k = 0; k < 2; ++k) \
;         acc[ai][bj][m][n] = __builtin_amdgcn_mfma_f32_16x16x32_bf16(Bt[n][k], At[m][k], acc[ai][bj][m][n], 0, 0, 0); __builtin_amdgcn_s_setprio(0); } while (0)
; #define PG8_WAIT_V(n) asm volatile("s_waitcnt vmcnt(" #n ")" ::: "memory")
; #define PG8_WAIT_L(n) asm volatile("s_waitcnt lgkmcnt(" #n ")" ::: "memory")
; #define PG8_BAR __builtin_amdgcn_s_barrier()
; #define PG8_SCHED __builtin_amdgcn_sched_barrier(0)
; template <class Epi, class Sched, bool ALIGN_EPI = false, bool SP2 = false>
; __device__ __forceinline__ void gemm_phase(PG8_LAS unsigned char* lds, const Gemm g, const Sched& S, const Epi& E) {
;     ...
;             PG8_LDB(B0, 0, 0); PG8_LDB(B1, 0, 1); PG8_SCHED; PG8_LDA(At, 0, 0); PG8_STAGE(PG8_SA(1, 1), a1 + hstep, voffA);
;             PG8_WAIT_V(8); PG8_WAIT_L(0); PG8_BAR; PG8_MMA(0, 0, At, B0); PG8_MMA(0, 1, At, B1); PG8_BAR; PG8_SCHED;
;             PG8_LDA(At, 0, 1); PG8_STAGE(PG8_SB(0, 0), b2, voffB); PG8_STAGE(PG8_SB(0, 1), b2 + hstep, voffB); PG8_STAGE(PG8_SA(0, 0), a2, voffA);
;             PG8_WAIT_V(8); PG8_WAIT_L(0); PG8_BAR; PG8_MMA(1, 0, At, B0); PG8_MMA(1, 1, At, B1); PG8_BAR; PG8_SCHED;
.LBB0_1977:
	s_add_u32 s53, s28, 0x100
	s_addc_u32 s54, s29, 0
	s_mov_b32 s55, -2
	s_waitcnt lgkmcnt(0)
	ds_read_b128 v[144:147], v151
	ds_read_b128 v[156:159], v151 offset:1024
	ds_read_b128 v[160:163], v151 offset:2048
	ds_read_b128 v[164:167], v151 offset:3072
	ds_read_b128 v[168:171], v152
	ds_read_b128 v[172:175], v152 offset:1024
	ds_read_b128 v[176:179], v152 offset:2048
	ds_read_b128 v[180:183], v152 offset:3072
	s_add_u32 s28, s26, 0x100
	s_addc_u32 s29, s27, 0
	s_cmp_eq_u32 s55, 40
	s_cselect_b32 s39, s1, s29
	s_cselect_b32 s38, s0, s28
	s_cselect_b32 s37, s25, s54
	s_cselect_b32 s36, s24, s53
	v_lshl_add_u64 v[218:219], s[26:27], 0, v[136:137]
	s_add_i32 m0, s33, 0xc000
	ds_read_b128 v[184:187], v153
	ds_read_b128 v[188:191], v153 offset:1024
	ds_read_b128 v[192:195], v153 offset:2048
	ds_read_b128 v[196:199], v153 offset:3072
	ds_read_b128 v[200:203], v153 offset:4096
	ds_read_b128 v[206:209], v153 offset:5120
	ds_read_b128 v[210:213], v153 offset:6144
	ds_read_b128 v[214:217], v153 offset:7168
	global_load_lds_dwordx4 v[218:219], off
	v_lshl_add_u64 v[218:219], s[26:27], 0, v[138:139]
	s_add_i32 m0, s33, 0xe000
	s_nop 0
	global_load_lds_dwordx4 v[218:219], off
	s_waitcnt vmcnt(8)
	s_waitcnt lgkmcnt(0)
	s_barrier
	s_setprio 1
	s_waitcnt lgkmcnt(0)
	v_mfma_f32_16x16x32_bf16 v[124:127], v[144:147], v[184:187], 0
	v_mfma_f32_16x16x32_bf16 v[120:123], v[160:163], v[184:187], 0
	v_mfma_f32_16x16x32_bf16 v[108:111], v[144:147], v[192:195], 0
	v_mfma_f32_16x16x32_bf16 v[104:107], v[160:163], v[192:195], 0
	v_mfma_f32_16x16x32_bf16 v[92:95], v[144:147], v[200:203], 0
	v_mfma_f32_16x16x32_bf16 v[88:91], v[160:163], v[200:203], 0
	v_mfma_f32_16x16x32_bf16 v[76:79], v[144:147], v[210:213], 0
	v_mfma_f32_16x16x32_bf16 v[72:75], v[160:163], v[210:213], 0
	v_mfma_f32_16x16x32_bf16 v[124:127], v[156:159], v[188:191], v[124:127]
	v_mfma_f32_16x16x32_bf16 v[120:123], v[164:167], v[188:191], v[120:123]
	v_mfma_f32_16x16x32_bf16 v[108:111], v[156:159], v[196:199], v[108:111]
	v_mfma_f32_16x16x32_bf16 v[104:107], v[164:167], v[196:199], v[104:107]
	v_mfma_f32_16x16x32_bf16 v[92:95], v[156:159], v[206:209], v[92:95]
	v_mfma_f32_16x16x32_bf16 v[88:91], v[164:167], v[206:209], v[88:91]
	v_mfma_f32_16x16x32_bf16 v[76:79], v[156:159], v[214:217], v[76:79]
	v_mfma_f32_16x16x32_bf16 v[72:75], v[164:167], v[214:217], v[72:75]
	s_setprio 0
	s_setprio 1
	v_mfma_f32_16x16x32_bf16 v[116:119], v[168:171], v[184:187], 0
	v_mfma_f32_16x16x32_bf16 v[112:115], v[176:179], v[184:187], 0
	v_mfma_f32_16x16x32_bf16 v[100:103], v[168:171], v[192:195], 0
	v_mfma_f32_16x16x32_bf16 v[96:99], v[176:179], v[192:195], 0
	v_mfma_f32_16x16x32_bf16 v[84:87], v[168:171], v[200:203], 0
	v_mfma_f32_16x16x32_bf16 v[80:83], v[176:179], v[200:203], 0
	v_mfma_f32_16x16x32_bf16 v[68:71], v[168:171], v[210:213], 0
	v_mfma_f32_16x16x32_bf16 v[64:67], v[176:179], v[210:213], 0
	v_mfma_f32_16x16x32_bf16 v[116:119], v[172:175], v[188:191], v[116:119]
	v_mfma_f32_16x16x32_bf16 v[112:115], v[180:183], v[188:191], v[112:115]
	v_mfma_f32_16x16x32_bf16 v[100:103], v[172:175], v[196:199], v[100:103]
	v_mfma_f32_16x16x32_bf16 v[96:99], v[180:183], v[196:199], v[96:99]
	v_mfma_f32_16x16x32_bf16 v[84:87], v[172:175], v[206:209], v[84:87]
	v_mfma_f32_16x16x32_bf16 v[80:83], v[180:183], v[206:209], v[80:83]
	v_mfma_f32_16x16x32_bf16 v[68:71], v[172:175], v[214:217], v[68:71]
	v_mfma_f32_16x16x32_bf16 v[64:67], v[180:183], v[214:217], v[64:67]
	s_setprio 0
	s_barrier
	s_add_i32 s26, s45, s15
	v_lshl_add_u64 v[218:219], s[36:37], 0, v[130:131]
	s_mov_b32 m0, s26
	ds_read_b128 v[184:187], v153 offset:16384
	ds_read_b128 v[188:191], v153 offset:17408
	ds_read_b128 v[192:195], v153 offset:18432
	ds_read_b128 v[196:199], v153 offset:19456
	ds_read_b128 v[200:203], v153 offset:20480
	ds_read_b128 v[206:209], v153 offset:21504
	ds_read_b128 v[210:213], v153 offset:22528
	ds_read_b128 v[214:217], v153 offset:23552
	global_load_lds_dwordx4 v[218:219], off
	s_add_i32 m0, s26, 0x2000
	s_add_u32 s26, s36, 0xb0000
	v_lshl_add_u64 v[220:221], s[36:37], 0, v[134:135]
	s_addc_u32 s27, s37, 0
	s_add_i32 s56, s46, s15
	global_load_lds_dwordx4 v[220:221], off
	v_lshl_add_u64 v[222:223], s[26:27], 0, v[130:131]
	s_mov_b32 m0, s56
	global_load_lds_dwordx4 v[222:223], off
	v_lshl_add_u64 v[222:223], s[26:27], 0, v[134:135]
	s_add_i32 m0, s56, 0x2000
	s_nop 0
	global_load_lds_dwordx4 v[222:223], off
	s_waitcnt vmcnt(6)
	s_waitcnt lgkmcnt(0)
	s_barrier
; #define PG8_STAGE(bufoff, gbase, voff) do { _Pragma("unroll") for (int _i = 0; _i < 2; ++_i) \
;         __builtin_amdgcn_global_load_lds((const unsigned*)((const char*)(gbase) + (voff)[_i]), (PG8_LAS unsigned*)(lds + (bufoff) + ldsw + _i * 8192), 16, 0, 0); } while (0)
; #define PG8_LDA(dst, b, h) do { _Pragma("unroll") for (int m = 0; m < 4; ++m) _Pragma("unroll") for (int k = 0; k < 2; ++k) dst[m][k] = *(const PG8_LAS bf16x8*)(lds + PG8_SA(b, h) + aoff + m * 2048 + k * 1024); } while (0)
; #define PG8_LDB(dst, b, h) do { _Pragma("unroll") for (int n = 0; n < 2; ++n) _Pragma("unroll") for (int k = 0; k < 2; ++k) dst[n][k] = *(const PG8_LAS bf16x8*)(lds + PG8_SB(b, h) + boff + n * 2048 + k * 1024); } while (0)
; #define PG8_MMA(ai, bj, At, Bt) do { __builtin_amdgcn_s_setprio(1); _Pragma("unroll") for (int m = 0; m < 4; ++m) _Pragma("unroll") for (int n = 0; n < 2; ++n) _Pragma("unroll") for (int k = 0; k < 2; ++k) \
;         acc[ai][bj][m][n] = __builtin_amdgcn_mfma_f32_16x16x32_bf16(Bt[n][k], At[m][k], acc[ai][bj][m][n], 0, 0, 0); __builtin_amdgcn_s_setprio(0); } while (0)
; #define PG8_WAIT_V(n) asm volatile("s_waitcnt vmcnt(" #n ")" ::: "memory")
; #define PG8_WAIT_L(n) asm volatile("s_waitcnt lgkmcnt(" #n ")" ::: "memory")
; #define PG8_BAR __builtin_amdgcn_s_barrier()
; #define PG8_SCHED __builtin_amdgcn_sched_barrier(0)
; template <class Epi, class Sched, bool ALIGN_EPI = false, bool SP2 = false>
; __device__ __forceinline__ void gemm_phase(PG8_LAS unsigned char* lds, const Gemm g, const Sched& S, const Epi& E) {
;     ...
;             PG8_WAIT_V(8); PG8_WAIT_L(0); PG8_BAR; PG8_MMA(1, 0, At, B0); PG8_MMA(1, 1, At, B1); PG8_BAR; PG8_SCHED;
;             PG8_LDB(B0, 1, 0); PG8_LDB(B1, 1, 1); PG8_SCHED; PG8_LDA(At, 1, 0); PG8_STAGE(PG8_SA(0, 1), a2 + hstep, voffA);
;             PG8_WAIT_V(8); PG8_WAIT_L(0); PG8_BAR; PG8_MMA(0, 0, At, B0); PG8_MMA(0, 1, At, B1); PG8_BAR; PG8_SCHED;
	s_setprio 1
	s_waitcnt lgkmcnt(0)
	v_mfma_f32_16x16x32_bf16 v[60:63], v[144:147], v[184:187], 0
	v_mfma_f32_16x16x32_bf16 v[56:59], v[160:163], v[184:187], 0
	v_mfma_f32_16x16x32_bf16 v[44:47], v[144:147], v[192:195], 0
	v_mfma_f32_16x16x32_bf16 v[40:43], v[160:163], v[192:195], 0
	v_mfma_f32_16x16x32_bf16 v[28:31], v[144:147], v[200:203], 0
	v_mfma_f32_16x16x32_bf16 v[24:27], v[160:163], v[200:203], 0
	v_mfma_f32_16x16x32_bf16 v[12:15], v[144:147], v[210:213], 0
	v_mfma_f32_16x16x32_bf16 v[8:11], v[160:163], v[210:213], 0
	v_mfma_f32_16x16x32_bf16 v[60:63], v[156:159], v[188:191], v[60:63]
	v_mfma_f32_16x16x32_bf16 v[56:59], v[164:167], v[188:191], v[56:59]
	v_mfma_f32_16x16x32_bf16 v[44:47], v[156:159], v[196:199], v[44:47]
	v_mfma_f32_16x16x32_bf16 v[40:43], v[164:167], v[196:199], v[40:43]
	v_mfma_f32_16x16x32_bf16 v[28:31], v[156:159], v[206:209], v[28:31]
	v_mfma_f32_16x16x32_bf16 v[24:27], v[164:167], v[206:209], v[24:27]
	v_mfma_f32_16x16x32_bf16 v[12:15], v[156:159], v[214:217], v[12:15]
	v_lshl_add_u64 v[222:223], s[38:39], 0, v[128:129]
	s_mov_b32 m0, s33
	s_nop 0
	global_load_lds_dwordx4 v[222:223], off
	v_mfma_f32_16x16x32_bf16 v[8:11], v[164:167], v[214:217], v[8:11]
	s_setprio 0
	s_setprio 1
	v_mfma_f32_16x16x32_bf16 v[52:55], v[168:171], v[184:187], 0
	v_mfma_f32_16x16x32_bf16 v[48:51], v[176:179], v[184:187], 0
	v_mfma_f32_16x16x32_bf16 v[36:39], v[168:171], v[192:195], 0
	v_mfma_f32_16x16x32_bf16 v[32:35], v[176:179], v[192:195], 0
	v_mfma_f32_16x16x32_bf16 v[20:23], v[168:171], v[200:203], 0
	v_mfma_f32_16x16x32_bf16 v[16:19], v[176:179], v[200:203], 0
	v_mfma_f32_16x16x32_bf16 v[4:7], v[168:171], v[210:213], 0
	v_mfma_f32_16x16x32_bf16 v[0:3], v[176:179], v[210:213], 0
	v_mfma_f32_16x16x32_bf16 v[52:55], v[172:175], v[188:191], v[52:55]
	v_mfma_f32_16x16x32_bf16 v[48:51], v[180:183], v[188:191], v[48:51]
	v_mfma_f32_16x16x32_bf16 v[36:39], v[172:175], v[196:199], v[36:39]
	v_mfma_f32_16x16x32_bf16 v[32:35], v[180:183], v[196:199], v[32:35]
	v_mfma_f32_16x16x32_bf16 v[20:23], v[172:175], v[206:209], v[20:23]
	v_mfma_f32_16x16x32_bf16 v[16:19], v[180:183], v[206:209], v[16:19]
	v_mfma_f32_16x16x32_bf16 v[4:7], v[172:175], v[214:217], v[4:7]
	v_lshl_add_u64 v[224:225], s[38:39], 0, v[132:133]
	s_mov_b32 m0, s34
	s_nop 0
	global_load_lds_dwordx4 v[224:225], off
	v_mfma_f32_16x16x32_bf16 v[0:3], v[180:183], v[214:217], v[0:3]
	s_setprio 0
	s_barrier
	s_add_i32 s56, 0, 0x18000
	v_add_u32_e32 v155, s56, v149
	s_add_i32 s57, 0, 0x1c000
	ds_read_b128 v[144:147], v155
	ds_read_b128 v[156:159], v155 offset:1024
	ds_read_b128 v[160:163], v155 offset:2048
	ds_read_b128 v[164:167], v155 offset:3072
	v_add_u32_e32 v155, s57, v149
	ds_read_b128 v[168:171], v155
	ds_read_b128 v[172:175], v155 offset:1024
	ds_read_b128 v[176:179], v155 offset:2048
	ds_read_b128 v[180:183], v155 offset:3072
	s_add_u32 s26, s38, 0xb0000
	s_addc_u32 s27, s39, 0
	s_mov_b32 m0, s40
	v_lshl_add_u64 v[226:227], s[26:27], 0, v[128:129]
	ds_read_b128 v[184:187], v153 offset:32768
	ds_read_b128 v[188:191], v153 offset:33792
	ds_read_b128 v[192:195], v153 offset:34816
	ds_read_b128 v[196:199], v153 offset:35840
	ds_read_b128 v[200:203], v153 offset:36864
	ds_read_b128 v[206:209], v153 offset:37888
	ds_read_b128 v[210:213], v153 offset:38912
	ds_read_b128 v[214:217], v153 offset:39936
	global_load_lds_dwordx4 v[226:227], off
	v_lshl_add_u64 v[226:227], s[26:27], 0, v[132:133]
	s_mov_b32 m0, s41
	s_nop 0
	global_load_lds_dwordx4 v[226:227], off
	s_waitcnt vmcnt(8)
	s_waitcnt lgkmcnt(0)
	s_barrier
	s_setprio 1
	s_waitcnt lgkmcnt(0)
	v_mfma_f32_16x16x32_bf16 v[124:127], v[144:147], v[184:187], v[124:127]
	v_mfma_f32_16x16x32_bf16 v[120:123], v[160:163], v[184:187], v[120:123]
	v_mfma_f32_16x16x32_bf16 v[108:111], v[144:147], v[192:195], v[108:111]
	v_mfma_f32_16x16x32_bf16 v[104:107], v[160:163], v[192:195], v[104:107]
	v_mfma_f32_16x16x32_bf16 v[92:95], v[144:147], v[200:203], v[92:95]
	v_mfma_f32_16x16x32_bf16 v[88:91], v[160:163], v[200:203], v[88:91]
	v_mfma_f32_16x16x32_bf16 v[76:79], v[144:147], v[210:213], v[76:79]
	v_mfma_f32_16x16x32_bf16 v[72:75], v[160:163], v[210:213], v[72:75]
	v_mfma_f32_16x16x32_bf16 v[124:127], v[156:159], v[188:191], v[124:127]
	v_mfma_f32_16x16x32_bf16 v[120:123], v[164:167], v[188:191], v[120:123]
	v_mfma_f32_16x16x32_bf16 v[108:111], v[156:159], v[196:199], v[108:111]
	v_mfma_f32_16x16x32_bf16 v[104:107], v[164:167], v[196:199], v[104:107]
	v_mfma_f32_16x16x32_bf16 v[92:95], v[156:159], v[206:209], v[92:95]
	v_mfma_f32_16x16x32_bf16 v[88:91], v[164:167], v[206:209], v[88:91]
	v_mfma_f32_16x16x32_bf16 v[76:79], v[156:159], v[214:217], v[76:79]
	v_mfma_f32_16x16x32_bf16 v[72:75], v[164:167], v[214:217], v[72:75]
	s_setprio 0
	s_setprio 1
	v_mfma_f32_16x16x32_bf16 v[116:119], v[168:171], v[184:187], v[116:119]
	v_mfma_f32_16x16x32_bf16 v[112:115], v[176:179], v[184:187], v[112:115]
	v_mfma_f32_16x16x32_bf16 v[100:103], v[168:171], v[192:195], v[100:103]
	v_mfma_f32_16x16x32_bf16 v[96:99], v[176:179], v[192:195], v[96:99]
	v_mfma_f32_16x16x32_bf16 v[84:87], v[168:171], v[200:203], v[84:87]
	v_mfma_f32_16x16x32_bf16 v[80:83], v[176:179], v[200:203], v[80:83]
	v_mfma_f32_16x16x32_bf16 v[68:71], v[168:171], v[210:213], v[68:71]
	v_mfma_f32_16x16x32_bf16 v[64:67], v[176:179], v[210:213], v[64:67]
	v_mfma_f32_16x16x32_bf16 v[116:119], v[172:175], v[188:191], v[116:119]
	v_mfma_f32_16x16x32_bf16 v[112:115], v[180:183], v[188:191], v[112:115]
	v_mfma_f32_16x16x32_bf16 v[100:103], v[172:175], v[196:199], v[100:103]
	v_mfma_f32_16x16x32_bf16 v[96:99], v[180:183], v[196:199], v[96:99]
	v_mfma_f32_16x16x32_bf16 v[84:87], v[172:175], v[206:209], v[84:87]
	v_mfma_f32_16x16x32_bf16 v[80:83], v[180:183], v[206:209], v[80:83]
	v_mfma_f32_16x16x32_bf16 v[68:71], v[172:175], v[214:217], v[68:71]
	v_mfma_f32_16x16x32_bf16 v[64:67], v[180:183], v[214:217], v[64:67]
	s_setprio 0
	s_barrier
; #define PG8_STAGE(bufoff, gbase, voff) do { _Pragma("unroll") for (int _i = 0; _i < 2; ++_i) \
;         __builtin_amdgcn_global_load_lds((const unsigned*)((const char*)(gbase) + (voff)[_i]), (PG8_LAS unsigned*)(lds + (bufoff) + ldsw + _i * 8192), 16, 0, 0); } while (0)
; #define PG8_LDA(dst, b, h) do { _Pragma("unroll") for (int m = 0; m < 4; ++m) _Pragma("unroll") for (int k = 0; k < 2; ++k) dst[m][k] = *(const PG8_LAS bf16x8*)(lds + PG8_SA(b, h) + aoff + m * 2048 + k * 1024); } while (0)
; #define PG8_LDB(dst, b, h) do { _Pragma("unroll") for (int n = 0; n < 2; ++n) _Pragma("unroll") for (int k = 0; k < 2; ++k) dst[n][k] = *(const PG8_LAS bf16x8*)(lds + PG8_SB(b, h) + boff + n * 2048 + k * 1024); } while (0)
; #define PG8_MMA(ai, bj, At, Bt) do { __builtin_amdgcn_s_setprio(1); _Pragma("unroll") for (int m = 0; m < 4; ++m) _Pragma("unroll") for (int n = 0; n < 2; ++n) _Pragma("unroll") for (int k = 0; k < 2; ++k) \
;         acc[ai][bj][m][n] = __builtin_amdgcn_mfma_f32_16x16x32_bf16(Bt[n][k], At[m][k], acc[ai][bj][m][n], 0, 0, 0); __builtin_amdgcn_s_setprio(0); } while (0)
; #define PG8_WAIT_V(n) asm volatile("s_waitcnt vmcnt(" #n ")" ::: "memory")
; #define PG8_WAIT_L(n) asm volatile("s_waitcnt lgkmcnt(" #n ")" ::: "memory")
; #define PG8_BAR __builtin_amdgcn_s_barrier()
; #define PG8_SCHED __builtin_amdgcn_sched_barrier(0)
; template <class Epi, class Sched, bool ALIGN_EPI = false, bool SP2 = false>
; __device__ __forceinline__ void gemm_phase(PG8_LAS unsigned char* lds, const Gemm g, const Sched& S, const Epi& E) {
;     ...
;             PG8_LDB(B0, 0, 0); PG8_LDB(B1, 0, 1); PG8_SCHED; PG8_LDA(At, 0, 0); PG8_STAGE(PG8_SA(1, 1), a1 + hstep, voffA);
;             PG8_WAIT_V(8); PG8_WAIT_L(0); PG8_BAR; PG8_MMA(0, 0, At, B0); PG8_MMA(0, 1, At, B1); PG8_BAR; PG8_SCHED;
;     ...
;             PG8_LDA(At, 1, 1); PG8_STAGE(PG8_SB(1, 0), b3, voffB); PG8_STAGE(PG8_SB(1, 1), b3 + hstep, voffB); PG8_STAGE(PG8_SA(1, 0), a3, voffA);
;             PG8_WAIT_V(8); PG8_WAIT_L(0); PG8_BAR; PG8_MMA(1, 0, At, B0); PG8_MMA(1, 1, At, B1); PG8_BAR; PG8_SCHED;
	s_add_i32 s26, s56, s15
	v_lshl_add_u64 v[218:219], v[218:219], 0, s[12:13]
	s_mov_b32 m0, s26
	ds_read_b128 v[184:187], v153 offset:49152
	ds_read_b128 v[188:191], v153 offset:50176
	ds_read_b128 v[192:195], v153 offset:51200
	ds_read_b128 v[196:199], v153 offset:52224
	ds_read_b128 v[200:203], v153 offset:53248
	ds_read_b128 v[206:209], v153 offset:54272
	ds_read_b128 v[210:213], v153 offset:55296
	ds_read_b128 v[214:217], v153 offset:56320
	global_load_lds_dwordx4 v[218:219], off
	s_add_i32 m0, s26, 0x2000
	s_add_u32 s26, s36, 0xb0080
	v_lshl_add_u64 v[218:219], v[220:221], 0, s[12:13]
	s_addc_u32 s27, s37, 0
	s_add_i32 s36, s57, s15
	global_load_lds_dwordx4 v[218:219], off
	v_lshl_add_u64 v[218:219], s[26:27], 0, v[130:131]
	s_mov_b32 m0, s36
	s_nop 0
	global_load_lds_dwordx4 v[218:219], off
	v_lshl_add_u64 v[218:219], s[26:27], 0, v[134:135]
	s_add_i32 m0, s36, 0x2000
	s_nop 0
	global_load_lds_dwordx4 v[218:219], off
	s_waitcnt vmcnt(6)
	s_waitcnt lgkmcnt(0)
	s_barrier
	s_setprio 1
	s_waitcnt lgkmcnt(0)
	v_mfma_f32_16x16x32_bf16 v[60:63], v[144:147], v[184:187], v[60:63]
	v_mfma_f32_16x16x32_bf16 v[56:59], v[160:163], v[184:187], v[56:59]
	v_mfma_f32_16x16x32_bf16 v[44:47], v[144:147], v[192:195], v[44:47]
	v_mfma_f32_16x16x32_bf16 v[40:43], v[160:163], v[192:195], v[40:43]
	v_mfma_f32_16x16x32_bf16 v[28:31], v[144:147], v[200:203], v[28:31]
	v_mfma_f32_16x16x32_bf16 v[24:27], v[160:163], v[200:203], v[24:27]
	v_mfma_f32_16x16x32_bf16 v[12:15], v[144:147], v[210:213], v[12:15]
	v_mfma_f32_16x16x32_bf16 v[8:11], v[160:163], v[210:213], v[8:11]
	v_mfma_f32_16x16x32_bf16 v[60:63], v[156:159], v[188:191], v[60:63]
	v_mfma_f32_16x16x32_bf16 v[56:59], v[164:167], v[188:191], v[56:59]
	v_mfma_f32_16x16x32_bf16 v[44:47], v[156:159], v[196:199], v[44:47]
	v_mfma_f32_16x16x32_bf16 v[40:43], v[164:167], v[196:199], v[40:43]
	v_mfma_f32_16x16x32_bf16 v[28:31], v[156:159], v[206:209], v[28:31]
	v_mfma_f32_16x16x32_bf16 v[24:27], v[164:167], v[206:209], v[24:27]
	v_mfma_f32_16x16x32_bf16 v[12:15], v[156:159], v[214:217], v[12:15]
	v_lshl_add_u64 v[218:219], v[222:223], 0, s[12:13]
	s_mov_b32 m0, s43
	s_nop 0
	global_load_lds_dwordx4 v[218:219], off
	v_mfma_f32_16x16x32_bf16 v[8:11], v[164:167], v[214:217], v[8:11]
	s_setprio 0
	s_setprio 1
	v_mfma_f32_16x16x32_bf16 v[52:55], v[168:171], v[184:187], v[52:55]
	v_mfma_f32_16x16x32_bf16 v[48:51], v[176:179], v[184:187], v[48:51]
	v_mfma_f32_16x16x32_bf16 v[36:39], v[168:171], v[192:195], v[36:39]
	v_mfma_f32_16x16x32_bf16 v[32:35], v[176:179], v[192:195], v[32:35]
	v_mfma_f32_16x16x32_bf16 v[20:23], v[168:171], v[200:203], v[20:23]
	v_mfma_f32_16x16x32_bf16 v[16:19], v[176:179], v[200:203], v[16:19]
	v_mfma_f32_16x16x32_bf16 v[4:7], v[168:171], v[210:213], v[4:7]
	v_mfma_f32_16x16x32_bf16 v[0:3], v[176:179], v[210:213], v[0:3]
	v_mfma_f32_16x16x32_bf16 v[52:55], v[172:175], v[188:191], v[52:55]
	v_mfma_f32_16x16x32_bf16 v[48:51], v[180:183], v[188:191], v[48:51]
	v_mfma_f32_16x16x32_bf16 v[36:39], v[172:175], v[196:199], v[36:39]
	v_mfma_f32_16x16x32_bf16 v[32:35], v[180:183], v[196:199], v[32:35]
	v_mfma_f32_16x16x32_bf16 v[20:23], v[172:175], v[206:209], v[20:23]
	v_mfma_f32_16x16x32_bf16 v[16:19], v[180:183], v[206:209], v[16:19]
	v_mfma_f32_16x16x32_bf16 v[4:7], v[172:175], v[214:217], v[4:7]
	v_lshl_add_u64 v[218:219], v[224:225], 0, s[12:13]
	s_mov_b32 m0, s44
	s_nop 0
	global_load_lds_dwordx4 v[218:219], off
	v_mfma_f32_16x16x32_bf16 v[0:3], v[180:183], v[214:217], v[0:3]
	s_setprio 0
	s_barrier
	s_add_i32 s55, s55, 2
	s_add_u32 s53, s53, 0x100
	s_addc_u32 s54, s54, 0
	s_mov_b64 s[26:27], s[28:29]
.LBB0_1978:
	ds_read_b128 v[144:147], v151
	ds_read_b128 v[156:159], v151 offset:1024
	ds_read_b128 v[160:163], v151 offset:2048
	ds_read_b128 v[164:167], v151 offset:3072
	ds_read_b128 v[168:171], v152
	ds_read_b128 v[172:175], v152 offset:1024
	ds_read_b128 v[176:179], v152 offset:2048
	ds_read_b128 v[180:183], v152 offset:3072
	s_add_u32 s28, s26, 0x100
	s_addc_u32 s29, s27, 0
	s_cmp_eq_u32 s55, 40
	s_cselect_b32 s39, s1, s29
	s_cselect_b32 s38, s0, s28
	s_cselect_b32 s37, s25, s54
	s_cselect_b32 s36, s24, s53
	v_lshl_add_u64 v[218:219], s[26:27], 0, v[136:137]
	s_add_i32 m0, s33, 0xc000
	ds_read_b128 v[184:187], v153
	ds_read_b128 v[188:191], v153 offset:1024
	ds_read_b128 v[192:195], v153 offset:2048
	ds_read_b128 v[196:199], v153 offset:3072
	ds_read_b128 v[200:203], v153 offset:4096
	ds_read_b128 v[206:209], v153 offset:5120
	ds_read_b128 v[210:213], v153 offset:6144
	ds_read_b128 v[214:217], v153 offset:7168
	global_load_lds_dwordx4 v[218:219], off
	v_lshl_add_u64 v[218:219], s[26:27], 0, v[138:139]
	s_add_i32 m0, s33, 0xe000
	s_nop 0
	global_load_lds_dwordx4 v[218:219], off
	s_waitcnt vmcnt(8)
	s_waitcnt lgkmcnt(0)
	s_barrier
; #define PG8_STAGE(bufoff, gbase, voff) do { _Pragma("unroll") for (int _i = 0; _i < 2; ++_i) \
;         __builtin_amdgcn_global_load_lds((const unsigned*)((const char*)(gbase) + (voff)[_i]), (PG8_LAS unsigned*)(lds + (bufoff) + ldsw + _i * 8192), 16, 0, 0); } while (0)
; #define PG8_LDA(dst, b, h) do { _Pragma("unroll") for (int m = 0; m < 4; ++m) _Pragma("unroll") for (int k = 0; k < 2; ++k) dst[m][k] = *(const PG8_LAS bf16x8*)(lds + PG8_SA(b, h) + aoff + m * 2048 + k * 1024); } while (0)
; #define PG8_MMA(ai, bj, At, Bt) do { __builtin_amdgcn_s_setprio(1); _Pragma("unroll") for (int m = 0; m < 4; ++m) _Pragma("unroll") for (int n = 0; n < 2; ++n) _Pragma("unroll") for (int k = 0; k < 2; ++k) \
;         acc[ai][bj][m][n] = __builtin_amdgcn_mfma_f32_16x16x32_bf16(Bt[n][k], At[m][k], acc[ai][bj][m][n], 0, 0, 0); __builtin_amdgcn_s_setprio(0); } while (0)
; #define PG8_WAIT_V(n) asm volatile("s_waitcnt vmcnt(" #n ")" ::: "memory")
; #define PG8_WAIT_L(n) asm volatile("s_waitcnt lgkmcnt(" #n ")" ::: "memory")
; #define PG8_BAR __builtin_amdgcn_s_barrier()
; #define PG8_SCHED __builtin_amdgcn_sched_barrier(0)
; template <class Epi, class Sched, bool ALIGN_EPI = false, bool SP2 = false>
; __device__ __forceinline__ void gemm_phase(PG8_LAS unsigned char* lds, const Gemm g, const Sched& S, const Epi& E) {
;     ...
;             PG8_WAIT_V(8); PG8_WAIT_L(0); PG8_BAR; PG8_MMA(0, 0, At, B0); PG8_MMA(0, 1, At, B1); PG8_BAR; PG8_SCHED;
;             PG8_LDA(At, 0, 1); PG8_STAGE(PG8_SB(0, 0), b2, voffB); PG8_STAGE(PG8_SB(0, 1), b2 + hstep, voffB); PG8_STAGE(PG8_SA(0, 0), a2, voffA);
;             PG8_WAIT_V(8); PG8_WAIT_L(0); PG8_BAR; PG8_MMA(1, 0, At, B0); PG8_MMA(1, 1, At, B1); PG8_BAR; PG8_SCHED;
	s_setprio 1
	s_waitcnt lgkmcnt(0)
	v_mfma_f32_16x16x32_bf16 v[124:127], v[144:147], v[184:187], v[124:127]
	v_mfma_f32_16x16x32_bf16 v[120:123], v[160:163], v[184:187], v[120:123]
	v_mfma_f32_16x16x32_bf16 v[108:111], v[144:147], v[192:195], v[108:111]
	v_mfma_f32_16x16x32_bf16 v[104:107], v[160:163], v[192:195], v[104:107]
	v_mfma_f32_16x16x32_bf16 v[92:95], v[144:147], v[200:203], v[92:95]
	v_mfma_f32_16x16x32_bf16 v[88:91], v[160:163], v[200:203], v[88:91]
	v_mfma_f32_16x16x32_bf16 v[76:79], v[144:147], v[210:213], v[76:79]
	v_mfma_f32_16x16x32_bf16 v[72:75], v[160:163], v[210:213], v[72:75]
	v_mfma_f32_16x16x32_bf16 v[124:127], v[156:159], v[188:191], v[124:127]
	v_mfma_f32_16x16x32_bf16 v[120:123], v[164:167], v[188:191], v[120:123]
	v_mfma_f32_16x16x32_bf16 v[108:111], v[156:159], v[196:199], v[108:111]
	v_mfma_f32_16x16x32_bf16 v[104:107], v[164:167], v[196:199], v[104:107]
	v_mfma_f32_16x16x32_bf16 v[92:95], v[156:159], v[206:209], v[92:95]
	v_mfma_f32_16x16x32_bf16 v[88:91], v[164:167], v[206:209], v[88:91]
	v_mfma_f32_16x16x32_bf16 v[76:79], v[156:159], v[214:217], v[76:79]
	v_mfma_f32_16x16x32_bf16 v[72:75], v[164:167], v[214:217], v[72:75]
	s_setprio 0
	s_setprio 1
	v_mfma_f32_16x16x32_bf16 v[116:119], v[168:171], v[184:187], v[116:119]
	v_mfma_f32_16x16x32_bf16 v[112:115], v[176:179], v[184:187], v[112:115]
	v_mfma_f32_16x16x32_bf16 v[100:103], v[168:171], v[192:195], v[100:103]
	v_mfma_f32_16x16x32_bf16 v[96:99], v[176:179], v[192:195], v[96:99]
	v_mfma_f32_16x16x32_bf16 v[84:87], v[168:171], v[200:203], v[84:87]
	v_mfma_f32_16x16x32_bf16 v[80:83], v[176:179], v[200:203], v[80:83]
	v_mfma_f32_16x16x32_bf16 v[68:71], v[168:171], v[210:213], v[68:71]
	v_mfma_f32_16x16x32_bf16 v[64:67], v[176:179], v[210:213], v[64:67]
	v_mfma_f32_16x16x32_bf16 v[116:119], v[172:175], v[188:191], v[116:119]
	v_mfma_f32_16x16x32_bf16 v[112:115], v[180:183], v[188:191], v[112:115]
	v_mfma_f32_16x16x32_bf16 v[100:103], v[172:175], v[196:199], v[100:103]
	v_mfma_f32_16x16x32_bf16 v[96:99], v[180:183], v[196:199], v[96:99]
	v_mfma_f32_16x16x32_bf16 v[84:87], v[172:175], v[206:209], v[84:87]
	v_mfma_f32_16x16x32_bf16 v[80:83], v[180:183], v[206:209], v[80:83]
	v_mfma_f32_16x16x32_bf16 v[68:71], v[172:175], v[214:217], v[68:71]
	v_mfma_f32_16x16x32_bf16 v[64:67], v[180:183], v[214:217], v[64:67]
	s_setprio 0
	s_barrier
	s_add_i32 s26, s45, s15
	v_lshl_add_u64 v[218:219], s[36:37], 0, v[130:131]
	s_mov_b32 m0, s26
	ds_read_b128 v[184:187], v153 offset:16384
	ds_read_b128 v[188:191], v153 offset:17408
	ds_read_b128 v[192:195], v153 offset:18432
	ds_read_b128 v[196:199], v153 offset:19456
	ds_read_b128 v[200:203], v153 offset:20480
	ds_read_b128 v[206:209], v153 offset:21504
	ds_read_b128 v[210:213], v153 offset:22528
	ds_read_b128 v[214:217], v153 offset:23552
	global_load_lds_dwordx4 v[218:219], off
	s_add_i32 m0, s26, 0x2000
	s_add_u32 s26, s36, 0xb0000
	v_lshl_add_u64 v[220:221], s[36:37], 0, v[134:135]
	s_addc_u32 s27, s37, 0
	s_add_i32 s56, s46, s15
	global_load_lds_dwordx4 v[220:221], off
	v_lshl_add_u64 v[222:223], s[26:27], 0, v[130:131]
	s_mov_b32 m0, s56
	global_load_lds_dwordx4 v[222:223], off
	v_lshl_add_u64 v[222:223], s[26:27], 0, v[134:135]
	s_add_i32 m0, s56, 0x2000
	s_nop 0
	global_load_lds_dwordx4 v[222:223], off
	s_waitcnt vmcnt(6)
	s_waitcnt lgkmcnt(0)
	s_barrier
	s_setprio 1
	s_waitcnt lgkmcnt(0)
	v_mfma_f32_16x16x32_bf16 v[60:63], v[144:147], v[184:187], v[60:63]
	v_mfma_f32_16x16x32_bf16 v[56:59], v[160:163], v[184:187], v[56:59]
	v_mfma_f32_16x16x32_bf16 v[44:47], v[144:147], v[192:195], v[44:47]
	v_mfma_f32_16x16x32_bf16 v[40:43], v[160:163], v[192:195], v[40:43]
	v_mfma_f32_16x16x32_bf16 v[28:31], v[144:147], v[200:203], v[28:31]
	v_mfma_f32_16x16x32_bf16 v[24:27], v[160:163], v[200:203], v[24:27]
	v_mfma_f32_16x16x32_bf16 v[12:15], v[144:147], v[210:213], v[12:15]
	v_mfma_f32_16x16x32_bf16 v[8:11], v[160:163], v[210:213], v[8:11]
	v_mfma_f32_16x16x32_bf16 v[60:63], v[156:159], v[188:191], v[60:63]
	v_mfma_f32_16x16x32_bf16 v[56:59], v[164:167], v[188:191], v[56:59]
	v_mfma_f32_16x16x32_bf16 v[44:47], v[156:159], v[196:199], v[44:47]
	v_mfma_f32_16x16x32_bf16 v[40:43], v[164:167], v[196:199], v[40:43]
	v_mfma_f32_16x16x32_bf16 v[28:31], v[156:159], v[206:209], v[28:31]
	v_mfma_f32_16x16x32_bf16 v[24:27], v[164:167], v[206:209], v[24:27]
	v_mfma_f32_16x16x32_bf16 v[12:15], v[156:159], v[214:217], v[12:15]
	v_lshl_add_u64 v[222:223], s[38:39], 0, v[128:129]
	s_mov_b32 m0, s33
	s_nop 0
	global_load_lds_dwordx4 v[222:223], off
	v_mfma_f32_16x16x32_bf16 v[8:11], v[164:167], v[214:217], v[8:11]
	s_setprio 0
	s_setprio 1
	v_mfma_f32_16x16x32_bf16 v[52:55], v[168:171], v[184:187], v[52:55]
	v_mfma_f32_16x16x32_bf16 v[48:51], v[176:179], v[184:187], v[48:51]
	v_mfma_f32_16x16x32_bf16 v[36:39], v[168:171], v[192:195], v[36:39]
	v_mfma_f32_16x16x32_bf16 v[32:35], v[176:179], v[192:195], v[32:35]
	v_mfma_f32_16x16x32_bf16 v[20:23], v[168:171], v[200:203], v[20:23]
	v_mfma_f32_16x16x32_bf16 v[16:19], v[176:179], v[200:203], v[16:19]
	v_mfma_f32_16x16x32_bf16 v[4:7], v[168:171], v[210:213], v[4:7]
	v_mfma_f32_16x16x32_bf16 v[0:3], v[176:179], v[210:213], v[0:3]
	v_mfma_f32_16x16x32_bf16 v[52:55], v[172:175], v[188:191], v[52:55]
	v_mfma_f32_16x16x32_bf16 v[48:51], v[180:183], v[188:191], v[48:51]
	v_mfma_f32_16x16x32_bf16 v[36:39], v[172:175], v[196:199], v[36:39]
	v_mfma_f32_16x16x32_bf16 v[32:35], v[180:183], v[196:199], v[32:35]
	v_mfma_f32_16x16x32_bf16 v[20:23], v[172:175], v[206:209], v[20:23]
	v_mfma_f32_16x16x32_bf16 v[16:19], v[180:183], v[206:209], v[16:19]
	v_mfma_f32_16x16x32_bf16 v[4:7], v[172:175], v[214:217], v[4:7]
	v_lshl_add_u64 v[224:225], s[38:39], 0, v[132:133]
	s_mov_b32 m0, s34
	s_nop 0
	global_load_lds_dwordx4 v[224:225], off
	v_mfma_f32_16x16x32_bf16 v[0:3], v[180:183], v[214:217], v[0:3]
	s_setprio 0
	s_barrier
; #define PG8_STAGE(bufoff, gbase, voff) do { _Pragma("unroll") for (int _i = 0; _i < 2; ++_i) \
;         __builtin_amdgcn_global_load_lds((const unsigned*)((const char*)(gbase) + (voff)[_i]), (PG8_LAS unsigned*)(lds + (bufoff) + ldsw + _i * 8192), 16, 0, 0); } while (0)
; #define PG8_LDA(dst, b, h) do { _Pragma("unroll") for (int m = 0; m < 4; ++m) _Pragma("unroll") for (int k = 0; k < 2; ++k) dst[m][k] = *(const PG8_LAS bf16x8*)(lds + PG8_SA(b, h) + aoff + m * 2048 + k * 1024); } while (0)
; #define PG8_LDB(dst, b, h) do { _Pragma("unroll") for (int n = 0; n < 2; ++n) _Pragma("unroll") for (int k = 0; k < 2; ++k) dst[n][k] = *(const PG8_LAS bf16x8*)(lds + PG8_SB(b, h) + boff + n * 2048 + k * 1024); } while (0)
; #define PG8_MMA(ai, bj, At, Bt) do { __builtin_amdgcn_s_setprio(1); _Pragma("unroll") for (int m = 0; m < 4; ++m) _Pragma("unroll") for (int n = 0; n < 2; ++n) _Pragma("unroll") for (int k = 0; k < 2; ++k) \
;         acc[ai][bj][m][n] = __builtin_amdgcn_mfma_f32_16x16x32_bf16(Bt[n][k], At[m][k], acc[ai][bj][m][n], 0, 0, 0); __builtin_amdgcn_s_setprio(0); } while (0)
; #define PG8_WAIT_V(n) asm volatile("s_waitcnt vmcnt(" #n ")" ::: "memory")
; #define PG8_WAIT_L(n) asm volatile("s_waitcnt lgkmcnt(" #n ")" ::: "memory")
; #define PG8_BAR __builtin_amdgcn_s_barrier()
; #define PG8_SCHED __builtin_amdgcn_sched_barrier(0)
; template <class Epi, class Sched, bool ALIGN_EPI = false, bool SP2 = false>
; __device__ __forceinline__ void gemm_phase(PG8_LAS unsigned char* lds, const Gemm g, const Sched& S, const Epi& E) {
;     ...
;             PG8_LDB(B0, 1, 0); PG8_LDB(B1, 1, 1); PG8_SCHED; PG8_LDA(At, 1, 0); PG8_STAGE(PG8_SA(0, 1), a2 + hstep, voffA);
;             PG8_WAIT_V(8); PG8_WAIT_L(0); PG8_BAR; PG8_MMA(0, 0, At, B0); PG8_MMA(0, 1, At, B1); PG8_BAR; PG8_SCHED;
	s_add_i32 s56, 0, 0x18000
	v_add_u32_e32 v155, s56, v149
	s_add_i32 s57, 0, 0x1c000
	ds_read_b128 v[144:147], v155
	ds_read_b128 v[156:159], v155 offset:1024
	ds_read_b128 v[160:163], v155 offset:2048
	ds_read_b128 v[164:167], v155 offset:3072
	v_add_u32_e32 v155, s57, v149
	ds_read_b128 v[168:171], v155
	ds_read_b128 v[172:175], v155 offset:1024
	ds_read_b128 v[176:179], v155 offset:2048
	ds_read_b128 v[180:183], v155 offset:3072
	s_add_u32 s26, s38, 0xb0000
	s_addc_u32 s27, s39, 0
	s_mov_b32 m0, s40
	v_lshl_add_u64 v[226:227], s[26:27], 0, v[128:129]
	ds_read_b128 v[184:187], v153 offset:32768
	ds_read_b128 v[188:191], v153 offset:33792
	ds_read_b128 v[192:195], v153 offset:34816
	ds_read_b128 v[196:199], v153 offset:35840
	ds_read_b128 v[200:203], v153 offset:36864
	ds_read_b128 v[206:209], v153 offset:37888
	ds_read_b128 v[210:213], v153 offset:38912
	ds_read_b128 v[214:217], v153 offset:39936
	global_load_lds_dwordx4 v[226:227], off
	v_lshl_add_u64 v[226:227], s[26:27], 0, v[132:133]
	s_mov_b32 m0, s41
	s_nop 0
	global_load_lds_dwordx4 v[226:227], off
	s_waitcnt vmcnt(8)
	s_waitcnt lgkmcnt(0)
	s_barrier
	s_setprio 1
	s_waitcnt lgkmcnt(0)
	v_mfma_f32_16x16x32_bf16 v[124:127], v[144:147], v[184:187], v[124:127]
	v_mfma_f32_16x16x32_bf16 v[120:123], v[160:163], v[184:187], v[120:123]
	v_mfma_f32_16x16x32_bf16 v[108:111], v[144:147], v[192:195], v[108:111]
	v_mfma_f32_16x16x32_bf16 v[104:107], v[160:163], v[192:195], v[104:107]
	v_mfma_f32_16x16x32_bf16 v[92:95], v[144:147], v[200:203], v[92:95]
	v_mfma_f32_16x16x32_bf16 v[88:91], v[160:163], v[200:203], v[88:91]
	v_mfma_f32_16x16x32_bf16 v[76:79], v[144:147], v[210:213], v[76:79]
	v_mfma_f32_16x16x32_bf16 v[72:75], v[160:163], v[210:213], v[72:75]
	v_mfma_f32_16x16x32_bf16 v[124:127], v[156:159], v[188:191], v[124:127]
	v_mfma_f32_16x16x32_bf16 v[120:123], v[164:167], v[188:191], v[120:123]
	v_mfma_f32_16x16x32_bf16 v[108:111], v[156:159], v[196:199], v[108:111]
	v_mfma_f32_16x16x32_bf16 v[104:107], v[164:167], v[196:199], v[104:107]
	v_mfma_f32_16x16x32_bf16 v[92:95], v[156:159], v[206:209], v[92:95]
	v_mfma_f32_16x16x32_bf16 v[88:91], v[164:167], v[206:209], v[88:91]
	v_mfma_f32_16x16x32_bf16 v[76:79], v[156:159], v[214:217], v[76:79]
	v_mfma_f32_16x16x32_bf16 v[72:75], v[164:167], v[214:217], v[72:75]
	s_setprio 0
	s_setprio 1
	v_mfma_f32_16x16x32_bf16 v[116:119], v[168:171], v[184:187], v[116:119]
	v_mfma_f32_16x16x32_bf16 v[112:115], v[176:179], v[184:187], v[112:115]
	v_mfma_f32_16x16x32_bf16 v[100:103], v[168:171], v[192:195], v[100:103]
	v_mfma_f32_16x16x32_bf16 v[96:99], v[176:179], v[192:195], v[96:99]
	v_mfma_f32_16x16x32_bf16 v[84:87], v[168:171], v[200:203], v[84:87]
	v_mfma_f32_16x16x32_bf16 v[80:83], v[176:179], v[200:203], v[80:83]
	v_mfma_f32_16x16x32_bf16 v[68:71], v[168:171], v[210:213], v[68:71]
	v_mfma_f32_16x16x32_bf16 v[64:67], v[176:179], v[210:213], v[64:67]
	v_mfma_f32_16x16x32_bf16 v[116:119], v[172:175], v[188:191], v[116:119]
	v_mfma_f32_16x16x32_bf16 v[112:115], v[180:183], v[188:191], v[112:115]
	v_mfma_f32_16x16x32_bf16 v[100:103], v[172:175], v[196:199], v[100:103]
	v_mfma_f32_16x16x32_bf16 v[96:99], v[180:183], v[196:199], v[96:99]
	v_mfma_f32_16x16x32_bf16 v[84:87], v[172:175], v[206:209], v[84:87]
	v_mfma_f32_16x16x32_bf16 v[80:83], v[180:183], v[206:209], v[80:83]
	v_mfma_f32_16x16x32_bf16 v[68:71], v[172:175], v[214:217], v[68:71]
	v_mfma_f32_16x16x32_bf16 v[64:67], v[180:183], v[214:217], v[64:67]
	s_setprio 0
	s_barrier
; #define PG8_STAGE(bufoff, gbase, voff) do { _Pragma("unroll") for (int _i = 0; _i < 2; ++_i) \
;         __builtin_amdgcn_global_load_lds((const unsigned*)((const char*)(gbase) + (voff)[_i]), (PG8_LAS unsigned*)(lds + (bufoff) + ldsw + _i * 8192), 16, 0, 0); } while (0)
; #define PG8_LDA(dst, b, h) do { _Pragma("unroll") for (int m = 0; m < 4; ++m) _Pragma("unroll") for (int k = 0; k < 2; ++k) dst[m][k] = *(const PG8_LAS bf16x8*)(lds + PG8_SA(b, h) + aoff + m * 2048 + k * 1024); } while (0)
; #define PG8_MMA(ai, bj, At, Bt) do { __builtin_amdgcn_s_setprio(1); _Pragma("unroll") for (int m = 0; m < 4; ++m) _Pragma("unroll") for (int n = 0; n < 2; ++n) _Pragma("unroll") for (int k = 0; k < 2; ++k) \
;         acc[ai][bj][m][n] = __builtin_amdgcn_mfma_f32_16x16x32_bf16(Bt[n][k], At[m][k], acc[ai][bj][m][n], 0, 0, 0); __builtin_amdgcn_s_setprio(0); } while (0)
; #define PG8_WAIT_V(n) asm volatile("s_waitcnt vmcnt(" #n ")" ::: "memory")
; #define PG8_WAIT_L(n) asm volatile("s_waitcnt lgkmcnt(" #n ")" ::: "memory")
; #define PG8_BAR __builtin_amdgcn_s_barrier()
; #define PG8_SCHED __builtin_amdgcn_sched_barrier(0)
; template <class Epi, class Sched, bool ALIGN_EPI = false, bool SP2 = false>
; __device__ __forceinline__ void gemm_phase(PG8_LAS unsigned char* lds, const Gemm g, const Sched& S, const Epi& E) {
;     ...
;             PG8_LDA(At, 1, 1); PG8_STAGE(PG8_SB(1, 0), b3, voffB); PG8_STAGE(PG8_SB(1, 1), b3 + hstep, voffB); PG8_STAGE(PG8_SA(1, 0), a3, voffA);
;             PG8_WAIT_V(8); PG8_WAIT_L(0); PG8_BAR; PG8_MMA(1, 0, At, B0); PG8_MMA(1, 1, At, B1); PG8_BAR; PG8_SCHED;
;     ...
;         if constexpr (ALIGN_EPI) { if (wr == 0) PG8_BAR; }
	s_add_i32 s26, s56, s15
	v_lshl_add_u64 v[218:219], v[218:219], 0, s[12:13]
	s_mov_b32 m0, s26
	ds_read_b128 v[184:187], v153 offset:49152
	ds_read_b128 v[188:191], v153 offset:50176
	ds_read_b128 v[192:195], v153 offset:51200
	ds_read_b128 v[196:199], v153 offset:52224
	ds_read_b128 v[200:203], v153 offset:53248
	ds_read_b128 v[206:209], v153 offset:54272
	ds_read_b128 v[210:213], v153 offset:55296
	ds_read_b128 v[214:217], v153 offset:56320
	global_load_lds_dwordx4 v[218:219], off
	s_add_i32 m0, s26, 0x2000
	s_add_u32 s26, s36, 0xb0080
	v_lshl_add_u64 v[218:219], v[220:221], 0, s[12:13]
	s_addc_u32 s27, s37, 0
	s_add_i32 s36, s57, s15
	global_load_lds_dwordx4 v[218:219], off
	v_lshl_add_u64 v[218:219], s[26:27], 0, v[130:131]
	s_mov_b32 m0, s36
	s_nop 0
	global_load_lds_dwordx4 v[218:219], off
	v_lshl_add_u64 v[218:219], s[26:27], 0, v[134:135]
	s_add_i32 m0, s36, 0x2000
	s_nop 0
	global_load_lds_dwordx4 v[218:219], off
	s_waitcnt vmcnt(6)
	s_waitcnt lgkmcnt(0)
	s_barrier
	s_setprio 1
	s_waitcnt lgkmcnt(0)
	v_mfma_f32_16x16x32_bf16 v[60:63], v[144:147], v[184:187], v[60:63]
	v_mfma_f32_16x16x32_bf16 v[56:59], v[160:163], v[184:187], v[56:59]
	v_mfma_f32_16x16x32_bf16 v[44:47], v[144:147], v[192:195], v[44:47]
	v_mfma_f32_16x16x32_bf16 v[40:43], v[160:163], v[192:195], v[40:43]
	v_mfma_f32_16x16x32_bf16 v[28:31], v[144:147], v[200:203], v[28:31]
	v_mfma_f32_16x16x32_bf16 v[24:27], v[160:163], v[200:203], v[24:27]
	v_mfma_f32_16x16x32_bf16 v[12:15], v[144:147], v[210:213], v[12:15]
	v_mfma_f32_16x16x32_bf16 v[8:11], v[160:163], v[210:213], v[8:11]
	v_mfma_f32_16x16x32_bf16 v[60:63], v[156:159], v[188:191], v[60:63]
	v_mfma_f32_16x16x32_bf16 v[56:59], v[164:167], v[188:191], v[56:59]
	v_mfma_f32_16x16x32_bf16 v[44:47], v[156:159], v[196:199], v[44:47]
	v_mfma_f32_16x16x32_bf16 v[40:43], v[164:167], v[196:199], v[40:43]
	v_mfma_f32_16x16x32_bf16 v[28:31], v[156:159], v[206:209], v[28:31]
	v_mfma_f32_16x16x32_bf16 v[24:27], v[164:167], v[206:209], v[24:27]
	v_mfma_f32_16x16x32_bf16 v[12:15], v[156:159], v[214:217], v[12:15]
	v_lshl_add_u64 v[218:219], v[222:223], 0, s[12:13]
	s_mov_b32 m0, s43
	s_nop 0
	global_load_lds_dwordx4 v[218:219], off
	v_mfma_f32_16x16x32_bf16 v[8:11], v[164:167], v[214:217], v[8:11]
	s_setprio 0
	s_setprio 1
	v_mfma_f32_16x16x32_bf16 v[52:55], v[168:171], v[184:187], v[52:55]
	v_mfma_f32_16x16x32_bf16 v[48:51], v[176:179], v[184:187], v[48:51]
	v_mfma_f32_16x16x32_bf16 v[36:39], v[168:171], v[192:195], v[36:39]
	v_mfma_f32_16x16x32_bf16 v[32:35], v[176:179], v[192:195], v[32:35]
	v_mfma_f32_16x16x32_bf16 v[20:23], v[168:171], v[200:203], v[20:23]
	v_mfma_f32_16x16x32_bf16 v[16:19], v[176:179], v[200:203], v[16:19]
	v_mfma_f32_16x16x32_bf16 v[4:7], v[168:171], v[210:213], v[4:7]
	v_mfma_f32_16x16x32_bf16 v[0:3], v[176:179], v[210:213], v[0:3]
	v_mfma_f32_16x16x32_bf16 v[52:55], v[172:175], v[188:191], v[52:55]
	v_mfma_f32_16x16x32_bf16 v[48:51], v[180:183], v[188:191], v[48:51]
	v_mfma_f32_16x16x32_bf16 v[36:39], v[172:175], v[196:199], v[36:39]
	v_mfma_f32_16x16x32_bf16 v[32:35], v[180:183], v[196:199], v[32:35]
	v_mfma_f32_16x16x32_bf16 v[20:23], v[172:175], v[206:209], v[20:23]
	v_mfma_f32_16x16x32_bf16 v[16:19], v[180:183], v[206:209], v[16:19]
	v_mfma_f32_16x16x32_bf16 v[4:7], v[172:175], v[214:217], v[4:7]
	v_lshl_add_u64 v[218:219], v[224:225], 0, s[12:13]
	s_mov_b32 m0, s44
	s_nop 0
	global_load_lds_dwordx4 v[218:219], off
	v_mfma_f32_16x16x32_bf16 v[0:3], v[180:183], v[214:217], v[0:3]
	s_setprio 0
	s_barrier
	s_add_i32 s55, s55, 2
	s_add_u32 s53, s53, 0x100
	s_addc_u32 s54, s54, 0
	s_cmp_gt_u32 s55, 41
	s_mov_b64 s[26:27], s[28:29]
	s_cbranch_scc0 .LBB0_1978
	s_and_b64 vcc, exec, s[16:17]
	s_cbranch_vccz .LBB0_1981
	s_barrier
